# GEMM MFMA issue order: snake over the 2x4 register tile so every consecutive MFMA pair shares one source operand (bit-identical)
# speedup vs baseline: 1.0058x; 1.0058x over previous
; #define PG8_STAGE(bufoff, gbase, voff) do { _Pragma("unroll") for (int _i = 0; _i < 2; ++_i) \
;         __builtin_amdgcn_global_load_lds((const unsigned*)((const char*)(gbase) + (voff)[_i]), (PG8_LAS unsigned*)(lds + (bufoff) + ldsw + _i * 8192), 16, 0, 0); } while (0)
; #define PG8_LDA(dst, b, h) do { _Pragma("unroll") for (int m = 0; m < 4; ++m) _Pragma("unroll") for (int k = 0; k < 2; ++k) dst[m][k] = *(const PG8_LAS bf16x8*)(lds + PG8_SA(b, h) + aoff + m * 2048 + k * 1024); } while (0)
; #define PG8_LDB(dst, b, h) do { _Pragma("unroll") for (int n = 0; n < 2; ++n) _Pragma("unroll") for (int k = 0; k < 2; ++k) dst[n][k] = *(const PG8_LAS bf16x8*)(lds + PG8_SB(b, h) + boff + n * 2048 + k * 1024); } while (0)
; #define PG8_WAIT_V(n) asm volatile("s_waitcnt vmcnt(" #n ")" ::: "memory")
; #define PG8_WAIT_L(n) asm volatile("s_waitcnt lgkmcnt(" #n ")" ::: "memory")
; #define PG8_BAR __builtin_amdgcn_s_barrier()
; #define PG8_SCHED __builtin_amdgcn_sched_barrier(0)
; template <class Epi, class Sched, bool ALIGN_EPI = false, bool SP2 = false>
; __device__ __forceinline__ void gemm_phase(PG8_LAS unsigned char* lds, const Gemm g, const Sched& S, const Epi& E) {
;     ...
;         const bool has_next = S.next(ui + 1, nxt);
;         const char* nA = has_next ? (const char*)g.A + (size_t)nxt.pm * tstep : cA; const char* nB = has_next ? (const char*)g.Bt + (size_t)nxt.pn * tstep : cB;
;         for (int t = 0; t < nt; t += 2) {
;             const bool last = (t == nt - 2);
;             const char* a1 = cA + (size_t)(t + 1) * kstep;
;             const char* a2 = last ? nA : cA + (size_t)(t + 2) * kstep; const char* b2 = last ? nB : cB + (size_t)(t + 2) * kstep;
;             const char* a3 = a2 + kstep; const char* b3 = b2 + kstep;
;             if (last && has_next) S.a_ready(nxt);
;             if constexpr (SP2) {
;             PG8_LDB(B0, 0, 0); PG8_LDB(B1, 0, 1); PG8_SCHED; PG8_LDA(At, 0, 0); PG8_STAGE(PG8_SA(1, 1), a1 + hstep, voffA);
;             PG8_WAIT_V(8); PG8_WAIT_L(0); PG8_BAR; PG8_MMA(0, 0, At, B0); PG8_MMA(0, 1, At, B1); PG8_BAR; PG8_SCHED;
;             PG8_LDA(At, 0, 1); PG8_STAGE(PG8_SB(0, 0), b2, voffB); PG8_STAGE(PG8_SB(0, 1), b2 + hstep, voffB); PG8_STAGE(PG8_SA(0, 0), a2, voffA);
;             PG8_WAIT_V(8); PG8_WAIT_L(0); PG8_BAR; PG8_MMA(1, 0, At, B0); PG8_MMA(1, 1, At, B1); PG8_BAR; PG8_SCHED;
.LBB0_190:
	s_ashr_i32 s27, s26, 31
	s_lshl_b64 s[14:15], s[26:27], 19
	s_add_u32 s28, s22, s14
	s_addc_u32 s29, s23, s15
	s_and_b64 s[14:15], s[0:1], exec
	s_cselect_b32 s27, s29, s49
	s_cselect_b32 s67, s28, s48
	s_ashr_i32 s25, s24, 31
	s_lshl_b64 s[14:15], s[24:25], 19
	s_add_u32 s40, s94, s14
	s_addc_u32 s41, s96, s15
	s_and_b64 s[14:15], s[0:1], exec
	s_cselect_b32 s25, s41, s51
	s_cselect_b32 s86, s40, s50
	s_add_u32 s48, s48, 0x40080
	s_addc_u32 s49, s49, 0
	s_add_u32 s87, s50, 0x100
	s_addc_u32 s88, s51, 0
	s_mov_b32 s89, -2
	ds_read_b128 v[144:147], v155
	ds_read_b128 v[148:151], v155 offset:1024
	ds_read_b128 v[160:163], v155 offset:2048
	ds_read_b128 v[168:171], v155 offset:3072
	ds_read_b128 v[172:175], v156
	ds_read_b128 v[176:179], v156 offset:1024
	ds_read_b128 v[182:185], v156 offset:2048
	ds_read_b128 v[186:189], v156 offset:3072
	s_add_u32 s3, s48, 0xfffc0080
	s_addc_u32 s14, s49, -1
	s_cmp_eq_u32 s89, 12
	s_cselect_b32 s55, s27, s14
	s_cselect_b32 s54, s67, s3
	s_cselect_b32 s51, s25, s88
	s_cselect_b32 s50, s86, s87
	v_lshl_add_u64 v[164:165], s[48:49], 0, v[136:137]
	s_add_i32 m0, s45, 0xc000
	ds_read_b128 v[190:193], v157
	ds_read_b128 v[194:197], v157 offset:1024
	ds_read_b128 v[198:201], v157 offset:2048
	ds_read_b128 v[208:211], v157 offset:3072
	ds_read_b128 v[212:215], v157 offset:4096
	ds_read_b128 v[216:219], v157 offset:5120
	ds_read_b128 v[220:223], v157 offset:6144
	ds_read_b128 v[224:227], v157 offset:7168
	global_load_lds_dwordx4 v[164:165], off
	v_lshl_add_u64 v[164:165], s[48:49], 0, v[138:139]
	s_add_i32 m0, s45, 0xe000
	s_nop 0
	global_load_lds_dwordx4 v[164:165], off
	s_waitcnt vmcnt(8)
	s_waitcnt lgkmcnt(0)
	s_barrier
	s_setprio 1
	s_waitcnt lgkmcnt(0)
	v_mfma_f32_16x16x32_bf16 v[124:127], v[144:147], v[190:193], 0
	v_mfma_f32_16x16x32_bf16 v[120:123], v[160:163], v[190:193], 0
	v_mfma_f32_16x16x32_bf16 v[104:107], v[160:163], v[198:201], 0
	v_mfma_f32_16x16x32_bf16 v[108:111], v[144:147], v[198:201], 0
	v_mfma_f32_16x16x32_bf16 v[92:95], v[144:147], v[212:215], 0
	v_mfma_f32_16x16x32_bf16 v[88:91], v[160:163], v[212:215], 0
	v_mfma_f32_16x16x32_bf16 v[72:75], v[160:163], v[220:223], 0
	v_mfma_f32_16x16x32_bf16 v[76:79], v[144:147], v[220:223], 0
	v_mfma_f32_16x16x32_bf16 v[124:127], v[148:151], v[194:197], v[124:127]
	v_mfma_f32_16x16x32_bf16 v[120:123], v[168:171], v[194:197], v[120:123]
	v_mfma_f32_16x16x32_bf16 v[104:107], v[168:171], v[208:211], v[104:107]
	v_mfma_f32_16x16x32_bf16 v[108:111], v[148:151], v[208:211], v[108:111]
	v_mfma_f32_16x16x32_bf16 v[92:95], v[148:151], v[216:219], v[92:95]
	v_mfma_f32_16x16x32_bf16 v[88:91], v[168:171], v[216:219], v[88:91]
	v_mfma_f32_16x16x32_bf16 v[72:75], v[168:171], v[224:227], v[72:75]
	v_mfma_f32_16x16x32_bf16 v[76:79], v[148:151], v[224:227], v[76:79]
	s_setprio 0
	s_setprio 1
	v_mfma_f32_16x16x32_bf16 v[116:119], v[172:175], v[190:193], 0
	v_mfma_f32_16x16x32_bf16 v[112:115], v[182:185], v[190:193], 0
	v_mfma_f32_16x16x32_bf16 v[96:99], v[182:185], v[198:201], 0
	v_mfma_f32_16x16x32_bf16 v[100:103], v[172:175], v[198:201], 0
	v_mfma_f32_16x16x32_bf16 v[84:87], v[172:175], v[212:215], 0
	v_mfma_f32_16x16x32_bf16 v[80:83], v[182:185], v[212:215], 0
	v_mfma_f32_16x16x32_bf16 v[64:67], v[182:185], v[220:223], 0
	v_mfma_f32_16x16x32_bf16 v[68:71], v[172:175], v[220:223], 0
	v_mfma_f32_16x16x32_bf16 v[116:119], v[176:179], v[194:197], v[116:119]
	v_mfma_f32_16x16x32_bf16 v[112:115], v[186:189], v[194:197], v[112:115]
	v_mfma_f32_16x16x32_bf16 v[96:99], v[186:189], v[208:211], v[96:99]
	v_mfma_f32_16x16x32_bf16 v[100:103], v[176:179], v[208:211], v[100:103]
	v_mfma_f32_16x16x32_bf16 v[84:87], v[176:179], v[216:219], v[84:87]
	v_mfma_f32_16x16x32_bf16 v[80:83], v[186:189], v[216:219], v[80:83]
	v_mfma_f32_16x16x32_bf16 v[64:67], v[186:189], v[224:227], v[64:67]
	v_mfma_f32_16x16x32_bf16 v[68:71], v[176:179], v[224:227], v[68:71]
	s_setprio 0
	s_barrier
	s_add_i32 s3, s63, s43
	v_lshl_add_u64 v[164:165], s[50:51], 0, v[132:133]
	s_mov_b32 m0, s3
	ds_read_b128 v[190:193], v157 offset:16384
	ds_read_b128 v[194:197], v157 offset:17408
	ds_read_b128 v[198:201], v157 offset:18432
	ds_read_b128 v[208:211], v157 offset:19456
	ds_read_b128 v[212:215], v157 offset:20480
	ds_read_b128 v[216:219], v157 offset:21504
	ds_read_b128 v[220:223], v157 offset:22528
	ds_read_b128 v[224:227], v157 offset:23552
	global_load_lds_dwordx4 v[164:165], off
	s_add_i32 m0, s3, 0x2000
	s_add_u32 s14, s50, 0x40000
	v_lshl_add_u64 v[202:203], s[50:51], 0, v[128:129]
	s_addc_u32 s15, s51, 0
	s_add_i32 s3, s64, s43
	global_load_lds_dwordx4 v[202:203], off
	v_lshl_add_u64 v[228:229], s[14:15], 0, v[132:133]
	s_mov_b32 m0, s3
	global_load_lds_dwordx4 v[228:229], off
	v_lshl_add_u64 v[228:229], s[14:15], 0, v[128:129]
	s_add_i32 m0, s3, 0x2000
	s_nop 0
	global_load_lds_dwordx4 v[228:229], off
	s_waitcnt vmcnt(6)
	s_waitcnt lgkmcnt(0)
	s_barrier
; #define PG8_STAGE(bufoff, gbase, voff) do { _Pragma("unroll") for (int _i = 0; _i < 2; ++_i) \
;         __builtin_amdgcn_global_load_lds((const unsigned*)((const char*)(gbase) + (voff)[_i]), (PG8_LAS unsigned*)(lds + (bufoff) + ldsw + _i * 8192), 16, 0, 0); } while (0)
; #define PG8_LDA(dst, b, h) do { _Pragma("unroll") for (int m = 0; m < 4; ++m) _Pragma("unroll") for (int k = 0; k < 2; ++k) dst[m][k] = *(const PG8_LAS bf16x8*)(lds + PG8_SA(b, h) + aoff + m * 2048 + k * 1024); } while (0)
; #define PG8_LDB(dst, b, h) do { _Pragma("unroll") for (int n = 0; n < 2; ++n) _Pragma("unroll") for (int k = 0; k < 2; ++k) dst[n][k] = *(const PG8_LAS bf16x8*)(lds + PG8_SB(b, h) + boff + n * 2048 + k * 1024); } while (0)
; #define PG8_MMA(ai, bj, At, Bt) do { __builtin_amdgcn_s_setprio(1); _Pragma("unroll") for (int m = 0; m < 4; ++m) _Pragma("unroll") for (int n = 0; n < 2; ++n) _Pragma("unroll") for (int k = 0; k < 2; ++k) \
;         acc[ai][bj][m][n] = __builtin_amdgcn_mfma_f32_16x16x32_bf16(Bt[n][k], At[m][k], acc[ai][bj][m][n], 0, 0, 0); __builtin_amdgcn_s_setprio(0); } while (0)
; #define PG8_WAIT_V(n) asm volatile("s_waitcnt vmcnt(" #n ")" ::: "memory")
; #define PG8_WAIT_L(n) asm volatile("s_waitcnt lgkmcnt(" #n ")" ::: "memory")
; #define PG8_BAR __builtin_amdgcn_s_barrier()
; #define PG8_SCHED __builtin_amdgcn_sched_barrier(0)
; template <class Epi, class Sched, bool ALIGN_EPI = false, bool SP2 = false>
; __device__ __forceinline__ void gemm_phase(PG8_LAS unsigned char* lds, const Gemm g, const Sched& S, const Epi& E) {
;     ...
;             PG8_WAIT_V(8); PG8_WAIT_L(0); PG8_BAR; PG8_MMA(0, 0, At, B0); PG8_MMA(0, 1, At, B1); PG8_BAR; PG8_SCHED;
;             PG8_LDA(At, 0, 1); PG8_STAGE(PG8_SB(0, 0), b2, voffB); PG8_STAGE(PG8_SB(0, 1), b2 + hstep, voffB); PG8_STAGE(PG8_SA(0, 0), a2, voffA);
;             PG8_WAIT_V(8); PG8_WAIT_L(0); PG8_BAR; PG8_MMA(1, 0, At, B0); PG8_MMA(1, 1, At, B1); PG8_BAR; PG8_SCHED;
;             PG8_LDB(B0, 1, 0); PG8_LDB(B1, 1, 1); PG8_SCHED; PG8_LDA(At, 1, 0); PG8_STAGE(PG8_SA(0, 1), a2 + hstep, voffA);
;             PG8_WAIT_V(8); PG8_WAIT_L(0); PG8_BAR; PG8_MMA(0, 0, At, B0); PG8_MMA(0, 1, At, B1); PG8_BAR; PG8_SCHED;
	s_setprio 1
	s_waitcnt lgkmcnt(0)
	v_mfma_f32_16x16x32_bf16 v[60:63], v[144:147], v[190:193], 0
	v_mfma_f32_16x16x32_bf16 v[56:59], v[160:163], v[190:193], 0
	v_mfma_f32_16x16x32_bf16 v[40:43], v[160:163], v[198:201], 0
	v_mfma_f32_16x16x32_bf16 v[44:47], v[144:147], v[198:201], 0
	v_mfma_f32_16x16x32_bf16 v[28:31], v[144:147], v[212:215], 0
	v_mfma_f32_16x16x32_bf16 v[24:27], v[160:163], v[212:215], 0
	v_mfma_f32_16x16x32_bf16 v[8:11], v[160:163], v[220:223], 0
	v_mfma_f32_16x16x32_bf16 v[12:15], v[144:147], v[220:223], 0
	v_mfma_f32_16x16x32_bf16 v[60:63], v[148:151], v[194:197], v[60:63]
	v_mfma_f32_16x16x32_bf16 v[56:59], v[168:171], v[194:197], v[56:59]
	v_mfma_f32_16x16x32_bf16 v[40:43], v[168:171], v[208:211], v[40:43]
	v_mfma_f32_16x16x32_bf16 v[44:47], v[148:151], v[208:211], v[44:47]
	v_mfma_f32_16x16x32_bf16 v[28:31], v[148:151], v[216:219], v[28:31]
	v_mfma_f32_16x16x32_bf16 v[24:27], v[168:171], v[216:219], v[24:27]
	v_lshl_add_u64 v[228:229], s[54:55], 0, v[134:135]
	s_mov_b32 m0, s45
	s_nop 0
	global_load_lds_dwordx4 v[228:229], off
	v_mfma_f32_16x16x32_bf16 v[8:11], v[168:171], v[224:227], v[8:11]
	v_mfma_f32_16x16x32_bf16 v[12:15], v[148:151], v[224:227], v[12:15]
	s_setprio 0
	s_setprio 1
	v_mfma_f32_16x16x32_bf16 v[52:55], v[172:175], v[190:193], 0
	v_mfma_f32_16x16x32_bf16 v[48:51], v[182:185], v[190:193], 0
	v_mfma_f32_16x16x32_bf16 v[32:35], v[182:185], v[198:201], 0
	v_mfma_f32_16x16x32_bf16 v[36:39], v[172:175], v[198:201], 0
	v_mfma_f32_16x16x32_bf16 v[20:23], v[172:175], v[212:215], 0
	v_mfma_f32_16x16x32_bf16 v[16:19], v[182:185], v[212:215], 0
	v_mfma_f32_16x16x32_bf16 v[0:3], v[182:185], v[220:223], 0
	v_mfma_f32_16x16x32_bf16 v[4:7], v[172:175], v[220:223], 0
	v_mfma_f32_16x16x32_bf16 v[52:55], v[176:179], v[194:197], v[52:55]
	v_mfma_f32_16x16x32_bf16 v[48:51], v[186:189], v[194:197], v[48:51]
	v_mfma_f32_16x16x32_bf16 v[32:35], v[186:189], v[208:211], v[32:35]
	v_mfma_f32_16x16x32_bf16 v[36:39], v[176:179], v[208:211], v[36:39]
	v_mfma_f32_16x16x32_bf16 v[20:23], v[176:179], v[216:219], v[20:23]
	v_mfma_f32_16x16x32_bf16 v[16:19], v[186:189], v[216:219], v[16:19]
	v_lshl_add_u64 v[230:231], s[54:55], 0, v[130:131]
	s_mov_b32 m0, s57
	s_nop 0
	global_load_lds_dwordx4 v[230:231], off
	v_mfma_f32_16x16x32_bf16 v[0:3], v[186:189], v[224:227], v[0:3]
	v_mfma_f32_16x16x32_bf16 v[4:7], v[176:179], v[224:227], v[4:7]
	s_setprio 0
	s_barrier
	s_add_i32 s3, 0, 0x18000
	v_add_u32_e32 v159, s3, v153
	s_add_i32 s33, 0, 0x1c000
	ds_read_b128 v[144:147], v159
	ds_read_b128 v[148:151], v159 offset:1024
	ds_read_b128 v[160:163], v159 offset:2048
	ds_read_b128 v[168:171], v159 offset:3072
	v_add_u32_e32 v159, s33, v153
	ds_read_b128 v[172:175], v159
	ds_read_b128 v[176:179], v159 offset:1024
	ds_read_b128 v[182:185], v159 offset:2048
	ds_read_b128 v[186:189], v159 offset:3072
	s_add_u32 s14, s54, 0x40000
	s_addc_u32 s15, s55, 0
	s_mov_b32 m0, s58
	v_lshl_add_u64 v[232:233], s[14:15], 0, v[134:135]
	ds_read_b128 v[190:193], v157 offset:32768
	ds_read_b128 v[194:197], v157 offset:33792
	ds_read_b128 v[198:201], v157 offset:34816
	ds_read_b128 v[208:211], v157 offset:35840
	ds_read_b128 v[212:215], v157 offset:36864
	ds_read_b128 v[216:219], v157 offset:37888
	ds_read_b128 v[220:223], v157 offset:38912
	ds_read_b128 v[224:227], v157 offset:39936
	global_load_lds_dwordx4 v[232:233], off
	v_lshl_add_u64 v[232:233], s[14:15], 0, v[130:131]
	s_mov_b32 m0, s59
	s_nop 0
	global_load_lds_dwordx4 v[232:233], off
	s_waitcnt vmcnt(8)
	s_waitcnt lgkmcnt(0)
	s_barrier
	s_setprio 1
	s_waitcnt lgkmcnt(0)
	v_mfma_f32_16x16x32_bf16 v[124:127], v[144:147], v[190:193], v[124:127]
	v_mfma_f32_16x16x32_bf16 v[120:123], v[160:163], v[190:193], v[120:123]
	v_mfma_f32_16x16x32_bf16 v[104:107], v[160:163], v[198:201], v[104:107]
	v_mfma_f32_16x16x32_bf16 v[108:111], v[144:147], v[198:201], v[108:111]
	v_mfma_f32_16x16x32_bf16 v[92:95], v[144:147], v[212:215], v[92:95]
	v_mfma_f32_16x16x32_bf16 v[88:91], v[160:163], v[212:215], v[88:91]
	v_mfma_f32_16x16x32_bf16 v[72:75], v[160:163], v[220:223], v[72:75]
	v_mfma_f32_16x16x32_bf16 v[76:79], v[144:147], v[220:223], v[76:79]
	v_mfma_f32_16x16x32_bf16 v[124:127], v[148:151], v[194:197], v[124:127]
	v_mfma_f32_16x16x32_bf16 v[120:123], v[168:171], v[194:197], v[120:123]
	v_mfma_f32_16x16x32_bf16 v[104:107], v[168:171], v[208:211], v[104:107]
	v_mfma_f32_16x16x32_bf16 v[108:111], v[148:151], v[208:211], v[108:111]
	v_mfma_f32_16x16x32_bf16 v[92:95], v[148:151], v[216:219], v[92:95]
	v_mfma_f32_16x16x32_bf16 v[88:91], v[168:171], v[216:219], v[88:91]
	v_mfma_f32_16x16x32_bf16 v[72:75], v[168:171], v[224:227], v[72:75]
	v_mfma_f32_16x16x32_bf16 v[76:79], v[148:151], v[224:227], v[76:79]
	s_setprio 0
	s_setprio 1
	v_mfma_f32_16x16x32_bf16 v[116:119], v[172:175], v[190:193], v[116:119]
	v_mfma_f32_16x16x32_bf16 v[112:115], v[182:185], v[190:193], v[112:115]
	v_mfma_f32_16x16x32_bf16 v[96:99], v[182:185], v[198:201], v[96:99]
	v_mfma_f32_16x16x32_bf16 v[100:103], v[172:175], v[198:201], v[100:103]
	v_mfma_f32_16x16x32_bf16 v[84:87], v[172:175], v[212:215], v[84:87]
	v_mfma_f32_16x16x32_bf16 v[80:83], v[182:185], v[212:215], v[80:83]
	v_mfma_f32_16x16x32_bf16 v[64:67], v[182:185], v[220:223], v[64:67]
	v_mfma_f32_16x16x32_bf16 v[68:71], v[172:175], v[220:223], v[68:71]
	v_mfma_f32_16x16x32_bf16 v[116:119], v[176:179], v[194:197], v[116:119]
	v_mfma_f32_16x16x32_bf16 v[112:115], v[186:189], v[194:197], v[112:115]
	v_mfma_f32_16x16x32_bf16 v[96:99], v[186:189], v[208:211], v[96:99]
	v_mfma_f32_16x16x32_bf16 v[100:103], v[176:179], v[208:211], v[100:103]
	v_mfma_f32_16x16x32_bf16 v[84:87], v[176:179], v[216:219], v[84:87]
	v_mfma_f32_16x16x32_bf16 v[80:83], v[186:189], v[216:219], v[80:83]
	v_mfma_f32_16x16x32_bf16 v[64:67], v[186:189], v[224:227], v[64:67]
	v_mfma_f32_16x16x32_bf16 v[68:71], v[176:179], v[224:227], v[68:71]
	s_setprio 0
	s_barrier
; #define PG8_STAGE(bufoff, gbase, voff) do { _Pragma("unroll") for (int _i = 0; _i < 2; ++_i) \
;         __builtin_amdgcn_global_load_lds((const unsigned*)((const char*)(gbase) + (voff)[_i]), (PG8_LAS unsigned*)(lds + (bufoff) + ldsw + _i * 8192), 16, 0, 0); } while (0)
; #define PG8_LDA(dst, b, h) do { _Pragma("unroll") for (int m = 0; m < 4; ++m) _Pragma("unroll") for (int k = 0; k < 2; ++k) dst[m][k] = *(const PG8_LAS bf16x8*)(lds + PG8_SA(b, h) + aoff + m * 2048 + k * 1024); } while (0)
; #define PG8_LDB(dst, b, h) do { _Pragma("unroll") for (int n = 0; n < 2; ++n) _Pragma("unroll") for (int k = 0; k < 2; ++k) dst[n][k] = *(const PG8_LAS bf16x8*)(lds + PG8_SB(b, h) + boff + n * 2048 + k * 1024); } while (0)
; #define PG8_MMA(ai, bj, At, Bt) do { __builtin_amdgcn_s_setprio(1); _Pragma("unroll") for (int m = 0; m < 4; ++m) _Pragma("unroll") for (int n = 0; n < 2; ++n) _Pragma("unroll") for (int k = 0; k < 2; ++k) \
;         acc[ai][bj][m][n] = __builtin_amdgcn_mfma_f32_16x16x32_bf16(Bt[n][k], At[m][k], acc[ai][bj][m][n], 0, 0, 0); __builtin_amdgcn_s_setprio(0); } while (0)
; #define PG8_WAIT_V(n) asm volatile("s_waitcnt vmcnt(" #n ")" ::: "memory")
; template <class Epi, class Sched, bool ALIGN_EPI = false, bool SP2 = false>
; __device__ __forceinline__ void gemm_phase(PG8_LAS unsigned char* lds, const Gemm g, const Sched& S, const Epi& E) {
;     ...
;             PG8_LDB(B0, 0, 0); PG8_LDB(B1, 0, 1); PG8_SCHED; PG8_LDA(At, 0, 0); PG8_STAGE(PG8_SA(1, 1), a1 + hstep, voffA);
;             PG8_WAIT_V(8); PG8_WAIT_L(0); PG8_BAR; PG8_MMA(0, 0, At, B0); PG8_MMA(0, 1, At, B1); PG8_BAR; PG8_SCHED;
;             PG8_LDA(At, 0, 1); PG8_STAGE(PG8_SB(0, 0), b2, voffB); PG8_STAGE(PG8_SB(0, 1), b2 + hstep, voffB); PG8_STAGE(PG8_SA(0, 0), a2, voffA);
;             PG8_WAIT_V(8); PG8_WAIT_L(0); PG8_BAR; PG8_MMA(1, 0, At, B0); PG8_MMA(1, 1, At, B1); PG8_BAR; PG8_SCHED;
;             PG8_LDB(B0, 1, 0); PG8_LDB(B1, 1, 1); PG8_SCHED; PG8_LDA(At, 1, 0); PG8_STAGE(PG8_SA(0, 1), a2 + hstep, voffA);
;             PG8_WAIT_V(8); PG8_WAIT_L(0); PG8_BAR; PG8_MMA(0, 0, At, B0); PG8_MMA(0, 1, At, B1); PG8_BAR; PG8_SCHED;
;             PG8_LDA(At, 1, 1); PG8_STAGE(PG8_SB(1, 0), b3, voffB); PG8_STAGE(PG8_SB(1, 1), b3 + hstep, voffB); PG8_STAGE(PG8_SA(1, 0), a3, voffA);
;             PG8_WAIT_V(8); PG8_WAIT_L(0); PG8_BAR; PG8_MMA(1, 0, At, B0); PG8_MMA(1, 1, At, B1); PG8_BAR; PG8_SCHED;
	s_add_i32 s3, s3, s43
	v_lshl_add_u64 v[164:165], v[164:165], 0, s[10:11]
	s_mov_b32 m0, s3
	ds_read_b128 v[190:193], v157 offset:49152
	ds_read_b128 v[194:197], v157 offset:50176
	ds_read_b128 v[198:201], v157 offset:51200
	ds_read_b128 v[208:211], v157 offset:52224
	ds_read_b128 v[212:215], v157 offset:53248
	ds_read_b128 v[216:219], v157 offset:54272
	ds_read_b128 v[220:223], v157 offset:55296
	ds_read_b128 v[224:227], v157 offset:56320
	global_load_lds_dwordx4 v[164:165], off
	s_add_i32 m0, s3, 0x2000
	s_add_u32 s14, s50, 0x40080
	v_lshl_add_u64 v[164:165], v[202:203], 0, s[10:11]
	s_addc_u32 s15, s51, 0
	s_add_i32 s3, s33, s43
	global_load_lds_dwordx4 v[164:165], off
	v_lshl_add_u64 v[164:165], s[14:15], 0, v[132:133]
	s_mov_b32 m0, s3
	s_nop 0
	global_load_lds_dwordx4 v[164:165], off
	v_lshl_add_u64 v[164:165], s[14:15], 0, v[128:129]
	s_add_i32 m0, s3, 0x2000
	s_nop 0
	global_load_lds_dwordx4 v[164:165], off
	s_waitcnt vmcnt(6)
	s_waitcnt lgkmcnt(0)
	s_barrier
	s_setprio 1
	s_waitcnt lgkmcnt(0)
	v_mfma_f32_16x16x32_bf16 v[60:63], v[144:147], v[190:193], v[60:63]
	v_mfma_f32_16x16x32_bf16 v[56:59], v[160:163], v[190:193], v[56:59]
	v_mfma_f32_16x16x32_bf16 v[40:43], v[160:163], v[198:201], v[40:43]
	v_mfma_f32_16x16x32_bf16 v[44:47], v[144:147], v[198:201], v[44:47]
	v_mfma_f32_16x16x32_bf16 v[28:31], v[144:147], v[212:215], v[28:31]
	v_mfma_f32_16x16x32_bf16 v[24:27], v[160:163], v[212:215], v[24:27]
	v_mfma_f32_16x16x32_bf16 v[8:11], v[160:163], v[220:223], v[8:11]
	v_mfma_f32_16x16x32_bf16 v[12:15], v[144:147], v[220:223], v[12:15]
	v_mfma_f32_16x16x32_bf16 v[60:63], v[148:151], v[194:197], v[60:63]
	v_mfma_f32_16x16x32_bf16 v[56:59], v[168:171], v[194:197], v[56:59]
	v_mfma_f32_16x16x32_bf16 v[40:43], v[168:171], v[208:211], v[40:43]
	v_mfma_f32_16x16x32_bf16 v[44:47], v[148:151], v[208:211], v[44:47]
	v_mfma_f32_16x16x32_bf16 v[28:31], v[148:151], v[216:219], v[28:31]
	v_mfma_f32_16x16x32_bf16 v[24:27], v[168:171], v[216:219], v[24:27]
	v_lshl_add_u64 v[164:165], v[228:229], 0, s[10:11]
	s_mov_b32 m0, s61
	s_nop 0
	global_load_lds_dwordx4 v[164:165], off
	v_mfma_f32_16x16x32_bf16 v[8:11], v[168:171], v[224:227], v[8:11]
	v_mfma_f32_16x16x32_bf16 v[12:15], v[148:151], v[224:227], v[12:15]
	s_setprio 0
	s_setprio 1
	v_mfma_f32_16x16x32_bf16 v[52:55], v[172:175], v[190:193], v[52:55]
	v_mfma_f32_16x16x32_bf16 v[48:51], v[182:185], v[190:193], v[48:51]
	v_mfma_f32_16x16x32_bf16 v[32:35], v[182:185], v[198:201], v[32:35]
	v_mfma_f32_16x16x32_bf16 v[36:39], v[172:175], v[198:201], v[36:39]
	v_mfma_f32_16x16x32_bf16 v[20:23], v[172:175], v[212:215], v[20:23]
	v_mfma_f32_16x16x32_bf16 v[16:19], v[182:185], v[212:215], v[16:19]
	v_mfma_f32_16x16x32_bf16 v[0:3], v[182:185], v[220:223], v[0:3]
	v_mfma_f32_16x16x32_bf16 v[4:7], v[172:175], v[220:223], v[4:7]
	v_mfma_f32_16x16x32_bf16 v[52:55], v[176:179], v[194:197], v[52:55]
	v_mfma_f32_16x16x32_bf16 v[48:51], v[186:189], v[194:197], v[48:51]
	v_mfma_f32_16x16x32_bf16 v[32:35], v[186:189], v[208:211], v[32:35]
	v_mfma_f32_16x16x32_bf16 v[36:39], v[176:179], v[208:211], v[36:39]
	v_mfma_f32_16x16x32_bf16 v[20:23], v[176:179], v[216:219], v[20:23]
	v_mfma_f32_16x16x32_bf16 v[16:19], v[186:189], v[216:219], v[16:19]
	v_lshl_add_u64 v[164:165], v[230:231], 0, s[10:11]
	s_mov_b32 m0, s62
	s_nop 0
	global_load_lds_dwordx4 v[164:165], off
	v_mfma_f32_16x16x32_bf16 v[0:3], v[186:189], v[224:227], v[0:3]
	v_mfma_f32_16x16x32_bf16 v[4:7], v[176:179], v[224:227], v[4:7]
	s_setprio 0
	s_barrier
	s_add_i32 s89, s89, 2
	s_add_u32 s48, s48, 0x100
	s_addc_u32 s49, s49, 0
	s_add_u32 s87, s87, 0x100
	s_addc_u32 s88, s88, 0
.LBB0_191:
	ds_read_b128 v[144:147], v155
	ds_read_b128 v[148:151], v155 offset:1024
	ds_read_b128 v[160:163], v155 offset:2048
	ds_read_b128 v[168:171], v155 offset:3072
	ds_read_b128 v[172:175], v156
	ds_read_b128 v[176:179], v156 offset:1024
	ds_read_b128 v[182:185], v156 offset:2048
	ds_read_b128 v[186:189], v156 offset:3072
	s_add_u32 s3, s48, 0xfffc0080
	s_addc_u32 s14, s49, -1
	s_cmp_eq_u32 s89, 12
	s_cselect_b32 s55, s27, s14
	s_cselect_b32 s54, s67, s3
	s_cselect_b32 s51, s25, s88
	s_cselect_b32 s50, s86, s87
	v_lshl_add_u64 v[164:165], s[48:49], 0, v[136:137]
	s_add_i32 m0, s45, 0xc000
	ds_read_b128 v[190:193], v157
	ds_read_b128 v[194:197], v157 offset:1024
	ds_read_b128 v[198:201], v157 offset:2048
	ds_read_b128 v[208:211], v157 offset:3072
	ds_read_b128 v[212:215], v157 offset:4096
	ds_read_b128 v[216:219], v157 offset:5120
	ds_read_b128 v[220:223], v157 offset:6144
	ds_read_b128 v[224:227], v157 offset:7168
	global_load_lds_dwordx4 v[164:165], off
	v_lshl_add_u64 v[164:165], s[48:49], 0, v[138:139]
	s_add_i32 m0, s45, 0xe000
	s_nop 0
	global_load_lds_dwordx4 v[164:165], off
	s_waitcnt vmcnt(8)
	s_waitcnt lgkmcnt(0)
	s_barrier
; #define PG8_STAGE(bufoff, gbase, voff) do { _Pragma("unroll") for (int _i = 0; _i < 2; ++_i) \
;         __builtin_amdgcn_global_load_lds((const unsigned*)((const char*)(gbase) + (voff)[_i]), (PG8_LAS unsigned*)(lds + (bufoff) + ldsw + _i * 8192), 16, 0, 0); } while (0)
; #define PG8_LDA(dst, b, h) do { _Pragma("unroll") for (int m = 0; m < 4; ++m) _Pragma("unroll") for (int k = 0; k < 2; ++k) dst[m][k] = *(const PG8_LAS bf16x8*)(lds + PG8_SA(b, h) + aoff + m * 2048 + k * 1024); } while (0)
; #define PG8_LDB(dst, b, h) do { _Pragma("unroll") for (int n = 0; n < 2; ++n) _Pragma("unroll") for (int k = 0; k < 2; ++k) dst[n][k] = *(const PG8_LAS bf16x8*)(lds + PG8_SB(b, h) + boff + n * 2048 + k * 1024); } while (0)
; #define PG8_MMA(ai, bj, At, Bt) do { __builtin_amdgcn_s_setprio(1); _Pragma("unroll") for (int m = 0; m < 4; ++m) _Pragma("unroll") for (int n = 0; n < 2; ++n) _Pragma("unroll") for (int k = 0; k < 2; ++k) \
;         acc[ai][bj][m][n] = __builtin_amdgcn_mfma_f32_16x16x32_bf16(Bt[n][k], At[m][k], acc[ai][bj][m][n], 0, 0, 0); __builtin_amdgcn_s_setprio(0); } while (0)
; #define PG8_WAIT_V(n) asm volatile("s_waitcnt vmcnt(" #n ")" ::: "memory")
; #define PG8_WAIT_L(n) asm volatile("s_waitcnt lgkmcnt(" #n ")" ::: "memory")
; #define PG8_BAR __builtin_amdgcn_s_barrier()
; #define PG8_SCHED __builtin_amdgcn_sched_barrier(0)
; template <class Epi, class Sched, bool ALIGN_EPI = false, bool SP2 = false>
; __device__ __forceinline__ void gemm_phase(PG8_LAS unsigned char* lds, const Gemm g, const Sched& S, const Epi& E) {
;     ...
;             PG8_LDB(B0, 0, 0); PG8_LDB(B1, 0, 1); PG8_SCHED; PG8_LDA(At, 0, 0); PG8_STAGE(PG8_SA(1, 1), a1 + hstep, voffA);
;             PG8_WAIT_V(8); PG8_WAIT_L(0); PG8_BAR; PG8_MMA(0, 0, At, B0); PG8_MMA(0, 1, At, B1); PG8_BAR; PG8_SCHED;
;             PG8_LDA(At, 0, 1); PG8_STAGE(PG8_SB(0, 0), b2, voffB); PG8_STAGE(PG8_SB(0, 1), b2 + hstep, voffB); PG8_STAGE(PG8_SA(0, 0), a2, voffA);
;             PG8_WAIT_V(8); PG8_WAIT_L(0); PG8_BAR; PG8_MMA(1, 0, At, B0); PG8_MMA(1, 1, At, B1); PG8_BAR; PG8_SCHED;
	s_setprio 1
	s_waitcnt lgkmcnt(0)
	v_mfma_f32_16x16x32_bf16 v[124:127], v[144:147], v[190:193], v[124:127]
	v_mfma_f32_16x16x32_bf16 v[120:123], v[160:163], v[190:193], v[120:123]
	v_mfma_f32_16x16x32_bf16 v[104:107], v[160:163], v[198:201], v[104:107]
	v_mfma_f32_16x16x32_bf16 v[108:111], v[144:147], v[198:201], v[108:111]
	v_mfma_f32_16x16x32_bf16 v[92:95], v[144:147], v[212:215], v[92:95]
	v_mfma_f32_16x16x32_bf16 v[88:91], v[160:163], v[212:215], v[88:91]
	v_mfma_f32_16x16x32_bf16 v[72:75], v[160:163], v[220:223], v[72:75]
	v_mfma_f32_16x16x32_bf16 v[76:79], v[144:147], v[220:223], v[76:79]
	v_mfma_f32_16x16x32_bf16 v[124:127], v[148:151], v[194:197], v[124:127]
	v_mfma_f32_16x16x32_bf16 v[120:123], v[168:171], v[194:197], v[120:123]
	v_mfma_f32_16x16x32_bf16 v[104:107], v[168:171], v[208:211], v[104:107]
	v_mfma_f32_16x16x32_bf16 v[108:111], v[148:151], v[208:211], v[108:111]
	v_mfma_f32_16x16x32_bf16 v[92:95], v[148:151], v[216:219], v[92:95]
	v_mfma_f32_16x16x32_bf16 v[88:91], v[168:171], v[216:219], v[88:91]
	v_mfma_f32_16x16x32_bf16 v[72:75], v[168:171], v[224:227], v[72:75]
	v_mfma_f32_16x16x32_bf16 v[76:79], v[148:151], v[224:227], v[76:79]
	s_setprio 0
	s_setprio 1
	v_mfma_f32_16x16x32_bf16 v[116:119], v[172:175], v[190:193], v[116:119]
	v_mfma_f32_16x16x32_bf16 v[112:115], v[182:185], v[190:193], v[112:115]
	v_mfma_f32_16x16x32_bf16 v[96:99], v[182:185], v[198:201], v[96:99]
	v_mfma_f32_16x16x32_bf16 v[100:103], v[172:175], v[198:201], v[100:103]
	v_mfma_f32_16x16x32_bf16 v[84:87], v[172:175], v[212:215], v[84:87]
	v_mfma_f32_16x16x32_bf16 v[80:83], v[182:185], v[212:215], v[80:83]
	v_mfma_f32_16x16x32_bf16 v[64:67], v[182:185], v[220:223], v[64:67]
	v_mfma_f32_16x16x32_bf16 v[68:71], v[172:175], v[220:223], v[68:71]
	v_mfma_f32_16x16x32_bf16 v[116:119], v[176:179], v[194:197], v[116:119]
	v_mfma_f32_16x16x32_bf16 v[112:115], v[186:189], v[194:197], v[112:115]
	v_mfma_f32_16x16x32_bf16 v[96:99], v[186:189], v[208:211], v[96:99]
	v_mfma_f32_16x16x32_bf16 v[100:103], v[176:179], v[208:211], v[100:103]
	v_mfma_f32_16x16x32_bf16 v[84:87], v[176:179], v[216:219], v[84:87]
	v_mfma_f32_16x16x32_bf16 v[80:83], v[186:189], v[216:219], v[80:83]
	v_mfma_f32_16x16x32_bf16 v[64:67], v[186:189], v[224:227], v[64:67]
	v_mfma_f32_16x16x32_bf16 v[68:71], v[176:179], v[224:227], v[68:71]
	s_setprio 0
	s_barrier
	s_add_i32 s3, s63, s43
	v_lshl_add_u64 v[164:165], s[50:51], 0, v[132:133]
	s_mov_b32 m0, s3
	ds_read_b128 v[190:193], v157 offset:16384
	ds_read_b128 v[194:197], v157 offset:17408
	ds_read_b128 v[198:201], v157 offset:18432
	ds_read_b128 v[208:211], v157 offset:19456
	ds_read_b128 v[212:215], v157 offset:20480
	ds_read_b128 v[216:219], v157 offset:21504
	ds_read_b128 v[220:223], v157 offset:22528
	ds_read_b128 v[224:227], v157 offset:23552
	global_load_lds_dwordx4 v[164:165], off
	s_add_i32 m0, s3, 0x2000
	s_add_u32 s14, s50, 0x40000
	v_lshl_add_u64 v[202:203], s[50:51], 0, v[128:129]
	s_addc_u32 s15, s51, 0
	s_add_i32 s3, s64, s43
	global_load_lds_dwordx4 v[202:203], off
	v_lshl_add_u64 v[228:229], s[14:15], 0, v[132:133]
	s_mov_b32 m0, s3
	global_load_lds_dwordx4 v[228:229], off
	v_lshl_add_u64 v[228:229], s[14:15], 0, v[128:129]
	s_add_i32 m0, s3, 0x2000
	s_nop 0
	global_load_lds_dwordx4 v[228:229], off
	s_waitcnt vmcnt(6)
	s_waitcnt lgkmcnt(0)
	s_barrier
	s_setprio 1
	s_waitcnt lgkmcnt(0)
	v_mfma_f32_16x16x32_bf16 v[60:63], v[144:147], v[190:193], v[60:63]
	v_mfma_f32_16x16x32_bf16 v[56:59], v[160:163], v[190:193], v[56:59]
	v_mfma_f32_16x16x32_bf16 v[40:43], v[160:163], v[198:201], v[40:43]
	v_mfma_f32_16x16x32_bf16 v[44:47], v[144:147], v[198:201], v[44:47]
	v_mfma_f32_16x16x32_bf16 v[28:31], v[144:147], v[212:215], v[28:31]
	v_mfma_f32_16x16x32_bf16 v[24:27], v[160:163], v[212:215], v[24:27]
	v_mfma_f32_16x16x32_bf16 v[8:11], v[160:163], v[220:223], v[8:11]
	v_mfma_f32_16x16x32_bf16 v[12:15], v[144:147], v[220:223], v[12:15]
	v_mfma_f32_16x16x32_bf16 v[60:63], v[148:151], v[194:197], v[60:63]
	v_mfma_f32_16x16x32_bf16 v[56:59], v[168:171], v[194:197], v[56:59]
	v_mfma_f32_16x16x32_bf16 v[40:43], v[168:171], v[208:211], v[40:43]
	v_mfma_f32_16x16x32_bf16 v[44:47], v[148:151], v[208:211], v[44:47]
	v_mfma_f32_16x16x32_bf16 v[28:31], v[148:151], v[216:219], v[28:31]
	v_mfma_f32_16x16x32_bf16 v[24:27], v[168:171], v[216:219], v[24:27]
	v_lshl_add_u64 v[228:229], s[54:55], 0, v[134:135]
	s_mov_b32 m0, s45
	s_nop 0
	global_load_lds_dwordx4 v[228:229], off
	v_mfma_f32_16x16x32_bf16 v[8:11], v[168:171], v[224:227], v[8:11]
	v_mfma_f32_16x16x32_bf16 v[12:15], v[148:151], v[224:227], v[12:15]
	s_setprio 0
	s_setprio 1
	v_mfma_f32_16x16x32_bf16 v[52:55], v[172:175], v[190:193], v[52:55]
	v_mfma_f32_16x16x32_bf16 v[48:51], v[182:185], v[190:193], v[48:51]
	v_mfma_f32_16x16x32_bf16 v[32:35], v[182:185], v[198:201], v[32:35]
	v_mfma_f32_16x16x32_bf16 v[36:39], v[172:175], v[198:201], v[36:39]
	v_mfma_f32_16x16x32_bf16 v[20:23], v[172:175], v[212:215], v[20:23]
	v_mfma_f32_16x16x32_bf16 v[16:19], v[182:185], v[212:215], v[16:19]
	v_mfma_f32_16x16x32_bf16 v[0:3], v[182:185], v[220:223], v[0:3]
	v_mfma_f32_16x16x32_bf16 v[4:7], v[172:175], v[220:223], v[4:7]
	v_mfma_f32_16x16x32_bf16 v[52:55], v[176:179], v[194:197], v[52:55]
	v_mfma_f32_16x16x32_bf16 v[48:51], v[186:189], v[194:197], v[48:51]
	v_mfma_f32_16x16x32_bf16 v[32:35], v[186:189], v[208:211], v[32:35]
	v_mfma_f32_16x16x32_bf16 v[36:39], v[176:179], v[208:211], v[36:39]
	v_mfma_f32_16x16x32_bf16 v[20:23], v[176:179], v[216:219], v[20:23]
	v_mfma_f32_16x16x32_bf16 v[16:19], v[186:189], v[216:219], v[16:19]
	v_lshl_add_u64 v[230:231], s[54:55], 0, v[130:131]
	s_mov_b32 m0, s57
	s_nop 0
	global_load_lds_dwordx4 v[230:231], off
	v_mfma_f32_16x16x32_bf16 v[0:3], v[186:189], v[224:227], v[0:3]
	v_mfma_f32_16x16x32_bf16 v[4:7], v[176:179], v[224:227], v[4:7]
	s_setprio 0
	s_barrier
; #define PG8_STAGE(bufoff, gbase, voff) do { _Pragma("unroll") for (int _i = 0; _i < 2; ++_i) \
;         __builtin_amdgcn_global_load_lds((const unsigned*)((const char*)(gbase) + (voff)[_i]), (PG8_LAS unsigned*)(lds + (bufoff) + ldsw + _i * 8192), 16, 0, 0); } while (0)
; #define PG8_LDA(dst, b, h) do { _Pragma("unroll") for (int m = 0; m < 4; ++m) _Pragma("unroll") for (int k = 0; k < 2; ++k) dst[m][k] = *(const PG8_LAS bf16x8*)(lds + PG8_SA(b, h) + aoff + m * 2048 + k * 1024); } while (0)
; #define PG8_LDB(dst, b, h) do { _Pragma("unroll") for (int n = 0; n < 2; ++n) _Pragma("unroll") for (int k = 0; k < 2; ++k) dst[n][k] = *(const PG8_LAS bf16x8*)(lds + PG8_SB(b, h) + boff + n * 2048 + k * 1024); } while (0)
; #define PG8_MMA(ai, bj, At, Bt) do { __builtin_amdgcn_s_setprio(1); _Pragma("unroll") for (int m = 0; m < 4; ++m) _Pragma("unroll") for (int n = 0; n < 2; ++n) _Pragma("unroll") for (int k = 0; k < 2; ++k) \
;         acc[ai][bj][m][n] = __builtin_amdgcn_mfma_f32_16x16x32_bf16(Bt[n][k], At[m][k], acc[ai][bj][m][n], 0, 0, 0); __builtin_amdgcn_s_setprio(0); } while (0)
; #define PG8_WAIT_V(n) asm volatile("s_waitcnt vmcnt(" #n ")" ::: "memory")
; #define PG8_WAIT_L(n) asm volatile("s_waitcnt lgkmcnt(" #n ")" ::: "memory")
; #define PG8_BAR __builtin_amdgcn_s_barrier()
; #define PG8_SCHED __builtin_amdgcn_sched_barrier(0)
; template <class Epi, class Sched, bool ALIGN_EPI = false, bool SP2 = false>
; __device__ __forceinline__ void gemm_phase(PG8_LAS unsigned char* lds, const Gemm g, const Sched& S, const Epi& E) {
;     ...
;             PG8_LDB(B0, 1, 0); PG8_LDB(B1, 1, 1); PG8_SCHED; PG8_LDA(At, 1, 0); PG8_STAGE(PG8_SA(0, 1), a2 + hstep, voffA);
;             PG8_WAIT_V(8); PG8_WAIT_L(0); PG8_BAR; PG8_MMA(0, 0, At, B0); PG8_MMA(0, 1, At, B1); PG8_BAR; PG8_SCHED;
	s_add_i32 s3, 0, 0x18000
	v_add_u32_e32 v159, s3, v153
	s_add_i32 s33, 0, 0x1c000
	ds_read_b128 v[144:147], v159
	ds_read_b128 v[148:151], v159 offset:1024
	ds_read_b128 v[160:163], v159 offset:2048
	ds_read_b128 v[168:171], v159 offset:3072
	v_add_u32_e32 v159, s33, v153
	ds_read_b128 v[172:175], v159
	ds_read_b128 v[176:179], v159 offset:1024
	ds_read_b128 v[182:185], v159 offset:2048
	ds_read_b128 v[186:189], v159 offset:3072
	s_add_u32 s14, s54, 0x40000
	s_addc_u32 s15, s55, 0
	s_mov_b32 m0, s58
	v_lshl_add_u64 v[232:233], s[14:15], 0, v[134:135]
	ds_read_b128 v[190:193], v157 offset:32768
	ds_read_b128 v[194:197], v157 offset:33792
	ds_read_b128 v[198:201], v157 offset:34816
	ds_read_b128 v[208:211], v157 offset:35840
	ds_read_b128 v[212:215], v157 offset:36864
	ds_read_b128 v[216:219], v157 offset:37888
	ds_read_b128 v[220:223], v157 offset:38912
	ds_read_b128 v[224:227], v157 offset:39936
	global_load_lds_dwordx4 v[232:233], off
	v_lshl_add_u64 v[232:233], s[14:15], 0, v[130:131]
	s_mov_b32 m0, s59
	s_nop 0
	global_load_lds_dwordx4 v[232:233], off
	s_waitcnt vmcnt(8)
	s_waitcnt lgkmcnt(0)
	s_barrier
	s_setprio 1
	s_waitcnt lgkmcnt(0)
	v_mfma_f32_16x16x32_bf16 v[124:127], v[144:147], v[190:193], v[124:127]
	v_mfma_f32_16x16x32_bf16 v[120:123], v[160:163], v[190:193], v[120:123]
	v_mfma_f32_16x16x32_bf16 v[104:107], v[160:163], v[198:201], v[104:107]
	v_mfma_f32_16x16x32_bf16 v[108:111], v[144:147], v[198:201], v[108:111]
	v_mfma_f32_16x16x32_bf16 v[92:95], v[144:147], v[212:215], v[92:95]
	v_mfma_f32_16x16x32_bf16 v[88:91], v[160:163], v[212:215], v[88:91]
	v_mfma_f32_16x16x32_bf16 v[72:75], v[160:163], v[220:223], v[72:75]
	v_mfma_f32_16x16x32_bf16 v[76:79], v[144:147], v[220:223], v[76:79]
	v_mfma_f32_16x16x32_bf16 v[124:127], v[148:151], v[194:197], v[124:127]
	v_mfma_f32_16x16x32_bf16 v[120:123], v[168:171], v[194:197], v[120:123]
	v_mfma_f32_16x16x32_bf16 v[104:107], v[168:171], v[208:211], v[104:107]
	v_mfma_f32_16x16x32_bf16 v[108:111], v[148:151], v[208:211], v[108:111]
	v_mfma_f32_16x16x32_bf16 v[92:95], v[148:151], v[216:219], v[92:95]
	v_mfma_f32_16x16x32_bf16 v[88:91], v[168:171], v[216:219], v[88:91]
	v_mfma_f32_16x16x32_bf16 v[72:75], v[168:171], v[224:227], v[72:75]
	v_mfma_f32_16x16x32_bf16 v[76:79], v[148:151], v[224:227], v[76:79]
	s_setprio 0
	s_setprio 1
	v_mfma_f32_16x16x32_bf16 v[116:119], v[172:175], v[190:193], v[116:119]
	v_mfma_f32_16x16x32_bf16 v[112:115], v[182:185], v[190:193], v[112:115]
	v_mfma_f32_16x16x32_bf16 v[96:99], v[182:185], v[198:201], v[96:99]
	v_mfma_f32_16x16x32_bf16 v[100:103], v[172:175], v[198:201], v[100:103]
	v_mfma_f32_16x16x32_bf16 v[84:87], v[172:175], v[212:215], v[84:87]
	v_mfma_f32_16x16x32_bf16 v[80:83], v[182:185], v[212:215], v[80:83]
	v_mfma_f32_16x16x32_bf16 v[64:67], v[182:185], v[220:223], v[64:67]
	v_mfma_f32_16x16x32_bf16 v[68:71], v[172:175], v[220:223], v[68:71]
	v_mfma_f32_16x16x32_bf16 v[116:119], v[176:179], v[194:197], v[116:119]
	v_mfma_f32_16x16x32_bf16 v[112:115], v[186:189], v[194:197], v[112:115]
	v_mfma_f32_16x16x32_bf16 v[96:99], v[186:189], v[208:211], v[96:99]
	v_mfma_f32_16x16x32_bf16 v[100:103], v[176:179], v[208:211], v[100:103]
	v_mfma_f32_16x16x32_bf16 v[84:87], v[176:179], v[216:219], v[84:87]
	v_mfma_f32_16x16x32_bf16 v[80:83], v[186:189], v[216:219], v[80:83]
	v_mfma_f32_16x16x32_bf16 v[64:67], v[186:189], v[224:227], v[64:67]
	v_mfma_f32_16x16x32_bf16 v[68:71], v[176:179], v[224:227], v[68:71]
	s_setprio 0
	s_barrier
; #define PG8_STAGE(bufoff, gbase, voff) do { _Pragma("unroll") for (int _i = 0; _i < 2; ++_i) \
;         __builtin_amdgcn_global_load_lds((const unsigned*)((const char*)(gbase) + (voff)[_i]), (PG8_LAS unsigned*)(lds + (bufoff) + ldsw + _i * 8192), 16, 0, 0); } while (0)
; #define PG8_LDA(dst, b, h) do { _Pragma("unroll") for (int m = 0; m < 4; ++m) _Pragma("unroll") for (int k = 0; k < 2; ++k) dst[m][k] = *(const PG8_LAS bf16x8*)(lds + PG8_SA(b, h) + aoff + m * 2048 + k * 1024); } while (0)
; #define PG8_WAIT_V(n) asm volatile("s_waitcnt vmcnt(" #n ")" ::: "memory")
; template <class Epi, class Sched, bool ALIGN_EPI = false, bool SP2 = false>
; __device__ __forceinline__ void gemm_phase(PG8_LAS unsigned char* lds, const Gemm g, const Sched& S, const Epi& E) {
;     ...
;             PG8_LDA(At, 1, 1); PG8_STAGE(PG8_SB(1, 0), b3, voffB); PG8_STAGE(PG8_SB(1, 1), b3 + hstep, voffB); PG8_STAGE(PG8_SA(1, 0), a3, voffA);
;             PG8_WAIT_V(8); PG8_WAIT_L(0); PG8_BAR; PG8_MMA(1, 0, At, B0); PG8_MMA(1, 1, At, B1); PG8_BAR; PG8_SCHED;
;             } else {
;             PG8_LDB(B0, 0, 0); PG8_SCHED; PG8_LDA(At, 0, 0); PG8_STAGE(PG8_SA(1, 1), a1 + hstep, voffA);
;             PG8_WAIT_L(8); PG8_BAR; PG8_WAIT_L(0); PG8_MMA(0, 0, At, B0); PG8_BAR; PG8_SCHED;
;             PG8_LDB(B1, 0, 1); PG8_STAGE(PG8_SB(0, 0), b2, voffB);
;             PG8_BAR; PG8_WAIT_L(0); PG8_MMA(0, 1, At, B1); PG8_BAR;
;             PG8_LDA(At, 0, 1); PG8_STAGE(PG8_SA(0, 0), a2, voffA);
;             PG8_BAR; PG8_WAIT_L(0); PG8_MMA(1, 0, At, B0); PG8_BAR; PG8_SCHED;
;             PG8_STAGE(PG8_SB(0, 1), b2 + hstep, voffB);
;             PG8_WAIT_V(6); PG8_BAR; PG8_MMA(1, 1, At, B1); PG8_BAR;
;             PG8_LDB(B0, 1, 0); PG8_SCHED; PG8_LDA(At, 1, 0); PG8_STAGE(PG8_SA(0, 1), a2 + hstep, voffA);
;             PG8_WAIT_L(8); PG8_BAR; PG8_WAIT_L(0); PG8_MMA(0, 0, At, B0); PG8_BAR; PG8_SCHED;
;             PG8_LDB(B1, 1, 1); PG8_STAGE(PG8_SB(1, 0), b3, voffB);
;             PG8_BAR; PG8_WAIT_L(0); PG8_MMA(0, 1, At, B1); PG8_BAR;
;             PG8_LDA(At, 1, 1); PG8_STAGE(PG8_SA(1, 0), a3, voffA);
;             PG8_BAR; PG8_WAIT_L(0); PG8_MMA(1, 0, At, B0); PG8_BAR; PG8_SCHED;
;             PG8_STAGE(PG8_SB(1, 1), b3 + hstep, voffB);
;             PG8_WAIT_V(6); PG8_BAR; PG8_MMA(1, 1, At, B1); PG8_BAR;
;             }
;         }
;         if constexpr (ALIGN_EPI) { if (wr == 0) PG8_BAR; }
	s_add_i32 s3, s3, s43
	v_lshl_add_u64 v[164:165], v[164:165], 0, s[10:11]
	s_mov_b32 m0, s3
	ds_read_b128 v[190:193], v157 offset:49152
	ds_read_b128 v[194:197], v157 offset:50176
	ds_read_b128 v[198:201], v157 offset:51200
	ds_read_b128 v[208:211], v157 offset:52224
	ds_read_b128 v[212:215], v157 offset:53248
	ds_read_b128 v[216:219], v157 offset:54272
	ds_read_b128 v[220:223], v157 offset:55296
	ds_read_b128 v[224:227], v157 offset:56320
	global_load_lds_dwordx4 v[164:165], off
	s_add_i32 m0, s3, 0x2000
	s_add_u32 s14, s50, 0x40080
	v_lshl_add_u64 v[164:165], v[202:203], 0, s[10:11]
	s_addc_u32 s15, s51, 0
	s_add_i32 s3, s33, s43
	global_load_lds_dwordx4 v[164:165], off
	v_lshl_add_u64 v[164:165], s[14:15], 0, v[132:133]
	s_mov_b32 m0, s3
	s_nop 0
	global_load_lds_dwordx4 v[164:165], off
	v_lshl_add_u64 v[164:165], s[14:15], 0, v[128:129]
	s_add_i32 m0, s3, 0x2000
	s_nop 0
	global_load_lds_dwordx4 v[164:165], off
	s_waitcnt vmcnt(6)
	s_waitcnt lgkmcnt(0)
	s_barrier
	s_setprio 1
	s_waitcnt lgkmcnt(0)
	v_mfma_f32_16x16x32_bf16 v[60:63], v[144:147], v[190:193], v[60:63]
	v_mfma_f32_16x16x32_bf16 v[56:59], v[160:163], v[190:193], v[56:59]
	v_mfma_f32_16x16x32_bf16 v[40:43], v[160:163], v[198:201], v[40:43]
	v_mfma_f32_16x16x32_bf16 v[44:47], v[144:147], v[198:201], v[44:47]
	v_mfma_f32_16x16x32_bf16 v[28:31], v[144:147], v[212:215], v[28:31]
	v_mfma_f32_16x16x32_bf16 v[24:27], v[160:163], v[212:215], v[24:27]
	v_mfma_f32_16x16x32_bf16 v[8:11], v[160:163], v[220:223], v[8:11]
	v_mfma_f32_16x16x32_bf16 v[12:15], v[144:147], v[220:223], v[12:15]
	v_mfma_f32_16x16x32_bf16 v[60:63], v[148:151], v[194:197], v[60:63]
	v_mfma_f32_16x16x32_bf16 v[56:59], v[168:171], v[194:197], v[56:59]
	v_mfma_f32_16x16x32_bf16 v[40:43], v[168:171], v[208:211], v[40:43]
	v_mfma_f32_16x16x32_bf16 v[44:47], v[148:151], v[208:211], v[44:47]
	v_mfma_f32_16x16x32_bf16 v[28:31], v[148:151], v[216:219], v[28:31]
	v_mfma_f32_16x16x32_bf16 v[24:27], v[168:171], v[216:219], v[24:27]
	v_lshl_add_u64 v[164:165], v[228:229], 0, s[10:11]
	s_mov_b32 m0, s61
	s_nop 0
	global_load_lds_dwordx4 v[164:165], off
	v_mfma_f32_16x16x32_bf16 v[8:11], v[168:171], v[224:227], v[8:11]
	v_mfma_f32_16x16x32_bf16 v[12:15], v[148:151], v[224:227], v[12:15]
	s_setprio 0
	s_setprio 1
	v_mfma_f32_16x16x32_bf16 v[52:55], v[172:175], v[190:193], v[52:55]
	v_mfma_f32_16x16x32_bf16 v[48:51], v[182:185], v[190:193], v[48:51]
	v_mfma_f32_16x16x32_bf16 v[32:35], v[182:185], v[198:201], v[32:35]
	v_mfma_f32_16x16x32_bf16 v[36:39], v[172:175], v[198:201], v[36:39]
	v_mfma_f32_16x16x32_bf16 v[20:23], v[172:175], v[212:215], v[20:23]
	v_mfma_f32_16x16x32_bf16 v[16:19], v[182:185], v[212:215], v[16:19]
	v_mfma_f32_16x16x32_bf16 v[0:3], v[182:185], v[220:223], v[0:3]
	v_mfma_f32_16x16x32_bf16 v[4:7], v[172:175], v[220:223], v[4:7]
	v_mfma_f32_16x16x32_bf16 v[52:55], v[176:179], v[194:197], v[52:55]
	v_mfma_f32_16x16x32_bf16 v[48:51], v[186:189], v[194:197], v[48:51]
	v_mfma_f32_16x16x32_bf16 v[32:35], v[186:189], v[208:211], v[32:35]
	v_mfma_f32_16x16x32_bf16 v[36:39], v[176:179], v[208:211], v[36:39]
	v_mfma_f32_16x16x32_bf16 v[20:23], v[176:179], v[216:219], v[20:23]
	v_mfma_f32_16x16x32_bf16 v[16:19], v[186:189], v[216:219], v[16:19]
	v_lshl_add_u64 v[164:165], v[230:231], 0, s[10:11]
	s_mov_b32 m0, s62
	s_nop 0
	global_load_lds_dwordx4 v[164:165], off
	v_mfma_f32_16x16x32_bf16 v[0:3], v[186:189], v[224:227], v[0:3]
	v_mfma_f32_16x16x32_bf16 v[4:7], v[176:179], v[224:227], v[4:7]
	s_setprio 0
	s_barrier
	s_add_i32 s89, s89, 2
	s_add_u32 s48, s48, 0x100
	s_addc_u32 s49, s49, 0
	s_add_u32 s87, s87, 0x100
	s_addc_u32 s88, s88, 0
	s_cmp_gt_u32 s89, 13
	s_cbranch_scc0 .LBB0_191
	v_lshl_add_u32 v144, s44, 8, v152
	v_ashrrev_i32_e32 v145, 31, v144
	v_lshl_add_u64 v[150:151], v[144:145], 3, s[6:7]
	global_load_dwordx2 v[182:183], v[150:151], off
	global_load_dwordx2 v[184:185], v[150:151], off offset:128
	global_load_dwordx2 v[186:187], v[150:151], off offset:256
	global_load_dwordx2 v[188:189], v[150:151], off offset:384
	global_load_dwordx2 v[190:191], v[150:151], off offset:1024
	global_load_dwordx2 v[192:193], v[150:151], off offset:1152
	global_load_dwordx2 v[194:195], v[150:151], off offset:1280
	global_load_dwordx2 v[196:197], v[150:151], off offset:1408
	s_and_b64 vcc, exec, s[16:17]
	s_cbranch_vccz .LBB0_194
	s_barrier

; #define PG8_STAGE(bufoff, gbase, voff) do { _Pragma("unroll") for (int _i = 0; _i < 2; ++_i) \
;         __builtin_amdgcn_global_load_lds((const unsigned*)((const char*)(gbase) + (voff)[_i]), (PG8_LAS unsigned*)(lds + (bufoff) + ldsw + _i * 8192), 16, 0, 0); } while (0)
; #define PG8_LDA(dst, b, h) do { _Pragma("unroll") for (int m = 0; m < 4; ++m) _Pragma("unroll") for (int k = 0; k < 2; ++k) dst[m][k] = *(const PG8_LAS bf16x8*)(lds + PG8_SA(b, h) + aoff + m * 2048 + k * 1024); } while (0)
; #define PG8_LDB(dst, b, h) do { _Pragma("unroll") for (int n = 0; n < 2; ++n) _Pragma("unroll") for (int k = 0; k < 2; ++k) dst[n][k] = *(const PG8_LAS bf16x8*)(lds + PG8_SB(b, h) + boff + n * 2048 + k * 1024); } while (0)
; #define PG8_WAIT_V(n) asm volatile("s_waitcnt vmcnt(" #n ")" ::: "memory")
; #define PG8_WAIT_L(n) asm volatile("s_waitcnt lgkmcnt(" #n ")" ::: "memory")
; #define PG8_BAR __builtin_amdgcn_s_barrier()
; #define PG8_SCHED __builtin_amdgcn_sched_barrier(0)
; template <class Epi, class Sched, bool ALIGN_EPI = false, bool SP2 = false>
; __device__ __forceinline__ void gemm_phase(PG8_LAS unsigned char* lds, const Gemm g, const Sched& S, const Epi& E) {
;     ...
;         const bool has_next = S.next(ui + 1, nxt);
;         const char* nA = has_next ? (const char*)g.A + (size_t)nxt.pm * tstep : cA; const char* nB = has_next ? (const char*)g.Bt + (size_t)nxt.pn * tstep : cB;
;         for (int t = 0; t < nt; t += 2) {
;             const bool last = (t == nt - 2);
;             const char* a1 = cA + (size_t)(t + 1) * kstep;
;             const char* a2 = last ? nA : cA + (size_t)(t + 2) * kstep; const char* b2 = last ? nB : cB + (size_t)(t + 2) * kstep;
;             const char* a3 = a2 + kstep; const char* b3 = b2 + kstep;
;             if (last && has_next) S.a_ready(nxt);
;             if constexpr (SP2) {
;             PG8_LDB(B0, 0, 0); PG8_LDB(B1, 0, 1); PG8_SCHED; PG8_LDA(At, 0, 0); PG8_STAGE(PG8_SA(1, 1), a1 + hstep, voffA);
;             PG8_WAIT_V(8); PG8_WAIT_L(0); PG8_BAR; PG8_MMA(0, 0, At, B0); PG8_MMA(0, 1, At, B1); PG8_BAR; PG8_SCHED;
;             PG8_LDA(At, 0, 1); PG8_STAGE(PG8_SB(0, 0), b2, voffB); PG8_STAGE(PG8_SB(0, 1), b2 + hstep, voffB); PG8_STAGE(PG8_SA(0, 0), a2, voffA);
;             PG8_WAIT_V(8); PG8_WAIT_L(0); PG8_BAR; PG8_MMA(1, 0, At, B0); PG8_MMA(1, 1, At, B1); PG8_BAR; PG8_SCHED;
.LBB0_268:
	s_add_u32 s91, s50, 0x100
	s_addc_u32 s92, s51, 0
	s_mov_b32 s93, -2
	s_waitcnt lgkmcnt(0)
	ds_read_b128 v[128:131], v165
	ds_read_b128 v[132:135], v165 offset:1024
	ds_read_b128 v[152:155], v165 offset:2048
	ds_read_b128 v[156:159], v165 offset:3072
	ds_read_b128 v[172:175], v168
	ds_read_b128 v[176:179], v168 offset:1024
	ds_read_b128 v[182:185], v168 offset:2048
	ds_read_b128 v[186:189], v168 offset:3072
	s_add_u32 s50, s10, 0x100
	s_addc_u32 s51, s11, 0
	s_cmp_eq_u32 s93, 40
	s_cselect_b32 s57, s1, s51
	s_cselect_b32 s56, s0, s50
	s_cselect_b32 s55, s49, s92
	s_cselect_b32 s54, s48, s91
	v_lshl_add_u64 v[160:161], s[10:11], 0, v[144:145]
	s_add_i32 m0, s58, 0xc000
	ds_read_b128 v[190:193], v169
	ds_read_b128 v[194:197], v169 offset:1024
	ds_read_b128 v[198:201], v169 offset:2048
	ds_read_b128 v[208:211], v169 offset:3072
	ds_read_b128 v[212:215], v169 offset:4096
	ds_read_b128 v[216:219], v169 offset:5120
	ds_read_b128 v[220:223], v169 offset:6144
	ds_read_b128 v[224:227], v169 offset:7168
	global_load_lds_dwordx4 v[160:161], off
	v_lshl_add_u64 v[160:161], s[10:11], 0, v[146:147]
	s_add_i32 m0, s58, 0xe000
	s_nop 0
	global_load_lds_dwordx4 v[160:161], off
	s_waitcnt vmcnt(8)
	s_waitcnt lgkmcnt(0)
	s_barrier
	s_setprio 1
	s_waitcnt lgkmcnt(0)
	v_mfma_f32_16x16x32_bf16 v[124:127], v[128:131], v[190:193], 0
	v_mfma_f32_16x16x32_bf16 v[120:123], v[152:155], v[190:193], 0
	v_mfma_f32_16x16x32_bf16 v[104:107], v[152:155], v[198:201], 0
	v_mfma_f32_16x16x32_bf16 v[108:111], v[128:131], v[198:201], 0
	v_mfma_f32_16x16x32_bf16 v[92:95], v[128:131], v[212:215], 0
	v_mfma_f32_16x16x32_bf16 v[88:91], v[152:155], v[212:215], 0
	v_mfma_f32_16x16x32_bf16 v[72:75], v[152:155], v[220:223], 0
	v_mfma_f32_16x16x32_bf16 v[76:79], v[128:131], v[220:223], 0
	v_mfma_f32_16x16x32_bf16 v[124:127], v[132:135], v[194:197], v[124:127]
	v_mfma_f32_16x16x32_bf16 v[120:123], v[156:159], v[194:197], v[120:123]
	v_mfma_f32_16x16x32_bf16 v[104:107], v[156:159], v[208:211], v[104:107]
	v_mfma_f32_16x16x32_bf16 v[108:111], v[132:135], v[208:211], v[108:111]
	v_mfma_f32_16x16x32_bf16 v[92:95], v[132:135], v[216:219], v[92:95]
	v_mfma_f32_16x16x32_bf16 v[88:91], v[156:159], v[216:219], v[88:91]
	v_mfma_f32_16x16x32_bf16 v[72:75], v[156:159], v[224:227], v[72:75]
	v_mfma_f32_16x16x32_bf16 v[76:79], v[132:135], v[224:227], v[76:79]
	s_setprio 0
	s_setprio 1
	v_mfma_f32_16x16x32_bf16 v[116:119], v[172:175], v[190:193], 0
	v_mfma_f32_16x16x32_bf16 v[112:115], v[182:185], v[190:193], 0
	v_mfma_f32_16x16x32_bf16 v[96:99], v[182:185], v[198:201], 0
	v_mfma_f32_16x16x32_bf16 v[100:103], v[172:175], v[198:201], 0
	v_mfma_f32_16x16x32_bf16 v[84:87], v[172:175], v[212:215], 0
	v_mfma_f32_16x16x32_bf16 v[80:83], v[182:185], v[212:215], 0
	v_mfma_f32_16x16x32_bf16 v[64:67], v[182:185], v[220:223], 0
	v_mfma_f32_16x16x32_bf16 v[68:71], v[172:175], v[220:223], 0
	v_mfma_f32_16x16x32_bf16 v[116:119], v[176:179], v[194:197], v[116:119]
	v_mfma_f32_16x16x32_bf16 v[112:115], v[186:189], v[194:197], v[112:115]
	v_mfma_f32_16x16x32_bf16 v[96:99], v[186:189], v[208:211], v[96:99]
	v_mfma_f32_16x16x32_bf16 v[100:103], v[176:179], v[208:211], v[100:103]
	v_mfma_f32_16x16x32_bf16 v[84:87], v[176:179], v[216:219], v[84:87]
	v_mfma_f32_16x16x32_bf16 v[80:83], v[186:189], v[216:219], v[80:83]
	v_mfma_f32_16x16x32_bf16 v[64:67], v[186:189], v[224:227], v[64:67]
	v_mfma_f32_16x16x32_bf16 v[68:71], v[176:179], v[224:227], v[68:71]
	s_setprio 0
	s_barrier
	s_add_i32 s3, s65, s43
	v_lshl_add_u64 v[160:161], s[54:55], 0, v[138:139]
	s_mov_b32 m0, s3
	ds_read_b128 v[190:193], v169 offset:16384
	ds_read_b128 v[194:197], v169 offset:17408
	ds_read_b128 v[198:201], v169 offset:18432
	ds_read_b128 v[208:211], v169 offset:19456
	ds_read_b128 v[212:215], v169 offset:20480
	ds_read_b128 v[216:219], v169 offset:21504
	ds_read_b128 v[220:223], v169 offset:22528
	ds_read_b128 v[224:227], v169 offset:23552
	global_load_lds_dwordx4 v[160:161], off
	s_add_i32 m0, s3, 0x2000
	s_add_u32 s10, s54, 0xb0000
	v_lshl_add_u64 v[202:203], s[54:55], 0, v[142:143]
	s_addc_u32 s11, s55, 0
	s_add_i32 s3, s66, s43
	global_load_lds_dwordx4 v[202:203], off
	v_lshl_add_u64 v[228:229], s[10:11], 0, v[138:139]
	s_mov_b32 m0, s3
	global_load_lds_dwordx4 v[228:229], off
	v_lshl_add_u64 v[228:229], s[10:11], 0, v[142:143]
	s_add_i32 m0, s3, 0x2000
	s_nop 0
	global_load_lds_dwordx4 v[228:229], off
	s_waitcnt vmcnt(6)
	s_waitcnt lgkmcnt(0)
	s_barrier
; #define PG8_STAGE(bufoff, gbase, voff) do { _Pragma("unroll") for (int _i = 0; _i < 2; ++_i) \
;         __builtin_amdgcn_global_load_lds((const unsigned*)((const char*)(gbase) + (voff)[_i]), (PG8_LAS unsigned*)(lds + (bufoff) + ldsw + _i * 8192), 16, 0, 0); } while (0)
; #define PG8_LDA(dst, b, h) do { _Pragma("unroll") for (int m = 0; m < 4; ++m) _Pragma("unroll") for (int k = 0; k < 2; ++k) dst[m][k] = *(const PG8_LAS bf16x8*)(lds + PG8_SA(b, h) + aoff + m * 2048 + k * 1024); } while (0)
; #define PG8_LDB(dst, b, h) do { _Pragma("unroll") for (int n = 0; n < 2; ++n) _Pragma("unroll") for (int k = 0; k < 2; ++k) dst[n][k] = *(const PG8_LAS bf16x8*)(lds + PG8_SB(b, h) + boff + n * 2048 + k * 1024); } while (0)
; #define PG8_MMA(ai, bj, At, Bt) do { __builtin_amdgcn_s_setprio(1); _Pragma("unroll") for (int m = 0; m < 4; ++m) _Pragma("unroll") for (int n = 0; n < 2; ++n) _Pragma("unroll") for (int k = 0; k < 2; ++k) \
;         acc[ai][bj][m][n] = __builtin_amdgcn_mfma_f32_16x16x32_bf16(Bt[n][k], At[m][k], acc[ai][bj][m][n], 0, 0, 0); __builtin_amdgcn_s_setprio(0); } while (0)
; #define PG8_WAIT_V(n) asm volatile("s_waitcnt vmcnt(" #n ")" ::: "memory")
; #define PG8_WAIT_L(n) asm volatile("s_waitcnt lgkmcnt(" #n ")" ::: "memory")
; #define PG8_BAR __builtin_amdgcn_s_barrier()
; #define PG8_SCHED __builtin_amdgcn_sched_barrier(0)
; template <class Epi, class Sched, bool ALIGN_EPI = false, bool SP2 = false>
; __device__ __forceinline__ void gemm_phase(PG8_LAS unsigned char* lds, const Gemm g, const Sched& S, const Epi& E) {
;     ...
;             PG8_WAIT_V(8); PG8_WAIT_L(0); PG8_BAR; PG8_MMA(0, 0, At, B0); PG8_MMA(0, 1, At, B1); PG8_BAR; PG8_SCHED;
;             PG8_LDA(At, 0, 1); PG8_STAGE(PG8_SB(0, 0), b2, voffB); PG8_STAGE(PG8_SB(0, 1), b2 + hstep, voffB); PG8_STAGE(PG8_SA(0, 0), a2, voffA);
;             PG8_WAIT_V(8); PG8_WAIT_L(0); PG8_BAR; PG8_MMA(1, 0, At, B0); PG8_MMA(1, 1, At, B1); PG8_BAR; PG8_SCHED;
;             PG8_LDB(B0, 1, 0); PG8_LDB(B1, 1, 1); PG8_SCHED; PG8_LDA(At, 1, 0); PG8_STAGE(PG8_SA(0, 1), a2 + hstep, voffA);
;             PG8_WAIT_V(8); PG8_WAIT_L(0); PG8_BAR; PG8_MMA(0, 0, At, B0); PG8_MMA(0, 1, At, B1); PG8_BAR; PG8_SCHED;
	s_setprio 1
	s_waitcnt lgkmcnt(0)
	v_mfma_f32_16x16x32_bf16 v[60:63], v[128:131], v[190:193], 0
	v_mfma_f32_16x16x32_bf16 v[56:59], v[152:155], v[190:193], 0
	v_mfma_f32_16x16x32_bf16 v[40:43], v[152:155], v[198:201], 0
	v_mfma_f32_16x16x32_bf16 v[44:47], v[128:131], v[198:201], 0
	v_mfma_f32_16x16x32_bf16 v[28:31], v[128:131], v[212:215], 0
	v_mfma_f32_16x16x32_bf16 v[24:27], v[152:155], v[212:215], 0
	v_mfma_f32_16x16x32_bf16 v[8:11], v[152:155], v[220:223], 0
	v_mfma_f32_16x16x32_bf16 v[12:15], v[128:131], v[220:223], 0
	v_mfma_f32_16x16x32_bf16 v[60:63], v[132:135], v[194:197], v[60:63]
	v_mfma_f32_16x16x32_bf16 v[56:59], v[156:159], v[194:197], v[56:59]
	v_mfma_f32_16x16x32_bf16 v[40:43], v[156:159], v[208:211], v[40:43]
	v_mfma_f32_16x16x32_bf16 v[44:47], v[132:135], v[208:211], v[44:47]
	v_mfma_f32_16x16x32_bf16 v[28:31], v[132:135], v[216:219], v[28:31]
	v_mfma_f32_16x16x32_bf16 v[24:27], v[156:159], v[216:219], v[24:27]
	v_lshl_add_u64 v[228:229], s[56:57], 0, v[136:137]
	s_mov_b32 m0, s58
	s_nop 0
	global_load_lds_dwordx4 v[228:229], off
	v_mfma_f32_16x16x32_bf16 v[8:11], v[156:159], v[224:227], v[8:11]
	v_mfma_f32_16x16x32_bf16 v[12:15], v[132:135], v[224:227], v[12:15]
	s_setprio 0
	s_setprio 1
	v_mfma_f32_16x16x32_bf16 v[52:55], v[172:175], v[190:193], 0
	v_mfma_f32_16x16x32_bf16 v[48:51], v[182:185], v[190:193], 0
	v_mfma_f32_16x16x32_bf16 v[32:35], v[182:185], v[198:201], 0
	v_mfma_f32_16x16x32_bf16 v[36:39], v[172:175], v[198:201], 0
	v_mfma_f32_16x16x32_bf16 v[20:23], v[172:175], v[212:215], 0
	v_mfma_f32_16x16x32_bf16 v[16:19], v[182:185], v[212:215], 0
	v_mfma_f32_16x16x32_bf16 v[0:3], v[182:185], v[220:223], 0
	v_mfma_f32_16x16x32_bf16 v[4:7], v[172:175], v[220:223], 0
	v_mfma_f32_16x16x32_bf16 v[52:55], v[176:179], v[194:197], v[52:55]
	v_mfma_f32_16x16x32_bf16 v[48:51], v[186:189], v[194:197], v[48:51]
	v_mfma_f32_16x16x32_bf16 v[32:35], v[186:189], v[208:211], v[32:35]
	v_mfma_f32_16x16x32_bf16 v[36:39], v[176:179], v[208:211], v[36:39]
	v_mfma_f32_16x16x32_bf16 v[20:23], v[176:179], v[216:219], v[20:23]
	v_mfma_f32_16x16x32_bf16 v[16:19], v[186:189], v[216:219], v[16:19]
	v_lshl_add_u64 v[230:231], s[56:57], 0, v[140:141]
	s_mov_b32 m0, s59
	s_nop 0
	global_load_lds_dwordx4 v[230:231], off
	v_mfma_f32_16x16x32_bf16 v[0:3], v[186:189], v[224:227], v[0:3]
	v_mfma_f32_16x16x32_bf16 v[4:7], v[176:179], v[224:227], v[4:7]
	s_setprio 0
	s_barrier
	s_add_i32 s3, 0, 0x18000
	s_add_i32 s14, 0, 0x1c000
	v_add_u32_e32 v156, s3, v163
	v_add_u32_e32 v171, s14, v163
	ds_read_b128 v[128:131], v156
	ds_read_b128 v[132:135], v156 offset:1024
	ds_read_b128 v[152:155], v156 offset:2048
	ds_read_b128 v[156:159], v156 offset:3072
	ds_read_b128 v[172:175], v171
	ds_read_b128 v[176:179], v171 offset:1024
	ds_read_b128 v[182:185], v171 offset:2048
	ds_read_b128 v[186:189], v171 offset:3072
	s_add_u32 s10, s56, 0xb0000
	s_addc_u32 s11, s57, 0
	s_mov_b32 m0, s60
	v_lshl_add_u64 v[232:233], s[10:11], 0, v[136:137]
	ds_read_b128 v[190:193], v169 offset:32768
	ds_read_b128 v[194:197], v169 offset:33792
	ds_read_b128 v[198:201], v169 offset:34816
	ds_read_b128 v[208:211], v169 offset:35840
	ds_read_b128 v[212:215], v169 offset:36864
	ds_read_b128 v[216:219], v169 offset:37888
	ds_read_b128 v[220:223], v169 offset:38912
	ds_read_b128 v[224:227], v169 offset:39936
	global_load_lds_dwordx4 v[232:233], off
	v_lshl_add_u64 v[232:233], s[10:11], 0, v[140:141]
	s_mov_b32 m0, s61
	s_nop 0
	global_load_lds_dwordx4 v[232:233], off
	s_waitcnt vmcnt(8)
	s_waitcnt lgkmcnt(0)
	s_barrier
	s_setprio 1
	s_waitcnt lgkmcnt(0)
	v_mfma_f32_16x16x32_bf16 v[124:127], v[128:131], v[190:193], v[124:127]
	v_mfma_f32_16x16x32_bf16 v[120:123], v[152:155], v[190:193], v[120:123]
	v_mfma_f32_16x16x32_bf16 v[104:107], v[152:155], v[198:201], v[104:107]
	v_mfma_f32_16x16x32_bf16 v[108:111], v[128:131], v[198:201], v[108:111]
	v_mfma_f32_16x16x32_bf16 v[92:95], v[128:131], v[212:215], v[92:95]
	v_mfma_f32_16x16x32_bf16 v[88:91], v[152:155], v[212:215], v[88:91]
	v_mfma_f32_16x16x32_bf16 v[72:75], v[152:155], v[220:223], v[72:75]
	v_mfma_f32_16x16x32_bf16 v[76:79], v[128:131], v[220:223], v[76:79]
	v_mfma_f32_16x16x32_bf16 v[124:127], v[132:135], v[194:197], v[124:127]
	v_mfma_f32_16x16x32_bf16 v[120:123], v[156:159], v[194:197], v[120:123]
	v_mfma_f32_16x16x32_bf16 v[104:107], v[156:159], v[208:211], v[104:107]
	v_mfma_f32_16x16x32_bf16 v[108:111], v[132:135], v[208:211], v[108:111]
	v_mfma_f32_16x16x32_bf16 v[92:95], v[132:135], v[216:219], v[92:95]
	v_mfma_f32_16x16x32_bf16 v[88:91], v[156:159], v[216:219], v[88:91]
	v_mfma_f32_16x16x32_bf16 v[72:75], v[156:159], v[224:227], v[72:75]
	v_mfma_f32_16x16x32_bf16 v[76:79], v[132:135], v[224:227], v[76:79]
	s_setprio 0
	s_setprio 1
	v_mfma_f32_16x16x32_bf16 v[116:119], v[172:175], v[190:193], v[116:119]
	v_mfma_f32_16x16x32_bf16 v[112:115], v[182:185], v[190:193], v[112:115]
	v_mfma_f32_16x16x32_bf16 v[96:99], v[182:185], v[198:201], v[96:99]
	v_mfma_f32_16x16x32_bf16 v[100:103], v[172:175], v[198:201], v[100:103]
	v_mfma_f32_16x16x32_bf16 v[84:87], v[172:175], v[212:215], v[84:87]
	v_mfma_f32_16x16x32_bf16 v[80:83], v[182:185], v[212:215], v[80:83]
	v_mfma_f32_16x16x32_bf16 v[64:67], v[182:185], v[220:223], v[64:67]
	v_mfma_f32_16x16x32_bf16 v[68:71], v[172:175], v[220:223], v[68:71]
	v_mfma_f32_16x16x32_bf16 v[116:119], v[176:179], v[194:197], v[116:119]
	v_mfma_f32_16x16x32_bf16 v[112:115], v[186:189], v[194:197], v[112:115]
	v_mfma_f32_16x16x32_bf16 v[96:99], v[186:189], v[208:211], v[96:99]
	v_mfma_f32_16x16x32_bf16 v[100:103], v[176:179], v[208:211], v[100:103]
	v_mfma_f32_16x16x32_bf16 v[84:87], v[176:179], v[216:219], v[84:87]
	v_mfma_f32_16x16x32_bf16 v[80:83], v[186:189], v[216:219], v[80:83]
	v_mfma_f32_16x16x32_bf16 v[64:67], v[186:189], v[224:227], v[64:67]
	v_mfma_f32_16x16x32_bf16 v[68:71], v[176:179], v[224:227], v[68:71]
	s_setprio 0
	s_barrier
; #define PG8_STAGE(bufoff, gbase, voff) do { _Pragma("unroll") for (int _i = 0; _i < 2; ++_i) \
;         __builtin_amdgcn_global_load_lds((const unsigned*)((const char*)(gbase) + (voff)[_i]), (PG8_LAS unsigned*)(lds + (bufoff) + ldsw + _i * 8192), 16, 0, 0); } while (0)
; #define PG8_LDA(dst, b, h) do { _Pragma("unroll") for (int m = 0; m < 4; ++m) _Pragma("unroll") for (int k = 0; k < 2; ++k) dst[m][k] = *(const PG8_LAS bf16x8*)(lds + PG8_SA(b, h) + aoff + m * 2048 + k * 1024); } while (0)
; #define PG8_LDB(dst, b, h) do { _Pragma("unroll") for (int n = 0; n < 2; ++n) _Pragma("unroll") for (int k = 0; k < 2; ++k) dst[n][k] = *(const PG8_LAS bf16x8*)(lds + PG8_SB(b, h) + boff + n * 2048 + k * 1024); } while (0)
; #define PG8_MMA(ai, bj, At, Bt) do { __builtin_amdgcn_s_setprio(1); _Pragma("unroll") for (int m = 0; m < 4; ++m) _Pragma("unroll") for (int n = 0; n < 2; ++n) _Pragma("unroll") for (int k = 0; k < 2; ++k) \
;         acc[ai][bj][m][n] = __builtin_amdgcn_mfma_f32_16x16x32_bf16(Bt[n][k], At[m][k], acc[ai][bj][m][n], 0, 0, 0); __builtin_amdgcn_s_setprio(0); } while (0)
; #define PG8_WAIT_V(n) asm volatile("s_waitcnt vmcnt(" #n ")" ::: "memory")
; template <class Epi, class Sched, bool ALIGN_EPI = false, bool SP2 = false>
; __device__ __forceinline__ void gemm_phase(PG8_LAS unsigned char* lds, const Gemm g, const Sched& S, const Epi& E) {
;     ...
;             PG8_LDB(B0, 0, 0); PG8_LDB(B1, 0, 1); PG8_SCHED; PG8_LDA(At, 0, 0); PG8_STAGE(PG8_SA(1, 1), a1 + hstep, voffA);
;             PG8_WAIT_V(8); PG8_WAIT_L(0); PG8_BAR; PG8_MMA(0, 0, At, B0); PG8_MMA(0, 1, At, B1); PG8_BAR; PG8_SCHED;
;             PG8_LDA(At, 0, 1); PG8_STAGE(PG8_SB(0, 0), b2, voffB); PG8_STAGE(PG8_SB(0, 1), b2 + hstep, voffB); PG8_STAGE(PG8_SA(0, 0), a2, voffA);
;             PG8_WAIT_V(8); PG8_WAIT_L(0); PG8_BAR; PG8_MMA(1, 0, At, B0); PG8_MMA(1, 1, At, B1); PG8_BAR; PG8_SCHED;
;             PG8_LDB(B0, 1, 0); PG8_LDB(B1, 1, 1); PG8_SCHED; PG8_LDA(At, 1, 0); PG8_STAGE(PG8_SA(0, 1), a2 + hstep, voffA);
;             PG8_WAIT_V(8); PG8_WAIT_L(0); PG8_BAR; PG8_MMA(0, 0, At, B0); PG8_MMA(0, 1, At, B1); PG8_BAR; PG8_SCHED;
;             PG8_LDA(At, 1, 1); PG8_STAGE(PG8_SB(1, 0), b3, voffB); PG8_STAGE(PG8_SB(1, 1), b3 + hstep, voffB); PG8_STAGE(PG8_SA(1, 0), a3, voffA);
;             PG8_WAIT_V(8); PG8_WAIT_L(0); PG8_BAR; PG8_MMA(1, 0, At, B0); PG8_MMA(1, 1, At, B1); PG8_BAR; PG8_SCHED;
	s_add_i32 s3, s3, s43
	v_lshl_add_u64 v[160:161], v[160:161], 0, s[40:41]
	s_mov_b32 m0, s3
	ds_read_b128 v[190:193], v169 offset:49152
	ds_read_b128 v[194:197], v169 offset:50176
	ds_read_b128 v[198:201], v169 offset:51200
	ds_read_b128 v[208:211], v169 offset:52224
	ds_read_b128 v[212:215], v169 offset:53248
	ds_read_b128 v[216:219], v169 offset:54272
	ds_read_b128 v[220:223], v169 offset:55296
	ds_read_b128 v[224:227], v169 offset:56320
	global_load_lds_dwordx4 v[160:161], off
	s_add_i32 m0, s3, 0x2000
	s_add_u32 s10, s54, 0xb0080
	v_lshl_add_u64 v[160:161], v[202:203], 0, s[40:41]
	s_addc_u32 s11, s55, 0
	s_add_i32 s3, s14, s43
	global_load_lds_dwordx4 v[160:161], off
	v_lshl_add_u64 v[160:161], s[10:11], 0, v[138:139]
	s_mov_b32 m0, s3
	s_nop 0
	global_load_lds_dwordx4 v[160:161], off
	v_lshl_add_u64 v[160:161], s[10:11], 0, v[142:143]
	s_add_i32 m0, s3, 0x2000
	s_nop 0
	global_load_lds_dwordx4 v[160:161], off
	s_waitcnt vmcnt(6)
	s_waitcnt lgkmcnt(0)
	s_barrier
	s_setprio 1
	s_waitcnt lgkmcnt(0)
	v_mfma_f32_16x16x32_bf16 v[60:63], v[128:131], v[190:193], v[60:63]
	v_mfma_f32_16x16x32_bf16 v[56:59], v[152:155], v[190:193], v[56:59]
	v_mfma_f32_16x16x32_bf16 v[40:43], v[152:155], v[198:201], v[40:43]
	v_mfma_f32_16x16x32_bf16 v[44:47], v[128:131], v[198:201], v[44:47]
	v_mfma_f32_16x16x32_bf16 v[28:31], v[128:131], v[212:215], v[28:31]
	v_mfma_f32_16x16x32_bf16 v[24:27], v[152:155], v[212:215], v[24:27]
	v_mfma_f32_16x16x32_bf16 v[8:11], v[152:155], v[220:223], v[8:11]
	v_mfma_f32_16x16x32_bf16 v[12:15], v[128:131], v[220:223], v[12:15]
	v_mfma_f32_16x16x32_bf16 v[60:63], v[132:135], v[194:197], v[60:63]
	v_mfma_f32_16x16x32_bf16 v[56:59], v[156:159], v[194:197], v[56:59]
	v_mfma_f32_16x16x32_bf16 v[40:43], v[156:159], v[208:211], v[40:43]
	v_mfma_f32_16x16x32_bf16 v[44:47], v[132:135], v[208:211], v[44:47]
	v_mfma_f32_16x16x32_bf16 v[28:31], v[132:135], v[216:219], v[28:31]
	v_mfma_f32_16x16x32_bf16 v[24:27], v[156:159], v[216:219], v[24:27]
	v_lshl_add_u64 v[160:161], v[228:229], 0, s[40:41]
	s_mov_b32 m0, s63
	s_nop 0
	global_load_lds_dwordx4 v[160:161], off
	v_mfma_f32_16x16x32_bf16 v[8:11], v[156:159], v[224:227], v[8:11]
	v_mfma_f32_16x16x32_bf16 v[12:15], v[132:135], v[224:227], v[12:15]
	s_setprio 0
	s_setprio 1
	v_mfma_f32_16x16x32_bf16 v[52:55], v[172:175], v[190:193], v[52:55]
	v_mfma_f32_16x16x32_bf16 v[48:51], v[182:185], v[190:193], v[48:51]
	v_mfma_f32_16x16x32_bf16 v[32:35], v[182:185], v[198:201], v[32:35]
	v_mfma_f32_16x16x32_bf16 v[36:39], v[172:175], v[198:201], v[36:39]
	v_mfma_f32_16x16x32_bf16 v[20:23], v[172:175], v[212:215], v[20:23]
	v_mfma_f32_16x16x32_bf16 v[16:19], v[182:185], v[212:215], v[16:19]
	v_mfma_f32_16x16x32_bf16 v[0:3], v[182:185], v[220:223], v[0:3]
	v_mfma_f32_16x16x32_bf16 v[4:7], v[172:175], v[220:223], v[4:7]
	v_mfma_f32_16x16x32_bf16 v[52:55], v[176:179], v[194:197], v[52:55]
	v_mfma_f32_16x16x32_bf16 v[48:51], v[186:189], v[194:197], v[48:51]
	v_mfma_f32_16x16x32_bf16 v[32:35], v[186:189], v[208:211], v[32:35]
	v_mfma_f32_16x16x32_bf16 v[36:39], v[176:179], v[208:211], v[36:39]
	v_mfma_f32_16x16x32_bf16 v[20:23], v[176:179], v[216:219], v[20:23]
	v_mfma_f32_16x16x32_bf16 v[16:19], v[186:189], v[216:219], v[16:19]
	v_lshl_add_u64 v[160:161], v[230:231], 0, s[40:41]
	s_mov_b32 m0, s64
	s_nop 0
	global_load_lds_dwordx4 v[160:161], off
	v_mfma_f32_16x16x32_bf16 v[0:3], v[186:189], v[224:227], v[0:3]
	v_mfma_f32_16x16x32_bf16 v[4:7], v[176:179], v[224:227], v[4:7]
	s_setprio 0
	s_barrier
	s_add_i32 s93, s93, 2
	s_add_u32 s91, s91, 0x100
	s_addc_u32 s92, s92, 0
	s_mov_b64 s[10:11], s[50:51]
.LBB0_269:
	ds_read_b128 v[128:131], v165
	ds_read_b128 v[132:135], v165 offset:1024
	ds_read_b128 v[152:155], v165 offset:2048
	ds_read_b128 v[156:159], v165 offset:3072
	ds_read_b128 v[172:175], v168
	ds_read_b128 v[176:179], v168 offset:1024
	ds_read_b128 v[182:185], v168 offset:2048
	ds_read_b128 v[186:189], v168 offset:3072
	s_add_u32 s50, s10, 0x100
	s_addc_u32 s51, s11, 0
	s_cmp_eq_u32 s93, 40
	s_cselect_b32 s57, s1, s51
	s_cselect_b32 s56, s0, s50
	s_cselect_b32 s55, s49, s92
	s_cselect_b32 s54, s48, s91
	v_lshl_add_u64 v[160:161], s[10:11], 0, v[144:145]
	s_add_i32 m0, s58, 0xc000
	ds_read_b128 v[190:193], v169
	ds_read_b128 v[194:197], v169 offset:1024
	ds_read_b128 v[198:201], v169 offset:2048
	ds_read_b128 v[208:211], v169 offset:3072
	ds_read_b128 v[212:215], v169 offset:4096
	ds_read_b128 v[216:219], v169 offset:5120
	ds_read_b128 v[220:223], v169 offset:6144
	ds_read_b128 v[224:227], v169 offset:7168
	global_load_lds_dwordx4 v[160:161], off
	v_lshl_add_u64 v[160:161], s[10:11], 0, v[146:147]
	s_add_i32 m0, s58, 0xe000
	s_nop 0
	global_load_lds_dwordx4 v[160:161], off
	s_waitcnt vmcnt(8)
	s_waitcnt lgkmcnt(0)
	s_barrier
; #define PG8_STAGE(bufoff, gbase, voff) do { _Pragma("unroll") for (int _i = 0; _i < 2; ++_i) \
;         __builtin_amdgcn_global_load_lds((const unsigned*)((const char*)(gbase) + (voff)[_i]), (PG8_LAS unsigned*)(lds + (bufoff) + ldsw + _i * 8192), 16, 0, 0); } while (0)
; #define PG8_LDA(dst, b, h) do { _Pragma("unroll") for (int m = 0; m < 4; ++m) _Pragma("unroll") for (int k = 0; k < 2; ++k) dst[m][k] = *(const PG8_LAS bf16x8*)(lds + PG8_SA(b, h) + aoff + m * 2048 + k * 1024); } while (0)
; #define PG8_LDB(dst, b, h) do { _Pragma("unroll") for (int n = 0; n < 2; ++n) _Pragma("unroll") for (int k = 0; k < 2; ++k) dst[n][k] = *(const PG8_LAS bf16x8*)(lds + PG8_SB(b, h) + boff + n * 2048 + k * 1024); } while (0)
; #define PG8_MMA(ai, bj, At, Bt) do { __builtin_amdgcn_s_setprio(1); _Pragma("unroll") for (int m = 0; m < 4; ++m) _Pragma("unroll") for (int n = 0; n < 2; ++n) _Pragma("unroll") for (int k = 0; k < 2; ++k) \
;         acc[ai][bj][m][n] = __builtin_amdgcn_mfma_f32_16x16x32_bf16(Bt[n][k], At[m][k], acc[ai][bj][m][n], 0, 0, 0); __builtin_amdgcn_s_setprio(0); } while (0)
; #define PG8_WAIT_V(n) asm volatile("s_waitcnt vmcnt(" #n ")" ::: "memory")
; #define PG8_WAIT_L(n) asm volatile("s_waitcnt lgkmcnt(" #n ")" ::: "memory")
; #define PG8_BAR __builtin_amdgcn_s_barrier()
; #define PG8_SCHED __builtin_amdgcn_sched_barrier(0)
; template <class Epi, class Sched, bool ALIGN_EPI = false, bool SP2 = false>
; __device__ __forceinline__ void gemm_phase(PG8_LAS unsigned char* lds, const Gemm g, const Sched& S, const Epi& E) {
;     ...
;             PG8_LDB(B0, 0, 0); PG8_LDB(B1, 0, 1); PG8_SCHED; PG8_LDA(At, 0, 0); PG8_STAGE(PG8_SA(1, 1), a1 + hstep, voffA);
;             PG8_WAIT_V(8); PG8_WAIT_L(0); PG8_BAR; PG8_MMA(0, 0, At, B0); PG8_MMA(0, 1, At, B1); PG8_BAR; PG8_SCHED;
;             PG8_LDA(At, 0, 1); PG8_STAGE(PG8_SB(0, 0), b2, voffB); PG8_STAGE(PG8_SB(0, 1), b2 + hstep, voffB); PG8_STAGE(PG8_SA(0, 0), a2, voffA);
;             PG8_WAIT_V(8); PG8_WAIT_L(0); PG8_BAR; PG8_MMA(1, 0, At, B0); PG8_MMA(1, 1, At, B1); PG8_BAR; PG8_SCHED;
	s_setprio 1
	s_waitcnt lgkmcnt(0)
	v_mfma_f32_16x16x32_bf16 v[124:127], v[128:131], v[190:193], v[124:127]
	v_mfma_f32_16x16x32_bf16 v[120:123], v[152:155], v[190:193], v[120:123]
	v_mfma_f32_16x16x32_bf16 v[104:107], v[152:155], v[198:201], v[104:107]
	v_mfma_f32_16x16x32_bf16 v[108:111], v[128:131], v[198:201], v[108:111]
	v_mfma_f32_16x16x32_bf16 v[92:95], v[128:131], v[212:215], v[92:95]
	v_mfma_f32_16x16x32_bf16 v[88:91], v[152:155], v[212:215], v[88:91]
	v_mfma_f32_16x16x32_bf16 v[72:75], v[152:155], v[220:223], v[72:75]
	v_mfma_f32_16x16x32_bf16 v[76:79], v[128:131], v[220:223], v[76:79]
	v_mfma_f32_16x16x32_bf16 v[124:127], v[132:135], v[194:197], v[124:127]
	v_mfma_f32_16x16x32_bf16 v[120:123], v[156:159], v[194:197], v[120:123]
	v_mfma_f32_16x16x32_bf16 v[104:107], v[156:159], v[208:211], v[104:107]
	v_mfma_f32_16x16x32_bf16 v[108:111], v[132:135], v[208:211], v[108:111]
	v_mfma_f32_16x16x32_bf16 v[92:95], v[132:135], v[216:219], v[92:95]
	v_mfma_f32_16x16x32_bf16 v[88:91], v[156:159], v[216:219], v[88:91]
	v_mfma_f32_16x16x32_bf16 v[72:75], v[156:159], v[224:227], v[72:75]
	v_mfma_f32_16x16x32_bf16 v[76:79], v[132:135], v[224:227], v[76:79]
	s_setprio 0
	s_setprio 1
	v_mfma_f32_16x16x32_bf16 v[116:119], v[172:175], v[190:193], v[116:119]
	v_mfma_f32_16x16x32_bf16 v[112:115], v[182:185], v[190:193], v[112:115]
	v_mfma_f32_16x16x32_bf16 v[96:99], v[182:185], v[198:201], v[96:99]
	v_mfma_f32_16x16x32_bf16 v[100:103], v[172:175], v[198:201], v[100:103]
	v_mfma_f32_16x16x32_bf16 v[84:87], v[172:175], v[212:215], v[84:87]
	v_mfma_f32_16x16x32_bf16 v[80:83], v[182:185], v[212:215], v[80:83]
	v_mfma_f32_16x16x32_bf16 v[64:67], v[182:185], v[220:223], v[64:67]
	v_mfma_f32_16x16x32_bf16 v[68:71], v[172:175], v[220:223], v[68:71]
	v_mfma_f32_16x16x32_bf16 v[116:119], v[176:179], v[194:197], v[116:119]
	v_mfma_f32_16x16x32_bf16 v[112:115], v[186:189], v[194:197], v[112:115]
	v_mfma_f32_16x16x32_bf16 v[96:99], v[186:189], v[208:211], v[96:99]
	v_mfma_f32_16x16x32_bf16 v[100:103], v[176:179], v[208:211], v[100:103]
	v_mfma_f32_16x16x32_bf16 v[84:87], v[176:179], v[216:219], v[84:87]
	v_mfma_f32_16x16x32_bf16 v[80:83], v[186:189], v[216:219], v[80:83]
	v_mfma_f32_16x16x32_bf16 v[64:67], v[186:189], v[224:227], v[64:67]
	v_mfma_f32_16x16x32_bf16 v[68:71], v[176:179], v[224:227], v[68:71]
	s_setprio 0
	s_barrier
	s_add_i32 s3, s65, s43
	v_lshl_add_u64 v[160:161], s[54:55], 0, v[138:139]
	s_mov_b32 m0, s3
	ds_read_b128 v[190:193], v169 offset:16384
	ds_read_b128 v[194:197], v169 offset:17408
	ds_read_b128 v[198:201], v169 offset:18432
	ds_read_b128 v[208:211], v169 offset:19456
	ds_read_b128 v[212:215], v169 offset:20480
	ds_read_b128 v[216:219], v169 offset:21504
	ds_read_b128 v[220:223], v169 offset:22528
	ds_read_b128 v[224:227], v169 offset:23552
	global_load_lds_dwordx4 v[160:161], off
	s_add_i32 m0, s3, 0x2000
	s_add_u32 s10, s54, 0xb0000
	v_lshl_add_u64 v[202:203], s[54:55], 0, v[142:143]
	s_addc_u32 s11, s55, 0
	s_add_i32 s3, s66, s43
	global_load_lds_dwordx4 v[202:203], off
	v_lshl_add_u64 v[228:229], s[10:11], 0, v[138:139]
	s_mov_b32 m0, s3
	global_load_lds_dwordx4 v[228:229], off
	v_lshl_add_u64 v[228:229], s[10:11], 0, v[142:143]
	s_add_i32 m0, s3, 0x2000
	s_nop 0
	global_load_lds_dwordx4 v[228:229], off
	s_waitcnt vmcnt(6)
	s_waitcnt lgkmcnt(0)
	s_barrier
	s_setprio 1
	s_waitcnt lgkmcnt(0)
	v_mfma_f32_16x16x32_bf16 v[60:63], v[128:131], v[190:193], v[60:63]
	v_mfma_f32_16x16x32_bf16 v[56:59], v[152:155], v[190:193], v[56:59]
	v_mfma_f32_16x16x32_bf16 v[40:43], v[152:155], v[198:201], v[40:43]
	v_mfma_f32_16x16x32_bf16 v[44:47], v[128:131], v[198:201], v[44:47]
	v_mfma_f32_16x16x32_bf16 v[28:31], v[128:131], v[212:215], v[28:31]
	v_mfma_f32_16x16x32_bf16 v[24:27], v[152:155], v[212:215], v[24:27]
	v_mfma_f32_16x16x32_bf16 v[8:11], v[152:155], v[220:223], v[8:11]
	v_mfma_f32_16x16x32_bf16 v[12:15], v[128:131], v[220:223], v[12:15]
	v_mfma_f32_16x16x32_bf16 v[60:63], v[132:135], v[194:197], v[60:63]
	v_mfma_f32_16x16x32_bf16 v[56:59], v[156:159], v[194:197], v[56:59]
	v_mfma_f32_16x16x32_bf16 v[40:43], v[156:159], v[208:211], v[40:43]
	v_mfma_f32_16x16x32_bf16 v[44:47], v[132:135], v[208:211], v[44:47]
	v_mfma_f32_16x16x32_bf16 v[28:31], v[132:135], v[216:219], v[28:31]
	v_mfma_f32_16x16x32_bf16 v[24:27], v[156:159], v[216:219], v[24:27]
	v_lshl_add_u64 v[228:229], s[56:57], 0, v[136:137]
	s_mov_b32 m0, s58
	s_nop 0
	global_load_lds_dwordx4 v[228:229], off
	v_mfma_f32_16x16x32_bf16 v[8:11], v[156:159], v[224:227], v[8:11]
	v_mfma_f32_16x16x32_bf16 v[12:15], v[132:135], v[224:227], v[12:15]
	s_setprio 0
	s_setprio 1
	v_mfma_f32_16x16x32_bf16 v[52:55], v[172:175], v[190:193], v[52:55]
	v_mfma_f32_16x16x32_bf16 v[48:51], v[182:185], v[190:193], v[48:51]
	v_mfma_f32_16x16x32_bf16 v[32:35], v[182:185], v[198:201], v[32:35]
	v_mfma_f32_16x16x32_bf16 v[36:39], v[172:175], v[198:201], v[36:39]
	v_mfma_f32_16x16x32_bf16 v[20:23], v[172:175], v[212:215], v[20:23]
	v_mfma_f32_16x16x32_bf16 v[16:19], v[182:185], v[212:215], v[16:19]
	v_mfma_f32_16x16x32_bf16 v[0:3], v[182:185], v[220:223], v[0:3]
	v_mfma_f32_16x16x32_bf16 v[4:7], v[172:175], v[220:223], v[4:7]
	v_mfma_f32_16x16x32_bf16 v[52:55], v[176:179], v[194:197], v[52:55]
	v_mfma_f32_16x16x32_bf16 v[48:51], v[186:189], v[194:197], v[48:51]
	v_mfma_f32_16x16x32_bf16 v[32:35], v[186:189], v[208:211], v[32:35]
	v_mfma_f32_16x16x32_bf16 v[36:39], v[176:179], v[208:211], v[36:39]
	v_mfma_f32_16x16x32_bf16 v[20:23], v[176:179], v[216:219], v[20:23]
	v_mfma_f32_16x16x32_bf16 v[16:19], v[186:189], v[216:219], v[16:19]
	v_lshl_add_u64 v[230:231], s[56:57], 0, v[140:141]
	s_mov_b32 m0, s59
	s_nop 0
	global_load_lds_dwordx4 v[230:231], off
	v_mfma_f32_16x16x32_bf16 v[0:3], v[186:189], v[224:227], v[0:3]
	v_mfma_f32_16x16x32_bf16 v[4:7], v[176:179], v[224:227], v[4:7]
	s_setprio 0
	s_barrier
; #define PG8_STAGE(bufoff, gbase, voff) do { _Pragma("unroll") for (int _i = 0; _i < 2; ++_i) \
;         __builtin_amdgcn_global_load_lds((const unsigned*)((const char*)(gbase) + (voff)[_i]), (PG8_LAS unsigned*)(lds + (bufoff) + ldsw + _i * 8192), 16, 0, 0); } while (0)
; #define PG8_LDA(dst, b, h) do { _Pragma("unroll") for (int m = 0; m < 4; ++m) _Pragma("unroll") for (int k = 0; k < 2; ++k) dst[m][k] = *(const PG8_LAS bf16x8*)(lds + PG8_SA(b, h) + aoff + m * 2048 + k * 1024); } while (0)
; #define PG8_LDB(dst, b, h) do { _Pragma("unroll") for (int n = 0; n < 2; ++n) _Pragma("unroll") for (int k = 0; k < 2; ++k) dst[n][k] = *(const PG8_LAS bf16x8*)(lds + PG8_SB(b, h) + boff + n * 2048 + k * 1024); } while (0)
; #define PG8_MMA(ai, bj, At, Bt) do { __builtin_amdgcn_s_setprio(1); _Pragma("unroll") for (int m = 0; m < 4; ++m) _Pragma("unroll") for (int n = 0; n < 2; ++n) _Pragma("unroll") for (int k = 0; k < 2; ++k) \
;         acc[ai][bj][m][n] = __builtin_amdgcn_mfma_f32_16x16x32_bf16(Bt[n][k], At[m][k], acc[ai][bj][m][n], 0, 0, 0); __builtin_amdgcn_s_setprio(0); } while (0)
; #define PG8_WAIT_V(n) asm volatile("s_waitcnt vmcnt(" #n ")" ::: "memory")
; #define PG8_WAIT_L(n) asm volatile("s_waitcnt lgkmcnt(" #n ")" ::: "memory")
; #define PG8_BAR __builtin_amdgcn_s_barrier()
; #define PG8_SCHED __builtin_amdgcn_sched_barrier(0)
; template <class Epi, class Sched, bool ALIGN_EPI = false, bool SP2 = false>
; __device__ __forceinline__ void gemm_phase(PG8_LAS unsigned char* lds, const Gemm g, const Sched& S, const Epi& E) {
;     ...
;             PG8_LDB(B0, 1, 0); PG8_LDB(B1, 1, 1); PG8_SCHED; PG8_LDA(At, 1, 0); PG8_STAGE(PG8_SA(0, 1), a2 + hstep, voffA);
;             PG8_WAIT_V(8); PG8_WAIT_L(0); PG8_BAR; PG8_MMA(0, 0, At, B0); PG8_MMA(0, 1, At, B1); PG8_BAR; PG8_SCHED;
	s_add_i32 s3, 0, 0x18000
	s_add_i32 s14, 0, 0x1c000
	v_add_u32_e32 v156, s3, v163
	v_add_u32_e32 v171, s14, v163
	ds_read_b128 v[128:131], v156
	ds_read_b128 v[132:135], v156 offset:1024
	ds_read_b128 v[152:155], v156 offset:2048
	ds_read_b128 v[156:159], v156 offset:3072
	ds_read_b128 v[172:175], v171
	ds_read_b128 v[176:179], v171 offset:1024
	ds_read_b128 v[182:185], v171 offset:2048
	ds_read_b128 v[186:189], v171 offset:3072
	s_add_u32 s10, s56, 0xb0000
	s_addc_u32 s11, s57, 0
	s_mov_b32 m0, s60
	v_lshl_add_u64 v[232:233], s[10:11], 0, v[136:137]
	ds_read_b128 v[190:193], v169 offset:32768
	ds_read_b128 v[194:197], v169 offset:33792
	ds_read_b128 v[198:201], v169 offset:34816
	ds_read_b128 v[208:211], v169 offset:35840
	ds_read_b128 v[212:215], v169 offset:36864
	ds_read_b128 v[216:219], v169 offset:37888
	ds_read_b128 v[220:223], v169 offset:38912
	ds_read_b128 v[224:227], v169 offset:39936
	global_load_lds_dwordx4 v[232:233], off
	v_lshl_add_u64 v[232:233], s[10:11], 0, v[140:141]
	s_mov_b32 m0, s61
	s_nop 0
	global_load_lds_dwordx4 v[232:233], off
	s_waitcnt vmcnt(8)
	s_waitcnt lgkmcnt(0)
	s_barrier
	s_setprio 1
	s_waitcnt lgkmcnt(0)
	v_mfma_f32_16x16x32_bf16 v[124:127], v[128:131], v[190:193], v[124:127]
	v_mfma_f32_16x16x32_bf16 v[120:123], v[152:155], v[190:193], v[120:123]
	v_mfma_f32_16x16x32_bf16 v[104:107], v[152:155], v[198:201], v[104:107]
	v_mfma_f32_16x16x32_bf16 v[108:111], v[128:131], v[198:201], v[108:111]
	v_mfma_f32_16x16x32_bf16 v[92:95], v[128:131], v[212:215], v[92:95]
	v_mfma_f32_16x16x32_bf16 v[88:91], v[152:155], v[212:215], v[88:91]
	v_mfma_f32_16x16x32_bf16 v[72:75], v[152:155], v[220:223], v[72:75]
	v_mfma_f32_16x16x32_bf16 v[76:79], v[128:131], v[220:223], v[76:79]
	v_mfma_f32_16x16x32_bf16 v[124:127], v[132:135], v[194:197], v[124:127]
	v_mfma_f32_16x16x32_bf16 v[120:123], v[156:159], v[194:197], v[120:123]
	v_mfma_f32_16x16x32_bf16 v[104:107], v[156:159], v[208:211], v[104:107]
	v_mfma_f32_16x16x32_bf16 v[108:111], v[132:135], v[208:211], v[108:111]
	v_mfma_f32_16x16x32_bf16 v[92:95], v[132:135], v[216:219], v[92:95]
	v_mfma_f32_16x16x32_bf16 v[88:91], v[156:159], v[216:219], v[88:91]
	v_mfma_f32_16x16x32_bf16 v[72:75], v[156:159], v[224:227], v[72:75]
	v_mfma_f32_16x16x32_bf16 v[76:79], v[132:135], v[224:227], v[76:79]
	s_setprio 0
	s_setprio 1
	v_mfma_f32_16x16x32_bf16 v[116:119], v[172:175], v[190:193], v[116:119]
	v_mfma_f32_16x16x32_bf16 v[112:115], v[182:185], v[190:193], v[112:115]
	v_mfma_f32_16x16x32_bf16 v[96:99], v[182:185], v[198:201], v[96:99]
	v_mfma_f32_16x16x32_bf16 v[100:103], v[172:175], v[198:201], v[100:103]
	v_mfma_f32_16x16x32_bf16 v[84:87], v[172:175], v[212:215], v[84:87]
	v_mfma_f32_16x16x32_bf16 v[80:83], v[182:185], v[212:215], v[80:83]
	v_mfma_f32_16x16x32_bf16 v[64:67], v[182:185], v[220:223], v[64:67]
	v_mfma_f32_16x16x32_bf16 v[68:71], v[172:175], v[220:223], v[68:71]
	v_mfma_f32_16x16x32_bf16 v[116:119], v[176:179], v[194:197], v[116:119]
	v_mfma_f32_16x16x32_bf16 v[112:115], v[186:189], v[194:197], v[112:115]
	v_mfma_f32_16x16x32_bf16 v[96:99], v[186:189], v[208:211], v[96:99]
	v_mfma_f32_16x16x32_bf16 v[100:103], v[176:179], v[208:211], v[100:103]
	v_mfma_f32_16x16x32_bf16 v[84:87], v[176:179], v[216:219], v[84:87]
	v_mfma_f32_16x16x32_bf16 v[80:83], v[186:189], v[216:219], v[80:83]
	v_mfma_f32_16x16x32_bf16 v[64:67], v[186:189], v[224:227], v[64:67]
	v_mfma_f32_16x16x32_bf16 v[68:71], v[176:179], v[224:227], v[68:71]
	s_setprio 0
	s_barrier
; #define PG8_STAGE(bufoff, gbase, voff) do { _Pragma("unroll") for (int _i = 0; _i < 2; ++_i) \
;         __builtin_amdgcn_global_load_lds((const unsigned*)((const char*)(gbase) + (voff)[_i]), (PG8_LAS unsigned*)(lds + (bufoff) + ldsw + _i * 8192), 16, 0, 0); } while (0)
; #define PG8_LDA(dst, b, h) do { _Pragma("unroll") for (int m = 0; m < 4; ++m) _Pragma("unroll") for (int k = 0; k < 2; ++k) dst[m][k] = *(const PG8_LAS bf16x8*)(lds + PG8_SA(b, h) + aoff + m * 2048 + k * 1024); } while (0)
; #define PG8_WAIT_V(n) asm volatile("s_waitcnt vmcnt(" #n ")" ::: "memory")
; template <class Epi, class Sched, bool ALIGN_EPI = false, bool SP2 = false>
; __device__ __forceinline__ void gemm_phase(PG8_LAS unsigned char* lds, const Gemm g, const Sched& S, const Epi& E) {
;     ...
;             PG8_LDA(At, 1, 1); PG8_STAGE(PG8_SB(1, 0), b3, voffB); PG8_STAGE(PG8_SB(1, 1), b3 + hstep, voffB); PG8_STAGE(PG8_SA(1, 0), a3, voffA);
;             PG8_WAIT_V(8); PG8_WAIT_L(0); PG8_BAR; PG8_MMA(1, 0, At, B0); PG8_MMA(1, 1, At, B1); PG8_BAR; PG8_SCHED;
;             } else {
;             PG8_LDB(B0, 0, 0); PG8_SCHED; PG8_LDA(At, 0, 0); PG8_STAGE(PG8_SA(1, 1), a1 + hstep, voffA);
;             PG8_WAIT_L(8); PG8_BAR; PG8_WAIT_L(0); PG8_MMA(0, 0, At, B0); PG8_BAR; PG8_SCHED;
;             PG8_LDB(B1, 0, 1); PG8_STAGE(PG8_SB(0, 0), b2, voffB);
;             PG8_BAR; PG8_WAIT_L(0); PG8_MMA(0, 1, At, B1); PG8_BAR;
;             PG8_LDA(At, 0, 1); PG8_STAGE(PG8_SA(0, 0), a2, voffA);
;             PG8_BAR; PG8_WAIT_L(0); PG8_MMA(1, 0, At, B0); PG8_BAR; PG8_SCHED;
;             PG8_STAGE(PG8_SB(0, 1), b2 + hstep, voffB);
;             PG8_WAIT_V(6); PG8_BAR; PG8_MMA(1, 1, At, B1); PG8_BAR;
;             PG8_LDB(B0, 1, 0); PG8_SCHED; PG8_LDA(At, 1, 0); PG8_STAGE(PG8_SA(0, 1), a2 + hstep, voffA);
;             PG8_WAIT_L(8); PG8_BAR; PG8_WAIT_L(0); PG8_MMA(0, 0, At, B0); PG8_BAR; PG8_SCHED;
;             PG8_LDB(B1, 1, 1); PG8_STAGE(PG8_SB(1, 0), b3, voffB);
;             PG8_BAR; PG8_WAIT_L(0); PG8_MMA(0, 1, At, B1); PG8_BAR;
;             PG8_LDA(At, 1, 1); PG8_STAGE(PG8_SA(1, 0), a3, voffA);
;             PG8_BAR; PG8_WAIT_L(0); PG8_MMA(1, 0, At, B0); PG8_BAR; PG8_SCHED;
;             PG8_STAGE(PG8_SB(1, 1), b3 + hstep, voffB);
;             PG8_WAIT_V(6); PG8_BAR; PG8_MMA(1, 1, At, B1); PG8_BAR;
;             }
;         }
;         if constexpr (ALIGN_EPI) { if (wr == 0) PG8_BAR; }
	s_add_i32 s3, s3, s43
	v_lshl_add_u64 v[160:161], v[160:161], 0, s[40:41]
	s_mov_b32 m0, s3
	ds_read_b128 v[190:193], v169 offset:49152
	ds_read_b128 v[194:197], v169 offset:50176
	ds_read_b128 v[198:201], v169 offset:51200
	ds_read_b128 v[208:211], v169 offset:52224
	ds_read_b128 v[212:215], v169 offset:53248
	ds_read_b128 v[216:219], v169 offset:54272
	ds_read_b128 v[220:223], v169 offset:55296
	ds_read_b128 v[224:227], v169 offset:56320
	global_load_lds_dwordx4 v[160:161], off
	s_add_i32 m0, s3, 0x2000
	s_add_u32 s10, s54, 0xb0080
	v_lshl_add_u64 v[160:161], v[202:203], 0, s[40:41]
	s_addc_u32 s11, s55, 0
	s_add_i32 s3, s14, s43
	global_load_lds_dwordx4 v[160:161], off
	v_lshl_add_u64 v[160:161], s[10:11], 0, v[138:139]
	s_mov_b32 m0, s3
	s_nop 0
	global_load_lds_dwordx4 v[160:161], off
	v_lshl_add_u64 v[160:161], s[10:11], 0, v[142:143]
	s_add_i32 m0, s3, 0x2000
	s_nop 0
	global_load_lds_dwordx4 v[160:161], off
	s_waitcnt vmcnt(6)
	s_waitcnt lgkmcnt(0)
	s_barrier
	s_setprio 1
	s_waitcnt lgkmcnt(0)
	v_mfma_f32_16x16x32_bf16 v[60:63], v[128:131], v[190:193], v[60:63]
	v_mfma_f32_16x16x32_bf16 v[56:59], v[152:155], v[190:193], v[56:59]
	v_mfma_f32_16x16x32_bf16 v[40:43], v[152:155], v[198:201], v[40:43]
	v_mfma_f32_16x16x32_bf16 v[44:47], v[128:131], v[198:201], v[44:47]
	v_mfma_f32_16x16x32_bf16 v[28:31], v[128:131], v[212:215], v[28:31]
	v_mfma_f32_16x16x32_bf16 v[24:27], v[152:155], v[212:215], v[24:27]
	v_mfma_f32_16x16x32_bf16 v[8:11], v[152:155], v[220:223], v[8:11]
	v_mfma_f32_16x16x32_bf16 v[12:15], v[128:131], v[220:223], v[12:15]
	v_mfma_f32_16x16x32_bf16 v[60:63], v[132:135], v[194:197], v[60:63]
	v_mfma_f32_16x16x32_bf16 v[56:59], v[156:159], v[194:197], v[56:59]
	v_mfma_f32_16x16x32_bf16 v[40:43], v[156:159], v[208:211], v[40:43]
	v_mfma_f32_16x16x32_bf16 v[44:47], v[132:135], v[208:211], v[44:47]
	v_mfma_f32_16x16x32_bf16 v[28:31], v[132:135], v[216:219], v[28:31]
	v_mfma_f32_16x16x32_bf16 v[24:27], v[156:159], v[216:219], v[24:27]
	v_lshl_add_u64 v[160:161], v[228:229], 0, s[40:41]
	s_mov_b32 m0, s63
	s_nop 0
	global_load_lds_dwordx4 v[160:161], off
	v_mfma_f32_16x16x32_bf16 v[8:11], v[156:159], v[224:227], v[8:11]
	v_mfma_f32_16x16x32_bf16 v[12:15], v[132:135], v[224:227], v[12:15]
	s_setprio 0
	s_setprio 1
	v_mfma_f32_16x16x32_bf16 v[52:55], v[172:175], v[190:193], v[52:55]
	v_mfma_f32_16x16x32_bf16 v[48:51], v[182:185], v[190:193], v[48:51]
	v_mfma_f32_16x16x32_bf16 v[32:35], v[182:185], v[198:201], v[32:35]
	v_mfma_f32_16x16x32_bf16 v[36:39], v[172:175], v[198:201], v[36:39]
	v_mfma_f32_16x16x32_bf16 v[20:23], v[172:175], v[212:215], v[20:23]
	v_mfma_f32_16x16x32_bf16 v[16:19], v[182:185], v[212:215], v[16:19]
	v_mfma_f32_16x16x32_bf16 v[0:3], v[182:185], v[220:223], v[0:3]
	v_mfma_f32_16x16x32_bf16 v[4:7], v[172:175], v[220:223], v[4:7]
	v_mfma_f32_16x16x32_bf16 v[52:55], v[176:179], v[194:197], v[52:55]
	v_mfma_f32_16x16x32_bf16 v[48:51], v[186:189], v[194:197], v[48:51]
	v_mfma_f32_16x16x32_bf16 v[32:35], v[186:189], v[208:211], v[32:35]
	v_mfma_f32_16x16x32_bf16 v[36:39], v[176:179], v[208:211], v[36:39]
	v_mfma_f32_16x16x32_bf16 v[20:23], v[176:179], v[216:219], v[20:23]
	v_mfma_f32_16x16x32_bf16 v[16:19], v[186:189], v[216:219], v[16:19]
	v_lshl_add_u64 v[160:161], v[230:231], 0, s[40:41]
	s_mov_b32 m0, s64
	s_nop 0
	global_load_lds_dwordx4 v[160:161], off
	v_mfma_f32_16x16x32_bf16 v[0:3], v[186:189], v[224:227], v[0:3]
	v_mfma_f32_16x16x32_bf16 v[4:7], v[176:179], v[224:227], v[4:7]
	s_setprio 0
	s_barrier
	s_add_i32 s93, s93, 2
	s_add_u32 s91, s91, 0x100
	s_addc_u32 s92, s92, 0
	s_cmp_gt_u32 s93, 41
	s_mov_b64 s[10:11], s[50:51]
	s_cbranch_scc0 .LBB0_269
	s_and_b64 vcc, exec, s[44:45]
	s_cbranch_vccz .LBB0_272
	s_barrier

; #define PG8_STAGE(bufoff, gbase, voff) do { _Pragma("unroll") for (int _i = 0; _i < 2; ++_i) \
;         __builtin_amdgcn_global_load_lds((const unsigned*)((const char*)(gbase) + (voff)[_i]), (PG8_LAS unsigned*)(lds + (bufoff) + ldsw + _i * 8192), 16, 0, 0); } while (0)
; #define PG8_LDA(dst, b, h) do { _Pragma("unroll") for (int m = 0; m < 4; ++m) _Pragma("unroll") for (int k = 0; k < 2; ++k) dst[m][k] = *(const PG8_LAS bf16x8*)(lds + PG8_SA(b, h) + aoff + m * 2048 + k * 1024); } while (0)
; #define PG8_LDB(dst, b, h) do { _Pragma("unroll") for (int n = 0; n < 2; ++n) _Pragma("unroll") for (int k = 0; k < 2; ++k) dst[n][k] = *(const PG8_LAS bf16x8*)(lds + PG8_SB(b, h) + boff + n * 2048 + k * 1024); } while (0)
; #define PG8_WAIT_V(n) asm volatile("s_waitcnt vmcnt(" #n ")" ::: "memory")
; #define PG8_WAIT_L(n) asm volatile("s_waitcnt lgkmcnt(" #n ")" ::: "memory")
; #define PG8_BAR __builtin_amdgcn_s_barrier()
; #define PG8_SCHED __builtin_amdgcn_sched_barrier(0)
; template <class Epi, class Sched, bool ALIGN_EPI = false, bool SP2 = false>
; __device__ __forceinline__ void gemm_phase(PG8_LAS unsigned char* lds, const Gemm g, const Sched& S, const Epi& E) {
;     ...
;         const bool has_next = S.next(ui + 1, nxt);
;         const char* nA = has_next ? (const char*)g.A + (size_t)nxt.pm * tstep : cA; const char* nB = has_next ? (const char*)g.Bt + (size_t)nxt.pn * tstep : cB;
;         for (int t = 0; t < nt; t += 2) {
;             const bool last = (t == nt - 2);
;             const char* a1 = cA + (size_t)(t + 1) * kstep;
;             const char* a2 = last ? nA : cA + (size_t)(t + 2) * kstep; const char* b2 = last ? nB : cB + (size_t)(t + 2) * kstep;
;             const char* a3 = a2 + kstep; const char* b3 = b2 + kstep;
;             if (last && has_next) S.a_ready(nxt);
;             if constexpr (SP2) {
;             PG8_LDB(B0, 0, 0); PG8_LDB(B1, 0, 1); PG8_SCHED; PG8_LDA(At, 0, 0); PG8_STAGE(PG8_SA(1, 1), a1 + hstep, voffA);
;             PG8_WAIT_V(8); PG8_WAIT_L(0); PG8_BAR; PG8_MMA(0, 0, At, B0); PG8_MMA(0, 1, At, B1); PG8_BAR; PG8_SCHED;
;             PG8_LDA(At, 0, 1); PG8_STAGE(PG8_SB(0, 0), b2, voffB); PG8_STAGE(PG8_SB(0, 1), b2 + hstep, voffB); PG8_STAGE(PG8_SA(0, 0), a2, voffA);
;             PG8_WAIT_V(8); PG8_WAIT_L(0); PG8_BAR; PG8_MMA(1, 0, At, B0); PG8_MMA(1, 1, At, B1); PG8_BAR; PG8_SCHED;
.LBB0_416:
	s_ashr_i32 s45, s44, 31
	s_lshl_b64 s[14:15], s[44:45], 19
	s_add_u32 s48, s22, s14
	s_addc_u32 s49, s23, s15
	s_and_b64 s[14:15], s[6:7], exec
	s_cselect_b32 s45, s49, s55
	s_cselect_b32 s89, s48, s54
	s_ashr_i32 s41, s40, 31
	s_lshl_b64 s[14:15], s[40:41], 19
	s_add_u32 s50, s84, s14
	s_addc_u32 s51, s85, s15
	s_and_b64 s[14:15], s[6:7], exec
	s_cselect_b32 s41, s51, s57
	s_cselect_b32 s90, s50, s56
	s_add_u32 s54, s54, 0x40080
	s_addc_u32 s55, s55, 0
	s_add_u32 s91, s56, 0x100
	s_addc_u32 s92, s57, 0
	s_mov_b32 s93, -2
	ds_read_b128 v[154:157], v169
	ds_read_b128 v[158:161], v169 offset:1024
	ds_read_b128 v[162:165], v169 offset:2048
	ds_read_b128 v[174:177], v169 offset:3072
	ds_read_b128 v[182:185], v170
	ds_read_b128 v[186:189], v170 offset:1024
	ds_read_b128 v[190:193], v170 offset:2048
	ds_read_b128 v[194:197], v170 offset:3072
	s_add_u32 s3, s54, 0xfffc0080
	s_addc_u32 s14, s55, -1
	s_cmp_eq_u32 s93, 12
	s_cselect_b32 s59, s45, s14
	s_cselect_b32 s58, s89, s3
	s_cselect_b32 s57, s41, s92
	s_cselect_b32 s56, s90, s91
	v_lshl_add_u64 v[178:179], s[54:55], 0, v[146:147]
	s_add_i32 m0, s60, 0xc000
	ds_read_b128 v[198:201], v171
	ds_read_b128 v[208:211], v171 offset:1024
	ds_read_b128 v[212:215], v171 offset:2048
	ds_read_b128 v[216:219], v171 offset:3072
	ds_read_b128 v[220:223], v171 offset:4096
	ds_read_b128 v[224:227], v171 offset:5120
	ds_read_b128 v[228:231], v171 offset:6144
	ds_read_b128 v[232:235], v171 offset:7168
	global_load_lds_dwordx4 v[178:179], off
	v_lshl_add_u64 v[178:179], s[54:55], 0, v[148:149]
	s_add_i32 m0, s60, 0xe000
	s_nop 0
	global_load_lds_dwordx4 v[178:179], off
	s_waitcnt vmcnt(8)
	s_waitcnt lgkmcnt(0)
	s_barrier
	s_setprio 1
	s_waitcnt lgkmcnt(0)
	v_mfma_f32_16x16x32_bf16 v[124:127], v[154:157], v[198:201], 0
	v_mfma_f32_16x16x32_bf16 v[120:123], v[162:165], v[198:201], 0
	v_mfma_f32_16x16x32_bf16 v[112:115], v[162:165], v[212:215], 0
	v_mfma_f32_16x16x32_bf16 v[116:119], v[154:157], v[212:215], 0
	v_mfma_f32_16x16x32_bf16 v[108:111], v[154:157], v[220:223], 0
	v_mfma_f32_16x16x32_bf16 v[104:107], v[162:165], v[220:223], 0
	v_mfma_f32_16x16x32_bf16 v[96:99], v[162:165], v[228:231], 0
	v_mfma_f32_16x16x32_bf16 v[100:103], v[154:157], v[228:231], 0
	v_mfma_f32_16x16x32_bf16 v[124:127], v[158:161], v[208:211], v[124:127]
	v_mfma_f32_16x16x32_bf16 v[120:123], v[174:177], v[208:211], v[120:123]
	v_mfma_f32_16x16x32_bf16 v[112:115], v[174:177], v[216:219], v[112:115]
	v_mfma_f32_16x16x32_bf16 v[116:119], v[158:161], v[216:219], v[116:119]
	v_mfma_f32_16x16x32_bf16 v[108:111], v[158:161], v[224:227], v[108:111]
	v_mfma_f32_16x16x32_bf16 v[104:107], v[174:177], v[224:227], v[104:107]
	v_mfma_f32_16x16x32_bf16 v[96:99], v[174:177], v[232:235], v[96:99]
	v_mfma_f32_16x16x32_bf16 v[100:103], v[158:161], v[232:235], v[100:103]
	s_setprio 0
	s_setprio 1
	v_mfma_f32_16x16x32_bf16 v[68:71], v[182:185], v[198:201], 0
	v_mfma_f32_16x16x32_bf16 v[64:67], v[190:193], v[198:201], 0
	v_mfma_f32_16x16x32_bf16 v[48:51], v[190:193], v[212:215], 0
	v_mfma_f32_16x16x32_bf16 v[52:55], v[182:185], v[212:215], 0
	v_mfma_f32_16x16x32_bf16 v[44:47], v[182:185], v[220:223], 0
	v_mfma_f32_16x16x32_bf16 v[40:43], v[190:193], v[220:223], 0
	v_mfma_f32_16x16x32_bf16 v[32:35], v[190:193], v[228:231], 0
	v_mfma_f32_16x16x32_bf16 v[36:39], v[182:185], v[228:231], 0
	v_mfma_f32_16x16x32_bf16 v[68:71], v[186:189], v[208:211], v[68:71]
	v_mfma_f32_16x16x32_bf16 v[64:67], v[194:197], v[208:211], v[64:67]
	v_mfma_f32_16x16x32_bf16 v[48:51], v[194:197], v[216:219], v[48:51]
	v_mfma_f32_16x16x32_bf16 v[52:55], v[186:189], v[216:219], v[52:55]
	v_mfma_f32_16x16x32_bf16 v[44:47], v[186:189], v[224:227], v[44:47]
	v_mfma_f32_16x16x32_bf16 v[40:43], v[194:197], v[224:227], v[40:43]
	v_mfma_f32_16x16x32_bf16 v[32:35], v[194:197], v[232:235], v[32:35]
	v_mfma_f32_16x16x32_bf16 v[36:39], v[186:189], v[232:235], v[36:39]
	s_setprio 0
	s_barrier
	s_add_i32 s3, s86, s34
	v_lshl_add_u64 v[178:179], s[56:57], 0, v[132:133]
	s_mov_b32 m0, s3
	ds_read_b128 v[198:201], v171 offset:16384
	ds_read_b128 v[208:211], v171 offset:17408
	ds_read_b128 v[212:215], v171 offset:18432
	ds_read_b128 v[216:219], v171 offset:19456
	ds_read_b128 v[220:223], v171 offset:20480
	ds_read_b128 v[224:227], v171 offset:21504
	ds_read_b128 v[228:231], v171 offset:22528
	ds_read_b128 v[232:235], v171 offset:23552
	global_load_lds_dwordx4 v[178:179], off
	s_add_i32 m0, s3, 0x2000
	s_add_u32 s14, s56, 0x40000
	v_lshl_add_u64 v[202:203], s[56:57], 0, v[128:129]
	s_addc_u32 s15, s57, 0
	s_add_i32 s3, s87, s34
	global_load_lds_dwordx4 v[202:203], off
	v_lshl_add_u64 v[236:237], s[14:15], 0, v[132:133]
	s_mov_b32 m0, s3
	global_load_lds_dwordx4 v[236:237], off
	v_lshl_add_u64 v[236:237], s[14:15], 0, v[128:129]
	s_add_i32 m0, s3, 0x2000
	s_nop 0
	global_load_lds_dwordx4 v[236:237], off
	s_waitcnt vmcnt(6)
	s_waitcnt lgkmcnt(0)
	s_barrier
; #define PG8_STAGE(bufoff, gbase, voff) do { _Pragma("unroll") for (int _i = 0; _i < 2; ++_i) \
;         __builtin_amdgcn_global_load_lds((const unsigned*)((const char*)(gbase) + (voff)[_i]), (PG8_LAS unsigned*)(lds + (bufoff) + ldsw + _i * 8192), 16, 0, 0); } while (0)
; #define PG8_LDA(dst, b, h) do { _Pragma("unroll") for (int m = 0; m < 4; ++m) _Pragma("unroll") for (int k = 0; k < 2; ++k) dst[m][k] = *(const PG8_LAS bf16x8*)(lds + PG8_SA(b, h) + aoff + m * 2048 + k * 1024); } while (0)
; #define PG8_LDB(dst, b, h) do { _Pragma("unroll") for (int n = 0; n < 2; ++n) _Pragma("unroll") for (int k = 0; k < 2; ++k) dst[n][k] = *(const PG8_LAS bf16x8*)(lds + PG8_SB(b, h) + boff + n * 2048 + k * 1024); } while (0)
; #define PG8_MMA(ai, bj, At, Bt) do { __builtin_amdgcn_s_setprio(1); _Pragma("unroll") for (int m = 0; m < 4; ++m) _Pragma("unroll") for (int n = 0; n < 2; ++n) _Pragma("unroll") for (int k = 0; k < 2; ++k) \
;         acc[ai][bj][m][n] = __builtin_amdgcn_mfma_f32_16x16x32_bf16(Bt[n][k], At[m][k], acc[ai][bj][m][n], 0, 0, 0); __builtin_amdgcn_s_setprio(0); } while (0)
; #define PG8_WAIT_V(n) asm volatile("s_waitcnt vmcnt(" #n ")" ::: "memory")
; #define PG8_WAIT_L(n) asm volatile("s_waitcnt lgkmcnt(" #n ")" ::: "memory")
; #define PG8_BAR __builtin_amdgcn_s_barrier()
; #define PG8_SCHED __builtin_amdgcn_sched_barrier(0)
; template <class Epi, class Sched, bool ALIGN_EPI = false, bool SP2 = false>
; __device__ __forceinline__ void gemm_phase(PG8_LAS unsigned char* lds, const Gemm g, const Sched& S, const Epi& E) {
;     ...
;             PG8_WAIT_V(8); PG8_WAIT_L(0); PG8_BAR; PG8_MMA(1, 0, At, B0); PG8_MMA(1, 1, At, B1); PG8_BAR; PG8_SCHED;
;             PG8_LDB(B0, 1, 0); PG8_LDB(B1, 1, 1); PG8_SCHED; PG8_LDA(At, 1, 0); PG8_STAGE(PG8_SA(0, 1), a2 + hstep, voffA);
;             PG8_WAIT_V(8); PG8_WAIT_L(0); PG8_BAR; PG8_MMA(0, 0, At, B0); PG8_MMA(0, 1, At, B1); PG8_BAR; PG8_SCHED;
	s_setprio 1
	s_waitcnt lgkmcnt(0)
	v_mfma_f32_16x16x32_bf16 v[92:95], v[154:157], v[198:201], 0
	v_mfma_f32_16x16x32_bf16 v[88:91], v[162:165], v[198:201], 0
	v_mfma_f32_16x16x32_bf16 v[80:83], v[162:165], v[212:215], 0
	v_mfma_f32_16x16x32_bf16 v[84:87], v[154:157], v[212:215], 0
	v_mfma_f32_16x16x32_bf16 v[76:79], v[154:157], v[220:223], 0
	v_mfma_f32_16x16x32_bf16 v[72:75], v[162:165], v[220:223], 0
	v_mfma_f32_16x16x32_bf16 v[56:59], v[162:165], v[228:231], 0
	v_mfma_f32_16x16x32_bf16 v[60:63], v[154:157], v[228:231], 0
	v_mfma_f32_16x16x32_bf16 v[92:95], v[158:161], v[208:211], v[92:95]
	v_mfma_f32_16x16x32_bf16 v[88:91], v[174:177], v[208:211], v[88:91]
	v_mfma_f32_16x16x32_bf16 v[80:83], v[174:177], v[216:219], v[80:83]
	v_mfma_f32_16x16x32_bf16 v[84:87], v[158:161], v[216:219], v[84:87]
	v_mfma_f32_16x16x32_bf16 v[76:79], v[158:161], v[224:227], v[76:79]
	v_mfma_f32_16x16x32_bf16 v[72:75], v[174:177], v[224:227], v[72:75]
	v_lshl_add_u64 v[236:237], s[58:59], 0, v[134:135]
	s_mov_b32 m0, s60
	s_nop 0
	global_load_lds_dwordx4 v[236:237], off
	v_mfma_f32_16x16x32_bf16 v[56:59], v[174:177], v[232:235], v[56:59]
	v_mfma_f32_16x16x32_bf16 v[60:63], v[158:161], v[232:235], v[60:63]
	s_setprio 0
	s_setprio 1
	v_mfma_f32_16x16x32_bf16 v[28:31], v[182:185], v[198:201], 0
	v_mfma_f32_16x16x32_bf16 v[24:27], v[190:193], v[198:201], 0
	v_mfma_f32_16x16x32_bf16 v[16:19], v[190:193], v[212:215], 0
	v_mfma_f32_16x16x32_bf16 v[20:23], v[182:185], v[212:215], 0
	v_mfma_f32_16x16x32_bf16 v[12:15], v[182:185], v[220:223], 0
	v_mfma_f32_16x16x32_bf16 v[8:11], v[190:193], v[220:223], 0
	v_mfma_f32_16x16x32_bf16 v[0:3], v[190:193], v[228:231], 0
	v_mfma_f32_16x16x32_bf16 v[4:7], v[182:185], v[228:231], 0
	v_mfma_f32_16x16x32_bf16 v[28:31], v[186:189], v[208:211], v[28:31]
	v_mfma_f32_16x16x32_bf16 v[24:27], v[194:197], v[208:211], v[24:27]
	v_mfma_f32_16x16x32_bf16 v[16:19], v[194:197], v[216:219], v[16:19]
	v_mfma_f32_16x16x32_bf16 v[20:23], v[186:189], v[216:219], v[20:23]
	v_mfma_f32_16x16x32_bf16 v[12:15], v[186:189], v[224:227], v[12:15]
	v_mfma_f32_16x16x32_bf16 v[8:11], v[194:197], v[224:227], v[8:11]
	v_lshl_add_u64 v[238:239], s[58:59], 0, v[130:131]
	s_mov_b32 m0, s61
	s_nop 0
	global_load_lds_dwordx4 v[238:239], off
	v_mfma_f32_16x16x32_bf16 v[0:3], v[194:197], v[232:235], v[0:3]
	v_mfma_f32_16x16x32_bf16 v[4:7], v[186:189], v[232:235], v[4:7]
	s_setprio 0
	s_barrier
	s_add_i32 s3, 0, 0x18000
	v_add_u32_e32 v136, s3, v143
	s_add_i32 s33, 0, 0x1c000
	ds_read_b128 v[154:157], v136
	ds_read_b128 v[158:161], v136 offset:1024
	ds_read_b128 v[162:165], v136 offset:2048
	ds_read_b128 v[174:177], v136 offset:3072
	v_add_u32_e32 v136, s33, v143
	ds_read_b128 v[182:185], v136
	ds_read_b128 v[186:189], v136 offset:1024
	ds_read_b128 v[190:193], v136 offset:2048
	ds_read_b128 v[194:197], v136 offset:3072
	s_add_u32 s14, s58, 0x40000
	s_addc_u32 s15, s59, 0
	s_mov_b32 m0, s62
	v_lshl_add_u64 v[240:241], s[14:15], 0, v[134:135]
	ds_read_b128 v[198:201], v171 offset:32768
	ds_read_b128 v[208:211], v171 offset:33792
	ds_read_b128 v[212:215], v171 offset:34816
	ds_read_b128 v[216:219], v171 offset:35840
	ds_read_b128 v[220:223], v171 offset:36864
	ds_read_b128 v[224:227], v171 offset:37888
	ds_read_b128 v[228:231], v171 offset:38912
	ds_read_b128 v[232:235], v171 offset:39936
	global_load_lds_dwordx4 v[240:241], off
	v_lshl_add_u64 v[240:241], s[14:15], 0, v[130:131]
	s_mov_b32 m0, s63
	s_nop 0
	global_load_lds_dwordx4 v[240:241], off
	s_waitcnt vmcnt(8)
	s_waitcnt lgkmcnt(0)
	s_barrier
	s_setprio 1
	s_waitcnt lgkmcnt(0)
	v_mfma_f32_16x16x32_bf16 v[124:127], v[154:157], v[198:201], v[124:127]
	v_mfma_f32_16x16x32_bf16 v[120:123], v[162:165], v[198:201], v[120:123]
	v_mfma_f32_16x16x32_bf16 v[112:115], v[162:165], v[212:215], v[112:115]
	v_mfma_f32_16x16x32_bf16 v[116:119], v[154:157], v[212:215], v[116:119]
	v_mfma_f32_16x16x32_bf16 v[108:111], v[154:157], v[220:223], v[108:111]
	v_mfma_f32_16x16x32_bf16 v[104:107], v[162:165], v[220:223], v[104:107]
	v_mfma_f32_16x16x32_bf16 v[96:99], v[162:165], v[228:231], v[96:99]
	v_mfma_f32_16x16x32_bf16 v[100:103], v[154:157], v[228:231], v[100:103]
	v_mfma_f32_16x16x32_bf16 v[124:127], v[158:161], v[208:211], v[124:127]
	v_mfma_f32_16x16x32_bf16 v[120:123], v[174:177], v[208:211], v[120:123]
	v_mfma_f32_16x16x32_bf16 v[112:115], v[174:177], v[216:219], v[112:115]
	v_mfma_f32_16x16x32_bf16 v[116:119], v[158:161], v[216:219], v[116:119]
	v_mfma_f32_16x16x32_bf16 v[108:111], v[158:161], v[224:227], v[108:111]
	v_mfma_f32_16x16x32_bf16 v[104:107], v[174:177], v[224:227], v[104:107]
	v_mfma_f32_16x16x32_bf16 v[96:99], v[174:177], v[232:235], v[96:99]
	v_mfma_f32_16x16x32_bf16 v[100:103], v[158:161], v[232:235], v[100:103]
	s_setprio 0
	s_setprio 1
	v_mfma_f32_16x16x32_bf16 v[68:71], v[182:185], v[198:201], v[68:71]
	v_mfma_f32_16x16x32_bf16 v[64:67], v[190:193], v[198:201], v[64:67]
	v_mfma_f32_16x16x32_bf16 v[48:51], v[190:193], v[212:215], v[48:51]
	v_mfma_f32_16x16x32_bf16 v[52:55], v[182:185], v[212:215], v[52:55]
	v_mfma_f32_16x16x32_bf16 v[44:47], v[182:185], v[220:223], v[44:47]
	v_mfma_f32_16x16x32_bf16 v[40:43], v[190:193], v[220:223], v[40:43]
	v_mfma_f32_16x16x32_bf16 v[32:35], v[190:193], v[228:231], v[32:35]
	v_mfma_f32_16x16x32_bf16 v[36:39], v[182:185], v[228:231], v[36:39]
	v_mfma_f32_16x16x32_bf16 v[68:71], v[186:189], v[208:211], v[68:71]
	v_mfma_f32_16x16x32_bf16 v[64:67], v[194:197], v[208:211], v[64:67]
	v_mfma_f32_16x16x32_bf16 v[48:51], v[194:197], v[216:219], v[48:51]
	v_mfma_f32_16x16x32_bf16 v[52:55], v[186:189], v[216:219], v[52:55]
	v_mfma_f32_16x16x32_bf16 v[44:47], v[186:189], v[224:227], v[44:47]
	v_mfma_f32_16x16x32_bf16 v[40:43], v[194:197], v[224:227], v[40:43]
	v_mfma_f32_16x16x32_bf16 v[32:35], v[194:197], v[232:235], v[32:35]
	v_mfma_f32_16x16x32_bf16 v[36:39], v[186:189], v[232:235], v[36:39]
	s_setprio 0
	s_barrier
; #define PG8_STAGE(bufoff, gbase, voff) do { _Pragma("unroll") for (int _i = 0; _i < 2; ++_i) \
;         __builtin_amdgcn_global_load_lds((const unsigned*)((const char*)(gbase) + (voff)[_i]), (PG8_LAS unsigned*)(lds + (bufoff) + ldsw + _i * 8192), 16, 0, 0); } while (0)
; #define PG8_LDA(dst, b, h) do { _Pragma("unroll") for (int m = 0; m < 4; ++m) _Pragma("unroll") for (int k = 0; k < 2; ++k) dst[m][k] = *(const PG8_LAS bf16x8*)(lds + PG8_SA(b, h) + aoff + m * 2048 + k * 1024); } while (0)
; #define PG8_LDB(dst, b, h) do { _Pragma("unroll") for (int n = 0; n < 2; ++n) _Pragma("unroll") for (int k = 0; k < 2; ++k) dst[n][k] = *(const PG8_LAS bf16x8*)(lds + PG8_SB(b, h) + boff + n * 2048 + k * 1024); } while (0)
; #define PG8_BAR __builtin_amdgcn_s_barrier()
; template <class Epi, class Sched, bool ALIGN_EPI = false, bool SP2 = false>
; __device__ __forceinline__ void gemm_phase(PG8_LAS unsigned char* lds, const Gemm g, const Sched& S, const Epi& E) {
;     ...
;             const bool last = (t == nt - 2);
;             const char* a1 = cA + (size_t)(t + 1) * kstep;
;             const char* a2 = last ? nA : cA + (size_t)(t + 2) * kstep; const char* b2 = last ? nB : cB + (size_t)(t + 2) * kstep;
;             const char* a3 = a2 + kstep; const char* b3 = b2 + kstep;
;             if (last && has_next) S.a_ready(nxt);
;             if constexpr (SP2) {
;             PG8_LDB(B0, 0, 0); PG8_LDB(B1, 0, 1); PG8_SCHED; PG8_LDA(At, 0, 0); PG8_STAGE(PG8_SA(1, 1), a1 + hstep, voffA);
;             PG8_WAIT_V(8); PG8_WAIT_L(0); PG8_BAR; PG8_MMA(0, 0, At, B0); PG8_MMA(0, 1, At, B1); PG8_BAR; PG8_SCHED;
;             PG8_LDA(At, 0, 1); PG8_STAGE(PG8_SB(0, 0), b2, voffB); PG8_STAGE(PG8_SB(0, 1), b2 + hstep, voffB); PG8_STAGE(PG8_SA(0, 0), a2, voffA);
;             PG8_WAIT_V(8); PG8_WAIT_L(0); PG8_BAR; PG8_MMA(1, 0, At, B0); PG8_MMA(1, 1, At, B1); PG8_BAR; PG8_SCHED;
;             PG8_LDB(B0, 1, 0); PG8_LDB(B1, 1, 1); PG8_SCHED; PG8_LDA(At, 1, 0); PG8_STAGE(PG8_SA(0, 1), a2 + hstep, voffA);
;             PG8_WAIT_V(8); PG8_WAIT_L(0); PG8_BAR; PG8_MMA(0, 0, At, B0); PG8_MMA(0, 1, At, B1); PG8_BAR; PG8_SCHED;
;             PG8_LDA(At, 1, 1); PG8_STAGE(PG8_SB(1, 0), b3, voffB); PG8_STAGE(PG8_SB(1, 1), b3 + hstep, voffB); PG8_STAGE(PG8_SA(1, 0), a3, voffA);
;             PG8_WAIT_V(8); PG8_WAIT_L(0); PG8_BAR; PG8_MMA(1, 0, At, B0); PG8_MMA(1, 1, At, B1); PG8_BAR; PG8_SCHED;
	s_add_i32 s3, s3, s34
	v_lshl_add_u64 v[178:179], v[178:179], 0, s[8:9]
	s_mov_b32 m0, s3
	ds_read_b128 v[198:201], v171 offset:49152
	ds_read_b128 v[208:211], v171 offset:50176
	ds_read_b128 v[212:215], v171 offset:51200
	ds_read_b128 v[216:219], v171 offset:52224
	ds_read_b128 v[220:223], v171 offset:53248
	ds_read_b128 v[224:227], v171 offset:54272
	ds_read_b128 v[228:231], v171 offset:55296
	ds_read_b128 v[232:235], v171 offset:56320
	global_load_lds_dwordx4 v[178:179], off
	s_add_i32 m0, s3, 0x2000
	s_add_u32 s14, s56, 0x40080
	v_lshl_add_u64 v[178:179], v[202:203], 0, s[8:9]
	s_addc_u32 s15, s57, 0
	s_add_i32 s3, s33, s34
	global_load_lds_dwordx4 v[178:179], off
	v_lshl_add_u64 v[178:179], s[14:15], 0, v[132:133]
	s_mov_b32 m0, s3
	s_nop 0
	global_load_lds_dwordx4 v[178:179], off
	v_lshl_add_u64 v[178:179], s[14:15], 0, v[128:129]
	s_add_i32 m0, s3, 0x2000
	s_nop 0
	global_load_lds_dwordx4 v[178:179], off
	s_waitcnt vmcnt(6)
	s_waitcnt lgkmcnt(0)
	s_barrier
	s_setprio 1
	s_waitcnt lgkmcnt(0)
	v_mfma_f32_16x16x32_bf16 v[92:95], v[154:157], v[198:201], v[92:95]
	v_mfma_f32_16x16x32_bf16 v[88:91], v[162:165], v[198:201], v[88:91]
	v_mfma_f32_16x16x32_bf16 v[80:83], v[162:165], v[212:215], v[80:83]
	v_mfma_f32_16x16x32_bf16 v[84:87], v[154:157], v[212:215], v[84:87]
	v_mfma_f32_16x16x32_bf16 v[76:79], v[154:157], v[220:223], v[76:79]
	v_mfma_f32_16x16x32_bf16 v[72:75], v[162:165], v[220:223], v[72:75]
	v_mfma_f32_16x16x32_bf16 v[56:59], v[162:165], v[228:231], v[56:59]
	v_mfma_f32_16x16x32_bf16 v[60:63], v[154:157], v[228:231], v[60:63]
	v_mfma_f32_16x16x32_bf16 v[92:95], v[158:161], v[208:211], v[92:95]
	v_mfma_f32_16x16x32_bf16 v[88:91], v[174:177], v[208:211], v[88:91]
	v_mfma_f32_16x16x32_bf16 v[80:83], v[174:177], v[216:219], v[80:83]
	v_mfma_f32_16x16x32_bf16 v[84:87], v[158:161], v[216:219], v[84:87]
	v_mfma_f32_16x16x32_bf16 v[76:79], v[158:161], v[224:227], v[76:79]
	v_mfma_f32_16x16x32_bf16 v[72:75], v[174:177], v[224:227], v[72:75]
	v_lshl_add_u64 v[178:179], v[236:237], 0, s[8:9]
	s_mov_b32 m0, s66
	s_nop 0
	global_load_lds_dwordx4 v[178:179], off
	v_mfma_f32_16x16x32_bf16 v[56:59], v[174:177], v[232:235], v[56:59]
	v_mfma_f32_16x16x32_bf16 v[60:63], v[158:161], v[232:235], v[60:63]
	s_setprio 0
	s_setprio 1
	v_mfma_f32_16x16x32_bf16 v[28:31], v[182:185], v[198:201], v[28:31]
	v_mfma_f32_16x16x32_bf16 v[24:27], v[190:193], v[198:201], v[24:27]
	v_mfma_f32_16x16x32_bf16 v[16:19], v[190:193], v[212:215], v[16:19]
	v_mfma_f32_16x16x32_bf16 v[20:23], v[182:185], v[212:215], v[20:23]
	v_mfma_f32_16x16x32_bf16 v[12:15], v[182:185], v[220:223], v[12:15]
	v_mfma_f32_16x16x32_bf16 v[8:11], v[190:193], v[220:223], v[8:11]
	v_mfma_f32_16x16x32_bf16 v[0:3], v[190:193], v[228:231], v[0:3]
	v_mfma_f32_16x16x32_bf16 v[4:7], v[182:185], v[228:231], v[4:7]
	v_mfma_f32_16x16x32_bf16 v[28:31], v[186:189], v[208:211], v[28:31]
	v_mfma_f32_16x16x32_bf16 v[24:27], v[194:197], v[208:211], v[24:27]
	v_mfma_f32_16x16x32_bf16 v[16:19], v[194:197], v[216:219], v[16:19]
	v_mfma_f32_16x16x32_bf16 v[20:23], v[186:189], v[216:219], v[20:23]
	v_mfma_f32_16x16x32_bf16 v[12:15], v[186:189], v[224:227], v[12:15]
	v_mfma_f32_16x16x32_bf16 v[8:11], v[194:197], v[224:227], v[8:11]
	v_lshl_add_u64 v[178:179], v[238:239], 0, s[8:9]
	s_mov_b32 m0, s67
	s_nop 0
	global_load_lds_dwordx4 v[178:179], off
	v_mfma_f32_16x16x32_bf16 v[0:3], v[194:197], v[232:235], v[0:3]
	v_mfma_f32_16x16x32_bf16 v[4:7], v[186:189], v[232:235], v[4:7]
	s_setprio 0
	s_barrier
	s_add_i32 s93, s93, 2
	s_add_u32 s54, s54, 0x100
	s_addc_u32 s55, s55, 0
	s_add_u32 s91, s91, 0x100
	s_addc_u32 s92, s92, 0
.LBB0_417:
	ds_read_b128 v[154:157], v169
	ds_read_b128 v[158:161], v169 offset:1024
	ds_read_b128 v[162:165], v169 offset:2048
	ds_read_b128 v[174:177], v169 offset:3072
	ds_read_b128 v[182:185], v170
	ds_read_b128 v[186:189], v170 offset:1024
	ds_read_b128 v[190:193], v170 offset:2048
	ds_read_b128 v[194:197], v170 offset:3072
	s_add_u32 s3, s54, 0xfffc0080
	s_addc_u32 s14, s55, -1
	s_cmp_eq_u32 s93, 12
	s_cselect_b32 s59, s45, s14
	s_cselect_b32 s58, s89, s3
	s_cselect_b32 s57, s41, s92
	s_cselect_b32 s56, s90, s91
	v_lshl_add_u64 v[178:179], s[54:55], 0, v[146:147]
	s_add_i32 m0, s60, 0xc000
	ds_read_b128 v[198:201], v171
	ds_read_b128 v[208:211], v171 offset:1024
	ds_read_b128 v[212:215], v171 offset:2048
	ds_read_b128 v[216:219], v171 offset:3072
	ds_read_b128 v[220:223], v171 offset:4096
	ds_read_b128 v[224:227], v171 offset:5120
	ds_read_b128 v[228:231], v171 offset:6144
	ds_read_b128 v[232:235], v171 offset:7168
	global_load_lds_dwordx4 v[178:179], off
	v_lshl_add_u64 v[178:179], s[54:55], 0, v[148:149]
	s_add_i32 m0, s60, 0xe000
	s_nop 0
	global_load_lds_dwordx4 v[178:179], off
	s_waitcnt vmcnt(8)
	s_waitcnt lgkmcnt(0)
	s_barrier
; #define PG8_STAGE(bufoff, gbase, voff) do { _Pragma("unroll") for (int _i = 0; _i < 2; ++_i) \
;         __builtin_amdgcn_global_load_lds((const unsigned*)((const char*)(gbase) + (voff)[_i]), (PG8_LAS unsigned*)(lds + (bufoff) + ldsw + _i * 8192), 16, 0, 0); } while (0)
; #define PG8_LDA(dst, b, h) do { _Pragma("unroll") for (int m = 0; m < 4; ++m) _Pragma("unroll") for (int k = 0; k < 2; ++k) dst[m][k] = *(const PG8_LAS bf16x8*)(lds + PG8_SA(b, h) + aoff + m * 2048 + k * 1024); } while (0)
; #define PG8_MMA(ai, bj, At, Bt) do { __builtin_amdgcn_s_setprio(1); _Pragma("unroll") for (int m = 0; m < 4; ++m) _Pragma("unroll") for (int n = 0; n < 2; ++n) _Pragma("unroll") for (int k = 0; k < 2; ++k) \
;         acc[ai][bj][m][n] = __builtin_amdgcn_mfma_f32_16x16x32_bf16(Bt[n][k], At[m][k], acc[ai][bj][m][n], 0, 0, 0); __builtin_amdgcn_s_setprio(0); } while (0)
; #define PG8_WAIT_V(n) asm volatile("s_waitcnt vmcnt(" #n ")" ::: "memory")
; #define PG8_WAIT_L(n) asm volatile("s_waitcnt lgkmcnt(" #n ")" ::: "memory")
; #define PG8_BAR __builtin_amdgcn_s_barrier()
; #define PG8_SCHED __builtin_amdgcn_sched_barrier(0)
; template <class Epi, class Sched, bool ALIGN_EPI = false, bool SP2 = false>
; __device__ __forceinline__ void gemm_phase(PG8_LAS unsigned char* lds, const Gemm g, const Sched& S, const Epi& E) {
;     ...
;             PG8_WAIT_V(8); PG8_WAIT_L(0); PG8_BAR; PG8_MMA(0, 0, At, B0); PG8_MMA(0, 1, At, B1); PG8_BAR; PG8_SCHED;
;             PG8_LDA(At, 0, 1); PG8_STAGE(PG8_SB(0, 0), b2, voffB); PG8_STAGE(PG8_SB(0, 1), b2 + hstep, voffB); PG8_STAGE(PG8_SA(0, 0), a2, voffA);
;             PG8_WAIT_V(8); PG8_WAIT_L(0); PG8_BAR; PG8_MMA(1, 0, At, B0); PG8_MMA(1, 1, At, B1); PG8_BAR; PG8_SCHED;
	s_setprio 1
	s_waitcnt lgkmcnt(0)
	v_mfma_f32_16x16x32_bf16 v[124:127], v[154:157], v[198:201], v[124:127]
	v_mfma_f32_16x16x32_bf16 v[120:123], v[162:165], v[198:201], v[120:123]
	v_mfma_f32_16x16x32_bf16 v[112:115], v[162:165], v[212:215], v[112:115]
	v_mfma_f32_16x16x32_bf16 v[116:119], v[154:157], v[212:215], v[116:119]
	v_mfma_f32_16x16x32_bf16 v[108:111], v[154:157], v[220:223], v[108:111]
	v_mfma_f32_16x16x32_bf16 v[104:107], v[162:165], v[220:223], v[104:107]
	v_mfma_f32_16x16x32_bf16 v[96:99], v[162:165], v[228:231], v[96:99]
	v_mfma_f32_16x16x32_bf16 v[100:103], v[154:157], v[228:231], v[100:103]
	v_mfma_f32_16x16x32_bf16 v[124:127], v[158:161], v[208:211], v[124:127]
	v_mfma_f32_16x16x32_bf16 v[120:123], v[174:177], v[208:211], v[120:123]
	v_mfma_f32_16x16x32_bf16 v[112:115], v[174:177], v[216:219], v[112:115]
	v_mfma_f32_16x16x32_bf16 v[116:119], v[158:161], v[216:219], v[116:119]
	v_mfma_f32_16x16x32_bf16 v[108:111], v[158:161], v[224:227], v[108:111]
	v_mfma_f32_16x16x32_bf16 v[104:107], v[174:177], v[224:227], v[104:107]
	v_mfma_f32_16x16x32_bf16 v[96:99], v[174:177], v[232:235], v[96:99]
	v_mfma_f32_16x16x32_bf16 v[100:103], v[158:161], v[232:235], v[100:103]
	s_setprio 0
	s_setprio 1
	v_mfma_f32_16x16x32_bf16 v[68:71], v[182:185], v[198:201], v[68:71]
	v_mfma_f32_16x16x32_bf16 v[64:67], v[190:193], v[198:201], v[64:67]
	v_mfma_f32_16x16x32_bf16 v[48:51], v[190:193], v[212:215], v[48:51]
	v_mfma_f32_16x16x32_bf16 v[52:55], v[182:185], v[212:215], v[52:55]
	v_mfma_f32_16x16x32_bf16 v[44:47], v[182:185], v[220:223], v[44:47]
	v_mfma_f32_16x16x32_bf16 v[40:43], v[190:193], v[220:223], v[40:43]
	v_mfma_f32_16x16x32_bf16 v[32:35], v[190:193], v[228:231], v[32:35]
	v_mfma_f32_16x16x32_bf16 v[36:39], v[182:185], v[228:231], v[36:39]
	v_mfma_f32_16x16x32_bf16 v[68:71], v[186:189], v[208:211], v[68:71]
	v_mfma_f32_16x16x32_bf16 v[64:67], v[194:197], v[208:211], v[64:67]
	v_mfma_f32_16x16x32_bf16 v[48:51], v[194:197], v[216:219], v[48:51]
	v_mfma_f32_16x16x32_bf16 v[52:55], v[186:189], v[216:219], v[52:55]
	v_mfma_f32_16x16x32_bf16 v[44:47], v[186:189], v[224:227], v[44:47]
	v_mfma_f32_16x16x32_bf16 v[40:43], v[194:197], v[224:227], v[40:43]
	v_mfma_f32_16x16x32_bf16 v[32:35], v[194:197], v[232:235], v[32:35]
	v_mfma_f32_16x16x32_bf16 v[36:39], v[186:189], v[232:235], v[36:39]
	s_setprio 0
	s_barrier
	s_add_i32 s3, s86, s34
	v_lshl_add_u64 v[178:179], s[56:57], 0, v[132:133]
	s_mov_b32 m0, s3
	ds_read_b128 v[198:201], v171 offset:16384
	ds_read_b128 v[208:211], v171 offset:17408
	ds_read_b128 v[212:215], v171 offset:18432
	ds_read_b128 v[216:219], v171 offset:19456
	ds_read_b128 v[220:223], v171 offset:20480
	ds_read_b128 v[224:227], v171 offset:21504
	ds_read_b128 v[228:231], v171 offset:22528
	ds_read_b128 v[232:235], v171 offset:23552
	global_load_lds_dwordx4 v[178:179], off
	s_add_i32 m0, s3, 0x2000
	s_add_u32 s14, s56, 0x40000
	v_lshl_add_u64 v[202:203], s[56:57], 0, v[128:129]
	s_addc_u32 s15, s57, 0
	s_add_i32 s3, s87, s34
	global_load_lds_dwordx4 v[202:203], off
	v_lshl_add_u64 v[236:237], s[14:15], 0, v[132:133]
	s_mov_b32 m0, s3
	global_load_lds_dwordx4 v[236:237], off
	v_lshl_add_u64 v[236:237], s[14:15], 0, v[128:129]
	s_add_i32 m0, s3, 0x2000
	s_nop 0
	global_load_lds_dwordx4 v[236:237], off
	s_waitcnt vmcnt(6)
	s_waitcnt lgkmcnt(0)
	s_barrier
	s_setprio 1
	s_waitcnt lgkmcnt(0)
	v_mfma_f32_16x16x32_bf16 v[92:95], v[154:157], v[198:201], v[92:95]
	v_mfma_f32_16x16x32_bf16 v[88:91], v[162:165], v[198:201], v[88:91]
	v_mfma_f32_16x16x32_bf16 v[80:83], v[162:165], v[212:215], v[80:83]
	v_mfma_f32_16x16x32_bf16 v[84:87], v[154:157], v[212:215], v[84:87]
	v_mfma_f32_16x16x32_bf16 v[76:79], v[154:157], v[220:223], v[76:79]
	v_mfma_f32_16x16x32_bf16 v[72:75], v[162:165], v[220:223], v[72:75]
	v_mfma_f32_16x16x32_bf16 v[56:59], v[162:165], v[228:231], v[56:59]
	v_mfma_f32_16x16x32_bf16 v[60:63], v[154:157], v[228:231], v[60:63]
	v_mfma_f32_16x16x32_bf16 v[92:95], v[158:161], v[208:211], v[92:95]
	v_mfma_f32_16x16x32_bf16 v[88:91], v[174:177], v[208:211], v[88:91]
	v_mfma_f32_16x16x32_bf16 v[80:83], v[174:177], v[216:219], v[80:83]
	v_mfma_f32_16x16x32_bf16 v[84:87], v[158:161], v[216:219], v[84:87]
	v_mfma_f32_16x16x32_bf16 v[76:79], v[158:161], v[224:227], v[76:79]
	v_mfma_f32_16x16x32_bf16 v[72:75], v[174:177], v[224:227], v[72:75]
	v_lshl_add_u64 v[236:237], s[58:59], 0, v[134:135]
	s_mov_b32 m0, s60
	s_nop 0
	global_load_lds_dwordx4 v[236:237], off
	v_mfma_f32_16x16x32_bf16 v[56:59], v[174:177], v[232:235], v[56:59]
	v_mfma_f32_16x16x32_bf16 v[60:63], v[158:161], v[232:235], v[60:63]
	s_setprio 0
	s_setprio 1
	v_mfma_f32_16x16x32_bf16 v[28:31], v[182:185], v[198:201], v[28:31]
	v_mfma_f32_16x16x32_bf16 v[24:27], v[190:193], v[198:201], v[24:27]
	v_mfma_f32_16x16x32_bf16 v[16:19], v[190:193], v[212:215], v[16:19]
	v_mfma_f32_16x16x32_bf16 v[20:23], v[182:185], v[212:215], v[20:23]
	v_mfma_f32_16x16x32_bf16 v[12:15], v[182:185], v[220:223], v[12:15]
	v_mfma_f32_16x16x32_bf16 v[8:11], v[190:193], v[220:223], v[8:11]
	v_mfma_f32_16x16x32_bf16 v[0:3], v[190:193], v[228:231], v[0:3]
	v_mfma_f32_16x16x32_bf16 v[4:7], v[182:185], v[228:231], v[4:7]
	v_mfma_f32_16x16x32_bf16 v[28:31], v[186:189], v[208:211], v[28:31]
	v_mfma_f32_16x16x32_bf16 v[24:27], v[194:197], v[208:211], v[24:27]
	v_mfma_f32_16x16x32_bf16 v[16:19], v[194:197], v[216:219], v[16:19]
	v_mfma_f32_16x16x32_bf16 v[20:23], v[186:189], v[216:219], v[20:23]
	v_mfma_f32_16x16x32_bf16 v[12:15], v[186:189], v[224:227], v[12:15]
	v_mfma_f32_16x16x32_bf16 v[8:11], v[194:197], v[224:227], v[8:11]
	v_lshl_add_u64 v[238:239], s[58:59], 0, v[130:131]
	s_mov_b32 m0, s61
	s_nop 0
	global_load_lds_dwordx4 v[238:239], off
	v_mfma_f32_16x16x32_bf16 v[0:3], v[194:197], v[232:235], v[0:3]
	v_mfma_f32_16x16x32_bf16 v[4:7], v[186:189], v[232:235], v[4:7]
	s_setprio 0
	s_barrier
; #define PG8_STAGE(bufoff, gbase, voff) do { _Pragma("unroll") for (int _i = 0; _i < 2; ++_i) \
;         __builtin_amdgcn_global_load_lds((const unsigned*)((const char*)(gbase) + (voff)[_i]), (PG8_LAS unsigned*)(lds + (bufoff) + ldsw + _i * 8192), 16, 0, 0); } while (0)
; #define PG8_LDA(dst, b, h) do { _Pragma("unroll") for (int m = 0; m < 4; ++m) _Pragma("unroll") for (int k = 0; k < 2; ++k) dst[m][k] = *(const PG8_LAS bf16x8*)(lds + PG8_SA(b, h) + aoff + m * 2048 + k * 1024); } while (0)
; #define PG8_LDB(dst, b, h) do { _Pragma("unroll") for (int n = 0; n < 2; ++n) _Pragma("unroll") for (int k = 0; k < 2; ++k) dst[n][k] = *(const PG8_LAS bf16x8*)(lds + PG8_SB(b, h) + boff + n * 2048 + k * 1024); } while (0)
; #define PG8_MMA(ai, bj, At, Bt) do { __builtin_amdgcn_s_setprio(1); _Pragma("unroll") for (int m = 0; m < 4; ++m) _Pragma("unroll") for (int n = 0; n < 2; ++n) _Pragma("unroll") for (int k = 0; k < 2; ++k) \
;         acc[ai][bj][m][n] = __builtin_amdgcn_mfma_f32_16x16x32_bf16(Bt[n][k], At[m][k], acc[ai][bj][m][n], 0, 0, 0); __builtin_amdgcn_s_setprio(0); } while (0)
; #define PG8_WAIT_V(n) asm volatile("s_waitcnt vmcnt(" #n ")" ::: "memory")
; #define PG8_WAIT_L(n) asm volatile("s_waitcnt lgkmcnt(" #n ")" ::: "memory")
; #define PG8_BAR __builtin_amdgcn_s_barrier()
; #define PG8_SCHED __builtin_amdgcn_sched_barrier(0)
; template <class Epi, class Sched, bool ALIGN_EPI = false, bool SP2 = false>
; __device__ __forceinline__ void gemm_phase(PG8_LAS unsigned char* lds, const Gemm g, const Sched& S, const Epi& E) {
;     ...
;             PG8_LDB(B0, 1, 0); PG8_LDB(B1, 1, 1); PG8_SCHED; PG8_LDA(At, 1, 0); PG8_STAGE(PG8_SA(0, 1), a2 + hstep, voffA);
;             PG8_WAIT_V(8); PG8_WAIT_L(0); PG8_BAR; PG8_MMA(0, 0, At, B0); PG8_MMA(0, 1, At, B1); PG8_BAR; PG8_SCHED;
	s_add_i32 s3, 0, 0x18000
	v_add_u32_e32 v136, s3, v143
	s_add_i32 s33, 0, 0x1c000
	ds_read_b128 v[154:157], v136
	ds_read_b128 v[158:161], v136 offset:1024
	ds_read_b128 v[162:165], v136 offset:2048
	ds_read_b128 v[174:177], v136 offset:3072
	v_add_u32_e32 v136, s33, v143
	ds_read_b128 v[182:185], v136
	ds_read_b128 v[186:189], v136 offset:1024
	ds_read_b128 v[190:193], v136 offset:2048
	ds_read_b128 v[194:197], v136 offset:3072
	s_add_u32 s14, s58, 0x40000
	s_addc_u32 s15, s59, 0
	s_mov_b32 m0, s62
	v_lshl_add_u64 v[240:241], s[14:15], 0, v[134:135]
	ds_read_b128 v[198:201], v171 offset:32768
	ds_read_b128 v[208:211], v171 offset:33792
	ds_read_b128 v[212:215], v171 offset:34816
	ds_read_b128 v[216:219], v171 offset:35840
	ds_read_b128 v[220:223], v171 offset:36864
	ds_read_b128 v[224:227], v171 offset:37888
	ds_read_b128 v[228:231], v171 offset:38912
	ds_read_b128 v[232:235], v171 offset:39936
	global_load_lds_dwordx4 v[240:241], off
	v_lshl_add_u64 v[240:241], s[14:15], 0, v[130:131]
	s_mov_b32 m0, s63
	s_nop 0
	global_load_lds_dwordx4 v[240:241], off
	s_waitcnt vmcnt(8)
	s_waitcnt lgkmcnt(0)
	s_barrier
	s_setprio 1
	s_waitcnt lgkmcnt(0)
	v_mfma_f32_16x16x32_bf16 v[124:127], v[154:157], v[198:201], v[124:127]
	v_mfma_f32_16x16x32_bf16 v[120:123], v[162:165], v[198:201], v[120:123]
	v_mfma_f32_16x16x32_bf16 v[112:115], v[162:165], v[212:215], v[112:115]
	v_mfma_f32_16x16x32_bf16 v[116:119], v[154:157], v[212:215], v[116:119]
	v_mfma_f32_16x16x32_bf16 v[108:111], v[154:157], v[220:223], v[108:111]
	v_mfma_f32_16x16x32_bf16 v[104:107], v[162:165], v[220:223], v[104:107]
	v_mfma_f32_16x16x32_bf16 v[96:99], v[162:165], v[228:231], v[96:99]
	v_mfma_f32_16x16x32_bf16 v[100:103], v[154:157], v[228:231], v[100:103]
	v_mfma_f32_16x16x32_bf16 v[124:127], v[158:161], v[208:211], v[124:127]
	v_mfma_f32_16x16x32_bf16 v[120:123], v[174:177], v[208:211], v[120:123]
	v_mfma_f32_16x16x32_bf16 v[112:115], v[174:177], v[216:219], v[112:115]
	v_mfma_f32_16x16x32_bf16 v[116:119], v[158:161], v[216:219], v[116:119]
	v_mfma_f32_16x16x32_bf16 v[108:111], v[158:161], v[224:227], v[108:111]
	v_mfma_f32_16x16x32_bf16 v[104:107], v[174:177], v[224:227], v[104:107]
	v_mfma_f32_16x16x32_bf16 v[96:99], v[174:177], v[232:235], v[96:99]
	v_mfma_f32_16x16x32_bf16 v[100:103], v[158:161], v[232:235], v[100:103]
	s_setprio 0
	s_setprio 1
	v_mfma_f32_16x16x32_bf16 v[68:71], v[182:185], v[198:201], v[68:71]
	v_mfma_f32_16x16x32_bf16 v[64:67], v[190:193], v[198:201], v[64:67]
	v_mfma_f32_16x16x32_bf16 v[48:51], v[190:193], v[212:215], v[48:51]
	v_mfma_f32_16x16x32_bf16 v[52:55], v[182:185], v[212:215], v[52:55]
	v_mfma_f32_16x16x32_bf16 v[44:47], v[182:185], v[220:223], v[44:47]
	v_mfma_f32_16x16x32_bf16 v[40:43], v[190:193], v[220:223], v[40:43]
	v_mfma_f32_16x16x32_bf16 v[32:35], v[190:193], v[228:231], v[32:35]
	v_mfma_f32_16x16x32_bf16 v[36:39], v[182:185], v[228:231], v[36:39]
	v_mfma_f32_16x16x32_bf16 v[68:71], v[186:189], v[208:211], v[68:71]
	v_mfma_f32_16x16x32_bf16 v[64:67], v[194:197], v[208:211], v[64:67]
	v_mfma_f32_16x16x32_bf16 v[48:51], v[194:197], v[216:219], v[48:51]
	v_mfma_f32_16x16x32_bf16 v[52:55], v[186:189], v[216:219], v[52:55]
	v_mfma_f32_16x16x32_bf16 v[44:47], v[186:189], v[224:227], v[44:47]
	v_mfma_f32_16x16x32_bf16 v[40:43], v[194:197], v[224:227], v[40:43]
	v_mfma_f32_16x16x32_bf16 v[32:35], v[194:197], v[232:235], v[32:35]
	v_mfma_f32_16x16x32_bf16 v[36:39], v[186:189], v[232:235], v[36:39]
	s_setprio 0
	s_barrier
; #define PG8_STAGE(bufoff, gbase, voff) do { _Pragma("unroll") for (int _i = 0; _i < 2; ++_i) \
;         __builtin_amdgcn_global_load_lds((const unsigned*)((const char*)(gbase) + (voff)[_i]), (PG8_LAS unsigned*)(lds + (bufoff) + ldsw + _i * 8192), 16, 0, 0); } while (0)
; #define PG8_LDA(dst, b, h) do { _Pragma("unroll") for (int m = 0; m < 4; ++m) _Pragma("unroll") for (int k = 0; k < 2; ++k) dst[m][k] = *(const PG8_LAS bf16x8*)(lds + PG8_SA(b, h) + aoff + m * 2048 + k * 1024); } while (0)
; #define PG8_MMA(ai, bj, At, Bt) do { __builtin_amdgcn_s_setprio(1); _Pragma("unroll") for (int m = 0; m < 4; ++m) _Pragma("unroll") for (int n = 0; n < 2; ++n) _Pragma("unroll") for (int k = 0; k < 2; ++k) \
;         acc[ai][bj][m][n] = __builtin_amdgcn_mfma_f32_16x16x32_bf16(Bt[n][k], At[m][k], acc[ai][bj][m][n], 0, 0, 0); __builtin_amdgcn_s_setprio(0); } while (0)
; #define PG8_WAIT_V(n) asm volatile("s_waitcnt vmcnt(" #n ")" ::: "memory")
; #define PG8_WAIT_L(n) asm volatile("s_waitcnt lgkmcnt(" #n ")" ::: "memory")
; #define PG8_BAR __builtin_amdgcn_s_barrier()
; #define PG8_SCHED __builtin_amdgcn_sched_barrier(0)
; template <class Epi, class Sched, bool ALIGN_EPI = false, bool SP2 = false>
; __device__ __forceinline__ void gemm_phase(PG8_LAS unsigned char* lds, const Gemm g, const Sched& S, const Epi& E) {
;     ...
;             PG8_LDA(At, 1, 1); PG8_STAGE(PG8_SB(1, 0), b3, voffB); PG8_STAGE(PG8_SB(1, 1), b3 + hstep, voffB); PG8_STAGE(PG8_SA(1, 0), a3, voffA);
;             PG8_WAIT_V(8); PG8_WAIT_L(0); PG8_BAR; PG8_MMA(1, 0, At, B0); PG8_MMA(1, 1, At, B1); PG8_BAR; PG8_SCHED;
;     ...
;         if constexpr (ALIGN_EPI) { if (wr == 0) PG8_BAR; }
	s_add_i32 s3, s3, s34
	v_lshl_add_u64 v[178:179], v[178:179], 0, s[8:9]
	s_mov_b32 m0, s3
	ds_read_b128 v[198:201], v171 offset:49152
	ds_read_b128 v[208:211], v171 offset:50176
	ds_read_b128 v[212:215], v171 offset:51200
	ds_read_b128 v[216:219], v171 offset:52224
	ds_read_b128 v[220:223], v171 offset:53248
	ds_read_b128 v[224:227], v171 offset:54272
	ds_read_b128 v[228:231], v171 offset:55296
	ds_read_b128 v[232:235], v171 offset:56320
	global_load_lds_dwordx4 v[178:179], off
	s_add_i32 m0, s3, 0x2000
	s_add_u32 s14, s56, 0x40080
	v_lshl_add_u64 v[178:179], v[202:203], 0, s[8:9]
	s_addc_u32 s15, s57, 0
	s_add_i32 s3, s33, s34
	global_load_lds_dwordx4 v[178:179], off
	v_lshl_add_u64 v[178:179], s[14:15], 0, v[132:133]
	s_mov_b32 m0, s3
	s_nop 0
	global_load_lds_dwordx4 v[178:179], off
	v_lshl_add_u64 v[178:179], s[14:15], 0, v[128:129]
	s_add_i32 m0, s3, 0x2000
	s_nop 0
	global_load_lds_dwordx4 v[178:179], off
	s_waitcnt vmcnt(6)
	s_waitcnt lgkmcnt(0)
	s_barrier
	s_setprio 1
	s_waitcnt lgkmcnt(0)
	v_mfma_f32_16x16x32_bf16 v[92:95], v[154:157], v[198:201], v[92:95]
	v_mfma_f32_16x16x32_bf16 v[88:91], v[162:165], v[198:201], v[88:91]
	v_mfma_f32_16x16x32_bf16 v[80:83], v[162:165], v[212:215], v[80:83]
	v_mfma_f32_16x16x32_bf16 v[84:87], v[154:157], v[212:215], v[84:87]
	v_mfma_f32_16x16x32_bf16 v[76:79], v[154:157], v[220:223], v[76:79]
	v_mfma_f32_16x16x32_bf16 v[72:75], v[162:165], v[220:223], v[72:75]
	v_mfma_f32_16x16x32_bf16 v[56:59], v[162:165], v[228:231], v[56:59]
	v_mfma_f32_16x16x32_bf16 v[60:63], v[154:157], v[228:231], v[60:63]
	v_mfma_f32_16x16x32_bf16 v[92:95], v[158:161], v[208:211], v[92:95]
	v_mfma_f32_16x16x32_bf16 v[88:91], v[174:177], v[208:211], v[88:91]
	v_mfma_f32_16x16x32_bf16 v[80:83], v[174:177], v[216:219], v[80:83]
	v_mfma_f32_16x16x32_bf16 v[84:87], v[158:161], v[216:219], v[84:87]
	v_mfma_f32_16x16x32_bf16 v[76:79], v[158:161], v[224:227], v[76:79]
	v_mfma_f32_16x16x32_bf16 v[72:75], v[174:177], v[224:227], v[72:75]
	v_lshl_add_u64 v[178:179], v[236:237], 0, s[8:9]
	s_mov_b32 m0, s66
	s_nop 0
	global_load_lds_dwordx4 v[178:179], off
	v_mfma_f32_16x16x32_bf16 v[56:59], v[174:177], v[232:235], v[56:59]
	v_mfma_f32_16x16x32_bf16 v[60:63], v[158:161], v[232:235], v[60:63]
	s_setprio 0
	s_setprio 1
	v_mfma_f32_16x16x32_bf16 v[28:31], v[182:185], v[198:201], v[28:31]
	v_mfma_f32_16x16x32_bf16 v[24:27], v[190:193], v[198:201], v[24:27]
	v_mfma_f32_16x16x32_bf16 v[16:19], v[190:193], v[212:215], v[16:19]
	v_mfma_f32_16x16x32_bf16 v[20:23], v[182:185], v[212:215], v[20:23]
	v_mfma_f32_16x16x32_bf16 v[12:15], v[182:185], v[220:223], v[12:15]
	v_mfma_f32_16x16x32_bf16 v[8:11], v[190:193], v[220:223], v[8:11]
	v_mfma_f32_16x16x32_bf16 v[0:3], v[190:193], v[228:231], v[0:3]
	v_mfma_f32_16x16x32_bf16 v[4:7], v[182:185], v[228:231], v[4:7]
	v_mfma_f32_16x16x32_bf16 v[28:31], v[186:189], v[208:211], v[28:31]
	v_mfma_f32_16x16x32_bf16 v[24:27], v[194:197], v[208:211], v[24:27]
	v_mfma_f32_16x16x32_bf16 v[16:19], v[194:197], v[216:219], v[16:19]
	v_mfma_f32_16x16x32_bf16 v[20:23], v[186:189], v[216:219], v[20:23]
	v_mfma_f32_16x16x32_bf16 v[12:15], v[186:189], v[224:227], v[12:15]
	v_mfma_f32_16x16x32_bf16 v[8:11], v[194:197], v[224:227], v[8:11]
	v_lshl_add_u64 v[178:179], v[238:239], 0, s[8:9]
	s_mov_b32 m0, s67
	s_nop 0
	global_load_lds_dwordx4 v[178:179], off
	v_mfma_f32_16x16x32_bf16 v[0:3], v[194:197], v[232:235], v[0:3]
	v_mfma_f32_16x16x32_bf16 v[4:7], v[186:189], v[232:235], v[4:7]
	s_setprio 0
	s_barrier
	s_add_i32 s93, s93, 2
	s_add_u32 s54, s54, 0x100
	s_addc_u32 s55, s55, 0
	s_add_u32 s91, s91, 0x100
	s_addc_u32 s92, s92, 0
	s_cmp_gt_u32 s93, 13
	s_cbranch_scc0 .LBB0_417
	s_and_b64 vcc, exec, s[10:11]
	s_cbranch_vccz .LBB0_420
	s_barrier

; #define PG8_STAGE(bufoff, gbase, voff) do { _Pragma("unroll") for (int _i = 0; _i < 2; ++_i) \
;         __builtin_amdgcn_global_load_lds((const unsigned*)((const char*)(gbase) + (voff)[_i]), (PG8_LAS unsigned*)(lds + (bufoff) + ldsw + _i * 8192), 16, 0, 0); } while (0)
; #define PG8_LDA(dst, b, h) do { _Pragma("unroll") for (int m = 0; m < 4; ++m) _Pragma("unroll") for (int k = 0; k < 2; ++k) dst[m][k] = *(const PG8_LAS bf16x8*)(lds + PG8_SA(b, h) + aoff + m * 2048 + k * 1024); } while (0)
; #define PG8_LDB(dst, b, h) do { _Pragma("unroll") for (int n = 0; n < 2; ++n) _Pragma("unroll") for (int k = 0; k < 2; ++k) dst[n][k] = *(const PG8_LAS bf16x8*)(lds + PG8_SB(b, h) + boff + n * 2048 + k * 1024); } while (0)
; #define PG8_MMA(ai, bj, At, Bt) do { __builtin_amdgcn_s_setprio(1); _Pragma("unroll") for (int m = 0; m < 4; ++m) _Pragma("unroll") for (int n = 0; n < 2; ++n) _Pragma("unroll") for (int k = 0; k < 2; ++k) \
;         acc[ai][bj][m][n] = __builtin_amdgcn_mfma_f32_16x16x32_bf16(Bt[n][k], At[m][k], acc[ai][bj][m][n], 0, 0, 0); __builtin_amdgcn_s_setprio(0); } while (0)
; #define PG8_BAR __builtin_amdgcn_s_barrier()
; template <class Epi, class Sched, bool ALIGN_EPI = false, bool SP2 = false>
; __device__ __forceinline__ void gemm_phase(PG8_LAS unsigned char* lds, const Gemm g, const Sched& S, const Epi& E) {
;     ...
;         const bool has_next = S.next(ui + 1, nxt);
;         const char* nA = has_next ? (const char*)g.A + (size_t)nxt.pm * tstep : cA; const char* nB = has_next ? (const char*)g.Bt + (size_t)nxt.pn * tstep : cB;
;         for (int t = 0; t < nt; t += 2) {
;             const bool last = (t == nt - 2);
;             const char* a1 = cA + (size_t)(t + 1) * kstep;
;             const char* a2 = last ? nA : cA + (size_t)(t + 2) * kstep; const char* b2 = last ? nB : cB + (size_t)(t + 2) * kstep;
;             const char* a3 = a2 + kstep; const char* b3 = b2 + kstep;
;             if (last && has_next) S.a_ready(nxt);
;             if constexpr (SP2) {
;             PG8_LDB(B0, 0, 0); PG8_LDB(B1, 0, 1); PG8_SCHED; PG8_LDA(At, 0, 0); PG8_STAGE(PG8_SA(1, 1), a1 + hstep, voffA);
;             PG8_WAIT_V(8); PG8_WAIT_L(0); PG8_BAR; PG8_MMA(0, 0, At, B0); PG8_MMA(0, 1, At, B1); PG8_BAR; PG8_SCHED;
;             PG8_LDA(At, 0, 1); PG8_STAGE(PG8_SB(0, 0), b2, voffB); PG8_STAGE(PG8_SB(0, 1), b2 + hstep, voffB); PG8_STAGE(PG8_SA(0, 0), a2, voffA);
.LBB0_458:
	s_ashr_i32 s49, s48, 31
	s_lshl_b64 s[14:15], s[48:49], 19
	s_add_u32 s50, s34, s14
	s_addc_u32 s51, s43, s15
	s_and_b64 s[14:15], s[40:41], exec
	s_cselect_b32 s49, s51, s59
	s_cselect_b32 s55, s50, s58
	s_ashr_i32 s45, s44, 31
	s_lshl_b64 s[14:15], s[44:45], 19
	v_readlane_b32 s3, v250, 13
	s_add_u32 s52, s3, s14
	v_readlane_b32 s3, v250, 14
	s_addc_u32 s53, s3, s15
	s_and_b64 s[14:15], s[40:41], exec
	s_cselect_b32 s45, s53, s61
	s_cselect_b32 s57, s52, s60
	s_add_u32 s58, s58, 0x40080
	s_addc_u32 s59, s59, 0
	s_add_u32 s96, s60, 0x100
	s_addc_u32 s97, s61, 0
	s_mov_b32 vcc_lo, -2
	ds_read_b128 v[170:173], v165
	ds_read_b128 v[174:177], v165 offset:1024
	ds_read_b128 v[182:185], v165 offset:2048
	ds_read_b128 v[186:189], v165 offset:3072
	ds_read_b128 v[190:193], v168
	ds_read_b128 v[194:197], v168 offset:1024
	ds_read_b128 v[198:201], v168 offset:2048
	ds_read_b128 v[208:211], v168 offset:3072
	s_add_u32 s3, s58, 0xfffc0080
	s_addc_u32 s14, s59, -1
	s_cmp_eq_u32 vcc_lo, 12
	s_cselect_b32 s63, s49, s14
	s_cselect_b32 s62, s55, s3
	s_cselect_b32 s61, s45, s97
	s_cselect_b32 s60, s57, s96
	v_lshl_add_u64 v[178:179], s[58:59], 0, v[160:161]
	s_add_i32 m0, s85, 0xc000
	ds_read_b128 v[212:215], v164
	ds_read_b128 v[216:219], v164 offset:1024
	ds_read_b128 v[220:223], v164 offset:2048
	ds_read_b128 v[224:227], v164 offset:3072
	ds_read_b128 v[228:231], v164 offset:4096
	ds_read_b128 v[232:235], v164 offset:5120
	ds_read_b128 v[236:239], v164 offset:6144
	ds_read_b128 v[240:243], v164 offset:7168
	global_load_lds_dwordx4 v[178:179], off
	v_lshl_add_u64 v[178:179], s[58:59], 0, v[162:163]
	s_add_i32 m0, s85, 0xe000
	s_nop 0
	global_load_lds_dwordx4 v[178:179], off
	s_waitcnt vmcnt(8)
	s_waitcnt lgkmcnt(0)
	s_barrier
	s_setprio 1
	s_waitcnt lgkmcnt(0)
	v_mfma_f32_16x16x32_bf16 v[124:127], v[170:173], v[212:215], 0
	v_mfma_f32_16x16x32_bf16 v[120:123], v[182:185], v[212:215], 0
	v_mfma_f32_16x16x32_bf16 v[112:115], v[182:185], v[220:223], 0
	v_mfma_f32_16x16x32_bf16 v[116:119], v[170:173], v[220:223], 0
	v_mfma_f32_16x16x32_bf16 v[108:111], v[170:173], v[228:231], 0
	v_mfma_f32_16x16x32_bf16 v[104:107], v[182:185], v[228:231], 0
	v_mfma_f32_16x16x32_bf16 v[96:99], v[182:185], v[236:239], 0
	v_mfma_f32_16x16x32_bf16 v[100:103], v[170:173], v[236:239], 0
	v_mfma_f32_16x16x32_bf16 v[124:127], v[174:177], v[216:219], v[124:127]
	v_mfma_f32_16x16x32_bf16 v[120:123], v[186:189], v[216:219], v[120:123]
	v_mfma_f32_16x16x32_bf16 v[112:115], v[186:189], v[224:227], v[112:115]
	v_mfma_f32_16x16x32_bf16 v[116:119], v[174:177], v[224:227], v[116:119]
	v_mfma_f32_16x16x32_bf16 v[108:111], v[174:177], v[232:235], v[108:111]
	v_mfma_f32_16x16x32_bf16 v[104:107], v[186:189], v[232:235], v[104:107]
	v_mfma_f32_16x16x32_bf16 v[96:99], v[186:189], v[240:243], v[96:99]
	v_mfma_f32_16x16x32_bf16 v[100:103], v[174:177], v[240:243], v[100:103]
	s_setprio 0
	s_setprio 1
	v_mfma_f32_16x16x32_bf16 v[60:63], v[190:193], v[212:215], 0
	v_mfma_f32_16x16x32_bf16 v[56:59], v[198:201], v[212:215], 0
	v_mfma_f32_16x16x32_bf16 v[48:51], v[198:201], v[220:223], 0
	v_mfma_f32_16x16x32_bf16 v[52:55], v[190:193], v[220:223], 0
	v_mfma_f32_16x16x32_bf16 v[44:47], v[190:193], v[228:231], 0
	v_mfma_f32_16x16x32_bf16 v[40:43], v[198:201], v[228:231], 0
	v_mfma_f32_16x16x32_bf16 v[32:35], v[198:201], v[236:239], 0
	v_mfma_f32_16x16x32_bf16 v[36:39], v[190:193], v[236:239], 0
	v_mfma_f32_16x16x32_bf16 v[60:63], v[194:197], v[216:219], v[60:63]
	v_mfma_f32_16x16x32_bf16 v[56:59], v[208:211], v[216:219], v[56:59]
	v_mfma_f32_16x16x32_bf16 v[48:51], v[208:211], v[224:227], v[48:51]
	v_mfma_f32_16x16x32_bf16 v[52:55], v[194:197], v[224:227], v[52:55]
	v_mfma_f32_16x16x32_bf16 v[44:47], v[194:197], v[232:235], v[44:47]
	v_mfma_f32_16x16x32_bf16 v[40:43], v[208:211], v[232:235], v[40:43]
	v_mfma_f32_16x16x32_bf16 v[32:35], v[208:211], v[240:243], v[32:35]
	v_mfma_f32_16x16x32_bf16 v[36:39], v[194:197], v[240:243], v[36:39]
	s_setprio 0
	s_barrier
	s_add_i32 s3, s94, s84
	v_lshl_add_u64 v[178:179], s[60:61], 0, v[130:131]
	s_mov_b32 m0, s3
	ds_read_b128 v[212:215], v164 offset:16384
	ds_read_b128 v[216:219], v164 offset:17408
	ds_read_b128 v[220:223], v164 offset:18432
	ds_read_b128 v[224:227], v164 offset:19456
	ds_read_b128 v[228:231], v164 offset:20480
	ds_read_b128 v[232:235], v164 offset:21504
	ds_read_b128 v[236:239], v164 offset:22528
	ds_read_b128 v[240:243], v164 offset:23552
	global_load_lds_dwordx4 v[178:179], off
	s_add_i32 m0, s3, 0x2000
	s_add_u32 s14, s60, 0x40000
	v_lshl_add_u64 v[202:203], s[60:61], 0, v[134:135]
	s_addc_u32 s15, s61, 0
	s_add_i32 s3, s95, s84
	global_load_lds_dwordx4 v[202:203], off
	v_lshl_add_u64 v[244:245], s[14:15], 0, v[130:131]
	s_mov_b32 m0, s3
	global_load_lds_dwordx4 v[244:245], off
	v_lshl_add_u64 v[244:245], s[14:15], 0, v[134:135]
	s_add_i32 m0, s3, 0x2000
	s_nop 0
	global_load_lds_dwordx4 v[244:245], off
	s_waitcnt vmcnt(6)
	s_waitcnt lgkmcnt(0)
	s_barrier
; #define PG8_STAGE(bufoff, gbase, voff) do { _Pragma("unroll") for (int _i = 0; _i < 2; ++_i) \
;         __builtin_amdgcn_global_load_lds((const unsigned*)((const char*)(gbase) + (voff)[_i]), (PG8_LAS unsigned*)(lds + (bufoff) + ldsw + _i * 8192), 16, 0, 0); } while (0)
; #define PG8_LDA(dst, b, h) do { _Pragma("unroll") for (int m = 0; m < 4; ++m) _Pragma("unroll") for (int k = 0; k < 2; ++k) dst[m][k] = *(const PG8_LAS bf16x8*)(lds + PG8_SA(b, h) + aoff + m * 2048 + k * 1024); } while (0)
; #define PG8_LDB(dst, b, h) do { _Pragma("unroll") for (int n = 0; n < 2; ++n) _Pragma("unroll") for (int k = 0; k < 2; ++k) dst[n][k] = *(const PG8_LAS bf16x8*)(lds + PG8_SB(b, h) + boff + n * 2048 + k * 1024); } while (0)
; #define PG8_MMA(ai, bj, At, Bt) do { __builtin_amdgcn_s_setprio(1); _Pragma("unroll") for (int m = 0; m < 4; ++m) _Pragma("unroll") for (int n = 0; n < 2; ++n) _Pragma("unroll") for (int k = 0; k < 2; ++k) \
;         acc[ai][bj][m][n] = __builtin_amdgcn_mfma_f32_16x16x32_bf16(Bt[n][k], At[m][k], acc[ai][bj][m][n], 0, 0, 0); __builtin_amdgcn_s_setprio(0); } while (0)
; #define PG8_WAIT_V(n) asm volatile("s_waitcnt vmcnt(" #n ")" ::: "memory")
; #define PG8_WAIT_L(n) asm volatile("s_waitcnt lgkmcnt(" #n ")" ::: "memory")
; #define PG8_BAR __builtin_amdgcn_s_barrier()
; #define PG8_SCHED __builtin_amdgcn_sched_barrier(0)
; template <class Epi, class Sched, bool ALIGN_EPI = false, bool SP2 = false>
; __device__ __forceinline__ void gemm_phase(PG8_LAS unsigned char* lds, const Gemm g, const Sched& S, const Epi& E) {
;     ...
;             PG8_WAIT_V(8); PG8_WAIT_L(0); PG8_BAR; PG8_MMA(1, 0, At, B0); PG8_MMA(1, 1, At, B1); PG8_BAR; PG8_SCHED;
;             PG8_LDB(B0, 1, 0); PG8_LDB(B1, 1, 1); PG8_SCHED; PG8_LDA(At, 1, 0); PG8_STAGE(PG8_SA(0, 1), a2 + hstep, voffA);
;             PG8_WAIT_V(8); PG8_WAIT_L(0); PG8_BAR; PG8_MMA(0, 0, At, B0); PG8_MMA(0, 1, At, B1); PG8_BAR; PG8_SCHED;
	s_setprio 1
	s_waitcnt lgkmcnt(0)
	v_mfma_f32_16x16x32_bf16 v[92:95], v[170:173], v[212:215], 0
	v_mfma_f32_16x16x32_bf16 v[88:91], v[182:185], v[212:215], 0
	v_mfma_f32_16x16x32_bf16 v[80:83], v[182:185], v[220:223], 0
	v_mfma_f32_16x16x32_bf16 v[84:87], v[170:173], v[220:223], 0
	v_mfma_f32_16x16x32_bf16 v[76:79], v[170:173], v[228:231], 0
	v_mfma_f32_16x16x32_bf16 v[72:75], v[182:185], v[228:231], 0
	v_mfma_f32_16x16x32_bf16 v[64:67], v[182:185], v[236:239], 0
	v_mfma_f32_16x16x32_bf16 v[68:71], v[170:173], v[236:239], 0
	v_mfma_f32_16x16x32_bf16 v[92:95], v[174:177], v[216:219], v[92:95]
	v_mfma_f32_16x16x32_bf16 v[88:91], v[186:189], v[216:219], v[88:91]
	v_mfma_f32_16x16x32_bf16 v[80:83], v[186:189], v[224:227], v[80:83]
	v_mfma_f32_16x16x32_bf16 v[84:87], v[174:177], v[224:227], v[84:87]
	v_mfma_f32_16x16x32_bf16 v[76:79], v[174:177], v[232:235], v[76:79]
	v_mfma_f32_16x16x32_bf16 v[72:75], v[186:189], v[232:235], v[72:75]
	v_lshl_add_u64 v[244:245], s[62:63], 0, v[128:129]
	s_mov_b32 m0, s85
	s_nop 0
	global_load_lds_dwordx4 v[244:245], off
	v_mfma_f32_16x16x32_bf16 v[64:67], v[186:189], v[240:243], v[64:67]
	v_mfma_f32_16x16x32_bf16 v[68:71], v[174:177], v[240:243], v[68:71]
	s_setprio 0
	s_setprio 1
	v_mfma_f32_16x16x32_bf16 v[28:31], v[190:193], v[212:215], 0
	v_mfma_f32_16x16x32_bf16 v[24:27], v[198:201], v[212:215], 0
	v_mfma_f32_16x16x32_bf16 v[16:19], v[198:201], v[220:223], 0
	v_mfma_f32_16x16x32_bf16 v[20:23], v[190:193], v[220:223], 0
	v_mfma_f32_16x16x32_bf16 v[12:15], v[190:193], v[228:231], 0
	v_mfma_f32_16x16x32_bf16 v[8:11], v[198:201], v[228:231], 0
	v_mfma_f32_16x16x32_bf16 v[0:3], v[198:201], v[236:239], 0
	v_mfma_f32_16x16x32_bf16 v[4:7], v[190:193], v[236:239], 0
	v_mfma_f32_16x16x32_bf16 v[28:31], v[194:197], v[216:219], v[28:31]
	v_mfma_f32_16x16x32_bf16 v[24:27], v[208:211], v[216:219], v[24:27]
	v_mfma_f32_16x16x32_bf16 v[16:19], v[208:211], v[224:227], v[16:19]
	v_mfma_f32_16x16x32_bf16 v[20:23], v[194:197], v[224:227], v[20:23]
	v_mfma_f32_16x16x32_bf16 v[12:15], v[194:197], v[232:235], v[12:15]
	v_mfma_f32_16x16x32_bf16 v[8:11], v[208:211], v[232:235], v[8:11]
	v_lshl_add_u64 v[246:247], s[62:63], 0, v[132:133]
	s_mov_b32 m0, s86
	s_nop 0
	global_load_lds_dwordx4 v[246:247], off
	v_mfma_f32_16x16x32_bf16 v[0:3], v[208:211], v[240:243], v[0:3]
	v_mfma_f32_16x16x32_bf16 v[4:7], v[194:197], v[240:243], v[4:7]
	s_setprio 0
	s_barrier
	s_add_i32 s3, 0, 0x18000
	v_add_u32_e32 v136, s3, v141
	s_add_i32 s33, 0, 0x1c000
	ds_read_b128 v[170:173], v136
	ds_read_b128 v[174:177], v136 offset:1024
	ds_read_b128 v[182:185], v136 offset:2048
	ds_read_b128 v[186:189], v136 offset:3072
	v_add_u32_e32 v136, s33, v141
	ds_read_b128 v[190:193], v136
	ds_read_b128 v[194:197], v136 offset:1024
	ds_read_b128 v[198:201], v136 offset:2048
	ds_read_b128 v[208:211], v136 offset:3072
	s_add_u32 s14, s62, 0x40000
	s_addc_u32 s15, s63, 0
	s_mov_b32 m0, s87
	v_lshl_add_u64 v[248:249], s[14:15], 0, v[128:129]
	ds_read_b128 v[212:215], v164 offset:32768
	ds_read_b128 v[216:219], v164 offset:33792
	ds_read_b128 v[220:223], v164 offset:34816
	ds_read_b128 v[224:227], v164 offset:35840
	ds_read_b128 v[228:231], v164 offset:36864
	ds_read_b128 v[232:235], v164 offset:37888
	ds_read_b128 v[236:239], v164 offset:38912
	ds_read_b128 v[240:243], v164 offset:39936
	global_load_lds_dwordx4 v[248:249], off
	v_lshl_add_u64 v[248:249], s[14:15], 0, v[132:133]
	s_mov_b32 m0, s88
	s_nop 0
	global_load_lds_dwordx4 v[248:249], off
	s_waitcnt vmcnt(8)
	s_waitcnt lgkmcnt(0)
	s_barrier
	s_setprio 1
	s_waitcnt lgkmcnt(0)
	v_mfma_f32_16x16x32_bf16 v[124:127], v[170:173], v[212:215], v[124:127]
	v_mfma_f32_16x16x32_bf16 v[120:123], v[182:185], v[212:215], v[120:123]
	v_mfma_f32_16x16x32_bf16 v[112:115], v[182:185], v[220:223], v[112:115]
	v_mfma_f32_16x16x32_bf16 v[116:119], v[170:173], v[220:223], v[116:119]
	v_mfma_f32_16x16x32_bf16 v[108:111], v[170:173], v[228:231], v[108:111]
	v_mfma_f32_16x16x32_bf16 v[104:107], v[182:185], v[228:231], v[104:107]
	v_mfma_f32_16x16x32_bf16 v[96:99], v[182:185], v[236:239], v[96:99]
	v_mfma_f32_16x16x32_bf16 v[100:103], v[170:173], v[236:239], v[100:103]
	v_mfma_f32_16x16x32_bf16 v[124:127], v[174:177], v[216:219], v[124:127]
	v_mfma_f32_16x16x32_bf16 v[120:123], v[186:189], v[216:219], v[120:123]
	v_mfma_f32_16x16x32_bf16 v[112:115], v[186:189], v[224:227], v[112:115]
	v_mfma_f32_16x16x32_bf16 v[116:119], v[174:177], v[224:227], v[116:119]
	v_mfma_f32_16x16x32_bf16 v[108:111], v[174:177], v[232:235], v[108:111]
	v_mfma_f32_16x16x32_bf16 v[104:107], v[186:189], v[232:235], v[104:107]
	v_mfma_f32_16x16x32_bf16 v[96:99], v[186:189], v[240:243], v[96:99]
	v_mfma_f32_16x16x32_bf16 v[100:103], v[174:177], v[240:243], v[100:103]
	s_setprio 0
	s_setprio 1
	v_mfma_f32_16x16x32_bf16 v[60:63], v[190:193], v[212:215], v[60:63]
	v_mfma_f32_16x16x32_bf16 v[56:59], v[198:201], v[212:215], v[56:59]
	v_mfma_f32_16x16x32_bf16 v[48:51], v[198:201], v[220:223], v[48:51]
	v_mfma_f32_16x16x32_bf16 v[52:55], v[190:193], v[220:223], v[52:55]
	v_mfma_f32_16x16x32_bf16 v[44:47], v[190:193], v[228:231], v[44:47]
	v_mfma_f32_16x16x32_bf16 v[40:43], v[198:201], v[228:231], v[40:43]
	v_mfma_f32_16x16x32_bf16 v[32:35], v[198:201], v[236:239], v[32:35]
	v_mfma_f32_16x16x32_bf16 v[36:39], v[190:193], v[236:239], v[36:39]
	v_mfma_f32_16x16x32_bf16 v[60:63], v[194:197], v[216:219], v[60:63]
	v_mfma_f32_16x16x32_bf16 v[56:59], v[208:211], v[216:219], v[56:59]
	v_mfma_f32_16x16x32_bf16 v[48:51], v[208:211], v[224:227], v[48:51]
	v_mfma_f32_16x16x32_bf16 v[52:55], v[194:197], v[224:227], v[52:55]
	v_mfma_f32_16x16x32_bf16 v[44:47], v[194:197], v[232:235], v[44:47]
	v_mfma_f32_16x16x32_bf16 v[40:43], v[208:211], v[232:235], v[40:43]
	v_mfma_f32_16x16x32_bf16 v[32:35], v[208:211], v[240:243], v[32:35]
	v_mfma_f32_16x16x32_bf16 v[36:39], v[194:197], v[240:243], v[36:39]
	s_setprio 0
	s_barrier
; #define PG8_STAGE(bufoff, gbase, voff) do { _Pragma("unroll") for (int _i = 0; _i < 2; ++_i) \
;         __builtin_amdgcn_global_load_lds((const unsigned*)((const char*)(gbase) + (voff)[_i]), (PG8_LAS unsigned*)(lds + (bufoff) + ldsw + _i * 8192), 16, 0, 0); } while (0)
; #define PG8_LDA(dst, b, h) do { _Pragma("unroll") for (int m = 0; m < 4; ++m) _Pragma("unroll") for (int k = 0; k < 2; ++k) dst[m][k] = *(const PG8_LAS bf16x8*)(lds + PG8_SA(b, h) + aoff + m * 2048 + k * 1024); } while (0)
; #define PG8_LDB(dst, b, h) do { _Pragma("unroll") for (int n = 0; n < 2; ++n) _Pragma("unroll") for (int k = 0; k < 2; ++k) dst[n][k] = *(const PG8_LAS bf16x8*)(lds + PG8_SB(b, h) + boff + n * 2048 + k * 1024); } while (0)
; #define PG8_BAR __builtin_amdgcn_s_barrier()
; template <class Epi, class Sched, bool ALIGN_EPI = false, bool SP2 = false>
; __device__ __forceinline__ void gemm_phase(PG8_LAS unsigned char* lds, const Gemm g, const Sched& S, const Epi& E) {
;     ...
;             const bool last = (t == nt - 2);
;             const char* a1 = cA + (size_t)(t + 1) * kstep;
;             const char* a2 = last ? nA : cA + (size_t)(t + 2) * kstep; const char* b2 = last ? nB : cB + (size_t)(t + 2) * kstep;
;             const char* a3 = a2 + kstep; const char* b3 = b2 + kstep;
;             if (last && has_next) S.a_ready(nxt);
;             if constexpr (SP2) {
;             PG8_LDB(B0, 0, 0); PG8_LDB(B1, 0, 1); PG8_SCHED; PG8_LDA(At, 0, 0); PG8_STAGE(PG8_SA(1, 1), a1 + hstep, voffA);
;             PG8_WAIT_V(8); PG8_WAIT_L(0); PG8_BAR; PG8_MMA(0, 0, At, B0); PG8_MMA(0, 1, At, B1); PG8_BAR; PG8_SCHED;
;             PG8_LDA(At, 0, 1); PG8_STAGE(PG8_SB(0, 0), b2, voffB); PG8_STAGE(PG8_SB(0, 1), b2 + hstep, voffB); PG8_STAGE(PG8_SA(0, 0), a2, voffA);
;             PG8_WAIT_V(8); PG8_WAIT_L(0); PG8_BAR; PG8_MMA(1, 0, At, B0); PG8_MMA(1, 1, At, B1); PG8_BAR; PG8_SCHED;
;             PG8_LDB(B0, 1, 0); PG8_LDB(B1, 1, 1); PG8_SCHED; PG8_LDA(At, 1, 0); PG8_STAGE(PG8_SA(0, 1), a2 + hstep, voffA);
;             PG8_WAIT_V(8); PG8_WAIT_L(0); PG8_BAR; PG8_MMA(0, 0, At, B0); PG8_MMA(0, 1, At, B1); PG8_BAR; PG8_SCHED;
;             PG8_LDA(At, 1, 1); PG8_STAGE(PG8_SB(1, 0), b3, voffB); PG8_STAGE(PG8_SB(1, 1), b3 + hstep, voffB); PG8_STAGE(PG8_SA(1, 0), a3, voffA);
;             PG8_WAIT_V(8); PG8_WAIT_L(0); PG8_BAR; PG8_MMA(1, 0, At, B0); PG8_MMA(1, 1, At, B1); PG8_BAR; PG8_SCHED;
	s_add_i32 s3, s3, s84
	v_lshl_add_u64 v[178:179], v[178:179], 0, s[8:9]
	s_mov_b32 m0, s3
	ds_read_b128 v[212:215], v164 offset:49152
	ds_read_b128 v[216:219], v164 offset:50176
	ds_read_b128 v[220:223], v164 offset:51200
	ds_read_b128 v[224:227], v164 offset:52224
	ds_read_b128 v[228:231], v164 offset:53248
	ds_read_b128 v[232:235], v164 offset:54272
	ds_read_b128 v[236:239], v164 offset:55296
	ds_read_b128 v[240:243], v164 offset:56320
	global_load_lds_dwordx4 v[178:179], off
	s_add_i32 m0, s3, 0x2000
	s_add_u32 s14, s60, 0x40080
	v_lshl_add_u64 v[178:179], v[202:203], 0, s[8:9]
	s_addc_u32 s15, s61, 0
	s_add_i32 s3, s33, s84
	global_load_lds_dwordx4 v[178:179], off
	v_lshl_add_u64 v[178:179], s[14:15], 0, v[130:131]
	s_mov_b32 m0, s3
	s_nop 0
	global_load_lds_dwordx4 v[178:179], off
	v_lshl_add_u64 v[178:179], s[14:15], 0, v[134:135]
	s_add_i32 m0, s3, 0x2000
	s_nop 0
	global_load_lds_dwordx4 v[178:179], off
	s_waitcnt vmcnt(6)
	s_waitcnt lgkmcnt(0)
	s_barrier
	s_setprio 1
	s_waitcnt lgkmcnt(0)
	v_mfma_f32_16x16x32_bf16 v[92:95], v[170:173], v[212:215], v[92:95]
	v_mfma_f32_16x16x32_bf16 v[88:91], v[182:185], v[212:215], v[88:91]
	v_mfma_f32_16x16x32_bf16 v[80:83], v[182:185], v[220:223], v[80:83]
	v_mfma_f32_16x16x32_bf16 v[84:87], v[170:173], v[220:223], v[84:87]
	v_mfma_f32_16x16x32_bf16 v[76:79], v[170:173], v[228:231], v[76:79]
	v_mfma_f32_16x16x32_bf16 v[72:75], v[182:185], v[228:231], v[72:75]
	v_mfma_f32_16x16x32_bf16 v[64:67], v[182:185], v[236:239], v[64:67]
	v_mfma_f32_16x16x32_bf16 v[68:71], v[170:173], v[236:239], v[68:71]
	v_mfma_f32_16x16x32_bf16 v[92:95], v[174:177], v[216:219], v[92:95]
	v_mfma_f32_16x16x32_bf16 v[88:91], v[186:189], v[216:219], v[88:91]
	v_mfma_f32_16x16x32_bf16 v[80:83], v[186:189], v[224:227], v[80:83]
	v_mfma_f32_16x16x32_bf16 v[84:87], v[174:177], v[224:227], v[84:87]
	v_mfma_f32_16x16x32_bf16 v[76:79], v[174:177], v[232:235], v[76:79]
	v_mfma_f32_16x16x32_bf16 v[72:75], v[186:189], v[232:235], v[72:75]
	v_lshl_add_u64 v[178:179], v[244:245], 0, s[8:9]
	s_mov_b32 m0, s90
	s_nop 0
	global_load_lds_dwordx4 v[178:179], off
	v_mfma_f32_16x16x32_bf16 v[64:67], v[186:189], v[240:243], v[64:67]
	v_mfma_f32_16x16x32_bf16 v[68:71], v[174:177], v[240:243], v[68:71]
	s_setprio 0
	s_setprio 1
	v_mfma_f32_16x16x32_bf16 v[28:31], v[190:193], v[212:215], v[28:31]
	v_mfma_f32_16x16x32_bf16 v[24:27], v[198:201], v[212:215], v[24:27]
	v_mfma_f32_16x16x32_bf16 v[16:19], v[198:201], v[220:223], v[16:19]
	v_mfma_f32_16x16x32_bf16 v[20:23], v[190:193], v[220:223], v[20:23]
	v_mfma_f32_16x16x32_bf16 v[12:15], v[190:193], v[228:231], v[12:15]
	v_mfma_f32_16x16x32_bf16 v[8:11], v[198:201], v[228:231], v[8:11]
	v_mfma_f32_16x16x32_bf16 v[0:3], v[198:201], v[236:239], v[0:3]
	v_mfma_f32_16x16x32_bf16 v[4:7], v[190:193], v[236:239], v[4:7]
	v_mfma_f32_16x16x32_bf16 v[28:31], v[194:197], v[216:219], v[28:31]
	v_mfma_f32_16x16x32_bf16 v[24:27], v[208:211], v[216:219], v[24:27]
	v_mfma_f32_16x16x32_bf16 v[16:19], v[208:211], v[224:227], v[16:19]
	v_mfma_f32_16x16x32_bf16 v[20:23], v[194:197], v[224:227], v[20:23]
	v_mfma_f32_16x16x32_bf16 v[12:15], v[194:197], v[232:235], v[12:15]
	v_mfma_f32_16x16x32_bf16 v[8:11], v[208:211], v[232:235], v[8:11]
	v_lshl_add_u64 v[178:179], v[246:247], 0, s[8:9]
	s_mov_b32 m0, s91
	s_nop 0
	global_load_lds_dwordx4 v[178:179], off
	v_mfma_f32_16x16x32_bf16 v[0:3], v[208:211], v[240:243], v[0:3]
	v_mfma_f32_16x16x32_bf16 v[4:7], v[194:197], v[240:243], v[4:7]
	s_setprio 0
	s_barrier
	s_add_i32 vcc_lo, vcc_lo, 2
	s_add_u32 s58, s58, 0x100
	s_addc_u32 s59, s59, 0
	s_add_u32 s96, s96, 0x100
	s_addc_u32 s97, s97, 0
.LBB0_459:
	ds_read_b128 v[170:173], v165
	ds_read_b128 v[174:177], v165 offset:1024
	ds_read_b128 v[182:185], v165 offset:2048
	ds_read_b128 v[186:189], v165 offset:3072
	ds_read_b128 v[190:193], v168
	ds_read_b128 v[194:197], v168 offset:1024
	ds_read_b128 v[198:201], v168 offset:2048
	ds_read_b128 v[208:211], v168 offset:3072
	s_add_u32 s3, s58, 0xfffc0080
	s_addc_u32 s14, s59, -1
	s_cmp_eq_u32 vcc_lo, 12
	s_cselect_b32 s63, s49, s14
	s_cselect_b32 s62, s55, s3
	s_cselect_b32 s61, s45, s97
	s_cselect_b32 s60, s57, s96
	v_lshl_add_u64 v[178:179], s[58:59], 0, v[160:161]
	s_add_i32 m0, s85, 0xc000
	ds_read_b128 v[212:215], v164
	ds_read_b128 v[216:219], v164 offset:1024
	ds_read_b128 v[220:223], v164 offset:2048
	ds_read_b128 v[224:227], v164 offset:3072
	ds_read_b128 v[228:231], v164 offset:4096
	ds_read_b128 v[232:235], v164 offset:5120
	ds_read_b128 v[236:239], v164 offset:6144
	ds_read_b128 v[240:243], v164 offset:7168
	global_load_lds_dwordx4 v[178:179], off
	v_lshl_add_u64 v[178:179], s[58:59], 0, v[162:163]
	s_add_i32 m0, s85, 0xe000
	s_nop 0
	global_load_lds_dwordx4 v[178:179], off
	s_waitcnt vmcnt(8)
	s_waitcnt lgkmcnt(0)
	s_barrier
; #define PG8_STAGE(bufoff, gbase, voff) do { _Pragma("unroll") for (int _i = 0; _i < 2; ++_i) \
;         __builtin_amdgcn_global_load_lds((const unsigned*)((const char*)(gbase) + (voff)[_i]), (PG8_LAS unsigned*)(lds + (bufoff) + ldsw + _i * 8192), 16, 0, 0); } while (0)
; #define PG8_LDA(dst, b, h) do { _Pragma("unroll") for (int m = 0; m < 4; ++m) _Pragma("unroll") for (int k = 0; k < 2; ++k) dst[m][k] = *(const PG8_LAS bf16x8*)(lds + PG8_SA(b, h) + aoff + m * 2048 + k * 1024); } while (0)
; #define PG8_MMA(ai, bj, At, Bt) do { __builtin_amdgcn_s_setprio(1); _Pragma("unroll") for (int m = 0; m < 4; ++m) _Pragma("unroll") for (int n = 0; n < 2; ++n) _Pragma("unroll") for (int k = 0; k < 2; ++k) \
;         acc[ai][bj][m][n] = __builtin_amdgcn_mfma_f32_16x16x32_bf16(Bt[n][k], At[m][k], acc[ai][bj][m][n], 0, 0, 0); __builtin_amdgcn_s_setprio(0); } while (0)
; #define PG8_WAIT_V(n) asm volatile("s_waitcnt vmcnt(" #n ")" ::: "memory")
; #define PG8_WAIT_L(n) asm volatile("s_waitcnt lgkmcnt(" #n ")" ::: "memory")
; #define PG8_BAR __builtin_amdgcn_s_barrier()
; #define PG8_SCHED __builtin_amdgcn_sched_barrier(0)
; template <class Epi, class Sched, bool ALIGN_EPI = false, bool SP2 = false>
; __device__ __forceinline__ void gemm_phase(PG8_LAS unsigned char* lds, const Gemm g, const Sched& S, const Epi& E) {
;     ...
;             PG8_WAIT_V(8); PG8_WAIT_L(0); PG8_BAR; PG8_MMA(0, 0, At, B0); PG8_MMA(0, 1, At, B1); PG8_BAR; PG8_SCHED;
;             PG8_LDA(At, 0, 1); PG8_STAGE(PG8_SB(0, 0), b2, voffB); PG8_STAGE(PG8_SB(0, 1), b2 + hstep, voffB); PG8_STAGE(PG8_SA(0, 0), a2, voffA);
;             PG8_WAIT_V(8); PG8_WAIT_L(0); PG8_BAR; PG8_MMA(1, 0, At, B0); PG8_MMA(1, 1, At, B1); PG8_BAR; PG8_SCHED;
	s_setprio 1
	s_waitcnt lgkmcnt(0)
	v_mfma_f32_16x16x32_bf16 v[124:127], v[170:173], v[212:215], v[124:127]
	v_mfma_f32_16x16x32_bf16 v[120:123], v[182:185], v[212:215], v[120:123]
	v_mfma_f32_16x16x32_bf16 v[112:115], v[182:185], v[220:223], v[112:115]
	v_mfma_f32_16x16x32_bf16 v[116:119], v[170:173], v[220:223], v[116:119]
	v_mfma_f32_16x16x32_bf16 v[108:111], v[170:173], v[228:231], v[108:111]
	v_mfma_f32_16x16x32_bf16 v[104:107], v[182:185], v[228:231], v[104:107]
	v_mfma_f32_16x16x32_bf16 v[96:99], v[182:185], v[236:239], v[96:99]
	v_mfma_f32_16x16x32_bf16 v[100:103], v[170:173], v[236:239], v[100:103]
	v_mfma_f32_16x16x32_bf16 v[124:127], v[174:177], v[216:219], v[124:127]
	v_mfma_f32_16x16x32_bf16 v[120:123], v[186:189], v[216:219], v[120:123]
	v_mfma_f32_16x16x32_bf16 v[112:115], v[186:189], v[224:227], v[112:115]
	v_mfma_f32_16x16x32_bf16 v[116:119], v[174:177], v[224:227], v[116:119]
	v_mfma_f32_16x16x32_bf16 v[108:111], v[174:177], v[232:235], v[108:111]
	v_mfma_f32_16x16x32_bf16 v[104:107], v[186:189], v[232:235], v[104:107]
	v_mfma_f32_16x16x32_bf16 v[96:99], v[186:189], v[240:243], v[96:99]
	v_mfma_f32_16x16x32_bf16 v[100:103], v[174:177], v[240:243], v[100:103]
	s_setprio 0
	s_setprio 1
	v_mfma_f32_16x16x32_bf16 v[60:63], v[190:193], v[212:215], v[60:63]
	v_mfma_f32_16x16x32_bf16 v[56:59], v[198:201], v[212:215], v[56:59]
	v_mfma_f32_16x16x32_bf16 v[48:51], v[198:201], v[220:223], v[48:51]
	v_mfma_f32_16x16x32_bf16 v[52:55], v[190:193], v[220:223], v[52:55]
	v_mfma_f32_16x16x32_bf16 v[44:47], v[190:193], v[228:231], v[44:47]
	v_mfma_f32_16x16x32_bf16 v[40:43], v[198:201], v[228:231], v[40:43]
	v_mfma_f32_16x16x32_bf16 v[32:35], v[198:201], v[236:239], v[32:35]
	v_mfma_f32_16x16x32_bf16 v[36:39], v[190:193], v[236:239], v[36:39]
	v_mfma_f32_16x16x32_bf16 v[60:63], v[194:197], v[216:219], v[60:63]
	v_mfma_f32_16x16x32_bf16 v[56:59], v[208:211], v[216:219], v[56:59]
	v_mfma_f32_16x16x32_bf16 v[48:51], v[208:211], v[224:227], v[48:51]
	v_mfma_f32_16x16x32_bf16 v[52:55], v[194:197], v[224:227], v[52:55]
	v_mfma_f32_16x16x32_bf16 v[44:47], v[194:197], v[232:235], v[44:47]
	v_mfma_f32_16x16x32_bf16 v[40:43], v[208:211], v[232:235], v[40:43]
	v_mfma_f32_16x16x32_bf16 v[32:35], v[208:211], v[240:243], v[32:35]
	v_mfma_f32_16x16x32_bf16 v[36:39], v[194:197], v[240:243], v[36:39]
	s_setprio 0
	s_barrier
	s_add_i32 s3, s94, s84
	v_lshl_add_u64 v[178:179], s[60:61], 0, v[130:131]
	s_mov_b32 m0, s3
	ds_read_b128 v[212:215], v164 offset:16384
	ds_read_b128 v[216:219], v164 offset:17408
	ds_read_b128 v[220:223], v164 offset:18432
	ds_read_b128 v[224:227], v164 offset:19456
	ds_read_b128 v[228:231], v164 offset:20480
	ds_read_b128 v[232:235], v164 offset:21504
	ds_read_b128 v[236:239], v164 offset:22528
	ds_read_b128 v[240:243], v164 offset:23552
	global_load_lds_dwordx4 v[178:179], off
	s_add_i32 m0, s3, 0x2000
	s_add_u32 s14, s60, 0x40000
	v_lshl_add_u64 v[202:203], s[60:61], 0, v[134:135]
	s_addc_u32 s15, s61, 0
	s_add_i32 s3, s95, s84
	global_load_lds_dwordx4 v[202:203], off
	v_lshl_add_u64 v[244:245], s[14:15], 0, v[130:131]
	s_mov_b32 m0, s3
	global_load_lds_dwordx4 v[244:245], off
	v_lshl_add_u64 v[244:245], s[14:15], 0, v[134:135]
	s_add_i32 m0, s3, 0x2000
	s_nop 0
	global_load_lds_dwordx4 v[244:245], off
	s_waitcnt vmcnt(6)
	s_waitcnt lgkmcnt(0)
	s_barrier
	s_setprio 1
	s_waitcnt lgkmcnt(0)
	v_mfma_f32_16x16x32_bf16 v[92:95], v[170:173], v[212:215], v[92:95]
	v_mfma_f32_16x16x32_bf16 v[88:91], v[182:185], v[212:215], v[88:91]
	v_mfma_f32_16x16x32_bf16 v[80:83], v[182:185], v[220:223], v[80:83]
	v_mfma_f32_16x16x32_bf16 v[84:87], v[170:173], v[220:223], v[84:87]
	v_mfma_f32_16x16x32_bf16 v[76:79], v[170:173], v[228:231], v[76:79]
	v_mfma_f32_16x16x32_bf16 v[72:75], v[182:185], v[228:231], v[72:75]
	v_mfma_f32_16x16x32_bf16 v[64:67], v[182:185], v[236:239], v[64:67]
	v_mfma_f32_16x16x32_bf16 v[68:71], v[170:173], v[236:239], v[68:71]
	v_mfma_f32_16x16x32_bf16 v[92:95], v[174:177], v[216:219], v[92:95]
	v_mfma_f32_16x16x32_bf16 v[88:91], v[186:189], v[216:219], v[88:91]
	v_mfma_f32_16x16x32_bf16 v[80:83], v[186:189], v[224:227], v[80:83]
	v_mfma_f32_16x16x32_bf16 v[84:87], v[174:177], v[224:227], v[84:87]
	v_mfma_f32_16x16x32_bf16 v[76:79], v[174:177], v[232:235], v[76:79]
	v_mfma_f32_16x16x32_bf16 v[72:75], v[186:189], v[232:235], v[72:75]
	v_lshl_add_u64 v[244:245], s[62:63], 0, v[128:129]
	s_mov_b32 m0, s85
	s_nop 0
	global_load_lds_dwordx4 v[244:245], off
	v_mfma_f32_16x16x32_bf16 v[64:67], v[186:189], v[240:243], v[64:67]
	v_mfma_f32_16x16x32_bf16 v[68:71], v[174:177], v[240:243], v[68:71]
	s_setprio 0
	s_setprio 1
	v_mfma_f32_16x16x32_bf16 v[28:31], v[190:193], v[212:215], v[28:31]
	v_mfma_f32_16x16x32_bf16 v[24:27], v[198:201], v[212:215], v[24:27]
	v_mfma_f32_16x16x32_bf16 v[16:19], v[198:201], v[220:223], v[16:19]
	v_mfma_f32_16x16x32_bf16 v[20:23], v[190:193], v[220:223], v[20:23]
	v_mfma_f32_16x16x32_bf16 v[12:15], v[190:193], v[228:231], v[12:15]
	v_mfma_f32_16x16x32_bf16 v[8:11], v[198:201], v[228:231], v[8:11]
	v_mfma_f32_16x16x32_bf16 v[0:3], v[198:201], v[236:239], v[0:3]
	v_mfma_f32_16x16x32_bf16 v[4:7], v[190:193], v[236:239], v[4:7]
	v_mfma_f32_16x16x32_bf16 v[28:31], v[194:197], v[216:219], v[28:31]
	v_mfma_f32_16x16x32_bf16 v[24:27], v[208:211], v[216:219], v[24:27]
	v_mfma_f32_16x16x32_bf16 v[16:19], v[208:211], v[224:227], v[16:19]
	v_mfma_f32_16x16x32_bf16 v[20:23], v[194:197], v[224:227], v[20:23]
	v_mfma_f32_16x16x32_bf16 v[12:15], v[194:197], v[232:235], v[12:15]
	v_mfma_f32_16x16x32_bf16 v[8:11], v[208:211], v[232:235], v[8:11]
	v_lshl_add_u64 v[246:247], s[62:63], 0, v[132:133]
	s_mov_b32 m0, s86
	s_nop 0
	global_load_lds_dwordx4 v[246:247], off
	v_mfma_f32_16x16x32_bf16 v[0:3], v[208:211], v[240:243], v[0:3]
	v_mfma_f32_16x16x32_bf16 v[4:7], v[194:197], v[240:243], v[4:7]
	s_setprio 0
	s_barrier
; #define PG8_STAGE(bufoff, gbase, voff) do { _Pragma("unroll") for (int _i = 0; _i < 2; ++_i) \
;         __builtin_amdgcn_global_load_lds((const unsigned*)((const char*)(gbase) + (voff)[_i]), (PG8_LAS unsigned*)(lds + (bufoff) + ldsw + _i * 8192), 16, 0, 0); } while (0)
; #define PG8_LDA(dst, b, h) do { _Pragma("unroll") for (int m = 0; m < 4; ++m) _Pragma("unroll") for (int k = 0; k < 2; ++k) dst[m][k] = *(const PG8_LAS bf16x8*)(lds + PG8_SA(b, h) + aoff + m * 2048 + k * 1024); } while (0)
; #define PG8_LDB(dst, b, h) do { _Pragma("unroll") for (int n = 0; n < 2; ++n) _Pragma("unroll") for (int k = 0; k < 2; ++k) dst[n][k] = *(const PG8_LAS bf16x8*)(lds + PG8_SB(b, h) + boff + n * 2048 + k * 1024); } while (0)
; #define PG8_MMA(ai, bj, At, Bt) do { __builtin_amdgcn_s_setprio(1); _Pragma("unroll") for (int m = 0; m < 4; ++m) _Pragma("unroll") for (int n = 0; n < 2; ++n) _Pragma("unroll") for (int k = 0; k < 2; ++k) \
;         acc[ai][bj][m][n] = __builtin_amdgcn_mfma_f32_16x16x32_bf16(Bt[n][k], At[m][k], acc[ai][bj][m][n], 0, 0, 0); __builtin_amdgcn_s_setprio(0); } while (0)
; #define PG8_WAIT_V(n) asm volatile("s_waitcnt vmcnt(" #n ")" ::: "memory")
; #define PG8_WAIT_L(n) asm volatile("s_waitcnt lgkmcnt(" #n ")" ::: "memory")
; #define PG8_BAR __builtin_amdgcn_s_barrier()
; #define PG8_SCHED __builtin_amdgcn_sched_barrier(0)
; template <class Epi, class Sched, bool ALIGN_EPI = false, bool SP2 = false>
; __device__ __forceinline__ void gemm_phase(PG8_LAS unsigned char* lds, const Gemm g, const Sched& S, const Epi& E) {
;     ...
;             PG8_LDB(B0, 1, 0); PG8_LDB(B1, 1, 1); PG8_SCHED; PG8_LDA(At, 1, 0); PG8_STAGE(PG8_SA(0, 1), a2 + hstep, voffA);
;             PG8_WAIT_V(8); PG8_WAIT_L(0); PG8_BAR; PG8_MMA(0, 0, At, B0); PG8_MMA(0, 1, At, B1); PG8_BAR; PG8_SCHED;
	s_add_i32 s3, 0, 0x18000
	v_add_u32_e32 v136, s3, v141
	s_add_i32 s33, 0, 0x1c000
	ds_read_b128 v[170:173], v136
	ds_read_b128 v[174:177], v136 offset:1024
	ds_read_b128 v[182:185], v136 offset:2048
	ds_read_b128 v[186:189], v136 offset:3072
	v_add_u32_e32 v136, s33, v141
	ds_read_b128 v[190:193], v136
	ds_read_b128 v[194:197], v136 offset:1024
	ds_read_b128 v[198:201], v136 offset:2048
	ds_read_b128 v[208:211], v136 offset:3072
	s_add_u32 s14, s62, 0x40000
	s_addc_u32 s15, s63, 0
	s_mov_b32 m0, s87
	v_lshl_add_u64 v[248:249], s[14:15], 0, v[128:129]
	ds_read_b128 v[212:215], v164 offset:32768
	ds_read_b128 v[216:219], v164 offset:33792
	ds_read_b128 v[220:223], v164 offset:34816
	ds_read_b128 v[224:227], v164 offset:35840
	ds_read_b128 v[228:231], v164 offset:36864
	ds_read_b128 v[232:235], v164 offset:37888
	ds_read_b128 v[236:239], v164 offset:38912
	ds_read_b128 v[240:243], v164 offset:39936
	global_load_lds_dwordx4 v[248:249], off
	v_lshl_add_u64 v[248:249], s[14:15], 0, v[132:133]
	s_mov_b32 m0, s88
	s_nop 0
	global_load_lds_dwordx4 v[248:249], off
	s_waitcnt vmcnt(8)
	s_waitcnt lgkmcnt(0)
	s_barrier
	s_setprio 1
	s_waitcnt lgkmcnt(0)
	v_mfma_f32_16x16x32_bf16 v[124:127], v[170:173], v[212:215], v[124:127]
	v_mfma_f32_16x16x32_bf16 v[120:123], v[182:185], v[212:215], v[120:123]
	v_mfma_f32_16x16x32_bf16 v[112:115], v[182:185], v[220:223], v[112:115]
	v_mfma_f32_16x16x32_bf16 v[116:119], v[170:173], v[220:223], v[116:119]
	v_mfma_f32_16x16x32_bf16 v[108:111], v[170:173], v[228:231], v[108:111]
	v_mfma_f32_16x16x32_bf16 v[104:107], v[182:185], v[228:231], v[104:107]
	v_mfma_f32_16x16x32_bf16 v[96:99], v[182:185], v[236:239], v[96:99]
	v_mfma_f32_16x16x32_bf16 v[100:103], v[170:173], v[236:239], v[100:103]
	v_mfma_f32_16x16x32_bf16 v[124:127], v[174:177], v[216:219], v[124:127]
	v_mfma_f32_16x16x32_bf16 v[120:123], v[186:189], v[216:219], v[120:123]
	v_mfma_f32_16x16x32_bf16 v[112:115], v[186:189], v[224:227], v[112:115]
	v_mfma_f32_16x16x32_bf16 v[116:119], v[174:177], v[224:227], v[116:119]
	v_mfma_f32_16x16x32_bf16 v[108:111], v[174:177], v[232:235], v[108:111]
	v_mfma_f32_16x16x32_bf16 v[104:107], v[186:189], v[232:235], v[104:107]
	v_mfma_f32_16x16x32_bf16 v[96:99], v[186:189], v[240:243], v[96:99]
	v_mfma_f32_16x16x32_bf16 v[100:103], v[174:177], v[240:243], v[100:103]
	s_setprio 0
	s_setprio 1
	v_mfma_f32_16x16x32_bf16 v[60:63], v[190:193], v[212:215], v[60:63]
	v_mfma_f32_16x16x32_bf16 v[56:59], v[198:201], v[212:215], v[56:59]
	v_mfma_f32_16x16x32_bf16 v[48:51], v[198:201], v[220:223], v[48:51]
	v_mfma_f32_16x16x32_bf16 v[52:55], v[190:193], v[220:223], v[52:55]
	v_mfma_f32_16x16x32_bf16 v[44:47], v[190:193], v[228:231], v[44:47]
	v_mfma_f32_16x16x32_bf16 v[40:43], v[198:201], v[228:231], v[40:43]
	v_mfma_f32_16x16x32_bf16 v[32:35], v[198:201], v[236:239], v[32:35]
	v_mfma_f32_16x16x32_bf16 v[36:39], v[190:193], v[236:239], v[36:39]
	v_mfma_f32_16x16x32_bf16 v[60:63], v[194:197], v[216:219], v[60:63]
	v_mfma_f32_16x16x32_bf16 v[56:59], v[208:211], v[216:219], v[56:59]
	v_mfma_f32_16x16x32_bf16 v[48:51], v[208:211], v[224:227], v[48:51]
	v_mfma_f32_16x16x32_bf16 v[52:55], v[194:197], v[224:227], v[52:55]
	v_mfma_f32_16x16x32_bf16 v[44:47], v[194:197], v[232:235], v[44:47]
	v_mfma_f32_16x16x32_bf16 v[40:43], v[208:211], v[232:235], v[40:43]
	v_mfma_f32_16x16x32_bf16 v[32:35], v[208:211], v[240:243], v[32:35]
	v_mfma_f32_16x16x32_bf16 v[36:39], v[194:197], v[240:243], v[36:39]
	s_setprio 0
	s_barrier
; #define PG8_STAGE(bufoff, gbase, voff) do { _Pragma("unroll") for (int _i = 0; _i < 2; ++_i) \
;         __builtin_amdgcn_global_load_lds((const unsigned*)((const char*)(gbase) + (voff)[_i]), (PG8_LAS unsigned*)(lds + (bufoff) + ldsw + _i * 8192), 16, 0, 0); } while (0)
; #define PG8_LDA(dst, b, h) do { _Pragma("unroll") for (int m = 0; m < 4; ++m) _Pragma("unroll") for (int k = 0; k < 2; ++k) dst[m][k] = *(const PG8_LAS bf16x8*)(lds + PG8_SA(b, h) + aoff + m * 2048 + k * 1024); } while (0)
; #define PG8_MMA(ai, bj, At, Bt) do { __builtin_amdgcn_s_setprio(1); _Pragma("unroll") for (int m = 0; m < 4; ++m) _Pragma("unroll") for (int n = 0; n < 2; ++n) _Pragma("unroll") for (int k = 0; k < 2; ++k) \
;         acc[ai][bj][m][n] = __builtin_amdgcn_mfma_f32_16x16x32_bf16(Bt[n][k], At[m][k], acc[ai][bj][m][n], 0, 0, 0); __builtin_amdgcn_s_setprio(0); } while (0)
; #define PG8_WAIT_V(n) asm volatile("s_waitcnt vmcnt(" #n ")" ::: "memory")
; #define PG8_WAIT_L(n) asm volatile("s_waitcnt lgkmcnt(" #n ")" ::: "memory")
; #define PG8_BAR __builtin_amdgcn_s_barrier()
; #define PG8_SCHED __builtin_amdgcn_sched_barrier(0)
; template <class Epi, class Sched, bool ALIGN_EPI = false, bool SP2 = false>
; __device__ __forceinline__ void gemm_phase(PG8_LAS unsigned char* lds, const Gemm g, const Sched& S, const Epi& E) {
;     ...
;             PG8_LDA(At, 1, 1); PG8_STAGE(PG8_SB(1, 0), b3, voffB); PG8_STAGE(PG8_SB(1, 1), b3 + hstep, voffB); PG8_STAGE(PG8_SA(1, 0), a3, voffA);
;             PG8_WAIT_V(8); PG8_WAIT_L(0); PG8_BAR; PG8_MMA(1, 0, At, B0); PG8_MMA(1, 1, At, B1); PG8_BAR; PG8_SCHED;
;     ...
;         if constexpr (ALIGN_EPI) { if (wr == 0) PG8_BAR; }
	s_add_i32 s3, s3, s84
	v_lshl_add_u64 v[178:179], v[178:179], 0, s[8:9]
	s_mov_b32 m0, s3
	ds_read_b128 v[212:215], v164 offset:49152
	ds_read_b128 v[216:219], v164 offset:50176
	ds_read_b128 v[220:223], v164 offset:51200
	ds_read_b128 v[224:227], v164 offset:52224
	ds_read_b128 v[228:231], v164 offset:53248
	ds_read_b128 v[232:235], v164 offset:54272
	ds_read_b128 v[236:239], v164 offset:55296
	ds_read_b128 v[240:243], v164 offset:56320
	global_load_lds_dwordx4 v[178:179], off
	s_add_i32 m0, s3, 0x2000
	s_add_u32 s14, s60, 0x40080
	v_lshl_add_u64 v[178:179], v[202:203], 0, s[8:9]
	s_addc_u32 s15, s61, 0
	s_add_i32 s3, s33, s84
	global_load_lds_dwordx4 v[178:179], off
	v_lshl_add_u64 v[178:179], s[14:15], 0, v[130:131]
	s_mov_b32 m0, s3
	s_nop 0
	global_load_lds_dwordx4 v[178:179], off
	v_lshl_add_u64 v[178:179], s[14:15], 0, v[134:135]
	s_add_i32 m0, s3, 0x2000
	s_nop 0
	global_load_lds_dwordx4 v[178:179], off
	s_waitcnt vmcnt(6)
	s_waitcnt lgkmcnt(0)
	s_barrier
	s_setprio 1
	s_waitcnt lgkmcnt(0)
	v_mfma_f32_16x16x32_bf16 v[92:95], v[170:173], v[212:215], v[92:95]
	v_mfma_f32_16x16x32_bf16 v[88:91], v[182:185], v[212:215], v[88:91]
	v_mfma_f32_16x16x32_bf16 v[80:83], v[182:185], v[220:223], v[80:83]
	v_mfma_f32_16x16x32_bf16 v[84:87], v[170:173], v[220:223], v[84:87]
	v_mfma_f32_16x16x32_bf16 v[76:79], v[170:173], v[228:231], v[76:79]
	v_mfma_f32_16x16x32_bf16 v[72:75], v[182:185], v[228:231], v[72:75]
	v_mfma_f32_16x16x32_bf16 v[64:67], v[182:185], v[236:239], v[64:67]
	v_mfma_f32_16x16x32_bf16 v[68:71], v[170:173], v[236:239], v[68:71]
	v_mfma_f32_16x16x32_bf16 v[92:95], v[174:177], v[216:219], v[92:95]
	v_mfma_f32_16x16x32_bf16 v[88:91], v[186:189], v[216:219], v[88:91]
	v_mfma_f32_16x16x32_bf16 v[80:83], v[186:189], v[224:227], v[80:83]
	v_mfma_f32_16x16x32_bf16 v[84:87], v[174:177], v[224:227], v[84:87]
	v_mfma_f32_16x16x32_bf16 v[76:79], v[174:177], v[232:235], v[76:79]
	v_mfma_f32_16x16x32_bf16 v[72:75], v[186:189], v[232:235], v[72:75]
	v_lshl_add_u64 v[178:179], v[244:245], 0, s[8:9]
	s_mov_b32 m0, s90
	s_nop 0
	global_load_lds_dwordx4 v[178:179], off
	v_mfma_f32_16x16x32_bf16 v[64:67], v[186:189], v[240:243], v[64:67]
	v_mfma_f32_16x16x32_bf16 v[68:71], v[174:177], v[240:243], v[68:71]
	s_setprio 0
	s_setprio 1
	v_mfma_f32_16x16x32_bf16 v[28:31], v[190:193], v[212:215], v[28:31]
	v_mfma_f32_16x16x32_bf16 v[24:27], v[198:201], v[212:215], v[24:27]
	v_mfma_f32_16x16x32_bf16 v[16:19], v[198:201], v[220:223], v[16:19]
	v_mfma_f32_16x16x32_bf16 v[20:23], v[190:193], v[220:223], v[20:23]
	v_mfma_f32_16x16x32_bf16 v[12:15], v[190:193], v[228:231], v[12:15]
	v_mfma_f32_16x16x32_bf16 v[8:11], v[198:201], v[228:231], v[8:11]
	v_mfma_f32_16x16x32_bf16 v[0:3], v[198:201], v[236:239], v[0:3]
	v_mfma_f32_16x16x32_bf16 v[4:7], v[190:193], v[236:239], v[4:7]
	v_mfma_f32_16x16x32_bf16 v[28:31], v[194:197], v[216:219], v[28:31]
	v_mfma_f32_16x16x32_bf16 v[24:27], v[208:211], v[216:219], v[24:27]
	v_mfma_f32_16x16x32_bf16 v[16:19], v[208:211], v[224:227], v[16:19]
	v_mfma_f32_16x16x32_bf16 v[20:23], v[194:197], v[224:227], v[20:23]
	v_mfma_f32_16x16x32_bf16 v[12:15], v[194:197], v[232:235], v[12:15]
	v_mfma_f32_16x16x32_bf16 v[8:11], v[208:211], v[232:235], v[8:11]
	v_lshl_add_u64 v[178:179], v[246:247], 0, s[8:9]
	s_mov_b32 m0, s91
	s_nop 0
	global_load_lds_dwordx4 v[178:179], off
	v_mfma_f32_16x16x32_bf16 v[0:3], v[208:211], v[240:243], v[0:3]
	v_mfma_f32_16x16x32_bf16 v[4:7], v[194:197], v[240:243], v[4:7]
	s_setprio 0
	s_barrier
	s_add_i32 vcc_lo, vcc_lo, 2
	s_add_u32 s58, s58, 0x100
	s_addc_u32 s59, s59, 0
	s_add_u32 s96, s96, 0x100
	s_addc_u32 s97, s97, 0
	s_cmp_gt_u32 vcc_lo, 13
	s_cbranch_scc0 .LBB0_459
	s_and_b64 vcc, exec, s[10:11]
	s_cbranch_vccz .LBB0_462
	s_barrier

; #define PG8_STAGE(bufoff, gbase, voff) do { _Pragma("unroll") for (int _i = 0; _i < 2; ++_i) \
;         __builtin_amdgcn_global_load_lds((const unsigned*)((const char*)(gbase) + (voff)[_i]), (PG8_LAS unsigned*)(lds + (bufoff) + ldsw + _i * 8192), 16, 0, 0); } while (0)
; #define PG8_LDA(dst, b, h) do { _Pragma("unroll") for (int m = 0; m < 4; ++m) _Pragma("unroll") for (int k = 0; k < 2; ++k) dst[m][k] = *(const PG8_LAS bf16x8*)(lds + PG8_SA(b, h) + aoff + m * 2048 + k * 1024); } while (0)
; #define PG8_LDB(dst, b, h) do { _Pragma("unroll") for (int n = 0; n < 2; ++n) _Pragma("unroll") for (int k = 0; k < 2; ++k) dst[n][k] = *(const PG8_LAS bf16x8*)(lds + PG8_SB(b, h) + boff + n * 2048 + k * 1024); } while (0)
; #define PG8_MMA(ai, bj, At, Bt) do { __builtin_amdgcn_s_setprio(1); _Pragma("unroll") for (int m = 0; m < 4; ++m) _Pragma("unroll") for (int n = 0; n < 2; ++n) _Pragma("unroll") for (int k = 0; k < 2; ++k) \
;         acc[ai][bj][m][n] = __builtin_amdgcn_mfma_f32_16x16x32_bf16(Bt[n][k], At[m][k], acc[ai][bj][m][n], 0, 0, 0); __builtin_amdgcn_s_setprio(0); } while (0)
; #define PG8_WAIT_V(n) asm volatile("s_waitcnt vmcnt(" #n ")" ::: "memory")
; #define PG8_WAIT_L(n) asm volatile("s_waitcnt lgkmcnt(" #n ")" ::: "memory")
; #define PG8_BAR __builtin_amdgcn_s_barrier()
; #define PG8_SCHED __builtin_amdgcn_sched_barrier(0)
; template <class Epi, class Sched, bool ALIGN_EPI = false, bool SP2 = false>
; __device__ __forceinline__ void gemm_phase(PG8_LAS unsigned char* lds, const Gemm g, const Sched& S, const Epi& E) {
;     ...
;             const bool last = (t == nt - 2);
;             const char* a1 = cA + (size_t)(t + 1) * kstep;
;             const char* a2 = last ? nA : cA + (size_t)(t + 2) * kstep; const char* b2 = last ? nB : cB + (size_t)(t + 2) * kstep;
;             const char* a3 = a2 + kstep; const char* b3 = b2 + kstep;
;             if (last && has_next) S.a_ready(nxt);
;             if constexpr (SP2) {
;             PG8_LDB(B0, 0, 0); PG8_LDB(B1, 0, 1); PG8_SCHED; PG8_LDA(At, 0, 0); PG8_STAGE(PG8_SA(1, 1), a1 + hstep, voffA);
;             PG8_WAIT_V(8); PG8_WAIT_L(0); PG8_BAR; PG8_MMA(0, 0, At, B0); PG8_MMA(0, 1, At, B1); PG8_BAR; PG8_SCHED;
;             PG8_LDA(At, 0, 1); PG8_STAGE(PG8_SB(0, 0), b2, voffB); PG8_STAGE(PG8_SB(0, 1), b2 + hstep, voffB); PG8_STAGE(PG8_SA(0, 0), a2, voffA);
.LBB0_495:
	ds_read_b128 v[170:173], v165
	ds_read_b128 v[174:177], v165 offset:1024
	ds_read_b128 v[182:185], v165 offset:2048
	ds_read_b128 v[186:189], v165 offset:3072
	ds_read_b128 v[190:193], v168
	ds_read_b128 v[194:197], v168 offset:1024
	ds_read_b128 v[198:201], v168 offset:2048
	ds_read_b128 v[208:211], v168 offset:3072
	s_add_u32 s3, s60, 0xfffc0080
	s_addc_u32 s14, s61, -1
	s_cmp_eq_u32 s97, 12
	s_cselect_b32 s65, s49, s14
	s_cselect_b32 s64, s57, s3
	s_cselect_b32 s63, s45, s96
	s_cselect_b32 s62, s94, s95
	v_lshl_add_u64 v[178:179], s[60:61], 0, v[160:161]
	s_add_i32 m0, s59, 0xc000
	ds_read_b128 v[212:215], v164
	ds_read_b128 v[216:219], v164 offset:1024
	ds_read_b128 v[220:223], v164 offset:2048
	ds_read_b128 v[224:227], v164 offset:3072
	ds_read_b128 v[228:231], v164 offset:4096
	ds_read_b128 v[232:235], v164 offset:5120
	ds_read_b128 v[236:239], v164 offset:6144
	ds_read_b128 v[240:243], v164 offset:7168
	global_load_lds_dwordx4 v[178:179], off
	v_lshl_add_u64 v[178:179], s[60:61], 0, v[162:163]
	s_add_i32 m0, s59, 0xe000
	s_nop 0
	global_load_lds_dwordx4 v[178:179], off
	s_waitcnt vmcnt(8)
	s_waitcnt lgkmcnt(0)
	s_barrier
	s_setprio 1
	s_waitcnt lgkmcnt(0)
	v_mfma_f32_16x16x32_bf16 v[124:127], v[170:173], v[212:215], v[124:127]
	v_mfma_f32_16x16x32_bf16 v[120:123], v[182:185], v[212:215], v[120:123]
	v_mfma_f32_16x16x32_bf16 v[112:115], v[182:185], v[220:223], v[112:115]
	v_mfma_f32_16x16x32_bf16 v[116:119], v[170:173], v[220:223], v[116:119]
	v_mfma_f32_16x16x32_bf16 v[108:111], v[170:173], v[228:231], v[108:111]
	v_mfma_f32_16x16x32_bf16 v[104:107], v[182:185], v[228:231], v[104:107]
	v_mfma_f32_16x16x32_bf16 v[96:99], v[182:185], v[236:239], v[96:99]
	v_mfma_f32_16x16x32_bf16 v[100:103], v[170:173], v[236:239], v[100:103]
	v_mfma_f32_16x16x32_bf16 v[124:127], v[174:177], v[216:219], v[124:127]
	v_mfma_f32_16x16x32_bf16 v[120:123], v[186:189], v[216:219], v[120:123]
	v_mfma_f32_16x16x32_bf16 v[112:115], v[186:189], v[224:227], v[112:115]
	v_mfma_f32_16x16x32_bf16 v[116:119], v[174:177], v[224:227], v[116:119]
	v_mfma_f32_16x16x32_bf16 v[108:111], v[174:177], v[232:235], v[108:111]
	v_mfma_f32_16x16x32_bf16 v[104:107], v[186:189], v[232:235], v[104:107]
	v_mfma_f32_16x16x32_bf16 v[96:99], v[186:189], v[240:243], v[96:99]
	v_mfma_f32_16x16x32_bf16 v[100:103], v[174:177], v[240:243], v[100:103]
	s_setprio 0
	s_setprio 1
	v_mfma_f32_16x16x32_bf16 v[60:63], v[190:193], v[212:215], v[60:63]
	v_mfma_f32_16x16x32_bf16 v[56:59], v[198:201], v[212:215], v[56:59]
	v_mfma_f32_16x16x32_bf16 v[48:51], v[198:201], v[220:223], v[48:51]
	v_mfma_f32_16x16x32_bf16 v[52:55], v[190:193], v[220:223], v[52:55]
	v_mfma_f32_16x16x32_bf16 v[44:47], v[190:193], v[228:231], v[44:47]
	v_mfma_f32_16x16x32_bf16 v[40:43], v[198:201], v[228:231], v[40:43]
	v_mfma_f32_16x16x32_bf16 v[32:35], v[198:201], v[236:239], v[32:35]
	v_mfma_f32_16x16x32_bf16 v[36:39], v[190:193], v[236:239], v[36:39]
	v_mfma_f32_16x16x32_bf16 v[60:63], v[194:197], v[216:219], v[60:63]
	v_mfma_f32_16x16x32_bf16 v[56:59], v[208:211], v[216:219], v[56:59]
	v_mfma_f32_16x16x32_bf16 v[48:51], v[208:211], v[224:227], v[48:51]
	v_mfma_f32_16x16x32_bf16 v[52:55], v[194:197], v[224:227], v[52:55]
	v_mfma_f32_16x16x32_bf16 v[44:47], v[194:197], v[232:235], v[44:47]
	v_mfma_f32_16x16x32_bf16 v[40:43], v[208:211], v[232:235], v[40:43]
	v_mfma_f32_16x16x32_bf16 v[32:35], v[208:211], v[240:243], v[32:35]
	v_mfma_f32_16x16x32_bf16 v[36:39], v[194:197], v[240:243], v[36:39]
	s_setprio 0
	s_barrier
	s_add_i32 s3, s92, s75
	v_lshl_add_u64 v[178:179], s[62:63], 0, v[130:131]
	s_mov_b32 m0, s3
	ds_read_b128 v[212:215], v164 offset:16384
	ds_read_b128 v[216:219], v164 offset:17408
	ds_read_b128 v[220:223], v164 offset:18432
	ds_read_b128 v[224:227], v164 offset:19456
	ds_read_b128 v[228:231], v164 offset:20480
	ds_read_b128 v[232:235], v164 offset:21504
	ds_read_b128 v[236:239], v164 offset:22528
	ds_read_b128 v[240:243], v164 offset:23552
	global_load_lds_dwordx4 v[178:179], off
	s_add_i32 m0, s3, 0x2000
	s_add_u32 s14, s62, 0x40000
	v_lshl_add_u64 v[202:203], s[62:63], 0, v[134:135]
	s_addc_u32 s15, s63, 0
	s_add_i32 s3, s93, s75
	global_load_lds_dwordx4 v[202:203], off
	v_lshl_add_u64 v[244:245], s[14:15], 0, v[130:131]
	s_mov_b32 m0, s3
	global_load_lds_dwordx4 v[244:245], off
	v_lshl_add_u64 v[244:245], s[14:15], 0, v[134:135]
	s_add_i32 m0, s3, 0x2000
	s_nop 0
	global_load_lds_dwordx4 v[244:245], off
	s_waitcnt vmcnt(6)
	s_waitcnt lgkmcnt(0)
	s_barrier
; #define PG8_STAGE(bufoff, gbase, voff) do { _Pragma("unroll") for (int _i = 0; _i < 2; ++_i) \
;         __builtin_amdgcn_global_load_lds((const unsigned*)((const char*)(gbase) + (voff)[_i]), (PG8_LAS unsigned*)(lds + (bufoff) + ldsw + _i * 8192), 16, 0, 0); } while (0)
; #define PG8_LDA(dst, b, h) do { _Pragma("unroll") for (int m = 0; m < 4; ++m) _Pragma("unroll") for (int k = 0; k < 2; ++k) dst[m][k] = *(const PG8_LAS bf16x8*)(lds + PG8_SA(b, h) + aoff + m * 2048 + k * 1024); } while (0)
; #define PG8_LDB(dst, b, h) do { _Pragma("unroll") for (int n = 0; n < 2; ++n) _Pragma("unroll") for (int k = 0; k < 2; ++k) dst[n][k] = *(const PG8_LAS bf16x8*)(lds + PG8_SB(b, h) + boff + n * 2048 + k * 1024); } while (0)
; #define PG8_MMA(ai, bj, At, Bt) do { __builtin_amdgcn_s_setprio(1); _Pragma("unroll") for (int m = 0; m < 4; ++m) _Pragma("unroll") for (int n = 0; n < 2; ++n) _Pragma("unroll") for (int k = 0; k < 2; ++k) \
;         acc[ai][bj][m][n] = __builtin_amdgcn_mfma_f32_16x16x32_bf16(Bt[n][k], At[m][k], acc[ai][bj][m][n], 0, 0, 0); __builtin_amdgcn_s_setprio(0); } while (0)
; #define PG8_WAIT_V(n) asm volatile("s_waitcnt vmcnt(" #n ")" ::: "memory")
; #define PG8_WAIT_L(n) asm volatile("s_waitcnt lgkmcnt(" #n ")" ::: "memory")
; #define PG8_BAR __builtin_amdgcn_s_barrier()
; #define PG8_SCHED __builtin_amdgcn_sched_barrier(0)
; template <class Epi, class Sched, bool ALIGN_EPI = false, bool SP2 = false>
; __device__ __forceinline__ void gemm_phase(PG8_LAS unsigned char* lds, const Gemm g, const Sched& S, const Epi& E) {
;     ...
;             PG8_WAIT_V(8); PG8_WAIT_L(0); PG8_BAR; PG8_MMA(1, 0, At, B0); PG8_MMA(1, 1, At, B1); PG8_BAR; PG8_SCHED;
;             PG8_LDB(B0, 1, 0); PG8_LDB(B1, 1, 1); PG8_SCHED; PG8_LDA(At, 1, 0); PG8_STAGE(PG8_SA(0, 1), a2 + hstep, voffA);
;             PG8_WAIT_V(8); PG8_WAIT_L(0); PG8_BAR; PG8_MMA(0, 0, At, B0); PG8_MMA(0, 1, At, B1); PG8_BAR; PG8_SCHED;
	s_setprio 1
	s_waitcnt lgkmcnt(0)
	v_mfma_f32_16x16x32_bf16 v[92:95], v[170:173], v[212:215], v[92:95]
	v_mfma_f32_16x16x32_bf16 v[88:91], v[182:185], v[212:215], v[88:91]
	v_mfma_f32_16x16x32_bf16 v[80:83], v[182:185], v[220:223], v[80:83]
	v_mfma_f32_16x16x32_bf16 v[84:87], v[170:173], v[220:223], v[84:87]
	v_mfma_f32_16x16x32_bf16 v[76:79], v[170:173], v[228:231], v[76:79]
	v_mfma_f32_16x16x32_bf16 v[72:75], v[182:185], v[228:231], v[72:75]
	v_mfma_f32_16x16x32_bf16 v[64:67], v[182:185], v[236:239], v[64:67]
	v_mfma_f32_16x16x32_bf16 v[68:71], v[170:173], v[236:239], v[68:71]
	v_mfma_f32_16x16x32_bf16 v[92:95], v[174:177], v[216:219], v[92:95]
	v_mfma_f32_16x16x32_bf16 v[88:91], v[186:189], v[216:219], v[88:91]
	v_mfma_f32_16x16x32_bf16 v[80:83], v[186:189], v[224:227], v[80:83]
	v_mfma_f32_16x16x32_bf16 v[84:87], v[174:177], v[224:227], v[84:87]
	v_mfma_f32_16x16x32_bf16 v[76:79], v[174:177], v[232:235], v[76:79]
	v_mfma_f32_16x16x32_bf16 v[72:75], v[186:189], v[232:235], v[72:75]
	v_lshl_add_u64 v[244:245], s[64:65], 0, v[128:129]
	s_mov_b32 m0, s59
	s_nop 0
	global_load_lds_dwordx4 v[244:245], off
	v_mfma_f32_16x16x32_bf16 v[64:67], v[186:189], v[240:243], v[64:67]
	v_mfma_f32_16x16x32_bf16 v[68:71], v[174:177], v[240:243], v[68:71]
	s_setprio 0
	s_setprio 1
	v_mfma_f32_16x16x32_bf16 v[28:31], v[190:193], v[212:215], v[28:31]
	v_mfma_f32_16x16x32_bf16 v[24:27], v[198:201], v[212:215], v[24:27]
	v_mfma_f32_16x16x32_bf16 v[16:19], v[198:201], v[220:223], v[16:19]
	v_mfma_f32_16x16x32_bf16 v[20:23], v[190:193], v[220:223], v[20:23]
	v_mfma_f32_16x16x32_bf16 v[12:15], v[190:193], v[228:231], v[12:15]
	v_mfma_f32_16x16x32_bf16 v[8:11], v[198:201], v[228:231], v[8:11]
	v_mfma_f32_16x16x32_bf16 v[0:3], v[198:201], v[236:239], v[0:3]
	v_mfma_f32_16x16x32_bf16 v[4:7], v[190:193], v[236:239], v[4:7]
	v_mfma_f32_16x16x32_bf16 v[28:31], v[194:197], v[216:219], v[28:31]
	v_mfma_f32_16x16x32_bf16 v[24:27], v[208:211], v[216:219], v[24:27]
	v_mfma_f32_16x16x32_bf16 v[16:19], v[208:211], v[224:227], v[16:19]
	v_mfma_f32_16x16x32_bf16 v[20:23], v[194:197], v[224:227], v[20:23]
	v_mfma_f32_16x16x32_bf16 v[12:15], v[194:197], v[232:235], v[12:15]
	v_mfma_f32_16x16x32_bf16 v[8:11], v[208:211], v[232:235], v[8:11]
	v_lshl_add_u64 v[246:247], s[64:65], 0, v[132:133]
	s_mov_b32 m0, s84
	s_nop 0
	global_load_lds_dwordx4 v[246:247], off
	v_mfma_f32_16x16x32_bf16 v[0:3], v[208:211], v[240:243], v[0:3]
	v_mfma_f32_16x16x32_bf16 v[4:7], v[194:197], v[240:243], v[4:7]
	s_setprio 0
	s_barrier
	s_add_i32 s3, 0, 0x18000
	v_add_u32_e32 v136, s3, v141
	s_add_i32 s33, 0, 0x1c000
	ds_read_b128 v[170:173], v136
	ds_read_b128 v[174:177], v136 offset:1024
	ds_read_b128 v[182:185], v136 offset:2048
	ds_read_b128 v[186:189], v136 offset:3072
	v_add_u32_e32 v136, s33, v141
	ds_read_b128 v[190:193], v136
	ds_read_b128 v[194:197], v136 offset:1024
	ds_read_b128 v[198:201], v136 offset:2048
	ds_read_b128 v[208:211], v136 offset:3072
	s_add_u32 s14, s64, 0x40000
	s_addc_u32 s15, s65, 0
	s_mov_b32 m0, s85
	v_lshl_add_u64 v[248:249], s[14:15], 0, v[128:129]
	ds_read_b128 v[212:215], v164 offset:32768
	ds_read_b128 v[216:219], v164 offset:33792
	ds_read_b128 v[220:223], v164 offset:34816
	ds_read_b128 v[224:227], v164 offset:35840
	ds_read_b128 v[228:231], v164 offset:36864
	ds_read_b128 v[232:235], v164 offset:37888
	ds_read_b128 v[236:239], v164 offset:38912
	ds_read_b128 v[240:243], v164 offset:39936
	global_load_lds_dwordx4 v[248:249], off
	v_lshl_add_u64 v[248:249], s[14:15], 0, v[132:133]
	s_mov_b32 m0, s86
	s_nop 0
	global_load_lds_dwordx4 v[248:249], off
	s_waitcnt vmcnt(8)
	s_waitcnt lgkmcnt(0)
	s_barrier
	s_setprio 1
	s_waitcnt lgkmcnt(0)
	v_mfma_f32_16x16x32_bf16 v[124:127], v[170:173], v[212:215], v[124:127]
	v_mfma_f32_16x16x32_bf16 v[120:123], v[182:185], v[212:215], v[120:123]
	v_mfma_f32_16x16x32_bf16 v[112:115], v[182:185], v[220:223], v[112:115]
	v_mfma_f32_16x16x32_bf16 v[116:119], v[170:173], v[220:223], v[116:119]
	v_mfma_f32_16x16x32_bf16 v[108:111], v[170:173], v[228:231], v[108:111]
	v_mfma_f32_16x16x32_bf16 v[104:107], v[182:185], v[228:231], v[104:107]
	v_mfma_f32_16x16x32_bf16 v[96:99], v[182:185], v[236:239], v[96:99]
	v_mfma_f32_16x16x32_bf16 v[100:103], v[170:173], v[236:239], v[100:103]
	v_mfma_f32_16x16x32_bf16 v[124:127], v[174:177], v[216:219], v[124:127]
	v_mfma_f32_16x16x32_bf16 v[120:123], v[186:189], v[216:219], v[120:123]
	v_mfma_f32_16x16x32_bf16 v[112:115], v[186:189], v[224:227], v[112:115]
	v_mfma_f32_16x16x32_bf16 v[116:119], v[174:177], v[224:227], v[116:119]
	v_mfma_f32_16x16x32_bf16 v[108:111], v[174:177], v[232:235], v[108:111]
	v_mfma_f32_16x16x32_bf16 v[104:107], v[186:189], v[232:235], v[104:107]
	v_mfma_f32_16x16x32_bf16 v[96:99], v[186:189], v[240:243], v[96:99]
	v_mfma_f32_16x16x32_bf16 v[100:103], v[174:177], v[240:243], v[100:103]
	s_setprio 0
	s_setprio 1
	v_mfma_f32_16x16x32_bf16 v[60:63], v[190:193], v[212:215], v[60:63]
	v_mfma_f32_16x16x32_bf16 v[56:59], v[198:201], v[212:215], v[56:59]
	v_mfma_f32_16x16x32_bf16 v[48:51], v[198:201], v[220:223], v[48:51]
	v_mfma_f32_16x16x32_bf16 v[52:55], v[190:193], v[220:223], v[52:55]
	v_mfma_f32_16x16x32_bf16 v[44:47], v[190:193], v[228:231], v[44:47]
	v_mfma_f32_16x16x32_bf16 v[40:43], v[198:201], v[228:231], v[40:43]
	v_mfma_f32_16x16x32_bf16 v[32:35], v[198:201], v[236:239], v[32:35]
	v_mfma_f32_16x16x32_bf16 v[36:39], v[190:193], v[236:239], v[36:39]
	v_mfma_f32_16x16x32_bf16 v[60:63], v[194:197], v[216:219], v[60:63]
	v_mfma_f32_16x16x32_bf16 v[56:59], v[208:211], v[216:219], v[56:59]
	v_mfma_f32_16x16x32_bf16 v[48:51], v[208:211], v[224:227], v[48:51]
	v_mfma_f32_16x16x32_bf16 v[52:55], v[194:197], v[224:227], v[52:55]
	v_mfma_f32_16x16x32_bf16 v[44:47], v[194:197], v[232:235], v[44:47]
	v_mfma_f32_16x16x32_bf16 v[40:43], v[208:211], v[232:235], v[40:43]
	v_mfma_f32_16x16x32_bf16 v[32:35], v[208:211], v[240:243], v[32:35]
	v_mfma_f32_16x16x32_bf16 v[36:39], v[194:197], v[240:243], v[36:39]
	s_setprio 0
	s_barrier
; #define PG8_STAGE(bufoff, gbase, voff) do { _Pragma("unroll") for (int _i = 0; _i < 2; ++_i) \
;         __builtin_amdgcn_global_load_lds((const unsigned*)((const char*)(gbase) + (voff)[_i]), (PG8_LAS unsigned*)(lds + (bufoff) + ldsw + _i * 8192), 16, 0, 0); } while (0)
; #define PG8_LDA(dst, b, h) do { _Pragma("unroll") for (int m = 0; m < 4; ++m) _Pragma("unroll") for (int k = 0; k < 2; ++k) dst[m][k] = *(const PG8_LAS bf16x8*)(lds + PG8_SA(b, h) + aoff + m * 2048 + k * 1024); } while (0)
; #define PG8_MMA(ai, bj, At, Bt) do { __builtin_amdgcn_s_setprio(1); _Pragma("unroll") for (int m = 0; m < 4; ++m) _Pragma("unroll") for (int n = 0; n < 2; ++n) _Pragma("unroll") for (int k = 0; k < 2; ++k) \
;         acc[ai][bj][m][n] = __builtin_amdgcn_mfma_f32_16x16x32_bf16(Bt[n][k], At[m][k], acc[ai][bj][m][n], 0, 0, 0); __builtin_amdgcn_s_setprio(0); } while (0)
; #define PG8_WAIT_V(n) asm volatile("s_waitcnt vmcnt(" #n ")" ::: "memory")
; #define PG8_WAIT_L(n) asm volatile("s_waitcnt lgkmcnt(" #n ")" ::: "memory")
; #define PG8_BAR __builtin_amdgcn_s_barrier()
; #define PG8_SCHED __builtin_amdgcn_sched_barrier(0)
; template <class Epi, class Sched, bool ALIGN_EPI = false, bool SP2 = false>
; __device__ __forceinline__ void gemm_phase(PG8_LAS unsigned char* lds, const Gemm g, const Sched& S, const Epi& E) {
;     ...
;             PG8_LDA(At, 1, 1); PG8_STAGE(PG8_SB(1, 0), b3, voffB); PG8_STAGE(PG8_SB(1, 1), b3 + hstep, voffB); PG8_STAGE(PG8_SA(1, 0), a3, voffA);
;             PG8_WAIT_V(8); PG8_WAIT_L(0); PG8_BAR; PG8_MMA(1, 0, At, B0); PG8_MMA(1, 1, At, B1); PG8_BAR; PG8_SCHED;
;     ...
;         if constexpr (ALIGN_EPI) { if (wr == 0) PG8_BAR; }
	s_add_i32 s3, s3, s75
	v_lshl_add_u64 v[178:179], v[178:179], 0, s[10:11]
	s_mov_b32 m0, s3
	ds_read_b128 v[212:215], v164 offset:49152
	ds_read_b128 v[216:219], v164 offset:50176
	ds_read_b128 v[220:223], v164 offset:51200
	ds_read_b128 v[224:227], v164 offset:52224
	ds_read_b128 v[228:231], v164 offset:53248
	ds_read_b128 v[232:235], v164 offset:54272
	ds_read_b128 v[236:239], v164 offset:55296
	ds_read_b128 v[240:243], v164 offset:56320
	global_load_lds_dwordx4 v[178:179], off
	s_add_i32 m0, s3, 0x2000
	s_add_u32 s14, s62, 0x40080
	v_lshl_add_u64 v[178:179], v[202:203], 0, s[10:11]
	s_addc_u32 s15, s63, 0
	s_add_i32 s3, s33, s75
	global_load_lds_dwordx4 v[178:179], off
	v_lshl_add_u64 v[178:179], s[14:15], 0, v[130:131]
	s_mov_b32 m0, s3
	s_nop 0
	global_load_lds_dwordx4 v[178:179], off
	v_lshl_add_u64 v[178:179], s[14:15], 0, v[134:135]
	s_add_i32 m0, s3, 0x2000
	s_nop 0
	global_load_lds_dwordx4 v[178:179], off
	s_waitcnt vmcnt(6)
	s_waitcnt lgkmcnt(0)
	s_barrier
	s_setprio 1
	s_waitcnt lgkmcnt(0)
	v_mfma_f32_16x16x32_bf16 v[92:95], v[170:173], v[212:215], v[92:95]
	v_mfma_f32_16x16x32_bf16 v[88:91], v[182:185], v[212:215], v[88:91]
	v_mfma_f32_16x16x32_bf16 v[80:83], v[182:185], v[220:223], v[80:83]
	v_mfma_f32_16x16x32_bf16 v[84:87], v[170:173], v[220:223], v[84:87]
	v_mfma_f32_16x16x32_bf16 v[76:79], v[170:173], v[228:231], v[76:79]
	v_mfma_f32_16x16x32_bf16 v[72:75], v[182:185], v[228:231], v[72:75]
	v_mfma_f32_16x16x32_bf16 v[64:67], v[182:185], v[236:239], v[64:67]
	v_mfma_f32_16x16x32_bf16 v[68:71], v[170:173], v[236:239], v[68:71]
	v_mfma_f32_16x16x32_bf16 v[92:95], v[174:177], v[216:219], v[92:95]
	v_mfma_f32_16x16x32_bf16 v[88:91], v[186:189], v[216:219], v[88:91]
	v_mfma_f32_16x16x32_bf16 v[80:83], v[186:189], v[224:227], v[80:83]
	v_mfma_f32_16x16x32_bf16 v[84:87], v[174:177], v[224:227], v[84:87]
	v_mfma_f32_16x16x32_bf16 v[76:79], v[174:177], v[232:235], v[76:79]
	v_mfma_f32_16x16x32_bf16 v[72:75], v[186:189], v[232:235], v[72:75]
	v_lshl_add_u64 v[178:179], v[244:245], 0, s[10:11]
	s_mov_b32 m0, s88
	s_nop 0
	global_load_lds_dwordx4 v[178:179], off
	v_mfma_f32_16x16x32_bf16 v[64:67], v[186:189], v[240:243], v[64:67]
	v_mfma_f32_16x16x32_bf16 v[68:71], v[174:177], v[240:243], v[68:71]
	s_setprio 0
	s_setprio 1
	v_mfma_f32_16x16x32_bf16 v[28:31], v[190:193], v[212:215], v[28:31]
	v_mfma_f32_16x16x32_bf16 v[24:27], v[198:201], v[212:215], v[24:27]
	v_mfma_f32_16x16x32_bf16 v[16:19], v[198:201], v[220:223], v[16:19]
	v_mfma_f32_16x16x32_bf16 v[20:23], v[190:193], v[220:223], v[20:23]
	v_mfma_f32_16x16x32_bf16 v[12:15], v[190:193], v[228:231], v[12:15]
	v_mfma_f32_16x16x32_bf16 v[8:11], v[198:201], v[228:231], v[8:11]
	v_mfma_f32_16x16x32_bf16 v[0:3], v[198:201], v[236:239], v[0:3]
	v_mfma_f32_16x16x32_bf16 v[4:7], v[190:193], v[236:239], v[4:7]
	v_mfma_f32_16x16x32_bf16 v[28:31], v[194:197], v[216:219], v[28:31]
	v_mfma_f32_16x16x32_bf16 v[24:27], v[208:211], v[216:219], v[24:27]
	v_mfma_f32_16x16x32_bf16 v[16:19], v[208:211], v[224:227], v[16:19]
	v_mfma_f32_16x16x32_bf16 v[20:23], v[194:197], v[224:227], v[20:23]
	v_mfma_f32_16x16x32_bf16 v[12:15], v[194:197], v[232:235], v[12:15]
	v_mfma_f32_16x16x32_bf16 v[8:11], v[208:211], v[232:235], v[8:11]
	v_lshl_add_u64 v[178:179], v[246:247], 0, s[10:11]
	s_mov_b32 m0, s89
	s_nop 0
	global_load_lds_dwordx4 v[178:179], off
	v_mfma_f32_16x16x32_bf16 v[0:3], v[208:211], v[240:243], v[0:3]
	v_mfma_f32_16x16x32_bf16 v[4:7], v[194:197], v[240:243], v[4:7]
	s_setprio 0
	s_barrier
	s_add_i32 s97, s97, 2
	s_add_u32 s60, s60, 0x100
	s_addc_u32 s61, s61, 0
	s_add_u32 s95, s95, 0x100
	s_addc_u32 s96, s96, 0
	s_cmp_lt_u32 s97, 14
	s_cbranch_scc1 .LBB0_495
	s_andn2_b64 vcc, exec, s[40:41]
	s_cbranch_vccnz .LBB0_498
	s_barrier

; #define PG8_STAGE(bufoff, gbase, voff) do { _Pragma("unroll") for (int _i = 0; _i < 2; ++_i) \
;         __builtin_amdgcn_global_load_lds((const unsigned*)((const char*)(gbase) + (voff)[_i]), (PG8_LAS unsigned*)(lds + (bufoff) + ldsw + _i * 8192), 16, 0, 0); } while (0)
; #define PG8_LDA(dst, b, h) do { _Pragma("unroll") for (int m = 0; m < 4; ++m) _Pragma("unroll") for (int k = 0; k < 2; ++k) dst[m][k] = *(const PG8_LAS bf16x8*)(lds + PG8_SA(b, h) + aoff + m * 2048 + k * 1024); } while (0)
; #define PG8_LDB(dst, b, h) do { _Pragma("unroll") for (int n = 0; n < 2; ++n) _Pragma("unroll") for (int k = 0; k < 2; ++k) dst[n][k] = *(const PG8_LAS bf16x8*)(lds + PG8_SB(b, h) + boff + n * 2048 + k * 1024); } while (0)
; #define PG8_MMA(ai, bj, At, Bt) do { __builtin_amdgcn_s_setprio(1); _Pragma("unroll") for (int m = 0; m < 4; ++m) _Pragma("unroll") for (int n = 0; n < 2; ++n) _Pragma("unroll") for (int k = 0; k < 2; ++k) \
;         acc[ai][bj][m][n] = __builtin_amdgcn_mfma_f32_16x16x32_bf16(Bt[n][k], At[m][k], acc[ai][bj][m][n], 0, 0, 0); __builtin_amdgcn_s_setprio(0); } while (0)
; #define PG8_BAR __builtin_amdgcn_s_barrier()
; template <class Epi, class Sched, bool ALIGN_EPI = false, bool SP2 = false>
; __device__ __forceinline__ void gemm_phase(PG8_LAS unsigned char* lds, const Gemm g, const Sched& S, const Epi& E) {
;     ...
;         const bool has_next = S.next(ui + 1, nxt);
;         const char* nA = has_next ? (const char*)g.A + (size_t)nxt.pm * tstep : cA; const char* nB = has_next ? (const char*)g.Bt + (size_t)nxt.pn * tstep : cB;
;         for (int t = 0; t < nt; t += 2) {
;             const bool last = (t == nt - 2);
;             const char* a1 = cA + (size_t)(t + 1) * kstep;
;             const char* a2 = last ? nA : cA + (size_t)(t + 2) * kstep; const char* b2 = last ? nB : cB + (size_t)(t + 2) * kstep;
;             const char* a3 = a2 + kstep; const char* b3 = b2 + kstep;
;             if (last && has_next) S.a_ready(nxt);
;             if constexpr (SP2) {
;             PG8_LDB(B0, 0, 0); PG8_LDB(B1, 0, 1); PG8_SCHED; PG8_LDA(At, 0, 0); PG8_STAGE(PG8_SA(1, 1), a1 + hstep, voffA);
;             PG8_WAIT_V(8); PG8_WAIT_L(0); PG8_BAR; PG8_MMA(0, 0, At, B0); PG8_MMA(0, 1, At, B1); PG8_BAR; PG8_SCHED;
;             PG8_LDA(At, 0, 1); PG8_STAGE(PG8_SB(0, 0), b2, voffB); PG8_STAGE(PG8_SB(0, 1), b2 + hstep, voffB); PG8_STAGE(PG8_SA(0, 0), a2, voffA);
.LBB0_649:
	s_ashr_i32 s51, s50, 31
	s_lshl_b64 s[14:15], s[50:51], 19
	s_add_u32 s52, s40, s14
	s_addc_u32 s53, s41, s15
	s_and_b64 s[14:15], s[8:9], exec
	s_cselect_b32 s51, s53, s61
	s_cselect_b32 s57, s52, s60
	s_ashr_i32 s49, s48, 31
	s_lshl_b64 s[14:15], s[48:49], 19
	s_add_u32 s54, s82, s14
	s_addc_u32 s55, s83, s15
	s_and_b64 s[14:15], s[8:9], exec
	s_cselect_b32 s49, s55, s63
	s_cselect_b32 s89, s54, s62
	s_add_u32 s60, s60, 0x40080
	s_addc_u32 s61, s61, 0
	s_add_u32 s90, s62, 0x100
	s_addc_u32 s91, s63, 0
	s_mov_b32 s92, -2
	s_waitcnt lgkmcnt(0)
	s_waitcnt vmcnt(0)
	ds_read_b128 v[148:151], v155
	ds_read_b128 v[160:163], v155 offset:1024
	ds_read_b128 v[164:167], v155 offset:2048
	ds_read_b128 v[168:171], v155 offset:3072
	ds_read_b128 v[172:175], v156
	ds_read_b128 v[176:179], v156 offset:1024
	ds_read_b128 v[182:185], v156 offset:2048
	ds_read_b128 v[186:189], v156 offset:3072
	s_add_u32 s3, s60, 0xfffc0080
	s_addc_u32 s14, s61, -1
	s_cmp_eq_u32 s92, 12
	s_cselect_b32 s65, s51, s14
	s_cselect_b32 s64, s57, s3
	s_cselect_b32 s63, s49, s91
	s_cselect_b32 s62, s89, s90
	v_lshl_add_u64 v[202:203], s[60:61], 0, v[140:141]
	s_add_i32 m0, s43, 0xc000
	ds_read_b128 v[190:193], v157
	ds_read_b128 v[194:197], v157 offset:1024
	ds_read_b128 v[198:201], v157 offset:2048
	ds_read_b128 v[208:211], v157 offset:3072
	ds_read_b128 v[212:215], v157 offset:4096
	ds_read_b128 v[216:219], v157 offset:5120
	ds_read_b128 v[220:223], v157 offset:6144
	ds_read_b128 v[224:227], v157 offset:7168
	global_load_lds_dwordx4 v[202:203], off
	v_lshl_add_u64 v[202:203], s[60:61], 0, v[142:143]
	s_add_i32 m0, s43, 0xe000
	s_nop 0
	global_load_lds_dwordx4 v[202:203], off
	s_waitcnt vmcnt(8)
	s_waitcnt lgkmcnt(0)
	s_barrier
	s_setprio 1
	s_waitcnt lgkmcnt(0)
	v_mfma_f32_16x16x32_bf16 v[124:127], v[148:151], v[190:193], 0
	v_mfma_f32_16x16x32_bf16 v[120:123], v[164:167], v[190:193], 0
	v_mfma_f32_16x16x32_bf16 v[104:107], v[164:167], v[198:201], 0
	v_mfma_f32_16x16x32_bf16 v[108:111], v[148:151], v[198:201], 0
	v_mfma_f32_16x16x32_bf16 v[92:95], v[148:151], v[212:215], 0
	v_mfma_f32_16x16x32_bf16 v[88:91], v[164:167], v[212:215], 0
	v_mfma_f32_16x16x32_bf16 v[72:75], v[164:167], v[220:223], 0
	v_mfma_f32_16x16x32_bf16 v[76:79], v[148:151], v[220:223], 0
	v_mfma_f32_16x16x32_bf16 v[124:127], v[160:163], v[194:197], v[124:127]
	v_mfma_f32_16x16x32_bf16 v[120:123], v[168:171], v[194:197], v[120:123]
	v_mfma_f32_16x16x32_bf16 v[104:107], v[168:171], v[208:211], v[104:107]
	v_mfma_f32_16x16x32_bf16 v[108:111], v[160:163], v[208:211], v[108:111]
	v_mfma_f32_16x16x32_bf16 v[92:95], v[160:163], v[216:219], v[92:95]
	v_mfma_f32_16x16x32_bf16 v[88:91], v[168:171], v[216:219], v[88:91]
	v_mfma_f32_16x16x32_bf16 v[72:75], v[168:171], v[224:227], v[72:75]
	v_mfma_f32_16x16x32_bf16 v[76:79], v[160:163], v[224:227], v[76:79]
	s_setprio 0
	s_setprio 1
	v_mfma_f32_16x16x32_bf16 v[116:119], v[172:175], v[190:193], 0
	v_mfma_f32_16x16x32_bf16 v[112:115], v[182:185], v[190:193], 0
	v_mfma_f32_16x16x32_bf16 v[96:99], v[182:185], v[198:201], 0
	v_mfma_f32_16x16x32_bf16 v[100:103], v[172:175], v[198:201], 0
	v_mfma_f32_16x16x32_bf16 v[84:87], v[172:175], v[212:215], 0
	v_mfma_f32_16x16x32_bf16 v[80:83], v[182:185], v[212:215], 0
	v_mfma_f32_16x16x32_bf16 v[64:67], v[182:185], v[220:223], 0
	v_mfma_f32_16x16x32_bf16 v[68:71], v[172:175], v[220:223], 0
	v_mfma_f32_16x16x32_bf16 v[116:119], v[176:179], v[194:197], v[116:119]
	v_mfma_f32_16x16x32_bf16 v[112:115], v[186:189], v[194:197], v[112:115]
	v_mfma_f32_16x16x32_bf16 v[96:99], v[186:189], v[208:211], v[96:99]
	v_mfma_f32_16x16x32_bf16 v[100:103], v[176:179], v[208:211], v[100:103]
	v_mfma_f32_16x16x32_bf16 v[84:87], v[176:179], v[216:219], v[84:87]
	v_mfma_f32_16x16x32_bf16 v[80:83], v[186:189], v[216:219], v[80:83]
	v_mfma_f32_16x16x32_bf16 v[64:67], v[186:189], v[224:227], v[64:67]
	v_mfma_f32_16x16x32_bf16 v[68:71], v[176:179], v[224:227], v[68:71]
	s_setprio 0
	s_barrier
	s_add_i32 s3, s85, s34
	v_lshl_add_u64 v[202:203], s[62:63], 0, v[134:135]
	s_mov_b32 m0, s3
	ds_read_b128 v[190:193], v157 offset:16384
	ds_read_b128 v[194:197], v157 offset:17408
	ds_read_b128 v[198:201], v157 offset:18432
	ds_read_b128 v[208:211], v157 offset:19456
	ds_read_b128 v[212:215], v157 offset:20480
	ds_read_b128 v[216:219], v157 offset:21504
	ds_read_b128 v[220:223], v157 offset:22528
	ds_read_b128 v[224:227], v157 offset:23552
	global_load_lds_dwordx4 v[202:203], off
	s_add_i32 m0, s3, 0x2000
	s_add_u32 s14, s62, 0x40000
	v_lshl_add_u64 v[228:229], s[62:63], 0, v[138:139]
	s_addc_u32 s15, s63, 0
	s_add_i32 s3, s86, s34
	global_load_lds_dwordx4 v[228:229], off
	v_lshl_add_u64 v[230:231], s[14:15], 0, v[134:135]
	s_mov_b32 m0, s3
	global_load_lds_dwordx4 v[230:231], off
	v_lshl_add_u64 v[230:231], s[14:15], 0, v[138:139]
	s_add_i32 m0, s3, 0x2000
	s_nop 0
	global_load_lds_dwordx4 v[230:231], off
	s_waitcnt vmcnt(6)
	s_waitcnt lgkmcnt(0)
	s_barrier
; #define PG8_STAGE(bufoff, gbase, voff) do { _Pragma("unroll") for (int _i = 0; _i < 2; ++_i) \
;         __builtin_amdgcn_global_load_lds((const unsigned*)((const char*)(gbase) + (voff)[_i]), (PG8_LAS unsigned*)(lds + (bufoff) + ldsw + _i * 8192), 16, 0, 0); } while (0)
; #define PG8_LDA(dst, b, h) do { _Pragma("unroll") for (int m = 0; m < 4; ++m) _Pragma("unroll") for (int k = 0; k < 2; ++k) dst[m][k] = *(const PG8_LAS bf16x8*)(lds + PG8_SA(b, h) + aoff + m * 2048 + k * 1024); } while (0)
; #define PG8_LDB(dst, b, h) do { _Pragma("unroll") for (int n = 0; n < 2; ++n) _Pragma("unroll") for (int k = 0; k < 2; ++k) dst[n][k] = *(const PG8_LAS bf16x8*)(lds + PG8_SB(b, h) + boff + n * 2048 + k * 1024); } while (0)
; #define PG8_MMA(ai, bj, At, Bt) do { __builtin_amdgcn_s_setprio(1); _Pragma("unroll") for (int m = 0; m < 4; ++m) _Pragma("unroll") for (int n = 0; n < 2; ++n) _Pragma("unroll") for (int k = 0; k < 2; ++k) \
;         acc[ai][bj][m][n] = __builtin_amdgcn_mfma_f32_16x16x32_bf16(Bt[n][k], At[m][k], acc[ai][bj][m][n], 0, 0, 0); __builtin_amdgcn_s_setprio(0); } while (0)
; #define PG8_WAIT_V(n) asm volatile("s_waitcnt vmcnt(" #n ")" ::: "memory")
; #define PG8_WAIT_L(n) asm volatile("s_waitcnt lgkmcnt(" #n ")" ::: "memory")
; #define PG8_BAR __builtin_amdgcn_s_barrier()
; #define PG8_SCHED __builtin_amdgcn_sched_barrier(0)
; template <class Epi, class Sched, bool ALIGN_EPI = false, bool SP2 = false>
; __device__ __forceinline__ void gemm_phase(PG8_LAS unsigned char* lds, const Gemm g, const Sched& S, const Epi& E) {
;     ...
;             PG8_WAIT_V(8); PG8_WAIT_L(0); PG8_BAR; PG8_MMA(1, 0, At, B0); PG8_MMA(1, 1, At, B1); PG8_BAR; PG8_SCHED;
;             PG8_LDB(B0, 1, 0); PG8_LDB(B1, 1, 1); PG8_SCHED; PG8_LDA(At, 1, 0); PG8_STAGE(PG8_SA(0, 1), a2 + hstep, voffA);
;             PG8_WAIT_V(8); PG8_WAIT_L(0); PG8_BAR; PG8_MMA(0, 0, At, B0); PG8_MMA(0, 1, At, B1); PG8_BAR; PG8_SCHED;
	s_setprio 1
	s_waitcnt lgkmcnt(0)
	v_mfma_f32_16x16x32_bf16 v[60:63], v[148:151], v[190:193], 0
	v_mfma_f32_16x16x32_bf16 v[56:59], v[164:167], v[190:193], 0
	v_mfma_f32_16x16x32_bf16 v[40:43], v[164:167], v[198:201], 0
	v_mfma_f32_16x16x32_bf16 v[44:47], v[148:151], v[198:201], 0
	v_mfma_f32_16x16x32_bf16 v[28:31], v[148:151], v[212:215], 0
	v_mfma_f32_16x16x32_bf16 v[24:27], v[164:167], v[212:215], 0
	v_mfma_f32_16x16x32_bf16 v[8:11], v[164:167], v[220:223], 0
	v_mfma_f32_16x16x32_bf16 v[12:15], v[148:151], v[220:223], 0
	v_mfma_f32_16x16x32_bf16 v[60:63], v[160:163], v[194:197], v[60:63]
	v_mfma_f32_16x16x32_bf16 v[56:59], v[168:171], v[194:197], v[56:59]
	v_mfma_f32_16x16x32_bf16 v[40:43], v[168:171], v[208:211], v[40:43]
	v_mfma_f32_16x16x32_bf16 v[44:47], v[160:163], v[208:211], v[44:47]
	v_mfma_f32_16x16x32_bf16 v[28:31], v[160:163], v[216:219], v[28:31]
	v_mfma_f32_16x16x32_bf16 v[24:27], v[168:171], v[216:219], v[24:27]
	v_lshl_add_u64 v[230:231], s[64:65], 0, v[132:133]
	s_mov_b32 m0, s43
	s_nop 0
	global_load_lds_dwordx4 v[230:231], off
	v_mfma_f32_16x16x32_bf16 v[8:11], v[168:171], v[224:227], v[8:11]
	v_mfma_f32_16x16x32_bf16 v[12:15], v[160:163], v[224:227], v[12:15]
	s_setprio 0
	s_setprio 1
	v_mfma_f32_16x16x32_bf16 v[52:55], v[172:175], v[190:193], 0
	v_mfma_f32_16x16x32_bf16 v[48:51], v[182:185], v[190:193], 0
	v_mfma_f32_16x16x32_bf16 v[32:35], v[182:185], v[198:201], 0
	v_mfma_f32_16x16x32_bf16 v[36:39], v[172:175], v[198:201], 0
	v_mfma_f32_16x16x32_bf16 v[20:23], v[172:175], v[212:215], 0
	v_mfma_f32_16x16x32_bf16 v[16:19], v[182:185], v[212:215], 0
	v_mfma_f32_16x16x32_bf16 v[0:3], v[182:185], v[220:223], 0
	v_mfma_f32_16x16x32_bf16 v[4:7], v[172:175], v[220:223], 0
	v_mfma_f32_16x16x32_bf16 v[52:55], v[176:179], v[194:197], v[52:55]
	v_mfma_f32_16x16x32_bf16 v[48:51], v[186:189], v[194:197], v[48:51]
	v_mfma_f32_16x16x32_bf16 v[32:35], v[186:189], v[208:211], v[32:35]
	v_mfma_f32_16x16x32_bf16 v[36:39], v[176:179], v[208:211], v[36:39]
	v_mfma_f32_16x16x32_bf16 v[20:23], v[176:179], v[216:219], v[20:23]
	v_mfma_f32_16x16x32_bf16 v[16:19], v[186:189], v[216:219], v[16:19]
	v_lshl_add_u64 v[232:233], s[64:65], 0, v[136:137]
	s_mov_b32 m0, s59
	s_nop 0
	global_load_lds_dwordx4 v[232:233], off
	v_mfma_f32_16x16x32_bf16 v[0:3], v[186:189], v[224:227], v[0:3]
	v_mfma_f32_16x16x32_bf16 v[4:7], v[176:179], v[224:227], v[4:7]
	s_setprio 0
	s_barrier
	s_add_i32 s3, 0, 0x18000
	v_add_u32_e32 v159, s3, v131
	s_add_i32 s33, 0, 0x1c000
	ds_read_b128 v[148:151], v159
	ds_read_b128 v[160:163], v159 offset:1024
	ds_read_b128 v[164:167], v159 offset:2048
	ds_read_b128 v[168:171], v159 offset:3072
	v_add_u32_e32 v159, s33, v131
	ds_read_b128 v[172:175], v159
	ds_read_b128 v[176:179], v159 offset:1024
	ds_read_b128 v[182:185], v159 offset:2048
	ds_read_b128 v[186:189], v159 offset:3072
	s_add_u32 s14, s64, 0x40000
	s_addc_u32 s15, s65, 0
	s_mov_b32 m0, s66
	v_lshl_add_u64 v[234:235], s[14:15], 0, v[132:133]
	ds_read_b128 v[190:193], v157 offset:32768
	ds_read_b128 v[194:197], v157 offset:33792
	ds_read_b128 v[198:201], v157 offset:34816
	ds_read_b128 v[208:211], v157 offset:35840
	ds_read_b128 v[212:215], v157 offset:36864
	ds_read_b128 v[216:219], v157 offset:37888
	ds_read_b128 v[220:223], v157 offset:38912
	ds_read_b128 v[224:227], v157 offset:39936
	global_load_lds_dwordx4 v[234:235], off
	v_lshl_add_u64 v[234:235], s[14:15], 0, v[136:137]
	s_mov_b32 m0, s67
	s_nop 0
	global_load_lds_dwordx4 v[234:235], off
	s_waitcnt vmcnt(8)
	s_waitcnt lgkmcnt(0)
	s_barrier
	s_setprio 1
	s_waitcnt lgkmcnt(0)
	v_mfma_f32_16x16x32_bf16 v[124:127], v[148:151], v[190:193], v[124:127]
	v_mfma_f32_16x16x32_bf16 v[120:123], v[164:167], v[190:193], v[120:123]
	v_mfma_f32_16x16x32_bf16 v[104:107], v[164:167], v[198:201], v[104:107]
	v_mfma_f32_16x16x32_bf16 v[108:111], v[148:151], v[198:201], v[108:111]
	v_mfma_f32_16x16x32_bf16 v[92:95], v[148:151], v[212:215], v[92:95]
	v_mfma_f32_16x16x32_bf16 v[88:91], v[164:167], v[212:215], v[88:91]
	v_mfma_f32_16x16x32_bf16 v[72:75], v[164:167], v[220:223], v[72:75]
	v_mfma_f32_16x16x32_bf16 v[76:79], v[148:151], v[220:223], v[76:79]
	v_mfma_f32_16x16x32_bf16 v[124:127], v[160:163], v[194:197], v[124:127]
	v_mfma_f32_16x16x32_bf16 v[120:123], v[168:171], v[194:197], v[120:123]
	v_mfma_f32_16x16x32_bf16 v[104:107], v[168:171], v[208:211], v[104:107]
	v_mfma_f32_16x16x32_bf16 v[108:111], v[160:163], v[208:211], v[108:111]
	v_mfma_f32_16x16x32_bf16 v[92:95], v[160:163], v[216:219], v[92:95]
	v_mfma_f32_16x16x32_bf16 v[88:91], v[168:171], v[216:219], v[88:91]
	v_mfma_f32_16x16x32_bf16 v[72:75], v[168:171], v[224:227], v[72:75]
	v_mfma_f32_16x16x32_bf16 v[76:79], v[160:163], v[224:227], v[76:79]
	s_setprio 0
	s_setprio 1
	v_mfma_f32_16x16x32_bf16 v[116:119], v[172:175], v[190:193], v[116:119]
	v_mfma_f32_16x16x32_bf16 v[112:115], v[182:185], v[190:193], v[112:115]
	v_mfma_f32_16x16x32_bf16 v[96:99], v[182:185], v[198:201], v[96:99]
	v_mfma_f32_16x16x32_bf16 v[100:103], v[172:175], v[198:201], v[100:103]
	v_mfma_f32_16x16x32_bf16 v[84:87], v[172:175], v[212:215], v[84:87]
	v_mfma_f32_16x16x32_bf16 v[80:83], v[182:185], v[212:215], v[80:83]
	v_mfma_f32_16x16x32_bf16 v[64:67], v[182:185], v[220:223], v[64:67]
	v_mfma_f32_16x16x32_bf16 v[68:71], v[172:175], v[220:223], v[68:71]
	v_mfma_f32_16x16x32_bf16 v[116:119], v[176:179], v[194:197], v[116:119]
	v_mfma_f32_16x16x32_bf16 v[112:115], v[186:189], v[194:197], v[112:115]
	v_mfma_f32_16x16x32_bf16 v[96:99], v[186:189], v[208:211], v[96:99]
	v_mfma_f32_16x16x32_bf16 v[100:103], v[176:179], v[208:211], v[100:103]
	v_mfma_f32_16x16x32_bf16 v[84:87], v[176:179], v[216:219], v[84:87]
	v_mfma_f32_16x16x32_bf16 v[80:83], v[186:189], v[216:219], v[80:83]
	v_mfma_f32_16x16x32_bf16 v[64:67], v[186:189], v[224:227], v[64:67]
	v_mfma_f32_16x16x32_bf16 v[68:71], v[176:179], v[224:227], v[68:71]
	s_setprio 0
	s_barrier
; #define PG8_STAGE(bufoff, gbase, voff) do { _Pragma("unroll") for (int _i = 0; _i < 2; ++_i) \
;         __builtin_amdgcn_global_load_lds((const unsigned*)((const char*)(gbase) + (voff)[_i]), (PG8_LAS unsigned*)(lds + (bufoff) + ldsw + _i * 8192), 16, 0, 0); } while (0)
; #define PG8_LDA(dst, b, h) do { _Pragma("unroll") for (int m = 0; m < 4; ++m) _Pragma("unroll") for (int k = 0; k < 2; ++k) dst[m][k] = *(const PG8_LAS bf16x8*)(lds + PG8_SA(b, h) + aoff + m * 2048 + k * 1024); } while (0)
; #define PG8_LDB(dst, b, h) do { _Pragma("unroll") for (int n = 0; n < 2; ++n) _Pragma("unroll") for (int k = 0; k < 2; ++k) dst[n][k] = *(const PG8_LAS bf16x8*)(lds + PG8_SB(b, h) + boff + n * 2048 + k * 1024); } while (0)
; #define PG8_BAR __builtin_amdgcn_s_barrier()
; template <class Epi, class Sched, bool ALIGN_EPI = false, bool SP2 = false>
; __device__ __forceinline__ void gemm_phase(PG8_LAS unsigned char* lds, const Gemm g, const Sched& S, const Epi& E) {
;     ...
;             const bool last = (t == nt - 2);
;             const char* a1 = cA + (size_t)(t + 1) * kstep;
;             const char* a2 = last ? nA : cA + (size_t)(t + 2) * kstep; const char* b2 = last ? nB : cB + (size_t)(t + 2) * kstep;
;             const char* a3 = a2 + kstep; const char* b3 = b2 + kstep;
;             if (last && has_next) S.a_ready(nxt);
;             if constexpr (SP2) {
;             PG8_LDB(B0, 0, 0); PG8_LDB(B1, 0, 1); PG8_SCHED; PG8_LDA(At, 0, 0); PG8_STAGE(PG8_SA(1, 1), a1 + hstep, voffA);
;             PG8_WAIT_V(8); PG8_WAIT_L(0); PG8_BAR; PG8_MMA(0, 0, At, B0); PG8_MMA(0, 1, At, B1); PG8_BAR; PG8_SCHED;
;             PG8_LDA(At, 0, 1); PG8_STAGE(PG8_SB(0, 0), b2, voffB); PG8_STAGE(PG8_SB(0, 1), b2 + hstep, voffB); PG8_STAGE(PG8_SA(0, 0), a2, voffA);
;             PG8_WAIT_V(8); PG8_WAIT_L(0); PG8_BAR; PG8_MMA(1, 0, At, B0); PG8_MMA(1, 1, At, B1); PG8_BAR; PG8_SCHED;
;             PG8_LDB(B0, 1, 0); PG8_LDB(B1, 1, 1); PG8_SCHED; PG8_LDA(At, 1, 0); PG8_STAGE(PG8_SA(0, 1), a2 + hstep, voffA);
;             PG8_WAIT_V(8); PG8_WAIT_L(0); PG8_BAR; PG8_MMA(0, 0, At, B0); PG8_MMA(0, 1, At, B1); PG8_BAR; PG8_SCHED;
;             PG8_LDA(At, 1, 1); PG8_STAGE(PG8_SB(1, 0), b3, voffB); PG8_STAGE(PG8_SB(1, 1), b3 + hstep, voffB); PG8_STAGE(PG8_SA(1, 0), a3, voffA);
;             PG8_WAIT_V(8); PG8_WAIT_L(0); PG8_BAR; PG8_MMA(1, 0, At, B0); PG8_MMA(1, 1, At, B1); PG8_BAR; PG8_SCHED;
	s_add_i32 s3, s3, s34
	v_lshl_add_u64 v[202:203], v[202:203], 0, s[38:39]
	s_mov_b32 m0, s3
	ds_read_b128 v[190:193], v157 offset:49152
	ds_read_b128 v[194:197], v157 offset:50176
	ds_read_b128 v[198:201], v157 offset:51200
	ds_read_b128 v[208:211], v157 offset:52224
	ds_read_b128 v[212:215], v157 offset:53248
	ds_read_b128 v[216:219], v157 offset:54272
	ds_read_b128 v[220:223], v157 offset:55296
	ds_read_b128 v[224:227], v157 offset:56320
	global_load_lds_dwordx4 v[202:203], off
	s_add_i32 m0, s3, 0x2000
	s_add_u32 s14, s62, 0x40080
	v_lshl_add_u64 v[202:203], v[228:229], 0, s[38:39]
	s_addc_u32 s15, s63, 0
	s_add_i32 s3, s33, s34
	global_load_lds_dwordx4 v[202:203], off
	v_lshl_add_u64 v[202:203], s[14:15], 0, v[134:135]
	s_mov_b32 m0, s3
	s_nop 0
	global_load_lds_dwordx4 v[202:203], off
	v_lshl_add_u64 v[202:203], s[14:15], 0, v[138:139]
	s_add_i32 m0, s3, 0x2000
	s_nop 0
	global_load_lds_dwordx4 v[202:203], off
	s_waitcnt vmcnt(6)
	s_waitcnt lgkmcnt(0)
	s_barrier
	s_setprio 1
	s_waitcnt lgkmcnt(0)
	v_mfma_f32_16x16x32_bf16 v[60:63], v[148:151], v[190:193], v[60:63]
	v_mfma_f32_16x16x32_bf16 v[56:59], v[164:167], v[190:193], v[56:59]
	v_mfma_f32_16x16x32_bf16 v[40:43], v[164:167], v[198:201], v[40:43]
	v_mfma_f32_16x16x32_bf16 v[44:47], v[148:151], v[198:201], v[44:47]
	v_mfma_f32_16x16x32_bf16 v[28:31], v[148:151], v[212:215], v[28:31]
	v_mfma_f32_16x16x32_bf16 v[24:27], v[164:167], v[212:215], v[24:27]
	v_mfma_f32_16x16x32_bf16 v[8:11], v[164:167], v[220:223], v[8:11]
	v_mfma_f32_16x16x32_bf16 v[12:15], v[148:151], v[220:223], v[12:15]
	v_mfma_f32_16x16x32_bf16 v[60:63], v[160:163], v[194:197], v[60:63]
	v_mfma_f32_16x16x32_bf16 v[56:59], v[168:171], v[194:197], v[56:59]
	v_mfma_f32_16x16x32_bf16 v[40:43], v[168:171], v[208:211], v[40:43]
	v_mfma_f32_16x16x32_bf16 v[44:47], v[160:163], v[208:211], v[44:47]
	v_mfma_f32_16x16x32_bf16 v[28:31], v[160:163], v[216:219], v[28:31]
	v_mfma_f32_16x16x32_bf16 v[24:27], v[168:171], v[216:219], v[24:27]
	v_lshl_add_u64 v[202:203], v[230:231], 0, s[38:39]
	s_mov_b32 m0, s75
	s_nop 0
	global_load_lds_dwordx4 v[202:203], off
	v_mfma_f32_16x16x32_bf16 v[8:11], v[168:171], v[224:227], v[8:11]
	v_mfma_f32_16x16x32_bf16 v[12:15], v[160:163], v[224:227], v[12:15]
	s_setprio 0
	s_setprio 1
	v_mfma_f32_16x16x32_bf16 v[52:55], v[172:175], v[190:193], v[52:55]
	v_mfma_f32_16x16x32_bf16 v[48:51], v[182:185], v[190:193], v[48:51]
	v_mfma_f32_16x16x32_bf16 v[32:35], v[182:185], v[198:201], v[32:35]
	v_mfma_f32_16x16x32_bf16 v[36:39], v[172:175], v[198:201], v[36:39]
	v_mfma_f32_16x16x32_bf16 v[20:23], v[172:175], v[212:215], v[20:23]
	v_mfma_f32_16x16x32_bf16 v[16:19], v[182:185], v[212:215], v[16:19]
	v_mfma_f32_16x16x32_bf16 v[0:3], v[182:185], v[220:223], v[0:3]
	v_mfma_f32_16x16x32_bf16 v[4:7], v[172:175], v[220:223], v[4:7]
	v_mfma_f32_16x16x32_bf16 v[52:55], v[176:179], v[194:197], v[52:55]
	v_mfma_f32_16x16x32_bf16 v[48:51], v[186:189], v[194:197], v[48:51]
	v_mfma_f32_16x16x32_bf16 v[32:35], v[186:189], v[208:211], v[32:35]
	v_mfma_f32_16x16x32_bf16 v[36:39], v[176:179], v[208:211], v[36:39]
	v_mfma_f32_16x16x32_bf16 v[20:23], v[176:179], v[216:219], v[20:23]
	v_mfma_f32_16x16x32_bf16 v[16:19], v[186:189], v[216:219], v[16:19]
	v_lshl_add_u64 v[202:203], v[232:233], 0, s[38:39]
	s_mov_b32 m0, s84
	s_nop 0
	global_load_lds_dwordx4 v[202:203], off
	v_mfma_f32_16x16x32_bf16 v[0:3], v[186:189], v[224:227], v[0:3]
	v_mfma_f32_16x16x32_bf16 v[4:7], v[176:179], v[224:227], v[4:7]
	s_setprio 0
	s_barrier
	s_add_i32 s92, s92, 2
	s_add_u32 s60, s60, 0x100
	s_addc_u32 s61, s61, 0
	s_add_u32 s90, s90, 0x100
	s_addc_u32 s91, s91, 0
.LBB0_650:
	ds_read_b128 v[148:151], v155
	ds_read_b128 v[160:163], v155 offset:1024
	ds_read_b128 v[164:167], v155 offset:2048
	ds_read_b128 v[168:171], v155 offset:3072
	ds_read_b128 v[172:175], v156
	ds_read_b128 v[176:179], v156 offset:1024
	ds_read_b128 v[182:185], v156 offset:2048
	ds_read_b128 v[186:189], v156 offset:3072
	s_add_u32 s3, s60, 0xfffc0080
	s_addc_u32 s14, s61, -1
	s_cmp_eq_u32 s92, 12
	s_cselect_b32 s65, s51, s14
	s_cselect_b32 s64, s57, s3
	s_cselect_b32 s63, s49, s91
	s_cselect_b32 s62, s89, s90
	v_lshl_add_u64 v[202:203], s[60:61], 0, v[140:141]
	s_add_i32 m0, s43, 0xc000
	ds_read_b128 v[190:193], v157
	ds_read_b128 v[194:197], v157 offset:1024
	ds_read_b128 v[198:201], v157 offset:2048
	ds_read_b128 v[208:211], v157 offset:3072
	ds_read_b128 v[212:215], v157 offset:4096
	ds_read_b128 v[216:219], v157 offset:5120
	ds_read_b128 v[220:223], v157 offset:6144
	ds_read_b128 v[224:227], v157 offset:7168
	global_load_lds_dwordx4 v[202:203], off
	v_lshl_add_u64 v[202:203], s[60:61], 0, v[142:143]
	s_add_i32 m0, s43, 0xe000
	s_nop 0
	global_load_lds_dwordx4 v[202:203], off
	s_waitcnt vmcnt(8)
	s_waitcnt lgkmcnt(0)
	s_barrier
; #define PG8_STAGE(bufoff, gbase, voff) do { _Pragma("unroll") for (int _i = 0; _i < 2; ++_i) \
;         __builtin_amdgcn_global_load_lds((const unsigned*)((const char*)(gbase) + (voff)[_i]), (PG8_LAS unsigned*)(lds + (bufoff) + ldsw + _i * 8192), 16, 0, 0); } while (0)
; #define PG8_LDA(dst, b, h) do { _Pragma("unroll") for (int m = 0; m < 4; ++m) _Pragma("unroll") for (int k = 0; k < 2; ++k) dst[m][k] = *(const PG8_LAS bf16x8*)(lds + PG8_SA(b, h) + aoff + m * 2048 + k * 1024); } while (0)
; #define PG8_MMA(ai, bj, At, Bt) do { __builtin_amdgcn_s_setprio(1); _Pragma("unroll") for (int m = 0; m < 4; ++m) _Pragma("unroll") for (int n = 0; n < 2; ++n) _Pragma("unroll") for (int k = 0; k < 2; ++k) \
;         acc[ai][bj][m][n] = __builtin_amdgcn_mfma_f32_16x16x32_bf16(Bt[n][k], At[m][k], acc[ai][bj][m][n], 0, 0, 0); __builtin_amdgcn_s_setprio(0); } while (0)
; #define PG8_WAIT_V(n) asm volatile("s_waitcnt vmcnt(" #n ")" ::: "memory")
; #define PG8_WAIT_L(n) asm volatile("s_waitcnt lgkmcnt(" #n ")" ::: "memory")
; #define PG8_BAR __builtin_amdgcn_s_barrier()
; #define PG8_SCHED __builtin_amdgcn_sched_barrier(0)
; template <class Epi, class Sched, bool ALIGN_EPI = false, bool SP2 = false>
; __device__ __forceinline__ void gemm_phase(PG8_LAS unsigned char* lds, const Gemm g, const Sched& S, const Epi& E) {
;     ...
;             PG8_WAIT_V(8); PG8_WAIT_L(0); PG8_BAR; PG8_MMA(0, 0, At, B0); PG8_MMA(0, 1, At, B1); PG8_BAR; PG8_SCHED;
;             PG8_LDA(At, 0, 1); PG8_STAGE(PG8_SB(0, 0), b2, voffB); PG8_STAGE(PG8_SB(0, 1), b2 + hstep, voffB); PG8_STAGE(PG8_SA(0, 0), a2, voffA);
;             PG8_WAIT_V(8); PG8_WAIT_L(0); PG8_BAR; PG8_MMA(1, 0, At, B0); PG8_MMA(1, 1, At, B1); PG8_BAR; PG8_SCHED;
	s_setprio 1
	s_waitcnt lgkmcnt(0)
	v_mfma_f32_16x16x32_bf16 v[124:127], v[148:151], v[190:193], v[124:127]
	v_mfma_f32_16x16x32_bf16 v[120:123], v[164:167], v[190:193], v[120:123]
	v_mfma_f32_16x16x32_bf16 v[104:107], v[164:167], v[198:201], v[104:107]
	v_mfma_f32_16x16x32_bf16 v[108:111], v[148:151], v[198:201], v[108:111]
	v_mfma_f32_16x16x32_bf16 v[92:95], v[148:151], v[212:215], v[92:95]
	v_mfma_f32_16x16x32_bf16 v[88:91], v[164:167], v[212:215], v[88:91]
	v_mfma_f32_16x16x32_bf16 v[72:75], v[164:167], v[220:223], v[72:75]
	v_mfma_f32_16x16x32_bf16 v[76:79], v[148:151], v[220:223], v[76:79]
	v_mfma_f32_16x16x32_bf16 v[124:127], v[160:163], v[194:197], v[124:127]
	v_mfma_f32_16x16x32_bf16 v[120:123], v[168:171], v[194:197], v[120:123]
	v_mfma_f32_16x16x32_bf16 v[104:107], v[168:171], v[208:211], v[104:107]
	v_mfma_f32_16x16x32_bf16 v[108:111], v[160:163], v[208:211], v[108:111]
	v_mfma_f32_16x16x32_bf16 v[92:95], v[160:163], v[216:219], v[92:95]
	v_mfma_f32_16x16x32_bf16 v[88:91], v[168:171], v[216:219], v[88:91]
	v_mfma_f32_16x16x32_bf16 v[72:75], v[168:171], v[224:227], v[72:75]
	v_mfma_f32_16x16x32_bf16 v[76:79], v[160:163], v[224:227], v[76:79]
	s_setprio 0
	s_setprio 1
	v_mfma_f32_16x16x32_bf16 v[116:119], v[172:175], v[190:193], v[116:119]
	v_mfma_f32_16x16x32_bf16 v[112:115], v[182:185], v[190:193], v[112:115]
	v_mfma_f32_16x16x32_bf16 v[96:99], v[182:185], v[198:201], v[96:99]
	v_mfma_f32_16x16x32_bf16 v[100:103], v[172:175], v[198:201], v[100:103]
	v_mfma_f32_16x16x32_bf16 v[84:87], v[172:175], v[212:215], v[84:87]
	v_mfma_f32_16x16x32_bf16 v[80:83], v[182:185], v[212:215], v[80:83]
	v_mfma_f32_16x16x32_bf16 v[64:67], v[182:185], v[220:223], v[64:67]
	v_mfma_f32_16x16x32_bf16 v[68:71], v[172:175], v[220:223], v[68:71]
	v_mfma_f32_16x16x32_bf16 v[116:119], v[176:179], v[194:197], v[116:119]
	v_mfma_f32_16x16x32_bf16 v[112:115], v[186:189], v[194:197], v[112:115]
	v_mfma_f32_16x16x32_bf16 v[96:99], v[186:189], v[208:211], v[96:99]
	v_mfma_f32_16x16x32_bf16 v[100:103], v[176:179], v[208:211], v[100:103]
	v_mfma_f32_16x16x32_bf16 v[84:87], v[176:179], v[216:219], v[84:87]
	v_mfma_f32_16x16x32_bf16 v[80:83], v[186:189], v[216:219], v[80:83]
	v_mfma_f32_16x16x32_bf16 v[64:67], v[186:189], v[224:227], v[64:67]
	v_mfma_f32_16x16x32_bf16 v[68:71], v[176:179], v[224:227], v[68:71]
	s_setprio 0
	s_barrier
	s_add_i32 s3, s85, s34
	v_lshl_add_u64 v[202:203], s[62:63], 0, v[134:135]
	s_mov_b32 m0, s3
	ds_read_b128 v[190:193], v157 offset:16384
	ds_read_b128 v[194:197], v157 offset:17408
	ds_read_b128 v[198:201], v157 offset:18432
	ds_read_b128 v[208:211], v157 offset:19456
	ds_read_b128 v[212:215], v157 offset:20480
	ds_read_b128 v[216:219], v157 offset:21504
	ds_read_b128 v[220:223], v157 offset:22528
	ds_read_b128 v[224:227], v157 offset:23552
	global_load_lds_dwordx4 v[202:203], off
	s_add_i32 m0, s3, 0x2000
	s_add_u32 s14, s62, 0x40000
	v_lshl_add_u64 v[228:229], s[62:63], 0, v[138:139]
	s_addc_u32 s15, s63, 0
	s_add_i32 s3, s86, s34
	global_load_lds_dwordx4 v[228:229], off
	v_lshl_add_u64 v[230:231], s[14:15], 0, v[134:135]
	s_mov_b32 m0, s3
	global_load_lds_dwordx4 v[230:231], off
	v_lshl_add_u64 v[230:231], s[14:15], 0, v[138:139]
	s_add_i32 m0, s3, 0x2000
	s_nop 0
	global_load_lds_dwordx4 v[230:231], off
	s_waitcnt vmcnt(6)
	s_waitcnt lgkmcnt(0)
	s_barrier
	s_setprio 1
	s_waitcnt lgkmcnt(0)
	v_mfma_f32_16x16x32_bf16 v[60:63], v[148:151], v[190:193], v[60:63]
	v_mfma_f32_16x16x32_bf16 v[56:59], v[164:167], v[190:193], v[56:59]
	v_mfma_f32_16x16x32_bf16 v[40:43], v[164:167], v[198:201], v[40:43]
	v_mfma_f32_16x16x32_bf16 v[44:47], v[148:151], v[198:201], v[44:47]
	v_mfma_f32_16x16x32_bf16 v[28:31], v[148:151], v[212:215], v[28:31]
	v_mfma_f32_16x16x32_bf16 v[24:27], v[164:167], v[212:215], v[24:27]
	v_mfma_f32_16x16x32_bf16 v[8:11], v[164:167], v[220:223], v[8:11]
	v_mfma_f32_16x16x32_bf16 v[12:15], v[148:151], v[220:223], v[12:15]
	v_mfma_f32_16x16x32_bf16 v[60:63], v[160:163], v[194:197], v[60:63]
	v_mfma_f32_16x16x32_bf16 v[56:59], v[168:171], v[194:197], v[56:59]
	v_mfma_f32_16x16x32_bf16 v[40:43], v[168:171], v[208:211], v[40:43]
	v_mfma_f32_16x16x32_bf16 v[44:47], v[160:163], v[208:211], v[44:47]
	v_mfma_f32_16x16x32_bf16 v[28:31], v[160:163], v[216:219], v[28:31]
	v_mfma_f32_16x16x32_bf16 v[24:27], v[168:171], v[216:219], v[24:27]
	v_lshl_add_u64 v[230:231], s[64:65], 0, v[132:133]
	s_mov_b32 m0, s43
	s_nop 0
	global_load_lds_dwordx4 v[230:231], off
	v_mfma_f32_16x16x32_bf16 v[8:11], v[168:171], v[224:227], v[8:11]
	v_mfma_f32_16x16x32_bf16 v[12:15], v[160:163], v[224:227], v[12:15]
	s_setprio 0
	s_setprio 1
	v_mfma_f32_16x16x32_bf16 v[52:55], v[172:175], v[190:193], v[52:55]
	v_mfma_f32_16x16x32_bf16 v[48:51], v[182:185], v[190:193], v[48:51]
	v_mfma_f32_16x16x32_bf16 v[32:35], v[182:185], v[198:201], v[32:35]
	v_mfma_f32_16x16x32_bf16 v[36:39], v[172:175], v[198:201], v[36:39]
	v_mfma_f32_16x16x32_bf16 v[20:23], v[172:175], v[212:215], v[20:23]
	v_mfma_f32_16x16x32_bf16 v[16:19], v[182:185], v[212:215], v[16:19]
	v_mfma_f32_16x16x32_bf16 v[0:3], v[182:185], v[220:223], v[0:3]
	v_mfma_f32_16x16x32_bf16 v[4:7], v[172:175], v[220:223], v[4:7]
	v_mfma_f32_16x16x32_bf16 v[52:55], v[176:179], v[194:197], v[52:55]
	v_mfma_f32_16x16x32_bf16 v[48:51], v[186:189], v[194:197], v[48:51]
	v_mfma_f32_16x16x32_bf16 v[32:35], v[186:189], v[208:211], v[32:35]
	v_mfma_f32_16x16x32_bf16 v[36:39], v[176:179], v[208:211], v[36:39]
	v_mfma_f32_16x16x32_bf16 v[20:23], v[176:179], v[216:219], v[20:23]
	v_mfma_f32_16x16x32_bf16 v[16:19], v[186:189], v[216:219], v[16:19]
	v_lshl_add_u64 v[232:233], s[64:65], 0, v[136:137]
	s_mov_b32 m0, s59
	s_nop 0
	global_load_lds_dwordx4 v[232:233], off
	v_mfma_f32_16x16x32_bf16 v[0:3], v[186:189], v[224:227], v[0:3]
	v_mfma_f32_16x16x32_bf16 v[4:7], v[176:179], v[224:227], v[4:7]
	s_setprio 0
	s_barrier
; #define PG8_STAGE(bufoff, gbase, voff) do { _Pragma("unroll") for (int _i = 0; _i < 2; ++_i) \
;         __builtin_amdgcn_global_load_lds((const unsigned*)((const char*)(gbase) + (voff)[_i]), (PG8_LAS unsigned*)(lds + (bufoff) + ldsw + _i * 8192), 16, 0, 0); } while (0)
; #define PG8_LDA(dst, b, h) do { _Pragma("unroll") for (int m = 0; m < 4; ++m) _Pragma("unroll") for (int k = 0; k < 2; ++k) dst[m][k] = *(const PG8_LAS bf16x8*)(lds + PG8_SA(b, h) + aoff + m * 2048 + k * 1024); } while (0)
; #define PG8_LDB(dst, b, h) do { _Pragma("unroll") for (int n = 0; n < 2; ++n) _Pragma("unroll") for (int k = 0; k < 2; ++k) dst[n][k] = *(const PG8_LAS bf16x8*)(lds + PG8_SB(b, h) + boff + n * 2048 + k * 1024); } while (0)
; #define PG8_MMA(ai, bj, At, Bt) do { __builtin_amdgcn_s_setprio(1); _Pragma("unroll") for (int m = 0; m < 4; ++m) _Pragma("unroll") for (int n = 0; n < 2; ++n) _Pragma("unroll") for (int k = 0; k < 2; ++k) \
;         acc[ai][bj][m][n] = __builtin_amdgcn_mfma_f32_16x16x32_bf16(Bt[n][k], At[m][k], acc[ai][bj][m][n], 0, 0, 0); __builtin_amdgcn_s_setprio(0); } while (0)
; #define PG8_WAIT_V(n) asm volatile("s_waitcnt vmcnt(" #n ")" ::: "memory")
; #define PG8_WAIT_L(n) asm volatile("s_waitcnt lgkmcnt(" #n ")" ::: "memory")
; #define PG8_BAR __builtin_amdgcn_s_barrier()
; #define PG8_SCHED __builtin_amdgcn_sched_barrier(0)
; template <class Epi, class Sched, bool ALIGN_EPI = false, bool SP2 = false>
; __device__ __forceinline__ void gemm_phase(PG8_LAS unsigned char* lds, const Gemm g, const Sched& S, const Epi& E) {
;     ...
;             PG8_LDB(B0, 1, 0); PG8_LDB(B1, 1, 1); PG8_SCHED; PG8_LDA(At, 1, 0); PG8_STAGE(PG8_SA(0, 1), a2 + hstep, voffA);
;             PG8_WAIT_V(8); PG8_WAIT_L(0); PG8_BAR; PG8_MMA(0, 0, At, B0); PG8_MMA(0, 1, At, B1); PG8_BAR; PG8_SCHED;
	s_add_i32 s3, 0, 0x18000
	v_add_u32_e32 v159, s3, v131
	s_add_i32 s33, 0, 0x1c000
	ds_read_b128 v[148:151], v159
	ds_read_b128 v[160:163], v159 offset:1024
	ds_read_b128 v[164:167], v159 offset:2048
	ds_read_b128 v[168:171], v159 offset:3072
	v_add_u32_e32 v159, s33, v131
	ds_read_b128 v[172:175], v159
	ds_read_b128 v[176:179], v159 offset:1024
	ds_read_b128 v[182:185], v159 offset:2048
	ds_read_b128 v[186:189], v159 offset:3072
	s_add_u32 s14, s64, 0x40000
	s_addc_u32 s15, s65, 0
	s_mov_b32 m0, s66
	v_lshl_add_u64 v[234:235], s[14:15], 0, v[132:133]
	ds_read_b128 v[190:193], v157 offset:32768
	ds_read_b128 v[194:197], v157 offset:33792
	ds_read_b128 v[198:201], v157 offset:34816
	ds_read_b128 v[208:211], v157 offset:35840
	ds_read_b128 v[212:215], v157 offset:36864
	ds_read_b128 v[216:219], v157 offset:37888
	ds_read_b128 v[220:223], v157 offset:38912
	ds_read_b128 v[224:227], v157 offset:39936
	global_load_lds_dwordx4 v[234:235], off
	v_lshl_add_u64 v[234:235], s[14:15], 0, v[136:137]
	s_mov_b32 m0, s67
	s_nop 0
	global_load_lds_dwordx4 v[234:235], off
	s_waitcnt vmcnt(8)
	s_waitcnt lgkmcnt(0)
	s_barrier
	s_setprio 1
	s_waitcnt lgkmcnt(0)
	v_mfma_f32_16x16x32_bf16 v[124:127], v[148:151], v[190:193], v[124:127]
	v_mfma_f32_16x16x32_bf16 v[120:123], v[164:167], v[190:193], v[120:123]
	v_mfma_f32_16x16x32_bf16 v[104:107], v[164:167], v[198:201], v[104:107]
	v_mfma_f32_16x16x32_bf16 v[108:111], v[148:151], v[198:201], v[108:111]
	v_mfma_f32_16x16x32_bf16 v[92:95], v[148:151], v[212:215], v[92:95]
	v_mfma_f32_16x16x32_bf16 v[88:91], v[164:167], v[212:215], v[88:91]
	v_mfma_f32_16x16x32_bf16 v[72:75], v[164:167], v[220:223], v[72:75]
	v_mfma_f32_16x16x32_bf16 v[76:79], v[148:151], v[220:223], v[76:79]
	v_mfma_f32_16x16x32_bf16 v[124:127], v[160:163], v[194:197], v[124:127]
	v_mfma_f32_16x16x32_bf16 v[120:123], v[168:171], v[194:197], v[120:123]
	v_mfma_f32_16x16x32_bf16 v[104:107], v[168:171], v[208:211], v[104:107]
	v_mfma_f32_16x16x32_bf16 v[108:111], v[160:163], v[208:211], v[108:111]
	v_mfma_f32_16x16x32_bf16 v[92:95], v[160:163], v[216:219], v[92:95]
	v_mfma_f32_16x16x32_bf16 v[88:91], v[168:171], v[216:219], v[88:91]
	v_mfma_f32_16x16x32_bf16 v[72:75], v[168:171], v[224:227], v[72:75]
	v_mfma_f32_16x16x32_bf16 v[76:79], v[160:163], v[224:227], v[76:79]
	s_setprio 0
	s_setprio 1
	v_mfma_f32_16x16x32_bf16 v[116:119], v[172:175], v[190:193], v[116:119]
	v_mfma_f32_16x16x32_bf16 v[112:115], v[182:185], v[190:193], v[112:115]
	v_mfma_f32_16x16x32_bf16 v[96:99], v[182:185], v[198:201], v[96:99]
	v_mfma_f32_16x16x32_bf16 v[100:103], v[172:175], v[198:201], v[100:103]
	v_mfma_f32_16x16x32_bf16 v[84:87], v[172:175], v[212:215], v[84:87]
	v_mfma_f32_16x16x32_bf16 v[80:83], v[182:185], v[212:215], v[80:83]
	v_mfma_f32_16x16x32_bf16 v[64:67], v[182:185], v[220:223], v[64:67]
	v_mfma_f32_16x16x32_bf16 v[68:71], v[172:175], v[220:223], v[68:71]
	v_mfma_f32_16x16x32_bf16 v[116:119], v[176:179], v[194:197], v[116:119]
	v_mfma_f32_16x16x32_bf16 v[112:115], v[186:189], v[194:197], v[112:115]
	v_mfma_f32_16x16x32_bf16 v[96:99], v[186:189], v[208:211], v[96:99]
	v_mfma_f32_16x16x32_bf16 v[100:103], v[176:179], v[208:211], v[100:103]
	v_mfma_f32_16x16x32_bf16 v[84:87], v[176:179], v[216:219], v[84:87]
	v_mfma_f32_16x16x32_bf16 v[80:83], v[186:189], v[216:219], v[80:83]
	v_mfma_f32_16x16x32_bf16 v[64:67], v[186:189], v[224:227], v[64:67]
	v_mfma_f32_16x16x32_bf16 v[68:71], v[176:179], v[224:227], v[68:71]
	s_setprio 0
	s_barrier
; #define PG8_STAGE(bufoff, gbase, voff) do { _Pragma("unroll") for (int _i = 0; _i < 2; ++_i) \
;         __builtin_amdgcn_global_load_lds((const unsigned*)((const char*)(gbase) + (voff)[_i]), (PG8_LAS unsigned*)(lds + (bufoff) + ldsw + _i * 8192), 16, 0, 0); } while (0)
; #define PG8_LDA(dst, b, h) do { _Pragma("unroll") for (int m = 0; m < 4; ++m) _Pragma("unroll") for (int k = 0; k < 2; ++k) dst[m][k] = *(const PG8_LAS bf16x8*)(lds + PG8_SA(b, h) + aoff + m * 2048 + k * 1024); } while (0)
; #define PG8_MMA(ai, bj, At, Bt) do { __builtin_amdgcn_s_setprio(1); _Pragma("unroll") for (int m = 0; m < 4; ++m) _Pragma("unroll") for (int n = 0; n < 2; ++n) _Pragma("unroll") for (int k = 0; k < 2; ++k) \
;         acc[ai][bj][m][n] = __builtin_amdgcn_mfma_f32_16x16x32_bf16(Bt[n][k], At[m][k], acc[ai][bj][m][n], 0, 0, 0); __builtin_amdgcn_s_setprio(0); } while (0)
; #define PG8_WAIT_V(n) asm volatile("s_waitcnt vmcnt(" #n ")" ::: "memory")
; #define PG8_WAIT_L(n) asm volatile("s_waitcnt lgkmcnt(" #n ")" ::: "memory")
; #define PG8_BAR __builtin_amdgcn_s_barrier()
; #define PG8_SCHED __builtin_amdgcn_sched_barrier(0)
; template <class Epi, class Sched, bool ALIGN_EPI = false, bool SP2 = false>
; __device__ __forceinline__ void gemm_phase(PG8_LAS unsigned char* lds, const Gemm g, const Sched& S, const Epi& E) {
;     ...
;             PG8_LDA(At, 1, 1); PG8_STAGE(PG8_SB(1, 0), b3, voffB); PG8_STAGE(PG8_SB(1, 1), b3 + hstep, voffB); PG8_STAGE(PG8_SA(1, 0), a3, voffA);
;             PG8_WAIT_V(8); PG8_WAIT_L(0); PG8_BAR; PG8_MMA(1, 0, At, B0); PG8_MMA(1, 1, At, B1); PG8_BAR; PG8_SCHED;
;     ...
;         if constexpr (ALIGN_EPI) { if (wr == 0) PG8_BAR; }
	s_add_i32 s3, s3, s34
	v_lshl_add_u64 v[202:203], v[202:203], 0, s[38:39]
	s_mov_b32 m0, s3
	ds_read_b128 v[190:193], v157 offset:49152
	ds_read_b128 v[194:197], v157 offset:50176
	ds_read_b128 v[198:201], v157 offset:51200
	ds_read_b128 v[208:211], v157 offset:52224
	ds_read_b128 v[212:215], v157 offset:53248
	ds_read_b128 v[216:219], v157 offset:54272
	ds_read_b128 v[220:223], v157 offset:55296
	ds_read_b128 v[224:227], v157 offset:56320
	global_load_lds_dwordx4 v[202:203], off
	s_add_i32 m0, s3, 0x2000
	s_add_u32 s14, s62, 0x40080
	v_lshl_add_u64 v[202:203], v[228:229], 0, s[38:39]
	s_addc_u32 s15, s63, 0
	s_add_i32 s3, s33, s34
	global_load_lds_dwordx4 v[202:203], off
	v_lshl_add_u64 v[202:203], s[14:15], 0, v[134:135]
	s_mov_b32 m0, s3
	s_nop 0
	global_load_lds_dwordx4 v[202:203], off
	v_lshl_add_u64 v[202:203], s[14:15], 0, v[138:139]
	s_add_i32 m0, s3, 0x2000
	s_nop 0
	global_load_lds_dwordx4 v[202:203], off
	s_waitcnt vmcnt(6)
	s_waitcnt lgkmcnt(0)
	s_barrier
	s_setprio 1
	s_waitcnt lgkmcnt(0)
	v_mfma_f32_16x16x32_bf16 v[60:63], v[148:151], v[190:193], v[60:63]
	v_mfma_f32_16x16x32_bf16 v[56:59], v[164:167], v[190:193], v[56:59]
	v_mfma_f32_16x16x32_bf16 v[40:43], v[164:167], v[198:201], v[40:43]
	v_mfma_f32_16x16x32_bf16 v[44:47], v[148:151], v[198:201], v[44:47]
	v_mfma_f32_16x16x32_bf16 v[28:31], v[148:151], v[212:215], v[28:31]
	v_mfma_f32_16x16x32_bf16 v[24:27], v[164:167], v[212:215], v[24:27]
	v_mfma_f32_16x16x32_bf16 v[8:11], v[164:167], v[220:223], v[8:11]
	v_mfma_f32_16x16x32_bf16 v[12:15], v[148:151], v[220:223], v[12:15]
	v_mfma_f32_16x16x32_bf16 v[60:63], v[160:163], v[194:197], v[60:63]
	v_mfma_f32_16x16x32_bf16 v[56:59], v[168:171], v[194:197], v[56:59]
	v_mfma_f32_16x16x32_bf16 v[40:43], v[168:171], v[208:211], v[40:43]
	v_mfma_f32_16x16x32_bf16 v[44:47], v[160:163], v[208:211], v[44:47]
	v_mfma_f32_16x16x32_bf16 v[28:31], v[160:163], v[216:219], v[28:31]
	v_mfma_f32_16x16x32_bf16 v[24:27], v[168:171], v[216:219], v[24:27]
	v_lshl_add_u64 v[202:203], v[230:231], 0, s[38:39]
	s_mov_b32 m0, s75
	s_nop 0
	global_load_lds_dwordx4 v[202:203], off
	v_mfma_f32_16x16x32_bf16 v[8:11], v[168:171], v[224:227], v[8:11]
	v_mfma_f32_16x16x32_bf16 v[12:15], v[160:163], v[224:227], v[12:15]
	s_setprio 0
	s_setprio 1
	v_mfma_f32_16x16x32_bf16 v[52:55], v[172:175], v[190:193], v[52:55]
	v_mfma_f32_16x16x32_bf16 v[48:51], v[182:185], v[190:193], v[48:51]
	v_mfma_f32_16x16x32_bf16 v[32:35], v[182:185], v[198:201], v[32:35]
	v_mfma_f32_16x16x32_bf16 v[36:39], v[172:175], v[198:201], v[36:39]
	v_mfma_f32_16x16x32_bf16 v[20:23], v[172:175], v[212:215], v[20:23]
	v_mfma_f32_16x16x32_bf16 v[16:19], v[182:185], v[212:215], v[16:19]
	v_mfma_f32_16x16x32_bf16 v[0:3], v[182:185], v[220:223], v[0:3]
	v_mfma_f32_16x16x32_bf16 v[4:7], v[172:175], v[220:223], v[4:7]
	v_mfma_f32_16x16x32_bf16 v[52:55], v[176:179], v[194:197], v[52:55]
	v_mfma_f32_16x16x32_bf16 v[48:51], v[186:189], v[194:197], v[48:51]
	v_mfma_f32_16x16x32_bf16 v[32:35], v[186:189], v[208:211], v[32:35]
	v_mfma_f32_16x16x32_bf16 v[36:39], v[176:179], v[208:211], v[36:39]
	v_mfma_f32_16x16x32_bf16 v[20:23], v[176:179], v[216:219], v[20:23]
	v_mfma_f32_16x16x32_bf16 v[16:19], v[186:189], v[216:219], v[16:19]
	v_lshl_add_u64 v[202:203], v[232:233], 0, s[38:39]
	s_mov_b32 m0, s84
	s_nop 0
	global_load_lds_dwordx4 v[202:203], off
	v_mfma_f32_16x16x32_bf16 v[0:3], v[186:189], v[224:227], v[0:3]
	v_mfma_f32_16x16x32_bf16 v[4:7], v[176:179], v[224:227], v[4:7]
	s_setprio 0
	s_barrier
	s_add_i32 s92, s92, 2
	s_add_u32 s60, s60, 0x100
	s_addc_u32 s61, s61, 0
	s_add_u32 s90, s90, 0x100
	s_addc_u32 s91, s91, 0
	s_cmp_gt_u32 s92, 13
	s_cbranch_scc0 .LBB0_650
	s_and_b64 vcc, exec, s[44:45]
	s_cbranch_vccz .LBB0_653
	s_barrier

; #define PG8_STAGE(bufoff, gbase, voff) do { _Pragma("unroll") for (int _i = 0; _i < 2; ++_i) \
;         __builtin_amdgcn_global_load_lds((const unsigned*)((const char*)(gbase) + (voff)[_i]), (PG8_LAS unsigned*)(lds + (bufoff) + ldsw + _i * 8192), 16, 0, 0); } while (0)
; #define PG8_LDA(dst, b, h) do { _Pragma("unroll") for (int m = 0; m < 4; ++m) _Pragma("unroll") for (int k = 0; k < 2; ++k) dst[m][k] = *(const PG8_LAS bf16x8*)(lds + PG8_SA(b, h) + aoff + m * 2048 + k * 1024); } while (0)
; #define PG8_LDB(dst, b, h) do { _Pragma("unroll") for (int n = 0; n < 2; ++n) _Pragma("unroll") for (int k = 0; k < 2; ++k) dst[n][k] = *(const PG8_LAS bf16x8*)(lds + PG8_SB(b, h) + boff + n * 2048 + k * 1024); } while (0)
; #define PG8_MMA(ai, bj, At, Bt) do { __builtin_amdgcn_s_setprio(1); _Pragma("unroll") for (int m = 0; m < 4; ++m) _Pragma("unroll") for (int n = 0; n < 2; ++n) _Pragma("unroll") for (int k = 0; k < 2; ++k) \
;         acc[ai][bj][m][n] = __builtin_amdgcn_mfma_f32_16x16x32_bf16(Bt[n][k], At[m][k], acc[ai][bj][m][n], 0, 0, 0); __builtin_amdgcn_s_setprio(0); } while (0)
; #define PG8_BAR __builtin_amdgcn_s_barrier()
; template <class Epi, class Sched, bool ALIGN_EPI = false, bool SP2 = false>
; __device__ __forceinline__ void gemm_phase(PG8_LAS unsigned char* lds, const Gemm g, const Sched& S, const Epi& E) {
;     ...
;         const bool has_next = S.next(ui + 1, nxt);
;         const char* nA = has_next ? (const char*)g.A + (size_t)nxt.pm * tstep : cA; const char* nB = has_next ? (const char*)g.Bt + (size_t)nxt.pn * tstep : cB;
;         for (int t = 0; t < nt; t += 2) {
;             const bool last = (t == nt - 2);
;             const char* a1 = cA + (size_t)(t + 1) * kstep;
;             const char* a2 = last ? nA : cA + (size_t)(t + 2) * kstep; const char* b2 = last ? nB : cB + (size_t)(t + 2) * kstep;
;             const char* a3 = a2 + kstep; const char* b3 = b2 + kstep;
;             if (last && has_next) S.a_ready(nxt);
;             if constexpr (SP2) {
;             PG8_LDB(B0, 0, 0); PG8_LDB(B1, 0, 1); PG8_SCHED; PG8_LDA(At, 0, 0); PG8_STAGE(PG8_SA(1, 1), a1 + hstep, voffA);
;             PG8_WAIT_V(8); PG8_WAIT_L(0); PG8_BAR; PG8_MMA(0, 0, At, B0); PG8_MMA(0, 1, At, B1); PG8_BAR; PG8_SCHED;
;             PG8_LDA(At, 0, 1); PG8_STAGE(PG8_SB(0, 0), b2, voffB); PG8_STAGE(PG8_SB(0, 1), b2 + hstep, voffB); PG8_STAGE(PG8_SA(0, 0), a2, voffA);
.LBB0_737:
	s_ashr_i32 s51, s50, 31
	s_lshl_b64 s[14:15], s[50:51], 19
	s_add_u32 s52, s22, s14
	s_addc_u32 s53, s23, s15
	s_and_b64 s[14:15], s[8:9], exec
	s_cselect_b32 s51, s53, s57
	s_cselect_b32 s82, s52, s56
	s_ashr_i32 s49, s48, 31
	s_lshl_b64 s[14:15], s[48:49], 19
	v_readlane_b32 s3, v250, 15
	s_add_u32 s54, s3, s14
	v_readlane_b32 s3, v250, 16
	s_addc_u32 s55, s3, s15
	s_and_b64 s[14:15], s[8:9], exec
	s_cselect_b32 s49, s55, s59
	s_cselect_b32 s83, s54, s58
	s_add_u32 s56, s56, 0x40080
	s_addc_u32 s57, s57, 0
	s_add_u32 s84, s58, 0x100
	s_addc_u32 s85, s59, 0
	s_mov_b32 s86, -2
	s_waitcnt vmcnt(0)
	ds_read_b128 v[148:151], v155
	ds_read_b128 v[160:163], v155 offset:1024
	ds_read_b128 v[164:167], v155 offset:2048
	ds_read_b128 v[168:171], v155 offset:3072
	ds_read_b128 v[172:175], v156
	ds_read_b128 v[176:179], v156 offset:1024
	ds_read_b128 v[182:185], v156 offset:2048
	ds_read_b128 v[186:189], v156 offset:3072
	s_add_u32 s3, s56, 0xfffc0080
	s_addc_u32 s14, s57, -1
	s_cmp_eq_u32 s86, 12
	s_cselect_b32 s61, s51, s14
	s_cselect_b32 s60, s82, s3
	s_cselect_b32 s59, s49, s85
	s_cselect_b32 s58, s83, s84
	v_lshl_add_u64 v[202:203], s[56:57], 0, v[140:141]
	s_add_i32 m0, s43, 0xc000
	ds_read_b128 v[190:193], v157
	ds_read_b128 v[194:197], v157 offset:1024
	ds_read_b128 v[198:201], v157 offset:2048
	ds_read_b128 v[208:211], v157 offset:3072
	ds_read_b128 v[212:215], v157 offset:4096
	ds_read_b128 v[216:219], v157 offset:5120
	ds_read_b128 v[220:223], v157 offset:6144
	ds_read_b128 v[224:227], v157 offset:7168
	global_load_lds_dwordx4 v[202:203], off
	v_lshl_add_u64 v[202:203], s[56:57], 0, v[142:143]
	s_add_i32 m0, s43, 0xe000
	s_nop 0
	global_load_lds_dwordx4 v[202:203], off
	s_waitcnt vmcnt(8)
	s_waitcnt lgkmcnt(0)
	s_barrier
	s_setprio 1
	s_waitcnt lgkmcnt(0)
	v_mfma_f32_16x16x32_bf16 v[124:127], v[148:151], v[190:193], 0
	v_mfma_f32_16x16x32_bf16 v[120:123], v[164:167], v[190:193], 0
	v_mfma_f32_16x16x32_bf16 v[104:107], v[164:167], v[198:201], 0
	v_mfma_f32_16x16x32_bf16 v[108:111], v[148:151], v[198:201], 0
	v_mfma_f32_16x16x32_bf16 v[92:95], v[148:151], v[212:215], 0
	v_mfma_f32_16x16x32_bf16 v[88:91], v[164:167], v[212:215], 0
	v_mfma_f32_16x16x32_bf16 v[72:75], v[164:167], v[220:223], 0
	v_mfma_f32_16x16x32_bf16 v[76:79], v[148:151], v[220:223], 0
	v_mfma_f32_16x16x32_bf16 v[124:127], v[160:163], v[194:197], v[124:127]
	v_mfma_f32_16x16x32_bf16 v[120:123], v[168:171], v[194:197], v[120:123]
	v_mfma_f32_16x16x32_bf16 v[104:107], v[168:171], v[208:211], v[104:107]
	v_mfma_f32_16x16x32_bf16 v[108:111], v[160:163], v[208:211], v[108:111]
	v_mfma_f32_16x16x32_bf16 v[92:95], v[160:163], v[216:219], v[92:95]
	v_mfma_f32_16x16x32_bf16 v[88:91], v[168:171], v[216:219], v[88:91]
	v_mfma_f32_16x16x32_bf16 v[72:75], v[168:171], v[224:227], v[72:75]
	v_mfma_f32_16x16x32_bf16 v[76:79], v[160:163], v[224:227], v[76:79]
	s_setprio 0
	s_setprio 1
	v_mfma_f32_16x16x32_bf16 v[116:119], v[172:175], v[190:193], 0
	v_mfma_f32_16x16x32_bf16 v[112:115], v[182:185], v[190:193], 0
	v_mfma_f32_16x16x32_bf16 v[96:99], v[182:185], v[198:201], 0
	v_mfma_f32_16x16x32_bf16 v[100:103], v[172:175], v[198:201], 0
	v_mfma_f32_16x16x32_bf16 v[84:87], v[172:175], v[212:215], 0
	v_mfma_f32_16x16x32_bf16 v[80:83], v[182:185], v[212:215], 0
	v_mfma_f32_16x16x32_bf16 v[64:67], v[182:185], v[220:223], 0
	v_mfma_f32_16x16x32_bf16 v[68:71], v[172:175], v[220:223], 0
	v_mfma_f32_16x16x32_bf16 v[116:119], v[176:179], v[194:197], v[116:119]
	v_mfma_f32_16x16x32_bf16 v[112:115], v[186:189], v[194:197], v[112:115]
	v_mfma_f32_16x16x32_bf16 v[96:99], v[186:189], v[208:211], v[96:99]
	v_mfma_f32_16x16x32_bf16 v[100:103], v[176:179], v[208:211], v[100:103]
	v_mfma_f32_16x16x32_bf16 v[84:87], v[176:179], v[216:219], v[84:87]
	v_mfma_f32_16x16x32_bf16 v[80:83], v[186:189], v[216:219], v[80:83]
	v_mfma_f32_16x16x32_bf16 v[64:67], v[186:189], v[224:227], v[64:67]
	v_mfma_f32_16x16x32_bf16 v[68:71], v[176:179], v[224:227], v[68:71]
	s_setprio 0
	s_barrier
	s_add_i32 s3, s74, s34
	v_lshl_add_u64 v[202:203], s[58:59], 0, v[136:137]
	s_mov_b32 m0, s3
	ds_read_b128 v[190:193], v157 offset:16384
	ds_read_b128 v[194:197], v157 offset:17408
	ds_read_b128 v[198:201], v157 offset:18432
	ds_read_b128 v[208:211], v157 offset:19456
	ds_read_b128 v[212:215], v157 offset:20480
	ds_read_b128 v[216:219], v157 offset:21504
	ds_read_b128 v[220:223], v157 offset:22528
	ds_read_b128 v[224:227], v157 offset:23552
	global_load_lds_dwordx4 v[202:203], off
	s_add_i32 m0, s3, 0x2000
	s_add_u32 s14, s58, 0x40000
	v_lshl_add_u64 v[228:229], s[58:59], 0, v[132:133]
	s_addc_u32 s15, s59, 0
	s_add_i32 s3, s75, s34
	global_load_lds_dwordx4 v[228:229], off
	v_lshl_add_u64 v[230:231], s[14:15], 0, v[136:137]
	s_mov_b32 m0, s3
	global_load_lds_dwordx4 v[230:231], off
	v_lshl_add_u64 v[230:231], s[14:15], 0, v[132:133]
	s_add_i32 m0, s3, 0x2000
	s_nop 0
	global_load_lds_dwordx4 v[230:231], off
	s_waitcnt vmcnt(6)
	s_waitcnt lgkmcnt(0)
	s_barrier
; #define PG8_STAGE(bufoff, gbase, voff) do { _Pragma("unroll") for (int _i = 0; _i < 2; ++_i) \
;         __builtin_amdgcn_global_load_lds((const unsigned*)((const char*)(gbase) + (voff)[_i]), (PG8_LAS unsigned*)(lds + (bufoff) + ldsw + _i * 8192), 16, 0, 0); } while (0)
; #define PG8_LDA(dst, b, h) do { _Pragma("unroll") for (int m = 0; m < 4; ++m) _Pragma("unroll") for (int k = 0; k < 2; ++k) dst[m][k] = *(const PG8_LAS bf16x8*)(lds + PG8_SA(b, h) + aoff + m * 2048 + k * 1024); } while (0)
; #define PG8_LDB(dst, b, h) do { _Pragma("unroll") for (int n = 0; n < 2; ++n) _Pragma("unroll") for (int k = 0; k < 2; ++k) dst[n][k] = *(const PG8_LAS bf16x8*)(lds + PG8_SB(b, h) + boff + n * 2048 + k * 1024); } while (0)
; #define PG8_MMA(ai, bj, At, Bt) do { __builtin_amdgcn_s_setprio(1); _Pragma("unroll") for (int m = 0; m < 4; ++m) _Pragma("unroll") for (int n = 0; n < 2; ++n) _Pragma("unroll") for (int k = 0; k < 2; ++k) \
;         acc[ai][bj][m][n] = __builtin_amdgcn_mfma_f32_16x16x32_bf16(Bt[n][k], At[m][k], acc[ai][bj][m][n], 0, 0, 0); __builtin_amdgcn_s_setprio(0); } while (0)
; #define PG8_WAIT_V(n) asm volatile("s_waitcnt vmcnt(" #n ")" ::: "memory")
; #define PG8_WAIT_L(n) asm volatile("s_waitcnt lgkmcnt(" #n ")" ::: "memory")
; #define PG8_BAR __builtin_amdgcn_s_barrier()
; #define PG8_SCHED __builtin_amdgcn_sched_barrier(0)
; template <class Epi, class Sched, bool ALIGN_EPI = false, bool SP2 = false>
; __device__ __forceinline__ void gemm_phase(PG8_LAS unsigned char* lds, const Gemm g, const Sched& S, const Epi& E) {
;     ...
;             PG8_WAIT_V(8); PG8_WAIT_L(0); PG8_BAR; PG8_MMA(1, 0, At, B0); PG8_MMA(1, 1, At, B1); PG8_BAR; PG8_SCHED;
;             PG8_LDB(B0, 1, 0); PG8_LDB(B1, 1, 1); PG8_SCHED; PG8_LDA(At, 1, 0); PG8_STAGE(PG8_SA(0, 1), a2 + hstep, voffA);
;             PG8_WAIT_V(8); PG8_WAIT_L(0); PG8_BAR; PG8_MMA(0, 0, At, B0); PG8_MMA(0, 1, At, B1); PG8_BAR; PG8_SCHED;
	s_setprio 1
	s_waitcnt lgkmcnt(0)
	v_mfma_f32_16x16x32_bf16 v[60:63], v[148:151], v[190:193], 0
	v_mfma_f32_16x16x32_bf16 v[56:59], v[164:167], v[190:193], 0
	v_mfma_f32_16x16x32_bf16 v[40:43], v[164:167], v[198:201], 0
	v_mfma_f32_16x16x32_bf16 v[44:47], v[148:151], v[198:201], 0
	v_mfma_f32_16x16x32_bf16 v[28:31], v[148:151], v[212:215], 0
	v_mfma_f32_16x16x32_bf16 v[24:27], v[164:167], v[212:215], 0
	v_mfma_f32_16x16x32_bf16 v[8:11], v[164:167], v[220:223], 0
	v_mfma_f32_16x16x32_bf16 v[12:15], v[148:151], v[220:223], 0
	v_mfma_f32_16x16x32_bf16 v[60:63], v[160:163], v[194:197], v[60:63]
	v_mfma_f32_16x16x32_bf16 v[56:59], v[168:171], v[194:197], v[56:59]
	v_mfma_f32_16x16x32_bf16 v[40:43], v[168:171], v[208:211], v[40:43]
	v_mfma_f32_16x16x32_bf16 v[44:47], v[160:163], v[208:211], v[44:47]
	v_mfma_f32_16x16x32_bf16 v[28:31], v[160:163], v[216:219], v[28:31]
	v_mfma_f32_16x16x32_bf16 v[24:27], v[168:171], v[216:219], v[24:27]
	v_lshl_add_u64 v[230:231], s[60:61], 0, v[138:139]
	s_mov_b32 m0, s43
	s_nop 0
	global_load_lds_dwordx4 v[230:231], off
	v_mfma_f32_16x16x32_bf16 v[8:11], v[168:171], v[224:227], v[8:11]
	v_mfma_f32_16x16x32_bf16 v[12:15], v[160:163], v[224:227], v[12:15]
	s_setprio 0
	s_setprio 1
	v_mfma_f32_16x16x32_bf16 v[52:55], v[172:175], v[190:193], 0
	v_mfma_f32_16x16x32_bf16 v[48:51], v[182:185], v[190:193], 0
	v_mfma_f32_16x16x32_bf16 v[32:35], v[182:185], v[198:201], 0
	v_mfma_f32_16x16x32_bf16 v[36:39], v[172:175], v[198:201], 0
	v_mfma_f32_16x16x32_bf16 v[20:23], v[172:175], v[212:215], 0
	v_mfma_f32_16x16x32_bf16 v[16:19], v[182:185], v[212:215], 0
	v_mfma_f32_16x16x32_bf16 v[0:3], v[182:185], v[220:223], 0
	v_mfma_f32_16x16x32_bf16 v[4:7], v[172:175], v[220:223], 0
	v_mfma_f32_16x16x32_bf16 v[52:55], v[176:179], v[194:197], v[52:55]
	v_mfma_f32_16x16x32_bf16 v[48:51], v[186:189], v[194:197], v[48:51]
	v_mfma_f32_16x16x32_bf16 v[32:35], v[186:189], v[208:211], v[32:35]
	v_mfma_f32_16x16x32_bf16 v[36:39], v[176:179], v[208:211], v[36:39]
	v_mfma_f32_16x16x32_bf16 v[20:23], v[176:179], v[216:219], v[20:23]
	v_mfma_f32_16x16x32_bf16 v[16:19], v[186:189], v[216:219], v[16:19]
	v_lshl_add_u64 v[232:233], s[60:61], 0, v[134:135]
	s_mov_b32 m0, s62
	s_nop 0
	global_load_lds_dwordx4 v[232:233], off
	v_mfma_f32_16x16x32_bf16 v[0:3], v[186:189], v[224:227], v[0:3]
	v_mfma_f32_16x16x32_bf16 v[4:7], v[176:179], v[224:227], v[4:7]
	s_setprio 0
	s_barrier
	s_add_i32 s3, 0, 0x18000
	v_add_u32_e32 v159, s3, v131
	s_add_i32 s33, 0, 0x1c000
	ds_read_b128 v[148:151], v159
	ds_read_b128 v[160:163], v159 offset:1024
	ds_read_b128 v[164:167], v159 offset:2048
	ds_read_b128 v[168:171], v159 offset:3072
	v_add_u32_e32 v159, s33, v131
	ds_read_b128 v[172:175], v159
	ds_read_b128 v[176:179], v159 offset:1024
	ds_read_b128 v[182:185], v159 offset:2048
	ds_read_b128 v[186:189], v159 offset:3072
	s_add_u32 s14, s60, 0x40000
	s_addc_u32 s15, s61, 0
	s_mov_b32 m0, s63
	v_lshl_add_u64 v[234:235], s[14:15], 0, v[138:139]
	ds_read_b128 v[190:193], v157 offset:32768
	ds_read_b128 v[194:197], v157 offset:33792
	ds_read_b128 v[198:201], v157 offset:34816
	ds_read_b128 v[208:211], v157 offset:35840
	ds_read_b128 v[212:215], v157 offset:36864
	ds_read_b128 v[216:219], v157 offset:37888
	ds_read_b128 v[220:223], v157 offset:38912
	ds_read_b128 v[224:227], v157 offset:39936
	global_load_lds_dwordx4 v[234:235], off
	v_lshl_add_u64 v[234:235], s[14:15], 0, v[134:135]
	s_mov_b32 m0, s64
	s_nop 0
	global_load_lds_dwordx4 v[234:235], off
	s_waitcnt vmcnt(8)
	s_waitcnt lgkmcnt(0)
	s_barrier
	s_setprio 1
	s_waitcnt lgkmcnt(0)
	v_mfma_f32_16x16x32_bf16 v[124:127], v[148:151], v[190:193], v[124:127]
	v_mfma_f32_16x16x32_bf16 v[120:123], v[164:167], v[190:193], v[120:123]
	v_mfma_f32_16x16x32_bf16 v[104:107], v[164:167], v[198:201], v[104:107]
	v_mfma_f32_16x16x32_bf16 v[108:111], v[148:151], v[198:201], v[108:111]
	v_mfma_f32_16x16x32_bf16 v[92:95], v[148:151], v[212:215], v[92:95]
	v_mfma_f32_16x16x32_bf16 v[88:91], v[164:167], v[212:215], v[88:91]
	v_mfma_f32_16x16x32_bf16 v[72:75], v[164:167], v[220:223], v[72:75]
	v_mfma_f32_16x16x32_bf16 v[76:79], v[148:151], v[220:223], v[76:79]
	v_mfma_f32_16x16x32_bf16 v[124:127], v[160:163], v[194:197], v[124:127]
	v_mfma_f32_16x16x32_bf16 v[120:123], v[168:171], v[194:197], v[120:123]
	v_mfma_f32_16x16x32_bf16 v[104:107], v[168:171], v[208:211], v[104:107]
	v_mfma_f32_16x16x32_bf16 v[108:111], v[160:163], v[208:211], v[108:111]
	v_mfma_f32_16x16x32_bf16 v[92:95], v[160:163], v[216:219], v[92:95]
	v_mfma_f32_16x16x32_bf16 v[88:91], v[168:171], v[216:219], v[88:91]
	v_mfma_f32_16x16x32_bf16 v[72:75], v[168:171], v[224:227], v[72:75]
	v_mfma_f32_16x16x32_bf16 v[76:79], v[160:163], v[224:227], v[76:79]
	s_setprio 0
	s_setprio 1
	v_mfma_f32_16x16x32_bf16 v[116:119], v[172:175], v[190:193], v[116:119]
	v_mfma_f32_16x16x32_bf16 v[112:115], v[182:185], v[190:193], v[112:115]
	v_mfma_f32_16x16x32_bf16 v[96:99], v[182:185], v[198:201], v[96:99]
	v_mfma_f32_16x16x32_bf16 v[100:103], v[172:175], v[198:201], v[100:103]
	v_mfma_f32_16x16x32_bf16 v[84:87], v[172:175], v[212:215], v[84:87]
	v_mfma_f32_16x16x32_bf16 v[80:83], v[182:185], v[212:215], v[80:83]
	v_mfma_f32_16x16x32_bf16 v[64:67], v[182:185], v[220:223], v[64:67]
	v_mfma_f32_16x16x32_bf16 v[68:71], v[172:175], v[220:223], v[68:71]
	v_mfma_f32_16x16x32_bf16 v[116:119], v[176:179], v[194:197], v[116:119]
	v_mfma_f32_16x16x32_bf16 v[112:115], v[186:189], v[194:197], v[112:115]
	v_mfma_f32_16x16x32_bf16 v[96:99], v[186:189], v[208:211], v[96:99]
	v_mfma_f32_16x16x32_bf16 v[100:103], v[176:179], v[208:211], v[100:103]
	v_mfma_f32_16x16x32_bf16 v[84:87], v[176:179], v[216:219], v[84:87]
	v_mfma_f32_16x16x32_bf16 v[80:83], v[186:189], v[216:219], v[80:83]
	v_mfma_f32_16x16x32_bf16 v[64:67], v[186:189], v[224:227], v[64:67]
	v_mfma_f32_16x16x32_bf16 v[68:71], v[176:179], v[224:227], v[68:71]
	s_setprio 0
	s_barrier
; #define PG8_STAGE(bufoff, gbase, voff) do { _Pragma("unroll") for (int _i = 0; _i < 2; ++_i) \
;         __builtin_amdgcn_global_load_lds((const unsigned*)((const char*)(gbase) + (voff)[_i]), (PG8_LAS unsigned*)(lds + (bufoff) + ldsw + _i * 8192), 16, 0, 0); } while (0)
; #define PG8_LDA(dst, b, h) do { _Pragma("unroll") for (int m = 0; m < 4; ++m) _Pragma("unroll") for (int k = 0; k < 2; ++k) dst[m][k] = *(const PG8_LAS bf16x8*)(lds + PG8_SA(b, h) + aoff + m * 2048 + k * 1024); } while (0)
; #define PG8_LDB(dst, b, h) do { _Pragma("unroll") for (int n = 0; n < 2; ++n) _Pragma("unroll") for (int k = 0; k < 2; ++k) dst[n][k] = *(const PG8_LAS bf16x8*)(lds + PG8_SB(b, h) + boff + n * 2048 + k * 1024); } while (0)
; #define PG8_MMA(ai, bj, At, Bt) do { __builtin_amdgcn_s_setprio(1); _Pragma("unroll") for (int m = 0; m < 4; ++m) _Pragma("unroll") for (int n = 0; n < 2; ++n) _Pragma("unroll") for (int k = 0; k < 2; ++k) \
;         acc[ai][bj][m][n] = __builtin_amdgcn_mfma_f32_16x16x32_bf16(Bt[n][k], At[m][k], acc[ai][bj][m][n], 0, 0, 0); __builtin_amdgcn_s_setprio(0); } while (0)
; #define PG8_WAIT_V(n) asm volatile("s_waitcnt vmcnt(" #n ")" ::: "memory")
; template <class Epi, class Sched, bool ALIGN_EPI = false, bool SP2 = false>
; __device__ __forceinline__ void gemm_phase(PG8_LAS unsigned char* lds, const Gemm g, const Sched& S, const Epi& E) {
;     ...
;             PG8_LDB(B0, 0, 0); PG8_LDB(B1, 0, 1); PG8_SCHED; PG8_LDA(At, 0, 0); PG8_STAGE(PG8_SA(1, 1), a1 + hstep, voffA);
;             PG8_WAIT_V(8); PG8_WAIT_L(0); PG8_BAR; PG8_MMA(0, 0, At, B0); PG8_MMA(0, 1, At, B1); PG8_BAR; PG8_SCHED;
;             PG8_LDA(At, 0, 1); PG8_STAGE(PG8_SB(0, 0), b2, voffB); PG8_STAGE(PG8_SB(0, 1), b2 + hstep, voffB); PG8_STAGE(PG8_SA(0, 0), a2, voffA);
;             PG8_WAIT_V(8); PG8_WAIT_L(0); PG8_BAR; PG8_MMA(1, 0, At, B0); PG8_MMA(1, 1, At, B1); PG8_BAR; PG8_SCHED;
;             PG8_LDB(B0, 1, 0); PG8_LDB(B1, 1, 1); PG8_SCHED; PG8_LDA(At, 1, 0); PG8_STAGE(PG8_SA(0, 1), a2 + hstep, voffA);
;             PG8_WAIT_V(8); PG8_WAIT_L(0); PG8_BAR; PG8_MMA(0, 0, At, B0); PG8_MMA(0, 1, At, B1); PG8_BAR; PG8_SCHED;
;             PG8_LDA(At, 1, 1); PG8_STAGE(PG8_SB(1, 0), b3, voffB); PG8_STAGE(PG8_SB(1, 1), b3 + hstep, voffB); PG8_STAGE(PG8_SA(1, 0), a3, voffA);
;             PG8_WAIT_V(8); PG8_WAIT_L(0); PG8_BAR; PG8_MMA(1, 0, At, B0); PG8_MMA(1, 1, At, B1); PG8_BAR; PG8_SCHED;
	s_add_i32 s3, s3, s34
	v_lshl_add_u64 v[202:203], v[202:203], 0, s[38:39]
	s_mov_b32 m0, s3
	ds_read_b128 v[190:193], v157 offset:49152
	ds_read_b128 v[194:197], v157 offset:50176
	ds_read_b128 v[198:201], v157 offset:51200
	ds_read_b128 v[208:211], v157 offset:52224
	ds_read_b128 v[212:215], v157 offset:53248
	ds_read_b128 v[216:219], v157 offset:54272
	ds_read_b128 v[220:223], v157 offset:55296
	ds_read_b128 v[224:227], v157 offset:56320
	global_load_lds_dwordx4 v[202:203], off
	s_add_i32 m0, s3, 0x2000
	s_add_u32 s14, s58, 0x40080
	v_lshl_add_u64 v[202:203], v[228:229], 0, s[38:39]
	s_addc_u32 s15, s59, 0
	s_add_i32 s3, s33, s34
	global_load_lds_dwordx4 v[202:203], off
	v_lshl_add_u64 v[202:203], s[14:15], 0, v[136:137]
	s_mov_b32 m0, s3
	s_nop 0
	global_load_lds_dwordx4 v[202:203], off
	v_lshl_add_u64 v[202:203], s[14:15], 0, v[132:133]
	s_add_i32 m0, s3, 0x2000
	s_nop 0
	global_load_lds_dwordx4 v[202:203], off
	s_waitcnt vmcnt(6)
	s_waitcnt lgkmcnt(0)
	s_barrier
	s_setprio 1
	s_waitcnt lgkmcnt(0)
	v_mfma_f32_16x16x32_bf16 v[60:63], v[148:151], v[190:193], v[60:63]
	v_mfma_f32_16x16x32_bf16 v[56:59], v[164:167], v[190:193], v[56:59]
	v_mfma_f32_16x16x32_bf16 v[40:43], v[164:167], v[198:201], v[40:43]
	v_mfma_f32_16x16x32_bf16 v[44:47], v[148:151], v[198:201], v[44:47]
	v_mfma_f32_16x16x32_bf16 v[28:31], v[148:151], v[212:215], v[28:31]
	v_mfma_f32_16x16x32_bf16 v[24:27], v[164:167], v[212:215], v[24:27]
	v_mfma_f32_16x16x32_bf16 v[8:11], v[164:167], v[220:223], v[8:11]
	v_mfma_f32_16x16x32_bf16 v[12:15], v[148:151], v[220:223], v[12:15]
	v_mfma_f32_16x16x32_bf16 v[60:63], v[160:163], v[194:197], v[60:63]
	v_mfma_f32_16x16x32_bf16 v[56:59], v[168:171], v[194:197], v[56:59]
	v_mfma_f32_16x16x32_bf16 v[40:43], v[168:171], v[208:211], v[40:43]
	v_mfma_f32_16x16x32_bf16 v[44:47], v[160:163], v[208:211], v[44:47]
	v_mfma_f32_16x16x32_bf16 v[28:31], v[160:163], v[216:219], v[28:31]
	v_mfma_f32_16x16x32_bf16 v[24:27], v[168:171], v[216:219], v[24:27]
	v_lshl_add_u64 v[202:203], v[230:231], 0, s[38:39]
	s_mov_b32 m0, s66
	s_nop 0
	global_load_lds_dwordx4 v[202:203], off
	v_mfma_f32_16x16x32_bf16 v[8:11], v[168:171], v[224:227], v[8:11]
	v_mfma_f32_16x16x32_bf16 v[12:15], v[160:163], v[224:227], v[12:15]
	s_setprio 0
	s_setprio 1
	v_mfma_f32_16x16x32_bf16 v[52:55], v[172:175], v[190:193], v[52:55]
	v_mfma_f32_16x16x32_bf16 v[48:51], v[182:185], v[190:193], v[48:51]
	v_mfma_f32_16x16x32_bf16 v[32:35], v[182:185], v[198:201], v[32:35]
	v_mfma_f32_16x16x32_bf16 v[36:39], v[172:175], v[198:201], v[36:39]
	v_mfma_f32_16x16x32_bf16 v[20:23], v[172:175], v[212:215], v[20:23]
	v_mfma_f32_16x16x32_bf16 v[16:19], v[182:185], v[212:215], v[16:19]
	v_mfma_f32_16x16x32_bf16 v[0:3], v[182:185], v[220:223], v[0:3]
	v_mfma_f32_16x16x32_bf16 v[4:7], v[172:175], v[220:223], v[4:7]
	v_mfma_f32_16x16x32_bf16 v[52:55], v[176:179], v[194:197], v[52:55]
	v_mfma_f32_16x16x32_bf16 v[48:51], v[186:189], v[194:197], v[48:51]
	v_mfma_f32_16x16x32_bf16 v[32:35], v[186:189], v[208:211], v[32:35]
	v_mfma_f32_16x16x32_bf16 v[36:39], v[176:179], v[208:211], v[36:39]
	v_mfma_f32_16x16x32_bf16 v[20:23], v[176:179], v[216:219], v[20:23]
	v_mfma_f32_16x16x32_bf16 v[16:19], v[186:189], v[216:219], v[16:19]
	v_lshl_add_u64 v[202:203], v[232:233], 0, s[38:39]
	s_mov_b32 m0, s67
	s_nop 0
	global_load_lds_dwordx4 v[202:203], off
	v_mfma_f32_16x16x32_bf16 v[0:3], v[186:189], v[224:227], v[0:3]
	v_mfma_f32_16x16x32_bf16 v[4:7], v[176:179], v[224:227], v[4:7]
	s_setprio 0
	s_barrier
	s_add_i32 s86, s86, 2
	s_add_u32 s56, s56, 0x100
	s_addc_u32 s57, s57, 0
	s_add_u32 s84, s84, 0x100
	s_addc_u32 s85, s85, 0
.LBB0_738:
	ds_read_b128 v[148:151], v155
	ds_read_b128 v[160:163], v155 offset:1024
	ds_read_b128 v[164:167], v155 offset:2048
	ds_read_b128 v[168:171], v155 offset:3072
	ds_read_b128 v[172:175], v156
	ds_read_b128 v[176:179], v156 offset:1024
	ds_read_b128 v[182:185], v156 offset:2048
	ds_read_b128 v[186:189], v156 offset:3072
	s_add_u32 s3, s56, 0xfffc0080
	s_addc_u32 s14, s57, -1
	s_cmp_eq_u32 s86, 12
	s_cselect_b32 s61, s51, s14
	s_cselect_b32 s60, s82, s3
	s_cselect_b32 s59, s49, s85
	s_cselect_b32 s58, s83, s84
	v_lshl_add_u64 v[202:203], s[56:57], 0, v[140:141]
	s_add_i32 m0, s43, 0xc000
	ds_read_b128 v[190:193], v157
	ds_read_b128 v[194:197], v157 offset:1024
	ds_read_b128 v[198:201], v157 offset:2048
	ds_read_b128 v[208:211], v157 offset:3072
	ds_read_b128 v[212:215], v157 offset:4096
	ds_read_b128 v[216:219], v157 offset:5120
	ds_read_b128 v[220:223], v157 offset:6144
	ds_read_b128 v[224:227], v157 offset:7168
	global_load_lds_dwordx4 v[202:203], off
	v_lshl_add_u64 v[202:203], s[56:57], 0, v[142:143]
	s_add_i32 m0, s43, 0xe000
	s_nop 0
	global_load_lds_dwordx4 v[202:203], off
	s_waitcnt vmcnt(8)
	s_waitcnt lgkmcnt(0)
	s_barrier
; #define PG8_STAGE(bufoff, gbase, voff) do { _Pragma("unroll") for (int _i = 0; _i < 2; ++_i) \
;         __builtin_amdgcn_global_load_lds((const unsigned*)((const char*)(gbase) + (voff)[_i]), (PG8_LAS unsigned*)(lds + (bufoff) + ldsw + _i * 8192), 16, 0, 0); } while (0)
; #define PG8_LDA(dst, b, h) do { _Pragma("unroll") for (int m = 0; m < 4; ++m) _Pragma("unroll") for (int k = 0; k < 2; ++k) dst[m][k] = *(const PG8_LAS bf16x8*)(lds + PG8_SA(b, h) + aoff + m * 2048 + k * 1024); } while (0)
; #define PG8_MMA(ai, bj, At, Bt) do { __builtin_amdgcn_s_setprio(1); _Pragma("unroll") for (int m = 0; m < 4; ++m) _Pragma("unroll") for (int n = 0; n < 2; ++n) _Pragma("unroll") for (int k = 0; k < 2; ++k) \
;         acc[ai][bj][m][n] = __builtin_amdgcn_mfma_f32_16x16x32_bf16(Bt[n][k], At[m][k], acc[ai][bj][m][n], 0, 0, 0); __builtin_amdgcn_s_setprio(0); } while (0)
; #define PG8_WAIT_V(n) asm volatile("s_waitcnt vmcnt(" #n ")" ::: "memory")
; #define PG8_WAIT_L(n) asm volatile("s_waitcnt lgkmcnt(" #n ")" ::: "memory")
; #define PG8_BAR __builtin_amdgcn_s_barrier()
; #define PG8_SCHED __builtin_amdgcn_sched_barrier(0)
; template <class Epi, class Sched, bool ALIGN_EPI = false, bool SP2 = false>
; __device__ __forceinline__ void gemm_phase(PG8_LAS unsigned char* lds, const Gemm g, const Sched& S, const Epi& E) {
;     ...
;             PG8_WAIT_V(8); PG8_WAIT_L(0); PG8_BAR; PG8_MMA(0, 0, At, B0); PG8_MMA(0, 1, At, B1); PG8_BAR; PG8_SCHED;
;             PG8_LDA(At, 0, 1); PG8_STAGE(PG8_SB(0, 0), b2, voffB); PG8_STAGE(PG8_SB(0, 1), b2 + hstep, voffB); PG8_STAGE(PG8_SA(0, 0), a2, voffA);
;             PG8_WAIT_V(8); PG8_WAIT_L(0); PG8_BAR; PG8_MMA(1, 0, At, B0); PG8_MMA(1, 1, At, B1); PG8_BAR; PG8_SCHED;
	s_setprio 1
	s_waitcnt lgkmcnt(0)
	v_mfma_f32_16x16x32_bf16 v[124:127], v[148:151], v[190:193], v[124:127]
	v_mfma_f32_16x16x32_bf16 v[120:123], v[164:167], v[190:193], v[120:123]
	v_mfma_f32_16x16x32_bf16 v[104:107], v[164:167], v[198:201], v[104:107]
	v_mfma_f32_16x16x32_bf16 v[108:111], v[148:151], v[198:201], v[108:111]
	v_mfma_f32_16x16x32_bf16 v[92:95], v[148:151], v[212:215], v[92:95]
	v_mfma_f32_16x16x32_bf16 v[88:91], v[164:167], v[212:215], v[88:91]
	v_mfma_f32_16x16x32_bf16 v[72:75], v[164:167], v[220:223], v[72:75]
	v_mfma_f32_16x16x32_bf16 v[76:79], v[148:151], v[220:223], v[76:79]
	v_mfma_f32_16x16x32_bf16 v[124:127], v[160:163], v[194:197], v[124:127]
	v_mfma_f32_16x16x32_bf16 v[120:123], v[168:171], v[194:197], v[120:123]
	v_mfma_f32_16x16x32_bf16 v[104:107], v[168:171], v[208:211], v[104:107]
	v_mfma_f32_16x16x32_bf16 v[108:111], v[160:163], v[208:211], v[108:111]
	v_mfma_f32_16x16x32_bf16 v[92:95], v[160:163], v[216:219], v[92:95]
	v_mfma_f32_16x16x32_bf16 v[88:91], v[168:171], v[216:219], v[88:91]
	v_mfma_f32_16x16x32_bf16 v[72:75], v[168:171], v[224:227], v[72:75]
	v_mfma_f32_16x16x32_bf16 v[76:79], v[160:163], v[224:227], v[76:79]
	s_setprio 0
	s_setprio 1
	v_mfma_f32_16x16x32_bf16 v[116:119], v[172:175], v[190:193], v[116:119]
	v_mfma_f32_16x16x32_bf16 v[112:115], v[182:185], v[190:193], v[112:115]
	v_mfma_f32_16x16x32_bf16 v[96:99], v[182:185], v[198:201], v[96:99]
	v_mfma_f32_16x16x32_bf16 v[100:103], v[172:175], v[198:201], v[100:103]
	v_mfma_f32_16x16x32_bf16 v[84:87], v[172:175], v[212:215], v[84:87]
	v_mfma_f32_16x16x32_bf16 v[80:83], v[182:185], v[212:215], v[80:83]
	v_mfma_f32_16x16x32_bf16 v[64:67], v[182:185], v[220:223], v[64:67]
	v_mfma_f32_16x16x32_bf16 v[68:71], v[172:175], v[220:223], v[68:71]
	v_mfma_f32_16x16x32_bf16 v[116:119], v[176:179], v[194:197], v[116:119]
	v_mfma_f32_16x16x32_bf16 v[112:115], v[186:189], v[194:197], v[112:115]
	v_mfma_f32_16x16x32_bf16 v[96:99], v[186:189], v[208:211], v[96:99]
	v_mfma_f32_16x16x32_bf16 v[100:103], v[176:179], v[208:211], v[100:103]
	v_mfma_f32_16x16x32_bf16 v[84:87], v[176:179], v[216:219], v[84:87]
	v_mfma_f32_16x16x32_bf16 v[80:83], v[186:189], v[216:219], v[80:83]
	v_mfma_f32_16x16x32_bf16 v[64:67], v[186:189], v[224:227], v[64:67]
	v_mfma_f32_16x16x32_bf16 v[68:71], v[176:179], v[224:227], v[68:71]
	s_setprio 0
	s_barrier
	s_add_i32 s3, s74, s34
	v_lshl_add_u64 v[202:203], s[58:59], 0, v[136:137]
	s_mov_b32 m0, s3
	ds_read_b128 v[190:193], v157 offset:16384
	ds_read_b128 v[194:197], v157 offset:17408
	ds_read_b128 v[198:201], v157 offset:18432
	ds_read_b128 v[208:211], v157 offset:19456
	ds_read_b128 v[212:215], v157 offset:20480
	ds_read_b128 v[216:219], v157 offset:21504
	ds_read_b128 v[220:223], v157 offset:22528
	ds_read_b128 v[224:227], v157 offset:23552
	global_load_lds_dwordx4 v[202:203], off
	s_add_i32 m0, s3, 0x2000
	s_add_u32 s14, s58, 0x40000
	v_lshl_add_u64 v[228:229], s[58:59], 0, v[132:133]
	s_addc_u32 s15, s59, 0
	s_add_i32 s3, s75, s34
	global_load_lds_dwordx4 v[228:229], off
	v_lshl_add_u64 v[230:231], s[14:15], 0, v[136:137]
	s_mov_b32 m0, s3
	global_load_lds_dwordx4 v[230:231], off
	v_lshl_add_u64 v[230:231], s[14:15], 0, v[132:133]
	s_add_i32 m0, s3, 0x2000
	s_nop 0
	global_load_lds_dwordx4 v[230:231], off
	s_waitcnt vmcnt(6)
	s_waitcnt lgkmcnt(0)
	s_barrier
	s_setprio 1
	s_waitcnt lgkmcnt(0)
	v_mfma_f32_16x16x32_bf16 v[60:63], v[148:151], v[190:193], v[60:63]
	v_mfma_f32_16x16x32_bf16 v[56:59], v[164:167], v[190:193], v[56:59]
	v_mfma_f32_16x16x32_bf16 v[40:43], v[164:167], v[198:201], v[40:43]
	v_mfma_f32_16x16x32_bf16 v[44:47], v[148:151], v[198:201], v[44:47]
	v_mfma_f32_16x16x32_bf16 v[28:31], v[148:151], v[212:215], v[28:31]
	v_mfma_f32_16x16x32_bf16 v[24:27], v[164:167], v[212:215], v[24:27]
	v_mfma_f32_16x16x32_bf16 v[8:11], v[164:167], v[220:223], v[8:11]
	v_mfma_f32_16x16x32_bf16 v[12:15], v[148:151], v[220:223], v[12:15]
	v_mfma_f32_16x16x32_bf16 v[60:63], v[160:163], v[194:197], v[60:63]
	v_mfma_f32_16x16x32_bf16 v[56:59], v[168:171], v[194:197], v[56:59]
	v_mfma_f32_16x16x32_bf16 v[40:43], v[168:171], v[208:211], v[40:43]
	v_mfma_f32_16x16x32_bf16 v[44:47], v[160:163], v[208:211], v[44:47]
	v_mfma_f32_16x16x32_bf16 v[28:31], v[160:163], v[216:219], v[28:31]
	v_mfma_f32_16x16x32_bf16 v[24:27], v[168:171], v[216:219], v[24:27]
	v_lshl_add_u64 v[230:231], s[60:61], 0, v[138:139]
	s_mov_b32 m0, s43
	s_nop 0
	global_load_lds_dwordx4 v[230:231], off
	v_mfma_f32_16x16x32_bf16 v[8:11], v[168:171], v[224:227], v[8:11]
	v_mfma_f32_16x16x32_bf16 v[12:15], v[160:163], v[224:227], v[12:15]
	s_setprio 0
	s_setprio 1
	v_mfma_f32_16x16x32_bf16 v[52:55], v[172:175], v[190:193], v[52:55]
	v_mfma_f32_16x16x32_bf16 v[48:51], v[182:185], v[190:193], v[48:51]
	v_mfma_f32_16x16x32_bf16 v[32:35], v[182:185], v[198:201], v[32:35]
	v_mfma_f32_16x16x32_bf16 v[36:39], v[172:175], v[198:201], v[36:39]
	v_mfma_f32_16x16x32_bf16 v[20:23], v[172:175], v[212:215], v[20:23]
	v_mfma_f32_16x16x32_bf16 v[16:19], v[182:185], v[212:215], v[16:19]
	v_mfma_f32_16x16x32_bf16 v[0:3], v[182:185], v[220:223], v[0:3]
	v_mfma_f32_16x16x32_bf16 v[4:7], v[172:175], v[220:223], v[4:7]
	v_mfma_f32_16x16x32_bf16 v[52:55], v[176:179], v[194:197], v[52:55]
	v_mfma_f32_16x16x32_bf16 v[48:51], v[186:189], v[194:197], v[48:51]
	v_mfma_f32_16x16x32_bf16 v[32:35], v[186:189], v[208:211], v[32:35]
	v_mfma_f32_16x16x32_bf16 v[36:39], v[176:179], v[208:211], v[36:39]
	v_mfma_f32_16x16x32_bf16 v[20:23], v[176:179], v[216:219], v[20:23]
	v_mfma_f32_16x16x32_bf16 v[16:19], v[186:189], v[216:219], v[16:19]
	v_lshl_add_u64 v[232:233], s[60:61], 0, v[134:135]
	s_mov_b32 m0, s62
	s_nop 0
	global_load_lds_dwordx4 v[232:233], off
	v_mfma_f32_16x16x32_bf16 v[0:3], v[186:189], v[224:227], v[0:3]
	v_mfma_f32_16x16x32_bf16 v[4:7], v[176:179], v[224:227], v[4:7]
	s_setprio 0
	s_barrier
; #define PG8_STAGE(bufoff, gbase, voff) do { _Pragma("unroll") for (int _i = 0; _i < 2; ++_i) \
;         __builtin_amdgcn_global_load_lds((const unsigned*)((const char*)(gbase) + (voff)[_i]), (PG8_LAS unsigned*)(lds + (bufoff) + ldsw + _i * 8192), 16, 0, 0); } while (0)
; #define PG8_LDA(dst, b, h) do { _Pragma("unroll") for (int m = 0; m < 4; ++m) _Pragma("unroll") for (int k = 0; k < 2; ++k) dst[m][k] = *(const PG8_LAS bf16x8*)(lds + PG8_SA(b, h) + aoff + m * 2048 + k * 1024); } while (0)
; #define PG8_LDB(dst, b, h) do { _Pragma("unroll") for (int n = 0; n < 2; ++n) _Pragma("unroll") for (int k = 0; k < 2; ++k) dst[n][k] = *(const PG8_LAS bf16x8*)(lds + PG8_SB(b, h) + boff + n * 2048 + k * 1024); } while (0)
; #define PG8_MMA(ai, bj, At, Bt) do { __builtin_amdgcn_s_setprio(1); _Pragma("unroll") for (int m = 0; m < 4; ++m) _Pragma("unroll") for (int n = 0; n < 2; ++n) _Pragma("unroll") for (int k = 0; k < 2; ++k) \
;         acc[ai][bj][m][n] = __builtin_amdgcn_mfma_f32_16x16x32_bf16(Bt[n][k], At[m][k], acc[ai][bj][m][n], 0, 0, 0); __builtin_amdgcn_s_setprio(0); } while (0)
; #define PG8_WAIT_V(n) asm volatile("s_waitcnt vmcnt(" #n ")" ::: "memory")
; #define PG8_WAIT_L(n) asm volatile("s_waitcnt lgkmcnt(" #n ")" ::: "memory")
; #define PG8_BAR __builtin_amdgcn_s_barrier()
; #define PG8_SCHED __builtin_amdgcn_sched_barrier(0)
; template <class Epi, class Sched, bool ALIGN_EPI = false, bool SP2 = false>
; __device__ __forceinline__ void gemm_phase(PG8_LAS unsigned char* lds, const Gemm g, const Sched& S, const Epi& E) {
;     ...
;             PG8_LDB(B0, 1, 0); PG8_LDB(B1, 1, 1); PG8_SCHED; PG8_LDA(At, 1, 0); PG8_STAGE(PG8_SA(0, 1), a2 + hstep, voffA);
;             PG8_WAIT_V(8); PG8_WAIT_L(0); PG8_BAR; PG8_MMA(0, 0, At, B0); PG8_MMA(0, 1, At, B1); PG8_BAR; PG8_SCHED;
	s_add_i32 s3, 0, 0x18000
	v_add_u32_e32 v159, s3, v131
	s_add_i32 s33, 0, 0x1c000
	ds_read_b128 v[148:151], v159
	ds_read_b128 v[160:163], v159 offset:1024
	ds_read_b128 v[164:167], v159 offset:2048
	ds_read_b128 v[168:171], v159 offset:3072
	v_add_u32_e32 v159, s33, v131
	ds_read_b128 v[172:175], v159
	ds_read_b128 v[176:179], v159 offset:1024
	ds_read_b128 v[182:185], v159 offset:2048
	ds_read_b128 v[186:189], v159 offset:3072
	s_add_u32 s14, s60, 0x40000
	s_addc_u32 s15, s61, 0
	s_mov_b32 m0, s63
	v_lshl_add_u64 v[234:235], s[14:15], 0, v[138:139]
	ds_read_b128 v[190:193], v157 offset:32768
	ds_read_b128 v[194:197], v157 offset:33792
	ds_read_b128 v[198:201], v157 offset:34816
	ds_read_b128 v[208:211], v157 offset:35840
	ds_read_b128 v[212:215], v157 offset:36864
	ds_read_b128 v[216:219], v157 offset:37888
	ds_read_b128 v[220:223], v157 offset:38912
	ds_read_b128 v[224:227], v157 offset:39936
	global_load_lds_dwordx4 v[234:235], off
	v_lshl_add_u64 v[234:235], s[14:15], 0, v[134:135]
	s_mov_b32 m0, s64
	s_nop 0
	global_load_lds_dwordx4 v[234:235], off
	s_waitcnt vmcnt(8)
	s_waitcnt lgkmcnt(0)
	s_barrier
	s_setprio 1
	s_waitcnt lgkmcnt(0)
	v_mfma_f32_16x16x32_bf16 v[124:127], v[148:151], v[190:193], v[124:127]
	v_mfma_f32_16x16x32_bf16 v[120:123], v[164:167], v[190:193], v[120:123]
	v_mfma_f32_16x16x32_bf16 v[104:107], v[164:167], v[198:201], v[104:107]
	v_mfma_f32_16x16x32_bf16 v[108:111], v[148:151], v[198:201], v[108:111]
	v_mfma_f32_16x16x32_bf16 v[92:95], v[148:151], v[212:215], v[92:95]
	v_mfma_f32_16x16x32_bf16 v[88:91], v[164:167], v[212:215], v[88:91]
	v_mfma_f32_16x16x32_bf16 v[72:75], v[164:167], v[220:223], v[72:75]
	v_mfma_f32_16x16x32_bf16 v[76:79], v[148:151], v[220:223], v[76:79]
	v_mfma_f32_16x16x32_bf16 v[124:127], v[160:163], v[194:197], v[124:127]
	v_mfma_f32_16x16x32_bf16 v[120:123], v[168:171], v[194:197], v[120:123]
	v_mfma_f32_16x16x32_bf16 v[104:107], v[168:171], v[208:211], v[104:107]
	v_mfma_f32_16x16x32_bf16 v[108:111], v[160:163], v[208:211], v[108:111]
	v_mfma_f32_16x16x32_bf16 v[92:95], v[160:163], v[216:219], v[92:95]
	v_mfma_f32_16x16x32_bf16 v[88:91], v[168:171], v[216:219], v[88:91]
	v_mfma_f32_16x16x32_bf16 v[72:75], v[168:171], v[224:227], v[72:75]
	v_mfma_f32_16x16x32_bf16 v[76:79], v[160:163], v[224:227], v[76:79]
	s_setprio 0
	s_setprio 1
	v_mfma_f32_16x16x32_bf16 v[116:119], v[172:175], v[190:193], v[116:119]
	v_mfma_f32_16x16x32_bf16 v[112:115], v[182:185], v[190:193], v[112:115]
	v_mfma_f32_16x16x32_bf16 v[96:99], v[182:185], v[198:201], v[96:99]
	v_mfma_f32_16x16x32_bf16 v[100:103], v[172:175], v[198:201], v[100:103]
	v_mfma_f32_16x16x32_bf16 v[84:87], v[172:175], v[212:215], v[84:87]
	v_mfma_f32_16x16x32_bf16 v[80:83], v[182:185], v[212:215], v[80:83]
	v_mfma_f32_16x16x32_bf16 v[64:67], v[182:185], v[220:223], v[64:67]
	v_mfma_f32_16x16x32_bf16 v[68:71], v[172:175], v[220:223], v[68:71]
	v_mfma_f32_16x16x32_bf16 v[116:119], v[176:179], v[194:197], v[116:119]
	v_mfma_f32_16x16x32_bf16 v[112:115], v[186:189], v[194:197], v[112:115]
	v_mfma_f32_16x16x32_bf16 v[96:99], v[186:189], v[208:211], v[96:99]
	v_mfma_f32_16x16x32_bf16 v[100:103], v[176:179], v[208:211], v[100:103]
	v_mfma_f32_16x16x32_bf16 v[84:87], v[176:179], v[216:219], v[84:87]
	v_mfma_f32_16x16x32_bf16 v[80:83], v[186:189], v[216:219], v[80:83]
	v_mfma_f32_16x16x32_bf16 v[64:67], v[186:189], v[224:227], v[64:67]
	v_mfma_f32_16x16x32_bf16 v[68:71], v[176:179], v[224:227], v[68:71]
	s_setprio 0
	s_barrier
; #define PG8_STAGE(bufoff, gbase, voff) do { _Pragma("unroll") for (int _i = 0; _i < 2; ++_i) \
;         __builtin_amdgcn_global_load_lds((const unsigned*)((const char*)(gbase) + (voff)[_i]), (PG8_LAS unsigned*)(lds + (bufoff) + ldsw + _i * 8192), 16, 0, 0); } while (0)
; #define PG8_LDA(dst, b, h) do { _Pragma("unroll") for (int m = 0; m < 4; ++m) _Pragma("unroll") for (int k = 0; k < 2; ++k) dst[m][k] = *(const PG8_LAS bf16x8*)(lds + PG8_SA(b, h) + aoff + m * 2048 + k * 1024); } while (0)
; #define PG8_MMA(ai, bj, At, Bt) do { __builtin_amdgcn_s_setprio(1); _Pragma("unroll") for (int m = 0; m < 4; ++m) _Pragma("unroll") for (int n = 0; n < 2; ++n) _Pragma("unroll") for (int k = 0; k < 2; ++k) \
;         acc[ai][bj][m][n] = __builtin_amdgcn_mfma_f32_16x16x32_bf16(Bt[n][k], At[m][k], acc[ai][bj][m][n], 0, 0, 0); __builtin_amdgcn_s_setprio(0); } while (0)
; #define PG8_WAIT_V(n) asm volatile("s_waitcnt vmcnt(" #n ")" ::: "memory")
; #define PG8_WAIT_L(n) asm volatile("s_waitcnt lgkmcnt(" #n ")" ::: "memory")
; #define PG8_BAR __builtin_amdgcn_s_barrier()
; #define PG8_SCHED __builtin_amdgcn_sched_barrier(0)
; template <class Epi, class Sched, bool ALIGN_EPI = false, bool SP2 = false>
; __device__ __forceinline__ void gemm_phase(PG8_LAS unsigned char* lds, const Gemm g, const Sched& S, const Epi& E) {
;     ...
;             PG8_LDA(At, 1, 1); PG8_STAGE(PG8_SB(1, 0), b3, voffB); PG8_STAGE(PG8_SB(1, 1), b3 + hstep, voffB); PG8_STAGE(PG8_SA(1, 0), a3, voffA);
;             PG8_WAIT_V(8); PG8_WAIT_L(0); PG8_BAR; PG8_MMA(1, 0, At, B0); PG8_MMA(1, 1, At, B1); PG8_BAR; PG8_SCHED;
;     ...
;         if constexpr (ALIGN_EPI) { if (wr == 0) PG8_BAR; }
	s_add_i32 s3, s3, s34
	v_lshl_add_u64 v[202:203], v[202:203], 0, s[38:39]
	s_mov_b32 m0, s3
	ds_read_b128 v[190:193], v157 offset:49152
	ds_read_b128 v[194:197], v157 offset:50176
	ds_read_b128 v[198:201], v157 offset:51200
	ds_read_b128 v[208:211], v157 offset:52224
	ds_read_b128 v[212:215], v157 offset:53248
	ds_read_b128 v[216:219], v157 offset:54272
	ds_read_b128 v[220:223], v157 offset:55296
	ds_read_b128 v[224:227], v157 offset:56320
	global_load_lds_dwordx4 v[202:203], off
	s_add_i32 m0, s3, 0x2000
	s_add_u32 s14, s58, 0x40080
	v_lshl_add_u64 v[202:203], v[228:229], 0, s[38:39]
	s_addc_u32 s15, s59, 0
	s_add_i32 s3, s33, s34
	global_load_lds_dwordx4 v[202:203], off
	v_lshl_add_u64 v[202:203], s[14:15], 0, v[136:137]
	s_mov_b32 m0, s3
	s_nop 0
	global_load_lds_dwordx4 v[202:203], off
	v_lshl_add_u64 v[202:203], s[14:15], 0, v[132:133]
	s_add_i32 m0, s3, 0x2000
	s_nop 0
	global_load_lds_dwordx4 v[202:203], off
	s_waitcnt vmcnt(6)
	s_waitcnt lgkmcnt(0)
	s_barrier
	s_setprio 1
	s_waitcnt lgkmcnt(0)
	v_mfma_f32_16x16x32_bf16 v[60:63], v[148:151], v[190:193], v[60:63]
	v_mfma_f32_16x16x32_bf16 v[56:59], v[164:167], v[190:193], v[56:59]
	v_mfma_f32_16x16x32_bf16 v[40:43], v[164:167], v[198:201], v[40:43]
	v_mfma_f32_16x16x32_bf16 v[44:47], v[148:151], v[198:201], v[44:47]
	v_mfma_f32_16x16x32_bf16 v[28:31], v[148:151], v[212:215], v[28:31]
	v_mfma_f32_16x16x32_bf16 v[24:27], v[164:167], v[212:215], v[24:27]
	v_mfma_f32_16x16x32_bf16 v[8:11], v[164:167], v[220:223], v[8:11]
	v_mfma_f32_16x16x32_bf16 v[12:15], v[148:151], v[220:223], v[12:15]
	v_mfma_f32_16x16x32_bf16 v[60:63], v[160:163], v[194:197], v[60:63]
	v_mfma_f32_16x16x32_bf16 v[56:59], v[168:171], v[194:197], v[56:59]
	v_mfma_f32_16x16x32_bf16 v[40:43], v[168:171], v[208:211], v[40:43]
	v_mfma_f32_16x16x32_bf16 v[44:47], v[160:163], v[208:211], v[44:47]
	v_mfma_f32_16x16x32_bf16 v[28:31], v[160:163], v[216:219], v[28:31]
	v_mfma_f32_16x16x32_bf16 v[24:27], v[168:171], v[216:219], v[24:27]
	v_lshl_add_u64 v[202:203], v[230:231], 0, s[38:39]
	s_mov_b32 m0, s66
	s_nop 0
	global_load_lds_dwordx4 v[202:203], off
	v_mfma_f32_16x16x32_bf16 v[8:11], v[168:171], v[224:227], v[8:11]
	v_mfma_f32_16x16x32_bf16 v[12:15], v[160:163], v[224:227], v[12:15]
	s_setprio 0
	s_setprio 1
	v_mfma_f32_16x16x32_bf16 v[52:55], v[172:175], v[190:193], v[52:55]
	v_mfma_f32_16x16x32_bf16 v[48:51], v[182:185], v[190:193], v[48:51]
	v_mfma_f32_16x16x32_bf16 v[32:35], v[182:185], v[198:201], v[32:35]
	v_mfma_f32_16x16x32_bf16 v[36:39], v[172:175], v[198:201], v[36:39]
	v_mfma_f32_16x16x32_bf16 v[20:23], v[172:175], v[212:215], v[20:23]
	v_mfma_f32_16x16x32_bf16 v[16:19], v[182:185], v[212:215], v[16:19]
	v_mfma_f32_16x16x32_bf16 v[0:3], v[182:185], v[220:223], v[0:3]
	v_mfma_f32_16x16x32_bf16 v[4:7], v[172:175], v[220:223], v[4:7]
	v_mfma_f32_16x16x32_bf16 v[52:55], v[176:179], v[194:197], v[52:55]
	v_mfma_f32_16x16x32_bf16 v[48:51], v[186:189], v[194:197], v[48:51]
	v_mfma_f32_16x16x32_bf16 v[32:35], v[186:189], v[208:211], v[32:35]
	v_mfma_f32_16x16x32_bf16 v[36:39], v[176:179], v[208:211], v[36:39]
	v_mfma_f32_16x16x32_bf16 v[20:23], v[176:179], v[216:219], v[20:23]
	v_mfma_f32_16x16x32_bf16 v[16:19], v[186:189], v[216:219], v[16:19]
	v_lshl_add_u64 v[202:203], v[232:233], 0, s[38:39]
	s_mov_b32 m0, s67
	s_nop 0
	global_load_lds_dwordx4 v[202:203], off
	v_mfma_f32_16x16x32_bf16 v[0:3], v[186:189], v[224:227], v[0:3]
	v_mfma_f32_16x16x32_bf16 v[4:7], v[176:179], v[224:227], v[4:7]
	s_setprio 0
	s_barrier
	s_add_i32 s86, s86, 2
	s_add_u32 s56, s56, 0x100
	s_addc_u32 s57, s57, 0
	s_add_u32 s84, s84, 0x100
	s_addc_u32 s85, s85, 0
	s_cmp_gt_u32 s86, 13
	s_cbranch_scc0 .LBB0_738
	s_and_b64 vcc, exec, s[44:45]
	s_cbranch_vccz .LBB0_741
	s_barrier

; #define PG8_STAGE(bufoff, gbase, voff) do { _Pragma("unroll") for (int _i = 0; _i < 2; ++_i) \
;         __builtin_amdgcn_global_load_lds((const unsigned*)((const char*)(gbase) + (voff)[_i]), (PG8_LAS unsigned*)(lds + (bufoff) + ldsw + _i * 8192), 16, 0, 0); } while (0)
; #define PG8_LDA(dst, b, h) do { _Pragma("unroll") for (int m = 0; m < 4; ++m) _Pragma("unroll") for (int k = 0; k < 2; ++k) dst[m][k] = *(const PG8_LAS bf16x8*)(lds + PG8_SA(b, h) + aoff + m * 2048 + k * 1024); } while (0)
; #define PG8_LDB(dst, b, h) do { _Pragma("unroll") for (int n = 0; n < 2; ++n) _Pragma("unroll") for (int k = 0; k < 2; ++k) dst[n][k] = *(const PG8_LAS bf16x8*)(lds + PG8_SB(b, h) + boff + n * 2048 + k * 1024); } while (0)
; #define PG8_MMA(ai, bj, At, Bt) do { __builtin_amdgcn_s_setprio(1); _Pragma("unroll") for (int m = 0; m < 4; ++m) _Pragma("unroll") for (int n = 0; n < 2; ++n) _Pragma("unroll") for (int k = 0; k < 2; ++k) \
;         acc[ai][bj][m][n] = __builtin_amdgcn_mfma_f32_16x16x32_bf16(Bt[n][k], At[m][k], acc[ai][bj][m][n], 0, 0, 0); __builtin_amdgcn_s_setprio(0); } while (0)
; #define PG8_WAIT_V(n) asm volatile("s_waitcnt vmcnt(" #n ")" ::: "memory")
; #define PG8_WAIT_L(n) asm volatile("s_waitcnt lgkmcnt(" #n ")" ::: "memory")
; #define PG8_BAR __builtin_amdgcn_s_barrier()
; template <class Epi, class Sched, bool ALIGN_EPI = false, bool SP2 = false>
; __device__ __forceinline__ void gemm_phase(PG8_LAS unsigned char* lds, const Gemm g, const Sched& S, const Epi& E) {
;     ...
;         const bool has_next = S.next(ui + 1, nxt);
;         const char* nA = has_next ? (const char*)g.A + (size_t)nxt.pm * tstep : cA; const char* nB = has_next ? (const char*)g.Bt + (size_t)nxt.pn * tstep : cB;
;         for (int t = 0; t < nt; t += 2) {
;             const bool last = (t == nt - 2);
;             const char* a1 = cA + (size_t)(t + 1) * kstep;
;             const char* a2 = last ? nA : cA + (size_t)(t + 2) * kstep; const char* b2 = last ? nB : cB + (size_t)(t + 2) * kstep;
;             const char* a3 = a2 + kstep; const char* b3 = b2 + kstep;
;             if (last && has_next) S.a_ready(nxt);
;             if constexpr (SP2) {
;             PG8_LDB(B0, 0, 0); PG8_LDB(B1, 0, 1); PG8_SCHED; PG8_LDA(At, 0, 0); PG8_STAGE(PG8_SA(1, 1), a1 + hstep, voffA);
;             PG8_WAIT_V(8); PG8_WAIT_L(0); PG8_BAR; PG8_MMA(0, 0, At, B0); PG8_MMA(0, 1, At, B1); PG8_BAR; PG8_SCHED;
.LBB0_872:
	s_ashr_i32 s49, s48, 31
	s_lshl_b64 s[50:51], s[48:49], 18
	s_add_u32 s50, s92, s50
	s_addc_u32 s51, s93, s51
	s_and_b64 s[52:53], s[10:11], exec
	s_cselect_b32 s49, s51, s59
	s_cselect_b32 s55, s50, s58
	s_ashr_i32 s45, s44, 31
	s_lshl_b64 s[52:53], s[44:45], 18
	s_add_u32 s52, s76, s52
	s_addc_u32 s53, s77, s53
	s_and_b64 s[62:63], s[10:11], exec
	s_cselect_b32 s45, s53, s61
	s_cselect_b32 s84, s52, s60
	s_add_u32 s58, s58, 0x20080
	s_addc_u32 s59, s59, 0
	s_add_u32 s85, s60, 0x100
	s_addc_u32 s86, s61, 0
	s_mov_b32 s87, -2
	s_waitcnt lgkmcnt(0)
	ds_read_b128 v[144:147], v151
	ds_read_b128 v[156:159], v151 offset:1024
	ds_read_b128 v[160:163], v151 offset:2048
	ds_read_b128 v[164:167], v151 offset:3072
	ds_read_b128 v[168:171], v152
	ds_read_b128 v[172:175], v152 offset:1024
	ds_read_b128 v[176:179], v152 offset:2048
	ds_read_b128 v[182:185], v152 offset:3072
	s_add_u32 s3, s58, 0xfffe0080
	s_addc_u32 s33, s59, -1
	s_cmp_eq_u32 s87, 4
	s_cselect_b32 s63, s49, s33
	s_cselect_b32 s62, s55, s3
	s_cselect_b32 s61, s45, s86
	s_cselect_b32 s60, s84, s85
	v_lshl_add_u64 v[202:203], s[58:59], 0, v[136:137]
	s_add_i32 m0, s15, 0xc000
	ds_read_b128 v[186:189], v153
	ds_read_b128 v[190:193], v153 offset:1024
	ds_read_b128 v[194:197], v153 offset:2048
	ds_read_b128 v[198:201], v153 offset:3072
	ds_read_b128 v[208:211], v153 offset:4096
	ds_read_b128 v[212:215], v153 offset:5120
	ds_read_b128 v[216:219], v153 offset:6144
	ds_read_b128 v[220:223], v153 offset:7168
	global_load_lds_dwordx4 v[202:203], off
	v_lshl_add_u64 v[202:203], s[58:59], 0, v[138:139]
	s_add_i32 m0, s15, 0xe000
	s_nop 0
	global_load_lds_dwordx4 v[202:203], off
	s_waitcnt vmcnt(8)
	s_waitcnt lgkmcnt(0)
	s_barrier
	s_setprio 1
	s_waitcnt lgkmcnt(0)
	v_mfma_f32_16x16x32_bf16 v[124:127], v[144:147], v[186:189], 0
	v_mfma_f32_16x16x32_bf16 v[120:123], v[160:163], v[186:189], 0
	v_mfma_f32_16x16x32_bf16 v[104:107], v[160:163], v[194:197], 0
	v_mfma_f32_16x16x32_bf16 v[108:111], v[144:147], v[194:197], 0
	v_mfma_f32_16x16x32_bf16 v[92:95], v[144:147], v[208:211], 0
	v_mfma_f32_16x16x32_bf16 v[88:91], v[160:163], v[208:211], 0
	v_mfma_f32_16x16x32_bf16 v[72:75], v[160:163], v[216:219], 0
	v_mfma_f32_16x16x32_bf16 v[76:79], v[144:147], v[216:219], 0
	v_mfma_f32_16x16x32_bf16 v[124:127], v[156:159], v[190:193], v[124:127]
	v_mfma_f32_16x16x32_bf16 v[120:123], v[164:167], v[190:193], v[120:123]
	v_mfma_f32_16x16x32_bf16 v[104:107], v[164:167], v[198:201], v[104:107]
	v_mfma_f32_16x16x32_bf16 v[108:111], v[156:159], v[198:201], v[108:111]
	v_mfma_f32_16x16x32_bf16 v[92:95], v[156:159], v[212:215], v[92:95]
	v_mfma_f32_16x16x32_bf16 v[88:91], v[164:167], v[212:215], v[88:91]
	v_mfma_f32_16x16x32_bf16 v[72:75], v[164:167], v[220:223], v[72:75]
	v_mfma_f32_16x16x32_bf16 v[76:79], v[156:159], v[220:223], v[76:79]
	s_setprio 0
	s_setprio 1
	v_mfma_f32_16x16x32_bf16 v[116:119], v[168:171], v[186:189], 0
	v_mfma_f32_16x16x32_bf16 v[112:115], v[176:179], v[186:189], 0
	v_mfma_f32_16x16x32_bf16 v[96:99], v[176:179], v[194:197], 0
	v_mfma_f32_16x16x32_bf16 v[100:103], v[168:171], v[194:197], 0
	v_mfma_f32_16x16x32_bf16 v[84:87], v[168:171], v[208:211], 0
	v_mfma_f32_16x16x32_bf16 v[80:83], v[176:179], v[208:211], 0
	v_mfma_f32_16x16x32_bf16 v[64:67], v[176:179], v[216:219], 0
	v_mfma_f32_16x16x32_bf16 v[68:71], v[168:171], v[216:219], 0
	v_mfma_f32_16x16x32_bf16 v[116:119], v[172:175], v[190:193], v[116:119]
	v_mfma_f32_16x16x32_bf16 v[112:115], v[182:185], v[190:193], v[112:115]
	v_mfma_f32_16x16x32_bf16 v[96:99], v[182:185], v[198:201], v[96:99]
	v_mfma_f32_16x16x32_bf16 v[100:103], v[172:175], v[198:201], v[100:103]
	v_mfma_f32_16x16x32_bf16 v[84:87], v[172:175], v[212:215], v[84:87]
	v_mfma_f32_16x16x32_bf16 v[80:83], v[182:185], v[212:215], v[80:83]
	v_mfma_f32_16x16x32_bf16 v[64:67], v[182:185], v[220:223], v[64:67]
	v_mfma_f32_16x16x32_bf16 v[68:71], v[172:175], v[220:223], v[68:71]
	s_setprio 0
	s_barrier
	s_add_i32 s3, s74, s14
	v_lshl_add_u64 v[202:203], s[60:61], 0, v[130:131]
	s_mov_b32 m0, s3
	ds_read_b128 v[186:189], v153 offset:16384
	ds_read_b128 v[190:193], v153 offset:17408
	ds_read_b128 v[194:197], v153 offset:18432
	ds_read_b128 v[198:201], v153 offset:19456
	ds_read_b128 v[208:211], v153 offset:20480
	ds_read_b128 v[212:215], v153 offset:21504
	ds_read_b128 v[216:219], v153 offset:22528
	ds_read_b128 v[220:223], v153 offset:23552
	global_load_lds_dwordx4 v[202:203], off
	s_add_i32 m0, s3, 0x2000
	s_add_u32 s78, s60, 0x20000
	v_lshl_add_u64 v[224:225], s[60:61], 0, v[134:135]
	s_addc_u32 s79, s61, 0
	s_add_i32 s3, s75, s14
	global_load_lds_dwordx4 v[224:225], off
	v_lshl_add_u64 v[226:227], s[78:79], 0, v[130:131]
	s_mov_b32 m0, s3
	global_load_lds_dwordx4 v[226:227], off
	v_lshl_add_u64 v[226:227], s[78:79], 0, v[134:135]
	s_add_i32 m0, s3, 0x2000
	s_nop 0
	global_load_lds_dwordx4 v[226:227], off
	s_waitcnt vmcnt(6)
	s_waitcnt lgkmcnt(0)
	s_barrier
; #define PG8_STAGE(bufoff, gbase, voff) do { _Pragma("unroll") for (int _i = 0; _i < 2; ++_i) \
;         __builtin_amdgcn_global_load_lds((const unsigned*)((const char*)(gbase) + (voff)[_i]), (PG8_LAS unsigned*)(lds + (bufoff) + ldsw + _i * 8192), 16, 0, 0); } while (0)
; #define PG8_LDA(dst, b, h) do { _Pragma("unroll") for (int m = 0; m < 4; ++m) _Pragma("unroll") for (int k = 0; k < 2; ++k) dst[m][k] = *(const PG8_LAS bf16x8*)(lds + PG8_SA(b, h) + aoff + m * 2048 + k * 1024); } while (0)
; #define PG8_LDB(dst, b, h) do { _Pragma("unroll") for (int n = 0; n < 2; ++n) _Pragma("unroll") for (int k = 0; k < 2; ++k) dst[n][k] = *(const PG8_LAS bf16x8*)(lds + PG8_SB(b, h) + boff + n * 2048 + k * 1024); } while (0)
; #define PG8_MMA(ai, bj, At, Bt) do { __builtin_amdgcn_s_setprio(1); _Pragma("unroll") for (int m = 0; m < 4; ++m) _Pragma("unroll") for (int n = 0; n < 2; ++n) _Pragma("unroll") for (int k = 0; k < 2; ++k) \
;         acc[ai][bj][m][n] = __builtin_amdgcn_mfma_f32_16x16x32_bf16(Bt[n][k], At[m][k], acc[ai][bj][m][n], 0, 0, 0); __builtin_amdgcn_s_setprio(0); } while (0)
; #define PG8_WAIT_V(n) asm volatile("s_waitcnt vmcnt(" #n ")" ::: "memory")
; #define PG8_WAIT_L(n) asm volatile("s_waitcnt lgkmcnt(" #n ")" ::: "memory")
; #define PG8_BAR __builtin_amdgcn_s_barrier()
; #define PG8_SCHED __builtin_amdgcn_sched_barrier(0)
; template <class Epi, class Sched, bool ALIGN_EPI = false, bool SP2 = false>
; __device__ __forceinline__ void gemm_phase(PG8_LAS unsigned char* lds, const Gemm g, const Sched& S, const Epi& E) {
;     ...
;             PG8_WAIT_V(8); PG8_WAIT_L(0); PG8_BAR; PG8_MMA(0, 0, At, B0); PG8_MMA(0, 1, At, B1); PG8_BAR; PG8_SCHED;
;             PG8_LDA(At, 0, 1); PG8_STAGE(PG8_SB(0, 0), b2, voffB); PG8_STAGE(PG8_SB(0, 1), b2 + hstep, voffB); PG8_STAGE(PG8_SA(0, 0), a2, voffA);
;             PG8_WAIT_V(8); PG8_WAIT_L(0); PG8_BAR; PG8_MMA(1, 0, At, B0); PG8_MMA(1, 1, At, B1); PG8_BAR; PG8_SCHED;
;             PG8_LDB(B0, 1, 0); PG8_LDB(B1, 1, 1); PG8_SCHED; PG8_LDA(At, 1, 0); PG8_STAGE(PG8_SA(0, 1), a2 + hstep, voffA);
;             PG8_WAIT_V(8); PG8_WAIT_L(0); PG8_BAR; PG8_MMA(0, 0, At, B0); PG8_MMA(0, 1, At, B1); PG8_BAR; PG8_SCHED;
	s_setprio 1
	s_waitcnt lgkmcnt(0)
	v_mfma_f32_16x16x32_bf16 v[60:63], v[144:147], v[186:189], 0
	v_mfma_f32_16x16x32_bf16 v[56:59], v[160:163], v[186:189], 0
	v_mfma_f32_16x16x32_bf16 v[40:43], v[160:163], v[194:197], 0
	v_mfma_f32_16x16x32_bf16 v[44:47], v[144:147], v[194:197], 0
	v_mfma_f32_16x16x32_bf16 v[28:31], v[144:147], v[208:211], 0
	v_mfma_f32_16x16x32_bf16 v[24:27], v[160:163], v[208:211], 0
	v_mfma_f32_16x16x32_bf16 v[8:11], v[160:163], v[216:219], 0
	v_mfma_f32_16x16x32_bf16 v[12:15], v[144:147], v[216:219], 0
	v_mfma_f32_16x16x32_bf16 v[60:63], v[156:159], v[190:193], v[60:63]
	v_mfma_f32_16x16x32_bf16 v[56:59], v[164:167], v[190:193], v[56:59]
	v_mfma_f32_16x16x32_bf16 v[40:43], v[164:167], v[198:201], v[40:43]
	v_mfma_f32_16x16x32_bf16 v[44:47], v[156:159], v[198:201], v[44:47]
	v_mfma_f32_16x16x32_bf16 v[28:31], v[156:159], v[212:215], v[28:31]
	v_mfma_f32_16x16x32_bf16 v[24:27], v[164:167], v[212:215], v[24:27]
	v_lshl_add_u64 v[226:227], s[62:63], 0, v[128:129]
	s_mov_b32 m0, s15
	s_nop 0
	global_load_lds_dwordx4 v[226:227], off
	v_mfma_f32_16x16x32_bf16 v[8:11], v[164:167], v[220:223], v[8:11]
	v_mfma_f32_16x16x32_bf16 v[12:15], v[156:159], v[220:223], v[12:15]
	s_setprio 0
	s_setprio 1
	v_mfma_f32_16x16x32_bf16 v[52:55], v[168:171], v[186:189], 0
	v_mfma_f32_16x16x32_bf16 v[48:51], v[176:179], v[186:189], 0
	v_mfma_f32_16x16x32_bf16 v[32:35], v[176:179], v[194:197], 0
	v_mfma_f32_16x16x32_bf16 v[36:39], v[168:171], v[194:197], 0
	v_mfma_f32_16x16x32_bf16 v[20:23], v[168:171], v[208:211], 0
	v_mfma_f32_16x16x32_bf16 v[16:19], v[176:179], v[208:211], 0
	v_mfma_f32_16x16x32_bf16 v[0:3], v[176:179], v[216:219], 0
	v_mfma_f32_16x16x32_bf16 v[4:7], v[168:171], v[216:219], 0
	v_mfma_f32_16x16x32_bf16 v[52:55], v[172:175], v[190:193], v[52:55]
	v_mfma_f32_16x16x32_bf16 v[48:51], v[182:185], v[190:193], v[48:51]
	v_mfma_f32_16x16x32_bf16 v[32:35], v[182:185], v[198:201], v[32:35]
	v_mfma_f32_16x16x32_bf16 v[36:39], v[172:175], v[198:201], v[36:39]
	v_mfma_f32_16x16x32_bf16 v[20:23], v[172:175], v[212:215], v[20:23]
	v_mfma_f32_16x16x32_bf16 v[16:19], v[182:185], v[212:215], v[16:19]
	v_lshl_add_u64 v[228:229], s[62:63], 0, v[132:133]
	s_mov_b32 m0, s34
	s_nop 0
	global_load_lds_dwordx4 v[228:229], off
	v_mfma_f32_16x16x32_bf16 v[0:3], v[182:185], v[220:223], v[0:3]
	v_mfma_f32_16x16x32_bf16 v[4:7], v[172:175], v[220:223], v[4:7]
	s_setprio 0
	s_barrier
	s_add_i32 s3, 0, 0x18000
	v_add_u32_e32 v155, s3, v149
	s_add_i32 s33, 0, 0x1c000
	ds_read_b128 v[144:147], v155
	ds_read_b128 v[156:159], v155 offset:1024
	ds_read_b128 v[160:163], v155 offset:2048
	ds_read_b128 v[164:167], v155 offset:3072
	v_add_u32_e32 v155, s33, v149
	ds_read_b128 v[168:171], v155
	ds_read_b128 v[172:175], v155 offset:1024
	ds_read_b128 v[176:179], v155 offset:2048
	ds_read_b128 v[182:185], v155 offset:3072
	s_add_u32 s62, s62, 0x20000
	s_addc_u32 s63, s63, 0
	s_mov_b32 m0, s57
	v_lshl_add_u64 v[230:231], s[62:63], 0, v[128:129]
	ds_read_b128 v[186:189], v153 offset:32768
	ds_read_b128 v[190:193], v153 offset:33792
	ds_read_b128 v[194:197], v153 offset:34816
	ds_read_b128 v[198:201], v153 offset:35840
	ds_read_b128 v[208:211], v153 offset:36864
	ds_read_b128 v[212:215], v153 offset:37888
	ds_read_b128 v[216:219], v153 offset:38912
	ds_read_b128 v[220:223], v153 offset:39936
	global_load_lds_dwordx4 v[230:231], off
	v_lshl_add_u64 v[230:231], s[62:63], 0, v[132:133]
	s_mov_b32 m0, s64
	s_nop 0
	global_load_lds_dwordx4 v[230:231], off
	s_waitcnt vmcnt(8)
	s_waitcnt lgkmcnt(0)
	s_barrier
	s_setprio 1
	s_waitcnt lgkmcnt(0)
	v_mfma_f32_16x16x32_bf16 v[124:127], v[144:147], v[186:189], v[124:127]
	v_mfma_f32_16x16x32_bf16 v[120:123], v[160:163], v[186:189], v[120:123]
	v_mfma_f32_16x16x32_bf16 v[104:107], v[160:163], v[194:197], v[104:107]
	v_mfma_f32_16x16x32_bf16 v[108:111], v[144:147], v[194:197], v[108:111]
	v_mfma_f32_16x16x32_bf16 v[92:95], v[144:147], v[208:211], v[92:95]
	v_mfma_f32_16x16x32_bf16 v[88:91], v[160:163], v[208:211], v[88:91]
	v_mfma_f32_16x16x32_bf16 v[72:75], v[160:163], v[216:219], v[72:75]
	v_mfma_f32_16x16x32_bf16 v[76:79], v[144:147], v[216:219], v[76:79]
	v_mfma_f32_16x16x32_bf16 v[124:127], v[156:159], v[190:193], v[124:127]
	v_mfma_f32_16x16x32_bf16 v[120:123], v[164:167], v[190:193], v[120:123]
	v_mfma_f32_16x16x32_bf16 v[104:107], v[164:167], v[198:201], v[104:107]
	v_mfma_f32_16x16x32_bf16 v[108:111], v[156:159], v[198:201], v[108:111]
	v_mfma_f32_16x16x32_bf16 v[92:95], v[156:159], v[212:215], v[92:95]
	v_mfma_f32_16x16x32_bf16 v[88:91], v[164:167], v[212:215], v[88:91]
	v_mfma_f32_16x16x32_bf16 v[72:75], v[164:167], v[220:223], v[72:75]
	v_mfma_f32_16x16x32_bf16 v[76:79], v[156:159], v[220:223], v[76:79]
	s_setprio 0
	s_setprio 1
	v_mfma_f32_16x16x32_bf16 v[116:119], v[168:171], v[186:189], v[116:119]
	v_mfma_f32_16x16x32_bf16 v[112:115], v[176:179], v[186:189], v[112:115]
	v_mfma_f32_16x16x32_bf16 v[96:99], v[176:179], v[194:197], v[96:99]
	v_mfma_f32_16x16x32_bf16 v[100:103], v[168:171], v[194:197], v[100:103]
	v_mfma_f32_16x16x32_bf16 v[84:87], v[168:171], v[208:211], v[84:87]
	v_mfma_f32_16x16x32_bf16 v[80:83], v[176:179], v[208:211], v[80:83]
	v_mfma_f32_16x16x32_bf16 v[64:67], v[176:179], v[216:219], v[64:67]
	v_mfma_f32_16x16x32_bf16 v[68:71], v[168:171], v[216:219], v[68:71]
	v_mfma_f32_16x16x32_bf16 v[116:119], v[172:175], v[190:193], v[116:119]
	v_mfma_f32_16x16x32_bf16 v[112:115], v[182:185], v[190:193], v[112:115]
	v_mfma_f32_16x16x32_bf16 v[96:99], v[182:185], v[198:201], v[96:99]
	v_mfma_f32_16x16x32_bf16 v[100:103], v[172:175], v[198:201], v[100:103]
	v_mfma_f32_16x16x32_bf16 v[84:87], v[172:175], v[212:215], v[84:87]
	v_mfma_f32_16x16x32_bf16 v[80:83], v[182:185], v[212:215], v[80:83]
	v_mfma_f32_16x16x32_bf16 v[64:67], v[182:185], v[220:223], v[64:67]
	v_mfma_f32_16x16x32_bf16 v[68:71], v[172:175], v[220:223], v[68:71]
	s_setprio 0
	s_barrier
; #define PG8_STAGE(bufoff, gbase, voff) do { _Pragma("unroll") for (int _i = 0; _i < 2; ++_i) \
;         __builtin_amdgcn_global_load_lds((const unsigned*)((const char*)(gbase) + (voff)[_i]), (PG8_LAS unsigned*)(lds + (bufoff) + ldsw + _i * 8192), 16, 0, 0); } while (0)
; #define PG8_LDA(dst, b, h) do { _Pragma("unroll") for (int m = 0; m < 4; ++m) _Pragma("unroll") for (int k = 0; k < 2; ++k) dst[m][k] = *(const PG8_LAS bf16x8*)(lds + PG8_SA(b, h) + aoff + m * 2048 + k * 1024); } while (0)
; #define PG8_LDB(dst, b, h) do { _Pragma("unroll") for (int n = 0; n < 2; ++n) _Pragma("unroll") for (int k = 0; k < 2; ++k) dst[n][k] = *(const PG8_LAS bf16x8*)(lds + PG8_SB(b, h) + boff + n * 2048 + k * 1024); } while (0)
; #define PG8_MMA(ai, bj, At, Bt) do { __builtin_amdgcn_s_setprio(1); _Pragma("unroll") for (int m = 0; m < 4; ++m) _Pragma("unroll") for (int n = 0; n < 2; ++n) _Pragma("unroll") for (int k = 0; k < 2; ++k) \
;         acc[ai][bj][m][n] = __builtin_amdgcn_mfma_f32_16x16x32_bf16(Bt[n][k], At[m][k], acc[ai][bj][m][n], 0, 0, 0); __builtin_amdgcn_s_setprio(0); } while (0)
; #define PG8_WAIT_V(n) asm volatile("s_waitcnt vmcnt(" #n ")" ::: "memory")
; #define PG8_WAIT_L(n) asm volatile("s_waitcnt lgkmcnt(" #n ")" ::: "memory")
; #define PG8_BAR __builtin_amdgcn_s_barrier()
; #define PG8_SCHED __builtin_amdgcn_sched_barrier(0)
; template <class Epi, class Sched, bool ALIGN_EPI = false, bool SP2 = false>
; __device__ __forceinline__ void gemm_phase(PG8_LAS unsigned char* lds, const Gemm g, const Sched& S, const Epi& E) {
;     ...
;             PG8_LDB(B0, 0, 0); PG8_LDB(B1, 0, 1); PG8_SCHED; PG8_LDA(At, 0, 0); PG8_STAGE(PG8_SA(1, 1), a1 + hstep, voffA);
;     ...
;             PG8_LDA(At, 1, 1); PG8_STAGE(PG8_SB(1, 0), b3, voffB); PG8_STAGE(PG8_SB(1, 1), b3 + hstep, voffB); PG8_STAGE(PG8_SA(1, 0), a3, voffA);
;             PG8_WAIT_V(8); PG8_WAIT_L(0); PG8_BAR; PG8_MMA(1, 0, At, B0); PG8_MMA(1, 1, At, B1); PG8_BAR; PG8_SCHED;
	s_add_i32 s3, s3, s14
	v_lshl_add_u64 v[202:203], v[202:203], 0, s[38:39]
	s_mov_b32 m0, s3
	ds_read_b128 v[186:189], v153 offset:49152
	ds_read_b128 v[190:193], v153 offset:50176
	ds_read_b128 v[194:197], v153 offset:51200
	ds_read_b128 v[198:201], v153 offset:52224
	ds_read_b128 v[208:211], v153 offset:53248
	ds_read_b128 v[212:215], v153 offset:54272
	ds_read_b128 v[216:219], v153 offset:55296
	ds_read_b128 v[220:223], v153 offset:56320
	global_load_lds_dwordx4 v[202:203], off
	s_add_i32 m0, s3, 0x2000
	s_add_u32 s60, s60, 0x20080
	v_lshl_add_u64 v[202:203], v[224:225], 0, s[38:39]
	s_addc_u32 s61, s61, 0
	s_add_i32 s3, s33, s14
	global_load_lds_dwordx4 v[202:203], off
	v_lshl_add_u64 v[202:203], s[60:61], 0, v[130:131]
	s_mov_b32 m0, s3
	s_nop 0
	global_load_lds_dwordx4 v[202:203], off
	v_lshl_add_u64 v[202:203], s[60:61], 0, v[134:135]
	s_add_i32 m0, s3, 0x2000
	s_nop 0
	global_load_lds_dwordx4 v[202:203], off
	s_waitcnt vmcnt(6)
	s_waitcnt lgkmcnt(0)
	s_barrier
	s_setprio 1
	s_waitcnt lgkmcnt(0)
	v_mfma_f32_16x16x32_bf16 v[60:63], v[144:147], v[186:189], v[60:63]
	v_mfma_f32_16x16x32_bf16 v[56:59], v[160:163], v[186:189], v[56:59]
	v_mfma_f32_16x16x32_bf16 v[40:43], v[160:163], v[194:197], v[40:43]
	v_mfma_f32_16x16x32_bf16 v[44:47], v[144:147], v[194:197], v[44:47]
	v_mfma_f32_16x16x32_bf16 v[28:31], v[144:147], v[208:211], v[28:31]
	v_mfma_f32_16x16x32_bf16 v[24:27], v[160:163], v[208:211], v[24:27]
	v_mfma_f32_16x16x32_bf16 v[8:11], v[160:163], v[216:219], v[8:11]
	v_mfma_f32_16x16x32_bf16 v[12:15], v[144:147], v[216:219], v[12:15]
	v_mfma_f32_16x16x32_bf16 v[60:63], v[156:159], v[190:193], v[60:63]
	v_mfma_f32_16x16x32_bf16 v[56:59], v[164:167], v[190:193], v[56:59]
	v_mfma_f32_16x16x32_bf16 v[40:43], v[164:167], v[198:201], v[40:43]
	v_mfma_f32_16x16x32_bf16 v[44:47], v[156:159], v[198:201], v[44:47]
	v_mfma_f32_16x16x32_bf16 v[28:31], v[156:159], v[212:215], v[28:31]
	v_mfma_f32_16x16x32_bf16 v[24:27], v[164:167], v[212:215], v[24:27]
	v_lshl_add_u64 v[202:203], v[226:227], 0, s[38:39]
	s_mov_b32 m0, s66
	s_nop 0
	global_load_lds_dwordx4 v[202:203], off
	v_mfma_f32_16x16x32_bf16 v[8:11], v[164:167], v[220:223], v[8:11]
	v_mfma_f32_16x16x32_bf16 v[12:15], v[156:159], v[220:223], v[12:15]
	s_setprio 0
	s_setprio 1
	v_mfma_f32_16x16x32_bf16 v[52:55], v[168:171], v[186:189], v[52:55]
	v_mfma_f32_16x16x32_bf16 v[48:51], v[176:179], v[186:189], v[48:51]
	v_mfma_f32_16x16x32_bf16 v[32:35], v[176:179], v[194:197], v[32:35]
	v_mfma_f32_16x16x32_bf16 v[36:39], v[168:171], v[194:197], v[36:39]
	v_mfma_f32_16x16x32_bf16 v[20:23], v[168:171], v[208:211], v[20:23]
	v_mfma_f32_16x16x32_bf16 v[16:19], v[176:179], v[208:211], v[16:19]
	v_mfma_f32_16x16x32_bf16 v[0:3], v[176:179], v[216:219], v[0:3]
	v_mfma_f32_16x16x32_bf16 v[4:7], v[168:171], v[216:219], v[4:7]
	v_mfma_f32_16x16x32_bf16 v[52:55], v[172:175], v[190:193], v[52:55]
	v_mfma_f32_16x16x32_bf16 v[48:51], v[182:185], v[190:193], v[48:51]
	v_mfma_f32_16x16x32_bf16 v[32:35], v[182:185], v[198:201], v[32:35]
	v_mfma_f32_16x16x32_bf16 v[36:39], v[172:175], v[198:201], v[36:39]
	v_mfma_f32_16x16x32_bf16 v[20:23], v[172:175], v[212:215], v[20:23]
	v_mfma_f32_16x16x32_bf16 v[16:19], v[182:185], v[212:215], v[16:19]
	v_lshl_add_u64 v[202:203], v[228:229], 0, s[38:39]
	s_mov_b32 m0, s67
	s_nop 0
	global_load_lds_dwordx4 v[202:203], off
	v_mfma_f32_16x16x32_bf16 v[0:3], v[182:185], v[220:223], v[0:3]
	v_mfma_f32_16x16x32_bf16 v[4:7], v[172:175], v[220:223], v[4:7]
	s_setprio 0
	s_barrier
	s_add_i32 s87, s87, 2
	s_add_u32 s58, s58, 0x100
	s_addc_u32 s59, s59, 0
	s_add_u32 s85, s85, 0x100
	s_addc_u32 s86, s86, 0
.LBB0_873:
	ds_read_b128 v[144:147], v151
	ds_read_b128 v[156:159], v151 offset:1024
	ds_read_b128 v[160:163], v151 offset:2048
	ds_read_b128 v[164:167], v151 offset:3072
	ds_read_b128 v[168:171], v152
	ds_read_b128 v[172:175], v152 offset:1024
	ds_read_b128 v[176:179], v152 offset:2048
	ds_read_b128 v[182:185], v152 offset:3072
	s_add_u32 s3, s58, 0xfffe0080
	s_addc_u32 s33, s59, -1
	s_cmp_eq_u32 s87, 4
	s_cselect_b32 s63, s49, s33
	s_cselect_b32 s62, s55, s3
	s_cselect_b32 s61, s45, s86
	s_cselect_b32 s60, s84, s85
	v_lshl_add_u64 v[202:203], s[58:59], 0, v[136:137]
	s_add_i32 m0, s15, 0xc000
	ds_read_b128 v[186:189], v153
	ds_read_b128 v[190:193], v153 offset:1024
	ds_read_b128 v[194:197], v153 offset:2048
	ds_read_b128 v[198:201], v153 offset:3072
	ds_read_b128 v[208:211], v153 offset:4096
	ds_read_b128 v[212:215], v153 offset:5120
	ds_read_b128 v[216:219], v153 offset:6144
	ds_read_b128 v[220:223], v153 offset:7168
	global_load_lds_dwordx4 v[202:203], off
	v_lshl_add_u64 v[202:203], s[58:59], 0, v[138:139]
	s_add_i32 m0, s15, 0xe000
	s_nop 0
	global_load_lds_dwordx4 v[202:203], off
	s_waitcnt vmcnt(8)
	s_waitcnt lgkmcnt(0)
	s_barrier
; #define PG8_STAGE(bufoff, gbase, voff) do { _Pragma("unroll") for (int _i = 0; _i < 2; ++_i) \
;         __builtin_amdgcn_global_load_lds((const unsigned*)((const char*)(gbase) + (voff)[_i]), (PG8_LAS unsigned*)(lds + (bufoff) + ldsw + _i * 8192), 16, 0, 0); } while (0)
; #define PG8_LDA(dst, b, h) do { _Pragma("unroll") for (int m = 0; m < 4; ++m) _Pragma("unroll") for (int k = 0; k < 2; ++k) dst[m][k] = *(const PG8_LAS bf16x8*)(lds + PG8_SA(b, h) + aoff + m * 2048 + k * 1024); } while (0)
; #define PG8_MMA(ai, bj, At, Bt) do { __builtin_amdgcn_s_setprio(1); _Pragma("unroll") for (int m = 0; m < 4; ++m) _Pragma("unroll") for (int n = 0; n < 2; ++n) _Pragma("unroll") for (int k = 0; k < 2; ++k) \
;         acc[ai][bj][m][n] = __builtin_amdgcn_mfma_f32_16x16x32_bf16(Bt[n][k], At[m][k], acc[ai][bj][m][n], 0, 0, 0); __builtin_amdgcn_s_setprio(0); } while (0)
; #define PG8_WAIT_V(n) asm volatile("s_waitcnt vmcnt(" #n ")" ::: "memory")
; #define PG8_WAIT_L(n) asm volatile("s_waitcnt lgkmcnt(" #n ")" ::: "memory")
; #define PG8_BAR __builtin_amdgcn_s_barrier()
; #define PG8_SCHED __builtin_amdgcn_sched_barrier(0)
; template <class Epi, class Sched, bool ALIGN_EPI = false, bool SP2 = false>
; __device__ __forceinline__ void gemm_phase(PG8_LAS unsigned char* lds, const Gemm g, const Sched& S, const Epi& E) {
;     ...
;             PG8_WAIT_V(8); PG8_WAIT_L(0); PG8_BAR; PG8_MMA(0, 0, At, B0); PG8_MMA(0, 1, At, B1); PG8_BAR; PG8_SCHED;
;             PG8_LDA(At, 0, 1); PG8_STAGE(PG8_SB(0, 0), b2, voffB); PG8_STAGE(PG8_SB(0, 1), b2 + hstep, voffB); PG8_STAGE(PG8_SA(0, 0), a2, voffA);
;             PG8_WAIT_V(8); PG8_WAIT_L(0); PG8_BAR; PG8_MMA(1, 0, At, B0); PG8_MMA(1, 1, At, B1); PG8_BAR; PG8_SCHED;
	s_setprio 1
	s_waitcnt lgkmcnt(0)
	v_mfma_f32_16x16x32_bf16 v[124:127], v[144:147], v[186:189], v[124:127]
	v_mfma_f32_16x16x32_bf16 v[120:123], v[160:163], v[186:189], v[120:123]
	v_mfma_f32_16x16x32_bf16 v[104:107], v[160:163], v[194:197], v[104:107]
	v_mfma_f32_16x16x32_bf16 v[108:111], v[144:147], v[194:197], v[108:111]
	v_mfma_f32_16x16x32_bf16 v[92:95], v[144:147], v[208:211], v[92:95]
	v_mfma_f32_16x16x32_bf16 v[88:91], v[160:163], v[208:211], v[88:91]
	v_mfma_f32_16x16x32_bf16 v[72:75], v[160:163], v[216:219], v[72:75]
	v_mfma_f32_16x16x32_bf16 v[76:79], v[144:147], v[216:219], v[76:79]
	v_mfma_f32_16x16x32_bf16 v[124:127], v[156:159], v[190:193], v[124:127]
	v_mfma_f32_16x16x32_bf16 v[120:123], v[164:167], v[190:193], v[120:123]
	v_mfma_f32_16x16x32_bf16 v[104:107], v[164:167], v[198:201], v[104:107]
	v_mfma_f32_16x16x32_bf16 v[108:111], v[156:159], v[198:201], v[108:111]
	v_mfma_f32_16x16x32_bf16 v[92:95], v[156:159], v[212:215], v[92:95]
	v_mfma_f32_16x16x32_bf16 v[88:91], v[164:167], v[212:215], v[88:91]
	v_mfma_f32_16x16x32_bf16 v[72:75], v[164:167], v[220:223], v[72:75]
	v_mfma_f32_16x16x32_bf16 v[76:79], v[156:159], v[220:223], v[76:79]
	s_setprio 0
	s_setprio 1
	v_mfma_f32_16x16x32_bf16 v[116:119], v[168:171], v[186:189], v[116:119]
	v_mfma_f32_16x16x32_bf16 v[112:115], v[176:179], v[186:189], v[112:115]
	v_mfma_f32_16x16x32_bf16 v[96:99], v[176:179], v[194:197], v[96:99]
	v_mfma_f32_16x16x32_bf16 v[100:103], v[168:171], v[194:197], v[100:103]
	v_mfma_f32_16x16x32_bf16 v[84:87], v[168:171], v[208:211], v[84:87]
	v_mfma_f32_16x16x32_bf16 v[80:83], v[176:179], v[208:211], v[80:83]
	v_mfma_f32_16x16x32_bf16 v[64:67], v[176:179], v[216:219], v[64:67]
	v_mfma_f32_16x16x32_bf16 v[68:71], v[168:171], v[216:219], v[68:71]
	v_mfma_f32_16x16x32_bf16 v[116:119], v[172:175], v[190:193], v[116:119]
	v_mfma_f32_16x16x32_bf16 v[112:115], v[182:185], v[190:193], v[112:115]
	v_mfma_f32_16x16x32_bf16 v[96:99], v[182:185], v[198:201], v[96:99]
	v_mfma_f32_16x16x32_bf16 v[100:103], v[172:175], v[198:201], v[100:103]
	v_mfma_f32_16x16x32_bf16 v[84:87], v[172:175], v[212:215], v[84:87]
	v_mfma_f32_16x16x32_bf16 v[80:83], v[182:185], v[212:215], v[80:83]
	v_mfma_f32_16x16x32_bf16 v[64:67], v[182:185], v[220:223], v[64:67]
	v_mfma_f32_16x16x32_bf16 v[68:71], v[172:175], v[220:223], v[68:71]
	s_setprio 0
	s_barrier
	s_add_i32 s3, s74, s14
	v_lshl_add_u64 v[202:203], s[60:61], 0, v[130:131]
	s_mov_b32 m0, s3
	ds_read_b128 v[186:189], v153 offset:16384
	ds_read_b128 v[190:193], v153 offset:17408
	ds_read_b128 v[194:197], v153 offset:18432
	ds_read_b128 v[198:201], v153 offset:19456
	ds_read_b128 v[208:211], v153 offset:20480
	ds_read_b128 v[212:215], v153 offset:21504
	ds_read_b128 v[216:219], v153 offset:22528
	ds_read_b128 v[220:223], v153 offset:23552
	global_load_lds_dwordx4 v[202:203], off
	s_add_i32 m0, s3, 0x2000
	s_add_u32 s78, s60, 0x20000
	v_lshl_add_u64 v[224:225], s[60:61], 0, v[134:135]
	s_addc_u32 s79, s61, 0
	s_add_i32 s3, s75, s14
	global_load_lds_dwordx4 v[224:225], off
	v_lshl_add_u64 v[226:227], s[78:79], 0, v[130:131]
	s_mov_b32 m0, s3
	global_load_lds_dwordx4 v[226:227], off
	v_lshl_add_u64 v[226:227], s[78:79], 0, v[134:135]
	s_add_i32 m0, s3, 0x2000
	s_nop 0
	global_load_lds_dwordx4 v[226:227], off
	s_waitcnt vmcnt(6)
	s_waitcnt lgkmcnt(0)
	s_barrier
	s_setprio 1
	s_waitcnt lgkmcnt(0)
	v_mfma_f32_16x16x32_bf16 v[60:63], v[144:147], v[186:189], v[60:63]
	v_mfma_f32_16x16x32_bf16 v[56:59], v[160:163], v[186:189], v[56:59]
	v_mfma_f32_16x16x32_bf16 v[40:43], v[160:163], v[194:197], v[40:43]
	v_mfma_f32_16x16x32_bf16 v[44:47], v[144:147], v[194:197], v[44:47]
	v_mfma_f32_16x16x32_bf16 v[28:31], v[144:147], v[208:211], v[28:31]
	v_mfma_f32_16x16x32_bf16 v[24:27], v[160:163], v[208:211], v[24:27]
	v_mfma_f32_16x16x32_bf16 v[8:11], v[160:163], v[216:219], v[8:11]
	v_mfma_f32_16x16x32_bf16 v[12:15], v[144:147], v[216:219], v[12:15]
	v_mfma_f32_16x16x32_bf16 v[60:63], v[156:159], v[190:193], v[60:63]
	v_mfma_f32_16x16x32_bf16 v[56:59], v[164:167], v[190:193], v[56:59]
	v_mfma_f32_16x16x32_bf16 v[40:43], v[164:167], v[198:201], v[40:43]
	v_mfma_f32_16x16x32_bf16 v[44:47], v[156:159], v[198:201], v[44:47]
	v_mfma_f32_16x16x32_bf16 v[28:31], v[156:159], v[212:215], v[28:31]
	v_mfma_f32_16x16x32_bf16 v[24:27], v[164:167], v[212:215], v[24:27]
	v_lshl_add_u64 v[226:227], s[62:63], 0, v[128:129]
	s_mov_b32 m0, s15
	s_nop 0
	global_load_lds_dwordx4 v[226:227], off
	v_mfma_f32_16x16x32_bf16 v[8:11], v[164:167], v[220:223], v[8:11]
	v_mfma_f32_16x16x32_bf16 v[12:15], v[156:159], v[220:223], v[12:15]
	s_setprio 0
	s_setprio 1
	v_mfma_f32_16x16x32_bf16 v[52:55], v[168:171], v[186:189], v[52:55]
	v_mfma_f32_16x16x32_bf16 v[48:51], v[176:179], v[186:189], v[48:51]
	v_mfma_f32_16x16x32_bf16 v[32:35], v[176:179], v[194:197], v[32:35]
	v_mfma_f32_16x16x32_bf16 v[36:39], v[168:171], v[194:197], v[36:39]
	v_mfma_f32_16x16x32_bf16 v[20:23], v[168:171], v[208:211], v[20:23]
	v_mfma_f32_16x16x32_bf16 v[16:19], v[176:179], v[208:211], v[16:19]
	v_mfma_f32_16x16x32_bf16 v[0:3], v[176:179], v[216:219], v[0:3]
	v_mfma_f32_16x16x32_bf16 v[4:7], v[168:171], v[216:219], v[4:7]
	v_mfma_f32_16x16x32_bf16 v[52:55], v[172:175], v[190:193], v[52:55]
	v_mfma_f32_16x16x32_bf16 v[48:51], v[182:185], v[190:193], v[48:51]
	v_mfma_f32_16x16x32_bf16 v[32:35], v[182:185], v[198:201], v[32:35]
	v_mfma_f32_16x16x32_bf16 v[36:39], v[172:175], v[198:201], v[36:39]
	v_mfma_f32_16x16x32_bf16 v[20:23], v[172:175], v[212:215], v[20:23]
	v_mfma_f32_16x16x32_bf16 v[16:19], v[182:185], v[212:215], v[16:19]
	v_lshl_add_u64 v[228:229], s[62:63], 0, v[132:133]
	s_mov_b32 m0, s34
	s_nop 0
	global_load_lds_dwordx4 v[228:229], off
	v_mfma_f32_16x16x32_bf16 v[0:3], v[182:185], v[220:223], v[0:3]
	v_mfma_f32_16x16x32_bf16 v[4:7], v[172:175], v[220:223], v[4:7]
	s_setprio 0
	s_barrier
; #define PG8_STAGE(bufoff, gbase, voff) do { _Pragma("unroll") for (int _i = 0; _i < 2; ++_i) \
;         __builtin_amdgcn_global_load_lds((const unsigned*)((const char*)(gbase) + (voff)[_i]), (PG8_LAS unsigned*)(lds + (bufoff) + ldsw + _i * 8192), 16, 0, 0); } while (0)
; #define PG8_LDA(dst, b, h) do { _Pragma("unroll") for (int m = 0; m < 4; ++m) _Pragma("unroll") for (int k = 0; k < 2; ++k) dst[m][k] = *(const PG8_LAS bf16x8*)(lds + PG8_SA(b, h) + aoff + m * 2048 + k * 1024); } while (0)
; #define PG8_LDB(dst, b, h) do { _Pragma("unroll") for (int n = 0; n < 2; ++n) _Pragma("unroll") for (int k = 0; k < 2; ++k) dst[n][k] = *(const PG8_LAS bf16x8*)(lds + PG8_SB(b, h) + boff + n * 2048 + k * 1024); } while (0)
; #define PG8_MMA(ai, bj, At, Bt) do { __builtin_amdgcn_s_setprio(1); _Pragma("unroll") for (int m = 0; m < 4; ++m) _Pragma("unroll") for (int n = 0; n < 2; ++n) _Pragma("unroll") for (int k = 0; k < 2; ++k) \
;         acc[ai][bj][m][n] = __builtin_amdgcn_mfma_f32_16x16x32_bf16(Bt[n][k], At[m][k], acc[ai][bj][m][n], 0, 0, 0); __builtin_amdgcn_s_setprio(0); } while (0)
; #define PG8_WAIT_V(n) asm volatile("s_waitcnt vmcnt(" #n ")" ::: "memory")
; #define PG8_WAIT_L(n) asm volatile("s_waitcnt lgkmcnt(" #n ")" ::: "memory")
; #define PG8_BAR __builtin_amdgcn_s_barrier()
; #define PG8_SCHED __builtin_amdgcn_sched_barrier(0)
; template <class Epi, class Sched, bool ALIGN_EPI = false, bool SP2 = false>
; __device__ __forceinline__ void gemm_phase(PG8_LAS unsigned char* lds, const Gemm g, const Sched& S, const Epi& E) {
;     ...
;             PG8_LDB(B0, 1, 0); PG8_LDB(B1, 1, 1); PG8_SCHED; PG8_LDA(At, 1, 0); PG8_STAGE(PG8_SA(0, 1), a2 + hstep, voffA);
;             PG8_WAIT_V(8); PG8_WAIT_L(0); PG8_BAR; PG8_MMA(0, 0, At, B0); PG8_MMA(0, 1, At, B1); PG8_BAR; PG8_SCHED;
	s_add_i32 s3, 0, 0x18000
	v_add_u32_e32 v155, s3, v149
	s_add_i32 s33, 0, 0x1c000
	ds_read_b128 v[144:147], v155
	ds_read_b128 v[156:159], v155 offset:1024
	ds_read_b128 v[160:163], v155 offset:2048
	ds_read_b128 v[164:167], v155 offset:3072
	v_add_u32_e32 v155, s33, v149
	ds_read_b128 v[168:171], v155
	ds_read_b128 v[172:175], v155 offset:1024
	ds_read_b128 v[176:179], v155 offset:2048
	ds_read_b128 v[182:185], v155 offset:3072
	s_add_u32 s62, s62, 0x20000
	s_addc_u32 s63, s63, 0
	s_mov_b32 m0, s57
	v_lshl_add_u64 v[230:231], s[62:63], 0, v[128:129]
	ds_read_b128 v[186:189], v153 offset:32768
	ds_read_b128 v[190:193], v153 offset:33792
	ds_read_b128 v[194:197], v153 offset:34816
	ds_read_b128 v[198:201], v153 offset:35840
	ds_read_b128 v[208:211], v153 offset:36864
	ds_read_b128 v[212:215], v153 offset:37888
	ds_read_b128 v[216:219], v153 offset:38912
	ds_read_b128 v[220:223], v153 offset:39936
	global_load_lds_dwordx4 v[230:231], off
	v_lshl_add_u64 v[230:231], s[62:63], 0, v[132:133]
	s_mov_b32 m0, s64
	s_nop 0
	global_load_lds_dwordx4 v[230:231], off
	s_waitcnt vmcnt(8)
	s_waitcnt lgkmcnt(0)
	s_barrier
	s_setprio 1
	s_waitcnt lgkmcnt(0)
	v_mfma_f32_16x16x32_bf16 v[124:127], v[144:147], v[186:189], v[124:127]
	v_mfma_f32_16x16x32_bf16 v[120:123], v[160:163], v[186:189], v[120:123]
	v_mfma_f32_16x16x32_bf16 v[104:107], v[160:163], v[194:197], v[104:107]
	v_mfma_f32_16x16x32_bf16 v[108:111], v[144:147], v[194:197], v[108:111]
	v_mfma_f32_16x16x32_bf16 v[92:95], v[144:147], v[208:211], v[92:95]
	v_mfma_f32_16x16x32_bf16 v[88:91], v[160:163], v[208:211], v[88:91]
	v_mfma_f32_16x16x32_bf16 v[72:75], v[160:163], v[216:219], v[72:75]
	v_mfma_f32_16x16x32_bf16 v[76:79], v[144:147], v[216:219], v[76:79]
	v_mfma_f32_16x16x32_bf16 v[124:127], v[156:159], v[190:193], v[124:127]
	v_mfma_f32_16x16x32_bf16 v[120:123], v[164:167], v[190:193], v[120:123]
	v_mfma_f32_16x16x32_bf16 v[104:107], v[164:167], v[198:201], v[104:107]
	v_mfma_f32_16x16x32_bf16 v[108:111], v[156:159], v[198:201], v[108:111]
	v_mfma_f32_16x16x32_bf16 v[92:95], v[156:159], v[212:215], v[92:95]
	v_mfma_f32_16x16x32_bf16 v[88:91], v[164:167], v[212:215], v[88:91]
	v_mfma_f32_16x16x32_bf16 v[72:75], v[164:167], v[220:223], v[72:75]
	v_mfma_f32_16x16x32_bf16 v[76:79], v[156:159], v[220:223], v[76:79]
	s_setprio 0
	s_setprio 1
	v_mfma_f32_16x16x32_bf16 v[116:119], v[168:171], v[186:189], v[116:119]
	v_mfma_f32_16x16x32_bf16 v[112:115], v[176:179], v[186:189], v[112:115]
	v_mfma_f32_16x16x32_bf16 v[96:99], v[176:179], v[194:197], v[96:99]
	v_mfma_f32_16x16x32_bf16 v[100:103], v[168:171], v[194:197], v[100:103]
	v_mfma_f32_16x16x32_bf16 v[84:87], v[168:171], v[208:211], v[84:87]
	v_mfma_f32_16x16x32_bf16 v[80:83], v[176:179], v[208:211], v[80:83]
	v_mfma_f32_16x16x32_bf16 v[64:67], v[176:179], v[216:219], v[64:67]
	v_mfma_f32_16x16x32_bf16 v[68:71], v[168:171], v[216:219], v[68:71]
	v_mfma_f32_16x16x32_bf16 v[116:119], v[172:175], v[190:193], v[116:119]
	v_mfma_f32_16x16x32_bf16 v[112:115], v[182:185], v[190:193], v[112:115]
	v_mfma_f32_16x16x32_bf16 v[96:99], v[182:185], v[198:201], v[96:99]
	v_mfma_f32_16x16x32_bf16 v[100:103], v[172:175], v[198:201], v[100:103]
	v_mfma_f32_16x16x32_bf16 v[84:87], v[172:175], v[212:215], v[84:87]
	v_mfma_f32_16x16x32_bf16 v[80:83], v[182:185], v[212:215], v[80:83]
	v_mfma_f32_16x16x32_bf16 v[64:67], v[182:185], v[220:223], v[64:67]
	v_mfma_f32_16x16x32_bf16 v[68:71], v[172:175], v[220:223], v[68:71]
	s_setprio 0
	s_barrier
; #define PG8_STAGE(bufoff, gbase, voff) do { _Pragma("unroll") for (int _i = 0; _i < 2; ++_i) \
;         __builtin_amdgcn_global_load_lds((const unsigned*)((const char*)(gbase) + (voff)[_i]), (PG8_LAS unsigned*)(lds + (bufoff) + ldsw + _i * 8192), 16, 0, 0); } while (0)
; #define PG8_LDA(dst, b, h) do { _Pragma("unroll") for (int m = 0; m < 4; ++m) _Pragma("unroll") for (int k = 0; k < 2; ++k) dst[m][k] = *(const PG8_LAS bf16x8*)(lds + PG8_SA(b, h) + aoff + m * 2048 + k * 1024); } while (0)
; #define PG8_MMA(ai, bj, At, Bt) do { __builtin_amdgcn_s_setprio(1); _Pragma("unroll") for (int m = 0; m < 4; ++m) _Pragma("unroll") for (int n = 0; n < 2; ++n) _Pragma("unroll") for (int k = 0; k < 2; ++k) \
;         acc[ai][bj][m][n] = __builtin_amdgcn_mfma_f32_16x16x32_bf16(Bt[n][k], At[m][k], acc[ai][bj][m][n], 0, 0, 0); __builtin_amdgcn_s_setprio(0); } while (0)
; #define PG8_WAIT_V(n) asm volatile("s_waitcnt vmcnt(" #n ")" ::: "memory")
; #define PG8_WAIT_L(n) asm volatile("s_waitcnt lgkmcnt(" #n ")" ::: "memory")
; #define PG8_BAR __builtin_amdgcn_s_barrier()
; #define PG8_SCHED __builtin_amdgcn_sched_barrier(0)
; template <class Epi, class Sched, bool ALIGN_EPI = false, bool SP2 = false>
; __device__ __forceinline__ void gemm_phase(PG8_LAS unsigned char* lds, const Gemm g, const Sched& S, const Epi& E) {
;     ...
;             PG8_LDA(At, 1, 1); PG8_STAGE(PG8_SB(1, 0), b3, voffB); PG8_STAGE(PG8_SB(1, 1), b3 + hstep, voffB); PG8_STAGE(PG8_SA(1, 0), a3, voffA);
;             PG8_WAIT_V(8); PG8_WAIT_L(0); PG8_BAR; PG8_MMA(1, 0, At, B0); PG8_MMA(1, 1, At, B1); PG8_BAR; PG8_SCHED;
;     ...
;         if constexpr (ALIGN_EPI) { if (wr == 0) PG8_BAR; }
	s_add_i32 s3, s3, s14
	v_lshl_add_u64 v[202:203], v[202:203], 0, s[38:39]
	s_mov_b32 m0, s3
	ds_read_b128 v[186:189], v153 offset:49152
	ds_read_b128 v[190:193], v153 offset:50176
	ds_read_b128 v[194:197], v153 offset:51200
	ds_read_b128 v[198:201], v153 offset:52224
	ds_read_b128 v[208:211], v153 offset:53248
	ds_read_b128 v[212:215], v153 offset:54272
	ds_read_b128 v[216:219], v153 offset:55296
	ds_read_b128 v[220:223], v153 offset:56320
	global_load_lds_dwordx4 v[202:203], off
	s_add_i32 m0, s3, 0x2000
	s_add_u32 s60, s60, 0x20080
	v_lshl_add_u64 v[202:203], v[224:225], 0, s[38:39]
	s_addc_u32 s61, s61, 0
	s_add_i32 s3, s33, s14
	global_load_lds_dwordx4 v[202:203], off
	v_lshl_add_u64 v[202:203], s[60:61], 0, v[130:131]
	s_mov_b32 m0, s3
	s_nop 0
	global_load_lds_dwordx4 v[202:203], off
	v_lshl_add_u64 v[202:203], s[60:61], 0, v[134:135]
	s_add_i32 m0, s3, 0x2000
	s_nop 0
	global_load_lds_dwordx4 v[202:203], off
	s_waitcnt vmcnt(6)
	s_waitcnt lgkmcnt(0)
	s_barrier
	s_setprio 1
	s_waitcnt lgkmcnt(0)
	v_mfma_f32_16x16x32_bf16 v[60:63], v[144:147], v[186:189], v[60:63]
	v_mfma_f32_16x16x32_bf16 v[56:59], v[160:163], v[186:189], v[56:59]
	v_mfma_f32_16x16x32_bf16 v[40:43], v[160:163], v[194:197], v[40:43]
	v_mfma_f32_16x16x32_bf16 v[44:47], v[144:147], v[194:197], v[44:47]
	v_mfma_f32_16x16x32_bf16 v[28:31], v[144:147], v[208:211], v[28:31]
	v_mfma_f32_16x16x32_bf16 v[24:27], v[160:163], v[208:211], v[24:27]
	v_mfma_f32_16x16x32_bf16 v[8:11], v[160:163], v[216:219], v[8:11]
	v_mfma_f32_16x16x32_bf16 v[12:15], v[144:147], v[216:219], v[12:15]
	v_mfma_f32_16x16x32_bf16 v[60:63], v[156:159], v[190:193], v[60:63]
	v_mfma_f32_16x16x32_bf16 v[56:59], v[164:167], v[190:193], v[56:59]
	v_mfma_f32_16x16x32_bf16 v[40:43], v[164:167], v[198:201], v[40:43]
	v_mfma_f32_16x16x32_bf16 v[44:47], v[156:159], v[198:201], v[44:47]
	v_mfma_f32_16x16x32_bf16 v[28:31], v[156:159], v[212:215], v[28:31]
	v_mfma_f32_16x16x32_bf16 v[24:27], v[164:167], v[212:215], v[24:27]
	v_lshl_add_u64 v[202:203], v[226:227], 0, s[38:39]
	s_mov_b32 m0, s66
	s_nop 0
	global_load_lds_dwordx4 v[202:203], off
	v_mfma_f32_16x16x32_bf16 v[8:11], v[164:167], v[220:223], v[8:11]
	v_mfma_f32_16x16x32_bf16 v[12:15], v[156:159], v[220:223], v[12:15]
	s_setprio 0
	s_setprio 1
	v_mfma_f32_16x16x32_bf16 v[52:55], v[168:171], v[186:189], v[52:55]
	v_mfma_f32_16x16x32_bf16 v[48:51], v[176:179], v[186:189], v[48:51]
	v_mfma_f32_16x16x32_bf16 v[32:35], v[176:179], v[194:197], v[32:35]
	v_mfma_f32_16x16x32_bf16 v[36:39], v[168:171], v[194:197], v[36:39]
	v_mfma_f32_16x16x32_bf16 v[20:23], v[168:171], v[208:211], v[20:23]
	v_mfma_f32_16x16x32_bf16 v[16:19], v[176:179], v[208:211], v[16:19]
	v_mfma_f32_16x16x32_bf16 v[0:3], v[176:179], v[216:219], v[0:3]
	v_mfma_f32_16x16x32_bf16 v[4:7], v[168:171], v[216:219], v[4:7]
	v_mfma_f32_16x16x32_bf16 v[52:55], v[172:175], v[190:193], v[52:55]
	v_mfma_f32_16x16x32_bf16 v[48:51], v[182:185], v[190:193], v[48:51]
	v_mfma_f32_16x16x32_bf16 v[32:35], v[182:185], v[198:201], v[32:35]
	v_mfma_f32_16x16x32_bf16 v[36:39], v[172:175], v[198:201], v[36:39]
	v_mfma_f32_16x16x32_bf16 v[20:23], v[172:175], v[212:215], v[20:23]
	v_mfma_f32_16x16x32_bf16 v[16:19], v[182:185], v[212:215], v[16:19]
	v_lshl_add_u64 v[202:203], v[228:229], 0, s[38:39]
	s_mov_b32 m0, s67
	s_nop 0
	global_load_lds_dwordx4 v[202:203], off
	v_mfma_f32_16x16x32_bf16 v[0:3], v[182:185], v[220:223], v[0:3]
	v_mfma_f32_16x16x32_bf16 v[4:7], v[172:175], v[220:223], v[4:7]
	s_setprio 0
	s_barrier
	s_add_i32 s87, s87, 2
	s_add_u32 s58, s58, 0x100
	s_addc_u32 s59, s59, 0
	s_add_u32 s85, s85, 0x100
	s_addc_u32 s86, s86, 0
	s_cmp_gt_u32 s87, 5
	s_cbranch_scc0 .LBB0_873
	s_and_b64 vcc, exec, s[42:43]
	s_cbranch_vccz .LBB0_876
	s_barrier

; #define PG8_STAGE(bufoff, gbase, voff) do { _Pragma("unroll") for (int _i = 0; _i < 2; ++_i) \
;         __builtin_amdgcn_global_load_lds((const unsigned*)((const char*)(gbase) + (voff)[_i]), (PG8_LAS unsigned*)(lds + (bufoff) + ldsw + _i * 8192), 16, 0, 0); } while (0)
; #define PG8_LDA(dst, b, h) do { _Pragma("unroll") for (int m = 0; m < 4; ++m) _Pragma("unroll") for (int k = 0; k < 2; ++k) dst[m][k] = *(const PG8_LAS bf16x8*)(lds + PG8_SA(b, h) + aoff + m * 2048 + k * 1024); } while (0)
; #define PG8_LDB(dst, b, h) do { _Pragma("unroll") for (int n = 0; n < 2; ++n) _Pragma("unroll") for (int k = 0; k < 2; ++k) dst[n][k] = *(const PG8_LAS bf16x8*)(lds + PG8_SB(b, h) + boff + n * 2048 + k * 1024); } while (0)
; #define PG8_MMA(ai, bj, At, Bt) do { __builtin_amdgcn_s_setprio(1); _Pragma("unroll") for (int m = 0; m < 4; ++m) _Pragma("unroll") for (int n = 0; n < 2; ++n) _Pragma("unroll") for (int k = 0; k < 2; ++k) \
;         acc[ai][bj][m][n] = __builtin_amdgcn_mfma_f32_16x16x32_bf16(Bt[n][k], At[m][k], acc[ai][bj][m][n], 0, 0, 0); __builtin_amdgcn_s_setprio(0); } while (0)
; #define PG8_WAIT_V(n) asm volatile("s_waitcnt vmcnt(" #n ")" ::: "memory")
; #define PG8_WAIT_L(n) asm volatile("s_waitcnt lgkmcnt(" #n ")" ::: "memory")
; #define PG8_BAR __builtin_amdgcn_s_barrier()
; template <class Epi, class Sched, bool ALIGN_EPI = false, bool SP2 = false>
; __device__ __forceinline__ void gemm_phase(PG8_LAS unsigned char* lds, const Gemm g, const Sched& S, const Epi& E) {
;     ...
;         const bool has_next = S.next(ui + 1, nxt);
;         const char* nA = has_next ? (const char*)g.A + (size_t)nxt.pm * tstep : cA; const char* nB = has_next ? (const char*)g.Bt + (size_t)nxt.pn * tstep : cB;
;         for (int t = 0; t < nt; t += 2) {
;             const bool last = (t == nt - 2);
;             const char* a1 = cA + (size_t)(t + 1) * kstep;
;             const char* a2 = last ? nA : cA + (size_t)(t + 2) * kstep; const char* b2 = last ? nB : cB + (size_t)(t + 2) * kstep;
;             const char* a3 = a2 + kstep; const char* b3 = b2 + kstep;
;             if (last && has_next) S.a_ready(nxt);
;             if constexpr (SP2) {
;             PG8_LDB(B0, 0, 0); PG8_LDB(B1, 0, 1); PG8_SCHED; PG8_LDA(At, 0, 0); PG8_STAGE(PG8_SA(1, 1), a1 + hstep, voffA);
;             PG8_WAIT_V(8); PG8_WAIT_L(0); PG8_BAR; PG8_MMA(0, 0, At, B0); PG8_MMA(0, 1, At, B1); PG8_BAR; PG8_SCHED;
.LBB0_956:
	s_ashr_i32 s45, s44, 31
	s_lshl_b64 s[48:49], s[44:45], 19
	s_add_u32 s48, s22, s48
	s_addc_u32 s49, s23, s49
	s_and_b64 s[50:51], s[10:11], exec
	s_cselect_b32 s45, s49, s55
	s_cselect_b32 s75, s48, s54
	s_ashr_i32 s43, s42, 31
	s_lshl_b64 s[50:51], s[42:43], 19
	v_readlane_b32 s3, v250, 18
	s_add_u32 s50, s3, s50
	v_readlane_b32 s3, v250, 19
	s_addc_u32 s51, s3, s51
	s_and_b64 s[58:59], s[10:11], exec
	s_cselect_b32 s43, s51, s57
	s_cselect_b32 s76, s50, s56
	s_add_u32 s54, s54, 0x40080
	s_addc_u32 s55, s55, 0
	s_add_u32 s77, s56, 0x100
	s_addc_u32 s82, s57, 0
	s_mov_b32 s83, -2
	ds_read_b128 v[144:147], v155
	ds_read_b128 v[148:151], v155 offset:1024
	ds_read_b128 v[160:163], v155 offset:2048
	ds_read_b128 v[164:167], v155 offset:3072
	ds_read_b128 v[168:171], v156
	ds_read_b128 v[172:175], v156 offset:1024
	ds_read_b128 v[176:179], v156 offset:2048
	ds_read_b128 v[182:185], v156 offset:3072
	s_add_u32 s3, s54, 0xfffc0080
	s_addc_u32 s33, s55, -1
	s_cmp_eq_u32 s83, 12
	s_cselect_b32 s59, s45, s33
	s_cselect_b32 s58, s75, s3
	s_cselect_b32 s57, s43, s82
	s_cselect_b32 s56, s76, s77
	v_lshl_add_u64 v[202:203], s[54:55], 0, v[136:137]
	s_add_i32 m0, s34, 0xc000
	ds_read_b128 v[186:189], v157
	ds_read_b128 v[190:193], v157 offset:1024
	ds_read_b128 v[194:197], v157 offset:2048
	ds_read_b128 v[198:201], v157 offset:3072
	ds_read_b128 v[208:211], v157 offset:4096
	ds_read_b128 v[212:215], v157 offset:5120
	ds_read_b128 v[216:219], v157 offset:6144
	ds_read_b128 v[220:223], v157 offset:7168
	global_load_lds_dwordx4 v[202:203], off
	v_lshl_add_u64 v[202:203], s[54:55], 0, v[138:139]
	s_add_i32 m0, s34, 0xe000
	s_nop 0
	global_load_lds_dwordx4 v[202:203], off
	s_waitcnt vmcnt(8)
	s_waitcnt lgkmcnt(0)
	s_barrier
	s_setprio 1
	s_waitcnt lgkmcnt(0)
	v_mfma_f32_16x16x32_bf16 v[124:127], v[144:147], v[186:189], 0
	v_mfma_f32_16x16x32_bf16 v[120:123], v[160:163], v[186:189], 0
	v_mfma_f32_16x16x32_bf16 v[104:107], v[160:163], v[194:197], 0
	v_mfma_f32_16x16x32_bf16 v[108:111], v[144:147], v[194:197], 0
	v_mfma_f32_16x16x32_bf16 v[92:95], v[144:147], v[208:211], 0
	v_mfma_f32_16x16x32_bf16 v[88:91], v[160:163], v[208:211], 0
	v_mfma_f32_16x16x32_bf16 v[72:75], v[160:163], v[216:219], 0
	v_mfma_f32_16x16x32_bf16 v[76:79], v[144:147], v[216:219], 0
	v_mfma_f32_16x16x32_bf16 v[124:127], v[148:151], v[190:193], v[124:127]
	v_mfma_f32_16x16x32_bf16 v[120:123], v[164:167], v[190:193], v[120:123]
	v_mfma_f32_16x16x32_bf16 v[104:107], v[164:167], v[198:201], v[104:107]
	v_mfma_f32_16x16x32_bf16 v[108:111], v[148:151], v[198:201], v[108:111]
	v_mfma_f32_16x16x32_bf16 v[92:95], v[148:151], v[212:215], v[92:95]
	v_mfma_f32_16x16x32_bf16 v[88:91], v[164:167], v[212:215], v[88:91]
	v_mfma_f32_16x16x32_bf16 v[72:75], v[164:167], v[220:223], v[72:75]
	v_mfma_f32_16x16x32_bf16 v[76:79], v[148:151], v[220:223], v[76:79]
	s_setprio 0
	s_setprio 1
	v_mfma_f32_16x16x32_bf16 v[116:119], v[168:171], v[186:189], 0
	v_mfma_f32_16x16x32_bf16 v[112:115], v[176:179], v[186:189], 0
	v_mfma_f32_16x16x32_bf16 v[96:99], v[176:179], v[194:197], 0
	v_mfma_f32_16x16x32_bf16 v[100:103], v[168:171], v[194:197], 0
	v_mfma_f32_16x16x32_bf16 v[84:87], v[168:171], v[208:211], 0
	v_mfma_f32_16x16x32_bf16 v[80:83], v[176:179], v[208:211], 0
	v_mfma_f32_16x16x32_bf16 v[64:67], v[176:179], v[216:219], 0
	v_mfma_f32_16x16x32_bf16 v[68:71], v[168:171], v[216:219], 0
	v_mfma_f32_16x16x32_bf16 v[116:119], v[172:175], v[190:193], v[116:119]
	v_mfma_f32_16x16x32_bf16 v[112:115], v[182:185], v[190:193], v[112:115]
	v_mfma_f32_16x16x32_bf16 v[96:99], v[182:185], v[198:201], v[96:99]
	v_mfma_f32_16x16x32_bf16 v[100:103], v[172:175], v[198:201], v[100:103]
	v_mfma_f32_16x16x32_bf16 v[84:87], v[172:175], v[212:215], v[84:87]
	v_mfma_f32_16x16x32_bf16 v[80:83], v[182:185], v[212:215], v[80:83]
	v_mfma_f32_16x16x32_bf16 v[64:67], v[182:185], v[220:223], v[64:67]
	v_mfma_f32_16x16x32_bf16 v[68:71], v[172:175], v[220:223], v[68:71]
	s_setprio 0
	s_barrier
	s_add_i32 s3, s65, s14
	v_lshl_add_u64 v[202:203], s[56:57], 0, v[132:133]
	s_mov_b32 m0, s3
	ds_read_b128 v[186:189], v157 offset:16384
	ds_read_b128 v[190:193], v157 offset:17408
	ds_read_b128 v[194:197], v157 offset:18432
	ds_read_b128 v[198:201], v157 offset:19456
	ds_read_b128 v[208:211], v157 offset:20480
	ds_read_b128 v[212:215], v157 offset:21504
	ds_read_b128 v[216:219], v157 offset:22528
	ds_read_b128 v[220:223], v157 offset:23552
	global_load_lds_dwordx4 v[202:203], off
	s_add_i32 m0, s3, 0x2000
	s_add_u32 s78, s56, 0x40000
	v_lshl_add_u64 v[224:225], s[56:57], 0, v[128:129]
	s_addc_u32 s79, s57, 0
	s_add_i32 s3, s66, s14
	global_load_lds_dwordx4 v[224:225], off
	v_lshl_add_u64 v[226:227], s[78:79], 0, v[132:133]
	s_mov_b32 m0, s3
	global_load_lds_dwordx4 v[226:227], off
	v_lshl_add_u64 v[226:227], s[78:79], 0, v[128:129]
	s_add_i32 m0, s3, 0x2000
	s_nop 0
	global_load_lds_dwordx4 v[226:227], off
	s_waitcnt vmcnt(6)
	s_waitcnt lgkmcnt(0)
	s_barrier
; #define PG8_STAGE(bufoff, gbase, voff) do { _Pragma("unroll") for (int _i = 0; _i < 2; ++_i) \
;         __builtin_amdgcn_global_load_lds((const unsigned*)((const char*)(gbase) + (voff)[_i]), (PG8_LAS unsigned*)(lds + (bufoff) + ldsw + _i * 8192), 16, 0, 0); } while (0)
; #define PG8_LDA(dst, b, h) do { _Pragma("unroll") for (int m = 0; m < 4; ++m) _Pragma("unroll") for (int k = 0; k < 2; ++k) dst[m][k] = *(const PG8_LAS bf16x8*)(lds + PG8_SA(b, h) + aoff + m * 2048 + k * 1024); } while (0)
; #define PG8_LDB(dst, b, h) do { _Pragma("unroll") for (int n = 0; n < 2; ++n) _Pragma("unroll") for (int k = 0; k < 2; ++k) dst[n][k] = *(const PG8_LAS bf16x8*)(lds + PG8_SB(b, h) + boff + n * 2048 + k * 1024); } while (0)
; #define PG8_MMA(ai, bj, At, Bt) do { __builtin_amdgcn_s_setprio(1); _Pragma("unroll") for (int m = 0; m < 4; ++m) _Pragma("unroll") for (int n = 0; n < 2; ++n) _Pragma("unroll") for (int k = 0; k < 2; ++k) \
;         acc[ai][bj][m][n] = __builtin_amdgcn_mfma_f32_16x16x32_bf16(Bt[n][k], At[m][k], acc[ai][bj][m][n], 0, 0, 0); __builtin_amdgcn_s_setprio(0); } while (0)
; #define PG8_WAIT_V(n) asm volatile("s_waitcnt vmcnt(" #n ")" ::: "memory")
; #define PG8_WAIT_L(n) asm volatile("s_waitcnt lgkmcnt(" #n ")" ::: "memory")
; #define PG8_BAR __builtin_amdgcn_s_barrier()
; #define PG8_SCHED __builtin_amdgcn_sched_barrier(0)
; template <class Epi, class Sched, bool ALIGN_EPI = false, bool SP2 = false>
; __device__ __forceinline__ void gemm_phase(PG8_LAS unsigned char* lds, const Gemm g, const Sched& S, const Epi& E) {
;     ...
;             PG8_WAIT_V(8); PG8_WAIT_L(0); PG8_BAR; PG8_MMA(0, 0, At, B0); PG8_MMA(0, 1, At, B1); PG8_BAR; PG8_SCHED;
;             PG8_LDA(At, 0, 1); PG8_STAGE(PG8_SB(0, 0), b2, voffB); PG8_STAGE(PG8_SB(0, 1), b2 + hstep, voffB); PG8_STAGE(PG8_SA(0, 0), a2, voffA);
;             PG8_WAIT_V(8); PG8_WAIT_L(0); PG8_BAR; PG8_MMA(1, 0, At, B0); PG8_MMA(1, 1, At, B1); PG8_BAR; PG8_SCHED;
;             PG8_LDB(B0, 1, 0); PG8_LDB(B1, 1, 1); PG8_SCHED; PG8_LDA(At, 1, 0); PG8_STAGE(PG8_SA(0, 1), a2 + hstep, voffA);
;             PG8_WAIT_V(8); PG8_WAIT_L(0); PG8_BAR; PG8_MMA(0, 0, At, B0); PG8_MMA(0, 1, At, B1); PG8_BAR; PG8_SCHED;
	s_setprio 1
	s_waitcnt lgkmcnt(0)
	v_mfma_f32_16x16x32_bf16 v[60:63], v[144:147], v[186:189], 0
	v_mfma_f32_16x16x32_bf16 v[56:59], v[160:163], v[186:189], 0
	v_mfma_f32_16x16x32_bf16 v[40:43], v[160:163], v[194:197], 0
	v_mfma_f32_16x16x32_bf16 v[44:47], v[144:147], v[194:197], 0
	v_mfma_f32_16x16x32_bf16 v[28:31], v[144:147], v[208:211], 0
	v_mfma_f32_16x16x32_bf16 v[24:27], v[160:163], v[208:211], 0
	v_mfma_f32_16x16x32_bf16 v[8:11], v[160:163], v[216:219], 0
	v_mfma_f32_16x16x32_bf16 v[12:15], v[144:147], v[216:219], 0
	v_mfma_f32_16x16x32_bf16 v[60:63], v[148:151], v[190:193], v[60:63]
	v_mfma_f32_16x16x32_bf16 v[56:59], v[164:167], v[190:193], v[56:59]
	v_mfma_f32_16x16x32_bf16 v[40:43], v[164:167], v[198:201], v[40:43]
	v_mfma_f32_16x16x32_bf16 v[44:47], v[148:151], v[198:201], v[44:47]
	v_mfma_f32_16x16x32_bf16 v[28:31], v[148:151], v[212:215], v[28:31]
	v_mfma_f32_16x16x32_bf16 v[24:27], v[164:167], v[212:215], v[24:27]
	v_lshl_add_u64 v[226:227], s[58:59], 0, v[134:135]
	s_mov_b32 m0, s34
	s_nop 0
	global_load_lds_dwordx4 v[226:227], off
	v_mfma_f32_16x16x32_bf16 v[8:11], v[164:167], v[220:223], v[8:11]
	v_mfma_f32_16x16x32_bf16 v[12:15], v[148:151], v[220:223], v[12:15]
	s_setprio 0
	s_setprio 1
	v_mfma_f32_16x16x32_bf16 v[52:55], v[168:171], v[186:189], 0
	v_mfma_f32_16x16x32_bf16 v[48:51], v[176:179], v[186:189], 0
	v_mfma_f32_16x16x32_bf16 v[32:35], v[176:179], v[194:197], 0
	v_mfma_f32_16x16x32_bf16 v[36:39], v[168:171], v[194:197], 0
	v_mfma_f32_16x16x32_bf16 v[20:23], v[168:171], v[208:211], 0
	v_mfma_f32_16x16x32_bf16 v[16:19], v[176:179], v[208:211], 0
	v_mfma_f32_16x16x32_bf16 v[0:3], v[176:179], v[216:219], 0
	v_mfma_f32_16x16x32_bf16 v[4:7], v[168:171], v[216:219], 0
	v_mfma_f32_16x16x32_bf16 v[52:55], v[172:175], v[190:193], v[52:55]
	v_mfma_f32_16x16x32_bf16 v[48:51], v[182:185], v[190:193], v[48:51]
	v_mfma_f32_16x16x32_bf16 v[32:35], v[182:185], v[198:201], v[32:35]
	v_mfma_f32_16x16x32_bf16 v[36:39], v[172:175], v[198:201], v[36:39]
	v_mfma_f32_16x16x32_bf16 v[20:23], v[172:175], v[212:215], v[20:23]
	v_mfma_f32_16x16x32_bf16 v[16:19], v[182:185], v[212:215], v[16:19]
	v_lshl_add_u64 v[228:229], s[58:59], 0, v[130:131]
	s_mov_b32 m0, s53
	s_nop 0
	global_load_lds_dwordx4 v[228:229], off
	v_mfma_f32_16x16x32_bf16 v[0:3], v[182:185], v[220:223], v[0:3]
	v_mfma_f32_16x16x32_bf16 v[4:7], v[172:175], v[220:223], v[4:7]
	s_setprio 0
	s_barrier
	s_add_i32 s3, 0, 0x18000
	v_add_u32_e32 v159, s3, v153
	s_add_i32 s33, 0, 0x1c000
	ds_read_b128 v[144:147], v159
	ds_read_b128 v[148:151], v159 offset:1024
	ds_read_b128 v[160:163], v159 offset:2048
	ds_read_b128 v[164:167], v159 offset:3072
	v_add_u32_e32 v159, s33, v153
	ds_read_b128 v[168:171], v159
	ds_read_b128 v[172:175], v159 offset:1024
	ds_read_b128 v[176:179], v159 offset:2048
	ds_read_b128 v[182:185], v159 offset:3072
	s_add_u32 s58, s58, 0x40000
	s_addc_u32 s59, s59, 0
	s_mov_b32 m0, s60
	v_lshl_add_u64 v[230:231], s[58:59], 0, v[134:135]
	ds_read_b128 v[186:189], v157 offset:32768
	ds_read_b128 v[190:193], v157 offset:33792
	ds_read_b128 v[194:197], v157 offset:34816
	ds_read_b128 v[198:201], v157 offset:35840
	ds_read_b128 v[208:211], v157 offset:36864
	ds_read_b128 v[212:215], v157 offset:37888
	ds_read_b128 v[216:219], v157 offset:38912
	ds_read_b128 v[220:223], v157 offset:39936
	global_load_lds_dwordx4 v[230:231], off
	v_lshl_add_u64 v[230:231], s[58:59], 0, v[130:131]
	s_mov_b32 m0, s61
	s_nop 0
	global_load_lds_dwordx4 v[230:231], off
	s_waitcnt vmcnt(8)
	s_waitcnt lgkmcnt(0)
	s_barrier
	s_setprio 1
	s_waitcnt lgkmcnt(0)
	v_mfma_f32_16x16x32_bf16 v[124:127], v[144:147], v[186:189], v[124:127]
	v_mfma_f32_16x16x32_bf16 v[120:123], v[160:163], v[186:189], v[120:123]
	v_mfma_f32_16x16x32_bf16 v[104:107], v[160:163], v[194:197], v[104:107]
	v_mfma_f32_16x16x32_bf16 v[108:111], v[144:147], v[194:197], v[108:111]
	v_mfma_f32_16x16x32_bf16 v[92:95], v[144:147], v[208:211], v[92:95]
	v_mfma_f32_16x16x32_bf16 v[88:91], v[160:163], v[208:211], v[88:91]
	v_mfma_f32_16x16x32_bf16 v[72:75], v[160:163], v[216:219], v[72:75]
	v_mfma_f32_16x16x32_bf16 v[76:79], v[144:147], v[216:219], v[76:79]
	v_mfma_f32_16x16x32_bf16 v[124:127], v[148:151], v[190:193], v[124:127]
	v_mfma_f32_16x16x32_bf16 v[120:123], v[164:167], v[190:193], v[120:123]
	v_mfma_f32_16x16x32_bf16 v[104:107], v[164:167], v[198:201], v[104:107]
	v_mfma_f32_16x16x32_bf16 v[108:111], v[148:151], v[198:201], v[108:111]
	v_mfma_f32_16x16x32_bf16 v[92:95], v[148:151], v[212:215], v[92:95]
	v_mfma_f32_16x16x32_bf16 v[88:91], v[164:167], v[212:215], v[88:91]
	v_mfma_f32_16x16x32_bf16 v[72:75], v[164:167], v[220:223], v[72:75]
	v_mfma_f32_16x16x32_bf16 v[76:79], v[148:151], v[220:223], v[76:79]
	s_setprio 0
	s_setprio 1
	v_mfma_f32_16x16x32_bf16 v[116:119], v[168:171], v[186:189], v[116:119]
	v_mfma_f32_16x16x32_bf16 v[112:115], v[176:179], v[186:189], v[112:115]
	v_mfma_f32_16x16x32_bf16 v[96:99], v[176:179], v[194:197], v[96:99]
	v_mfma_f32_16x16x32_bf16 v[100:103], v[168:171], v[194:197], v[100:103]
	v_mfma_f32_16x16x32_bf16 v[84:87], v[168:171], v[208:211], v[84:87]
	v_mfma_f32_16x16x32_bf16 v[80:83], v[176:179], v[208:211], v[80:83]
	v_mfma_f32_16x16x32_bf16 v[64:67], v[176:179], v[216:219], v[64:67]
	v_mfma_f32_16x16x32_bf16 v[68:71], v[168:171], v[216:219], v[68:71]
	v_mfma_f32_16x16x32_bf16 v[116:119], v[172:175], v[190:193], v[116:119]
	v_mfma_f32_16x16x32_bf16 v[112:115], v[182:185], v[190:193], v[112:115]
	v_mfma_f32_16x16x32_bf16 v[96:99], v[182:185], v[198:201], v[96:99]
	v_mfma_f32_16x16x32_bf16 v[100:103], v[172:175], v[198:201], v[100:103]
	v_mfma_f32_16x16x32_bf16 v[84:87], v[172:175], v[212:215], v[84:87]
	v_mfma_f32_16x16x32_bf16 v[80:83], v[182:185], v[212:215], v[80:83]
	v_mfma_f32_16x16x32_bf16 v[64:67], v[182:185], v[220:223], v[64:67]
	v_mfma_f32_16x16x32_bf16 v[68:71], v[172:175], v[220:223], v[68:71]
	s_setprio 0
	s_barrier
; #define PG8_STAGE(bufoff, gbase, voff) do { _Pragma("unroll") for (int _i = 0; _i < 2; ++_i) \
;         __builtin_amdgcn_global_load_lds((const unsigned*)((const char*)(gbase) + (voff)[_i]), (PG8_LAS unsigned*)(lds + (bufoff) + ldsw + _i * 8192), 16, 0, 0); } while (0)
; #define PG8_LDA(dst, b, h) do { _Pragma("unroll") for (int m = 0; m < 4; ++m) _Pragma("unroll") for (int k = 0; k < 2; ++k) dst[m][k] = *(const PG8_LAS bf16x8*)(lds + PG8_SA(b, h) + aoff + m * 2048 + k * 1024); } while (0)
; #define PG8_LDB(dst, b, h) do { _Pragma("unroll") for (int n = 0; n < 2; ++n) _Pragma("unroll") for (int k = 0; k < 2; ++k) dst[n][k] = *(const PG8_LAS bf16x8*)(lds + PG8_SB(b, h) + boff + n * 2048 + k * 1024); } while (0)
; #define PG8_MMA(ai, bj, At, Bt) do { __builtin_amdgcn_s_setprio(1); _Pragma("unroll") for (int m = 0; m < 4; ++m) _Pragma("unroll") for (int n = 0; n < 2; ++n) _Pragma("unroll") for (int k = 0; k < 2; ++k) \
;         acc[ai][bj][m][n] = __builtin_amdgcn_mfma_f32_16x16x32_bf16(Bt[n][k], At[m][k], acc[ai][bj][m][n], 0, 0, 0); __builtin_amdgcn_s_setprio(0); } while (0)
; #define PG8_WAIT_V(n) asm volatile("s_waitcnt vmcnt(" #n ")" ::: "memory")
; #define PG8_WAIT_L(n) asm volatile("s_waitcnt lgkmcnt(" #n ")" ::: "memory")
; #define PG8_BAR __builtin_amdgcn_s_barrier()
; #define PG8_SCHED __builtin_amdgcn_sched_barrier(0)
; template <class Epi, class Sched, bool ALIGN_EPI = false, bool SP2 = false>
; __device__ __forceinline__ void gemm_phase(PG8_LAS unsigned char* lds, const Gemm g, const Sched& S, const Epi& E) {
;     ...
;             PG8_LDB(B0, 0, 0); PG8_LDB(B1, 0, 1); PG8_SCHED; PG8_LDA(At, 0, 0); PG8_STAGE(PG8_SA(1, 1), a1 + hstep, voffA);
;     ...
;             PG8_LDA(At, 1, 1); PG8_STAGE(PG8_SB(1, 0), b3, voffB); PG8_STAGE(PG8_SB(1, 1), b3 + hstep, voffB); PG8_STAGE(PG8_SA(1, 0), a3, voffA);
;             PG8_WAIT_V(8); PG8_WAIT_L(0); PG8_BAR; PG8_MMA(1, 0, At, B0); PG8_MMA(1, 1, At, B1); PG8_BAR; PG8_SCHED;
	s_add_i32 s3, s3, s14
	v_lshl_add_u64 v[202:203], v[202:203], 0, s[36:37]
	s_mov_b32 m0, s3
	ds_read_b128 v[186:189], v157 offset:49152
	ds_read_b128 v[190:193], v157 offset:50176
	ds_read_b128 v[194:197], v157 offset:51200
	ds_read_b128 v[198:201], v157 offset:52224
	ds_read_b128 v[208:211], v157 offset:53248
	ds_read_b128 v[212:215], v157 offset:54272
	ds_read_b128 v[216:219], v157 offset:55296
	ds_read_b128 v[220:223], v157 offset:56320
	global_load_lds_dwordx4 v[202:203], off
	s_add_i32 m0, s3, 0x2000
	s_add_u32 s56, s56, 0x40080
	v_lshl_add_u64 v[202:203], v[224:225], 0, s[36:37]
	s_addc_u32 s57, s57, 0
	s_add_i32 s3, s33, s14
	global_load_lds_dwordx4 v[202:203], off
	v_lshl_add_u64 v[202:203], s[56:57], 0, v[132:133]
	s_mov_b32 m0, s3
	s_nop 0
	global_load_lds_dwordx4 v[202:203], off
	v_lshl_add_u64 v[202:203], s[56:57], 0, v[128:129]
	s_add_i32 m0, s3, 0x2000
	s_nop 0
	global_load_lds_dwordx4 v[202:203], off
	s_waitcnt vmcnt(6)
	s_waitcnt lgkmcnt(0)
	s_barrier
	s_setprio 1
	s_waitcnt lgkmcnt(0)
	v_mfma_f32_16x16x32_bf16 v[60:63], v[144:147], v[186:189], v[60:63]
	v_mfma_f32_16x16x32_bf16 v[56:59], v[160:163], v[186:189], v[56:59]
	v_mfma_f32_16x16x32_bf16 v[40:43], v[160:163], v[194:197], v[40:43]
	v_mfma_f32_16x16x32_bf16 v[44:47], v[144:147], v[194:197], v[44:47]
	v_mfma_f32_16x16x32_bf16 v[28:31], v[144:147], v[208:211], v[28:31]
	v_mfma_f32_16x16x32_bf16 v[24:27], v[160:163], v[208:211], v[24:27]
	v_mfma_f32_16x16x32_bf16 v[8:11], v[160:163], v[216:219], v[8:11]
	v_mfma_f32_16x16x32_bf16 v[12:15], v[144:147], v[216:219], v[12:15]
	v_mfma_f32_16x16x32_bf16 v[60:63], v[148:151], v[190:193], v[60:63]
	v_mfma_f32_16x16x32_bf16 v[56:59], v[164:167], v[190:193], v[56:59]
	v_mfma_f32_16x16x32_bf16 v[40:43], v[164:167], v[198:201], v[40:43]
	v_mfma_f32_16x16x32_bf16 v[44:47], v[148:151], v[198:201], v[44:47]
	v_mfma_f32_16x16x32_bf16 v[28:31], v[148:151], v[212:215], v[28:31]
	v_mfma_f32_16x16x32_bf16 v[24:27], v[164:167], v[212:215], v[24:27]
	v_lshl_add_u64 v[202:203], v[226:227], 0, s[36:37]
	s_mov_b32 m0, s63
	s_nop 0
	global_load_lds_dwordx4 v[202:203], off
	v_mfma_f32_16x16x32_bf16 v[8:11], v[164:167], v[220:223], v[8:11]
	v_mfma_f32_16x16x32_bf16 v[12:15], v[148:151], v[220:223], v[12:15]
	s_setprio 0
	s_setprio 1
	v_mfma_f32_16x16x32_bf16 v[52:55], v[168:171], v[186:189], v[52:55]
	v_mfma_f32_16x16x32_bf16 v[48:51], v[176:179], v[186:189], v[48:51]
	v_mfma_f32_16x16x32_bf16 v[32:35], v[176:179], v[194:197], v[32:35]
	v_mfma_f32_16x16x32_bf16 v[36:39], v[168:171], v[194:197], v[36:39]
	v_mfma_f32_16x16x32_bf16 v[20:23], v[168:171], v[208:211], v[20:23]
	v_mfma_f32_16x16x32_bf16 v[16:19], v[176:179], v[208:211], v[16:19]
	v_mfma_f32_16x16x32_bf16 v[0:3], v[176:179], v[216:219], v[0:3]
	v_mfma_f32_16x16x32_bf16 v[4:7], v[168:171], v[216:219], v[4:7]
	v_mfma_f32_16x16x32_bf16 v[52:55], v[172:175], v[190:193], v[52:55]
	v_mfma_f32_16x16x32_bf16 v[48:51], v[182:185], v[190:193], v[48:51]
	v_mfma_f32_16x16x32_bf16 v[32:35], v[182:185], v[198:201], v[32:35]
	v_mfma_f32_16x16x32_bf16 v[36:39], v[172:175], v[198:201], v[36:39]
	v_mfma_f32_16x16x32_bf16 v[20:23], v[172:175], v[212:215], v[20:23]
	v_mfma_f32_16x16x32_bf16 v[16:19], v[182:185], v[212:215], v[16:19]
	v_lshl_add_u64 v[202:203], v[228:229], 0, s[36:37]
	s_mov_b32 m0, s64
	s_nop 0
	global_load_lds_dwordx4 v[202:203], off
	v_mfma_f32_16x16x32_bf16 v[0:3], v[182:185], v[220:223], v[0:3]
	v_mfma_f32_16x16x32_bf16 v[4:7], v[172:175], v[220:223], v[4:7]
	s_setprio 0
	s_barrier
	s_add_i32 s83, s83, 2
	s_add_u32 s54, s54, 0x100
	s_addc_u32 s55, s55, 0
	s_add_u32 s77, s77, 0x100
	s_addc_u32 s82, s82, 0
.LBB0_957:
	ds_read_b128 v[144:147], v155
	ds_read_b128 v[148:151], v155 offset:1024
	ds_read_b128 v[160:163], v155 offset:2048
	ds_read_b128 v[164:167], v155 offset:3072
	ds_read_b128 v[168:171], v156
	ds_read_b128 v[172:175], v156 offset:1024
	ds_read_b128 v[176:179], v156 offset:2048
	ds_read_b128 v[182:185], v156 offset:3072
	s_add_u32 s3, s54, 0xfffc0080
	s_addc_u32 s33, s55, -1
	s_cmp_eq_u32 s83, 12
	s_cselect_b32 s59, s45, s33
	s_cselect_b32 s58, s75, s3
	s_cselect_b32 s57, s43, s82
	s_cselect_b32 s56, s76, s77
	v_lshl_add_u64 v[202:203], s[54:55], 0, v[136:137]
	s_add_i32 m0, s34, 0xc000
	ds_read_b128 v[186:189], v157
	ds_read_b128 v[190:193], v157 offset:1024
	ds_read_b128 v[194:197], v157 offset:2048
	ds_read_b128 v[198:201], v157 offset:3072
	ds_read_b128 v[208:211], v157 offset:4096
	ds_read_b128 v[212:215], v157 offset:5120
	ds_read_b128 v[216:219], v157 offset:6144
	ds_read_b128 v[220:223], v157 offset:7168
	global_load_lds_dwordx4 v[202:203], off
	v_lshl_add_u64 v[202:203], s[54:55], 0, v[138:139]
	s_add_i32 m0, s34, 0xe000
	s_nop 0
	global_load_lds_dwordx4 v[202:203], off
	s_waitcnt vmcnt(8)
	s_waitcnt lgkmcnt(0)
	s_barrier
; #define PG8_STAGE(bufoff, gbase, voff) do { _Pragma("unroll") for (int _i = 0; _i < 2; ++_i) \
;         __builtin_amdgcn_global_load_lds((const unsigned*)((const char*)(gbase) + (voff)[_i]), (PG8_LAS unsigned*)(lds + (bufoff) + ldsw + _i * 8192), 16, 0, 0); } while (0)
; #define PG8_LDA(dst, b, h) do { _Pragma("unroll") for (int m = 0; m < 4; ++m) _Pragma("unroll") for (int k = 0; k < 2; ++k) dst[m][k] = *(const PG8_LAS bf16x8*)(lds + PG8_SA(b, h) + aoff + m * 2048 + k * 1024); } while (0)
; #define PG8_MMA(ai, bj, At, Bt) do { __builtin_amdgcn_s_setprio(1); _Pragma("unroll") for (int m = 0; m < 4; ++m) _Pragma("unroll") for (int n = 0; n < 2; ++n) _Pragma("unroll") for (int k = 0; k < 2; ++k) \
;         acc[ai][bj][m][n] = __builtin_amdgcn_mfma_f32_16x16x32_bf16(Bt[n][k], At[m][k], acc[ai][bj][m][n], 0, 0, 0); __builtin_amdgcn_s_setprio(0); } while (0)
; #define PG8_WAIT_V(n) asm volatile("s_waitcnt vmcnt(" #n ")" ::: "memory")
; #define PG8_WAIT_L(n) asm volatile("s_waitcnt lgkmcnt(" #n ")" ::: "memory")
; #define PG8_BAR __builtin_amdgcn_s_barrier()
; #define PG8_SCHED __builtin_amdgcn_sched_barrier(0)
; template <class Epi, class Sched, bool ALIGN_EPI = false, bool SP2 = false>
; __device__ __forceinline__ void gemm_phase(PG8_LAS unsigned char* lds, const Gemm g, const Sched& S, const Epi& E) {
;     ...
;             PG8_WAIT_V(8); PG8_WAIT_L(0); PG8_BAR; PG8_MMA(0, 0, At, B0); PG8_MMA(0, 1, At, B1); PG8_BAR; PG8_SCHED;
;             PG8_LDA(At, 0, 1); PG8_STAGE(PG8_SB(0, 0), b2, voffB); PG8_STAGE(PG8_SB(0, 1), b2 + hstep, voffB); PG8_STAGE(PG8_SA(0, 0), a2, voffA);
;             PG8_WAIT_V(8); PG8_WAIT_L(0); PG8_BAR; PG8_MMA(1, 0, At, B0); PG8_MMA(1, 1, At, B1); PG8_BAR; PG8_SCHED;
	s_setprio 1
	s_waitcnt lgkmcnt(0)
	v_mfma_f32_16x16x32_bf16 v[124:127], v[144:147], v[186:189], v[124:127]
	v_mfma_f32_16x16x32_bf16 v[120:123], v[160:163], v[186:189], v[120:123]
	v_mfma_f32_16x16x32_bf16 v[104:107], v[160:163], v[194:197], v[104:107]
	v_mfma_f32_16x16x32_bf16 v[108:111], v[144:147], v[194:197], v[108:111]
	v_mfma_f32_16x16x32_bf16 v[92:95], v[144:147], v[208:211], v[92:95]
	v_mfma_f32_16x16x32_bf16 v[88:91], v[160:163], v[208:211], v[88:91]
	v_mfma_f32_16x16x32_bf16 v[72:75], v[160:163], v[216:219], v[72:75]
	v_mfma_f32_16x16x32_bf16 v[76:79], v[144:147], v[216:219], v[76:79]
	v_mfma_f32_16x16x32_bf16 v[124:127], v[148:151], v[190:193], v[124:127]
	v_mfma_f32_16x16x32_bf16 v[120:123], v[164:167], v[190:193], v[120:123]
	v_mfma_f32_16x16x32_bf16 v[104:107], v[164:167], v[198:201], v[104:107]
	v_mfma_f32_16x16x32_bf16 v[108:111], v[148:151], v[198:201], v[108:111]
	v_mfma_f32_16x16x32_bf16 v[92:95], v[148:151], v[212:215], v[92:95]
	v_mfma_f32_16x16x32_bf16 v[88:91], v[164:167], v[212:215], v[88:91]
	v_mfma_f32_16x16x32_bf16 v[72:75], v[164:167], v[220:223], v[72:75]
	v_mfma_f32_16x16x32_bf16 v[76:79], v[148:151], v[220:223], v[76:79]
	s_setprio 0
	s_setprio 1
	v_mfma_f32_16x16x32_bf16 v[116:119], v[168:171], v[186:189], v[116:119]
	v_mfma_f32_16x16x32_bf16 v[112:115], v[176:179], v[186:189], v[112:115]
	v_mfma_f32_16x16x32_bf16 v[96:99], v[176:179], v[194:197], v[96:99]
	v_mfma_f32_16x16x32_bf16 v[100:103], v[168:171], v[194:197], v[100:103]
	v_mfma_f32_16x16x32_bf16 v[84:87], v[168:171], v[208:211], v[84:87]
	v_mfma_f32_16x16x32_bf16 v[80:83], v[176:179], v[208:211], v[80:83]
	v_mfma_f32_16x16x32_bf16 v[64:67], v[176:179], v[216:219], v[64:67]
	v_mfma_f32_16x16x32_bf16 v[68:71], v[168:171], v[216:219], v[68:71]
	v_mfma_f32_16x16x32_bf16 v[116:119], v[172:175], v[190:193], v[116:119]
	v_mfma_f32_16x16x32_bf16 v[112:115], v[182:185], v[190:193], v[112:115]
	v_mfma_f32_16x16x32_bf16 v[96:99], v[182:185], v[198:201], v[96:99]
	v_mfma_f32_16x16x32_bf16 v[100:103], v[172:175], v[198:201], v[100:103]
	v_mfma_f32_16x16x32_bf16 v[84:87], v[172:175], v[212:215], v[84:87]
	v_mfma_f32_16x16x32_bf16 v[80:83], v[182:185], v[212:215], v[80:83]
	v_mfma_f32_16x16x32_bf16 v[64:67], v[182:185], v[220:223], v[64:67]
	v_mfma_f32_16x16x32_bf16 v[68:71], v[172:175], v[220:223], v[68:71]
	s_setprio 0
	s_barrier
	s_add_i32 s3, s65, s14
	v_lshl_add_u64 v[202:203], s[56:57], 0, v[132:133]
	s_mov_b32 m0, s3
	ds_read_b128 v[186:189], v157 offset:16384
	ds_read_b128 v[190:193], v157 offset:17408
	ds_read_b128 v[194:197], v157 offset:18432
	ds_read_b128 v[198:201], v157 offset:19456
	ds_read_b128 v[208:211], v157 offset:20480
	ds_read_b128 v[212:215], v157 offset:21504
	ds_read_b128 v[216:219], v157 offset:22528
	ds_read_b128 v[220:223], v157 offset:23552
	global_load_lds_dwordx4 v[202:203], off
	s_add_i32 m0, s3, 0x2000
	s_add_u32 s78, s56, 0x40000
	v_lshl_add_u64 v[224:225], s[56:57], 0, v[128:129]
	s_addc_u32 s79, s57, 0
	s_add_i32 s3, s66, s14
	global_load_lds_dwordx4 v[224:225], off
	v_lshl_add_u64 v[226:227], s[78:79], 0, v[132:133]
	s_mov_b32 m0, s3
	global_load_lds_dwordx4 v[226:227], off
	v_lshl_add_u64 v[226:227], s[78:79], 0, v[128:129]
	s_add_i32 m0, s3, 0x2000
	s_nop 0
	global_load_lds_dwordx4 v[226:227], off
	s_waitcnt vmcnt(6)
	s_waitcnt lgkmcnt(0)
	s_barrier
	s_setprio 1
	s_waitcnt lgkmcnt(0)
	v_mfma_f32_16x16x32_bf16 v[60:63], v[144:147], v[186:189], v[60:63]
	v_mfma_f32_16x16x32_bf16 v[56:59], v[160:163], v[186:189], v[56:59]
	v_mfma_f32_16x16x32_bf16 v[40:43], v[160:163], v[194:197], v[40:43]
	v_mfma_f32_16x16x32_bf16 v[44:47], v[144:147], v[194:197], v[44:47]
	v_mfma_f32_16x16x32_bf16 v[28:31], v[144:147], v[208:211], v[28:31]
	v_mfma_f32_16x16x32_bf16 v[24:27], v[160:163], v[208:211], v[24:27]
	v_mfma_f32_16x16x32_bf16 v[8:11], v[160:163], v[216:219], v[8:11]
	v_mfma_f32_16x16x32_bf16 v[12:15], v[144:147], v[216:219], v[12:15]
	v_mfma_f32_16x16x32_bf16 v[60:63], v[148:151], v[190:193], v[60:63]
	v_mfma_f32_16x16x32_bf16 v[56:59], v[164:167], v[190:193], v[56:59]
	v_mfma_f32_16x16x32_bf16 v[40:43], v[164:167], v[198:201], v[40:43]
	v_mfma_f32_16x16x32_bf16 v[44:47], v[148:151], v[198:201], v[44:47]
	v_mfma_f32_16x16x32_bf16 v[28:31], v[148:151], v[212:215], v[28:31]
	v_mfma_f32_16x16x32_bf16 v[24:27], v[164:167], v[212:215], v[24:27]
	v_lshl_add_u64 v[226:227], s[58:59], 0, v[134:135]
	s_mov_b32 m0, s34
	s_nop 0
	global_load_lds_dwordx4 v[226:227], off
	v_mfma_f32_16x16x32_bf16 v[8:11], v[164:167], v[220:223], v[8:11]
	v_mfma_f32_16x16x32_bf16 v[12:15], v[148:151], v[220:223], v[12:15]
	s_setprio 0
	s_setprio 1
	v_mfma_f32_16x16x32_bf16 v[52:55], v[168:171], v[186:189], v[52:55]
	v_mfma_f32_16x16x32_bf16 v[48:51], v[176:179], v[186:189], v[48:51]
	v_mfma_f32_16x16x32_bf16 v[32:35], v[176:179], v[194:197], v[32:35]
	v_mfma_f32_16x16x32_bf16 v[36:39], v[168:171], v[194:197], v[36:39]
	v_mfma_f32_16x16x32_bf16 v[20:23], v[168:171], v[208:211], v[20:23]
	v_mfma_f32_16x16x32_bf16 v[16:19], v[176:179], v[208:211], v[16:19]
	v_mfma_f32_16x16x32_bf16 v[0:3], v[176:179], v[216:219], v[0:3]
	v_mfma_f32_16x16x32_bf16 v[4:7], v[168:171], v[216:219], v[4:7]
	v_mfma_f32_16x16x32_bf16 v[52:55], v[172:175], v[190:193], v[52:55]
	v_mfma_f32_16x16x32_bf16 v[48:51], v[182:185], v[190:193], v[48:51]
	v_mfma_f32_16x16x32_bf16 v[32:35], v[182:185], v[198:201], v[32:35]
	v_mfma_f32_16x16x32_bf16 v[36:39], v[172:175], v[198:201], v[36:39]
	v_mfma_f32_16x16x32_bf16 v[20:23], v[172:175], v[212:215], v[20:23]
	v_mfma_f32_16x16x32_bf16 v[16:19], v[182:185], v[212:215], v[16:19]
	v_lshl_add_u64 v[228:229], s[58:59], 0, v[130:131]
	s_mov_b32 m0, s53
	s_nop 0
	global_load_lds_dwordx4 v[228:229], off
	v_mfma_f32_16x16x32_bf16 v[0:3], v[182:185], v[220:223], v[0:3]
	v_mfma_f32_16x16x32_bf16 v[4:7], v[172:175], v[220:223], v[4:7]
	s_setprio 0
	s_barrier
; #define PG8_STAGE(bufoff, gbase, voff) do { _Pragma("unroll") for (int _i = 0; _i < 2; ++_i) \
;         __builtin_amdgcn_global_load_lds((const unsigned*)((const char*)(gbase) + (voff)[_i]), (PG8_LAS unsigned*)(lds + (bufoff) + ldsw + _i * 8192), 16, 0, 0); } while (0)
; #define PG8_LDA(dst, b, h) do { _Pragma("unroll") for (int m = 0; m < 4; ++m) _Pragma("unroll") for (int k = 0; k < 2; ++k) dst[m][k] = *(const PG8_LAS bf16x8*)(lds + PG8_SA(b, h) + aoff + m * 2048 + k * 1024); } while (0)
; #define PG8_LDB(dst, b, h) do { _Pragma("unroll") for (int n = 0; n < 2; ++n) _Pragma("unroll") for (int k = 0; k < 2; ++k) dst[n][k] = *(const PG8_LAS bf16x8*)(lds + PG8_SB(b, h) + boff + n * 2048 + k * 1024); } while (0)
; #define PG8_MMA(ai, bj, At, Bt) do { __builtin_amdgcn_s_setprio(1); _Pragma("unroll") for (int m = 0; m < 4; ++m) _Pragma("unroll") for (int n = 0; n < 2; ++n) _Pragma("unroll") for (int k = 0; k < 2; ++k) \
;         acc[ai][bj][m][n] = __builtin_amdgcn_mfma_f32_16x16x32_bf16(Bt[n][k], At[m][k], acc[ai][bj][m][n], 0, 0, 0); __builtin_amdgcn_s_setprio(0); } while (0)
; #define PG8_WAIT_V(n) asm volatile("s_waitcnt vmcnt(" #n ")" ::: "memory")
; #define PG8_WAIT_L(n) asm volatile("s_waitcnt lgkmcnt(" #n ")" ::: "memory")
; #define PG8_BAR __builtin_amdgcn_s_barrier()
; #define PG8_SCHED __builtin_amdgcn_sched_barrier(0)
; template <class Epi, class Sched, bool ALIGN_EPI = false, bool SP2 = false>
; __device__ __forceinline__ void gemm_phase(PG8_LAS unsigned char* lds, const Gemm g, const Sched& S, const Epi& E) {
;     ...
;             PG8_LDB(B0, 1, 0); PG8_LDB(B1, 1, 1); PG8_SCHED; PG8_LDA(At, 1, 0); PG8_STAGE(PG8_SA(0, 1), a2 + hstep, voffA);
;             PG8_WAIT_V(8); PG8_WAIT_L(0); PG8_BAR; PG8_MMA(0, 0, At, B0); PG8_MMA(0, 1, At, B1); PG8_BAR; PG8_SCHED;
	s_add_i32 s3, 0, 0x18000
	v_add_u32_e32 v159, s3, v153
	s_add_i32 s33, 0, 0x1c000
	ds_read_b128 v[144:147], v159
	ds_read_b128 v[148:151], v159 offset:1024
	ds_read_b128 v[160:163], v159 offset:2048
	ds_read_b128 v[164:167], v159 offset:3072
	v_add_u32_e32 v159, s33, v153
	ds_read_b128 v[168:171], v159
	ds_read_b128 v[172:175], v159 offset:1024
	ds_read_b128 v[176:179], v159 offset:2048
	ds_read_b128 v[182:185], v159 offset:3072
	s_add_u32 s58, s58, 0x40000
	s_addc_u32 s59, s59, 0
	s_mov_b32 m0, s60
	v_lshl_add_u64 v[230:231], s[58:59], 0, v[134:135]
	ds_read_b128 v[186:189], v157 offset:32768
	ds_read_b128 v[190:193], v157 offset:33792
	ds_read_b128 v[194:197], v157 offset:34816
	ds_read_b128 v[198:201], v157 offset:35840
	ds_read_b128 v[208:211], v157 offset:36864
	ds_read_b128 v[212:215], v157 offset:37888
	ds_read_b128 v[216:219], v157 offset:38912
	ds_read_b128 v[220:223], v157 offset:39936
	global_load_lds_dwordx4 v[230:231], off
	v_lshl_add_u64 v[230:231], s[58:59], 0, v[130:131]
	s_mov_b32 m0, s61
	s_nop 0
	global_load_lds_dwordx4 v[230:231], off
	s_waitcnt vmcnt(8)
	s_waitcnt lgkmcnt(0)
	s_barrier
	s_setprio 1
	s_waitcnt lgkmcnt(0)
	v_mfma_f32_16x16x32_bf16 v[124:127], v[144:147], v[186:189], v[124:127]
	v_mfma_f32_16x16x32_bf16 v[120:123], v[160:163], v[186:189], v[120:123]
	v_mfma_f32_16x16x32_bf16 v[104:107], v[160:163], v[194:197], v[104:107]
	v_mfma_f32_16x16x32_bf16 v[108:111], v[144:147], v[194:197], v[108:111]
	v_mfma_f32_16x16x32_bf16 v[92:95], v[144:147], v[208:211], v[92:95]
	v_mfma_f32_16x16x32_bf16 v[88:91], v[160:163], v[208:211], v[88:91]
	v_mfma_f32_16x16x32_bf16 v[72:75], v[160:163], v[216:219], v[72:75]
	v_mfma_f32_16x16x32_bf16 v[76:79], v[144:147], v[216:219], v[76:79]
	v_mfma_f32_16x16x32_bf16 v[124:127], v[148:151], v[190:193], v[124:127]
	v_mfma_f32_16x16x32_bf16 v[120:123], v[164:167], v[190:193], v[120:123]
	v_mfma_f32_16x16x32_bf16 v[104:107], v[164:167], v[198:201], v[104:107]
	v_mfma_f32_16x16x32_bf16 v[108:111], v[148:151], v[198:201], v[108:111]
	v_mfma_f32_16x16x32_bf16 v[92:95], v[148:151], v[212:215], v[92:95]
	v_mfma_f32_16x16x32_bf16 v[88:91], v[164:167], v[212:215], v[88:91]
	v_mfma_f32_16x16x32_bf16 v[72:75], v[164:167], v[220:223], v[72:75]
	v_mfma_f32_16x16x32_bf16 v[76:79], v[148:151], v[220:223], v[76:79]
	s_setprio 0
	s_setprio 1
	v_mfma_f32_16x16x32_bf16 v[116:119], v[168:171], v[186:189], v[116:119]
	v_mfma_f32_16x16x32_bf16 v[112:115], v[176:179], v[186:189], v[112:115]
	v_mfma_f32_16x16x32_bf16 v[96:99], v[176:179], v[194:197], v[96:99]
	v_mfma_f32_16x16x32_bf16 v[100:103], v[168:171], v[194:197], v[100:103]
	v_mfma_f32_16x16x32_bf16 v[84:87], v[168:171], v[208:211], v[84:87]
	v_mfma_f32_16x16x32_bf16 v[80:83], v[176:179], v[208:211], v[80:83]
	v_mfma_f32_16x16x32_bf16 v[64:67], v[176:179], v[216:219], v[64:67]
	v_mfma_f32_16x16x32_bf16 v[68:71], v[168:171], v[216:219], v[68:71]
	v_mfma_f32_16x16x32_bf16 v[116:119], v[172:175], v[190:193], v[116:119]
	v_mfma_f32_16x16x32_bf16 v[112:115], v[182:185], v[190:193], v[112:115]
	v_mfma_f32_16x16x32_bf16 v[96:99], v[182:185], v[198:201], v[96:99]
	v_mfma_f32_16x16x32_bf16 v[100:103], v[172:175], v[198:201], v[100:103]
	v_mfma_f32_16x16x32_bf16 v[84:87], v[172:175], v[212:215], v[84:87]
	v_mfma_f32_16x16x32_bf16 v[80:83], v[182:185], v[212:215], v[80:83]
	v_mfma_f32_16x16x32_bf16 v[64:67], v[182:185], v[220:223], v[64:67]
	v_mfma_f32_16x16x32_bf16 v[68:71], v[172:175], v[220:223], v[68:71]
	s_setprio 0
	s_barrier
; #define PG8_STAGE(bufoff, gbase, voff) do { _Pragma("unroll") for (int _i = 0; _i < 2; ++_i) \
;         __builtin_amdgcn_global_load_lds((const unsigned*)((const char*)(gbase) + (voff)[_i]), (PG8_LAS unsigned*)(lds + (bufoff) + ldsw + _i * 8192), 16, 0, 0); } while (0)
; #define PG8_LDA(dst, b, h) do { _Pragma("unroll") for (int m = 0; m < 4; ++m) _Pragma("unroll") for (int k = 0; k < 2; ++k) dst[m][k] = *(const PG8_LAS bf16x8*)(lds + PG8_SA(b, h) + aoff + m * 2048 + k * 1024); } while (0)
; #define PG8_MMA(ai, bj, At, Bt) do { __builtin_amdgcn_s_setprio(1); _Pragma("unroll") for (int m = 0; m < 4; ++m) _Pragma("unroll") for (int n = 0; n < 2; ++n) _Pragma("unroll") for (int k = 0; k < 2; ++k) \
;         acc[ai][bj][m][n] = __builtin_amdgcn_mfma_f32_16x16x32_bf16(Bt[n][k], At[m][k], acc[ai][bj][m][n], 0, 0, 0); __builtin_amdgcn_s_setprio(0); } while (0)
; #define PG8_WAIT_V(n) asm volatile("s_waitcnt vmcnt(" #n ")" ::: "memory")
; #define PG8_WAIT_L(n) asm volatile("s_waitcnt lgkmcnt(" #n ")" ::: "memory")
; #define PG8_BAR __builtin_amdgcn_s_barrier()
; #define PG8_SCHED __builtin_amdgcn_sched_barrier(0)
; __device__ __forceinline__ float row_rs(const float* ssp, int row) { const unsigned long long v = ((const unsigned long long*)ssp)[row];
;     return __builtin_amdgcn_rsqf((float)v * (1.0f / 4294967296.0f) * (1.0f / 1024.0f) + RMS_EPS); }
; template <class Epi, class Sched, bool ALIGN_EPI = false, bool SP2 = false>
; __device__ __forceinline__ void gemm_phase(PG8_LAS unsigned char* lds, const Gemm g, const Sched& S, const Epi& E) {
;     ...
;             PG8_LDA(At, 1, 1); PG8_STAGE(PG8_SB(1, 0), b3, voffB); PG8_STAGE(PG8_SB(1, 1), b3 + hstep, voffB); PG8_STAGE(PG8_SA(1, 0), a3, voffA);
;             PG8_WAIT_V(8); PG8_WAIT_L(0); PG8_BAR; PG8_MMA(1, 0, At, B0); PG8_MMA(1, 1, At, B1); PG8_BAR; PG8_SCHED;
	s_add_i32 s3, s3, s14
	v_lshl_add_u64 v[202:203], v[202:203], 0, s[36:37]
	s_mov_b32 m0, s3
	ds_read_b128 v[186:189], v157 offset:49152
	ds_read_b128 v[190:193], v157 offset:50176
	ds_read_b128 v[194:197], v157 offset:51200
	ds_read_b128 v[198:201], v157 offset:52224
	ds_read_b128 v[208:211], v157 offset:53248
	ds_read_b128 v[212:215], v157 offset:54272
	ds_read_b128 v[216:219], v157 offset:55296
	ds_read_b128 v[220:223], v157 offset:56320
	global_load_lds_dwordx4 v[202:203], off
	s_add_i32 m0, s3, 0x2000
	s_add_u32 s56, s56, 0x40080
	v_lshl_add_u64 v[202:203], v[224:225], 0, s[36:37]
	s_addc_u32 s57, s57, 0
	s_add_i32 s3, s33, s14
	global_load_lds_dwordx4 v[202:203], off
	v_lshl_add_u64 v[202:203], s[56:57], 0, v[132:133]
	s_mov_b32 m0, s3
	s_nop 0
	global_load_lds_dwordx4 v[202:203], off
	v_lshl_add_u64 v[202:203], s[56:57], 0, v[128:129]
	s_add_i32 m0, s3, 0x2000
	s_nop 0
	global_load_lds_dwordx4 v[202:203], off
	s_waitcnt vmcnt(6)
	s_waitcnt lgkmcnt(0)
	s_barrier
	s_setprio 1
	s_waitcnt lgkmcnt(0)
	v_mfma_f32_16x16x32_bf16 v[60:63], v[144:147], v[186:189], v[60:63]
	v_mfma_f32_16x16x32_bf16 v[56:59], v[160:163], v[186:189], v[56:59]
	v_mfma_f32_16x16x32_bf16 v[40:43], v[160:163], v[194:197], v[40:43]
	v_mfma_f32_16x16x32_bf16 v[44:47], v[144:147], v[194:197], v[44:47]
	v_mfma_f32_16x16x32_bf16 v[28:31], v[144:147], v[208:211], v[28:31]
	v_mfma_f32_16x16x32_bf16 v[24:27], v[160:163], v[208:211], v[24:27]
	v_mfma_f32_16x16x32_bf16 v[8:11], v[160:163], v[216:219], v[8:11]
	v_mfma_f32_16x16x32_bf16 v[12:15], v[144:147], v[216:219], v[12:15]
	v_mfma_f32_16x16x32_bf16 v[60:63], v[148:151], v[190:193], v[60:63]
	v_mfma_f32_16x16x32_bf16 v[56:59], v[164:167], v[190:193], v[56:59]
	v_mfma_f32_16x16x32_bf16 v[40:43], v[164:167], v[198:201], v[40:43]
	v_mfma_f32_16x16x32_bf16 v[44:47], v[148:151], v[198:201], v[44:47]
	v_mfma_f32_16x16x32_bf16 v[28:31], v[148:151], v[212:215], v[28:31]
	v_mfma_f32_16x16x32_bf16 v[24:27], v[164:167], v[212:215], v[24:27]
	v_lshl_add_u64 v[202:203], v[226:227], 0, s[36:37]
	s_mov_b32 m0, s63
	s_nop 0
	global_load_lds_dwordx4 v[202:203], off
	v_mfma_f32_16x16x32_bf16 v[8:11], v[164:167], v[220:223], v[8:11]
	v_mfma_f32_16x16x32_bf16 v[12:15], v[148:151], v[220:223], v[12:15]
	s_setprio 0
	s_setprio 1
	v_mfma_f32_16x16x32_bf16 v[52:55], v[168:171], v[186:189], v[52:55]
	v_mfma_f32_16x16x32_bf16 v[48:51], v[176:179], v[186:189], v[48:51]
	v_mfma_f32_16x16x32_bf16 v[32:35], v[176:179], v[194:197], v[32:35]
	v_mfma_f32_16x16x32_bf16 v[36:39], v[168:171], v[194:197], v[36:39]
	v_mfma_f32_16x16x32_bf16 v[20:23], v[168:171], v[208:211], v[20:23]
	v_mfma_f32_16x16x32_bf16 v[16:19], v[176:179], v[208:211], v[16:19]
	v_mfma_f32_16x16x32_bf16 v[0:3], v[176:179], v[216:219], v[0:3]
	v_mfma_f32_16x16x32_bf16 v[4:7], v[168:171], v[216:219], v[4:7]
	v_mfma_f32_16x16x32_bf16 v[52:55], v[172:175], v[190:193], v[52:55]
	v_mfma_f32_16x16x32_bf16 v[48:51], v[182:185], v[190:193], v[48:51]
	v_mfma_f32_16x16x32_bf16 v[32:35], v[182:185], v[198:201], v[32:35]
	v_mfma_f32_16x16x32_bf16 v[36:39], v[172:175], v[198:201], v[36:39]
	v_mfma_f32_16x16x32_bf16 v[20:23], v[172:175], v[212:215], v[20:23]
	v_mfma_f32_16x16x32_bf16 v[16:19], v[182:185], v[212:215], v[16:19]
	v_lshl_add_u64 v[202:203], v[228:229], 0, s[36:37]
	s_mov_b32 m0, s64
	s_nop 0
	global_load_lds_dwordx4 v[202:203], off
	v_mfma_f32_16x16x32_bf16 v[0:3], v[182:185], v[220:223], v[0:3]
	v_mfma_f32_16x16x32_bf16 v[4:7], v[172:175], v[220:223], v[4:7]
	s_setprio 0
	s_barrier
	s_add_i32 s83, s83, 2
	s_add_u32 s54, s54, 0x100
	s_addc_u32 s55, s55, 0
	s_add_u32 s77, s77, 0x100
	s_addc_u32 s82, s82, 0
	s_cmp_gt_u32 s83, 13
	s_cbranch_scc0 .LBB0_957
	v_lshl_add_u32 v144, s52, 8, v152
	v_ashrrev_i32_e32 v145, 31, v144
	v_lshl_add_u64 v[150:151], v[144:145], 3, s[0:1]
	global_load_dwordx2 v[182:183], v[150:151], off
	global_load_dwordx2 v[184:185], v[150:151], off offset:128
	global_load_dwordx2 v[186:187], v[150:151], off offset:256
	global_load_dwordx2 v[188:189], v[150:151], off offset:384
	global_load_dwordx2 v[190:191], v[150:151], off offset:1024
	global_load_dwordx2 v[192:193], v[150:151], off offset:1152
	global_load_dwordx2 v[194:195], v[150:151], off offset:1280
	global_load_dwordx2 v[196:197], v[150:151], off offset:1408
	s_and_b64 vcc, exec, s[38:39]
	s_cbranch_vccz .LBB0_960
	s_barrier

; #define PG8_STAGE(bufoff, gbase, voff) do { _Pragma("unroll") for (int _i = 0; _i < 2; ++_i) \
;         __builtin_amdgcn_global_load_lds((const unsigned*)((const char*)(gbase) + (voff)[_i]), (PG8_LAS unsigned*)(lds + (bufoff) + ldsw + _i * 8192), 16, 0, 0); } while (0)
; #define PG8_LDA(dst, b, h) do { _Pragma("unroll") for (int m = 0; m < 4; ++m) _Pragma("unroll") for (int k = 0; k < 2; ++k) dst[m][k] = *(const PG8_LAS bf16x8*)(lds + PG8_SA(b, h) + aoff + m * 2048 + k * 1024); } while (0)
; #define PG8_LDB(dst, b, h) do { _Pragma("unroll") for (int n = 0; n < 2; ++n) _Pragma("unroll") for (int k = 0; k < 2; ++k) dst[n][k] = *(const PG8_LAS bf16x8*)(lds + PG8_SB(b, h) + boff + n * 2048 + k * 1024); } while (0)
; #define PG8_MMA(ai, bj, At, Bt) do { __builtin_amdgcn_s_setprio(1); _Pragma("unroll") for (int m = 0; m < 4; ++m) _Pragma("unroll") for (int n = 0; n < 2; ++n) _Pragma("unroll") for (int k = 0; k < 2; ++k) \
;         acc[ai][bj][m][n] = __builtin_amdgcn_mfma_f32_16x16x32_bf16(Bt[n][k], At[m][k], acc[ai][bj][m][n], 0, 0, 0); __builtin_amdgcn_s_setprio(0); } while (0)
; #define PG8_WAIT_V(n) asm volatile("s_waitcnt vmcnt(" #n ")" ::: "memory")
; #define PG8_WAIT_L(n) asm volatile("s_waitcnt lgkmcnt(" #n ")" ::: "memory")
; #define PG8_BAR __builtin_amdgcn_s_barrier()
; #define PG8_SCHED __builtin_amdgcn_sched_barrier(0)
; template <class Epi, class Sched, bool ALIGN_EPI = false, bool SP2 = false>
; __device__ __forceinline__ void gemm_phase(PG8_LAS unsigned char* lds, const Gemm g, const Sched& S, const Epi& E) {
;     ...
;         for (int t = 0; t < nt; t += 2) {
;             const bool last = (t == nt - 2);
;             const char* a1 = cA + (size_t)(t + 1) * kstep;
;             const char* a2 = last ? nA : cA + (size_t)(t + 2) * kstep; const char* b2 = last ? nB : cB + (size_t)(t + 2) * kstep;
;             const char* a3 = a2 + kstep; const char* b3 = b2 + kstep;
;             if (last && has_next) S.a_ready(nxt);
;             if constexpr (SP2) {
;             PG8_LDB(B0, 0, 0); PG8_LDB(B1, 0, 1); PG8_SCHED; PG8_LDA(At, 0, 0); PG8_STAGE(PG8_SA(1, 1), a1 + hstep, voffA);
;             PG8_WAIT_V(8); PG8_WAIT_L(0); PG8_BAR; PG8_MMA(0, 0, At, B0); PG8_MMA(0, 1, At, B1); PG8_BAR; PG8_SCHED;
;             PG8_LDA(At, 0, 1); PG8_STAGE(PG8_SB(0, 0), b2, voffB); PG8_STAGE(PG8_SB(0, 1), b2 + hstep, voffB); PG8_STAGE(PG8_SA(0, 0), a2, voffA);
.LBB0_1034:
	s_add_u32 s75, s52, 0x100
	s_addc_u32 s76, s53, 0
	s_mov_b32 s77, -2
	s_waitcnt lgkmcnt(0)
	ds_read_b128 v[144:147], v151
	ds_read_b128 v[156:159], v151 offset:1024
	ds_read_b128 v[160:163], v151 offset:2048
	ds_read_b128 v[164:167], v151 offset:3072
	ds_read_b128 v[168:171], v152
	ds_read_b128 v[172:175], v152 offset:1024
	ds_read_b128 v[176:179], v152 offset:2048
	ds_read_b128 v[182:185], v152 offset:3072
	s_add_u32 s52, s50, 0x100
	s_addc_u32 s53, s51, 0
	s_cmp_eq_u32 s77, 40
	s_cselect_b32 s57, s1, s53
	s_cselect_b32 s56, s0, s52
	s_cselect_b32 s55, s49, s76
	s_cselect_b32 s54, s48, s75
	v_lshl_add_u64 v[202:203], s[50:51], 0, v[136:137]
	s_add_i32 m0, s14, 0xc000
	ds_read_b128 v[186:189], v153
	ds_read_b128 v[190:193], v153 offset:1024
	ds_read_b128 v[194:197], v153 offset:2048
	ds_read_b128 v[198:201], v153 offset:3072
	ds_read_b128 v[208:211], v153 offset:4096
	ds_read_b128 v[212:215], v153 offset:5120
	ds_read_b128 v[216:219], v153 offset:6144
	ds_read_b128 v[220:223], v153 offset:7168
	global_load_lds_dwordx4 v[202:203], off
	v_lshl_add_u64 v[202:203], s[50:51], 0, v[138:139]
	s_add_i32 m0, s14, 0xe000
	s_nop 0
	global_load_lds_dwordx4 v[202:203], off
	s_waitcnt vmcnt(8)
	s_waitcnt lgkmcnt(0)
	s_barrier
	s_setprio 1
	s_waitcnt lgkmcnt(0)
	v_mfma_f32_16x16x32_bf16 v[124:127], v[144:147], v[186:189], 0
	v_mfma_f32_16x16x32_bf16 v[120:123], v[160:163], v[186:189], 0
	v_mfma_f32_16x16x32_bf16 v[104:107], v[160:163], v[194:197], 0
	v_mfma_f32_16x16x32_bf16 v[108:111], v[144:147], v[194:197], 0
	v_mfma_f32_16x16x32_bf16 v[92:95], v[144:147], v[208:211], 0
	v_mfma_f32_16x16x32_bf16 v[88:91], v[160:163], v[208:211], 0
	v_mfma_f32_16x16x32_bf16 v[72:75], v[160:163], v[216:219], 0
	v_mfma_f32_16x16x32_bf16 v[76:79], v[144:147], v[216:219], 0
	v_mfma_f32_16x16x32_bf16 v[124:127], v[156:159], v[190:193], v[124:127]
	v_mfma_f32_16x16x32_bf16 v[120:123], v[164:167], v[190:193], v[120:123]
	v_mfma_f32_16x16x32_bf16 v[104:107], v[164:167], v[198:201], v[104:107]
	v_mfma_f32_16x16x32_bf16 v[108:111], v[156:159], v[198:201], v[108:111]
	v_mfma_f32_16x16x32_bf16 v[92:95], v[156:159], v[212:215], v[92:95]
	v_mfma_f32_16x16x32_bf16 v[88:91], v[164:167], v[212:215], v[88:91]
	v_mfma_f32_16x16x32_bf16 v[72:75], v[164:167], v[220:223], v[72:75]
	v_mfma_f32_16x16x32_bf16 v[76:79], v[156:159], v[220:223], v[76:79]
	s_setprio 0
	s_setprio 1
	v_mfma_f32_16x16x32_bf16 v[116:119], v[168:171], v[186:189], 0
	v_mfma_f32_16x16x32_bf16 v[112:115], v[176:179], v[186:189], 0
	v_mfma_f32_16x16x32_bf16 v[96:99], v[176:179], v[194:197], 0
	v_mfma_f32_16x16x32_bf16 v[100:103], v[168:171], v[194:197], 0
	v_mfma_f32_16x16x32_bf16 v[84:87], v[168:171], v[208:211], 0
	v_mfma_f32_16x16x32_bf16 v[80:83], v[176:179], v[208:211], 0
	v_mfma_f32_16x16x32_bf16 v[64:67], v[176:179], v[216:219], 0
	v_mfma_f32_16x16x32_bf16 v[68:71], v[168:171], v[216:219], 0
	v_mfma_f32_16x16x32_bf16 v[116:119], v[172:175], v[190:193], v[116:119]
	v_mfma_f32_16x16x32_bf16 v[112:115], v[182:185], v[190:193], v[112:115]
	v_mfma_f32_16x16x32_bf16 v[96:99], v[182:185], v[198:201], v[96:99]
	v_mfma_f32_16x16x32_bf16 v[100:103], v[172:175], v[198:201], v[100:103]
	v_mfma_f32_16x16x32_bf16 v[84:87], v[172:175], v[212:215], v[84:87]
	v_mfma_f32_16x16x32_bf16 v[80:83], v[182:185], v[212:215], v[80:83]
	v_mfma_f32_16x16x32_bf16 v[64:67], v[182:185], v[220:223], v[64:67]
	v_mfma_f32_16x16x32_bf16 v[68:71], v[172:175], v[220:223], v[68:71]
	s_setprio 0
	s_barrier
	s_add_i32 s50, s61, s3
	v_lshl_add_u64 v[202:203], s[54:55], 0, v[130:131]
	s_mov_b32 m0, s50
	ds_read_b128 v[186:189], v153 offset:16384
	ds_read_b128 v[190:193], v153 offset:17408
	ds_read_b128 v[194:197], v153 offset:18432
	ds_read_b128 v[198:201], v153 offset:19456
	ds_read_b128 v[208:211], v153 offset:20480
	ds_read_b128 v[212:215], v153 offset:21504
	ds_read_b128 v[216:219], v153 offset:22528
	ds_read_b128 v[220:223], v153 offset:23552
	global_load_lds_dwordx4 v[202:203], off
	s_add_i32 m0, s50, 0x2000
	s_add_u32 s50, s54, 0xb0000
	v_lshl_add_u64 v[224:225], s[54:55], 0, v[134:135]
	s_addc_u32 s51, s55, 0
	s_add_i32 s78, s62, s3
	global_load_lds_dwordx4 v[224:225], off
	v_lshl_add_u64 v[226:227], s[50:51], 0, v[130:131]
	s_mov_b32 m0, s78
	global_load_lds_dwordx4 v[226:227], off
	v_lshl_add_u64 v[226:227], s[50:51], 0, v[134:135]
	s_add_i32 m0, s78, 0x2000
	s_nop 0
	global_load_lds_dwordx4 v[226:227], off
	s_waitcnt vmcnt(6)
	s_waitcnt lgkmcnt(0)
	s_barrier
; #define PG8_STAGE(bufoff, gbase, voff) do { _Pragma("unroll") for (int _i = 0; _i < 2; ++_i) \
;         __builtin_amdgcn_global_load_lds((const unsigned*)((const char*)(gbase) + (voff)[_i]), (PG8_LAS unsigned*)(lds + (bufoff) + ldsw + _i * 8192), 16, 0, 0); } while (0)
; #define PG8_LDA(dst, b, h) do { _Pragma("unroll") for (int m = 0; m < 4; ++m) _Pragma("unroll") for (int k = 0; k < 2; ++k) dst[m][k] = *(const PG8_LAS bf16x8*)(lds + PG8_SA(b, h) + aoff + m * 2048 + k * 1024); } while (0)
; #define PG8_LDB(dst, b, h) do { _Pragma("unroll") for (int n = 0; n < 2; ++n) _Pragma("unroll") for (int k = 0; k < 2; ++k) dst[n][k] = *(const PG8_LAS bf16x8*)(lds + PG8_SB(b, h) + boff + n * 2048 + k * 1024); } while (0)
; #define PG8_MMA(ai, bj, At, Bt) do { __builtin_amdgcn_s_setprio(1); _Pragma("unroll") for (int m = 0; m < 4; ++m) _Pragma("unroll") for (int n = 0; n < 2; ++n) _Pragma("unroll") for (int k = 0; k < 2; ++k) \
;         acc[ai][bj][m][n] = __builtin_amdgcn_mfma_f32_16x16x32_bf16(Bt[n][k], At[m][k], acc[ai][bj][m][n], 0, 0, 0); __builtin_amdgcn_s_setprio(0); } while (0)
; #define PG8_WAIT_V(n) asm volatile("s_waitcnt vmcnt(" #n ")" ::: "memory")
; #define PG8_WAIT_L(n) asm volatile("s_waitcnt lgkmcnt(" #n ")" ::: "memory")
; #define PG8_BAR __builtin_amdgcn_s_barrier()
; #define PG8_SCHED __builtin_amdgcn_sched_barrier(0)
; template <class Epi, class Sched, bool ALIGN_EPI = false, bool SP2 = false>
; __device__ __forceinline__ void gemm_phase(PG8_LAS unsigned char* lds, const Gemm g, const Sched& S, const Epi& E) {
;     ...
;             PG8_WAIT_V(8); PG8_WAIT_L(0); PG8_BAR; PG8_MMA(0, 0, At, B0); PG8_MMA(0, 1, At, B1); PG8_BAR; PG8_SCHED;
;             PG8_LDA(At, 0, 1); PG8_STAGE(PG8_SB(0, 0), b2, voffB); PG8_STAGE(PG8_SB(0, 1), b2 + hstep, voffB); PG8_STAGE(PG8_SA(0, 0), a2, voffA);
;             PG8_WAIT_V(8); PG8_WAIT_L(0); PG8_BAR; PG8_MMA(1, 0, At, B0); PG8_MMA(1, 1, At, B1); PG8_BAR; PG8_SCHED;
;             PG8_LDB(B0, 1, 0); PG8_LDB(B1, 1, 1); PG8_SCHED; PG8_LDA(At, 1, 0); PG8_STAGE(PG8_SA(0, 1), a2 + hstep, voffA);
;             PG8_WAIT_V(8); PG8_WAIT_L(0); PG8_BAR; PG8_MMA(0, 0, At, B0); PG8_MMA(0, 1, At, B1); PG8_BAR; PG8_SCHED;
	s_setprio 1
	s_waitcnt lgkmcnt(0)
	v_mfma_f32_16x16x32_bf16 v[60:63], v[144:147], v[186:189], 0
	v_mfma_f32_16x16x32_bf16 v[56:59], v[160:163], v[186:189], 0
	v_mfma_f32_16x16x32_bf16 v[40:43], v[160:163], v[194:197], 0
	v_mfma_f32_16x16x32_bf16 v[44:47], v[144:147], v[194:197], 0
	v_mfma_f32_16x16x32_bf16 v[28:31], v[144:147], v[208:211], 0
	v_mfma_f32_16x16x32_bf16 v[24:27], v[160:163], v[208:211], 0
	v_mfma_f32_16x16x32_bf16 v[8:11], v[160:163], v[216:219], 0
	v_mfma_f32_16x16x32_bf16 v[12:15], v[144:147], v[216:219], 0
	v_mfma_f32_16x16x32_bf16 v[60:63], v[156:159], v[190:193], v[60:63]
	v_mfma_f32_16x16x32_bf16 v[56:59], v[164:167], v[190:193], v[56:59]
	v_mfma_f32_16x16x32_bf16 v[40:43], v[164:167], v[198:201], v[40:43]
	v_mfma_f32_16x16x32_bf16 v[44:47], v[156:159], v[198:201], v[44:47]
	v_mfma_f32_16x16x32_bf16 v[28:31], v[156:159], v[212:215], v[28:31]
	v_mfma_f32_16x16x32_bf16 v[24:27], v[164:167], v[212:215], v[24:27]
	v_lshl_add_u64 v[226:227], s[56:57], 0, v[128:129]
	s_mov_b32 m0, s14
	s_nop 0
	global_load_lds_dwordx4 v[226:227], off
	v_mfma_f32_16x16x32_bf16 v[8:11], v[164:167], v[220:223], v[8:11]
	v_mfma_f32_16x16x32_bf16 v[12:15], v[156:159], v[220:223], v[12:15]
	s_setprio 0
	s_setprio 1
	v_mfma_f32_16x16x32_bf16 v[52:55], v[168:171], v[186:189], 0
	v_mfma_f32_16x16x32_bf16 v[48:51], v[176:179], v[186:189], 0
	v_mfma_f32_16x16x32_bf16 v[32:35], v[176:179], v[194:197], 0
	v_mfma_f32_16x16x32_bf16 v[36:39], v[168:171], v[194:197], 0
	v_mfma_f32_16x16x32_bf16 v[20:23], v[168:171], v[208:211], 0
	v_mfma_f32_16x16x32_bf16 v[16:19], v[176:179], v[208:211], 0
	v_mfma_f32_16x16x32_bf16 v[0:3], v[176:179], v[216:219], 0
	v_mfma_f32_16x16x32_bf16 v[4:7], v[168:171], v[216:219], 0
	v_mfma_f32_16x16x32_bf16 v[52:55], v[172:175], v[190:193], v[52:55]
	v_mfma_f32_16x16x32_bf16 v[48:51], v[182:185], v[190:193], v[48:51]
	v_mfma_f32_16x16x32_bf16 v[32:35], v[182:185], v[198:201], v[32:35]
	v_mfma_f32_16x16x32_bf16 v[36:39], v[172:175], v[198:201], v[36:39]
	v_mfma_f32_16x16x32_bf16 v[20:23], v[172:175], v[212:215], v[20:23]
	v_mfma_f32_16x16x32_bf16 v[16:19], v[182:185], v[212:215], v[16:19]
	v_lshl_add_u64 v[228:229], s[56:57], 0, v[132:133]
	s_mov_b32 m0, s15
	s_nop 0
	global_load_lds_dwordx4 v[228:229], off
	v_mfma_f32_16x16x32_bf16 v[0:3], v[182:185], v[220:223], v[0:3]
	v_mfma_f32_16x16x32_bf16 v[4:7], v[172:175], v[220:223], v[4:7]
	s_setprio 0
	s_barrier
	s_add_i32 s78, 0, 0x18000
	v_add_u32_e32 v155, s78, v149
	s_add_i32 s79, 0, 0x1c000
	ds_read_b128 v[144:147], v155
	ds_read_b128 v[156:159], v155 offset:1024
	ds_read_b128 v[160:163], v155 offset:2048
	ds_read_b128 v[164:167], v155 offset:3072
	v_add_u32_e32 v155, s79, v149
	ds_read_b128 v[168:171], v155
	ds_read_b128 v[172:175], v155 offset:1024
	ds_read_b128 v[176:179], v155 offset:2048
	ds_read_b128 v[182:185], v155 offset:3072
	s_add_u32 s50, s56, 0xb0000
	s_addc_u32 s51, s57, 0
	s_mov_b32 m0, s33
	v_lshl_add_u64 v[230:231], s[50:51], 0, v[128:129]
	ds_read_b128 v[186:189], v153 offset:32768
	ds_read_b128 v[190:193], v153 offset:33792
	ds_read_b128 v[194:197], v153 offset:34816
	ds_read_b128 v[198:201], v153 offset:35840
	ds_read_b128 v[208:211], v153 offset:36864
	ds_read_b128 v[212:215], v153 offset:37888
	ds_read_b128 v[216:219], v153 offset:38912
	ds_read_b128 v[220:223], v153 offset:39936
	global_load_lds_dwordx4 v[230:231], off
	v_lshl_add_u64 v[230:231], s[50:51], 0, v[132:133]
	s_mov_b32 m0, s34
	s_nop 0
	global_load_lds_dwordx4 v[230:231], off
	s_waitcnt vmcnt(8)
	s_waitcnt lgkmcnt(0)
	s_barrier
	s_setprio 1
	s_waitcnt lgkmcnt(0)
	v_mfma_f32_16x16x32_bf16 v[124:127], v[144:147], v[186:189], v[124:127]
	v_mfma_f32_16x16x32_bf16 v[120:123], v[160:163], v[186:189], v[120:123]
	v_mfma_f32_16x16x32_bf16 v[104:107], v[160:163], v[194:197], v[104:107]
	v_mfma_f32_16x16x32_bf16 v[108:111], v[144:147], v[194:197], v[108:111]
	v_mfma_f32_16x16x32_bf16 v[92:95], v[144:147], v[208:211], v[92:95]
	v_mfma_f32_16x16x32_bf16 v[88:91], v[160:163], v[208:211], v[88:91]
	v_mfma_f32_16x16x32_bf16 v[72:75], v[160:163], v[216:219], v[72:75]
	v_mfma_f32_16x16x32_bf16 v[76:79], v[144:147], v[216:219], v[76:79]
	v_mfma_f32_16x16x32_bf16 v[124:127], v[156:159], v[190:193], v[124:127]
	v_mfma_f32_16x16x32_bf16 v[120:123], v[164:167], v[190:193], v[120:123]
	v_mfma_f32_16x16x32_bf16 v[104:107], v[164:167], v[198:201], v[104:107]
	v_mfma_f32_16x16x32_bf16 v[108:111], v[156:159], v[198:201], v[108:111]
	v_mfma_f32_16x16x32_bf16 v[92:95], v[156:159], v[212:215], v[92:95]
	v_mfma_f32_16x16x32_bf16 v[88:91], v[164:167], v[212:215], v[88:91]
	v_mfma_f32_16x16x32_bf16 v[72:75], v[164:167], v[220:223], v[72:75]
	v_mfma_f32_16x16x32_bf16 v[76:79], v[156:159], v[220:223], v[76:79]
	s_setprio 0
	s_setprio 1
	v_mfma_f32_16x16x32_bf16 v[116:119], v[168:171], v[186:189], v[116:119]
	v_mfma_f32_16x16x32_bf16 v[112:115], v[176:179], v[186:189], v[112:115]
	v_mfma_f32_16x16x32_bf16 v[96:99], v[176:179], v[194:197], v[96:99]
	v_mfma_f32_16x16x32_bf16 v[100:103], v[168:171], v[194:197], v[100:103]
	v_mfma_f32_16x16x32_bf16 v[84:87], v[168:171], v[208:211], v[84:87]
	v_mfma_f32_16x16x32_bf16 v[80:83], v[176:179], v[208:211], v[80:83]
	v_mfma_f32_16x16x32_bf16 v[64:67], v[176:179], v[216:219], v[64:67]
	v_mfma_f32_16x16x32_bf16 v[68:71], v[168:171], v[216:219], v[68:71]
	v_mfma_f32_16x16x32_bf16 v[116:119], v[172:175], v[190:193], v[116:119]
	v_mfma_f32_16x16x32_bf16 v[112:115], v[182:185], v[190:193], v[112:115]
	v_mfma_f32_16x16x32_bf16 v[96:99], v[182:185], v[198:201], v[96:99]
	v_mfma_f32_16x16x32_bf16 v[100:103], v[172:175], v[198:201], v[100:103]
	v_mfma_f32_16x16x32_bf16 v[84:87], v[172:175], v[212:215], v[84:87]
	v_mfma_f32_16x16x32_bf16 v[80:83], v[182:185], v[212:215], v[80:83]
	v_mfma_f32_16x16x32_bf16 v[64:67], v[182:185], v[220:223], v[64:67]
	v_mfma_f32_16x16x32_bf16 v[68:71], v[172:175], v[220:223], v[68:71]
	s_setprio 0
	s_barrier
; #define PG8_STAGE(bufoff, gbase, voff) do { _Pragma("unroll") for (int _i = 0; _i < 2; ++_i) \
;         __builtin_amdgcn_global_load_lds((const unsigned*)((const char*)(gbase) + (voff)[_i]), (PG8_LAS unsigned*)(lds + (bufoff) + ldsw + _i * 8192), 16, 0, 0); } while (0)
; #define PG8_LDA(dst, b, h) do { _Pragma("unroll") for (int m = 0; m < 4; ++m) _Pragma("unroll") for (int k = 0; k < 2; ++k) dst[m][k] = *(const PG8_LAS bf16x8*)(lds + PG8_SA(b, h) + aoff + m * 2048 + k * 1024); } while (0)
; #define PG8_LDB(dst, b, h) do { _Pragma("unroll") for (int n = 0; n < 2; ++n) _Pragma("unroll") for (int k = 0; k < 2; ++k) dst[n][k] = *(const PG8_LAS bf16x8*)(lds + PG8_SB(b, h) + boff + n * 2048 + k * 1024); } while (0)
; #define PG8_MMA(ai, bj, At, Bt) do { __builtin_amdgcn_s_setprio(1); _Pragma("unroll") for (int m = 0; m < 4; ++m) _Pragma("unroll") for (int n = 0; n < 2; ++n) _Pragma("unroll") for (int k = 0; k < 2; ++k) \
;         acc[ai][bj][m][n] = __builtin_amdgcn_mfma_f32_16x16x32_bf16(Bt[n][k], At[m][k], acc[ai][bj][m][n], 0, 0, 0); __builtin_amdgcn_s_setprio(0); } while (0)
; #define PG8_WAIT_V(n) asm volatile("s_waitcnt vmcnt(" #n ")" ::: "memory")
; #define PG8_WAIT_L(n) asm volatile("s_waitcnt lgkmcnt(" #n ")" ::: "memory")
; #define PG8_BAR __builtin_amdgcn_s_barrier()
; #define PG8_SCHED __builtin_amdgcn_sched_barrier(0)
; template <class Epi, class Sched, bool ALIGN_EPI = false, bool SP2 = false>
; __device__ __forceinline__ void gemm_phase(PG8_LAS unsigned char* lds, const Gemm g, const Sched& S, const Epi& E) {
;     ...
;             PG8_LDB(B0, 0, 0); PG8_LDB(B1, 0, 1); PG8_SCHED; PG8_LDA(At, 0, 0); PG8_STAGE(PG8_SA(1, 1), a1 + hstep, voffA);
;     ...
;             PG8_LDA(At, 1, 1); PG8_STAGE(PG8_SB(1, 0), b3, voffB); PG8_STAGE(PG8_SB(1, 1), b3 + hstep, voffB); PG8_STAGE(PG8_SA(1, 0), a3, voffA);
;             PG8_WAIT_V(8); PG8_WAIT_L(0); PG8_BAR; PG8_MMA(1, 0, At, B0); PG8_MMA(1, 1, At, B1); PG8_BAR; PG8_SCHED;
	s_add_i32 s50, s78, s3
	v_lshl_add_u64 v[202:203], v[202:203], 0, s[42:43]
	s_mov_b32 m0, s50
	ds_read_b128 v[186:189], v153 offset:49152
	ds_read_b128 v[190:193], v153 offset:50176
	ds_read_b128 v[194:197], v153 offset:51200
	ds_read_b128 v[198:201], v153 offset:52224
	ds_read_b128 v[208:211], v153 offset:53248
	ds_read_b128 v[212:215], v153 offset:54272
	ds_read_b128 v[216:219], v153 offset:55296
	ds_read_b128 v[220:223], v153 offset:56320
	global_load_lds_dwordx4 v[202:203], off
	s_add_i32 m0, s50, 0x2000
	s_add_u32 s50, s54, 0xb0080
	v_lshl_add_u64 v[202:203], v[224:225], 0, s[42:43]
	s_addc_u32 s51, s55, 0
	s_add_i32 s54, s79, s3
	global_load_lds_dwordx4 v[202:203], off
	v_lshl_add_u64 v[202:203], s[50:51], 0, v[130:131]
	s_mov_b32 m0, s54
	s_nop 0
	global_load_lds_dwordx4 v[202:203], off
	v_lshl_add_u64 v[202:203], s[50:51], 0, v[134:135]
	s_add_i32 m0, s54, 0x2000
	s_nop 0
	global_load_lds_dwordx4 v[202:203], off
	s_waitcnt vmcnt(6)
	s_waitcnt lgkmcnt(0)
	s_barrier
	s_setprio 1
	s_waitcnt lgkmcnt(0)
	v_mfma_f32_16x16x32_bf16 v[60:63], v[144:147], v[186:189], v[60:63]
	v_mfma_f32_16x16x32_bf16 v[56:59], v[160:163], v[186:189], v[56:59]
	v_mfma_f32_16x16x32_bf16 v[40:43], v[160:163], v[194:197], v[40:43]
	v_mfma_f32_16x16x32_bf16 v[44:47], v[144:147], v[194:197], v[44:47]
	v_mfma_f32_16x16x32_bf16 v[28:31], v[144:147], v[208:211], v[28:31]
	v_mfma_f32_16x16x32_bf16 v[24:27], v[160:163], v[208:211], v[24:27]
	v_mfma_f32_16x16x32_bf16 v[8:11], v[160:163], v[216:219], v[8:11]
	v_mfma_f32_16x16x32_bf16 v[12:15], v[144:147], v[216:219], v[12:15]
	v_mfma_f32_16x16x32_bf16 v[60:63], v[156:159], v[190:193], v[60:63]
	v_mfma_f32_16x16x32_bf16 v[56:59], v[164:167], v[190:193], v[56:59]
	v_mfma_f32_16x16x32_bf16 v[40:43], v[164:167], v[198:201], v[40:43]
	v_mfma_f32_16x16x32_bf16 v[44:47], v[156:159], v[198:201], v[44:47]
	v_mfma_f32_16x16x32_bf16 v[28:31], v[156:159], v[212:215], v[28:31]
	v_mfma_f32_16x16x32_bf16 v[24:27], v[164:167], v[212:215], v[24:27]
	v_lshl_add_u64 v[202:203], v[226:227], 0, s[42:43]
	s_mov_b32 m0, s59
	s_nop 0
	global_load_lds_dwordx4 v[202:203], off
	v_mfma_f32_16x16x32_bf16 v[8:11], v[164:167], v[220:223], v[8:11]
	v_mfma_f32_16x16x32_bf16 v[12:15], v[156:159], v[220:223], v[12:15]
	s_setprio 0
	s_setprio 1
	v_mfma_f32_16x16x32_bf16 v[52:55], v[168:171], v[186:189], v[52:55]
	v_mfma_f32_16x16x32_bf16 v[48:51], v[176:179], v[186:189], v[48:51]
	v_mfma_f32_16x16x32_bf16 v[32:35], v[176:179], v[194:197], v[32:35]
	v_mfma_f32_16x16x32_bf16 v[36:39], v[168:171], v[194:197], v[36:39]
	v_mfma_f32_16x16x32_bf16 v[20:23], v[168:171], v[208:211], v[20:23]
	v_mfma_f32_16x16x32_bf16 v[16:19], v[176:179], v[208:211], v[16:19]
	v_mfma_f32_16x16x32_bf16 v[0:3], v[176:179], v[216:219], v[0:3]
	v_mfma_f32_16x16x32_bf16 v[4:7], v[168:171], v[216:219], v[4:7]
	v_mfma_f32_16x16x32_bf16 v[52:55], v[172:175], v[190:193], v[52:55]
	v_mfma_f32_16x16x32_bf16 v[48:51], v[182:185], v[190:193], v[48:51]
	v_mfma_f32_16x16x32_bf16 v[32:35], v[182:185], v[198:201], v[32:35]
	v_mfma_f32_16x16x32_bf16 v[36:39], v[172:175], v[198:201], v[36:39]
	v_mfma_f32_16x16x32_bf16 v[20:23], v[172:175], v[212:215], v[20:23]
	v_mfma_f32_16x16x32_bf16 v[16:19], v[182:185], v[212:215], v[16:19]
	v_lshl_add_u64 v[202:203], v[228:229], 0, s[42:43]
	s_mov_b32 m0, s60
	s_nop 0
	global_load_lds_dwordx4 v[202:203], off
	v_mfma_f32_16x16x32_bf16 v[0:3], v[182:185], v[220:223], v[0:3]
	v_mfma_f32_16x16x32_bf16 v[4:7], v[172:175], v[220:223], v[4:7]
	s_setprio 0
	s_barrier
	s_add_i32 s77, s77, 2
	s_add_u32 s75, s75, 0x100
	s_addc_u32 s76, s76, 0
	s_mov_b64 s[50:51], s[52:53]
.LBB0_1035:
	ds_read_b128 v[144:147], v151
	ds_read_b128 v[156:159], v151 offset:1024
	ds_read_b128 v[160:163], v151 offset:2048
	ds_read_b128 v[164:167], v151 offset:3072
	ds_read_b128 v[168:171], v152
	ds_read_b128 v[172:175], v152 offset:1024
	ds_read_b128 v[176:179], v152 offset:2048
	ds_read_b128 v[182:185], v152 offset:3072
	s_add_u32 s52, s50, 0x100
	s_addc_u32 s53, s51, 0
	s_cmp_eq_u32 s77, 40
	s_cselect_b32 s57, s1, s53
	s_cselect_b32 s56, s0, s52
	s_cselect_b32 s55, s49, s76
	s_cselect_b32 s54, s48, s75
	v_lshl_add_u64 v[202:203], s[50:51], 0, v[136:137]
	s_add_i32 m0, s14, 0xc000
	ds_read_b128 v[186:189], v153
	ds_read_b128 v[190:193], v153 offset:1024
	ds_read_b128 v[194:197], v153 offset:2048
	ds_read_b128 v[198:201], v153 offset:3072
	ds_read_b128 v[208:211], v153 offset:4096
	ds_read_b128 v[212:215], v153 offset:5120
	ds_read_b128 v[216:219], v153 offset:6144
	ds_read_b128 v[220:223], v153 offset:7168
	global_load_lds_dwordx4 v[202:203], off
	v_lshl_add_u64 v[202:203], s[50:51], 0, v[138:139]
	s_add_i32 m0, s14, 0xe000
	s_nop 0
	global_load_lds_dwordx4 v[202:203], off
	s_waitcnt vmcnt(8)
	s_waitcnt lgkmcnt(0)
	s_barrier
; #define PG8_STAGE(bufoff, gbase, voff) do { _Pragma("unroll") for (int _i = 0; _i < 2; ++_i) \
;         __builtin_amdgcn_global_load_lds((const unsigned*)((const char*)(gbase) + (voff)[_i]), (PG8_LAS unsigned*)(lds + (bufoff) + ldsw + _i * 8192), 16, 0, 0); } while (0)
; #define PG8_LDA(dst, b, h) do { _Pragma("unroll") for (int m = 0; m < 4; ++m) _Pragma("unroll") for (int k = 0; k < 2; ++k) dst[m][k] = *(const PG8_LAS bf16x8*)(lds + PG8_SA(b, h) + aoff + m * 2048 + k * 1024); } while (0)
; #define PG8_MMA(ai, bj, At, Bt) do { __builtin_amdgcn_s_setprio(1); _Pragma("unroll") for (int m = 0; m < 4; ++m) _Pragma("unroll") for (int n = 0; n < 2; ++n) _Pragma("unroll") for (int k = 0; k < 2; ++k) \
;         acc[ai][bj][m][n] = __builtin_amdgcn_mfma_f32_16x16x32_bf16(Bt[n][k], At[m][k], acc[ai][bj][m][n], 0, 0, 0); __builtin_amdgcn_s_setprio(0); } while (0)
; #define PG8_WAIT_V(n) asm volatile("s_waitcnt vmcnt(" #n ")" ::: "memory")
; #define PG8_WAIT_L(n) asm volatile("s_waitcnt lgkmcnt(" #n ")" ::: "memory")
; #define PG8_BAR __builtin_amdgcn_s_barrier()
; #define PG8_SCHED __builtin_amdgcn_sched_barrier(0)
; template <class Epi, class Sched, bool ALIGN_EPI = false, bool SP2 = false>
; __device__ __forceinline__ void gemm_phase(PG8_LAS unsigned char* lds, const Gemm g, const Sched& S, const Epi& E) {
;     ...
;             PG8_WAIT_V(8); PG8_WAIT_L(0); PG8_BAR; PG8_MMA(0, 0, At, B0); PG8_MMA(0, 1, At, B1); PG8_BAR; PG8_SCHED;
;             PG8_LDA(At, 0, 1); PG8_STAGE(PG8_SB(0, 0), b2, voffB); PG8_STAGE(PG8_SB(0, 1), b2 + hstep, voffB); PG8_STAGE(PG8_SA(0, 0), a2, voffA);
;             PG8_WAIT_V(8); PG8_WAIT_L(0); PG8_BAR; PG8_MMA(1, 0, At, B0); PG8_MMA(1, 1, At, B1); PG8_BAR; PG8_SCHED;
	s_setprio 1
	s_waitcnt lgkmcnt(0)
	v_mfma_f32_16x16x32_bf16 v[124:127], v[144:147], v[186:189], v[124:127]
	v_mfma_f32_16x16x32_bf16 v[120:123], v[160:163], v[186:189], v[120:123]
	v_mfma_f32_16x16x32_bf16 v[104:107], v[160:163], v[194:197], v[104:107]
	v_mfma_f32_16x16x32_bf16 v[108:111], v[144:147], v[194:197], v[108:111]
	v_mfma_f32_16x16x32_bf16 v[92:95], v[144:147], v[208:211], v[92:95]
	v_mfma_f32_16x16x32_bf16 v[88:91], v[160:163], v[208:211], v[88:91]
	v_mfma_f32_16x16x32_bf16 v[72:75], v[160:163], v[216:219], v[72:75]
	v_mfma_f32_16x16x32_bf16 v[76:79], v[144:147], v[216:219], v[76:79]
	v_mfma_f32_16x16x32_bf16 v[124:127], v[156:159], v[190:193], v[124:127]
	v_mfma_f32_16x16x32_bf16 v[120:123], v[164:167], v[190:193], v[120:123]
	v_mfma_f32_16x16x32_bf16 v[104:107], v[164:167], v[198:201], v[104:107]
	v_mfma_f32_16x16x32_bf16 v[108:111], v[156:159], v[198:201], v[108:111]
	v_mfma_f32_16x16x32_bf16 v[92:95], v[156:159], v[212:215], v[92:95]
	v_mfma_f32_16x16x32_bf16 v[88:91], v[164:167], v[212:215], v[88:91]
	v_mfma_f32_16x16x32_bf16 v[72:75], v[164:167], v[220:223], v[72:75]
	v_mfma_f32_16x16x32_bf16 v[76:79], v[156:159], v[220:223], v[76:79]
	s_setprio 0
	s_setprio 1
	v_mfma_f32_16x16x32_bf16 v[116:119], v[168:171], v[186:189], v[116:119]
	v_mfma_f32_16x16x32_bf16 v[112:115], v[176:179], v[186:189], v[112:115]
	v_mfma_f32_16x16x32_bf16 v[96:99], v[176:179], v[194:197], v[96:99]
	v_mfma_f32_16x16x32_bf16 v[100:103], v[168:171], v[194:197], v[100:103]
	v_mfma_f32_16x16x32_bf16 v[84:87], v[168:171], v[208:211], v[84:87]
	v_mfma_f32_16x16x32_bf16 v[80:83], v[176:179], v[208:211], v[80:83]
	v_mfma_f32_16x16x32_bf16 v[64:67], v[176:179], v[216:219], v[64:67]
	v_mfma_f32_16x16x32_bf16 v[68:71], v[168:171], v[216:219], v[68:71]
	v_mfma_f32_16x16x32_bf16 v[116:119], v[172:175], v[190:193], v[116:119]
	v_mfma_f32_16x16x32_bf16 v[112:115], v[182:185], v[190:193], v[112:115]
	v_mfma_f32_16x16x32_bf16 v[96:99], v[182:185], v[198:201], v[96:99]
	v_mfma_f32_16x16x32_bf16 v[100:103], v[172:175], v[198:201], v[100:103]
	v_mfma_f32_16x16x32_bf16 v[84:87], v[172:175], v[212:215], v[84:87]
	v_mfma_f32_16x16x32_bf16 v[80:83], v[182:185], v[212:215], v[80:83]
	v_mfma_f32_16x16x32_bf16 v[64:67], v[182:185], v[220:223], v[64:67]
	v_mfma_f32_16x16x32_bf16 v[68:71], v[172:175], v[220:223], v[68:71]
	s_setprio 0
	s_barrier
	s_add_i32 s50, s61, s3
	v_lshl_add_u64 v[202:203], s[54:55], 0, v[130:131]
	s_mov_b32 m0, s50
	ds_read_b128 v[186:189], v153 offset:16384
	ds_read_b128 v[190:193], v153 offset:17408
	ds_read_b128 v[194:197], v153 offset:18432
	ds_read_b128 v[198:201], v153 offset:19456
	ds_read_b128 v[208:211], v153 offset:20480
	ds_read_b128 v[212:215], v153 offset:21504
	ds_read_b128 v[216:219], v153 offset:22528
	ds_read_b128 v[220:223], v153 offset:23552
	global_load_lds_dwordx4 v[202:203], off
	s_add_i32 m0, s50, 0x2000
	s_add_u32 s50, s54, 0xb0000
	v_lshl_add_u64 v[224:225], s[54:55], 0, v[134:135]
	s_addc_u32 s51, s55, 0
	s_add_i32 s78, s62, s3
	global_load_lds_dwordx4 v[224:225], off
	v_lshl_add_u64 v[226:227], s[50:51], 0, v[130:131]
	s_mov_b32 m0, s78
	global_load_lds_dwordx4 v[226:227], off
	v_lshl_add_u64 v[226:227], s[50:51], 0, v[134:135]
	s_add_i32 m0, s78, 0x2000
	s_nop 0
	global_load_lds_dwordx4 v[226:227], off
	s_waitcnt vmcnt(6)
	s_waitcnt lgkmcnt(0)
	s_barrier
	s_setprio 1
	s_waitcnt lgkmcnt(0)
	v_mfma_f32_16x16x32_bf16 v[60:63], v[144:147], v[186:189], v[60:63]
	v_mfma_f32_16x16x32_bf16 v[56:59], v[160:163], v[186:189], v[56:59]
	v_mfma_f32_16x16x32_bf16 v[40:43], v[160:163], v[194:197], v[40:43]
	v_mfma_f32_16x16x32_bf16 v[44:47], v[144:147], v[194:197], v[44:47]
	v_mfma_f32_16x16x32_bf16 v[28:31], v[144:147], v[208:211], v[28:31]
	v_mfma_f32_16x16x32_bf16 v[24:27], v[160:163], v[208:211], v[24:27]
	v_mfma_f32_16x16x32_bf16 v[8:11], v[160:163], v[216:219], v[8:11]
	v_mfma_f32_16x16x32_bf16 v[12:15], v[144:147], v[216:219], v[12:15]
	v_mfma_f32_16x16x32_bf16 v[60:63], v[156:159], v[190:193], v[60:63]
	v_mfma_f32_16x16x32_bf16 v[56:59], v[164:167], v[190:193], v[56:59]
	v_mfma_f32_16x16x32_bf16 v[40:43], v[164:167], v[198:201], v[40:43]
	v_mfma_f32_16x16x32_bf16 v[44:47], v[156:159], v[198:201], v[44:47]
	v_mfma_f32_16x16x32_bf16 v[28:31], v[156:159], v[212:215], v[28:31]
	v_mfma_f32_16x16x32_bf16 v[24:27], v[164:167], v[212:215], v[24:27]
	v_lshl_add_u64 v[226:227], s[56:57], 0, v[128:129]
	s_mov_b32 m0, s14
	s_nop 0
	global_load_lds_dwordx4 v[226:227], off
	v_mfma_f32_16x16x32_bf16 v[8:11], v[164:167], v[220:223], v[8:11]
	v_mfma_f32_16x16x32_bf16 v[12:15], v[156:159], v[220:223], v[12:15]
	s_setprio 0
	s_setprio 1
	v_mfma_f32_16x16x32_bf16 v[52:55], v[168:171], v[186:189], v[52:55]
	v_mfma_f32_16x16x32_bf16 v[48:51], v[176:179], v[186:189], v[48:51]
	v_mfma_f32_16x16x32_bf16 v[32:35], v[176:179], v[194:197], v[32:35]
	v_mfma_f32_16x16x32_bf16 v[36:39], v[168:171], v[194:197], v[36:39]
	v_mfma_f32_16x16x32_bf16 v[20:23], v[168:171], v[208:211], v[20:23]
	v_mfma_f32_16x16x32_bf16 v[16:19], v[176:179], v[208:211], v[16:19]
	v_mfma_f32_16x16x32_bf16 v[0:3], v[176:179], v[216:219], v[0:3]
	v_mfma_f32_16x16x32_bf16 v[4:7], v[168:171], v[216:219], v[4:7]
	v_mfma_f32_16x16x32_bf16 v[52:55], v[172:175], v[190:193], v[52:55]
	v_mfma_f32_16x16x32_bf16 v[48:51], v[182:185], v[190:193], v[48:51]
	v_mfma_f32_16x16x32_bf16 v[32:35], v[182:185], v[198:201], v[32:35]
	v_mfma_f32_16x16x32_bf16 v[36:39], v[172:175], v[198:201], v[36:39]
	v_mfma_f32_16x16x32_bf16 v[20:23], v[172:175], v[212:215], v[20:23]
	v_mfma_f32_16x16x32_bf16 v[16:19], v[182:185], v[212:215], v[16:19]
	v_lshl_add_u64 v[228:229], s[56:57], 0, v[132:133]
	s_mov_b32 m0, s15
	s_nop 0
	global_load_lds_dwordx4 v[228:229], off
	v_mfma_f32_16x16x32_bf16 v[0:3], v[182:185], v[220:223], v[0:3]
	v_mfma_f32_16x16x32_bf16 v[4:7], v[172:175], v[220:223], v[4:7]
	s_setprio 0
	s_barrier
; #define PG8_STAGE(bufoff, gbase, voff) do { _Pragma("unroll") for (int _i = 0; _i < 2; ++_i) \
;         __builtin_amdgcn_global_load_lds((const unsigned*)((const char*)(gbase) + (voff)[_i]), (PG8_LAS unsigned*)(lds + (bufoff) + ldsw + _i * 8192), 16, 0, 0); } while (0)
; #define PG8_LDA(dst, b, h) do { _Pragma("unroll") for (int m = 0; m < 4; ++m) _Pragma("unroll") for (int k = 0; k < 2; ++k) dst[m][k] = *(const PG8_LAS bf16x8*)(lds + PG8_SA(b, h) + aoff + m * 2048 + k * 1024); } while (0)
; #define PG8_LDB(dst, b, h) do { _Pragma("unroll") for (int n = 0; n < 2; ++n) _Pragma("unroll") for (int k = 0; k < 2; ++k) dst[n][k] = *(const PG8_LAS bf16x8*)(lds + PG8_SB(b, h) + boff + n * 2048 + k * 1024); } while (0)
; #define PG8_MMA(ai, bj, At, Bt) do { __builtin_amdgcn_s_setprio(1); _Pragma("unroll") for (int m = 0; m < 4; ++m) _Pragma("unroll") for (int n = 0; n < 2; ++n) _Pragma("unroll") for (int k = 0; k < 2; ++k) \
;         acc[ai][bj][m][n] = __builtin_amdgcn_mfma_f32_16x16x32_bf16(Bt[n][k], At[m][k], acc[ai][bj][m][n], 0, 0, 0); __builtin_amdgcn_s_setprio(0); } while (0)
; #define PG8_WAIT_V(n) asm volatile("s_waitcnt vmcnt(" #n ")" ::: "memory")
; #define PG8_WAIT_L(n) asm volatile("s_waitcnt lgkmcnt(" #n ")" ::: "memory")
; #define PG8_BAR __builtin_amdgcn_s_barrier()
; #define PG8_SCHED __builtin_amdgcn_sched_barrier(0)
; template <class Epi, class Sched, bool ALIGN_EPI = false, bool SP2 = false>
; __device__ __forceinline__ void gemm_phase(PG8_LAS unsigned char* lds, const Gemm g, const Sched& S, const Epi& E) {
;     ...
;             PG8_LDB(B0, 1, 0); PG8_LDB(B1, 1, 1); PG8_SCHED; PG8_LDA(At, 1, 0); PG8_STAGE(PG8_SA(0, 1), a2 + hstep, voffA);
;             PG8_WAIT_V(8); PG8_WAIT_L(0); PG8_BAR; PG8_MMA(0, 0, At, B0); PG8_MMA(0, 1, At, B1); PG8_BAR; PG8_SCHED;
	s_add_i32 s78, 0, 0x18000
	v_add_u32_e32 v155, s78, v149
	s_add_i32 s79, 0, 0x1c000
	ds_read_b128 v[144:147], v155
	ds_read_b128 v[156:159], v155 offset:1024
	ds_read_b128 v[160:163], v155 offset:2048
	ds_read_b128 v[164:167], v155 offset:3072
	v_add_u32_e32 v155, s79, v149
	ds_read_b128 v[168:171], v155
	ds_read_b128 v[172:175], v155 offset:1024
	ds_read_b128 v[176:179], v155 offset:2048
	ds_read_b128 v[182:185], v155 offset:3072
	s_add_u32 s50, s56, 0xb0000
	s_addc_u32 s51, s57, 0
	s_mov_b32 m0, s33
	v_lshl_add_u64 v[230:231], s[50:51], 0, v[128:129]
	ds_read_b128 v[186:189], v153 offset:32768
	ds_read_b128 v[190:193], v153 offset:33792
	ds_read_b128 v[194:197], v153 offset:34816
	ds_read_b128 v[198:201], v153 offset:35840
	ds_read_b128 v[208:211], v153 offset:36864
	ds_read_b128 v[212:215], v153 offset:37888
	ds_read_b128 v[216:219], v153 offset:38912
	ds_read_b128 v[220:223], v153 offset:39936
	global_load_lds_dwordx4 v[230:231], off
	v_lshl_add_u64 v[230:231], s[50:51], 0, v[132:133]
	s_mov_b32 m0, s34
	s_nop 0
	global_load_lds_dwordx4 v[230:231], off
	s_waitcnt vmcnt(8)
	s_waitcnt lgkmcnt(0)
	s_barrier
	s_setprio 1
	s_waitcnt lgkmcnt(0)
	v_mfma_f32_16x16x32_bf16 v[124:127], v[144:147], v[186:189], v[124:127]
	v_mfma_f32_16x16x32_bf16 v[120:123], v[160:163], v[186:189], v[120:123]
	v_mfma_f32_16x16x32_bf16 v[104:107], v[160:163], v[194:197], v[104:107]
	v_mfma_f32_16x16x32_bf16 v[108:111], v[144:147], v[194:197], v[108:111]
	v_mfma_f32_16x16x32_bf16 v[92:95], v[144:147], v[208:211], v[92:95]
	v_mfma_f32_16x16x32_bf16 v[88:91], v[160:163], v[208:211], v[88:91]
	v_mfma_f32_16x16x32_bf16 v[72:75], v[160:163], v[216:219], v[72:75]
	v_mfma_f32_16x16x32_bf16 v[76:79], v[144:147], v[216:219], v[76:79]
	v_mfma_f32_16x16x32_bf16 v[124:127], v[156:159], v[190:193], v[124:127]
	v_mfma_f32_16x16x32_bf16 v[120:123], v[164:167], v[190:193], v[120:123]
	v_mfma_f32_16x16x32_bf16 v[104:107], v[164:167], v[198:201], v[104:107]
	v_mfma_f32_16x16x32_bf16 v[108:111], v[156:159], v[198:201], v[108:111]
	v_mfma_f32_16x16x32_bf16 v[92:95], v[156:159], v[212:215], v[92:95]
	v_mfma_f32_16x16x32_bf16 v[88:91], v[164:167], v[212:215], v[88:91]
	v_mfma_f32_16x16x32_bf16 v[72:75], v[164:167], v[220:223], v[72:75]
	v_mfma_f32_16x16x32_bf16 v[76:79], v[156:159], v[220:223], v[76:79]
	s_setprio 0
	s_setprio 1
	v_mfma_f32_16x16x32_bf16 v[116:119], v[168:171], v[186:189], v[116:119]
	v_mfma_f32_16x16x32_bf16 v[112:115], v[176:179], v[186:189], v[112:115]
	v_mfma_f32_16x16x32_bf16 v[96:99], v[176:179], v[194:197], v[96:99]
	v_mfma_f32_16x16x32_bf16 v[100:103], v[168:171], v[194:197], v[100:103]
	v_mfma_f32_16x16x32_bf16 v[84:87], v[168:171], v[208:211], v[84:87]
	v_mfma_f32_16x16x32_bf16 v[80:83], v[176:179], v[208:211], v[80:83]
	v_mfma_f32_16x16x32_bf16 v[64:67], v[176:179], v[216:219], v[64:67]
	v_mfma_f32_16x16x32_bf16 v[68:71], v[168:171], v[216:219], v[68:71]
	v_mfma_f32_16x16x32_bf16 v[116:119], v[172:175], v[190:193], v[116:119]
	v_mfma_f32_16x16x32_bf16 v[112:115], v[182:185], v[190:193], v[112:115]
	v_mfma_f32_16x16x32_bf16 v[96:99], v[182:185], v[198:201], v[96:99]
	v_mfma_f32_16x16x32_bf16 v[100:103], v[172:175], v[198:201], v[100:103]
	v_mfma_f32_16x16x32_bf16 v[84:87], v[172:175], v[212:215], v[84:87]
	v_mfma_f32_16x16x32_bf16 v[80:83], v[182:185], v[212:215], v[80:83]
	v_mfma_f32_16x16x32_bf16 v[64:67], v[182:185], v[220:223], v[64:67]
	v_mfma_f32_16x16x32_bf16 v[68:71], v[172:175], v[220:223], v[68:71]
	s_setprio 0
	s_barrier
; #define PG8_STAGE(bufoff, gbase, voff) do { _Pragma("unroll") for (int _i = 0; _i < 2; ++_i) \
;         __builtin_amdgcn_global_load_lds((const unsigned*)((const char*)(gbase) + (voff)[_i]), (PG8_LAS unsigned*)(lds + (bufoff) + ldsw + _i * 8192), 16, 0, 0); } while (0)
; #define PG8_LDA(dst, b, h) do { _Pragma("unroll") for (int m = 0; m < 4; ++m) _Pragma("unroll") for (int k = 0; k < 2; ++k) dst[m][k] = *(const PG8_LAS bf16x8*)(lds + PG8_SA(b, h) + aoff + m * 2048 + k * 1024); } while (0)
; #define PG8_MMA(ai, bj, At, Bt) do { __builtin_amdgcn_s_setprio(1); _Pragma("unroll") for (int m = 0; m < 4; ++m) _Pragma("unroll") for (int n = 0; n < 2; ++n) _Pragma("unroll") for (int k = 0; k < 2; ++k) \
;         acc[ai][bj][m][n] = __builtin_amdgcn_mfma_f32_16x16x32_bf16(Bt[n][k], At[m][k], acc[ai][bj][m][n], 0, 0, 0); __builtin_amdgcn_s_setprio(0); } while (0)
; #define PG8_WAIT_V(n) asm volatile("s_waitcnt vmcnt(" #n ")" ::: "memory")
; #define PG8_WAIT_L(n) asm volatile("s_waitcnt lgkmcnt(" #n ")" ::: "memory")
; #define PG8_BAR __builtin_amdgcn_s_barrier()
; #define PG8_SCHED __builtin_amdgcn_sched_barrier(0)
; template <class Epi, class Sched, bool ALIGN_EPI = false, bool SP2 = false>
; __device__ __forceinline__ void gemm_phase(PG8_LAS unsigned char* lds, const Gemm g, const Sched& S, const Epi& E) {
;     ...
;             PG8_LDA(At, 1, 1); PG8_STAGE(PG8_SB(1, 0), b3, voffB); PG8_STAGE(PG8_SB(1, 1), b3 + hstep, voffB); PG8_STAGE(PG8_SA(1, 0), a3, voffA);
;             PG8_WAIT_V(8); PG8_WAIT_L(0); PG8_BAR; PG8_MMA(1, 0, At, B0); PG8_MMA(1, 1, At, B1); PG8_BAR; PG8_SCHED;
;     ...
;         if constexpr (ALIGN_EPI) { if (wr == 0) PG8_BAR; }
	s_add_i32 s50, s78, s3
	v_lshl_add_u64 v[202:203], v[202:203], 0, s[42:43]
	s_mov_b32 m0, s50
	ds_read_b128 v[186:189], v153 offset:49152
	ds_read_b128 v[190:193], v153 offset:50176
	ds_read_b128 v[194:197], v153 offset:51200
	ds_read_b128 v[198:201], v153 offset:52224
	ds_read_b128 v[208:211], v153 offset:53248
	ds_read_b128 v[212:215], v153 offset:54272
	ds_read_b128 v[216:219], v153 offset:55296
	ds_read_b128 v[220:223], v153 offset:56320
	global_load_lds_dwordx4 v[202:203], off
	s_add_i32 m0, s50, 0x2000
	s_add_u32 s50, s54, 0xb0080
	v_lshl_add_u64 v[202:203], v[224:225], 0, s[42:43]
	s_addc_u32 s51, s55, 0
	s_add_i32 s54, s79, s3
	global_load_lds_dwordx4 v[202:203], off
	v_lshl_add_u64 v[202:203], s[50:51], 0, v[130:131]
	s_mov_b32 m0, s54
	s_nop 0
	global_load_lds_dwordx4 v[202:203], off
	v_lshl_add_u64 v[202:203], s[50:51], 0, v[134:135]
	s_add_i32 m0, s54, 0x2000
	s_nop 0
	global_load_lds_dwordx4 v[202:203], off
	s_waitcnt vmcnt(6)
	s_waitcnt lgkmcnt(0)
	s_barrier
	s_setprio 1
	s_waitcnt lgkmcnt(0)
	v_mfma_f32_16x16x32_bf16 v[60:63], v[144:147], v[186:189], v[60:63]
	v_mfma_f32_16x16x32_bf16 v[56:59], v[160:163], v[186:189], v[56:59]
	v_mfma_f32_16x16x32_bf16 v[40:43], v[160:163], v[194:197], v[40:43]
	v_mfma_f32_16x16x32_bf16 v[44:47], v[144:147], v[194:197], v[44:47]
	v_mfma_f32_16x16x32_bf16 v[28:31], v[144:147], v[208:211], v[28:31]
	v_mfma_f32_16x16x32_bf16 v[24:27], v[160:163], v[208:211], v[24:27]
	v_mfma_f32_16x16x32_bf16 v[8:11], v[160:163], v[216:219], v[8:11]
	v_mfma_f32_16x16x32_bf16 v[12:15], v[144:147], v[216:219], v[12:15]
	v_mfma_f32_16x16x32_bf16 v[60:63], v[156:159], v[190:193], v[60:63]
	v_mfma_f32_16x16x32_bf16 v[56:59], v[164:167], v[190:193], v[56:59]
	v_mfma_f32_16x16x32_bf16 v[40:43], v[164:167], v[198:201], v[40:43]
	v_mfma_f32_16x16x32_bf16 v[44:47], v[156:159], v[198:201], v[44:47]
	v_mfma_f32_16x16x32_bf16 v[28:31], v[156:159], v[212:215], v[28:31]
	v_mfma_f32_16x16x32_bf16 v[24:27], v[164:167], v[212:215], v[24:27]
	v_lshl_add_u64 v[202:203], v[226:227], 0, s[42:43]
	s_mov_b32 m0, s59
	s_nop 0
	global_load_lds_dwordx4 v[202:203], off
	v_mfma_f32_16x16x32_bf16 v[8:11], v[164:167], v[220:223], v[8:11]
	v_mfma_f32_16x16x32_bf16 v[12:15], v[156:159], v[220:223], v[12:15]
	s_setprio 0
	s_setprio 1
	v_mfma_f32_16x16x32_bf16 v[52:55], v[168:171], v[186:189], v[52:55]
	v_mfma_f32_16x16x32_bf16 v[48:51], v[176:179], v[186:189], v[48:51]
	v_mfma_f32_16x16x32_bf16 v[32:35], v[176:179], v[194:197], v[32:35]
	v_mfma_f32_16x16x32_bf16 v[36:39], v[168:171], v[194:197], v[36:39]
	v_mfma_f32_16x16x32_bf16 v[20:23], v[168:171], v[208:211], v[20:23]
	v_mfma_f32_16x16x32_bf16 v[16:19], v[176:179], v[208:211], v[16:19]
	v_mfma_f32_16x16x32_bf16 v[0:3], v[176:179], v[216:219], v[0:3]
	v_mfma_f32_16x16x32_bf16 v[4:7], v[168:171], v[216:219], v[4:7]
	v_mfma_f32_16x16x32_bf16 v[52:55], v[172:175], v[190:193], v[52:55]
	v_mfma_f32_16x16x32_bf16 v[48:51], v[182:185], v[190:193], v[48:51]
	v_mfma_f32_16x16x32_bf16 v[32:35], v[182:185], v[198:201], v[32:35]
	v_mfma_f32_16x16x32_bf16 v[36:39], v[172:175], v[198:201], v[36:39]
	v_mfma_f32_16x16x32_bf16 v[20:23], v[172:175], v[212:215], v[20:23]
	v_mfma_f32_16x16x32_bf16 v[16:19], v[182:185], v[212:215], v[16:19]
	v_lshl_add_u64 v[202:203], v[228:229], 0, s[42:43]
	s_mov_b32 m0, s60
	s_nop 0
	global_load_lds_dwordx4 v[202:203], off
	v_mfma_f32_16x16x32_bf16 v[0:3], v[182:185], v[220:223], v[0:3]
	v_mfma_f32_16x16x32_bf16 v[4:7], v[172:175], v[220:223], v[4:7]
	s_setprio 0
	s_barrier
	s_add_i32 s77, s77, 2
	s_add_u32 s75, s75, 0x100
	s_addc_u32 s76, s76, 0
	s_cmp_gt_u32 s77, 41
	s_mov_b64 s[50:51], s[52:53]
	s_cbranch_scc0 .LBB0_1035
	s_and_b64 vcc, exec, s[44:45]
	s_cbranch_vccz .LBB0_1038
	s_barrier

; #define PG8_STAGE(bufoff, gbase, voff) do { _Pragma("unroll") for (int _i = 0; _i < 2; ++_i) \
;         __builtin_amdgcn_global_load_lds((const unsigned*)((const char*)(gbase) + (voff)[_i]), (PG8_LAS unsigned*)(lds + (bufoff) + ldsw + _i * 8192), 16, 0, 0); } while (0)
; #define PG8_LDA(dst, b, h) do { _Pragma("unroll") for (int m = 0; m < 4; ++m) _Pragma("unroll") for (int k = 0; k < 2; ++k) dst[m][k] = *(const PG8_LAS bf16x8*)(lds + PG8_SA(b, h) + aoff + m * 2048 + k * 1024); } while (0)
; #define PG8_LDB(dst, b, h) do { _Pragma("unroll") for (int n = 0; n < 2; ++n) _Pragma("unroll") for (int k = 0; k < 2; ++k) dst[n][k] = *(const PG8_LAS bf16x8*)(lds + PG8_SB(b, h) + boff + n * 2048 + k * 1024); } while (0)
; #define PG8_MMA(ai, bj, At, Bt) do { __builtin_amdgcn_s_setprio(1); _Pragma("unroll") for (int m = 0; m < 4; ++m) _Pragma("unroll") for (int n = 0; n < 2; ++n) _Pragma("unroll") for (int k = 0; k < 2; ++k) \
;         acc[ai][bj][m][n] = __builtin_amdgcn_mfma_f32_16x16x32_bf16(Bt[n][k], At[m][k], acc[ai][bj][m][n], 0, 0, 0); __builtin_amdgcn_s_setprio(0); } while (0)
; #define PG8_WAIT_V(n) asm volatile("s_waitcnt vmcnt(" #n ")" ::: "memory")
; #define PG8_WAIT_L(n) asm volatile("s_waitcnt lgkmcnt(" #n ")" ::: "memory")
; #define PG8_BAR __builtin_amdgcn_s_barrier()
; template <class Epi, class Sched, bool ALIGN_EPI = false, bool SP2 = false>
; __device__ __forceinline__ void gemm_phase(PG8_LAS unsigned char* lds, const Gemm g, const Sched& S, const Epi& E) {
;     ...
;         const bool has_next = S.next(ui + 1, nxt);
;         const char* nA = has_next ? (const char*)g.A + (size_t)nxt.pm * tstep : cA; const char* nB = has_next ? (const char*)g.Bt + (size_t)nxt.pn * tstep : cB;
;         for (int t = 0; t < nt; t += 2) {
;             const bool last = (t == nt - 2);
;             const char* a1 = cA + (size_t)(t + 1) * kstep;
;             const char* a2 = last ? nA : cA + (size_t)(t + 2) * kstep; const char* b2 = last ? nB : cB + (size_t)(t + 2) * kstep;
;             const char* a3 = a2 + kstep; const char* b3 = b2 + kstep;
;             if (last && has_next) S.a_ready(nxt);
;             if constexpr (SP2) {
;             PG8_LDB(B0, 0, 0); PG8_LDB(B1, 0, 1); PG8_SCHED; PG8_LDA(At, 0, 0); PG8_STAGE(PG8_SA(1, 1), a1 + hstep, voffA);
;             PG8_WAIT_V(8); PG8_WAIT_L(0); PG8_BAR; PG8_MMA(0, 0, At, B0); PG8_MMA(0, 1, At, B1); PG8_BAR; PG8_SCHED;
.LBB0_1118:
	s_ashr_i32 s45, s44, 31
	s_lshl_b64 s[48:49], s[44:45], 19
	s_add_u32 s48, s22, s48
	s_addc_u32 s49, s23, s49
	s_and_b64 s[50:51], s[10:11], exec
	s_cselect_b32 s45, s49, s55
	s_cselect_b32 s76, s48, s54
	s_ashr_i32 s43, s42, 31
	s_lshl_b64 s[50:51], s[42:43], 19
	s_add_u32 s50, s14, s50
	s_addc_u32 s51, s15, s51
	s_and_b64 s[58:59], s[10:11], exec
	s_cselect_b32 s43, s51, s57
	s_cselect_b32 s77, s50, s56
	s_add_u32 s54, s54, 0x40080
	s_addc_u32 s55, s55, 0
	s_add_u32 s82, s56, 0x100
	s_addc_u32 s83, s57, 0
	s_mov_b32 s84, -2
	ds_read_b128 v[144:147], v155
	ds_read_b128 v[148:151], v155 offset:1024
	ds_read_b128 v[160:163], v155 offset:2048
	ds_read_b128 v[164:167], v155 offset:3072
	ds_read_b128 v[168:171], v156
	ds_read_b128 v[172:175], v156 offset:1024
	ds_read_b128 v[176:179], v156 offset:2048
	ds_read_b128 v[182:185], v156 offset:3072
	s_add_u32 s56, s54, 0xfffc0080
	s_addc_u32 s57, s55, -1
	s_cmp_eq_u32 s84, 12
	s_cselect_b32 s59, s45, s57
	s_cselect_b32 s58, s76, s56
	s_cselect_b32 s57, s43, s83
	s_cselect_b32 s56, s77, s82
	v_lshl_add_u64 v[224:225], s[54:55], 0, v[136:137]
	s_add_i32 m0, s53, 0xc000
	ds_read_b128 v[186:189], v157
	ds_read_b128 v[190:193], v157 offset:1024
	ds_read_b128 v[194:197], v157 offset:2048
	ds_read_b128 v[198:201], v157 offset:3072
	ds_read_b128 v[208:211], v157 offset:4096
	ds_read_b128 v[212:215], v157 offset:5120
	ds_read_b128 v[216:219], v157 offset:6144
	ds_read_b128 v[220:223], v157 offset:7168
	global_load_lds_dwordx4 v[224:225], off
	v_lshl_add_u64 v[224:225], s[54:55], 0, v[138:139]
	s_add_i32 m0, s53, 0xe000
	s_nop 0
	global_load_lds_dwordx4 v[224:225], off
	s_waitcnt vmcnt(8)
	s_waitcnt lgkmcnt(0)
	s_barrier
	s_setprio 1
	s_waitcnt lgkmcnt(0)
	v_mfma_f32_16x16x32_bf16 v[124:127], v[144:147], v[186:189], 0
	v_mfma_f32_16x16x32_bf16 v[120:123], v[160:163], v[186:189], 0
	v_mfma_f32_16x16x32_bf16 v[104:107], v[160:163], v[194:197], 0
	v_mfma_f32_16x16x32_bf16 v[108:111], v[144:147], v[194:197], 0
	v_mfma_f32_16x16x32_bf16 v[92:95], v[144:147], v[208:211], 0
	v_mfma_f32_16x16x32_bf16 v[88:91], v[160:163], v[208:211], 0
	v_mfma_f32_16x16x32_bf16 v[72:75], v[160:163], v[216:219], 0
	v_mfma_f32_16x16x32_bf16 v[76:79], v[144:147], v[216:219], 0
	v_mfma_f32_16x16x32_bf16 v[124:127], v[148:151], v[190:193], v[124:127]
	v_mfma_f32_16x16x32_bf16 v[120:123], v[164:167], v[190:193], v[120:123]
	v_mfma_f32_16x16x32_bf16 v[104:107], v[164:167], v[198:201], v[104:107]
	v_mfma_f32_16x16x32_bf16 v[108:111], v[148:151], v[198:201], v[108:111]
	v_mfma_f32_16x16x32_bf16 v[92:95], v[148:151], v[212:215], v[92:95]
	v_mfma_f32_16x16x32_bf16 v[88:91], v[164:167], v[212:215], v[88:91]
	v_mfma_f32_16x16x32_bf16 v[72:75], v[164:167], v[220:223], v[72:75]
	v_mfma_f32_16x16x32_bf16 v[76:79], v[148:151], v[220:223], v[76:79]
	s_setprio 0
	s_setprio 1
	v_mfma_f32_16x16x32_bf16 v[116:119], v[168:171], v[186:189], 0
	v_mfma_f32_16x16x32_bf16 v[112:115], v[176:179], v[186:189], 0
	v_mfma_f32_16x16x32_bf16 v[96:99], v[176:179], v[194:197], 0
	v_mfma_f32_16x16x32_bf16 v[100:103], v[168:171], v[194:197], 0
	v_mfma_f32_16x16x32_bf16 v[84:87], v[168:171], v[208:211], 0
	v_mfma_f32_16x16x32_bf16 v[80:83], v[176:179], v[208:211], 0
	v_mfma_f32_16x16x32_bf16 v[64:67], v[176:179], v[216:219], 0
	v_mfma_f32_16x16x32_bf16 v[68:71], v[168:171], v[216:219], 0
	v_mfma_f32_16x16x32_bf16 v[116:119], v[172:175], v[190:193], v[116:119]
	v_mfma_f32_16x16x32_bf16 v[112:115], v[182:185], v[190:193], v[112:115]
	v_mfma_f32_16x16x32_bf16 v[96:99], v[182:185], v[198:201], v[96:99]
	v_mfma_f32_16x16x32_bf16 v[100:103], v[172:175], v[198:201], v[100:103]
	v_mfma_f32_16x16x32_bf16 v[84:87], v[172:175], v[212:215], v[84:87]
	v_mfma_f32_16x16x32_bf16 v[80:83], v[182:185], v[212:215], v[80:83]
	v_mfma_f32_16x16x32_bf16 v[64:67], v[182:185], v[220:223], v[64:67]
	v_mfma_f32_16x16x32_bf16 v[68:71], v[172:175], v[220:223], v[68:71]
	s_setprio 0
	s_barrier
	s_add_i32 s78, s66, s33
	v_lshl_add_u64 v[224:225], s[56:57], 0, v[132:133]
	s_mov_b32 m0, s78
	ds_read_b128 v[186:189], v157 offset:16384
	ds_read_b128 v[190:193], v157 offset:17408
	ds_read_b128 v[194:197], v157 offset:18432
	ds_read_b128 v[198:201], v157 offset:19456
	ds_read_b128 v[208:211], v157 offset:20480
	ds_read_b128 v[212:215], v157 offset:21504
	ds_read_b128 v[216:219], v157 offset:22528
	ds_read_b128 v[220:223], v157 offset:23552
	global_load_lds_dwordx4 v[224:225], off
	s_add_i32 m0, s78, 0x2000
	s_add_u32 s78, s56, 0x40000
	v_lshl_add_u64 v[226:227], s[56:57], 0, v[128:129]
	s_addc_u32 s79, s57, 0
	s_add_i32 s85, s67, s33
	global_load_lds_dwordx4 v[226:227], off
	v_lshl_add_u64 v[228:229], s[78:79], 0, v[132:133]
	s_mov_b32 m0, s85
	global_load_lds_dwordx4 v[228:229], off
	v_lshl_add_u64 v[228:229], s[78:79], 0, v[128:129]
	s_add_i32 m0, s85, 0x2000
	s_nop 0
	global_load_lds_dwordx4 v[228:229], off
	s_waitcnt vmcnt(6)
	s_waitcnt lgkmcnt(0)
	s_barrier
; #define PG8_STAGE(bufoff, gbase, voff) do { _Pragma("unroll") for (int _i = 0; _i < 2; ++_i) \
;         __builtin_amdgcn_global_load_lds((const unsigned*)((const char*)(gbase) + (voff)[_i]), (PG8_LAS unsigned*)(lds + (bufoff) + ldsw + _i * 8192), 16, 0, 0); } while (0)
; #define PG8_LDA(dst, b, h) do { _Pragma("unroll") for (int m = 0; m < 4; ++m) _Pragma("unroll") for (int k = 0; k < 2; ++k) dst[m][k] = *(const PG8_LAS bf16x8*)(lds + PG8_SA(b, h) + aoff + m * 2048 + k * 1024); } while (0)
; #define PG8_LDB(dst, b, h) do { _Pragma("unroll") for (int n = 0; n < 2; ++n) _Pragma("unroll") for (int k = 0; k < 2; ++k) dst[n][k] = *(const PG8_LAS bf16x8*)(lds + PG8_SB(b, h) + boff + n * 2048 + k * 1024); } while (0)
; #define PG8_MMA(ai, bj, At, Bt) do { __builtin_amdgcn_s_setprio(1); _Pragma("unroll") for (int m = 0; m < 4; ++m) _Pragma("unroll") for (int n = 0; n < 2; ++n) _Pragma("unroll") for (int k = 0; k < 2; ++k) \
;         acc[ai][bj][m][n] = __builtin_amdgcn_mfma_f32_16x16x32_bf16(Bt[n][k], At[m][k], acc[ai][bj][m][n], 0, 0, 0); __builtin_amdgcn_s_setprio(0); } while (0)
; #define PG8_WAIT_V(n) asm volatile("s_waitcnt vmcnt(" #n ")" ::: "memory")
; #define PG8_WAIT_L(n) asm volatile("s_waitcnt lgkmcnt(" #n ")" ::: "memory")
; #define PG8_BAR __builtin_amdgcn_s_barrier()
; #define PG8_SCHED __builtin_amdgcn_sched_barrier(0)
; template <class Epi, class Sched, bool ALIGN_EPI = false, bool SP2 = false>
; __device__ __forceinline__ void gemm_phase(PG8_LAS unsigned char* lds, const Gemm g, const Sched& S, const Epi& E) {
;     ...
;             PG8_WAIT_V(8); PG8_WAIT_L(0); PG8_BAR; PG8_MMA(1, 0, At, B0); PG8_MMA(1, 1, At, B1); PG8_BAR; PG8_SCHED;
;             PG8_LDB(B0, 1, 0); PG8_LDB(B1, 1, 1); PG8_SCHED; PG8_LDA(At, 1, 0); PG8_STAGE(PG8_SA(0, 1), a2 + hstep, voffA);
;             PG8_WAIT_V(8); PG8_WAIT_L(0); PG8_BAR; PG8_MMA(0, 0, At, B0); PG8_MMA(0, 1, At, B1); PG8_BAR; PG8_SCHED;
	s_setprio 1
	s_waitcnt lgkmcnt(0)
	v_mfma_f32_16x16x32_bf16 v[60:63], v[144:147], v[186:189], 0
	v_mfma_f32_16x16x32_bf16 v[56:59], v[160:163], v[186:189], 0
	v_mfma_f32_16x16x32_bf16 v[40:43], v[160:163], v[194:197], 0
	v_mfma_f32_16x16x32_bf16 v[44:47], v[144:147], v[194:197], 0
	v_mfma_f32_16x16x32_bf16 v[28:31], v[144:147], v[208:211], 0
	v_mfma_f32_16x16x32_bf16 v[24:27], v[160:163], v[208:211], 0
	v_mfma_f32_16x16x32_bf16 v[8:11], v[160:163], v[216:219], 0
	v_mfma_f32_16x16x32_bf16 v[12:15], v[144:147], v[216:219], 0
	v_mfma_f32_16x16x32_bf16 v[60:63], v[148:151], v[190:193], v[60:63]
	v_mfma_f32_16x16x32_bf16 v[56:59], v[164:167], v[190:193], v[56:59]
	v_mfma_f32_16x16x32_bf16 v[40:43], v[164:167], v[198:201], v[40:43]
	v_mfma_f32_16x16x32_bf16 v[44:47], v[148:151], v[198:201], v[44:47]
	v_mfma_f32_16x16x32_bf16 v[28:31], v[148:151], v[212:215], v[28:31]
	v_mfma_f32_16x16x32_bf16 v[24:27], v[164:167], v[212:215], v[24:27]
	v_lshl_add_u64 v[228:229], s[58:59], 0, v[134:135]
	s_mov_b32 m0, s53
	s_nop 0
	global_load_lds_dwordx4 v[228:229], off
	v_mfma_f32_16x16x32_bf16 v[8:11], v[164:167], v[220:223], v[8:11]
	v_mfma_f32_16x16x32_bf16 v[12:15], v[148:151], v[220:223], v[12:15]
	s_setprio 0
	s_setprio 1
	v_mfma_f32_16x16x32_bf16 v[52:55], v[168:171], v[186:189], 0
	v_mfma_f32_16x16x32_bf16 v[48:51], v[176:179], v[186:189], 0
	v_mfma_f32_16x16x32_bf16 v[32:35], v[176:179], v[194:197], 0
	v_mfma_f32_16x16x32_bf16 v[36:39], v[168:171], v[194:197], 0
	v_mfma_f32_16x16x32_bf16 v[20:23], v[168:171], v[208:211], 0
	v_mfma_f32_16x16x32_bf16 v[16:19], v[176:179], v[208:211], 0
	v_mfma_f32_16x16x32_bf16 v[0:3], v[176:179], v[216:219], 0
	v_mfma_f32_16x16x32_bf16 v[4:7], v[168:171], v[216:219], 0
	v_mfma_f32_16x16x32_bf16 v[52:55], v[172:175], v[190:193], v[52:55]
	v_mfma_f32_16x16x32_bf16 v[48:51], v[182:185], v[190:193], v[48:51]
	v_mfma_f32_16x16x32_bf16 v[32:35], v[182:185], v[198:201], v[32:35]
	v_mfma_f32_16x16x32_bf16 v[36:39], v[172:175], v[198:201], v[36:39]
	v_mfma_f32_16x16x32_bf16 v[20:23], v[172:175], v[212:215], v[20:23]
	v_mfma_f32_16x16x32_bf16 v[16:19], v[182:185], v[212:215], v[16:19]
	v_lshl_add_u64 v[230:231], s[58:59], 0, v[130:131]
	s_mov_b32 m0, s60
	s_nop 0
	global_load_lds_dwordx4 v[230:231], off
	v_mfma_f32_16x16x32_bf16 v[0:3], v[182:185], v[220:223], v[0:3]
	v_mfma_f32_16x16x32_bf16 v[4:7], v[172:175], v[220:223], v[4:7]
	s_setprio 0
	s_barrier
	s_add_i32 s78, 0, 0x18000
	v_add_u32_e32 v159, s78, v153
	s_add_i32 s79, 0, 0x1c000
	ds_read_b128 v[144:147], v159
	ds_read_b128 v[148:151], v159 offset:1024
	ds_read_b128 v[160:163], v159 offset:2048
	ds_read_b128 v[164:167], v159 offset:3072
	v_add_u32_e32 v159, s79, v153
	ds_read_b128 v[168:171], v159
	ds_read_b128 v[172:175], v159 offset:1024
	ds_read_b128 v[176:179], v159 offset:2048
	ds_read_b128 v[182:185], v159 offset:3072
	s_add_u32 s58, s58, 0x40000
	s_addc_u32 s59, s59, 0
	s_mov_b32 m0, s61
	v_lshl_add_u64 v[232:233], s[58:59], 0, v[134:135]
	ds_read_b128 v[186:189], v157 offset:32768
	ds_read_b128 v[190:193], v157 offset:33792
	ds_read_b128 v[194:197], v157 offset:34816
	ds_read_b128 v[198:201], v157 offset:35840
	ds_read_b128 v[208:211], v157 offset:36864
	ds_read_b128 v[212:215], v157 offset:37888
	ds_read_b128 v[216:219], v157 offset:38912
	ds_read_b128 v[220:223], v157 offset:39936
	global_load_lds_dwordx4 v[232:233], off
	v_lshl_add_u64 v[232:233], s[58:59], 0, v[130:131]
	s_mov_b32 m0, s62
	s_nop 0
	global_load_lds_dwordx4 v[232:233], off
	s_waitcnt vmcnt(8)
	s_waitcnt lgkmcnt(0)
	s_barrier
	s_setprio 1
	s_waitcnt lgkmcnt(0)
	v_mfma_f32_16x16x32_bf16 v[124:127], v[144:147], v[186:189], v[124:127]
	v_mfma_f32_16x16x32_bf16 v[120:123], v[160:163], v[186:189], v[120:123]
	v_mfma_f32_16x16x32_bf16 v[104:107], v[160:163], v[194:197], v[104:107]
	v_mfma_f32_16x16x32_bf16 v[108:111], v[144:147], v[194:197], v[108:111]
	v_mfma_f32_16x16x32_bf16 v[92:95], v[144:147], v[208:211], v[92:95]
	v_mfma_f32_16x16x32_bf16 v[88:91], v[160:163], v[208:211], v[88:91]
	v_mfma_f32_16x16x32_bf16 v[72:75], v[160:163], v[216:219], v[72:75]
	v_mfma_f32_16x16x32_bf16 v[76:79], v[144:147], v[216:219], v[76:79]
	v_mfma_f32_16x16x32_bf16 v[124:127], v[148:151], v[190:193], v[124:127]
	v_mfma_f32_16x16x32_bf16 v[120:123], v[164:167], v[190:193], v[120:123]
	v_mfma_f32_16x16x32_bf16 v[104:107], v[164:167], v[198:201], v[104:107]
	v_mfma_f32_16x16x32_bf16 v[108:111], v[148:151], v[198:201], v[108:111]
	v_mfma_f32_16x16x32_bf16 v[92:95], v[148:151], v[212:215], v[92:95]
	v_mfma_f32_16x16x32_bf16 v[88:91], v[164:167], v[212:215], v[88:91]
	v_mfma_f32_16x16x32_bf16 v[72:75], v[164:167], v[220:223], v[72:75]
	v_mfma_f32_16x16x32_bf16 v[76:79], v[148:151], v[220:223], v[76:79]
	s_setprio 0
	s_setprio 1
	v_mfma_f32_16x16x32_bf16 v[116:119], v[168:171], v[186:189], v[116:119]
	v_mfma_f32_16x16x32_bf16 v[112:115], v[176:179], v[186:189], v[112:115]
	v_mfma_f32_16x16x32_bf16 v[96:99], v[176:179], v[194:197], v[96:99]
	v_mfma_f32_16x16x32_bf16 v[100:103], v[168:171], v[194:197], v[100:103]
	v_mfma_f32_16x16x32_bf16 v[84:87], v[168:171], v[208:211], v[84:87]
	v_mfma_f32_16x16x32_bf16 v[80:83], v[176:179], v[208:211], v[80:83]
	v_mfma_f32_16x16x32_bf16 v[64:67], v[176:179], v[216:219], v[64:67]
	v_mfma_f32_16x16x32_bf16 v[68:71], v[168:171], v[216:219], v[68:71]
	v_mfma_f32_16x16x32_bf16 v[116:119], v[172:175], v[190:193], v[116:119]
	v_mfma_f32_16x16x32_bf16 v[112:115], v[182:185], v[190:193], v[112:115]
	v_mfma_f32_16x16x32_bf16 v[96:99], v[182:185], v[198:201], v[96:99]
	v_mfma_f32_16x16x32_bf16 v[100:103], v[172:175], v[198:201], v[100:103]
	v_mfma_f32_16x16x32_bf16 v[84:87], v[172:175], v[212:215], v[84:87]
	v_mfma_f32_16x16x32_bf16 v[80:83], v[182:185], v[212:215], v[80:83]
	v_mfma_f32_16x16x32_bf16 v[64:67], v[182:185], v[220:223], v[64:67]
	v_mfma_f32_16x16x32_bf16 v[68:71], v[172:175], v[220:223], v[68:71]
	s_setprio 0
	s_barrier
; #define PG8_STAGE(bufoff, gbase, voff) do { _Pragma("unroll") for (int _i = 0; _i < 2; ++_i) \
;         __builtin_amdgcn_global_load_lds((const unsigned*)((const char*)(gbase) + (voff)[_i]), (PG8_LAS unsigned*)(lds + (bufoff) + ldsw + _i * 8192), 16, 0, 0); } while (0)
; #define PG8_LDA(dst, b, h) do { _Pragma("unroll") for (int m = 0; m < 4; ++m) _Pragma("unroll") for (int k = 0; k < 2; ++k) dst[m][k] = *(const PG8_LAS bf16x8*)(lds + PG8_SA(b, h) + aoff + m * 2048 + k * 1024); } while (0)
; #define PG8_LDB(dst, b, h) do { _Pragma("unroll") for (int n = 0; n < 2; ++n) _Pragma("unroll") for (int k = 0; k < 2; ++k) dst[n][k] = *(const PG8_LAS bf16x8*)(lds + PG8_SB(b, h) + boff + n * 2048 + k * 1024); } while (0)
; #define PG8_MMA(ai, bj, At, Bt) do { __builtin_amdgcn_s_setprio(1); _Pragma("unroll") for (int m = 0; m < 4; ++m) _Pragma("unroll") for (int n = 0; n < 2; ++n) _Pragma("unroll") for (int k = 0; k < 2; ++k) \
;         acc[ai][bj][m][n] = __builtin_amdgcn_mfma_f32_16x16x32_bf16(Bt[n][k], At[m][k], acc[ai][bj][m][n], 0, 0, 0); __builtin_amdgcn_s_setprio(0); } while (0)
; #define PG8_WAIT_V(n) asm volatile("s_waitcnt vmcnt(" #n ")" ::: "memory")
; #define PG8_WAIT_L(n) asm volatile("s_waitcnt lgkmcnt(" #n ")" ::: "memory")
; #define PG8_BAR __builtin_amdgcn_s_barrier()
; #define PG8_SCHED __builtin_amdgcn_sched_barrier(0)
; template <class Epi, class Sched, bool ALIGN_EPI = false, bool SP2 = false>
; __device__ __forceinline__ void gemm_phase(PG8_LAS unsigned char* lds, const Gemm g, const Sched& S, const Epi& E) {
;     ...
;             PG8_LDB(B0, 0, 0); PG8_LDB(B1, 0, 1); PG8_SCHED; PG8_LDA(At, 0, 0); PG8_STAGE(PG8_SA(1, 1), a1 + hstep, voffA);
;     ...
;             PG8_LDA(At, 1, 1); PG8_STAGE(PG8_SB(1, 0), b3, voffB); PG8_STAGE(PG8_SB(1, 1), b3 + hstep, voffB); PG8_STAGE(PG8_SA(1, 0), a3, voffA);
;             PG8_WAIT_V(8); PG8_WAIT_L(0); PG8_BAR; PG8_MMA(1, 0, At, B0); PG8_MMA(1, 1, At, B1); PG8_BAR; PG8_SCHED;
	s_add_i32 s58, s78, s33
	v_lshl_add_u64 v[224:225], v[224:225], 0, s[12:13]
	s_mov_b32 m0, s58
	ds_read_b128 v[186:189], v157 offset:49152
	ds_read_b128 v[190:193], v157 offset:50176
	ds_read_b128 v[194:197], v157 offset:51200
	ds_read_b128 v[198:201], v157 offset:52224
	ds_read_b128 v[208:211], v157 offset:53248
	ds_read_b128 v[212:215], v157 offset:54272
	ds_read_b128 v[216:219], v157 offset:55296
	ds_read_b128 v[220:223], v157 offset:56320
	global_load_lds_dwordx4 v[224:225], off
	s_add_i32 m0, s58, 0x2000
	s_add_u32 s56, s56, 0x40080
	v_lshl_add_u64 v[224:225], v[226:227], 0, s[12:13]
	s_addc_u32 s57, s57, 0
	s_add_i32 s58, s79, s33
	global_load_lds_dwordx4 v[224:225], off
	v_lshl_add_u64 v[224:225], s[56:57], 0, v[132:133]
	s_mov_b32 m0, s58
	s_nop 0
	global_load_lds_dwordx4 v[224:225], off
	v_lshl_add_u64 v[224:225], s[56:57], 0, v[128:129]
	s_add_i32 m0, s58, 0x2000
	s_nop 0
	global_load_lds_dwordx4 v[224:225], off
	s_waitcnt vmcnt(6)
	s_waitcnt lgkmcnt(0)
	s_barrier
	s_setprio 1
	s_waitcnt lgkmcnt(0)
	v_mfma_f32_16x16x32_bf16 v[60:63], v[144:147], v[186:189], v[60:63]
	v_mfma_f32_16x16x32_bf16 v[56:59], v[160:163], v[186:189], v[56:59]
	v_mfma_f32_16x16x32_bf16 v[40:43], v[160:163], v[194:197], v[40:43]
	v_mfma_f32_16x16x32_bf16 v[44:47], v[144:147], v[194:197], v[44:47]
	v_mfma_f32_16x16x32_bf16 v[28:31], v[144:147], v[208:211], v[28:31]
	v_mfma_f32_16x16x32_bf16 v[24:27], v[160:163], v[208:211], v[24:27]
	v_mfma_f32_16x16x32_bf16 v[8:11], v[160:163], v[216:219], v[8:11]
	v_mfma_f32_16x16x32_bf16 v[12:15], v[144:147], v[216:219], v[12:15]
	v_mfma_f32_16x16x32_bf16 v[60:63], v[148:151], v[190:193], v[60:63]
	v_mfma_f32_16x16x32_bf16 v[56:59], v[164:167], v[190:193], v[56:59]
	v_mfma_f32_16x16x32_bf16 v[40:43], v[164:167], v[198:201], v[40:43]
	v_mfma_f32_16x16x32_bf16 v[44:47], v[148:151], v[198:201], v[44:47]
	v_mfma_f32_16x16x32_bf16 v[28:31], v[148:151], v[212:215], v[28:31]
	v_mfma_f32_16x16x32_bf16 v[24:27], v[164:167], v[212:215], v[24:27]
	v_lshl_add_u64 v[224:225], v[228:229], 0, s[12:13]
	s_mov_b32 m0, s64
	s_nop 0
	global_load_lds_dwordx4 v[224:225], off
	v_mfma_f32_16x16x32_bf16 v[8:11], v[164:167], v[220:223], v[8:11]
	v_mfma_f32_16x16x32_bf16 v[12:15], v[148:151], v[220:223], v[12:15]
	s_setprio 0
	s_setprio 1
	v_mfma_f32_16x16x32_bf16 v[52:55], v[168:171], v[186:189], v[52:55]
	v_mfma_f32_16x16x32_bf16 v[48:51], v[176:179], v[186:189], v[48:51]
	v_mfma_f32_16x16x32_bf16 v[32:35], v[176:179], v[194:197], v[32:35]
	v_mfma_f32_16x16x32_bf16 v[36:39], v[168:171], v[194:197], v[36:39]
	v_mfma_f32_16x16x32_bf16 v[20:23], v[168:171], v[208:211], v[20:23]
	v_mfma_f32_16x16x32_bf16 v[16:19], v[176:179], v[208:211], v[16:19]
	v_mfma_f32_16x16x32_bf16 v[0:3], v[176:179], v[216:219], v[0:3]
	v_mfma_f32_16x16x32_bf16 v[4:7], v[168:171], v[216:219], v[4:7]
	v_mfma_f32_16x16x32_bf16 v[52:55], v[172:175], v[190:193], v[52:55]
	v_mfma_f32_16x16x32_bf16 v[48:51], v[182:185], v[190:193], v[48:51]
	v_mfma_f32_16x16x32_bf16 v[32:35], v[182:185], v[198:201], v[32:35]
	v_mfma_f32_16x16x32_bf16 v[36:39], v[172:175], v[198:201], v[36:39]
	v_mfma_f32_16x16x32_bf16 v[20:23], v[172:175], v[212:215], v[20:23]
	v_mfma_f32_16x16x32_bf16 v[16:19], v[182:185], v[212:215], v[16:19]
	v_lshl_add_u64 v[224:225], v[230:231], 0, s[12:13]
	s_mov_b32 m0, s65
	s_nop 0
	global_load_lds_dwordx4 v[224:225], off
	v_mfma_f32_16x16x32_bf16 v[0:3], v[182:185], v[220:223], v[0:3]
	v_mfma_f32_16x16x32_bf16 v[4:7], v[172:175], v[220:223], v[4:7]
	s_setprio 0
	s_barrier
	s_add_i32 s84, s84, 2
	s_add_u32 s54, s54, 0x100
	s_addc_u32 s55, s55, 0
	s_add_u32 s82, s82, 0x100
	s_addc_u32 s83, s83, 0
.LBB0_1119:
	ds_read_b128 v[144:147], v155
	ds_read_b128 v[148:151], v155 offset:1024
	ds_read_b128 v[160:163], v155 offset:2048
	ds_read_b128 v[164:167], v155 offset:3072
	ds_read_b128 v[168:171], v156
	ds_read_b128 v[172:175], v156 offset:1024
	ds_read_b128 v[176:179], v156 offset:2048
	ds_read_b128 v[182:185], v156 offset:3072
	s_add_u32 s56, s54, 0xfffc0080
	s_addc_u32 s57, s55, -1
	s_cmp_eq_u32 s84, 12
	s_cselect_b32 s59, s45, s57
	s_cselect_b32 s58, s76, s56
	s_cselect_b32 s57, s43, s83
	s_cselect_b32 s56, s77, s82
	v_lshl_add_u64 v[224:225], s[54:55], 0, v[136:137]
	s_add_i32 m0, s53, 0xc000
	ds_read_b128 v[186:189], v157
	ds_read_b128 v[190:193], v157 offset:1024
	ds_read_b128 v[194:197], v157 offset:2048
	ds_read_b128 v[198:201], v157 offset:3072
	ds_read_b128 v[208:211], v157 offset:4096
	ds_read_b128 v[212:215], v157 offset:5120
	ds_read_b128 v[216:219], v157 offset:6144
	ds_read_b128 v[220:223], v157 offset:7168
	global_load_lds_dwordx4 v[224:225], off
	v_lshl_add_u64 v[224:225], s[54:55], 0, v[138:139]
	s_add_i32 m0, s53, 0xe000
	s_nop 0
	global_load_lds_dwordx4 v[224:225], off
	s_waitcnt vmcnt(8)
	s_waitcnt lgkmcnt(0)
	s_barrier
; #define PG8_STAGE(bufoff, gbase, voff) do { _Pragma("unroll") for (int _i = 0; _i < 2; ++_i) \
;         __builtin_amdgcn_global_load_lds((const unsigned*)((const char*)(gbase) + (voff)[_i]), (PG8_LAS unsigned*)(lds + (bufoff) + ldsw + _i * 8192), 16, 0, 0); } while (0)
; #define PG8_LDA(dst, b, h) do { _Pragma("unroll") for (int m = 0; m < 4; ++m) _Pragma("unroll") for (int k = 0; k < 2; ++k) dst[m][k] = *(const PG8_LAS bf16x8*)(lds + PG8_SA(b, h) + aoff + m * 2048 + k * 1024); } while (0)
; #define PG8_MMA(ai, bj, At, Bt) do { __builtin_amdgcn_s_setprio(1); _Pragma("unroll") for (int m = 0; m < 4; ++m) _Pragma("unroll") for (int n = 0; n < 2; ++n) _Pragma("unroll") for (int k = 0; k < 2; ++k) \
;         acc[ai][bj][m][n] = __builtin_amdgcn_mfma_f32_16x16x32_bf16(Bt[n][k], At[m][k], acc[ai][bj][m][n], 0, 0, 0); __builtin_amdgcn_s_setprio(0); } while (0)
; #define PG8_WAIT_V(n) asm volatile("s_waitcnt vmcnt(" #n ")" ::: "memory")
; #define PG8_WAIT_L(n) asm volatile("s_waitcnt lgkmcnt(" #n ")" ::: "memory")
; #define PG8_BAR __builtin_amdgcn_s_barrier()
; #define PG8_SCHED __builtin_amdgcn_sched_barrier(0)
; template <class Epi, class Sched, bool ALIGN_EPI = false, bool SP2 = false>
; __device__ __forceinline__ void gemm_phase(PG8_LAS unsigned char* lds, const Gemm g, const Sched& S, const Epi& E) {
;     ...
;             PG8_WAIT_V(8); PG8_WAIT_L(0); PG8_BAR; PG8_MMA(0, 0, At, B0); PG8_MMA(0, 1, At, B1); PG8_BAR; PG8_SCHED;
;             PG8_LDA(At, 0, 1); PG8_STAGE(PG8_SB(0, 0), b2, voffB); PG8_STAGE(PG8_SB(0, 1), b2 + hstep, voffB); PG8_STAGE(PG8_SA(0, 0), a2, voffA);
;             PG8_WAIT_V(8); PG8_WAIT_L(0); PG8_BAR; PG8_MMA(1, 0, At, B0); PG8_MMA(1, 1, At, B1); PG8_BAR; PG8_SCHED;
	s_setprio 1
	s_waitcnt lgkmcnt(0)
	v_mfma_f32_16x16x32_bf16 v[124:127], v[144:147], v[186:189], v[124:127]
	v_mfma_f32_16x16x32_bf16 v[120:123], v[160:163], v[186:189], v[120:123]
	v_mfma_f32_16x16x32_bf16 v[104:107], v[160:163], v[194:197], v[104:107]
	v_mfma_f32_16x16x32_bf16 v[108:111], v[144:147], v[194:197], v[108:111]
	v_mfma_f32_16x16x32_bf16 v[92:95], v[144:147], v[208:211], v[92:95]
	v_mfma_f32_16x16x32_bf16 v[88:91], v[160:163], v[208:211], v[88:91]
	v_mfma_f32_16x16x32_bf16 v[72:75], v[160:163], v[216:219], v[72:75]
	v_mfma_f32_16x16x32_bf16 v[76:79], v[144:147], v[216:219], v[76:79]
	v_mfma_f32_16x16x32_bf16 v[124:127], v[148:151], v[190:193], v[124:127]
	v_mfma_f32_16x16x32_bf16 v[120:123], v[164:167], v[190:193], v[120:123]
	v_mfma_f32_16x16x32_bf16 v[104:107], v[164:167], v[198:201], v[104:107]
	v_mfma_f32_16x16x32_bf16 v[108:111], v[148:151], v[198:201], v[108:111]
	v_mfma_f32_16x16x32_bf16 v[92:95], v[148:151], v[212:215], v[92:95]
	v_mfma_f32_16x16x32_bf16 v[88:91], v[164:167], v[212:215], v[88:91]
	v_mfma_f32_16x16x32_bf16 v[72:75], v[164:167], v[220:223], v[72:75]
	v_mfma_f32_16x16x32_bf16 v[76:79], v[148:151], v[220:223], v[76:79]
	s_setprio 0
	s_setprio 1
	v_mfma_f32_16x16x32_bf16 v[116:119], v[168:171], v[186:189], v[116:119]
	v_mfma_f32_16x16x32_bf16 v[112:115], v[176:179], v[186:189], v[112:115]
	v_mfma_f32_16x16x32_bf16 v[96:99], v[176:179], v[194:197], v[96:99]
	v_mfma_f32_16x16x32_bf16 v[100:103], v[168:171], v[194:197], v[100:103]
	v_mfma_f32_16x16x32_bf16 v[84:87], v[168:171], v[208:211], v[84:87]
	v_mfma_f32_16x16x32_bf16 v[80:83], v[176:179], v[208:211], v[80:83]
	v_mfma_f32_16x16x32_bf16 v[64:67], v[176:179], v[216:219], v[64:67]
	v_mfma_f32_16x16x32_bf16 v[68:71], v[168:171], v[216:219], v[68:71]
	v_mfma_f32_16x16x32_bf16 v[116:119], v[172:175], v[190:193], v[116:119]
	v_mfma_f32_16x16x32_bf16 v[112:115], v[182:185], v[190:193], v[112:115]
	v_mfma_f32_16x16x32_bf16 v[96:99], v[182:185], v[198:201], v[96:99]
	v_mfma_f32_16x16x32_bf16 v[100:103], v[172:175], v[198:201], v[100:103]
	v_mfma_f32_16x16x32_bf16 v[84:87], v[172:175], v[212:215], v[84:87]
	v_mfma_f32_16x16x32_bf16 v[80:83], v[182:185], v[212:215], v[80:83]
	v_mfma_f32_16x16x32_bf16 v[64:67], v[182:185], v[220:223], v[64:67]
	v_mfma_f32_16x16x32_bf16 v[68:71], v[172:175], v[220:223], v[68:71]
	s_setprio 0
	s_barrier
	s_add_i32 s78, s66, s33
	v_lshl_add_u64 v[224:225], s[56:57], 0, v[132:133]
	s_mov_b32 m0, s78
	ds_read_b128 v[186:189], v157 offset:16384
	ds_read_b128 v[190:193], v157 offset:17408
	ds_read_b128 v[194:197], v157 offset:18432
	ds_read_b128 v[198:201], v157 offset:19456
	ds_read_b128 v[208:211], v157 offset:20480
	ds_read_b128 v[212:215], v157 offset:21504
	ds_read_b128 v[216:219], v157 offset:22528
	ds_read_b128 v[220:223], v157 offset:23552
	global_load_lds_dwordx4 v[224:225], off
	s_add_i32 m0, s78, 0x2000
	s_add_u32 s78, s56, 0x40000
	v_lshl_add_u64 v[226:227], s[56:57], 0, v[128:129]
	s_addc_u32 s79, s57, 0
	s_add_i32 s85, s67, s33
	global_load_lds_dwordx4 v[226:227], off
	v_lshl_add_u64 v[228:229], s[78:79], 0, v[132:133]
	s_mov_b32 m0, s85
	global_load_lds_dwordx4 v[228:229], off
	v_lshl_add_u64 v[228:229], s[78:79], 0, v[128:129]
	s_add_i32 m0, s85, 0x2000
	s_nop 0
	global_load_lds_dwordx4 v[228:229], off
	s_waitcnt vmcnt(6)
	s_waitcnt lgkmcnt(0)
	s_barrier
	s_setprio 1
	s_waitcnt lgkmcnt(0)
	v_mfma_f32_16x16x32_bf16 v[60:63], v[144:147], v[186:189], v[60:63]
	v_mfma_f32_16x16x32_bf16 v[56:59], v[160:163], v[186:189], v[56:59]
	v_mfma_f32_16x16x32_bf16 v[40:43], v[160:163], v[194:197], v[40:43]
	v_mfma_f32_16x16x32_bf16 v[44:47], v[144:147], v[194:197], v[44:47]
	v_mfma_f32_16x16x32_bf16 v[28:31], v[144:147], v[208:211], v[28:31]
	v_mfma_f32_16x16x32_bf16 v[24:27], v[160:163], v[208:211], v[24:27]
	v_mfma_f32_16x16x32_bf16 v[8:11], v[160:163], v[216:219], v[8:11]
	v_mfma_f32_16x16x32_bf16 v[12:15], v[144:147], v[216:219], v[12:15]
	v_mfma_f32_16x16x32_bf16 v[60:63], v[148:151], v[190:193], v[60:63]
	v_mfma_f32_16x16x32_bf16 v[56:59], v[164:167], v[190:193], v[56:59]
	v_mfma_f32_16x16x32_bf16 v[40:43], v[164:167], v[198:201], v[40:43]
	v_mfma_f32_16x16x32_bf16 v[44:47], v[148:151], v[198:201], v[44:47]
	v_mfma_f32_16x16x32_bf16 v[28:31], v[148:151], v[212:215], v[28:31]
	v_mfma_f32_16x16x32_bf16 v[24:27], v[164:167], v[212:215], v[24:27]
	v_lshl_add_u64 v[228:229], s[58:59], 0, v[134:135]
	s_mov_b32 m0, s53
	s_nop 0
	global_load_lds_dwordx4 v[228:229], off
	v_mfma_f32_16x16x32_bf16 v[8:11], v[164:167], v[220:223], v[8:11]
	v_mfma_f32_16x16x32_bf16 v[12:15], v[148:151], v[220:223], v[12:15]
	s_setprio 0
	s_setprio 1
	v_mfma_f32_16x16x32_bf16 v[52:55], v[168:171], v[186:189], v[52:55]
	v_mfma_f32_16x16x32_bf16 v[48:51], v[176:179], v[186:189], v[48:51]
	v_mfma_f32_16x16x32_bf16 v[32:35], v[176:179], v[194:197], v[32:35]
	v_mfma_f32_16x16x32_bf16 v[36:39], v[168:171], v[194:197], v[36:39]
	v_mfma_f32_16x16x32_bf16 v[20:23], v[168:171], v[208:211], v[20:23]
	v_mfma_f32_16x16x32_bf16 v[16:19], v[176:179], v[208:211], v[16:19]
	v_mfma_f32_16x16x32_bf16 v[0:3], v[176:179], v[216:219], v[0:3]
	v_mfma_f32_16x16x32_bf16 v[4:7], v[168:171], v[216:219], v[4:7]
	v_mfma_f32_16x16x32_bf16 v[52:55], v[172:175], v[190:193], v[52:55]
	v_mfma_f32_16x16x32_bf16 v[48:51], v[182:185], v[190:193], v[48:51]
	v_mfma_f32_16x16x32_bf16 v[32:35], v[182:185], v[198:201], v[32:35]
	v_mfma_f32_16x16x32_bf16 v[36:39], v[172:175], v[198:201], v[36:39]
	v_mfma_f32_16x16x32_bf16 v[20:23], v[172:175], v[212:215], v[20:23]
	v_mfma_f32_16x16x32_bf16 v[16:19], v[182:185], v[212:215], v[16:19]
	v_lshl_add_u64 v[230:231], s[58:59], 0, v[130:131]
	s_mov_b32 m0, s60
	s_nop 0
	global_load_lds_dwordx4 v[230:231], off
	v_mfma_f32_16x16x32_bf16 v[0:3], v[182:185], v[220:223], v[0:3]
	v_mfma_f32_16x16x32_bf16 v[4:7], v[172:175], v[220:223], v[4:7]
	s_setprio 0
	s_barrier
; #define PG8_STAGE(bufoff, gbase, voff) do { _Pragma("unroll") for (int _i = 0; _i < 2; ++_i) \
;         __builtin_amdgcn_global_load_lds((const unsigned*)((const char*)(gbase) + (voff)[_i]), (PG8_LAS unsigned*)(lds + (bufoff) + ldsw + _i * 8192), 16, 0, 0); } while (0)
; #define PG8_LDA(dst, b, h) do { _Pragma("unroll") for (int m = 0; m < 4; ++m) _Pragma("unroll") for (int k = 0; k < 2; ++k) dst[m][k] = *(const PG8_LAS bf16x8*)(lds + PG8_SA(b, h) + aoff + m * 2048 + k * 1024); } while (0)
; #define PG8_LDB(dst, b, h) do { _Pragma("unroll") for (int n = 0; n < 2; ++n) _Pragma("unroll") for (int k = 0; k < 2; ++k) dst[n][k] = *(const PG8_LAS bf16x8*)(lds + PG8_SB(b, h) + boff + n * 2048 + k * 1024); } while (0)
; #define PG8_MMA(ai, bj, At, Bt) do { __builtin_amdgcn_s_setprio(1); _Pragma("unroll") for (int m = 0; m < 4; ++m) _Pragma("unroll") for (int n = 0; n < 2; ++n) _Pragma("unroll") for (int k = 0; k < 2; ++k) \
;         acc[ai][bj][m][n] = __builtin_amdgcn_mfma_f32_16x16x32_bf16(Bt[n][k], At[m][k], acc[ai][bj][m][n], 0, 0, 0); __builtin_amdgcn_s_setprio(0); } while (0)
; #define PG8_WAIT_V(n) asm volatile("s_waitcnt vmcnt(" #n ")" ::: "memory")
; #define PG8_WAIT_L(n) asm volatile("s_waitcnt lgkmcnt(" #n ")" ::: "memory")
; #define PG8_BAR __builtin_amdgcn_s_barrier()
; #define PG8_SCHED __builtin_amdgcn_sched_barrier(0)
; template <class Epi, class Sched, bool ALIGN_EPI = false, bool SP2 = false>
; __device__ __forceinline__ void gemm_phase(PG8_LAS unsigned char* lds, const Gemm g, const Sched& S, const Epi& E) {
;     ...
;             PG8_LDB(B0, 1, 0); PG8_LDB(B1, 1, 1); PG8_SCHED; PG8_LDA(At, 1, 0); PG8_STAGE(PG8_SA(0, 1), a2 + hstep, voffA);
;             PG8_WAIT_V(8); PG8_WAIT_L(0); PG8_BAR; PG8_MMA(0, 0, At, B0); PG8_MMA(0, 1, At, B1); PG8_BAR; PG8_SCHED;
	s_add_i32 s78, 0, 0x18000
	v_add_u32_e32 v159, s78, v153
	s_add_i32 s79, 0, 0x1c000
	ds_read_b128 v[144:147], v159
	ds_read_b128 v[148:151], v159 offset:1024
	ds_read_b128 v[160:163], v159 offset:2048
	ds_read_b128 v[164:167], v159 offset:3072
	v_add_u32_e32 v159, s79, v153
	ds_read_b128 v[168:171], v159
	ds_read_b128 v[172:175], v159 offset:1024
	ds_read_b128 v[176:179], v159 offset:2048
	ds_read_b128 v[182:185], v159 offset:3072
	s_add_u32 s58, s58, 0x40000
	s_addc_u32 s59, s59, 0
	s_mov_b32 m0, s61
	v_lshl_add_u64 v[232:233], s[58:59], 0, v[134:135]
	ds_read_b128 v[186:189], v157 offset:32768
	ds_read_b128 v[190:193], v157 offset:33792
	ds_read_b128 v[194:197], v157 offset:34816
	ds_read_b128 v[198:201], v157 offset:35840
	ds_read_b128 v[208:211], v157 offset:36864
	ds_read_b128 v[212:215], v157 offset:37888
	ds_read_b128 v[216:219], v157 offset:38912
	ds_read_b128 v[220:223], v157 offset:39936
	global_load_lds_dwordx4 v[232:233], off
	v_lshl_add_u64 v[232:233], s[58:59], 0, v[130:131]
	s_mov_b32 m0, s62
	s_nop 0
	global_load_lds_dwordx4 v[232:233], off
	s_waitcnt vmcnt(8)
	s_waitcnt lgkmcnt(0)
	s_barrier
	s_setprio 1
	s_waitcnt lgkmcnt(0)
	v_mfma_f32_16x16x32_bf16 v[124:127], v[144:147], v[186:189], v[124:127]
	v_mfma_f32_16x16x32_bf16 v[120:123], v[160:163], v[186:189], v[120:123]
	v_mfma_f32_16x16x32_bf16 v[104:107], v[160:163], v[194:197], v[104:107]
	v_mfma_f32_16x16x32_bf16 v[108:111], v[144:147], v[194:197], v[108:111]
	v_mfma_f32_16x16x32_bf16 v[92:95], v[144:147], v[208:211], v[92:95]
	v_mfma_f32_16x16x32_bf16 v[88:91], v[160:163], v[208:211], v[88:91]
	v_mfma_f32_16x16x32_bf16 v[72:75], v[160:163], v[216:219], v[72:75]
	v_mfma_f32_16x16x32_bf16 v[76:79], v[144:147], v[216:219], v[76:79]
	v_mfma_f32_16x16x32_bf16 v[124:127], v[148:151], v[190:193], v[124:127]
	v_mfma_f32_16x16x32_bf16 v[120:123], v[164:167], v[190:193], v[120:123]
	v_mfma_f32_16x16x32_bf16 v[104:107], v[164:167], v[198:201], v[104:107]
	v_mfma_f32_16x16x32_bf16 v[108:111], v[148:151], v[198:201], v[108:111]
	v_mfma_f32_16x16x32_bf16 v[92:95], v[148:151], v[212:215], v[92:95]
	v_mfma_f32_16x16x32_bf16 v[88:91], v[164:167], v[212:215], v[88:91]
	v_mfma_f32_16x16x32_bf16 v[72:75], v[164:167], v[220:223], v[72:75]
	v_mfma_f32_16x16x32_bf16 v[76:79], v[148:151], v[220:223], v[76:79]
	s_setprio 0
	s_setprio 1
	v_mfma_f32_16x16x32_bf16 v[116:119], v[168:171], v[186:189], v[116:119]
	v_mfma_f32_16x16x32_bf16 v[112:115], v[176:179], v[186:189], v[112:115]
	v_mfma_f32_16x16x32_bf16 v[96:99], v[176:179], v[194:197], v[96:99]
	v_mfma_f32_16x16x32_bf16 v[100:103], v[168:171], v[194:197], v[100:103]
	v_mfma_f32_16x16x32_bf16 v[84:87], v[168:171], v[208:211], v[84:87]
	v_mfma_f32_16x16x32_bf16 v[80:83], v[176:179], v[208:211], v[80:83]
	v_mfma_f32_16x16x32_bf16 v[64:67], v[176:179], v[216:219], v[64:67]
	v_mfma_f32_16x16x32_bf16 v[68:71], v[168:171], v[216:219], v[68:71]
	v_mfma_f32_16x16x32_bf16 v[116:119], v[172:175], v[190:193], v[116:119]
	v_mfma_f32_16x16x32_bf16 v[112:115], v[182:185], v[190:193], v[112:115]
	v_mfma_f32_16x16x32_bf16 v[96:99], v[182:185], v[198:201], v[96:99]
	v_mfma_f32_16x16x32_bf16 v[100:103], v[172:175], v[198:201], v[100:103]
	v_mfma_f32_16x16x32_bf16 v[84:87], v[172:175], v[212:215], v[84:87]
	v_mfma_f32_16x16x32_bf16 v[80:83], v[182:185], v[212:215], v[80:83]
	v_mfma_f32_16x16x32_bf16 v[64:67], v[182:185], v[220:223], v[64:67]
	v_mfma_f32_16x16x32_bf16 v[68:71], v[172:175], v[220:223], v[68:71]
	s_setprio 0
	s_barrier
; #define PG8_STAGE(bufoff, gbase, voff) do { _Pragma("unroll") for (int _i = 0; _i < 2; ++_i) \
;         __builtin_amdgcn_global_load_lds((const unsigned*)((const char*)(gbase) + (voff)[_i]), (PG8_LAS unsigned*)(lds + (bufoff) + ldsw + _i * 8192), 16, 0, 0); } while (0)
; #define PG8_LDA(dst, b, h) do { _Pragma("unroll") for (int m = 0; m < 4; ++m) _Pragma("unroll") for (int k = 0; k < 2; ++k) dst[m][k] = *(const PG8_LAS bf16x8*)(lds + PG8_SA(b, h) + aoff + m * 2048 + k * 1024); } while (0)
; #define PG8_MMA(ai, bj, At, Bt) do { __builtin_amdgcn_s_setprio(1); _Pragma("unroll") for (int m = 0; m < 4; ++m) _Pragma("unroll") for (int n = 0; n < 2; ++n) _Pragma("unroll") for (int k = 0; k < 2; ++k) \
;         acc[ai][bj][m][n] = __builtin_amdgcn_mfma_f32_16x16x32_bf16(Bt[n][k], At[m][k], acc[ai][bj][m][n], 0, 0, 0); __builtin_amdgcn_s_setprio(0); } while (0)
; #define PG8_WAIT_V(n) asm volatile("s_waitcnt vmcnt(" #n ")" ::: "memory")
; #define PG8_WAIT_L(n) asm volatile("s_waitcnt lgkmcnt(" #n ")" ::: "memory")
; #define PG8_BAR __builtin_amdgcn_s_barrier()
; #define PG8_SCHED __builtin_amdgcn_sched_barrier(0)
; __device__ __forceinline__ float row_rs(const float* ssp, int row) { const unsigned long long v = ((const unsigned long long*)ssp)[row];
;     return __builtin_amdgcn_rsqf((float)v * (1.0f / 4294967296.0f) * (1.0f / 1024.0f) + RMS_EPS); }
; template <class Epi, class Sched, bool ALIGN_EPI = false, bool SP2 = false>
; __device__ __forceinline__ void gemm_phase(PG8_LAS unsigned char* lds, const Gemm g, const Sched& S, const Epi& E) {
;     ...
;             PG8_LDA(At, 1, 1); PG8_STAGE(PG8_SB(1, 0), b3, voffB); PG8_STAGE(PG8_SB(1, 1), b3 + hstep, voffB); PG8_STAGE(PG8_SA(1, 0), a3, voffA);
;             PG8_WAIT_V(8); PG8_WAIT_L(0); PG8_BAR; PG8_MMA(1, 0, At, B0); PG8_MMA(1, 1, At, B1); PG8_BAR; PG8_SCHED;
	s_add_i32 s58, s78, s33
	v_lshl_add_u64 v[224:225], v[224:225], 0, s[12:13]
	s_mov_b32 m0, s58
	ds_read_b128 v[186:189], v157 offset:49152
	ds_read_b128 v[190:193], v157 offset:50176
	ds_read_b128 v[194:197], v157 offset:51200
	ds_read_b128 v[198:201], v157 offset:52224
	ds_read_b128 v[208:211], v157 offset:53248
	ds_read_b128 v[212:215], v157 offset:54272
	ds_read_b128 v[216:219], v157 offset:55296
	ds_read_b128 v[220:223], v157 offset:56320
	global_load_lds_dwordx4 v[224:225], off
	s_add_i32 m0, s58, 0x2000
	s_add_u32 s56, s56, 0x40080
	v_lshl_add_u64 v[224:225], v[226:227], 0, s[12:13]
	s_addc_u32 s57, s57, 0
	s_add_i32 s58, s79, s33
	global_load_lds_dwordx4 v[224:225], off
	v_lshl_add_u64 v[224:225], s[56:57], 0, v[132:133]
	s_mov_b32 m0, s58
	s_nop 0
	global_load_lds_dwordx4 v[224:225], off
	v_lshl_add_u64 v[224:225], s[56:57], 0, v[128:129]
	s_add_i32 m0, s58, 0x2000
	s_nop 0
	global_load_lds_dwordx4 v[224:225], off
	s_waitcnt vmcnt(6)
	s_waitcnt lgkmcnt(0)
	s_barrier
	s_setprio 1
	s_waitcnt lgkmcnt(0)
	v_mfma_f32_16x16x32_bf16 v[60:63], v[144:147], v[186:189], v[60:63]
	v_mfma_f32_16x16x32_bf16 v[56:59], v[160:163], v[186:189], v[56:59]
	v_mfma_f32_16x16x32_bf16 v[40:43], v[160:163], v[194:197], v[40:43]
	v_mfma_f32_16x16x32_bf16 v[44:47], v[144:147], v[194:197], v[44:47]
	v_mfma_f32_16x16x32_bf16 v[28:31], v[144:147], v[208:211], v[28:31]
	v_mfma_f32_16x16x32_bf16 v[24:27], v[160:163], v[208:211], v[24:27]
	v_mfma_f32_16x16x32_bf16 v[8:11], v[160:163], v[216:219], v[8:11]
	v_mfma_f32_16x16x32_bf16 v[12:15], v[144:147], v[216:219], v[12:15]
	v_mfma_f32_16x16x32_bf16 v[60:63], v[148:151], v[190:193], v[60:63]
	v_mfma_f32_16x16x32_bf16 v[56:59], v[164:167], v[190:193], v[56:59]
	v_mfma_f32_16x16x32_bf16 v[40:43], v[164:167], v[198:201], v[40:43]
	v_mfma_f32_16x16x32_bf16 v[44:47], v[148:151], v[198:201], v[44:47]
	v_mfma_f32_16x16x32_bf16 v[28:31], v[148:151], v[212:215], v[28:31]
	v_mfma_f32_16x16x32_bf16 v[24:27], v[164:167], v[212:215], v[24:27]
	v_lshl_add_u64 v[224:225], v[228:229], 0, s[12:13]
	s_mov_b32 m0, s64
	s_nop 0
	global_load_lds_dwordx4 v[224:225], off
	v_mfma_f32_16x16x32_bf16 v[8:11], v[164:167], v[220:223], v[8:11]
	v_mfma_f32_16x16x32_bf16 v[12:15], v[148:151], v[220:223], v[12:15]
	s_setprio 0
	s_setprio 1
	v_mfma_f32_16x16x32_bf16 v[52:55], v[168:171], v[186:189], v[52:55]
	v_mfma_f32_16x16x32_bf16 v[48:51], v[176:179], v[186:189], v[48:51]
	v_mfma_f32_16x16x32_bf16 v[32:35], v[176:179], v[194:197], v[32:35]
	v_mfma_f32_16x16x32_bf16 v[36:39], v[168:171], v[194:197], v[36:39]
	v_mfma_f32_16x16x32_bf16 v[20:23], v[168:171], v[208:211], v[20:23]
	v_mfma_f32_16x16x32_bf16 v[16:19], v[176:179], v[208:211], v[16:19]
	v_mfma_f32_16x16x32_bf16 v[0:3], v[176:179], v[216:219], v[0:3]
	v_mfma_f32_16x16x32_bf16 v[4:7], v[168:171], v[216:219], v[4:7]
	v_mfma_f32_16x16x32_bf16 v[52:55], v[172:175], v[190:193], v[52:55]
	v_mfma_f32_16x16x32_bf16 v[48:51], v[182:185], v[190:193], v[48:51]
	v_mfma_f32_16x16x32_bf16 v[32:35], v[182:185], v[198:201], v[32:35]
	v_mfma_f32_16x16x32_bf16 v[36:39], v[172:175], v[198:201], v[36:39]
	v_mfma_f32_16x16x32_bf16 v[20:23], v[172:175], v[212:215], v[20:23]
	v_mfma_f32_16x16x32_bf16 v[16:19], v[182:185], v[212:215], v[16:19]
	v_lshl_add_u64 v[224:225], v[230:231], 0, s[12:13]
	s_mov_b32 m0, s65
	s_nop 0
	global_load_lds_dwordx4 v[224:225], off
	v_mfma_f32_16x16x32_bf16 v[0:3], v[182:185], v[220:223], v[0:3]
	v_mfma_f32_16x16x32_bf16 v[4:7], v[172:175], v[220:223], v[4:7]
	s_setprio 0
	s_barrier
	s_add_i32 s84, s84, 2
	s_add_u32 s54, s54, 0x100
	s_addc_u32 s55, s55, 0
	s_add_u32 s82, s82, 0x100
	s_addc_u32 s83, s83, 0
	s_cmp_gt_u32 s84, 13
	s_cbranch_scc0 .LBB0_1119
	v_lshl_add_u32 v144, s52, 8, v152
	v_ashrrev_i32_e32 v145, 31, v144
	v_lshl_add_u64 v[150:151], v[144:145], 3, s[36:37]
	global_load_dwordx2 v[182:183], v[150:151], off
	global_load_dwordx2 v[184:185], v[150:151], off offset:128
	global_load_dwordx2 v[186:187], v[150:151], off offset:256
	global_load_dwordx2 v[188:189], v[150:151], off offset:384
	global_load_dwordx2 v[190:191], v[150:151], off offset:1024
	global_load_dwordx2 v[192:193], v[150:151], off offset:1152
	global_load_dwordx2 v[194:195], v[150:151], off offset:1280
	global_load_dwordx2 v[196:197], v[150:151], off offset:1408
	s_and_b64 vcc, exec, s[38:39]
	s_cbranch_vccz .LBB0_1122
	s_barrier

; #define PG8_STAGE(bufoff, gbase, voff) do { _Pragma("unroll") for (int _i = 0; _i < 2; ++_i) \
;         __builtin_amdgcn_global_load_lds((const unsigned*)((const char*)(gbase) + (voff)[_i]), (PG8_LAS unsigned*)(lds + (bufoff) + ldsw + _i * 8192), 16, 0, 0); } while (0)
; #define PG8_LDA(dst, b, h) do { _Pragma("unroll") for (int m = 0; m < 4; ++m) _Pragma("unroll") for (int k = 0; k < 2; ++k) dst[m][k] = *(const PG8_LAS bf16x8*)(lds + PG8_SA(b, h) + aoff + m * 2048 + k * 1024); } while (0)
; #define PG8_LDB(dst, b, h) do { _Pragma("unroll") for (int n = 0; n < 2; ++n) _Pragma("unroll") for (int k = 0; k < 2; ++k) dst[n][k] = *(const PG8_LAS bf16x8*)(lds + PG8_SB(b, h) + boff + n * 2048 + k * 1024); } while (0)
; #define PG8_MMA(ai, bj, At, Bt) do { __builtin_amdgcn_s_setprio(1); _Pragma("unroll") for (int m = 0; m < 4; ++m) _Pragma("unroll") for (int n = 0; n < 2; ++n) _Pragma("unroll") for (int k = 0; k < 2; ++k) \
;         acc[ai][bj][m][n] = __builtin_amdgcn_mfma_f32_16x16x32_bf16(Bt[n][k], At[m][k], acc[ai][bj][m][n], 0, 0, 0); __builtin_amdgcn_s_setprio(0); } while (0)
; #define PG8_WAIT_V(n) asm volatile("s_waitcnt vmcnt(" #n ")" ::: "memory")
; #define PG8_WAIT_L(n) asm volatile("s_waitcnt lgkmcnt(" #n ")" ::: "memory")
; #define PG8_BAR __builtin_amdgcn_s_barrier()
; #define PG8_SCHED __builtin_amdgcn_sched_barrier(0)
; template <class Epi, class Sched, bool ALIGN_EPI = false, bool SP2 = false>
; __device__ __forceinline__ void gemm_phase(PG8_LAS unsigned char* lds, const Gemm g, const Sched& S, const Epi& E) {
;     ...
;         for (int t = 0; t < nt; t += 2) {
;             const bool last = (t == nt - 2);
;             const char* a1 = cA + (size_t)(t + 1) * kstep;
;             const char* a2 = last ? nA : cA + (size_t)(t + 2) * kstep; const char* b2 = last ? nB : cB + (size_t)(t + 2) * kstep;
;             const char* a3 = a2 + kstep; const char* b3 = b2 + kstep;
;             if (last && has_next) S.a_ready(nxt);
;             if constexpr (SP2) {
;             PG8_LDB(B0, 0, 0); PG8_LDB(B1, 0, 1); PG8_SCHED; PG8_LDA(At, 0, 0); PG8_STAGE(PG8_SA(1, 1), a1 + hstep, voffA);
;             PG8_WAIT_V(8); PG8_WAIT_L(0); PG8_BAR; PG8_MMA(0, 0, At, B0); PG8_MMA(0, 1, At, B1); PG8_BAR; PG8_SCHED;
;             PG8_LDA(At, 0, 1); PG8_STAGE(PG8_SB(0, 0), b2, voffB); PG8_STAGE(PG8_SB(0, 1), b2 + hstep, voffB); PG8_STAGE(PG8_SA(0, 0), a2, voffA);
.LBB0_1196:
	s_add_u32 s82, s52, 0x100
	s_addc_u32 s83, s53, 0
	s_mov_b32 s84, -2
	s_waitcnt lgkmcnt(0)
	ds_read_b128 v[144:147], v151
	ds_read_b128 v[156:159], v151 offset:1024
	ds_read_b128 v[160:163], v151 offset:2048
	ds_read_b128 v[164:167], v151 offset:3072
	ds_read_b128 v[168:171], v152
	ds_read_b128 v[172:175], v152 offset:1024
	ds_read_b128 v[176:179], v152 offset:2048
	ds_read_b128 v[182:185], v152 offset:3072
	s_add_u32 s52, s50, 0x100
	s_addc_u32 s53, s51, 0
	s_cmp_eq_u32 s84, 40
	s_cselect_b32 s57, s1, s53
	s_cselect_b32 s56, s0, s52
	s_cselect_b32 s55, s49, s83
	s_cselect_b32 s54, s48, s82
	v_lshl_add_u64 v[224:225], s[50:51], 0, v[136:137]
	s_add_i32 m0, s34, 0xc000
	ds_read_b128 v[186:189], v153
	ds_read_b128 v[190:193], v153 offset:1024
	ds_read_b128 v[194:197], v153 offset:2048
	ds_read_b128 v[198:201], v153 offset:3072
	ds_read_b128 v[208:211], v153 offset:4096
	ds_read_b128 v[212:215], v153 offset:5120
	ds_read_b128 v[216:219], v153 offset:6144
	ds_read_b128 v[220:223], v153 offset:7168
	global_load_lds_dwordx4 v[224:225], off
	v_lshl_add_u64 v[224:225], s[50:51], 0, v[138:139]
	s_add_i32 m0, s34, 0xe000
	s_nop 0
	global_load_lds_dwordx4 v[224:225], off
	s_waitcnt vmcnt(8)
	s_waitcnt lgkmcnt(0)
	s_barrier
	s_setprio 1
	s_waitcnt lgkmcnt(0)
	v_mfma_f32_16x16x32_bf16 v[124:127], v[144:147], v[186:189], 0
	v_mfma_f32_16x16x32_bf16 v[120:123], v[160:163], v[186:189], 0
	v_mfma_f32_16x16x32_bf16 v[104:107], v[160:163], v[194:197], 0
	v_mfma_f32_16x16x32_bf16 v[108:111], v[144:147], v[194:197], 0
	v_mfma_f32_16x16x32_bf16 v[92:95], v[144:147], v[208:211], 0
	v_mfma_f32_16x16x32_bf16 v[88:91], v[160:163], v[208:211], 0
	v_mfma_f32_16x16x32_bf16 v[72:75], v[160:163], v[216:219], 0
	v_mfma_f32_16x16x32_bf16 v[76:79], v[144:147], v[216:219], 0
	v_mfma_f32_16x16x32_bf16 v[124:127], v[156:159], v[190:193], v[124:127]
	v_mfma_f32_16x16x32_bf16 v[120:123], v[164:167], v[190:193], v[120:123]
	v_mfma_f32_16x16x32_bf16 v[104:107], v[164:167], v[198:201], v[104:107]
	v_mfma_f32_16x16x32_bf16 v[108:111], v[156:159], v[198:201], v[108:111]
	v_mfma_f32_16x16x32_bf16 v[92:95], v[156:159], v[212:215], v[92:95]
	v_mfma_f32_16x16x32_bf16 v[88:91], v[164:167], v[212:215], v[88:91]
	v_mfma_f32_16x16x32_bf16 v[72:75], v[164:167], v[220:223], v[72:75]
	v_mfma_f32_16x16x32_bf16 v[76:79], v[156:159], v[220:223], v[76:79]
	s_setprio 0
	s_setprio 1
	v_mfma_f32_16x16x32_bf16 v[116:119], v[168:171], v[186:189], 0
	v_mfma_f32_16x16x32_bf16 v[112:115], v[176:179], v[186:189], 0
	v_mfma_f32_16x16x32_bf16 v[96:99], v[176:179], v[194:197], 0
	v_mfma_f32_16x16x32_bf16 v[100:103], v[168:171], v[194:197], 0
	v_mfma_f32_16x16x32_bf16 v[84:87], v[168:171], v[208:211], 0
	v_mfma_f32_16x16x32_bf16 v[80:83], v[176:179], v[208:211], 0
	v_mfma_f32_16x16x32_bf16 v[64:67], v[176:179], v[216:219], 0
	v_mfma_f32_16x16x32_bf16 v[68:71], v[168:171], v[216:219], 0
	v_mfma_f32_16x16x32_bf16 v[116:119], v[172:175], v[190:193], v[116:119]
	v_mfma_f32_16x16x32_bf16 v[112:115], v[182:185], v[190:193], v[112:115]
	v_mfma_f32_16x16x32_bf16 v[96:99], v[182:185], v[198:201], v[96:99]
	v_mfma_f32_16x16x32_bf16 v[100:103], v[172:175], v[198:201], v[100:103]
	v_mfma_f32_16x16x32_bf16 v[84:87], v[172:175], v[212:215], v[84:87]
	v_mfma_f32_16x16x32_bf16 v[80:83], v[182:185], v[212:215], v[80:83]
	v_mfma_f32_16x16x32_bf16 v[64:67], v[182:185], v[220:223], v[64:67]
	v_mfma_f32_16x16x32_bf16 v[68:71], v[172:175], v[220:223], v[68:71]
	s_setprio 0
	s_barrier
	s_add_i32 s50, s64, s33
	v_lshl_add_u64 v[224:225], s[54:55], 0, v[130:131]
	s_mov_b32 m0, s50
	ds_read_b128 v[186:189], v153 offset:16384
	ds_read_b128 v[190:193], v153 offset:17408
	ds_read_b128 v[194:197], v153 offset:18432
	ds_read_b128 v[198:201], v153 offset:19456
	ds_read_b128 v[208:211], v153 offset:20480
	ds_read_b128 v[212:215], v153 offset:21504
	ds_read_b128 v[216:219], v153 offset:22528
	ds_read_b128 v[220:223], v153 offset:23552
	global_load_lds_dwordx4 v[224:225], off
	s_add_i32 m0, s50, 0x2000
	s_add_u32 s50, s54, 0xb0000
	v_lshl_add_u64 v[226:227], s[54:55], 0, v[134:135]
	s_addc_u32 s51, s55, 0
	s_add_i32 s78, s65, s33
	global_load_lds_dwordx4 v[226:227], off
	v_lshl_add_u64 v[228:229], s[50:51], 0, v[130:131]
	s_mov_b32 m0, s78
	global_load_lds_dwordx4 v[228:229], off
	v_lshl_add_u64 v[228:229], s[50:51], 0, v[134:135]
	s_add_i32 m0, s78, 0x2000
	s_nop 0
	global_load_lds_dwordx4 v[228:229], off
	s_waitcnt vmcnt(6)
	s_waitcnt lgkmcnt(0)
	s_barrier
; #define PG8_STAGE(bufoff, gbase, voff) do { _Pragma("unroll") for (int _i = 0; _i < 2; ++_i) \
;         __builtin_amdgcn_global_load_lds((const unsigned*)((const char*)(gbase) + (voff)[_i]), (PG8_LAS unsigned*)(lds + (bufoff) + ldsw + _i * 8192), 16, 0, 0); } while (0)
; #define PG8_LDA(dst, b, h) do { _Pragma("unroll") for (int m = 0; m < 4; ++m) _Pragma("unroll") for (int k = 0; k < 2; ++k) dst[m][k] = *(const PG8_LAS bf16x8*)(lds + PG8_SA(b, h) + aoff + m * 2048 + k * 1024); } while (0)
; #define PG8_LDB(dst, b, h) do { _Pragma("unroll") for (int n = 0; n < 2; ++n) _Pragma("unroll") for (int k = 0; k < 2; ++k) dst[n][k] = *(const PG8_LAS bf16x8*)(lds + PG8_SB(b, h) + boff + n * 2048 + k * 1024); } while (0)
; #define PG8_MMA(ai, bj, At, Bt) do { __builtin_amdgcn_s_setprio(1); _Pragma("unroll") for (int m = 0; m < 4; ++m) _Pragma("unroll") for (int n = 0; n < 2; ++n) _Pragma("unroll") for (int k = 0; k < 2; ++k) \
;         acc[ai][bj][m][n] = __builtin_amdgcn_mfma_f32_16x16x32_bf16(Bt[n][k], At[m][k], acc[ai][bj][m][n], 0, 0, 0); __builtin_amdgcn_s_setprio(0); } while (0)
; #define PG8_WAIT_V(n) asm volatile("s_waitcnt vmcnt(" #n ")" ::: "memory")
; #define PG8_WAIT_L(n) asm volatile("s_waitcnt lgkmcnt(" #n ")" ::: "memory")
; #define PG8_BAR __builtin_amdgcn_s_barrier()
; #define PG8_SCHED __builtin_amdgcn_sched_barrier(0)
; template <class Epi, class Sched, bool ALIGN_EPI = false, bool SP2 = false>
; __device__ __forceinline__ void gemm_phase(PG8_LAS unsigned char* lds, const Gemm g, const Sched& S, const Epi& E) {
;     ...
;             PG8_WAIT_V(8); PG8_WAIT_L(0); PG8_BAR; PG8_MMA(1, 0, At, B0); PG8_MMA(1, 1, At, B1); PG8_BAR; PG8_SCHED;
;             PG8_LDB(B0, 1, 0); PG8_LDB(B1, 1, 1); PG8_SCHED; PG8_LDA(At, 1, 0); PG8_STAGE(PG8_SA(0, 1), a2 + hstep, voffA);
;             PG8_WAIT_V(8); PG8_WAIT_L(0); PG8_BAR; PG8_MMA(0, 0, At, B0); PG8_MMA(0, 1, At, B1); PG8_BAR; PG8_SCHED;
	s_setprio 1
	s_waitcnt lgkmcnt(0)
	v_mfma_f32_16x16x32_bf16 v[60:63], v[144:147], v[186:189], 0
	v_mfma_f32_16x16x32_bf16 v[56:59], v[160:163], v[186:189], 0
	v_mfma_f32_16x16x32_bf16 v[40:43], v[160:163], v[194:197], 0
	v_mfma_f32_16x16x32_bf16 v[44:47], v[144:147], v[194:197], 0
	v_mfma_f32_16x16x32_bf16 v[28:31], v[144:147], v[208:211], 0
	v_mfma_f32_16x16x32_bf16 v[24:27], v[160:163], v[208:211], 0
	v_mfma_f32_16x16x32_bf16 v[8:11], v[160:163], v[216:219], 0
	v_mfma_f32_16x16x32_bf16 v[12:15], v[144:147], v[216:219], 0
	v_mfma_f32_16x16x32_bf16 v[60:63], v[156:159], v[190:193], v[60:63]
	v_mfma_f32_16x16x32_bf16 v[56:59], v[164:167], v[190:193], v[56:59]
	v_mfma_f32_16x16x32_bf16 v[40:43], v[164:167], v[198:201], v[40:43]
	v_mfma_f32_16x16x32_bf16 v[44:47], v[156:159], v[198:201], v[44:47]
	v_mfma_f32_16x16x32_bf16 v[28:31], v[156:159], v[212:215], v[28:31]
	v_mfma_f32_16x16x32_bf16 v[24:27], v[164:167], v[212:215], v[24:27]
	v_lshl_add_u64 v[228:229], s[56:57], 0, v[128:129]
	s_mov_b32 m0, s34
	s_nop 0
	global_load_lds_dwordx4 v[228:229], off
	v_mfma_f32_16x16x32_bf16 v[8:11], v[164:167], v[220:223], v[8:11]
	v_mfma_f32_16x16x32_bf16 v[12:15], v[156:159], v[220:223], v[12:15]
	s_setprio 0
	s_setprio 1
	v_mfma_f32_16x16x32_bf16 v[52:55], v[168:171], v[186:189], 0
	v_mfma_f32_16x16x32_bf16 v[48:51], v[176:179], v[186:189], 0
	v_mfma_f32_16x16x32_bf16 v[32:35], v[176:179], v[194:197], 0
	v_mfma_f32_16x16x32_bf16 v[36:39], v[168:171], v[194:197], 0
	v_mfma_f32_16x16x32_bf16 v[20:23], v[168:171], v[208:211], 0
	v_mfma_f32_16x16x32_bf16 v[16:19], v[176:179], v[208:211], 0
	v_mfma_f32_16x16x32_bf16 v[0:3], v[176:179], v[216:219], 0
	v_mfma_f32_16x16x32_bf16 v[4:7], v[168:171], v[216:219], 0
	v_mfma_f32_16x16x32_bf16 v[52:55], v[172:175], v[190:193], v[52:55]
	v_mfma_f32_16x16x32_bf16 v[48:51], v[182:185], v[190:193], v[48:51]
	v_mfma_f32_16x16x32_bf16 v[32:35], v[182:185], v[198:201], v[32:35]
	v_mfma_f32_16x16x32_bf16 v[36:39], v[172:175], v[198:201], v[36:39]
	v_mfma_f32_16x16x32_bf16 v[20:23], v[172:175], v[212:215], v[20:23]
	v_mfma_f32_16x16x32_bf16 v[16:19], v[182:185], v[212:215], v[16:19]
	v_lshl_add_u64 v[230:231], s[56:57], 0, v[132:133]
	s_mov_b32 m0, s58
	s_nop 0
	global_load_lds_dwordx4 v[230:231], off
	v_mfma_f32_16x16x32_bf16 v[0:3], v[182:185], v[220:223], v[0:3]
	v_mfma_f32_16x16x32_bf16 v[4:7], v[172:175], v[220:223], v[4:7]
	s_setprio 0
	s_barrier
	s_add_i32 s78, 0, 0x18000
	v_add_u32_e32 v155, s78, v149
	s_add_i32 s79, 0, 0x1c000
	ds_read_b128 v[144:147], v155
	ds_read_b128 v[156:159], v155 offset:1024
	ds_read_b128 v[160:163], v155 offset:2048
	ds_read_b128 v[164:167], v155 offset:3072
	v_add_u32_e32 v155, s79, v149
	ds_read_b128 v[168:171], v155
	ds_read_b128 v[172:175], v155 offset:1024
	ds_read_b128 v[176:179], v155 offset:2048
	ds_read_b128 v[182:185], v155 offset:3072
	s_add_u32 s50, s56, 0xb0000
	s_addc_u32 s51, s57, 0
	s_mov_b32 m0, s59
	v_lshl_add_u64 v[232:233], s[50:51], 0, v[128:129]
	ds_read_b128 v[186:189], v153 offset:32768
	ds_read_b128 v[190:193], v153 offset:33792
	ds_read_b128 v[194:197], v153 offset:34816
	ds_read_b128 v[198:201], v153 offset:35840
	ds_read_b128 v[208:211], v153 offset:36864
	ds_read_b128 v[212:215], v153 offset:37888
	ds_read_b128 v[216:219], v153 offset:38912
	ds_read_b128 v[220:223], v153 offset:39936
	global_load_lds_dwordx4 v[232:233], off
	v_lshl_add_u64 v[232:233], s[50:51], 0, v[132:133]
	s_mov_b32 m0, s60
	s_nop 0
	global_load_lds_dwordx4 v[232:233], off
	s_waitcnt vmcnt(8)
	s_waitcnt lgkmcnt(0)
	s_barrier
	s_setprio 1
	s_waitcnt lgkmcnt(0)
	v_mfma_f32_16x16x32_bf16 v[124:127], v[144:147], v[186:189], v[124:127]
	v_mfma_f32_16x16x32_bf16 v[120:123], v[160:163], v[186:189], v[120:123]
	v_mfma_f32_16x16x32_bf16 v[104:107], v[160:163], v[194:197], v[104:107]
	v_mfma_f32_16x16x32_bf16 v[108:111], v[144:147], v[194:197], v[108:111]
	v_mfma_f32_16x16x32_bf16 v[92:95], v[144:147], v[208:211], v[92:95]
	v_mfma_f32_16x16x32_bf16 v[88:91], v[160:163], v[208:211], v[88:91]
	v_mfma_f32_16x16x32_bf16 v[72:75], v[160:163], v[216:219], v[72:75]
	v_mfma_f32_16x16x32_bf16 v[76:79], v[144:147], v[216:219], v[76:79]
	v_mfma_f32_16x16x32_bf16 v[124:127], v[156:159], v[190:193], v[124:127]
	v_mfma_f32_16x16x32_bf16 v[120:123], v[164:167], v[190:193], v[120:123]
	v_mfma_f32_16x16x32_bf16 v[104:107], v[164:167], v[198:201], v[104:107]
	v_mfma_f32_16x16x32_bf16 v[108:111], v[156:159], v[198:201], v[108:111]
	v_mfma_f32_16x16x32_bf16 v[92:95], v[156:159], v[212:215], v[92:95]
	v_mfma_f32_16x16x32_bf16 v[88:91], v[164:167], v[212:215], v[88:91]
	v_mfma_f32_16x16x32_bf16 v[72:75], v[164:167], v[220:223], v[72:75]
	v_mfma_f32_16x16x32_bf16 v[76:79], v[156:159], v[220:223], v[76:79]
	s_setprio 0
	s_setprio 1
	v_mfma_f32_16x16x32_bf16 v[116:119], v[168:171], v[186:189], v[116:119]
	v_mfma_f32_16x16x32_bf16 v[112:115], v[176:179], v[186:189], v[112:115]
	v_mfma_f32_16x16x32_bf16 v[96:99], v[176:179], v[194:197], v[96:99]
	v_mfma_f32_16x16x32_bf16 v[100:103], v[168:171], v[194:197], v[100:103]
	v_mfma_f32_16x16x32_bf16 v[84:87], v[168:171], v[208:211], v[84:87]
	v_mfma_f32_16x16x32_bf16 v[80:83], v[176:179], v[208:211], v[80:83]
	v_mfma_f32_16x16x32_bf16 v[64:67], v[176:179], v[216:219], v[64:67]
	v_mfma_f32_16x16x32_bf16 v[68:71], v[168:171], v[216:219], v[68:71]
	v_mfma_f32_16x16x32_bf16 v[116:119], v[172:175], v[190:193], v[116:119]
	v_mfma_f32_16x16x32_bf16 v[112:115], v[182:185], v[190:193], v[112:115]
	v_mfma_f32_16x16x32_bf16 v[96:99], v[182:185], v[198:201], v[96:99]
	v_mfma_f32_16x16x32_bf16 v[100:103], v[172:175], v[198:201], v[100:103]
	v_mfma_f32_16x16x32_bf16 v[84:87], v[172:175], v[212:215], v[84:87]
	v_mfma_f32_16x16x32_bf16 v[80:83], v[182:185], v[212:215], v[80:83]
	v_mfma_f32_16x16x32_bf16 v[64:67], v[182:185], v[220:223], v[64:67]
	v_mfma_f32_16x16x32_bf16 v[68:71], v[172:175], v[220:223], v[68:71]
	s_setprio 0
	s_barrier
; #define PG8_STAGE(bufoff, gbase, voff) do { _Pragma("unroll") for (int _i = 0; _i < 2; ++_i) \
;         __builtin_amdgcn_global_load_lds((const unsigned*)((const char*)(gbase) + (voff)[_i]), (PG8_LAS unsigned*)(lds + (bufoff) + ldsw + _i * 8192), 16, 0, 0); } while (0)
; #define PG8_LDA(dst, b, h) do { _Pragma("unroll") for (int m = 0; m < 4; ++m) _Pragma("unroll") for (int k = 0; k < 2; ++k) dst[m][k] = *(const PG8_LAS bf16x8*)(lds + PG8_SA(b, h) + aoff + m * 2048 + k * 1024); } while (0)
; #define PG8_LDB(dst, b, h) do { _Pragma("unroll") for (int n = 0; n < 2; ++n) _Pragma("unroll") for (int k = 0; k < 2; ++k) dst[n][k] = *(const PG8_LAS bf16x8*)(lds + PG8_SB(b, h) + boff + n * 2048 + k * 1024); } while (0)
; #define PG8_MMA(ai, bj, At, Bt) do { __builtin_amdgcn_s_setprio(1); _Pragma("unroll") for (int m = 0; m < 4; ++m) _Pragma("unroll") for (int n = 0; n < 2; ++n) _Pragma("unroll") for (int k = 0; k < 2; ++k) \
;         acc[ai][bj][m][n] = __builtin_amdgcn_mfma_f32_16x16x32_bf16(Bt[n][k], At[m][k], acc[ai][bj][m][n], 0, 0, 0); __builtin_amdgcn_s_setprio(0); } while (0)
; #define PG8_WAIT_V(n) asm volatile("s_waitcnt vmcnt(" #n ")" ::: "memory")
; #define PG8_WAIT_L(n) asm volatile("s_waitcnt lgkmcnt(" #n ")" ::: "memory")
; #define PG8_BAR __builtin_amdgcn_s_barrier()
; #define PG8_SCHED __builtin_amdgcn_sched_barrier(0)
; template <class Epi, class Sched, bool ALIGN_EPI = false, bool SP2 = false>
; __device__ __forceinline__ void gemm_phase(PG8_LAS unsigned char* lds, const Gemm g, const Sched& S, const Epi& E) {
;     ...
;             PG8_LDB(B0, 0, 0); PG8_LDB(B1, 0, 1); PG8_SCHED; PG8_LDA(At, 0, 0); PG8_STAGE(PG8_SA(1, 1), a1 + hstep, voffA);
;     ...
;             PG8_LDA(At, 1, 1); PG8_STAGE(PG8_SB(1, 0), b3, voffB); PG8_STAGE(PG8_SB(1, 1), b3 + hstep, voffB); PG8_STAGE(PG8_SA(1, 0), a3, voffA);
;             PG8_WAIT_V(8); PG8_WAIT_L(0); PG8_BAR; PG8_MMA(1, 0, At, B0); PG8_MMA(1, 1, At, B1); PG8_BAR; PG8_SCHED;
	s_add_i32 s50, s78, s33
	v_lshl_add_u64 v[224:225], v[224:225], 0, s[42:43]
	s_mov_b32 m0, s50
	ds_read_b128 v[186:189], v153 offset:49152
	ds_read_b128 v[190:193], v153 offset:50176
	ds_read_b128 v[194:197], v153 offset:51200
	ds_read_b128 v[198:201], v153 offset:52224
	ds_read_b128 v[208:211], v153 offset:53248
	ds_read_b128 v[212:215], v153 offset:54272
	ds_read_b128 v[216:219], v153 offset:55296
	ds_read_b128 v[220:223], v153 offset:56320
	global_load_lds_dwordx4 v[224:225], off
	s_add_i32 m0, s50, 0x2000
	s_add_u32 s50, s54, 0xb0080
	v_lshl_add_u64 v[224:225], v[226:227], 0, s[42:43]
	s_addc_u32 s51, s55, 0
	s_add_i32 s54, s79, s33
	global_load_lds_dwordx4 v[224:225], off
	v_lshl_add_u64 v[224:225], s[50:51], 0, v[130:131]
	s_mov_b32 m0, s54
	s_nop 0
	global_load_lds_dwordx4 v[224:225], off
	v_lshl_add_u64 v[224:225], s[50:51], 0, v[134:135]
	s_add_i32 m0, s54, 0x2000
	s_nop 0
	global_load_lds_dwordx4 v[224:225], off
	s_waitcnt vmcnt(6)
	s_waitcnt lgkmcnt(0)
	s_barrier
	s_setprio 1
	s_waitcnt lgkmcnt(0)
	v_mfma_f32_16x16x32_bf16 v[60:63], v[144:147], v[186:189], v[60:63]
	v_mfma_f32_16x16x32_bf16 v[56:59], v[160:163], v[186:189], v[56:59]
	v_mfma_f32_16x16x32_bf16 v[40:43], v[160:163], v[194:197], v[40:43]
	v_mfma_f32_16x16x32_bf16 v[44:47], v[144:147], v[194:197], v[44:47]
	v_mfma_f32_16x16x32_bf16 v[28:31], v[144:147], v[208:211], v[28:31]
	v_mfma_f32_16x16x32_bf16 v[24:27], v[160:163], v[208:211], v[24:27]
	v_mfma_f32_16x16x32_bf16 v[8:11], v[160:163], v[216:219], v[8:11]
	v_mfma_f32_16x16x32_bf16 v[12:15], v[144:147], v[216:219], v[12:15]
	v_mfma_f32_16x16x32_bf16 v[60:63], v[156:159], v[190:193], v[60:63]
	v_mfma_f32_16x16x32_bf16 v[56:59], v[164:167], v[190:193], v[56:59]
	v_mfma_f32_16x16x32_bf16 v[40:43], v[164:167], v[198:201], v[40:43]
	v_mfma_f32_16x16x32_bf16 v[44:47], v[156:159], v[198:201], v[44:47]
	v_mfma_f32_16x16x32_bf16 v[28:31], v[156:159], v[212:215], v[28:31]
	v_mfma_f32_16x16x32_bf16 v[24:27], v[164:167], v[212:215], v[24:27]
	v_lshl_add_u64 v[224:225], v[228:229], 0, s[42:43]
	s_mov_b32 m0, s62
	s_nop 0
	global_load_lds_dwordx4 v[224:225], off
	v_mfma_f32_16x16x32_bf16 v[8:11], v[164:167], v[220:223], v[8:11]
	v_mfma_f32_16x16x32_bf16 v[12:15], v[156:159], v[220:223], v[12:15]
	s_setprio 0
	s_setprio 1
	v_mfma_f32_16x16x32_bf16 v[52:55], v[168:171], v[186:189], v[52:55]
	v_mfma_f32_16x16x32_bf16 v[48:51], v[176:179], v[186:189], v[48:51]
	v_mfma_f32_16x16x32_bf16 v[32:35], v[176:179], v[194:197], v[32:35]
	v_mfma_f32_16x16x32_bf16 v[36:39], v[168:171], v[194:197], v[36:39]
	v_mfma_f32_16x16x32_bf16 v[20:23], v[168:171], v[208:211], v[20:23]
	v_mfma_f32_16x16x32_bf16 v[16:19], v[176:179], v[208:211], v[16:19]
	v_mfma_f32_16x16x32_bf16 v[0:3], v[176:179], v[216:219], v[0:3]
	v_mfma_f32_16x16x32_bf16 v[4:7], v[168:171], v[216:219], v[4:7]
	v_mfma_f32_16x16x32_bf16 v[52:55], v[172:175], v[190:193], v[52:55]
	v_mfma_f32_16x16x32_bf16 v[48:51], v[182:185], v[190:193], v[48:51]
	v_mfma_f32_16x16x32_bf16 v[32:35], v[182:185], v[198:201], v[32:35]
	v_mfma_f32_16x16x32_bf16 v[36:39], v[172:175], v[198:201], v[36:39]
	v_mfma_f32_16x16x32_bf16 v[20:23], v[172:175], v[212:215], v[20:23]
	v_mfma_f32_16x16x32_bf16 v[16:19], v[182:185], v[212:215], v[16:19]
	v_lshl_add_u64 v[224:225], v[230:231], 0, s[42:43]
	s_mov_b32 m0, s63
	s_nop 0
	global_load_lds_dwordx4 v[224:225], off
	v_mfma_f32_16x16x32_bf16 v[0:3], v[182:185], v[220:223], v[0:3]
	v_mfma_f32_16x16x32_bf16 v[4:7], v[172:175], v[220:223], v[4:7]
	s_setprio 0
	s_barrier
	s_add_i32 s84, s84, 2
	s_add_u32 s82, s82, 0x100
	s_addc_u32 s83, s83, 0
	s_mov_b64 s[50:51], s[52:53]
.LBB0_1197:
	ds_read_b128 v[144:147], v151
	ds_read_b128 v[156:159], v151 offset:1024
	ds_read_b128 v[160:163], v151 offset:2048
	ds_read_b128 v[164:167], v151 offset:3072
	ds_read_b128 v[168:171], v152
	ds_read_b128 v[172:175], v152 offset:1024
	ds_read_b128 v[176:179], v152 offset:2048
	ds_read_b128 v[182:185], v152 offset:3072
	s_add_u32 s52, s50, 0x100
	s_addc_u32 s53, s51, 0
	s_cmp_eq_u32 s84, 40
	s_cselect_b32 s57, s1, s53
	s_cselect_b32 s56, s0, s52
	s_cselect_b32 s55, s49, s83
	s_cselect_b32 s54, s48, s82
	v_lshl_add_u64 v[224:225], s[50:51], 0, v[136:137]
	s_add_i32 m0, s34, 0xc000
	ds_read_b128 v[186:189], v153
	ds_read_b128 v[190:193], v153 offset:1024
	ds_read_b128 v[194:197], v153 offset:2048
	ds_read_b128 v[198:201], v153 offset:3072
	ds_read_b128 v[208:211], v153 offset:4096
	ds_read_b128 v[212:215], v153 offset:5120
	ds_read_b128 v[216:219], v153 offset:6144
	ds_read_b128 v[220:223], v153 offset:7168
	global_load_lds_dwordx4 v[224:225], off
	v_lshl_add_u64 v[224:225], s[50:51], 0, v[138:139]
	s_add_i32 m0, s34, 0xe000
	s_nop 0
	global_load_lds_dwordx4 v[224:225], off
	s_waitcnt vmcnt(8)
	s_waitcnt lgkmcnt(0)
	s_barrier
; #define PG8_STAGE(bufoff, gbase, voff) do { _Pragma("unroll") for (int _i = 0; _i < 2; ++_i) \
;         __builtin_amdgcn_global_load_lds((const unsigned*)((const char*)(gbase) + (voff)[_i]), (PG8_LAS unsigned*)(lds + (bufoff) + ldsw + _i * 8192), 16, 0, 0); } while (0)
; #define PG8_LDA(dst, b, h) do { _Pragma("unroll") for (int m = 0; m < 4; ++m) _Pragma("unroll") for (int k = 0; k < 2; ++k) dst[m][k] = *(const PG8_LAS bf16x8*)(lds + PG8_SA(b, h) + aoff + m * 2048 + k * 1024); } while (0)
; #define PG8_MMA(ai, bj, At, Bt) do { __builtin_amdgcn_s_setprio(1); _Pragma("unroll") for (int m = 0; m < 4; ++m) _Pragma("unroll") for (int n = 0; n < 2; ++n) _Pragma("unroll") for (int k = 0; k < 2; ++k) \
;         acc[ai][bj][m][n] = __builtin_amdgcn_mfma_f32_16x16x32_bf16(Bt[n][k], At[m][k], acc[ai][bj][m][n], 0, 0, 0); __builtin_amdgcn_s_setprio(0); } while (0)
; #define PG8_WAIT_V(n) asm volatile("s_waitcnt vmcnt(" #n ")" ::: "memory")
; #define PG8_WAIT_L(n) asm volatile("s_waitcnt lgkmcnt(" #n ")" ::: "memory")
; #define PG8_BAR __builtin_amdgcn_s_barrier()
; #define PG8_SCHED __builtin_amdgcn_sched_barrier(0)
; template <class Epi, class Sched, bool ALIGN_EPI = false, bool SP2 = false>
; __device__ __forceinline__ void gemm_phase(PG8_LAS unsigned char* lds, const Gemm g, const Sched& S, const Epi& E) {
;     ...
;             PG8_WAIT_V(8); PG8_WAIT_L(0); PG8_BAR; PG8_MMA(0, 0, At, B0); PG8_MMA(0, 1, At, B1); PG8_BAR; PG8_SCHED;
;             PG8_LDA(At, 0, 1); PG8_STAGE(PG8_SB(0, 0), b2, voffB); PG8_STAGE(PG8_SB(0, 1), b2 + hstep, voffB); PG8_STAGE(PG8_SA(0, 0), a2, voffA);
;             PG8_WAIT_V(8); PG8_WAIT_L(0); PG8_BAR; PG8_MMA(1, 0, At, B0); PG8_MMA(1, 1, At, B1); PG8_BAR; PG8_SCHED;
	s_setprio 1
	s_waitcnt lgkmcnt(0)
	v_mfma_f32_16x16x32_bf16 v[124:127], v[144:147], v[186:189], v[124:127]
	v_mfma_f32_16x16x32_bf16 v[120:123], v[160:163], v[186:189], v[120:123]
	v_mfma_f32_16x16x32_bf16 v[104:107], v[160:163], v[194:197], v[104:107]
	v_mfma_f32_16x16x32_bf16 v[108:111], v[144:147], v[194:197], v[108:111]
	v_mfma_f32_16x16x32_bf16 v[92:95], v[144:147], v[208:211], v[92:95]
	v_mfma_f32_16x16x32_bf16 v[88:91], v[160:163], v[208:211], v[88:91]
	v_mfma_f32_16x16x32_bf16 v[72:75], v[160:163], v[216:219], v[72:75]
	v_mfma_f32_16x16x32_bf16 v[76:79], v[144:147], v[216:219], v[76:79]
	v_mfma_f32_16x16x32_bf16 v[124:127], v[156:159], v[190:193], v[124:127]
	v_mfma_f32_16x16x32_bf16 v[120:123], v[164:167], v[190:193], v[120:123]
	v_mfma_f32_16x16x32_bf16 v[104:107], v[164:167], v[198:201], v[104:107]
	v_mfma_f32_16x16x32_bf16 v[108:111], v[156:159], v[198:201], v[108:111]
	v_mfma_f32_16x16x32_bf16 v[92:95], v[156:159], v[212:215], v[92:95]
	v_mfma_f32_16x16x32_bf16 v[88:91], v[164:167], v[212:215], v[88:91]
	v_mfma_f32_16x16x32_bf16 v[72:75], v[164:167], v[220:223], v[72:75]
	v_mfma_f32_16x16x32_bf16 v[76:79], v[156:159], v[220:223], v[76:79]
	s_setprio 0
	s_setprio 1
	v_mfma_f32_16x16x32_bf16 v[116:119], v[168:171], v[186:189], v[116:119]
	v_mfma_f32_16x16x32_bf16 v[112:115], v[176:179], v[186:189], v[112:115]
	v_mfma_f32_16x16x32_bf16 v[96:99], v[176:179], v[194:197], v[96:99]
	v_mfma_f32_16x16x32_bf16 v[100:103], v[168:171], v[194:197], v[100:103]
	v_mfma_f32_16x16x32_bf16 v[84:87], v[168:171], v[208:211], v[84:87]
	v_mfma_f32_16x16x32_bf16 v[80:83], v[176:179], v[208:211], v[80:83]
	v_mfma_f32_16x16x32_bf16 v[64:67], v[176:179], v[216:219], v[64:67]
	v_mfma_f32_16x16x32_bf16 v[68:71], v[168:171], v[216:219], v[68:71]
	v_mfma_f32_16x16x32_bf16 v[116:119], v[172:175], v[190:193], v[116:119]
	v_mfma_f32_16x16x32_bf16 v[112:115], v[182:185], v[190:193], v[112:115]
	v_mfma_f32_16x16x32_bf16 v[96:99], v[182:185], v[198:201], v[96:99]
	v_mfma_f32_16x16x32_bf16 v[100:103], v[172:175], v[198:201], v[100:103]
	v_mfma_f32_16x16x32_bf16 v[84:87], v[172:175], v[212:215], v[84:87]
	v_mfma_f32_16x16x32_bf16 v[80:83], v[182:185], v[212:215], v[80:83]
	v_mfma_f32_16x16x32_bf16 v[64:67], v[182:185], v[220:223], v[64:67]
	v_mfma_f32_16x16x32_bf16 v[68:71], v[172:175], v[220:223], v[68:71]
	s_setprio 0
	s_barrier
	s_add_i32 s50, s64, s33
	v_lshl_add_u64 v[224:225], s[54:55], 0, v[130:131]
	s_mov_b32 m0, s50
	ds_read_b128 v[186:189], v153 offset:16384
	ds_read_b128 v[190:193], v153 offset:17408
	ds_read_b128 v[194:197], v153 offset:18432
	ds_read_b128 v[198:201], v153 offset:19456
	ds_read_b128 v[208:211], v153 offset:20480
	ds_read_b128 v[212:215], v153 offset:21504
	ds_read_b128 v[216:219], v153 offset:22528
	ds_read_b128 v[220:223], v153 offset:23552
	global_load_lds_dwordx4 v[224:225], off
	s_add_i32 m0, s50, 0x2000
	s_add_u32 s50, s54, 0xb0000
	v_lshl_add_u64 v[226:227], s[54:55], 0, v[134:135]
	s_addc_u32 s51, s55, 0
	s_add_i32 s78, s65, s33
	global_load_lds_dwordx4 v[226:227], off
	v_lshl_add_u64 v[228:229], s[50:51], 0, v[130:131]
	s_mov_b32 m0, s78
	global_load_lds_dwordx4 v[228:229], off
	v_lshl_add_u64 v[228:229], s[50:51], 0, v[134:135]
	s_add_i32 m0, s78, 0x2000
	s_nop 0
	global_load_lds_dwordx4 v[228:229], off
	s_waitcnt vmcnt(6)
	s_waitcnt lgkmcnt(0)
	s_barrier
	s_setprio 1
	s_waitcnt lgkmcnt(0)
	v_mfma_f32_16x16x32_bf16 v[60:63], v[144:147], v[186:189], v[60:63]
	v_mfma_f32_16x16x32_bf16 v[56:59], v[160:163], v[186:189], v[56:59]
	v_mfma_f32_16x16x32_bf16 v[40:43], v[160:163], v[194:197], v[40:43]
	v_mfma_f32_16x16x32_bf16 v[44:47], v[144:147], v[194:197], v[44:47]
	v_mfma_f32_16x16x32_bf16 v[28:31], v[144:147], v[208:211], v[28:31]
	v_mfma_f32_16x16x32_bf16 v[24:27], v[160:163], v[208:211], v[24:27]
	v_mfma_f32_16x16x32_bf16 v[8:11], v[160:163], v[216:219], v[8:11]
	v_mfma_f32_16x16x32_bf16 v[12:15], v[144:147], v[216:219], v[12:15]
	v_mfma_f32_16x16x32_bf16 v[60:63], v[156:159], v[190:193], v[60:63]
	v_mfma_f32_16x16x32_bf16 v[56:59], v[164:167], v[190:193], v[56:59]
	v_mfma_f32_16x16x32_bf16 v[40:43], v[164:167], v[198:201], v[40:43]
	v_mfma_f32_16x16x32_bf16 v[44:47], v[156:159], v[198:201], v[44:47]
	v_mfma_f32_16x16x32_bf16 v[28:31], v[156:159], v[212:215], v[28:31]
	v_mfma_f32_16x16x32_bf16 v[24:27], v[164:167], v[212:215], v[24:27]
	v_lshl_add_u64 v[228:229], s[56:57], 0, v[128:129]
	s_mov_b32 m0, s34
	s_nop 0
	global_load_lds_dwordx4 v[228:229], off
	v_mfma_f32_16x16x32_bf16 v[8:11], v[164:167], v[220:223], v[8:11]
	v_mfma_f32_16x16x32_bf16 v[12:15], v[156:159], v[220:223], v[12:15]
	s_setprio 0
	s_setprio 1
	v_mfma_f32_16x16x32_bf16 v[52:55], v[168:171], v[186:189], v[52:55]
	v_mfma_f32_16x16x32_bf16 v[48:51], v[176:179], v[186:189], v[48:51]
	v_mfma_f32_16x16x32_bf16 v[32:35], v[176:179], v[194:197], v[32:35]
	v_mfma_f32_16x16x32_bf16 v[36:39], v[168:171], v[194:197], v[36:39]
	v_mfma_f32_16x16x32_bf16 v[20:23], v[168:171], v[208:211], v[20:23]
	v_mfma_f32_16x16x32_bf16 v[16:19], v[176:179], v[208:211], v[16:19]
	v_mfma_f32_16x16x32_bf16 v[0:3], v[176:179], v[216:219], v[0:3]
	v_mfma_f32_16x16x32_bf16 v[4:7], v[168:171], v[216:219], v[4:7]
	v_mfma_f32_16x16x32_bf16 v[52:55], v[172:175], v[190:193], v[52:55]
	v_mfma_f32_16x16x32_bf16 v[48:51], v[182:185], v[190:193], v[48:51]
	v_mfma_f32_16x16x32_bf16 v[32:35], v[182:185], v[198:201], v[32:35]
	v_mfma_f32_16x16x32_bf16 v[36:39], v[172:175], v[198:201], v[36:39]
	v_mfma_f32_16x16x32_bf16 v[20:23], v[172:175], v[212:215], v[20:23]
	v_mfma_f32_16x16x32_bf16 v[16:19], v[182:185], v[212:215], v[16:19]
	v_lshl_add_u64 v[230:231], s[56:57], 0, v[132:133]
	s_mov_b32 m0, s58
	s_nop 0
	global_load_lds_dwordx4 v[230:231], off
	v_mfma_f32_16x16x32_bf16 v[0:3], v[182:185], v[220:223], v[0:3]
	v_mfma_f32_16x16x32_bf16 v[4:7], v[172:175], v[220:223], v[4:7]
	s_setprio 0
	s_barrier
; #define PG8_STAGE(bufoff, gbase, voff) do { _Pragma("unroll") for (int _i = 0; _i < 2; ++_i) \
;         __builtin_amdgcn_global_load_lds((const unsigned*)((const char*)(gbase) + (voff)[_i]), (PG8_LAS unsigned*)(lds + (bufoff) + ldsw + _i * 8192), 16, 0, 0); } while (0)
; #define PG8_LDA(dst, b, h) do { _Pragma("unroll") for (int m = 0; m < 4; ++m) _Pragma("unroll") for (int k = 0; k < 2; ++k) dst[m][k] = *(const PG8_LAS bf16x8*)(lds + PG8_SA(b, h) + aoff + m * 2048 + k * 1024); } while (0)
; #define PG8_LDB(dst, b, h) do { _Pragma("unroll") for (int n = 0; n < 2; ++n) _Pragma("unroll") for (int k = 0; k < 2; ++k) dst[n][k] = *(const PG8_LAS bf16x8*)(lds + PG8_SB(b, h) + boff + n * 2048 + k * 1024); } while (0)
; #define PG8_MMA(ai, bj, At, Bt) do { __builtin_amdgcn_s_setprio(1); _Pragma("unroll") for (int m = 0; m < 4; ++m) _Pragma("unroll") for (int n = 0; n < 2; ++n) _Pragma("unroll") for (int k = 0; k < 2; ++k) \
;         acc[ai][bj][m][n] = __builtin_amdgcn_mfma_f32_16x16x32_bf16(Bt[n][k], At[m][k], acc[ai][bj][m][n], 0, 0, 0); __builtin_amdgcn_s_setprio(0); } while (0)
; #define PG8_WAIT_V(n) asm volatile("s_waitcnt vmcnt(" #n ")" ::: "memory")
; #define PG8_WAIT_L(n) asm volatile("s_waitcnt lgkmcnt(" #n ")" ::: "memory")
; #define PG8_BAR __builtin_amdgcn_s_barrier()
; #define PG8_SCHED __builtin_amdgcn_sched_barrier(0)
; template <class Epi, class Sched, bool ALIGN_EPI = false, bool SP2 = false>
; __device__ __forceinline__ void gemm_phase(PG8_LAS unsigned char* lds, const Gemm g, const Sched& S, const Epi& E) {
;     ...
;             PG8_LDB(B0, 1, 0); PG8_LDB(B1, 1, 1); PG8_SCHED; PG8_LDA(At, 1, 0); PG8_STAGE(PG8_SA(0, 1), a2 + hstep, voffA);
;             PG8_WAIT_V(8); PG8_WAIT_L(0); PG8_BAR; PG8_MMA(0, 0, At, B0); PG8_MMA(0, 1, At, B1); PG8_BAR; PG8_SCHED;
	s_add_i32 s78, 0, 0x18000
	v_add_u32_e32 v155, s78, v149
	s_add_i32 s79, 0, 0x1c000
	ds_read_b128 v[144:147], v155
	ds_read_b128 v[156:159], v155 offset:1024
	ds_read_b128 v[160:163], v155 offset:2048
	ds_read_b128 v[164:167], v155 offset:3072
	v_add_u32_e32 v155, s79, v149
	ds_read_b128 v[168:171], v155
	ds_read_b128 v[172:175], v155 offset:1024
	ds_read_b128 v[176:179], v155 offset:2048
	ds_read_b128 v[182:185], v155 offset:3072
	s_add_u32 s50, s56, 0xb0000
	s_addc_u32 s51, s57, 0
	s_mov_b32 m0, s59
	v_lshl_add_u64 v[232:233], s[50:51], 0, v[128:129]
	ds_read_b128 v[186:189], v153 offset:32768
	ds_read_b128 v[190:193], v153 offset:33792
	ds_read_b128 v[194:197], v153 offset:34816
	ds_read_b128 v[198:201], v153 offset:35840
	ds_read_b128 v[208:211], v153 offset:36864
	ds_read_b128 v[212:215], v153 offset:37888
	ds_read_b128 v[216:219], v153 offset:38912
	ds_read_b128 v[220:223], v153 offset:39936
	global_load_lds_dwordx4 v[232:233], off
	v_lshl_add_u64 v[232:233], s[50:51], 0, v[132:133]
	s_mov_b32 m0, s60
	s_nop 0
	global_load_lds_dwordx4 v[232:233], off
	s_waitcnt vmcnt(8)
	s_waitcnt lgkmcnt(0)
	s_barrier
	s_setprio 1
	s_waitcnt lgkmcnt(0)
	v_mfma_f32_16x16x32_bf16 v[124:127], v[144:147], v[186:189], v[124:127]
	v_mfma_f32_16x16x32_bf16 v[120:123], v[160:163], v[186:189], v[120:123]
	v_mfma_f32_16x16x32_bf16 v[104:107], v[160:163], v[194:197], v[104:107]
	v_mfma_f32_16x16x32_bf16 v[108:111], v[144:147], v[194:197], v[108:111]
	v_mfma_f32_16x16x32_bf16 v[92:95], v[144:147], v[208:211], v[92:95]
	v_mfma_f32_16x16x32_bf16 v[88:91], v[160:163], v[208:211], v[88:91]
	v_mfma_f32_16x16x32_bf16 v[72:75], v[160:163], v[216:219], v[72:75]
	v_mfma_f32_16x16x32_bf16 v[76:79], v[144:147], v[216:219], v[76:79]
	v_mfma_f32_16x16x32_bf16 v[124:127], v[156:159], v[190:193], v[124:127]
	v_mfma_f32_16x16x32_bf16 v[120:123], v[164:167], v[190:193], v[120:123]
	v_mfma_f32_16x16x32_bf16 v[104:107], v[164:167], v[198:201], v[104:107]
	v_mfma_f32_16x16x32_bf16 v[108:111], v[156:159], v[198:201], v[108:111]
	v_mfma_f32_16x16x32_bf16 v[92:95], v[156:159], v[212:215], v[92:95]
	v_mfma_f32_16x16x32_bf16 v[88:91], v[164:167], v[212:215], v[88:91]
	v_mfma_f32_16x16x32_bf16 v[72:75], v[164:167], v[220:223], v[72:75]
	v_mfma_f32_16x16x32_bf16 v[76:79], v[156:159], v[220:223], v[76:79]
	s_setprio 0
	s_setprio 1
	v_mfma_f32_16x16x32_bf16 v[116:119], v[168:171], v[186:189], v[116:119]
	v_mfma_f32_16x16x32_bf16 v[112:115], v[176:179], v[186:189], v[112:115]
	v_mfma_f32_16x16x32_bf16 v[96:99], v[176:179], v[194:197], v[96:99]
	v_mfma_f32_16x16x32_bf16 v[100:103], v[168:171], v[194:197], v[100:103]
	v_mfma_f32_16x16x32_bf16 v[84:87], v[168:171], v[208:211], v[84:87]
	v_mfma_f32_16x16x32_bf16 v[80:83], v[176:179], v[208:211], v[80:83]
	v_mfma_f32_16x16x32_bf16 v[64:67], v[176:179], v[216:219], v[64:67]
	v_mfma_f32_16x16x32_bf16 v[68:71], v[168:171], v[216:219], v[68:71]
	v_mfma_f32_16x16x32_bf16 v[116:119], v[172:175], v[190:193], v[116:119]
	v_mfma_f32_16x16x32_bf16 v[112:115], v[182:185], v[190:193], v[112:115]
	v_mfma_f32_16x16x32_bf16 v[96:99], v[182:185], v[198:201], v[96:99]
	v_mfma_f32_16x16x32_bf16 v[100:103], v[172:175], v[198:201], v[100:103]
	v_mfma_f32_16x16x32_bf16 v[84:87], v[172:175], v[212:215], v[84:87]
	v_mfma_f32_16x16x32_bf16 v[80:83], v[182:185], v[212:215], v[80:83]
	v_mfma_f32_16x16x32_bf16 v[64:67], v[182:185], v[220:223], v[64:67]
	v_mfma_f32_16x16x32_bf16 v[68:71], v[172:175], v[220:223], v[68:71]
	s_setprio 0
	s_barrier
; #define PG8_STAGE(bufoff, gbase, voff) do { _Pragma("unroll") for (int _i = 0; _i < 2; ++_i) \
;         __builtin_amdgcn_global_load_lds((const unsigned*)((const char*)(gbase) + (voff)[_i]), (PG8_LAS unsigned*)(lds + (bufoff) + ldsw + _i * 8192), 16, 0, 0); } while (0)
; #define PG8_LDA(dst, b, h) do { _Pragma("unroll") for (int m = 0; m < 4; ++m) _Pragma("unroll") for (int k = 0; k < 2; ++k) dst[m][k] = *(const PG8_LAS bf16x8*)(lds + PG8_SA(b, h) + aoff + m * 2048 + k * 1024); } while (0)
; #define PG8_MMA(ai, bj, At, Bt) do { __builtin_amdgcn_s_setprio(1); _Pragma("unroll") for (int m = 0; m < 4; ++m) _Pragma("unroll") for (int n = 0; n < 2; ++n) _Pragma("unroll") for (int k = 0; k < 2; ++k) \
;         acc[ai][bj][m][n] = __builtin_amdgcn_mfma_f32_16x16x32_bf16(Bt[n][k], At[m][k], acc[ai][bj][m][n], 0, 0, 0); __builtin_amdgcn_s_setprio(0); } while (0)
; #define PG8_WAIT_V(n) asm volatile("s_waitcnt vmcnt(" #n ")" ::: "memory")
; #define PG8_WAIT_L(n) asm volatile("s_waitcnt lgkmcnt(" #n ")" ::: "memory")
; #define PG8_BAR __builtin_amdgcn_s_barrier()
; #define PG8_SCHED __builtin_amdgcn_sched_barrier(0)
; template <class Epi, class Sched, bool ALIGN_EPI = false, bool SP2 = false>
; __device__ __forceinline__ void gemm_phase(PG8_LAS unsigned char* lds, const Gemm g, const Sched& S, const Epi& E) {
;     ...
;             PG8_LDA(At, 1, 1); PG8_STAGE(PG8_SB(1, 0), b3, voffB); PG8_STAGE(PG8_SB(1, 1), b3 + hstep, voffB); PG8_STAGE(PG8_SA(1, 0), a3, voffA);
;             PG8_WAIT_V(8); PG8_WAIT_L(0); PG8_BAR; PG8_MMA(1, 0, At, B0); PG8_MMA(1, 1, At, B1); PG8_BAR; PG8_SCHED;
;     ...
;         if constexpr (ALIGN_EPI) { if (wr == 0) PG8_BAR; }
	s_add_i32 s50, s78, s33
	v_lshl_add_u64 v[224:225], v[224:225], 0, s[42:43]
	s_mov_b32 m0, s50
	ds_read_b128 v[186:189], v153 offset:49152
	ds_read_b128 v[190:193], v153 offset:50176
	ds_read_b128 v[194:197], v153 offset:51200
	ds_read_b128 v[198:201], v153 offset:52224
	ds_read_b128 v[208:211], v153 offset:53248
	ds_read_b128 v[212:215], v153 offset:54272
	ds_read_b128 v[216:219], v153 offset:55296
	ds_read_b128 v[220:223], v153 offset:56320
	global_load_lds_dwordx4 v[224:225], off
	s_add_i32 m0, s50, 0x2000
	s_add_u32 s50, s54, 0xb0080
	v_lshl_add_u64 v[224:225], v[226:227], 0, s[42:43]
	s_addc_u32 s51, s55, 0
	s_add_i32 s54, s79, s33
	global_load_lds_dwordx4 v[224:225], off
	v_lshl_add_u64 v[224:225], s[50:51], 0, v[130:131]
	s_mov_b32 m0, s54
	s_nop 0
	global_load_lds_dwordx4 v[224:225], off
	v_lshl_add_u64 v[224:225], s[50:51], 0, v[134:135]
	s_add_i32 m0, s54, 0x2000
	s_nop 0
	global_load_lds_dwordx4 v[224:225], off
	s_waitcnt vmcnt(6)
	s_waitcnt lgkmcnt(0)
	s_barrier
	s_setprio 1
	s_waitcnt lgkmcnt(0)
	v_mfma_f32_16x16x32_bf16 v[60:63], v[144:147], v[186:189], v[60:63]
	v_mfma_f32_16x16x32_bf16 v[56:59], v[160:163], v[186:189], v[56:59]
	v_mfma_f32_16x16x32_bf16 v[40:43], v[160:163], v[194:197], v[40:43]
	v_mfma_f32_16x16x32_bf16 v[44:47], v[144:147], v[194:197], v[44:47]
	v_mfma_f32_16x16x32_bf16 v[28:31], v[144:147], v[208:211], v[28:31]
	v_mfma_f32_16x16x32_bf16 v[24:27], v[160:163], v[208:211], v[24:27]
	v_mfma_f32_16x16x32_bf16 v[8:11], v[160:163], v[216:219], v[8:11]
	v_mfma_f32_16x16x32_bf16 v[12:15], v[144:147], v[216:219], v[12:15]
	v_mfma_f32_16x16x32_bf16 v[60:63], v[156:159], v[190:193], v[60:63]
	v_mfma_f32_16x16x32_bf16 v[56:59], v[164:167], v[190:193], v[56:59]
	v_mfma_f32_16x16x32_bf16 v[40:43], v[164:167], v[198:201], v[40:43]
	v_mfma_f32_16x16x32_bf16 v[44:47], v[156:159], v[198:201], v[44:47]
	v_mfma_f32_16x16x32_bf16 v[28:31], v[156:159], v[212:215], v[28:31]
	v_mfma_f32_16x16x32_bf16 v[24:27], v[164:167], v[212:215], v[24:27]
	v_lshl_add_u64 v[224:225], v[228:229], 0, s[42:43]
	s_mov_b32 m0, s62
	s_nop 0
	global_load_lds_dwordx4 v[224:225], off
	v_mfma_f32_16x16x32_bf16 v[8:11], v[164:167], v[220:223], v[8:11]
	v_mfma_f32_16x16x32_bf16 v[12:15], v[156:159], v[220:223], v[12:15]
	s_setprio 0
	s_setprio 1
	v_mfma_f32_16x16x32_bf16 v[52:55], v[168:171], v[186:189], v[52:55]
	v_mfma_f32_16x16x32_bf16 v[48:51], v[176:179], v[186:189], v[48:51]
	v_mfma_f32_16x16x32_bf16 v[32:35], v[176:179], v[194:197], v[32:35]
	v_mfma_f32_16x16x32_bf16 v[36:39], v[168:171], v[194:197], v[36:39]
	v_mfma_f32_16x16x32_bf16 v[20:23], v[168:171], v[208:211], v[20:23]
	v_mfma_f32_16x16x32_bf16 v[16:19], v[176:179], v[208:211], v[16:19]
	v_mfma_f32_16x16x32_bf16 v[0:3], v[176:179], v[216:219], v[0:3]
	v_mfma_f32_16x16x32_bf16 v[4:7], v[168:171], v[216:219], v[4:7]
	v_mfma_f32_16x16x32_bf16 v[52:55], v[172:175], v[190:193], v[52:55]
	v_mfma_f32_16x16x32_bf16 v[48:51], v[182:185], v[190:193], v[48:51]
	v_mfma_f32_16x16x32_bf16 v[32:35], v[182:185], v[198:201], v[32:35]
	v_mfma_f32_16x16x32_bf16 v[36:39], v[172:175], v[198:201], v[36:39]
	v_mfma_f32_16x16x32_bf16 v[20:23], v[172:175], v[212:215], v[20:23]
	v_mfma_f32_16x16x32_bf16 v[16:19], v[182:185], v[212:215], v[16:19]
	v_lshl_add_u64 v[224:225], v[230:231], 0, s[42:43]
	s_mov_b32 m0, s63
	s_nop 0
	global_load_lds_dwordx4 v[224:225], off
	v_mfma_f32_16x16x32_bf16 v[0:3], v[182:185], v[220:223], v[0:3]
	v_mfma_f32_16x16x32_bf16 v[4:7], v[172:175], v[220:223], v[4:7]
	s_setprio 0
	s_barrier
	s_add_i32 s84, s84, 2
	s_add_u32 s82, s82, 0x100
	s_addc_u32 s83, s83, 0
	s_cmp_gt_u32 s84, 41
	s_mov_b64 s[50:51], s[52:53]
	s_cbranch_scc0 .LBB0_1197
	s_and_b64 vcc, exec, s[44:45]
	s_cbranch_vccz .LBB0_1200
	s_barrier

; #define PG8_STAGE(bufoff, gbase, voff) do { _Pragma("unroll") for (int _i = 0; _i < 2; ++_i) \
;         __builtin_amdgcn_global_load_lds((const unsigned*)((const char*)(gbase) + (voff)[_i]), (PG8_LAS unsigned*)(lds + (bufoff) + ldsw + _i * 8192), 16, 0, 0); } while (0)
; #define PG8_LDA(dst, b, h) do { _Pragma("unroll") for (int m = 0; m < 4; ++m) _Pragma("unroll") for (int k = 0; k < 2; ++k) dst[m][k] = *(const PG8_LAS bf16x8*)(lds + PG8_SA(b, h) + aoff + m * 2048 + k * 1024); } while (0)
; #define PG8_LDB(dst, b, h) do { _Pragma("unroll") for (int n = 0; n < 2; ++n) _Pragma("unroll") for (int k = 0; k < 2; ++k) dst[n][k] = *(const PG8_LAS bf16x8*)(lds + PG8_SB(b, h) + boff + n * 2048 + k * 1024); } while (0)
; #define PG8_MMA(ai, bj, At, Bt) do { __builtin_amdgcn_s_setprio(1); _Pragma("unroll") for (int m = 0; m < 4; ++m) _Pragma("unroll") for (int n = 0; n < 2; ++n) _Pragma("unroll") for (int k = 0; k < 2; ++k) \
;         acc[ai][bj][m][n] = __builtin_amdgcn_mfma_f32_16x16x32_bf16(Bt[n][k], At[m][k], acc[ai][bj][m][n], 0, 0, 0); __builtin_amdgcn_s_setprio(0); } while (0)
; #define PG8_BAR __builtin_amdgcn_s_barrier()
; template <class Epi, class Sched, bool ALIGN_EPI = false, bool SP2 = false>
; __device__ __forceinline__ void gemm_phase(PG8_LAS unsigned char* lds, const Gemm g, const Sched& S, const Epi& E) {
;     ...
;         const bool has_next = S.next(ui + 1, nxt);
;         const char* nA = has_next ? (const char*)g.A + (size_t)nxt.pm * tstep : cA; const char* nB = has_next ? (const char*)g.Bt + (size_t)nxt.pn * tstep : cB;
;         for (int t = 0; t < nt; t += 2) {
;             const bool last = (t == nt - 2);
;             const char* a1 = cA + (size_t)(t + 1) * kstep;
;             const char* a2 = last ? nA : cA + (size_t)(t + 2) * kstep; const char* b2 = last ? nB : cB + (size_t)(t + 2) * kstep;
;             const char* a3 = a2 + kstep; const char* b3 = b2 + kstep;
;             if (last && has_next) S.a_ready(nxt);
;             if constexpr (SP2) {
;             PG8_LDB(B0, 0, 0); PG8_LDB(B1, 0, 1); PG8_SCHED; PG8_LDA(At, 0, 0); PG8_STAGE(PG8_SA(1, 1), a1 + hstep, voffA);
;             PG8_WAIT_V(8); PG8_WAIT_L(0); PG8_BAR; PG8_MMA(0, 0, At, B0); PG8_MMA(0, 1, At, B1); PG8_BAR; PG8_SCHED;
;             PG8_LDA(At, 0, 1); PG8_STAGE(PG8_SB(0, 0), b2, voffB); PG8_STAGE(PG8_SB(0, 1), b2 + hstep, voffB); PG8_STAGE(PG8_SA(0, 0), a2, voffA);
.LBB0_1286:
	s_ashr_i32 s51, s50, 31
	s_lshl_b64 s[52:53], s[50:51], 19
	s_add_u32 s52, s22, s52
	s_addc_u32 s53, s23, s53
	s_and_b64 s[54:55], s[12:13], exec
	s_cselect_b32 s51, s53, s59
	s_cselect_b32 s61, s52, s58
	s_ashr_i32 s49, s48, 31
	s_lshl_b64 s[54:55], s[48:49], 19
	v_readlane_b32 s64, v250, 9
	v_readlane_b32 s65, v250, 10
	s_add_u32 s54, s64, s54
	s_addc_u32 s55, s65, s55
	s_and_b64 s[64:65], s[12:13], exec
	s_cselect_b32 s49, s55, s63
	s_cselect_b32 s87, s54, s62
	s_add_u32 s58, s58, 0x40080
	s_addc_u32 s59, s59, 0
	s_add_u32 s88, s62, 0x100
	s_addc_u32 s89, s63, 0
	s_mov_b32 s90, -2
	s_waitcnt lgkmcnt(0)
	ds_read_b128 v[128:131], v181
	ds_read_b128 v[160:163], v181 offset:1024
	ds_read_b128 v[164:167], v181 offset:2048
	ds_read_b128 v[168:171], v181 offset:3072
	ds_read_b128 v[172:175], v203
	ds_read_b128 v[176:179], v203 offset:1024
	ds_read_b128 v[182:185], v203 offset:2048
	ds_read_b128 v[186:189], v203 offset:3072
	s_add_u32 s62, s58, 0xfffc0080
	s_addc_u32 s63, s59, -1
	s_cmp_eq_u32 s90, 12
	s_cselect_b32 s65, s51, s63
	s_cselect_b32 s64, s61, s62
	s_cselect_b32 s63, s49, s89
	s_cselect_b32 s62, s87, s88
	v_lshl_add_u64 v[232:233], s[58:59], 0, v[152:153]
	s_add_i32 m0, s15, 0xc000
	ds_read_b128 v[190:193], v208
	ds_read_b128 v[194:197], v208 offset:1024
	ds_read_b128 v[198:201], v208 offset:2048
	ds_read_b128 v[212:215], v208 offset:3072
	ds_read_b128 v[216:219], v208 offset:4096
	ds_read_b128 v[220:223], v208 offset:5120
	ds_read_b128 v[224:227], v208 offset:6144
	ds_read_b128 v[228:231], v208 offset:7168
	global_load_lds_dwordx4 v[232:233], off
	v_lshl_add_u64 v[232:233], s[58:59], 0, v[154:155]
	s_add_i32 m0, s15, 0xe000
	s_nop 0
	global_load_lds_dwordx4 v[232:233], off
	s_waitcnt vmcnt(8)
	s_waitcnt lgkmcnt(0)
	s_barrier
	s_setprio 1
	s_waitcnt lgkmcnt(0)
	v_mfma_f32_16x16x32_bf16 v[124:127], v[128:131], v[190:193], 0
	v_mfma_f32_16x16x32_bf16 v[120:123], v[164:167], v[190:193], 0
	v_mfma_f32_16x16x32_bf16 v[112:115], v[164:167], v[198:201], 0
	v_mfma_f32_16x16x32_bf16 v[116:119], v[128:131], v[198:201], 0
	v_mfma_f32_16x16x32_bf16 v[108:111], v[128:131], v[216:219], 0
	v_mfma_f32_16x16x32_bf16 v[104:107], v[164:167], v[216:219], 0
	v_mfma_f32_16x16x32_bf16 v[96:99], v[164:167], v[224:227], 0
	v_mfma_f32_16x16x32_bf16 v[100:103], v[128:131], v[224:227], 0
	v_mfma_f32_16x16x32_bf16 v[124:127], v[160:163], v[194:197], v[124:127]
	v_mfma_f32_16x16x32_bf16 v[120:123], v[168:171], v[194:197], v[120:123]
	v_mfma_f32_16x16x32_bf16 v[112:115], v[168:171], v[212:215], v[112:115]
	v_mfma_f32_16x16x32_bf16 v[116:119], v[160:163], v[212:215], v[116:119]
	v_mfma_f32_16x16x32_bf16 v[108:111], v[160:163], v[220:223], v[108:111]
	v_mfma_f32_16x16x32_bf16 v[104:107], v[168:171], v[220:223], v[104:107]
	v_mfma_f32_16x16x32_bf16 v[96:99], v[168:171], v[228:231], v[96:99]
	v_mfma_f32_16x16x32_bf16 v[100:103], v[160:163], v[228:231], v[100:103]
	s_setprio 0
	s_setprio 1
	v_mfma_f32_16x16x32_bf16 v[60:63], v[172:175], v[190:193], 0
	v_mfma_f32_16x16x32_bf16 v[56:59], v[182:185], v[190:193], 0
	v_mfma_f32_16x16x32_bf16 v[48:51], v[182:185], v[198:201], 0
	v_mfma_f32_16x16x32_bf16 v[52:55], v[172:175], v[198:201], 0
	v_mfma_f32_16x16x32_bf16 v[44:47], v[172:175], v[216:219], 0
	v_mfma_f32_16x16x32_bf16 v[40:43], v[182:185], v[216:219], 0
	v_mfma_f32_16x16x32_bf16 v[32:35], v[182:185], v[224:227], 0
	v_mfma_f32_16x16x32_bf16 v[36:39], v[172:175], v[224:227], 0
	v_mfma_f32_16x16x32_bf16 v[60:63], v[176:179], v[194:197], v[60:63]
	v_mfma_f32_16x16x32_bf16 v[56:59], v[186:189], v[194:197], v[56:59]
	v_mfma_f32_16x16x32_bf16 v[48:51], v[186:189], v[212:215], v[48:51]
	v_mfma_f32_16x16x32_bf16 v[52:55], v[176:179], v[212:215], v[52:55]
	v_mfma_f32_16x16x32_bf16 v[44:47], v[176:179], v[220:223], v[44:47]
	v_mfma_f32_16x16x32_bf16 v[40:43], v[186:189], v[220:223], v[40:43]
	v_mfma_f32_16x16x32_bf16 v[32:35], v[186:189], v[228:231], v[32:35]
	v_mfma_f32_16x16x32_bf16 v[36:39], v[176:179], v[228:231], v[36:39]
	s_setprio 0
	s_barrier
	s_add_i32 s78, s75, s14
	v_lshl_add_u64 v[232:233], s[62:63], 0, v[134:135]
	s_mov_b32 m0, s78
	ds_read_b128 v[190:193], v208 offset:16384
	ds_read_b128 v[194:197], v208 offset:17408
	ds_read_b128 v[198:201], v208 offset:18432
	ds_read_b128 v[212:215], v208 offset:19456
	ds_read_b128 v[216:219], v208 offset:20480
	ds_read_b128 v[220:223], v208 offset:21504
	ds_read_b128 v[224:227], v208 offset:22528
	ds_read_b128 v[228:231], v208 offset:23552
	global_load_lds_dwordx4 v[232:233], off
	s_add_i32 m0, s78, 0x2000
	s_add_u32 s78, s62, 0x40000
	v_lshl_add_u64 v[234:235], s[62:63], 0, v[138:139]
	s_addc_u32 s79, s63, 0
	s_add_i32 s91, s76, s14
	global_load_lds_dwordx4 v[234:235], off
	v_lshl_add_u64 v[236:237], s[78:79], 0, v[134:135]
	s_mov_b32 m0, s91
	global_load_lds_dwordx4 v[236:237], off
	v_lshl_add_u64 v[236:237], s[78:79], 0, v[138:139]
	s_add_i32 m0, s91, 0x2000
	s_nop 0
	global_load_lds_dwordx4 v[236:237], off
	s_waitcnt vmcnt(6)
	s_waitcnt lgkmcnt(0)
	s_barrier
; #define PG8_STAGE(bufoff, gbase, voff) do { _Pragma("unroll") for (int _i = 0; _i < 2; ++_i) \
;         __builtin_amdgcn_global_load_lds((const unsigned*)((const char*)(gbase) + (voff)[_i]), (PG8_LAS unsigned*)(lds + (bufoff) + ldsw + _i * 8192), 16, 0, 0); } while (0)
; #define PG8_LDA(dst, b, h) do { _Pragma("unroll") for (int m = 0; m < 4; ++m) _Pragma("unroll") for (int k = 0; k < 2; ++k) dst[m][k] = *(const PG8_LAS bf16x8*)(lds + PG8_SA(b, h) + aoff + m * 2048 + k * 1024); } while (0)
; #define PG8_LDB(dst, b, h) do { _Pragma("unroll") for (int n = 0; n < 2; ++n) _Pragma("unroll") for (int k = 0; k < 2; ++k) dst[n][k] = *(const PG8_LAS bf16x8*)(lds + PG8_SB(b, h) + boff + n * 2048 + k * 1024); } while (0)
; #define PG8_MMA(ai, bj, At, Bt) do { __builtin_amdgcn_s_setprio(1); _Pragma("unroll") for (int m = 0; m < 4; ++m) _Pragma("unroll") for (int n = 0; n < 2; ++n) _Pragma("unroll") for (int k = 0; k < 2; ++k) \
;         acc[ai][bj][m][n] = __builtin_amdgcn_mfma_f32_16x16x32_bf16(Bt[n][k], At[m][k], acc[ai][bj][m][n], 0, 0, 0); __builtin_amdgcn_s_setprio(0); } while (0)
; #define PG8_WAIT_V(n) asm volatile("s_waitcnt vmcnt(" #n ")" ::: "memory")
; #define PG8_WAIT_L(n) asm volatile("s_waitcnt lgkmcnt(" #n ")" ::: "memory")
; #define PG8_BAR __builtin_amdgcn_s_barrier()
; #define PG8_SCHED __builtin_amdgcn_sched_barrier(0)
; template <class Epi, class Sched, bool ALIGN_EPI = false, bool SP2 = false>
; __device__ __forceinline__ void gemm_phase(PG8_LAS unsigned char* lds, const Gemm g, const Sched& S, const Epi& E) {
;     ...
;             PG8_WAIT_V(8); PG8_WAIT_L(0); PG8_BAR; PG8_MMA(1, 0, At, B0); PG8_MMA(1, 1, At, B1); PG8_BAR; PG8_SCHED;
;             PG8_LDB(B0, 1, 0); PG8_LDB(B1, 1, 1); PG8_SCHED; PG8_LDA(At, 1, 0); PG8_STAGE(PG8_SA(0, 1), a2 + hstep, voffA);
;             PG8_WAIT_V(8); PG8_WAIT_L(0); PG8_BAR; PG8_MMA(0, 0, At, B0); PG8_MMA(0, 1, At, B1); PG8_BAR; PG8_SCHED;
	s_setprio 1
	s_waitcnt lgkmcnt(0)
	v_mfma_f32_16x16x32_bf16 v[92:95], v[128:131], v[190:193], 0
	v_mfma_f32_16x16x32_bf16 v[88:91], v[164:167], v[190:193], 0
	v_mfma_f32_16x16x32_bf16 v[80:83], v[164:167], v[198:201], 0
	v_mfma_f32_16x16x32_bf16 v[84:87], v[128:131], v[198:201], 0
	v_mfma_f32_16x16x32_bf16 v[76:79], v[128:131], v[216:219], 0
	v_mfma_f32_16x16x32_bf16 v[72:75], v[164:167], v[216:219], 0
	v_mfma_f32_16x16x32_bf16 v[64:67], v[164:167], v[224:227], 0
	v_mfma_f32_16x16x32_bf16 v[68:71], v[128:131], v[224:227], 0
	v_mfma_f32_16x16x32_bf16 v[92:95], v[160:163], v[194:197], v[92:95]
	v_mfma_f32_16x16x32_bf16 v[88:91], v[168:171], v[194:197], v[88:91]
	v_mfma_f32_16x16x32_bf16 v[80:83], v[168:171], v[212:215], v[80:83]
	v_mfma_f32_16x16x32_bf16 v[84:87], v[160:163], v[212:215], v[84:87]
	v_mfma_f32_16x16x32_bf16 v[76:79], v[160:163], v[220:223], v[76:79]
	v_mfma_f32_16x16x32_bf16 v[72:75], v[168:171], v[220:223], v[72:75]
	v_lshl_add_u64 v[236:237], s[64:65], 0, v[132:133]
	s_mov_b32 m0, s15
	s_nop 0
	global_load_lds_dwordx4 v[236:237], off
	v_mfma_f32_16x16x32_bf16 v[64:67], v[168:171], v[228:231], v[64:67]
	v_mfma_f32_16x16x32_bf16 v[68:71], v[160:163], v[228:231], v[68:71]
	s_setprio 0
	s_setprio 1
	v_mfma_f32_16x16x32_bf16 v[28:31], v[172:175], v[190:193], 0
	v_mfma_f32_16x16x32_bf16 v[24:27], v[182:185], v[190:193], 0
	v_mfma_f32_16x16x32_bf16 v[16:19], v[182:185], v[198:201], 0
	v_mfma_f32_16x16x32_bf16 v[20:23], v[172:175], v[198:201], 0
	v_mfma_f32_16x16x32_bf16 v[12:15], v[172:175], v[216:219], 0
	v_mfma_f32_16x16x32_bf16 v[8:11], v[182:185], v[216:219], 0
	v_mfma_f32_16x16x32_bf16 v[0:3], v[182:185], v[224:227], 0
	v_mfma_f32_16x16x32_bf16 v[4:7], v[172:175], v[224:227], 0
	v_mfma_f32_16x16x32_bf16 v[28:31], v[176:179], v[194:197], v[28:31]
	v_mfma_f32_16x16x32_bf16 v[24:27], v[186:189], v[194:197], v[24:27]
	v_mfma_f32_16x16x32_bf16 v[16:19], v[186:189], v[212:215], v[16:19]
	v_mfma_f32_16x16x32_bf16 v[20:23], v[176:179], v[212:215], v[20:23]
	v_mfma_f32_16x16x32_bf16 v[12:15], v[176:179], v[220:223], v[12:15]
	v_mfma_f32_16x16x32_bf16 v[8:11], v[186:189], v[220:223], v[8:11]
	v_lshl_add_u64 v[238:239], s[64:65], 0, v[136:137]
	s_mov_b32 m0, s33
	s_nop 0
	global_load_lds_dwordx4 v[238:239], off
	v_mfma_f32_16x16x32_bf16 v[0:3], v[186:189], v[228:231], v[0:3]
	v_mfma_f32_16x16x32_bf16 v[4:7], v[176:179], v[228:231], v[4:7]
	s_setprio 0
	s_barrier
	s_add_i32 s78, 0, 0x18000
	v_add_u32_e32 v140, s78, v147
	s_add_i32 s79, 0, 0x1c000
	ds_read_b128 v[128:131], v140
	ds_read_b128 v[160:163], v140 offset:1024
	ds_read_b128 v[164:167], v140 offset:2048
	ds_read_b128 v[168:171], v140 offset:3072
	v_add_u32_e32 v140, s79, v147
	ds_read_b128 v[172:175], v140
	ds_read_b128 v[176:179], v140 offset:1024
	ds_read_b128 v[182:185], v140 offset:2048
	ds_read_b128 v[186:189], v140 offset:3072
	s_add_u32 s64, s64, 0x40000
	s_addc_u32 s65, s65, 0
	s_mov_b32 m0, s34
	v_lshl_add_u64 v[240:241], s[64:65], 0, v[132:133]
	ds_read_b128 v[190:193], v208 offset:32768
	ds_read_b128 v[194:197], v208 offset:33792
	ds_read_b128 v[198:201], v208 offset:34816
	ds_read_b128 v[212:215], v208 offset:35840
	ds_read_b128 v[216:219], v208 offset:36864
	ds_read_b128 v[220:223], v208 offset:37888
	ds_read_b128 v[224:227], v208 offset:38912
	ds_read_b128 v[228:231], v208 offset:39936
	global_load_lds_dwordx4 v[240:241], off
	v_lshl_add_u64 v[240:241], s[64:65], 0, v[136:137]
	s_mov_b32 m0, s57
	s_nop 0
	global_load_lds_dwordx4 v[240:241], off
	s_waitcnt vmcnt(8)
	s_waitcnt lgkmcnt(0)
	s_barrier
	s_setprio 1
	s_waitcnt lgkmcnt(0)
	v_mfma_f32_16x16x32_bf16 v[124:127], v[128:131], v[190:193], v[124:127]
	v_mfma_f32_16x16x32_bf16 v[120:123], v[164:167], v[190:193], v[120:123]
	v_mfma_f32_16x16x32_bf16 v[112:115], v[164:167], v[198:201], v[112:115]
	v_mfma_f32_16x16x32_bf16 v[116:119], v[128:131], v[198:201], v[116:119]
	v_mfma_f32_16x16x32_bf16 v[108:111], v[128:131], v[216:219], v[108:111]
	v_mfma_f32_16x16x32_bf16 v[104:107], v[164:167], v[216:219], v[104:107]
	v_mfma_f32_16x16x32_bf16 v[96:99], v[164:167], v[224:227], v[96:99]
	v_mfma_f32_16x16x32_bf16 v[100:103], v[128:131], v[224:227], v[100:103]
	v_mfma_f32_16x16x32_bf16 v[124:127], v[160:163], v[194:197], v[124:127]
	v_mfma_f32_16x16x32_bf16 v[120:123], v[168:171], v[194:197], v[120:123]
	v_mfma_f32_16x16x32_bf16 v[112:115], v[168:171], v[212:215], v[112:115]
	v_mfma_f32_16x16x32_bf16 v[116:119], v[160:163], v[212:215], v[116:119]
	v_mfma_f32_16x16x32_bf16 v[108:111], v[160:163], v[220:223], v[108:111]
	v_mfma_f32_16x16x32_bf16 v[104:107], v[168:171], v[220:223], v[104:107]
	v_mfma_f32_16x16x32_bf16 v[96:99], v[168:171], v[228:231], v[96:99]
	v_mfma_f32_16x16x32_bf16 v[100:103], v[160:163], v[228:231], v[100:103]
	s_setprio 0
	s_setprio 1
	v_mfma_f32_16x16x32_bf16 v[60:63], v[172:175], v[190:193], v[60:63]
	v_mfma_f32_16x16x32_bf16 v[56:59], v[182:185], v[190:193], v[56:59]
	v_mfma_f32_16x16x32_bf16 v[48:51], v[182:185], v[198:201], v[48:51]
	v_mfma_f32_16x16x32_bf16 v[52:55], v[172:175], v[198:201], v[52:55]
	v_mfma_f32_16x16x32_bf16 v[44:47], v[172:175], v[216:219], v[44:47]
	v_mfma_f32_16x16x32_bf16 v[40:43], v[182:185], v[216:219], v[40:43]
	v_mfma_f32_16x16x32_bf16 v[32:35], v[182:185], v[224:227], v[32:35]
	v_mfma_f32_16x16x32_bf16 v[36:39], v[172:175], v[224:227], v[36:39]
	v_mfma_f32_16x16x32_bf16 v[60:63], v[176:179], v[194:197], v[60:63]
	v_mfma_f32_16x16x32_bf16 v[56:59], v[186:189], v[194:197], v[56:59]
	v_mfma_f32_16x16x32_bf16 v[48:51], v[186:189], v[212:215], v[48:51]
	v_mfma_f32_16x16x32_bf16 v[52:55], v[176:179], v[212:215], v[52:55]
	v_mfma_f32_16x16x32_bf16 v[44:47], v[176:179], v[220:223], v[44:47]
	v_mfma_f32_16x16x32_bf16 v[40:43], v[186:189], v[220:223], v[40:43]
	v_mfma_f32_16x16x32_bf16 v[32:35], v[186:189], v[228:231], v[32:35]
	v_mfma_f32_16x16x32_bf16 v[36:39], v[176:179], v[228:231], v[36:39]
	s_setprio 0
	s_barrier
; #define PG8_STAGE(bufoff, gbase, voff) do { _Pragma("unroll") for (int _i = 0; _i < 2; ++_i) \
;         __builtin_amdgcn_global_load_lds((const unsigned*)((const char*)(gbase) + (voff)[_i]), (PG8_LAS unsigned*)(lds + (bufoff) + ldsw + _i * 8192), 16, 0, 0); } while (0)
; #define PG8_LDA(dst, b, h) do { _Pragma("unroll") for (int m = 0; m < 4; ++m) _Pragma("unroll") for (int k = 0; k < 2; ++k) dst[m][k] = *(const PG8_LAS bf16x8*)(lds + PG8_SA(b, h) + aoff + m * 2048 + k * 1024); } while (0)
; #define PG8_LDB(dst, b, h) do { _Pragma("unroll") for (int n = 0; n < 2; ++n) _Pragma("unroll") for (int k = 0; k < 2; ++k) dst[n][k] = *(const PG8_LAS bf16x8*)(lds + PG8_SB(b, h) + boff + n * 2048 + k * 1024); } while (0)
; #define PG8_MMA(ai, bj, At, Bt) do { __builtin_amdgcn_s_setprio(1); _Pragma("unroll") for (int m = 0; m < 4; ++m) _Pragma("unroll") for (int n = 0; n < 2; ++n) _Pragma("unroll") for (int k = 0; k < 2; ++k) \
;         acc[ai][bj][m][n] = __builtin_amdgcn_mfma_f32_16x16x32_bf16(Bt[n][k], At[m][k], acc[ai][bj][m][n], 0, 0, 0); __builtin_amdgcn_s_setprio(0); } while (0)
; #define PG8_WAIT_V(n) asm volatile("s_waitcnt vmcnt(" #n ")" ::: "memory")
; #define PG8_WAIT_L(n) asm volatile("s_waitcnt lgkmcnt(" #n ")" ::: "memory")
; #define PG8_BAR __builtin_amdgcn_s_barrier()
; #define PG8_SCHED __builtin_amdgcn_sched_barrier(0)
; template <class Epi, class Sched, bool ALIGN_EPI = false, bool SP2 = false>
; __device__ __forceinline__ void gemm_phase(PG8_LAS unsigned char* lds, const Gemm g, const Sched& S, const Epi& E) {
;     ...
;             PG8_LDB(B0, 0, 0); PG8_LDB(B1, 0, 1); PG8_SCHED; PG8_LDA(At, 0, 0); PG8_STAGE(PG8_SA(1, 1), a1 + hstep, voffA);
;     ...
;             PG8_LDA(At, 1, 1); PG8_STAGE(PG8_SB(1, 0), b3, voffB); PG8_STAGE(PG8_SB(1, 1), b3 + hstep, voffB); PG8_STAGE(PG8_SA(1, 0), a3, voffA);
;             PG8_WAIT_V(8); PG8_WAIT_L(0); PG8_BAR; PG8_MMA(1, 0, At, B0); PG8_MMA(1, 1, At, B1); PG8_BAR; PG8_SCHED;
	s_add_i32 s64, s78, s14
	v_lshl_add_u64 v[232:233], v[232:233], 0, s[42:43]
	s_mov_b32 m0, s64
	ds_read_b128 v[190:193], v208 offset:49152
	ds_read_b128 v[194:197], v208 offset:50176
	ds_read_b128 v[198:201], v208 offset:51200
	ds_read_b128 v[212:215], v208 offset:52224
	ds_read_b128 v[216:219], v208 offset:53248
	ds_read_b128 v[220:223], v208 offset:54272
	ds_read_b128 v[224:227], v208 offset:55296
	ds_read_b128 v[228:231], v208 offset:56320
	global_load_lds_dwordx4 v[232:233], off
	s_add_i32 m0, s64, 0x2000
	s_add_u32 s62, s62, 0x40080
	v_lshl_add_u64 v[232:233], v[234:235], 0, s[42:43]
	s_addc_u32 s63, s63, 0
	s_add_i32 s64, s79, s14
	global_load_lds_dwordx4 v[232:233], off
	v_lshl_add_u64 v[232:233], s[62:63], 0, v[134:135]
	s_mov_b32 m0, s64
	s_nop 0
	global_load_lds_dwordx4 v[232:233], off
	v_lshl_add_u64 v[232:233], s[62:63], 0, v[138:139]
	s_add_i32 m0, s64, 0x2000
	s_nop 0
	global_load_lds_dwordx4 v[232:233], off
	s_waitcnt vmcnt(6)
	s_waitcnt lgkmcnt(0)
	s_barrier
	s_setprio 1
	s_waitcnt lgkmcnt(0)
	v_mfma_f32_16x16x32_bf16 v[92:95], v[128:131], v[190:193], v[92:95]
	v_mfma_f32_16x16x32_bf16 v[88:91], v[164:167], v[190:193], v[88:91]
	v_mfma_f32_16x16x32_bf16 v[80:83], v[164:167], v[198:201], v[80:83]
	v_mfma_f32_16x16x32_bf16 v[84:87], v[128:131], v[198:201], v[84:87]
	v_mfma_f32_16x16x32_bf16 v[76:79], v[128:131], v[216:219], v[76:79]
	v_mfma_f32_16x16x32_bf16 v[72:75], v[164:167], v[216:219], v[72:75]
	v_mfma_f32_16x16x32_bf16 v[64:67], v[164:167], v[224:227], v[64:67]
	v_mfma_f32_16x16x32_bf16 v[68:71], v[128:131], v[224:227], v[68:71]
	v_mfma_f32_16x16x32_bf16 v[92:95], v[160:163], v[194:197], v[92:95]
	v_mfma_f32_16x16x32_bf16 v[88:91], v[168:171], v[194:197], v[88:91]
	v_mfma_f32_16x16x32_bf16 v[80:83], v[168:171], v[212:215], v[80:83]
	v_mfma_f32_16x16x32_bf16 v[84:87], v[160:163], v[212:215], v[84:87]
	v_mfma_f32_16x16x32_bf16 v[76:79], v[160:163], v[220:223], v[76:79]
	v_mfma_f32_16x16x32_bf16 v[72:75], v[168:171], v[220:223], v[72:75]
	v_lshl_add_u64 v[232:233], v[236:237], 0, s[42:43]
	s_mov_b32 m0, s67
	s_nop 0
	global_load_lds_dwordx4 v[232:233], off
	v_mfma_f32_16x16x32_bf16 v[64:67], v[168:171], v[228:231], v[64:67]
	v_mfma_f32_16x16x32_bf16 v[68:71], v[160:163], v[228:231], v[68:71]
	s_setprio 0
	s_setprio 1
	v_mfma_f32_16x16x32_bf16 v[28:31], v[172:175], v[190:193], v[28:31]
	v_mfma_f32_16x16x32_bf16 v[24:27], v[182:185], v[190:193], v[24:27]
	v_mfma_f32_16x16x32_bf16 v[16:19], v[182:185], v[198:201], v[16:19]
	v_mfma_f32_16x16x32_bf16 v[20:23], v[172:175], v[198:201], v[20:23]
	v_mfma_f32_16x16x32_bf16 v[12:15], v[172:175], v[216:219], v[12:15]
	v_mfma_f32_16x16x32_bf16 v[8:11], v[182:185], v[216:219], v[8:11]
	v_mfma_f32_16x16x32_bf16 v[0:3], v[182:185], v[224:227], v[0:3]
	v_mfma_f32_16x16x32_bf16 v[4:7], v[172:175], v[224:227], v[4:7]
	v_mfma_f32_16x16x32_bf16 v[28:31], v[176:179], v[194:197], v[28:31]
	v_mfma_f32_16x16x32_bf16 v[24:27], v[186:189], v[194:197], v[24:27]
	v_mfma_f32_16x16x32_bf16 v[16:19], v[186:189], v[212:215], v[16:19]
	v_mfma_f32_16x16x32_bf16 v[20:23], v[176:179], v[212:215], v[20:23]
	v_mfma_f32_16x16x32_bf16 v[12:15], v[176:179], v[220:223], v[12:15]
	v_mfma_f32_16x16x32_bf16 v[8:11], v[186:189], v[220:223], v[8:11]
	v_lshl_add_u64 v[232:233], v[238:239], 0, s[42:43]
	s_mov_b32 m0, s74
	s_nop 0
	global_load_lds_dwordx4 v[232:233], off
	v_mfma_f32_16x16x32_bf16 v[0:3], v[186:189], v[228:231], v[0:3]
	v_mfma_f32_16x16x32_bf16 v[4:7], v[176:179], v[228:231], v[4:7]
	s_setprio 0
	s_barrier
	s_add_i32 s90, s90, 2
	s_add_u32 s58, s58, 0x100
	s_addc_u32 s59, s59, 0
	s_add_u32 s88, s88, 0x100
	s_addc_u32 s89, s89, 0
.LBB0_1287:
	ds_read_b128 v[128:131], v181
	ds_read_b128 v[160:163], v181 offset:1024
	ds_read_b128 v[164:167], v181 offset:2048
	ds_read_b128 v[168:171], v181 offset:3072
	ds_read_b128 v[172:175], v203
	ds_read_b128 v[176:179], v203 offset:1024
	ds_read_b128 v[182:185], v203 offset:2048
	ds_read_b128 v[186:189], v203 offset:3072
	s_add_u32 s62, s58, 0xfffc0080
	s_addc_u32 s63, s59, -1
	s_cmp_eq_u32 s90, 12
	s_cselect_b32 s65, s51, s63
	s_cselect_b32 s64, s61, s62
	s_cselect_b32 s63, s49, s89
	s_cselect_b32 s62, s87, s88
	v_lshl_add_u64 v[232:233], s[58:59], 0, v[152:153]
	s_add_i32 m0, s15, 0xc000
	ds_read_b128 v[190:193], v208
	ds_read_b128 v[194:197], v208 offset:1024
	ds_read_b128 v[198:201], v208 offset:2048
	ds_read_b128 v[212:215], v208 offset:3072
	ds_read_b128 v[216:219], v208 offset:4096
	ds_read_b128 v[220:223], v208 offset:5120
	ds_read_b128 v[224:227], v208 offset:6144
	ds_read_b128 v[228:231], v208 offset:7168
	global_load_lds_dwordx4 v[232:233], off
	v_lshl_add_u64 v[232:233], s[58:59], 0, v[154:155]
	s_add_i32 m0, s15, 0xe000
	s_nop 0
	global_load_lds_dwordx4 v[232:233], off
	s_waitcnt vmcnt(8)
	s_waitcnt lgkmcnt(0)
	s_barrier
; #define PG8_STAGE(bufoff, gbase, voff) do { _Pragma("unroll") for (int _i = 0; _i < 2; ++_i) \
;         __builtin_amdgcn_global_load_lds((const unsigned*)((const char*)(gbase) + (voff)[_i]), (PG8_LAS unsigned*)(lds + (bufoff) + ldsw + _i * 8192), 16, 0, 0); } while (0)
; #define PG8_LDA(dst, b, h) do { _Pragma("unroll") for (int m = 0; m < 4; ++m) _Pragma("unroll") for (int k = 0; k < 2; ++k) dst[m][k] = *(const PG8_LAS bf16x8*)(lds + PG8_SA(b, h) + aoff + m * 2048 + k * 1024); } while (0)
; #define PG8_MMA(ai, bj, At, Bt) do { __builtin_amdgcn_s_setprio(1); _Pragma("unroll") for (int m = 0; m < 4; ++m) _Pragma("unroll") for (int n = 0; n < 2; ++n) _Pragma("unroll") for (int k = 0; k < 2; ++k) \
;         acc[ai][bj][m][n] = __builtin_amdgcn_mfma_f32_16x16x32_bf16(Bt[n][k], At[m][k], acc[ai][bj][m][n], 0, 0, 0); __builtin_amdgcn_s_setprio(0); } while (0)
; #define PG8_WAIT_V(n) asm volatile("s_waitcnt vmcnt(" #n ")" ::: "memory")
; #define PG8_WAIT_L(n) asm volatile("s_waitcnt lgkmcnt(" #n ")" ::: "memory")
; #define PG8_BAR __builtin_amdgcn_s_barrier()
; #define PG8_SCHED __builtin_amdgcn_sched_barrier(0)
; template <class Epi, class Sched, bool ALIGN_EPI = false, bool SP2 = false>
; __device__ __forceinline__ void gemm_phase(PG8_LAS unsigned char* lds, const Gemm g, const Sched& S, const Epi& E) {
;     ...
;             PG8_WAIT_V(8); PG8_WAIT_L(0); PG8_BAR; PG8_MMA(0, 0, At, B0); PG8_MMA(0, 1, At, B1); PG8_BAR; PG8_SCHED;
;             PG8_LDA(At, 0, 1); PG8_STAGE(PG8_SB(0, 0), b2, voffB); PG8_STAGE(PG8_SB(0, 1), b2 + hstep, voffB); PG8_STAGE(PG8_SA(0, 0), a2, voffA);
;             PG8_WAIT_V(8); PG8_WAIT_L(0); PG8_BAR; PG8_MMA(1, 0, At, B0); PG8_MMA(1, 1, At, B1); PG8_BAR; PG8_SCHED;
	s_setprio 1
	s_waitcnt lgkmcnt(0)
	v_mfma_f32_16x16x32_bf16 v[124:127], v[128:131], v[190:193], v[124:127]
	v_mfma_f32_16x16x32_bf16 v[120:123], v[164:167], v[190:193], v[120:123]
	v_mfma_f32_16x16x32_bf16 v[112:115], v[164:167], v[198:201], v[112:115]
	v_mfma_f32_16x16x32_bf16 v[116:119], v[128:131], v[198:201], v[116:119]
	v_mfma_f32_16x16x32_bf16 v[108:111], v[128:131], v[216:219], v[108:111]
	v_mfma_f32_16x16x32_bf16 v[104:107], v[164:167], v[216:219], v[104:107]
	v_mfma_f32_16x16x32_bf16 v[96:99], v[164:167], v[224:227], v[96:99]
	v_mfma_f32_16x16x32_bf16 v[100:103], v[128:131], v[224:227], v[100:103]
	v_mfma_f32_16x16x32_bf16 v[124:127], v[160:163], v[194:197], v[124:127]
	v_mfma_f32_16x16x32_bf16 v[120:123], v[168:171], v[194:197], v[120:123]
	v_mfma_f32_16x16x32_bf16 v[112:115], v[168:171], v[212:215], v[112:115]
	v_mfma_f32_16x16x32_bf16 v[116:119], v[160:163], v[212:215], v[116:119]
	v_mfma_f32_16x16x32_bf16 v[108:111], v[160:163], v[220:223], v[108:111]
	v_mfma_f32_16x16x32_bf16 v[104:107], v[168:171], v[220:223], v[104:107]
	v_mfma_f32_16x16x32_bf16 v[96:99], v[168:171], v[228:231], v[96:99]
	v_mfma_f32_16x16x32_bf16 v[100:103], v[160:163], v[228:231], v[100:103]
	s_setprio 0
	s_setprio 1
	v_mfma_f32_16x16x32_bf16 v[60:63], v[172:175], v[190:193], v[60:63]
	v_mfma_f32_16x16x32_bf16 v[56:59], v[182:185], v[190:193], v[56:59]
	v_mfma_f32_16x16x32_bf16 v[48:51], v[182:185], v[198:201], v[48:51]
	v_mfma_f32_16x16x32_bf16 v[52:55], v[172:175], v[198:201], v[52:55]
	v_mfma_f32_16x16x32_bf16 v[44:47], v[172:175], v[216:219], v[44:47]
	v_mfma_f32_16x16x32_bf16 v[40:43], v[182:185], v[216:219], v[40:43]
	v_mfma_f32_16x16x32_bf16 v[32:35], v[182:185], v[224:227], v[32:35]
	v_mfma_f32_16x16x32_bf16 v[36:39], v[172:175], v[224:227], v[36:39]
	v_mfma_f32_16x16x32_bf16 v[60:63], v[176:179], v[194:197], v[60:63]
	v_mfma_f32_16x16x32_bf16 v[56:59], v[186:189], v[194:197], v[56:59]
	v_mfma_f32_16x16x32_bf16 v[48:51], v[186:189], v[212:215], v[48:51]
	v_mfma_f32_16x16x32_bf16 v[52:55], v[176:179], v[212:215], v[52:55]
	v_mfma_f32_16x16x32_bf16 v[44:47], v[176:179], v[220:223], v[44:47]
	v_mfma_f32_16x16x32_bf16 v[40:43], v[186:189], v[220:223], v[40:43]
	v_mfma_f32_16x16x32_bf16 v[32:35], v[186:189], v[228:231], v[32:35]
	v_mfma_f32_16x16x32_bf16 v[36:39], v[176:179], v[228:231], v[36:39]
	s_setprio 0
	s_barrier
	s_add_i32 s78, s75, s14
	v_lshl_add_u64 v[232:233], s[62:63], 0, v[134:135]
	s_mov_b32 m0, s78
	ds_read_b128 v[190:193], v208 offset:16384
	ds_read_b128 v[194:197], v208 offset:17408
	ds_read_b128 v[198:201], v208 offset:18432
	ds_read_b128 v[212:215], v208 offset:19456
	ds_read_b128 v[216:219], v208 offset:20480
	ds_read_b128 v[220:223], v208 offset:21504
	ds_read_b128 v[224:227], v208 offset:22528
	ds_read_b128 v[228:231], v208 offset:23552
	global_load_lds_dwordx4 v[232:233], off
	s_add_i32 m0, s78, 0x2000
	s_add_u32 s78, s62, 0x40000
	v_lshl_add_u64 v[234:235], s[62:63], 0, v[138:139]
	s_addc_u32 s79, s63, 0
	s_add_i32 s91, s76, s14
	global_load_lds_dwordx4 v[234:235], off
	v_lshl_add_u64 v[236:237], s[78:79], 0, v[134:135]
	s_mov_b32 m0, s91
	global_load_lds_dwordx4 v[236:237], off
	v_lshl_add_u64 v[236:237], s[78:79], 0, v[138:139]
	s_add_i32 m0, s91, 0x2000
	s_nop 0
	global_load_lds_dwordx4 v[236:237], off
	s_waitcnt vmcnt(6)
	s_waitcnt lgkmcnt(0)
	s_barrier
	s_setprio 1
	s_waitcnt lgkmcnt(0)
	v_mfma_f32_16x16x32_bf16 v[92:95], v[128:131], v[190:193], v[92:95]
	v_mfma_f32_16x16x32_bf16 v[88:91], v[164:167], v[190:193], v[88:91]
	v_mfma_f32_16x16x32_bf16 v[80:83], v[164:167], v[198:201], v[80:83]
	v_mfma_f32_16x16x32_bf16 v[84:87], v[128:131], v[198:201], v[84:87]
	v_mfma_f32_16x16x32_bf16 v[76:79], v[128:131], v[216:219], v[76:79]
	v_mfma_f32_16x16x32_bf16 v[72:75], v[164:167], v[216:219], v[72:75]
	v_mfma_f32_16x16x32_bf16 v[64:67], v[164:167], v[224:227], v[64:67]
	v_mfma_f32_16x16x32_bf16 v[68:71], v[128:131], v[224:227], v[68:71]
	v_mfma_f32_16x16x32_bf16 v[92:95], v[160:163], v[194:197], v[92:95]
	v_mfma_f32_16x16x32_bf16 v[88:91], v[168:171], v[194:197], v[88:91]
	v_mfma_f32_16x16x32_bf16 v[80:83], v[168:171], v[212:215], v[80:83]
	v_mfma_f32_16x16x32_bf16 v[84:87], v[160:163], v[212:215], v[84:87]
	v_mfma_f32_16x16x32_bf16 v[76:79], v[160:163], v[220:223], v[76:79]
	v_mfma_f32_16x16x32_bf16 v[72:75], v[168:171], v[220:223], v[72:75]
	v_lshl_add_u64 v[236:237], s[64:65], 0, v[132:133]
	s_mov_b32 m0, s15
	s_nop 0
	global_load_lds_dwordx4 v[236:237], off
	v_mfma_f32_16x16x32_bf16 v[64:67], v[168:171], v[228:231], v[64:67]
	v_mfma_f32_16x16x32_bf16 v[68:71], v[160:163], v[228:231], v[68:71]
	s_setprio 0
	s_setprio 1
	v_mfma_f32_16x16x32_bf16 v[28:31], v[172:175], v[190:193], v[28:31]
	v_mfma_f32_16x16x32_bf16 v[24:27], v[182:185], v[190:193], v[24:27]
	v_mfma_f32_16x16x32_bf16 v[16:19], v[182:185], v[198:201], v[16:19]
	v_mfma_f32_16x16x32_bf16 v[20:23], v[172:175], v[198:201], v[20:23]
	v_mfma_f32_16x16x32_bf16 v[12:15], v[172:175], v[216:219], v[12:15]
	v_mfma_f32_16x16x32_bf16 v[8:11], v[182:185], v[216:219], v[8:11]
	v_mfma_f32_16x16x32_bf16 v[0:3], v[182:185], v[224:227], v[0:3]
	v_mfma_f32_16x16x32_bf16 v[4:7], v[172:175], v[224:227], v[4:7]
	v_mfma_f32_16x16x32_bf16 v[28:31], v[176:179], v[194:197], v[28:31]
	v_mfma_f32_16x16x32_bf16 v[24:27], v[186:189], v[194:197], v[24:27]
	v_mfma_f32_16x16x32_bf16 v[16:19], v[186:189], v[212:215], v[16:19]
	v_mfma_f32_16x16x32_bf16 v[20:23], v[176:179], v[212:215], v[20:23]
	v_mfma_f32_16x16x32_bf16 v[12:15], v[176:179], v[220:223], v[12:15]
	v_mfma_f32_16x16x32_bf16 v[8:11], v[186:189], v[220:223], v[8:11]
	v_lshl_add_u64 v[238:239], s[64:65], 0, v[136:137]
	s_mov_b32 m0, s33
	s_nop 0
	global_load_lds_dwordx4 v[238:239], off
	v_mfma_f32_16x16x32_bf16 v[0:3], v[186:189], v[228:231], v[0:3]
	v_mfma_f32_16x16x32_bf16 v[4:7], v[176:179], v[228:231], v[4:7]
	s_setprio 0
	s_barrier
; #define PG8_STAGE(bufoff, gbase, voff) do { _Pragma("unroll") for (int _i = 0; _i < 2; ++_i) \
;         __builtin_amdgcn_global_load_lds((const unsigned*)((const char*)(gbase) + (voff)[_i]), (PG8_LAS unsigned*)(lds + (bufoff) + ldsw + _i * 8192), 16, 0, 0); } while (0)
; #define PG8_LDA(dst, b, h) do { _Pragma("unroll") for (int m = 0; m < 4; ++m) _Pragma("unroll") for (int k = 0; k < 2; ++k) dst[m][k] = *(const PG8_LAS bf16x8*)(lds + PG8_SA(b, h) + aoff + m * 2048 + k * 1024); } while (0)
; #define PG8_LDB(dst, b, h) do { _Pragma("unroll") for (int n = 0; n < 2; ++n) _Pragma("unroll") for (int k = 0; k < 2; ++k) dst[n][k] = *(const PG8_LAS bf16x8*)(lds + PG8_SB(b, h) + boff + n * 2048 + k * 1024); } while (0)
; #define PG8_MMA(ai, bj, At, Bt) do { __builtin_amdgcn_s_setprio(1); _Pragma("unroll") for (int m = 0; m < 4; ++m) _Pragma("unroll") for (int n = 0; n < 2; ++n) _Pragma("unroll") for (int k = 0; k < 2; ++k) \
;         acc[ai][bj][m][n] = __builtin_amdgcn_mfma_f32_16x16x32_bf16(Bt[n][k], At[m][k], acc[ai][bj][m][n], 0, 0, 0); __builtin_amdgcn_s_setprio(0); } while (0)
; #define PG8_WAIT_V(n) asm volatile("s_waitcnt vmcnt(" #n ")" ::: "memory")
; #define PG8_WAIT_L(n) asm volatile("s_waitcnt lgkmcnt(" #n ")" ::: "memory")
; #define PG8_BAR __builtin_amdgcn_s_barrier()
; #define PG8_SCHED __builtin_amdgcn_sched_barrier(0)
; template <class Epi, class Sched, bool ALIGN_EPI = false, bool SP2 = false>
; __device__ __forceinline__ void gemm_phase(PG8_LAS unsigned char* lds, const Gemm g, const Sched& S, const Epi& E) {
;     ...
;             PG8_LDB(B0, 1, 0); PG8_LDB(B1, 1, 1); PG8_SCHED; PG8_LDA(At, 1, 0); PG8_STAGE(PG8_SA(0, 1), a2 + hstep, voffA);
;             PG8_WAIT_V(8); PG8_WAIT_L(0); PG8_BAR; PG8_MMA(0, 0, At, B0); PG8_MMA(0, 1, At, B1); PG8_BAR; PG8_SCHED;
	s_add_i32 s78, 0, 0x18000
	v_add_u32_e32 v140, s78, v147
	s_add_i32 s79, 0, 0x1c000
	ds_read_b128 v[128:131], v140
	ds_read_b128 v[160:163], v140 offset:1024
	ds_read_b128 v[164:167], v140 offset:2048
	ds_read_b128 v[168:171], v140 offset:3072
	v_add_u32_e32 v140, s79, v147
	ds_read_b128 v[172:175], v140
	ds_read_b128 v[176:179], v140 offset:1024
	ds_read_b128 v[182:185], v140 offset:2048
	ds_read_b128 v[186:189], v140 offset:3072
	s_add_u32 s64, s64, 0x40000
	s_addc_u32 s65, s65, 0
	s_mov_b32 m0, s34
	v_lshl_add_u64 v[240:241], s[64:65], 0, v[132:133]
	ds_read_b128 v[190:193], v208 offset:32768
	ds_read_b128 v[194:197], v208 offset:33792
	ds_read_b128 v[198:201], v208 offset:34816
	ds_read_b128 v[212:215], v208 offset:35840
	ds_read_b128 v[216:219], v208 offset:36864
	ds_read_b128 v[220:223], v208 offset:37888
	ds_read_b128 v[224:227], v208 offset:38912
	ds_read_b128 v[228:231], v208 offset:39936
	global_load_lds_dwordx4 v[240:241], off
	v_lshl_add_u64 v[240:241], s[64:65], 0, v[136:137]
	s_mov_b32 m0, s57
	s_nop 0
	global_load_lds_dwordx4 v[240:241], off
	s_waitcnt vmcnt(8)
	s_waitcnt lgkmcnt(0)
	s_barrier
	s_setprio 1
	s_waitcnt lgkmcnt(0)
	v_mfma_f32_16x16x32_bf16 v[124:127], v[128:131], v[190:193], v[124:127]
	v_mfma_f32_16x16x32_bf16 v[120:123], v[164:167], v[190:193], v[120:123]
	v_mfma_f32_16x16x32_bf16 v[112:115], v[164:167], v[198:201], v[112:115]
	v_mfma_f32_16x16x32_bf16 v[116:119], v[128:131], v[198:201], v[116:119]
	v_mfma_f32_16x16x32_bf16 v[108:111], v[128:131], v[216:219], v[108:111]
	v_mfma_f32_16x16x32_bf16 v[104:107], v[164:167], v[216:219], v[104:107]
	v_mfma_f32_16x16x32_bf16 v[96:99], v[164:167], v[224:227], v[96:99]
	v_mfma_f32_16x16x32_bf16 v[100:103], v[128:131], v[224:227], v[100:103]
	v_mfma_f32_16x16x32_bf16 v[124:127], v[160:163], v[194:197], v[124:127]
	v_mfma_f32_16x16x32_bf16 v[120:123], v[168:171], v[194:197], v[120:123]
	v_mfma_f32_16x16x32_bf16 v[112:115], v[168:171], v[212:215], v[112:115]
	v_mfma_f32_16x16x32_bf16 v[116:119], v[160:163], v[212:215], v[116:119]
	v_mfma_f32_16x16x32_bf16 v[108:111], v[160:163], v[220:223], v[108:111]
	v_mfma_f32_16x16x32_bf16 v[104:107], v[168:171], v[220:223], v[104:107]
	v_mfma_f32_16x16x32_bf16 v[96:99], v[168:171], v[228:231], v[96:99]
	v_mfma_f32_16x16x32_bf16 v[100:103], v[160:163], v[228:231], v[100:103]
	s_setprio 0
	s_setprio 1
	v_mfma_f32_16x16x32_bf16 v[60:63], v[172:175], v[190:193], v[60:63]
	v_mfma_f32_16x16x32_bf16 v[56:59], v[182:185], v[190:193], v[56:59]
	v_mfma_f32_16x16x32_bf16 v[48:51], v[182:185], v[198:201], v[48:51]
	v_mfma_f32_16x16x32_bf16 v[52:55], v[172:175], v[198:201], v[52:55]
	v_mfma_f32_16x16x32_bf16 v[44:47], v[172:175], v[216:219], v[44:47]
	v_mfma_f32_16x16x32_bf16 v[40:43], v[182:185], v[216:219], v[40:43]
	v_mfma_f32_16x16x32_bf16 v[32:35], v[182:185], v[224:227], v[32:35]
	v_mfma_f32_16x16x32_bf16 v[36:39], v[172:175], v[224:227], v[36:39]
	v_mfma_f32_16x16x32_bf16 v[60:63], v[176:179], v[194:197], v[60:63]
	v_mfma_f32_16x16x32_bf16 v[56:59], v[186:189], v[194:197], v[56:59]
	v_mfma_f32_16x16x32_bf16 v[48:51], v[186:189], v[212:215], v[48:51]
	v_mfma_f32_16x16x32_bf16 v[52:55], v[176:179], v[212:215], v[52:55]
	v_mfma_f32_16x16x32_bf16 v[44:47], v[176:179], v[220:223], v[44:47]
	v_mfma_f32_16x16x32_bf16 v[40:43], v[186:189], v[220:223], v[40:43]
	v_mfma_f32_16x16x32_bf16 v[32:35], v[186:189], v[228:231], v[32:35]
	v_mfma_f32_16x16x32_bf16 v[36:39], v[176:179], v[228:231], v[36:39]
	s_setprio 0
	s_barrier
; #define PG8_STAGE(bufoff, gbase, voff) do { _Pragma("unroll") for (int _i = 0; _i < 2; ++_i) \
;         __builtin_amdgcn_global_load_lds((const unsigned*)((const char*)(gbase) + (voff)[_i]), (PG8_LAS unsigned*)(lds + (bufoff) + ldsw + _i * 8192), 16, 0, 0); } while (0)
; #define PG8_LDA(dst, b, h) do { _Pragma("unroll") for (int m = 0; m < 4; ++m) _Pragma("unroll") for (int k = 0; k < 2; ++k) dst[m][k] = *(const PG8_LAS bf16x8*)(lds + PG8_SA(b, h) + aoff + m * 2048 + k * 1024); } while (0)
; #define PG8_MMA(ai, bj, At, Bt) do { __builtin_amdgcn_s_setprio(1); _Pragma("unroll") for (int m = 0; m < 4; ++m) _Pragma("unroll") for (int n = 0; n < 2; ++n) _Pragma("unroll") for (int k = 0; k < 2; ++k) \
;         acc[ai][bj][m][n] = __builtin_amdgcn_mfma_f32_16x16x32_bf16(Bt[n][k], At[m][k], acc[ai][bj][m][n], 0, 0, 0); __builtin_amdgcn_s_setprio(0); } while (0)
; #define PG8_WAIT_V(n) asm volatile("s_waitcnt vmcnt(" #n ")" ::: "memory")
; #define PG8_WAIT_L(n) asm volatile("s_waitcnt lgkmcnt(" #n ")" ::: "memory")
; #define PG8_BAR __builtin_amdgcn_s_barrier()
; #define PG8_SCHED __builtin_amdgcn_sched_barrier(0)
; template <class Epi, class Sched, bool ALIGN_EPI = false, bool SP2 = false>
; __device__ __forceinline__ void gemm_phase(PG8_LAS unsigned char* lds, const Gemm g, const Sched& S, const Epi& E) {
;     ...
;             PG8_LDA(At, 1, 1); PG8_STAGE(PG8_SB(1, 0), b3, voffB); PG8_STAGE(PG8_SB(1, 1), b3 + hstep, voffB); PG8_STAGE(PG8_SA(1, 0), a3, voffA);
;             PG8_WAIT_V(8); PG8_WAIT_L(0); PG8_BAR; PG8_MMA(1, 0, At, B0); PG8_MMA(1, 1, At, B1); PG8_BAR; PG8_SCHED;
;     ...
;         if constexpr (ALIGN_EPI) { if (wr == 0) PG8_BAR; }
	s_add_i32 s64, s78, s14
	v_lshl_add_u64 v[232:233], v[232:233], 0, s[42:43]
	s_mov_b32 m0, s64
	ds_read_b128 v[190:193], v208 offset:49152
	ds_read_b128 v[194:197], v208 offset:50176
	ds_read_b128 v[198:201], v208 offset:51200
	ds_read_b128 v[212:215], v208 offset:52224
	ds_read_b128 v[216:219], v208 offset:53248
	ds_read_b128 v[220:223], v208 offset:54272
	ds_read_b128 v[224:227], v208 offset:55296
	ds_read_b128 v[228:231], v208 offset:56320
	global_load_lds_dwordx4 v[232:233], off
	s_add_i32 m0, s64, 0x2000
	s_add_u32 s62, s62, 0x40080
	v_lshl_add_u64 v[232:233], v[234:235], 0, s[42:43]
	s_addc_u32 s63, s63, 0
	s_add_i32 s64, s79, s14
	global_load_lds_dwordx4 v[232:233], off
	v_lshl_add_u64 v[232:233], s[62:63], 0, v[134:135]
	s_mov_b32 m0, s64
	s_nop 0
	global_load_lds_dwordx4 v[232:233], off
	v_lshl_add_u64 v[232:233], s[62:63], 0, v[138:139]
	s_add_i32 m0, s64, 0x2000
	s_nop 0
	global_load_lds_dwordx4 v[232:233], off
	s_waitcnt vmcnt(6)
	s_waitcnt lgkmcnt(0)
	s_barrier
	s_setprio 1
	s_waitcnt lgkmcnt(0)
	v_mfma_f32_16x16x32_bf16 v[92:95], v[128:131], v[190:193], v[92:95]
	v_mfma_f32_16x16x32_bf16 v[88:91], v[164:167], v[190:193], v[88:91]
	v_mfma_f32_16x16x32_bf16 v[80:83], v[164:167], v[198:201], v[80:83]
	v_mfma_f32_16x16x32_bf16 v[84:87], v[128:131], v[198:201], v[84:87]
	v_mfma_f32_16x16x32_bf16 v[76:79], v[128:131], v[216:219], v[76:79]
	v_mfma_f32_16x16x32_bf16 v[72:75], v[164:167], v[216:219], v[72:75]
	v_mfma_f32_16x16x32_bf16 v[64:67], v[164:167], v[224:227], v[64:67]
	v_mfma_f32_16x16x32_bf16 v[68:71], v[128:131], v[224:227], v[68:71]
	v_mfma_f32_16x16x32_bf16 v[92:95], v[160:163], v[194:197], v[92:95]
	v_mfma_f32_16x16x32_bf16 v[88:91], v[168:171], v[194:197], v[88:91]
	v_mfma_f32_16x16x32_bf16 v[80:83], v[168:171], v[212:215], v[80:83]
	v_mfma_f32_16x16x32_bf16 v[84:87], v[160:163], v[212:215], v[84:87]
	v_mfma_f32_16x16x32_bf16 v[76:79], v[160:163], v[220:223], v[76:79]
	v_mfma_f32_16x16x32_bf16 v[72:75], v[168:171], v[220:223], v[72:75]
	v_lshl_add_u64 v[232:233], v[236:237], 0, s[42:43]
	s_mov_b32 m0, s67
	s_nop 0
	global_load_lds_dwordx4 v[232:233], off
	v_mfma_f32_16x16x32_bf16 v[64:67], v[168:171], v[228:231], v[64:67]
	v_mfma_f32_16x16x32_bf16 v[68:71], v[160:163], v[228:231], v[68:71]
	s_setprio 0
	s_setprio 1
	v_mfma_f32_16x16x32_bf16 v[28:31], v[172:175], v[190:193], v[28:31]
	v_mfma_f32_16x16x32_bf16 v[24:27], v[182:185], v[190:193], v[24:27]
	v_mfma_f32_16x16x32_bf16 v[16:19], v[182:185], v[198:201], v[16:19]
	v_mfma_f32_16x16x32_bf16 v[20:23], v[172:175], v[198:201], v[20:23]
	v_mfma_f32_16x16x32_bf16 v[12:15], v[172:175], v[216:219], v[12:15]
	v_mfma_f32_16x16x32_bf16 v[8:11], v[182:185], v[216:219], v[8:11]
	v_mfma_f32_16x16x32_bf16 v[0:3], v[182:185], v[224:227], v[0:3]
	v_mfma_f32_16x16x32_bf16 v[4:7], v[172:175], v[224:227], v[4:7]
	v_mfma_f32_16x16x32_bf16 v[28:31], v[176:179], v[194:197], v[28:31]
	v_mfma_f32_16x16x32_bf16 v[24:27], v[186:189], v[194:197], v[24:27]
	v_mfma_f32_16x16x32_bf16 v[16:19], v[186:189], v[212:215], v[16:19]
	v_mfma_f32_16x16x32_bf16 v[20:23], v[176:179], v[212:215], v[20:23]
	v_mfma_f32_16x16x32_bf16 v[12:15], v[176:179], v[220:223], v[12:15]
	v_mfma_f32_16x16x32_bf16 v[8:11], v[186:189], v[220:223], v[8:11]
	v_lshl_add_u64 v[232:233], v[238:239], 0, s[42:43]
	s_mov_b32 m0, s74
	s_nop 0
	global_load_lds_dwordx4 v[232:233], off
	v_mfma_f32_16x16x32_bf16 v[0:3], v[186:189], v[228:231], v[0:3]
	v_mfma_f32_16x16x32_bf16 v[4:7], v[176:179], v[228:231], v[4:7]
	s_setprio 0
	s_barrier
	s_add_i32 s90, s90, 2
	s_add_u32 s58, s58, 0x100
	s_addc_u32 s59, s59, 0
	s_add_u32 s88, s88, 0x100
	s_addc_u32 s89, s89, 0
	s_cmp_gt_u32 s90, 13
	s_cbranch_scc0 .LBB0_1287
	s_and_b64 vcc, exec, s[44:45]
	s_cbranch_vccz .LBB0_1290
	s_barrier

; #define PG8_STAGE(bufoff, gbase, voff) do { _Pragma("unroll") for (int _i = 0; _i < 2; ++_i) \
;         __builtin_amdgcn_global_load_lds((const unsigned*)((const char*)(gbase) + (voff)[_i]), (PG8_LAS unsigned*)(lds + (bufoff) + ldsw + _i * 8192), 16, 0, 0); } while (0)
; #define PG8_LDA(dst, b, h) do { _Pragma("unroll") for (int m = 0; m < 4; ++m) _Pragma("unroll") for (int k = 0; k < 2; ++k) dst[m][k] = *(const PG8_LAS bf16x8*)(lds + PG8_SA(b, h) + aoff + m * 2048 + k * 1024); } while (0)
; #define PG8_LDB(dst, b, h) do { _Pragma("unroll") for (int n = 0; n < 2; ++n) _Pragma("unroll") for (int k = 0; k < 2; ++k) dst[n][k] = *(const PG8_LAS bf16x8*)(lds + PG8_SB(b, h) + boff + n * 2048 + k * 1024); } while (0)
; #define PG8_MMA(ai, bj, At, Bt) do { __builtin_amdgcn_s_setprio(1); _Pragma("unroll") for (int m = 0; m < 4; ++m) _Pragma("unroll") for (int n = 0; n < 2; ++n) _Pragma("unroll") for (int k = 0; k < 2; ++k) \
;         acc[ai][bj][m][n] = __builtin_amdgcn_mfma_f32_16x16x32_bf16(Bt[n][k], At[m][k], acc[ai][bj][m][n], 0, 0, 0); __builtin_amdgcn_s_setprio(0); } while (0)
; #define PG8_BAR __builtin_amdgcn_s_barrier()
; template <class Epi, class Sched, bool ALIGN_EPI = false, bool SP2 = false>
; __device__ __forceinline__ void gemm_phase(PG8_LAS unsigned char* lds, const Gemm g, const Sched& S, const Epi& E) {
;     ...
;         const bool has_next = S.next(ui + 1, nxt);
;         const char* nA = has_next ? (const char*)g.A + (size_t)nxt.pm * tstep : cA; const char* nB = has_next ? (const char*)g.Bt + (size_t)nxt.pn * tstep : cB;
;         for (int t = 0; t < nt; t += 2) {
;             const bool last = (t == nt - 2);
;             const char* a1 = cA + (size_t)(t + 1) * kstep;
;             const char* a2 = last ? nA : cA + (size_t)(t + 2) * kstep; const char* b2 = last ? nB : cB + (size_t)(t + 2) * kstep;
;             const char* a3 = a2 + kstep; const char* b3 = b2 + kstep;
;             if (last && has_next) S.a_ready(nxt);
;             if constexpr (SP2) {
;             PG8_LDB(B0, 0, 0); PG8_LDB(B1, 0, 1); PG8_SCHED; PG8_LDA(At, 0, 0); PG8_STAGE(PG8_SA(1, 1), a1 + hstep, voffA);
;             PG8_WAIT_V(8); PG8_WAIT_L(0); PG8_BAR; PG8_MMA(0, 0, At, B0); PG8_MMA(0, 1, At, B1); PG8_BAR; PG8_SCHED;
;             PG8_LDA(At, 0, 1); PG8_STAGE(PG8_SB(0, 0), b2, voffB); PG8_STAGE(PG8_SB(0, 1), b2 + hstep, voffB); PG8_STAGE(PG8_SA(0, 0), a2, voffA);
.LBB0_1592:
	s_ashr_i32 s39, s38, 31
	s_lshl_b64 s[42:43], s[38:39], 19
	s_add_u32 s42, s40, s42
	s_addc_u32 s43, s41, s43
	s_and_b64 s[44:45], s[10:11], exec
	s_cselect_b32 s39, s43, s51
	s_cselect_b32 s47, s42, s50
	s_ashr_i32 s37, s36, 31
	s_lshl_b64 s[44:45], s[36:37], 19
	v_readlane_b32 s54, v250, 11
	v_readlane_b32 s55, v250, 12
	s_add_u32 s44, s54, s44
	s_addc_u32 s45, s55, s45
	s_and_b64 s[54:55], s[10:11], exec
	s_cselect_b32 s37, s45, s53
	s_cselect_b32 s64, s44, s52
	s_add_u32 s50, s50, 0x40080
	s_addc_u32 s51, s51, 0
	s_add_u32 s65, s52, 0x100
	s_addc_u32 s66, s53, 0
	s_mov_b32 s67, -2
	s_waitcnt lgkmcnt(0)
	ds_read_b128 v[146:149], v152
	ds_read_b128 v[156:159], v152 offset:1024
	ds_read_b128 v[160:163], v152 offset:2048
	ds_read_b128 v[164:167], v152 offset:3072
	ds_read_b128 v[168:171], v153
	ds_read_b128 v[172:175], v153 offset:1024
	ds_read_b128 v[180:183], v153 offset:2048
	ds_read_b128 v[184:187], v153 offset:3072
	s_add_u32 s52, s50, 0xfffc0080
	s_addc_u32 s53, s51, -1
	s_cmp_eq_u32 s67, 12
	s_cselect_b32 s55, s39, s53
	s_cselect_b32 s54, s47, s52
	s_cselect_b32 s53, s37, s66
	s_cselect_b32 s52, s64, s65
	v_lshl_add_u64 v[200:201], s[50:51], 0, v[136:137]
	s_add_i32 m0, s33, 0xc000
	ds_read_b128 v[188:191], v154
	ds_read_b128 v[192:195], v154 offset:1024
	ds_read_b128 v[196:199], v154 offset:2048
	ds_read_b128 v[206:209], v154 offset:3072
	ds_read_b128 v[210:213], v154 offset:4096
	ds_read_b128 v[214:217], v154 offset:5120
	ds_read_b128 v[218:221], v154 offset:6144
	ds_read_b128 v[222:225], v154 offset:7168
	global_load_lds_dwordx4 v[200:201], off
	v_lshl_add_u64 v[200:201], s[50:51], 0, v[138:139]
	s_add_i32 m0, s33, 0xe000
	s_nop 0
	global_load_lds_dwordx4 v[200:201], off
	s_waitcnt vmcnt(8)
	s_waitcnt lgkmcnt(0)
	s_barrier
	s_setprio 1
	s_waitcnt lgkmcnt(0)
	v_mfma_f32_16x16x32_bf16 v[124:127], v[146:149], v[188:191], 0
	v_mfma_f32_16x16x32_bf16 v[120:123], v[160:163], v[188:191], 0
	v_mfma_f32_16x16x32_bf16 v[104:107], v[160:163], v[196:199], 0
	v_mfma_f32_16x16x32_bf16 v[108:111], v[146:149], v[196:199], 0
	v_mfma_f32_16x16x32_bf16 v[92:95], v[146:149], v[210:213], 0
	v_mfma_f32_16x16x32_bf16 v[88:91], v[160:163], v[210:213], 0
	v_mfma_f32_16x16x32_bf16 v[72:75], v[160:163], v[218:221], 0
	v_mfma_f32_16x16x32_bf16 v[76:79], v[146:149], v[218:221], 0
	v_mfma_f32_16x16x32_bf16 v[124:127], v[156:159], v[192:195], v[124:127]
	v_mfma_f32_16x16x32_bf16 v[120:123], v[164:167], v[192:195], v[120:123]
	v_mfma_f32_16x16x32_bf16 v[104:107], v[164:167], v[206:209], v[104:107]
	v_mfma_f32_16x16x32_bf16 v[108:111], v[156:159], v[206:209], v[108:111]
	v_mfma_f32_16x16x32_bf16 v[92:95], v[156:159], v[214:217], v[92:95]
	v_mfma_f32_16x16x32_bf16 v[88:91], v[164:167], v[214:217], v[88:91]
	v_mfma_f32_16x16x32_bf16 v[72:75], v[164:167], v[222:225], v[72:75]
	v_mfma_f32_16x16x32_bf16 v[76:79], v[156:159], v[222:225], v[76:79]
	s_setprio 0
	s_setprio 1
	v_mfma_f32_16x16x32_bf16 v[116:119], v[168:171], v[188:191], 0
	v_mfma_f32_16x16x32_bf16 v[112:115], v[180:183], v[188:191], 0
	v_mfma_f32_16x16x32_bf16 v[96:99], v[180:183], v[196:199], 0
	v_mfma_f32_16x16x32_bf16 v[100:103], v[168:171], v[196:199], 0
	v_mfma_f32_16x16x32_bf16 v[84:87], v[168:171], v[210:213], 0
	v_mfma_f32_16x16x32_bf16 v[80:83], v[180:183], v[210:213], 0
	v_mfma_f32_16x16x32_bf16 v[64:67], v[180:183], v[218:221], 0
	v_mfma_f32_16x16x32_bf16 v[68:71], v[168:171], v[218:221], 0
	v_mfma_f32_16x16x32_bf16 v[116:119], v[172:175], v[192:195], v[116:119]
	v_mfma_f32_16x16x32_bf16 v[112:115], v[184:187], v[192:195], v[112:115]
	v_mfma_f32_16x16x32_bf16 v[96:99], v[184:187], v[206:209], v[96:99]
	v_mfma_f32_16x16x32_bf16 v[100:103], v[172:175], v[206:209], v[100:103]
	v_mfma_f32_16x16x32_bf16 v[84:87], v[172:175], v[214:217], v[84:87]
	v_mfma_f32_16x16x32_bf16 v[80:83], v[184:187], v[214:217], v[80:83]
	v_mfma_f32_16x16x32_bf16 v[64:67], v[184:187], v[222:225], v[64:67]
	v_mfma_f32_16x16x32_bf16 v[68:71], v[172:175], v[222:225], v[68:71]
	s_setprio 0
	s_barrier
	s_add_i32 s74, s60, s15
	v_lshl_add_u64 v[200:201], s[52:53], 0, v[130:131]
	s_mov_b32 m0, s74
	ds_read_b128 v[188:191], v154 offset:16384
	ds_read_b128 v[192:195], v154 offset:17408
	ds_read_b128 v[196:199], v154 offset:18432
	ds_read_b128 v[206:209], v154 offset:19456
	ds_read_b128 v[210:213], v154 offset:20480
	ds_read_b128 v[214:217], v154 offset:21504
	ds_read_b128 v[218:221], v154 offset:22528
	ds_read_b128 v[222:225], v154 offset:23552
	global_load_lds_dwordx4 v[200:201], off
	s_add_i32 m0, s74, 0x2000
	s_add_u32 s74, s52, 0x40000
	v_lshl_add_u64 v[226:227], s[52:53], 0, v[134:135]
	s_addc_u32 s75, s53, 0
	s_add_i32 s76, s61, s15
	global_load_lds_dwordx4 v[226:227], off
	v_lshl_add_u64 v[228:229], s[74:75], 0, v[130:131]
	s_mov_b32 m0, s76
	global_load_lds_dwordx4 v[228:229], off
	v_lshl_add_u64 v[228:229], s[74:75], 0, v[134:135]
	s_add_i32 m0, s76, 0x2000
	s_nop 0
	global_load_lds_dwordx4 v[228:229], off
	s_waitcnt vmcnt(6)
	s_waitcnt lgkmcnt(0)
	s_barrier
; #define PG8_STAGE(bufoff, gbase, voff) do { _Pragma("unroll") for (int _i = 0; _i < 2; ++_i) \
;         __builtin_amdgcn_global_load_lds((const unsigned*)((const char*)(gbase) + (voff)[_i]), (PG8_LAS unsigned*)(lds + (bufoff) + ldsw + _i * 8192), 16, 0, 0); } while (0)
; #define PG8_LDA(dst, b, h) do { _Pragma("unroll") for (int m = 0; m < 4; ++m) _Pragma("unroll") for (int k = 0; k < 2; ++k) dst[m][k] = *(const PG8_LAS bf16x8*)(lds + PG8_SA(b, h) + aoff + m * 2048 + k * 1024); } while (0)
; #define PG8_LDB(dst, b, h) do { _Pragma("unroll") for (int n = 0; n < 2; ++n) _Pragma("unroll") for (int k = 0; k < 2; ++k) dst[n][k] = *(const PG8_LAS bf16x8*)(lds + PG8_SB(b, h) + boff + n * 2048 + k * 1024); } while (0)
; #define PG8_MMA(ai, bj, At, Bt) do { __builtin_amdgcn_s_setprio(1); _Pragma("unroll") for (int m = 0; m < 4; ++m) _Pragma("unroll") for (int n = 0; n < 2; ++n) _Pragma("unroll") for (int k = 0; k < 2; ++k) \
;         acc[ai][bj][m][n] = __builtin_amdgcn_mfma_f32_16x16x32_bf16(Bt[n][k], At[m][k], acc[ai][bj][m][n], 0, 0, 0); __builtin_amdgcn_s_setprio(0); } while (0)
; #define PG8_WAIT_V(n) asm volatile("s_waitcnt vmcnt(" #n ")" ::: "memory")
; #define PG8_WAIT_L(n) asm volatile("s_waitcnt lgkmcnt(" #n ")" ::: "memory")
; #define PG8_BAR __builtin_amdgcn_s_barrier()
; #define PG8_SCHED __builtin_amdgcn_sched_barrier(0)
; template <class Epi, class Sched, bool ALIGN_EPI = false, bool SP2 = false>
; __device__ __forceinline__ void gemm_phase(PG8_LAS unsigned char* lds, const Gemm g, const Sched& S, const Epi& E) {
;     ...
;             PG8_WAIT_V(8); PG8_WAIT_L(0); PG8_BAR; PG8_MMA(1, 0, At, B0); PG8_MMA(1, 1, At, B1); PG8_BAR; PG8_SCHED;
;             PG8_LDB(B0, 1, 0); PG8_LDB(B1, 1, 1); PG8_SCHED; PG8_LDA(At, 1, 0); PG8_STAGE(PG8_SA(0, 1), a2 + hstep, voffA);
;             PG8_WAIT_V(8); PG8_WAIT_L(0); PG8_BAR; PG8_MMA(0, 0, At, B0); PG8_MMA(0, 1, At, B1); PG8_BAR; PG8_SCHED;
	s_setprio 1
	s_waitcnt lgkmcnt(0)
	v_mfma_f32_16x16x32_bf16 v[60:63], v[146:149], v[188:191], 0
	v_mfma_f32_16x16x32_bf16 v[56:59], v[160:163], v[188:191], 0
	v_mfma_f32_16x16x32_bf16 v[40:43], v[160:163], v[196:199], 0
	v_mfma_f32_16x16x32_bf16 v[44:47], v[146:149], v[196:199], 0
	v_mfma_f32_16x16x32_bf16 v[28:31], v[146:149], v[210:213], 0
	v_mfma_f32_16x16x32_bf16 v[24:27], v[160:163], v[210:213], 0
	v_mfma_f32_16x16x32_bf16 v[8:11], v[160:163], v[218:221], 0
	v_mfma_f32_16x16x32_bf16 v[12:15], v[146:149], v[218:221], 0
	v_mfma_f32_16x16x32_bf16 v[60:63], v[156:159], v[192:195], v[60:63]
	v_mfma_f32_16x16x32_bf16 v[56:59], v[164:167], v[192:195], v[56:59]
	v_mfma_f32_16x16x32_bf16 v[40:43], v[164:167], v[206:209], v[40:43]
	v_mfma_f32_16x16x32_bf16 v[44:47], v[156:159], v[206:209], v[44:47]
	v_mfma_f32_16x16x32_bf16 v[28:31], v[156:159], v[214:217], v[28:31]
	v_mfma_f32_16x16x32_bf16 v[24:27], v[164:167], v[214:217], v[24:27]
	v_lshl_add_u64 v[228:229], s[54:55], 0, v[128:129]
	s_mov_b32 m0, s33
	s_nop 0
	global_load_lds_dwordx4 v[228:229], off
	v_mfma_f32_16x16x32_bf16 v[8:11], v[164:167], v[222:225], v[8:11]
	v_mfma_f32_16x16x32_bf16 v[12:15], v[156:159], v[222:225], v[12:15]
	s_setprio 0
	s_setprio 1
	v_mfma_f32_16x16x32_bf16 v[52:55], v[168:171], v[188:191], 0
	v_mfma_f32_16x16x32_bf16 v[48:51], v[180:183], v[188:191], 0
	v_mfma_f32_16x16x32_bf16 v[32:35], v[180:183], v[196:199], 0
	v_mfma_f32_16x16x32_bf16 v[36:39], v[168:171], v[196:199], 0
	v_mfma_f32_16x16x32_bf16 v[20:23], v[168:171], v[210:213], 0
	v_mfma_f32_16x16x32_bf16 v[16:19], v[180:183], v[210:213], 0
	v_mfma_f32_16x16x32_bf16 v[0:3], v[180:183], v[218:221], 0
	v_mfma_f32_16x16x32_bf16 v[4:7], v[168:171], v[218:221], 0
	v_mfma_f32_16x16x32_bf16 v[52:55], v[172:175], v[192:195], v[52:55]
	v_mfma_f32_16x16x32_bf16 v[48:51], v[184:187], v[192:195], v[48:51]
	v_mfma_f32_16x16x32_bf16 v[32:35], v[184:187], v[206:209], v[32:35]
	v_mfma_f32_16x16x32_bf16 v[36:39], v[172:175], v[206:209], v[36:39]
	v_mfma_f32_16x16x32_bf16 v[20:23], v[172:175], v[214:217], v[20:23]
	v_mfma_f32_16x16x32_bf16 v[16:19], v[184:187], v[214:217], v[16:19]
	v_lshl_add_u64 v[230:231], s[54:55], 0, v[132:133]
	s_mov_b32 m0, s34
	s_nop 0
	global_load_lds_dwordx4 v[230:231], off
	v_mfma_f32_16x16x32_bf16 v[0:3], v[184:187], v[222:225], v[0:3]
	v_mfma_f32_16x16x32_bf16 v[4:7], v[172:175], v[222:225], v[4:7]
	s_setprio 0
	s_barrier
	s_add_i32 s74, 0, 0x18000
	s_add_i32 s75, 0, 0x1c000
	v_add_u32_e32 v164, s74, v150
	v_add_u32_e32 v179, s75, v150
	ds_read_b128 v[146:149], v164
	ds_read_b128 v[156:159], v164 offset:1024
	ds_read_b128 v[160:163], v164 offset:2048
	ds_read_b128 v[164:167], v164 offset:3072
	ds_read_b128 v[168:171], v179
	ds_read_b128 v[172:175], v179 offset:1024
	ds_read_b128 v[180:183], v179 offset:2048
	ds_read_b128 v[184:187], v179 offset:3072
	s_add_u32 s54, s54, 0x40000
	s_addc_u32 s55, s55, 0
	s_mov_b32 m0, s49
	v_lshl_add_u64 v[232:233], s[54:55], 0, v[128:129]
	ds_read_b128 v[188:191], v154 offset:32768
	ds_read_b128 v[192:195], v154 offset:33792
	ds_read_b128 v[196:199], v154 offset:34816
	ds_read_b128 v[206:209], v154 offset:35840
	ds_read_b128 v[210:213], v154 offset:36864
	ds_read_b128 v[214:217], v154 offset:37888
	ds_read_b128 v[218:221], v154 offset:38912
	ds_read_b128 v[222:225], v154 offset:39936
	global_load_lds_dwordx4 v[232:233], off
	v_lshl_add_u64 v[232:233], s[54:55], 0, v[132:133]
	s_mov_b32 m0, s56
	s_nop 0
	global_load_lds_dwordx4 v[232:233], off
	s_waitcnt vmcnt(8)
	s_waitcnt lgkmcnt(0)
	s_barrier
	s_setprio 1
	s_waitcnt lgkmcnt(0)
	v_mfma_f32_16x16x32_bf16 v[124:127], v[146:149], v[188:191], v[124:127]
	v_mfma_f32_16x16x32_bf16 v[120:123], v[160:163], v[188:191], v[120:123]
	v_mfma_f32_16x16x32_bf16 v[104:107], v[160:163], v[196:199], v[104:107]
	v_mfma_f32_16x16x32_bf16 v[108:111], v[146:149], v[196:199], v[108:111]
	v_mfma_f32_16x16x32_bf16 v[92:95], v[146:149], v[210:213], v[92:95]
	v_mfma_f32_16x16x32_bf16 v[88:91], v[160:163], v[210:213], v[88:91]
	v_mfma_f32_16x16x32_bf16 v[72:75], v[160:163], v[218:221], v[72:75]
	v_mfma_f32_16x16x32_bf16 v[76:79], v[146:149], v[218:221], v[76:79]
	v_mfma_f32_16x16x32_bf16 v[124:127], v[156:159], v[192:195], v[124:127]
	v_mfma_f32_16x16x32_bf16 v[120:123], v[164:167], v[192:195], v[120:123]
	v_mfma_f32_16x16x32_bf16 v[104:107], v[164:167], v[206:209], v[104:107]
	v_mfma_f32_16x16x32_bf16 v[108:111], v[156:159], v[206:209], v[108:111]
	v_mfma_f32_16x16x32_bf16 v[92:95], v[156:159], v[214:217], v[92:95]
	v_mfma_f32_16x16x32_bf16 v[88:91], v[164:167], v[214:217], v[88:91]
	v_mfma_f32_16x16x32_bf16 v[72:75], v[164:167], v[222:225], v[72:75]
	v_mfma_f32_16x16x32_bf16 v[76:79], v[156:159], v[222:225], v[76:79]
	s_setprio 0
	s_setprio 1
	v_mfma_f32_16x16x32_bf16 v[116:119], v[168:171], v[188:191], v[116:119]
	v_mfma_f32_16x16x32_bf16 v[112:115], v[180:183], v[188:191], v[112:115]
	v_mfma_f32_16x16x32_bf16 v[96:99], v[180:183], v[196:199], v[96:99]
	v_mfma_f32_16x16x32_bf16 v[100:103], v[168:171], v[196:199], v[100:103]
	v_mfma_f32_16x16x32_bf16 v[84:87], v[168:171], v[210:213], v[84:87]
	v_mfma_f32_16x16x32_bf16 v[80:83], v[180:183], v[210:213], v[80:83]
	v_mfma_f32_16x16x32_bf16 v[64:67], v[180:183], v[218:221], v[64:67]
	v_mfma_f32_16x16x32_bf16 v[68:71], v[168:171], v[218:221], v[68:71]
	v_mfma_f32_16x16x32_bf16 v[116:119], v[172:175], v[192:195], v[116:119]
	v_mfma_f32_16x16x32_bf16 v[112:115], v[184:187], v[192:195], v[112:115]
	v_mfma_f32_16x16x32_bf16 v[96:99], v[184:187], v[206:209], v[96:99]
	v_mfma_f32_16x16x32_bf16 v[100:103], v[172:175], v[206:209], v[100:103]
	v_mfma_f32_16x16x32_bf16 v[84:87], v[172:175], v[214:217], v[84:87]
	v_mfma_f32_16x16x32_bf16 v[80:83], v[184:187], v[214:217], v[80:83]
	v_mfma_f32_16x16x32_bf16 v[64:67], v[184:187], v[222:225], v[64:67]
	v_mfma_f32_16x16x32_bf16 v[68:71], v[172:175], v[222:225], v[68:71]
	s_setprio 0
	s_barrier
; #define PG8_STAGE(bufoff, gbase, voff) do { _Pragma("unroll") for (int _i = 0; _i < 2; ++_i) \
;         __builtin_amdgcn_global_load_lds((const unsigned*)((const char*)(gbase) + (voff)[_i]), (PG8_LAS unsigned*)(lds + (bufoff) + ldsw + _i * 8192), 16, 0, 0); } while (0)
; #define PG8_LDA(dst, b, h) do { _Pragma("unroll") for (int m = 0; m < 4; ++m) _Pragma("unroll") for (int k = 0; k < 2; ++k) dst[m][k] = *(const PG8_LAS bf16x8*)(lds + PG8_SA(b, h) + aoff + m * 2048 + k * 1024); } while (0)
; #define PG8_LDB(dst, b, h) do { _Pragma("unroll") for (int n = 0; n < 2; ++n) _Pragma("unroll") for (int k = 0; k < 2; ++k) dst[n][k] = *(const PG8_LAS bf16x8*)(lds + PG8_SB(b, h) + boff + n * 2048 + k * 1024); } while (0)
; #define PG8_MMA(ai, bj, At, Bt) do { __builtin_amdgcn_s_setprio(1); _Pragma("unroll") for (int m = 0; m < 4; ++m) _Pragma("unroll") for (int n = 0; n < 2; ++n) _Pragma("unroll") for (int k = 0; k < 2; ++k) \
;         acc[ai][bj][m][n] = __builtin_amdgcn_mfma_f32_16x16x32_bf16(Bt[n][k], At[m][k], acc[ai][bj][m][n], 0, 0, 0); __builtin_amdgcn_s_setprio(0); } while (0)
; #define PG8_WAIT_V(n) asm volatile("s_waitcnt vmcnt(" #n ")" ::: "memory")
; #define PG8_WAIT_L(n) asm volatile("s_waitcnt lgkmcnt(" #n ")" ::: "memory")
; #define PG8_BAR __builtin_amdgcn_s_barrier()
; #define PG8_SCHED __builtin_amdgcn_sched_barrier(0)
; template <class Epi, class Sched, bool ALIGN_EPI = false, bool SP2 = false>
; __device__ __forceinline__ void gemm_phase(PG8_LAS unsigned char* lds, const Gemm g, const Sched& S, const Epi& E) {
;     ...
;             PG8_LDB(B0, 0, 0); PG8_LDB(B1, 0, 1); PG8_SCHED; PG8_LDA(At, 0, 0); PG8_STAGE(PG8_SA(1, 1), a1 + hstep, voffA);
;     ...
;             PG8_LDA(At, 1, 1); PG8_STAGE(PG8_SB(1, 0), b3, voffB); PG8_STAGE(PG8_SB(1, 1), b3 + hstep, voffB); PG8_STAGE(PG8_SA(1, 0), a3, voffA);
;             PG8_WAIT_V(8); PG8_WAIT_L(0); PG8_BAR; PG8_MMA(1, 0, At, B0); PG8_MMA(1, 1, At, B1); PG8_BAR; PG8_SCHED;
	s_add_i32 s54, s74, s15
	v_lshl_add_u64 v[200:201], v[200:201], 0, s[26:27]
	s_mov_b32 m0, s54
	ds_read_b128 v[188:191], v154 offset:49152
	ds_read_b128 v[192:195], v154 offset:50176
	ds_read_b128 v[196:199], v154 offset:51200
	ds_read_b128 v[206:209], v154 offset:52224
	ds_read_b128 v[210:213], v154 offset:53248
	ds_read_b128 v[214:217], v154 offset:54272
	ds_read_b128 v[218:221], v154 offset:55296
	ds_read_b128 v[222:225], v154 offset:56320
	global_load_lds_dwordx4 v[200:201], off
	s_add_i32 m0, s54, 0x2000
	s_add_u32 s52, s52, 0x40080
	v_lshl_add_u64 v[200:201], v[226:227], 0, s[26:27]
	s_addc_u32 s53, s53, 0
	s_add_i32 s54, s75, s15
	global_load_lds_dwordx4 v[200:201], off
	v_lshl_add_u64 v[200:201], s[52:53], 0, v[130:131]
	s_mov_b32 m0, s54
	s_nop 0
	global_load_lds_dwordx4 v[200:201], off
	v_lshl_add_u64 v[200:201], s[52:53], 0, v[134:135]
	s_add_i32 m0, s54, 0x2000
	s_nop 0
	global_load_lds_dwordx4 v[200:201], off
	s_waitcnt vmcnt(6)
	s_waitcnt lgkmcnt(0)
	s_barrier
	s_setprio 1
	s_waitcnt lgkmcnt(0)
	v_mfma_f32_16x16x32_bf16 v[60:63], v[146:149], v[188:191], v[60:63]
	v_mfma_f32_16x16x32_bf16 v[56:59], v[160:163], v[188:191], v[56:59]
	v_mfma_f32_16x16x32_bf16 v[40:43], v[160:163], v[196:199], v[40:43]
	v_mfma_f32_16x16x32_bf16 v[44:47], v[146:149], v[196:199], v[44:47]
	v_mfma_f32_16x16x32_bf16 v[28:31], v[146:149], v[210:213], v[28:31]
	v_mfma_f32_16x16x32_bf16 v[24:27], v[160:163], v[210:213], v[24:27]
	v_mfma_f32_16x16x32_bf16 v[8:11], v[160:163], v[218:221], v[8:11]
	v_mfma_f32_16x16x32_bf16 v[12:15], v[146:149], v[218:221], v[12:15]
	v_mfma_f32_16x16x32_bf16 v[60:63], v[156:159], v[192:195], v[60:63]
	v_mfma_f32_16x16x32_bf16 v[56:59], v[164:167], v[192:195], v[56:59]
	v_mfma_f32_16x16x32_bf16 v[40:43], v[164:167], v[206:209], v[40:43]
	v_mfma_f32_16x16x32_bf16 v[44:47], v[156:159], v[206:209], v[44:47]
	v_mfma_f32_16x16x32_bf16 v[28:31], v[156:159], v[214:217], v[28:31]
	v_mfma_f32_16x16x32_bf16 v[24:27], v[164:167], v[214:217], v[24:27]
	v_lshl_add_u64 v[200:201], v[228:229], 0, s[26:27]
	s_mov_b32 m0, s58
	s_nop 0
	global_load_lds_dwordx4 v[200:201], off
	v_mfma_f32_16x16x32_bf16 v[8:11], v[164:167], v[222:225], v[8:11]
	v_mfma_f32_16x16x32_bf16 v[12:15], v[156:159], v[222:225], v[12:15]
	s_setprio 0
	s_setprio 1
	v_mfma_f32_16x16x32_bf16 v[52:55], v[168:171], v[188:191], v[52:55]
	v_mfma_f32_16x16x32_bf16 v[48:51], v[180:183], v[188:191], v[48:51]
	v_mfma_f32_16x16x32_bf16 v[32:35], v[180:183], v[196:199], v[32:35]
	v_mfma_f32_16x16x32_bf16 v[36:39], v[168:171], v[196:199], v[36:39]
	v_mfma_f32_16x16x32_bf16 v[20:23], v[168:171], v[210:213], v[20:23]
	v_mfma_f32_16x16x32_bf16 v[16:19], v[180:183], v[210:213], v[16:19]
	v_mfma_f32_16x16x32_bf16 v[0:3], v[180:183], v[218:221], v[0:3]
	v_mfma_f32_16x16x32_bf16 v[4:7], v[168:171], v[218:221], v[4:7]
	v_mfma_f32_16x16x32_bf16 v[52:55], v[172:175], v[192:195], v[52:55]
	v_mfma_f32_16x16x32_bf16 v[48:51], v[184:187], v[192:195], v[48:51]
	v_mfma_f32_16x16x32_bf16 v[32:35], v[184:187], v[206:209], v[32:35]
	v_mfma_f32_16x16x32_bf16 v[36:39], v[172:175], v[206:209], v[36:39]
	v_mfma_f32_16x16x32_bf16 v[20:23], v[172:175], v[214:217], v[20:23]
	v_mfma_f32_16x16x32_bf16 v[16:19], v[184:187], v[214:217], v[16:19]
	v_lshl_add_u64 v[200:201], v[230:231], 0, s[26:27]
	s_mov_b32 m0, s59
	s_nop 0
	global_load_lds_dwordx4 v[200:201], off
	v_mfma_f32_16x16x32_bf16 v[0:3], v[184:187], v[222:225], v[0:3]
	v_mfma_f32_16x16x32_bf16 v[4:7], v[172:175], v[222:225], v[4:7]
	s_setprio 0
	s_barrier
	s_add_i32 s67, s67, 2
	s_add_u32 s50, s50, 0x100
	s_addc_u32 s51, s51, 0
	s_add_u32 s65, s65, 0x100
	s_addc_u32 s66, s66, 0
.LBB0_1593:
	ds_read_b128 v[146:149], v152
	ds_read_b128 v[156:159], v152 offset:1024
	ds_read_b128 v[160:163], v152 offset:2048
	ds_read_b128 v[164:167], v152 offset:3072
	ds_read_b128 v[168:171], v153
	ds_read_b128 v[172:175], v153 offset:1024
	ds_read_b128 v[180:183], v153 offset:2048
	ds_read_b128 v[184:187], v153 offset:3072
	s_add_u32 s52, s50, 0xfffc0080
	s_addc_u32 s53, s51, -1
	s_cmp_eq_u32 s67, 12
	s_cselect_b32 s55, s39, s53
	s_cselect_b32 s54, s47, s52
	s_cselect_b32 s53, s37, s66
	s_cselect_b32 s52, s64, s65
	v_lshl_add_u64 v[200:201], s[50:51], 0, v[136:137]
	s_add_i32 m0, s33, 0xc000
	ds_read_b128 v[188:191], v154
	ds_read_b128 v[192:195], v154 offset:1024
	ds_read_b128 v[196:199], v154 offset:2048
	ds_read_b128 v[206:209], v154 offset:3072
	ds_read_b128 v[210:213], v154 offset:4096
	ds_read_b128 v[214:217], v154 offset:5120
	ds_read_b128 v[218:221], v154 offset:6144
	ds_read_b128 v[222:225], v154 offset:7168
	global_load_lds_dwordx4 v[200:201], off
	v_lshl_add_u64 v[200:201], s[50:51], 0, v[138:139]
	s_add_i32 m0, s33, 0xe000
	s_nop 0
	global_load_lds_dwordx4 v[200:201], off
	s_waitcnt vmcnt(8)
	s_waitcnt lgkmcnt(0)
	s_barrier
; #define PG8_STAGE(bufoff, gbase, voff) do { _Pragma("unroll") for (int _i = 0; _i < 2; ++_i) \
;         __builtin_amdgcn_global_load_lds((const unsigned*)((const char*)(gbase) + (voff)[_i]), (PG8_LAS unsigned*)(lds + (bufoff) + ldsw + _i * 8192), 16, 0, 0); } while (0)
; #define PG8_LDA(dst, b, h) do { _Pragma("unroll") for (int m = 0; m < 4; ++m) _Pragma("unroll") for (int k = 0; k < 2; ++k) dst[m][k] = *(const PG8_LAS bf16x8*)(lds + PG8_SA(b, h) + aoff + m * 2048 + k * 1024); } while (0)
; #define PG8_MMA(ai, bj, At, Bt) do { __builtin_amdgcn_s_setprio(1); _Pragma("unroll") for (int m = 0; m < 4; ++m) _Pragma("unroll") for (int n = 0; n < 2; ++n) _Pragma("unroll") for (int k = 0; k < 2; ++k) \
;         acc[ai][bj][m][n] = __builtin_amdgcn_mfma_f32_16x16x32_bf16(Bt[n][k], At[m][k], acc[ai][bj][m][n], 0, 0, 0); __builtin_amdgcn_s_setprio(0); } while (0)
; #define PG8_WAIT_V(n) asm volatile("s_waitcnt vmcnt(" #n ")" ::: "memory")
; #define PG8_WAIT_L(n) asm volatile("s_waitcnt lgkmcnt(" #n ")" ::: "memory")
; #define PG8_BAR __builtin_amdgcn_s_barrier()
; #define PG8_SCHED __builtin_amdgcn_sched_barrier(0)
; template <class Epi, class Sched, bool ALIGN_EPI = false, bool SP2 = false>
; __device__ __forceinline__ void gemm_phase(PG8_LAS unsigned char* lds, const Gemm g, const Sched& S, const Epi& E) {
;     ...
;             PG8_WAIT_V(8); PG8_WAIT_L(0); PG8_BAR; PG8_MMA(0, 0, At, B0); PG8_MMA(0, 1, At, B1); PG8_BAR; PG8_SCHED;
;             PG8_LDA(At, 0, 1); PG8_STAGE(PG8_SB(0, 0), b2, voffB); PG8_STAGE(PG8_SB(0, 1), b2 + hstep, voffB); PG8_STAGE(PG8_SA(0, 0), a2, voffA);
;             PG8_WAIT_V(8); PG8_WAIT_L(0); PG8_BAR; PG8_MMA(1, 0, At, B0); PG8_MMA(1, 1, At, B1); PG8_BAR; PG8_SCHED;
	s_setprio 1
	s_waitcnt lgkmcnt(0)
	v_mfma_f32_16x16x32_bf16 v[124:127], v[146:149], v[188:191], v[124:127]
	v_mfma_f32_16x16x32_bf16 v[120:123], v[160:163], v[188:191], v[120:123]
	v_mfma_f32_16x16x32_bf16 v[104:107], v[160:163], v[196:199], v[104:107]
	v_mfma_f32_16x16x32_bf16 v[108:111], v[146:149], v[196:199], v[108:111]
	v_mfma_f32_16x16x32_bf16 v[92:95], v[146:149], v[210:213], v[92:95]
	v_mfma_f32_16x16x32_bf16 v[88:91], v[160:163], v[210:213], v[88:91]
	v_mfma_f32_16x16x32_bf16 v[72:75], v[160:163], v[218:221], v[72:75]
	v_mfma_f32_16x16x32_bf16 v[76:79], v[146:149], v[218:221], v[76:79]
	v_mfma_f32_16x16x32_bf16 v[124:127], v[156:159], v[192:195], v[124:127]
	v_mfma_f32_16x16x32_bf16 v[120:123], v[164:167], v[192:195], v[120:123]
	v_mfma_f32_16x16x32_bf16 v[104:107], v[164:167], v[206:209], v[104:107]
	v_mfma_f32_16x16x32_bf16 v[108:111], v[156:159], v[206:209], v[108:111]
	v_mfma_f32_16x16x32_bf16 v[92:95], v[156:159], v[214:217], v[92:95]
	v_mfma_f32_16x16x32_bf16 v[88:91], v[164:167], v[214:217], v[88:91]
	v_mfma_f32_16x16x32_bf16 v[72:75], v[164:167], v[222:225], v[72:75]
	v_mfma_f32_16x16x32_bf16 v[76:79], v[156:159], v[222:225], v[76:79]
	s_setprio 0
	s_setprio 1
	v_mfma_f32_16x16x32_bf16 v[116:119], v[168:171], v[188:191], v[116:119]
	v_mfma_f32_16x16x32_bf16 v[112:115], v[180:183], v[188:191], v[112:115]
	v_mfma_f32_16x16x32_bf16 v[96:99], v[180:183], v[196:199], v[96:99]
	v_mfma_f32_16x16x32_bf16 v[100:103], v[168:171], v[196:199], v[100:103]
	v_mfma_f32_16x16x32_bf16 v[84:87], v[168:171], v[210:213], v[84:87]
	v_mfma_f32_16x16x32_bf16 v[80:83], v[180:183], v[210:213], v[80:83]
	v_mfma_f32_16x16x32_bf16 v[64:67], v[180:183], v[218:221], v[64:67]
	v_mfma_f32_16x16x32_bf16 v[68:71], v[168:171], v[218:221], v[68:71]
	v_mfma_f32_16x16x32_bf16 v[116:119], v[172:175], v[192:195], v[116:119]
	v_mfma_f32_16x16x32_bf16 v[112:115], v[184:187], v[192:195], v[112:115]
	v_mfma_f32_16x16x32_bf16 v[96:99], v[184:187], v[206:209], v[96:99]
	v_mfma_f32_16x16x32_bf16 v[100:103], v[172:175], v[206:209], v[100:103]
	v_mfma_f32_16x16x32_bf16 v[84:87], v[172:175], v[214:217], v[84:87]
	v_mfma_f32_16x16x32_bf16 v[80:83], v[184:187], v[214:217], v[80:83]
	v_mfma_f32_16x16x32_bf16 v[64:67], v[184:187], v[222:225], v[64:67]
	v_mfma_f32_16x16x32_bf16 v[68:71], v[172:175], v[222:225], v[68:71]
	s_setprio 0
	s_barrier
	s_add_i32 s74, s60, s15
	v_lshl_add_u64 v[200:201], s[52:53], 0, v[130:131]
	s_mov_b32 m0, s74
	ds_read_b128 v[188:191], v154 offset:16384
	ds_read_b128 v[192:195], v154 offset:17408
	ds_read_b128 v[196:199], v154 offset:18432
	ds_read_b128 v[206:209], v154 offset:19456
	ds_read_b128 v[210:213], v154 offset:20480
	ds_read_b128 v[214:217], v154 offset:21504
	ds_read_b128 v[218:221], v154 offset:22528
	ds_read_b128 v[222:225], v154 offset:23552
	global_load_lds_dwordx4 v[200:201], off
	s_add_i32 m0, s74, 0x2000
	s_add_u32 s74, s52, 0x40000
	v_lshl_add_u64 v[226:227], s[52:53], 0, v[134:135]
	s_addc_u32 s75, s53, 0
	s_add_i32 s76, s61, s15
	global_load_lds_dwordx4 v[226:227], off
	v_lshl_add_u64 v[228:229], s[74:75], 0, v[130:131]
	s_mov_b32 m0, s76
	global_load_lds_dwordx4 v[228:229], off
	v_lshl_add_u64 v[228:229], s[74:75], 0, v[134:135]
	s_add_i32 m0, s76, 0x2000
	s_nop 0
	global_load_lds_dwordx4 v[228:229], off
	s_waitcnt vmcnt(6)
	s_waitcnt lgkmcnt(0)
	s_barrier
	s_setprio 1
	s_waitcnt lgkmcnt(0)
	v_mfma_f32_16x16x32_bf16 v[60:63], v[146:149], v[188:191], v[60:63]
	v_mfma_f32_16x16x32_bf16 v[56:59], v[160:163], v[188:191], v[56:59]
	v_mfma_f32_16x16x32_bf16 v[40:43], v[160:163], v[196:199], v[40:43]
	v_mfma_f32_16x16x32_bf16 v[44:47], v[146:149], v[196:199], v[44:47]
	v_mfma_f32_16x16x32_bf16 v[28:31], v[146:149], v[210:213], v[28:31]
	v_mfma_f32_16x16x32_bf16 v[24:27], v[160:163], v[210:213], v[24:27]
	v_mfma_f32_16x16x32_bf16 v[8:11], v[160:163], v[218:221], v[8:11]
	v_mfma_f32_16x16x32_bf16 v[12:15], v[146:149], v[218:221], v[12:15]
	v_mfma_f32_16x16x32_bf16 v[60:63], v[156:159], v[192:195], v[60:63]
	v_mfma_f32_16x16x32_bf16 v[56:59], v[164:167], v[192:195], v[56:59]
	v_mfma_f32_16x16x32_bf16 v[40:43], v[164:167], v[206:209], v[40:43]
	v_mfma_f32_16x16x32_bf16 v[44:47], v[156:159], v[206:209], v[44:47]
	v_mfma_f32_16x16x32_bf16 v[28:31], v[156:159], v[214:217], v[28:31]
	v_mfma_f32_16x16x32_bf16 v[24:27], v[164:167], v[214:217], v[24:27]
	v_lshl_add_u64 v[228:229], s[54:55], 0, v[128:129]
	s_mov_b32 m0, s33
	s_nop 0
	global_load_lds_dwordx4 v[228:229], off
	v_mfma_f32_16x16x32_bf16 v[8:11], v[164:167], v[222:225], v[8:11]
	v_mfma_f32_16x16x32_bf16 v[12:15], v[156:159], v[222:225], v[12:15]
	s_setprio 0
	s_setprio 1
	v_mfma_f32_16x16x32_bf16 v[52:55], v[168:171], v[188:191], v[52:55]
	v_mfma_f32_16x16x32_bf16 v[48:51], v[180:183], v[188:191], v[48:51]
	v_mfma_f32_16x16x32_bf16 v[32:35], v[180:183], v[196:199], v[32:35]
	v_mfma_f32_16x16x32_bf16 v[36:39], v[168:171], v[196:199], v[36:39]
	v_mfma_f32_16x16x32_bf16 v[20:23], v[168:171], v[210:213], v[20:23]
	v_mfma_f32_16x16x32_bf16 v[16:19], v[180:183], v[210:213], v[16:19]
	v_mfma_f32_16x16x32_bf16 v[0:3], v[180:183], v[218:221], v[0:3]
	v_mfma_f32_16x16x32_bf16 v[4:7], v[168:171], v[218:221], v[4:7]
	v_mfma_f32_16x16x32_bf16 v[52:55], v[172:175], v[192:195], v[52:55]
	v_mfma_f32_16x16x32_bf16 v[48:51], v[184:187], v[192:195], v[48:51]
	v_mfma_f32_16x16x32_bf16 v[32:35], v[184:187], v[206:209], v[32:35]
	v_mfma_f32_16x16x32_bf16 v[36:39], v[172:175], v[206:209], v[36:39]
	v_mfma_f32_16x16x32_bf16 v[20:23], v[172:175], v[214:217], v[20:23]
	v_mfma_f32_16x16x32_bf16 v[16:19], v[184:187], v[214:217], v[16:19]
	v_lshl_add_u64 v[230:231], s[54:55], 0, v[132:133]
	s_mov_b32 m0, s34
	s_nop 0
	global_load_lds_dwordx4 v[230:231], off
	v_mfma_f32_16x16x32_bf16 v[0:3], v[184:187], v[222:225], v[0:3]
	v_mfma_f32_16x16x32_bf16 v[4:7], v[172:175], v[222:225], v[4:7]
	s_setprio 0
	s_barrier
; #define PG8_STAGE(bufoff, gbase, voff) do { _Pragma("unroll") for (int _i = 0; _i < 2; ++_i) \
;         __builtin_amdgcn_global_load_lds((const unsigned*)((const char*)(gbase) + (voff)[_i]), (PG8_LAS unsigned*)(lds + (bufoff) + ldsw + _i * 8192), 16, 0, 0); } while (0)
; #define PG8_LDA(dst, b, h) do { _Pragma("unroll") for (int m = 0; m < 4; ++m) _Pragma("unroll") for (int k = 0; k < 2; ++k) dst[m][k] = *(const PG8_LAS bf16x8*)(lds + PG8_SA(b, h) + aoff + m * 2048 + k * 1024); } while (0)
; #define PG8_LDB(dst, b, h) do { _Pragma("unroll") for (int n = 0; n < 2; ++n) _Pragma("unroll") for (int k = 0; k < 2; ++k) dst[n][k] = *(const PG8_LAS bf16x8*)(lds + PG8_SB(b, h) + boff + n * 2048 + k * 1024); } while (0)
; #define PG8_MMA(ai, bj, At, Bt) do { __builtin_amdgcn_s_setprio(1); _Pragma("unroll") for (int m = 0; m < 4; ++m) _Pragma("unroll") for (int n = 0; n < 2; ++n) _Pragma("unroll") for (int k = 0; k < 2; ++k) \
;         acc[ai][bj][m][n] = __builtin_amdgcn_mfma_f32_16x16x32_bf16(Bt[n][k], At[m][k], acc[ai][bj][m][n], 0, 0, 0); __builtin_amdgcn_s_setprio(0); } while (0)
; #define PG8_WAIT_V(n) asm volatile("s_waitcnt vmcnt(" #n ")" ::: "memory")
; #define PG8_WAIT_L(n) asm volatile("s_waitcnt lgkmcnt(" #n ")" ::: "memory")
; #define PG8_BAR __builtin_amdgcn_s_barrier()
; #define PG8_SCHED __builtin_amdgcn_sched_barrier(0)
; template <class Epi, class Sched, bool ALIGN_EPI = false, bool SP2 = false>
; __device__ __forceinline__ void gemm_phase(PG8_LAS unsigned char* lds, const Gemm g, const Sched& S, const Epi& E) {
;     ...
;             PG8_LDB(B0, 1, 0); PG8_LDB(B1, 1, 1); PG8_SCHED; PG8_LDA(At, 1, 0); PG8_STAGE(PG8_SA(0, 1), a2 + hstep, voffA);
;             PG8_WAIT_V(8); PG8_WAIT_L(0); PG8_BAR; PG8_MMA(0, 0, At, B0); PG8_MMA(0, 1, At, B1); PG8_BAR; PG8_SCHED;
	s_add_i32 s74, 0, 0x18000
	s_add_i32 s75, 0, 0x1c000
	v_add_u32_e32 v164, s74, v150
	v_add_u32_e32 v179, s75, v150
	ds_read_b128 v[146:149], v164
	ds_read_b128 v[156:159], v164 offset:1024
	ds_read_b128 v[160:163], v164 offset:2048
	ds_read_b128 v[164:167], v164 offset:3072
	ds_read_b128 v[168:171], v179
	ds_read_b128 v[172:175], v179 offset:1024
	ds_read_b128 v[180:183], v179 offset:2048
	ds_read_b128 v[184:187], v179 offset:3072
	s_add_u32 s54, s54, 0x40000
	s_addc_u32 s55, s55, 0
	s_mov_b32 m0, s49
	v_lshl_add_u64 v[232:233], s[54:55], 0, v[128:129]
	ds_read_b128 v[188:191], v154 offset:32768
	ds_read_b128 v[192:195], v154 offset:33792
	ds_read_b128 v[196:199], v154 offset:34816
	ds_read_b128 v[206:209], v154 offset:35840
	ds_read_b128 v[210:213], v154 offset:36864
	ds_read_b128 v[214:217], v154 offset:37888
	ds_read_b128 v[218:221], v154 offset:38912
	ds_read_b128 v[222:225], v154 offset:39936
	global_load_lds_dwordx4 v[232:233], off
	v_lshl_add_u64 v[232:233], s[54:55], 0, v[132:133]
	s_mov_b32 m0, s56
	s_nop 0
	global_load_lds_dwordx4 v[232:233], off
	s_waitcnt vmcnt(8)
	s_waitcnt lgkmcnt(0)
	s_barrier
	s_setprio 1
	s_waitcnt lgkmcnt(0)
	v_mfma_f32_16x16x32_bf16 v[124:127], v[146:149], v[188:191], v[124:127]
	v_mfma_f32_16x16x32_bf16 v[120:123], v[160:163], v[188:191], v[120:123]
	v_mfma_f32_16x16x32_bf16 v[104:107], v[160:163], v[196:199], v[104:107]
	v_mfma_f32_16x16x32_bf16 v[108:111], v[146:149], v[196:199], v[108:111]
	v_mfma_f32_16x16x32_bf16 v[92:95], v[146:149], v[210:213], v[92:95]
	v_mfma_f32_16x16x32_bf16 v[88:91], v[160:163], v[210:213], v[88:91]
	v_mfma_f32_16x16x32_bf16 v[72:75], v[160:163], v[218:221], v[72:75]
	v_mfma_f32_16x16x32_bf16 v[76:79], v[146:149], v[218:221], v[76:79]
	v_mfma_f32_16x16x32_bf16 v[124:127], v[156:159], v[192:195], v[124:127]
	v_mfma_f32_16x16x32_bf16 v[120:123], v[164:167], v[192:195], v[120:123]
	v_mfma_f32_16x16x32_bf16 v[104:107], v[164:167], v[206:209], v[104:107]
	v_mfma_f32_16x16x32_bf16 v[108:111], v[156:159], v[206:209], v[108:111]
	v_mfma_f32_16x16x32_bf16 v[92:95], v[156:159], v[214:217], v[92:95]
	v_mfma_f32_16x16x32_bf16 v[88:91], v[164:167], v[214:217], v[88:91]
	v_mfma_f32_16x16x32_bf16 v[72:75], v[164:167], v[222:225], v[72:75]
	v_mfma_f32_16x16x32_bf16 v[76:79], v[156:159], v[222:225], v[76:79]
	s_setprio 0
	s_setprio 1
	v_mfma_f32_16x16x32_bf16 v[116:119], v[168:171], v[188:191], v[116:119]
	v_mfma_f32_16x16x32_bf16 v[112:115], v[180:183], v[188:191], v[112:115]
	v_mfma_f32_16x16x32_bf16 v[96:99], v[180:183], v[196:199], v[96:99]
	v_mfma_f32_16x16x32_bf16 v[100:103], v[168:171], v[196:199], v[100:103]
	v_mfma_f32_16x16x32_bf16 v[84:87], v[168:171], v[210:213], v[84:87]
	v_mfma_f32_16x16x32_bf16 v[80:83], v[180:183], v[210:213], v[80:83]
	v_mfma_f32_16x16x32_bf16 v[64:67], v[180:183], v[218:221], v[64:67]
	v_mfma_f32_16x16x32_bf16 v[68:71], v[168:171], v[218:221], v[68:71]
	v_mfma_f32_16x16x32_bf16 v[116:119], v[172:175], v[192:195], v[116:119]
	v_mfma_f32_16x16x32_bf16 v[112:115], v[184:187], v[192:195], v[112:115]
	v_mfma_f32_16x16x32_bf16 v[96:99], v[184:187], v[206:209], v[96:99]
	v_mfma_f32_16x16x32_bf16 v[100:103], v[172:175], v[206:209], v[100:103]
	v_mfma_f32_16x16x32_bf16 v[84:87], v[172:175], v[214:217], v[84:87]
	v_mfma_f32_16x16x32_bf16 v[80:83], v[184:187], v[214:217], v[80:83]
	v_mfma_f32_16x16x32_bf16 v[64:67], v[184:187], v[222:225], v[64:67]
	v_mfma_f32_16x16x32_bf16 v[68:71], v[172:175], v[222:225], v[68:71]
	s_setprio 0
	s_barrier
; #define PG8_STAGE(bufoff, gbase, voff) do { _Pragma("unroll") for (int _i = 0; _i < 2; ++_i) \
;         __builtin_amdgcn_global_load_lds((const unsigned*)((const char*)(gbase) + (voff)[_i]), (PG8_LAS unsigned*)(lds + (bufoff) + ldsw + _i * 8192), 16, 0, 0); } while (0)
; #define PG8_LDA(dst, b, h) do { _Pragma("unroll") for (int m = 0; m < 4; ++m) _Pragma("unroll") for (int k = 0; k < 2; ++k) dst[m][k] = *(const PG8_LAS bf16x8*)(lds + PG8_SA(b, h) + aoff + m * 2048 + k * 1024); } while (0)
; #define PG8_MMA(ai, bj, At, Bt) do { __builtin_amdgcn_s_setprio(1); _Pragma("unroll") for (int m = 0; m < 4; ++m) _Pragma("unroll") for (int n = 0; n < 2; ++n) _Pragma("unroll") for (int k = 0; k < 2; ++k) \
;         acc[ai][bj][m][n] = __builtin_amdgcn_mfma_f32_16x16x32_bf16(Bt[n][k], At[m][k], acc[ai][bj][m][n], 0, 0, 0); __builtin_amdgcn_s_setprio(0); } while (0)
; #define PG8_WAIT_V(n) asm volatile("s_waitcnt vmcnt(" #n ")" ::: "memory")
; #define PG8_WAIT_L(n) asm volatile("s_waitcnt lgkmcnt(" #n ")" ::: "memory")
; #define PG8_BAR __builtin_amdgcn_s_barrier()
; #define PG8_SCHED __builtin_amdgcn_sched_barrier(0)
; template <class Epi, class Sched, bool ALIGN_EPI = false, bool SP2 = false>
; __device__ __forceinline__ void gemm_phase(PG8_LAS unsigned char* lds, const Gemm g, const Sched& S, const Epi& E) {
;     ...
;             PG8_LDA(At, 1, 1); PG8_STAGE(PG8_SB(1, 0), b3, voffB); PG8_STAGE(PG8_SB(1, 1), b3 + hstep, voffB); PG8_STAGE(PG8_SA(1, 0), a3, voffA);
;             PG8_WAIT_V(8); PG8_WAIT_L(0); PG8_BAR; PG8_MMA(1, 0, At, B0); PG8_MMA(1, 1, At, B1); PG8_BAR; PG8_SCHED;
;     ...
;         if constexpr (ALIGN_EPI) { if (wr == 0) PG8_BAR; }
	s_add_i32 s54, s74, s15
	v_lshl_add_u64 v[200:201], v[200:201], 0, s[26:27]
	s_mov_b32 m0, s54
	ds_read_b128 v[188:191], v154 offset:49152
	ds_read_b128 v[192:195], v154 offset:50176
	ds_read_b128 v[196:199], v154 offset:51200
	ds_read_b128 v[206:209], v154 offset:52224
	ds_read_b128 v[210:213], v154 offset:53248
	ds_read_b128 v[214:217], v154 offset:54272
	ds_read_b128 v[218:221], v154 offset:55296
	ds_read_b128 v[222:225], v154 offset:56320
	global_load_lds_dwordx4 v[200:201], off
	s_add_i32 m0, s54, 0x2000
	s_add_u32 s52, s52, 0x40080
	v_lshl_add_u64 v[200:201], v[226:227], 0, s[26:27]
	s_addc_u32 s53, s53, 0
	s_add_i32 s54, s75, s15
	global_load_lds_dwordx4 v[200:201], off
	v_lshl_add_u64 v[200:201], s[52:53], 0, v[130:131]
	s_mov_b32 m0, s54
	s_nop 0
	global_load_lds_dwordx4 v[200:201], off
	v_lshl_add_u64 v[200:201], s[52:53], 0, v[134:135]
	s_add_i32 m0, s54, 0x2000
	s_nop 0
	global_load_lds_dwordx4 v[200:201], off
	s_waitcnt vmcnt(6)
	s_waitcnt lgkmcnt(0)
	s_barrier
	s_setprio 1
	s_waitcnt lgkmcnt(0)
	v_mfma_f32_16x16x32_bf16 v[60:63], v[146:149], v[188:191], v[60:63]
	v_mfma_f32_16x16x32_bf16 v[56:59], v[160:163], v[188:191], v[56:59]
	v_mfma_f32_16x16x32_bf16 v[40:43], v[160:163], v[196:199], v[40:43]
	v_mfma_f32_16x16x32_bf16 v[44:47], v[146:149], v[196:199], v[44:47]
	v_mfma_f32_16x16x32_bf16 v[28:31], v[146:149], v[210:213], v[28:31]
	v_mfma_f32_16x16x32_bf16 v[24:27], v[160:163], v[210:213], v[24:27]
	v_mfma_f32_16x16x32_bf16 v[8:11], v[160:163], v[218:221], v[8:11]
	v_mfma_f32_16x16x32_bf16 v[12:15], v[146:149], v[218:221], v[12:15]
	v_mfma_f32_16x16x32_bf16 v[60:63], v[156:159], v[192:195], v[60:63]
	v_mfma_f32_16x16x32_bf16 v[56:59], v[164:167], v[192:195], v[56:59]
	v_mfma_f32_16x16x32_bf16 v[40:43], v[164:167], v[206:209], v[40:43]
	v_mfma_f32_16x16x32_bf16 v[44:47], v[156:159], v[206:209], v[44:47]
	v_mfma_f32_16x16x32_bf16 v[28:31], v[156:159], v[214:217], v[28:31]
	v_mfma_f32_16x16x32_bf16 v[24:27], v[164:167], v[214:217], v[24:27]
	v_lshl_add_u64 v[200:201], v[228:229], 0, s[26:27]
	s_mov_b32 m0, s58
	s_nop 0
	global_load_lds_dwordx4 v[200:201], off
	v_mfma_f32_16x16x32_bf16 v[8:11], v[164:167], v[222:225], v[8:11]
	v_mfma_f32_16x16x32_bf16 v[12:15], v[156:159], v[222:225], v[12:15]
	s_setprio 0
	s_setprio 1
	v_mfma_f32_16x16x32_bf16 v[52:55], v[168:171], v[188:191], v[52:55]
	v_mfma_f32_16x16x32_bf16 v[48:51], v[180:183], v[188:191], v[48:51]
	v_mfma_f32_16x16x32_bf16 v[32:35], v[180:183], v[196:199], v[32:35]
	v_mfma_f32_16x16x32_bf16 v[36:39], v[168:171], v[196:199], v[36:39]
	v_mfma_f32_16x16x32_bf16 v[20:23], v[168:171], v[210:213], v[20:23]
	v_mfma_f32_16x16x32_bf16 v[16:19], v[180:183], v[210:213], v[16:19]
	v_mfma_f32_16x16x32_bf16 v[0:3], v[180:183], v[218:221], v[0:3]
	v_mfma_f32_16x16x32_bf16 v[4:7], v[168:171], v[218:221], v[4:7]
	v_mfma_f32_16x16x32_bf16 v[52:55], v[172:175], v[192:195], v[52:55]
	v_mfma_f32_16x16x32_bf16 v[48:51], v[184:187], v[192:195], v[48:51]
	v_mfma_f32_16x16x32_bf16 v[32:35], v[184:187], v[206:209], v[32:35]
	v_mfma_f32_16x16x32_bf16 v[36:39], v[172:175], v[206:209], v[36:39]
	v_mfma_f32_16x16x32_bf16 v[20:23], v[172:175], v[214:217], v[20:23]
	v_mfma_f32_16x16x32_bf16 v[16:19], v[184:187], v[214:217], v[16:19]
	v_lshl_add_u64 v[200:201], v[230:231], 0, s[26:27]
	s_mov_b32 m0, s59
	s_nop 0
	global_load_lds_dwordx4 v[200:201], off
	v_mfma_f32_16x16x32_bf16 v[0:3], v[184:187], v[222:225], v[0:3]
	v_mfma_f32_16x16x32_bf16 v[4:7], v[172:175], v[222:225], v[4:7]
	s_setprio 0
	s_barrier
	s_add_i32 s67, s67, 2
	s_add_u32 s50, s50, 0x100
	s_addc_u32 s51, s51, 0
	s_add_u32 s65, s65, 0x100
	s_addc_u32 s66, s66, 0
	s_cmp_gt_u32 s67, 13
	s_cbranch_scc0 .LBB0_1593
	s_and_b64 vcc, exec, s[28:29]
	s_cbranch_vccz .LBB0_1596
	s_barrier

; #define PG8_STAGE(bufoff, gbase, voff) do { _Pragma("unroll") for (int _i = 0; _i < 2; ++_i) \
;         __builtin_amdgcn_global_load_lds((const unsigned*)((const char*)(gbase) + (voff)[_i]), (PG8_LAS unsigned*)(lds + (bufoff) + ldsw + _i * 8192), 16, 0, 0); } while (0)
; #define PG8_LDA(dst, b, h) do { _Pragma("unroll") for (int m = 0; m < 4; ++m) _Pragma("unroll") for (int k = 0; k < 2; ++k) dst[m][k] = *(const PG8_LAS bf16x8*)(lds + PG8_SA(b, h) + aoff + m * 2048 + k * 1024); } while (0)
; #define PG8_LDB(dst, b, h) do { _Pragma("unroll") for (int n = 0; n < 2; ++n) _Pragma("unroll") for (int k = 0; k < 2; ++k) dst[n][k] = *(const PG8_LAS bf16x8*)(lds + PG8_SB(b, h) + boff + n * 2048 + k * 1024); } while (0)
; #define PG8_WAIT_V(n) asm volatile("s_waitcnt vmcnt(" #n ")" ::: "memory")
; #define PG8_WAIT_L(n) asm volatile("s_waitcnt lgkmcnt(" #n ")" ::: "memory")
; #define PG8_BAR __builtin_amdgcn_s_barrier()
; #define PG8_SCHED __builtin_amdgcn_sched_barrier(0)
; template <class Epi, class Sched, bool ALIGN_EPI = false, bool SP2 = false>
; __device__ __forceinline__ void gemm_phase(PG8_LAS unsigned char* lds, const Gemm g, const Sched& S, const Epi& E) {
;     ...
;         const bool has_next = S.next(ui + 1, nxt);
;         const char* nA = has_next ? (const char*)g.A + (size_t)nxt.pm * tstep : cA; const char* nB = has_next ? (const char*)g.Bt + (size_t)nxt.pn * tstep : cB;
;         for (int t = 0; t < nt; t += 2) {
;             const bool last = (t == nt - 2);
;             const char* a1 = cA + (size_t)(t + 1) * kstep;
;             const char* a2 = last ? nA : cA + (size_t)(t + 2) * kstep; const char* b2 = last ? nB : cB + (size_t)(t + 2) * kstep;
;             const char* a3 = a2 + kstep; const char* b3 = b2 + kstep;
;             if (last && has_next) S.a_ready(nxt);
;             if constexpr (SP2) {
;             PG8_LDB(B0, 0, 0); PG8_LDB(B1, 0, 1); PG8_SCHED; PG8_LDA(At, 0, 0); PG8_STAGE(PG8_SA(1, 1), a1 + hstep, voffA);
;             PG8_WAIT_V(8); PG8_WAIT_L(0); PG8_BAR; PG8_MMA(0, 0, At, B0); PG8_MMA(0, 1, At, B1); PG8_BAR; PG8_SCHED;
;             PG8_LDA(At, 0, 1); PG8_STAGE(PG8_SB(0, 0), b2, voffB); PG8_STAGE(PG8_SB(0, 1), b2 + hstep, voffB); PG8_STAGE(PG8_SA(0, 0), a2, voffA);
;             PG8_WAIT_V(8); PG8_WAIT_L(0); PG8_BAR; PG8_MMA(1, 0, At, B0); PG8_MMA(1, 1, At, B1); PG8_BAR; PG8_SCHED;
.LBB0_1680:
	s_ashr_i32 s47, s46, 31
	s_lshl_b64 s[48:49], s[46:47], 19
	s_add_u32 s48, s22, s48
	s_addc_u32 s49, s23, s49
	s_and_b64 s[50:51], s[4:5], exec
	s_cselect_b32 s47, s49, s53
	s_cselect_b32 s77, s48, s52
	s_ashr_i32 s45, s44, 31
	s_lshl_b64 s[50:51], s[44:45], 19
	s_add_u32 s50, s15, s50
	s_addc_u32 s51, s33, s51
	s_and_b64 s[56:57], s[4:5], exec
	s_cselect_b32 s45, s51, s55
	s_cselect_b32 s78, s50, s54
	s_add_u32 s52, s52, 0x40080
	s_addc_u32 s53, s53, 0
	s_add_u32 s79, s54, 0x100
	s_addc_u32 s80, s55, 0
	s_mov_b32 s81, -2
	ds_read_b128 v[146:149], v152
	ds_read_b128 v[156:159], v152 offset:1024
	ds_read_b128 v[160:163], v152 offset:2048
	ds_read_b128 v[164:167], v152 offset:3072
	ds_read_b128 v[168:171], v153
	ds_read_b128 v[172:175], v153 offset:1024
	ds_read_b128 v[180:183], v153 offset:2048
	ds_read_b128 v[184:187], v153 offset:3072
	s_add_u32 s54, s52, 0xfffc0080
	s_addc_u32 s55, s53, -1
	s_cmp_eq_u32 s81, 12
	s_cselect_b32 s57, s47, s55
	s_cselect_b32 s56, s77, s54
	s_cselect_b32 s55, s45, s80
	s_cselect_b32 s54, s78, s79
	v_lshl_add_u64 v[200:201], s[52:53], 0, v[136:137]
	s_add_i32 m0, s58, 0xc000
	ds_read_b128 v[188:191], v154
	ds_read_b128 v[192:195], v154 offset:1024
	ds_read_b128 v[196:199], v154 offset:2048
	ds_read_b128 v[206:209], v154 offset:3072
	ds_read_b128 v[210:213], v154 offset:4096
	ds_read_b128 v[214:217], v154 offset:5120
	ds_read_b128 v[218:221], v154 offset:6144
	ds_read_b128 v[222:225], v154 offset:7168
	global_load_lds_dwordx4 v[200:201], off
	v_lshl_add_u64 v[200:201], s[52:53], 0, v[138:139]
	s_add_i32 m0, s58, 0xe000
	s_nop 0
	global_load_lds_dwordx4 v[200:201], off
	s_waitcnt vmcnt(8)
	s_waitcnt lgkmcnt(0)
	s_barrier
	s_setprio 1
	s_waitcnt lgkmcnt(0)
	v_mfma_f32_16x16x32_bf16 v[124:127], v[146:149], v[188:191], 0
	v_mfma_f32_16x16x32_bf16 v[120:123], v[160:163], v[188:191], 0
	v_mfma_f32_16x16x32_bf16 v[104:107], v[160:163], v[196:199], 0
	v_mfma_f32_16x16x32_bf16 v[108:111], v[146:149], v[196:199], 0
	v_mfma_f32_16x16x32_bf16 v[92:95], v[146:149], v[210:213], 0
	v_mfma_f32_16x16x32_bf16 v[88:91], v[160:163], v[210:213], 0
	v_mfma_f32_16x16x32_bf16 v[72:75], v[160:163], v[218:221], 0
	v_mfma_f32_16x16x32_bf16 v[76:79], v[146:149], v[218:221], 0
	v_mfma_f32_16x16x32_bf16 v[124:127], v[156:159], v[192:195], v[124:127]
	v_mfma_f32_16x16x32_bf16 v[120:123], v[164:167], v[192:195], v[120:123]
	v_mfma_f32_16x16x32_bf16 v[104:107], v[164:167], v[206:209], v[104:107]
	v_mfma_f32_16x16x32_bf16 v[108:111], v[156:159], v[206:209], v[108:111]
	v_mfma_f32_16x16x32_bf16 v[92:95], v[156:159], v[214:217], v[92:95]
	v_mfma_f32_16x16x32_bf16 v[88:91], v[164:167], v[214:217], v[88:91]
	v_mfma_f32_16x16x32_bf16 v[72:75], v[164:167], v[222:225], v[72:75]
	v_mfma_f32_16x16x32_bf16 v[76:79], v[156:159], v[222:225], v[76:79]
	s_setprio 0
	s_setprio 1
	v_mfma_f32_16x16x32_bf16 v[116:119], v[168:171], v[188:191], 0
	v_mfma_f32_16x16x32_bf16 v[112:115], v[180:183], v[188:191], 0
	v_mfma_f32_16x16x32_bf16 v[96:99], v[180:183], v[196:199], 0
	v_mfma_f32_16x16x32_bf16 v[100:103], v[168:171], v[196:199], 0
	v_mfma_f32_16x16x32_bf16 v[84:87], v[168:171], v[210:213], 0
	v_mfma_f32_16x16x32_bf16 v[80:83], v[180:183], v[210:213], 0
	v_mfma_f32_16x16x32_bf16 v[64:67], v[180:183], v[218:221], 0
	v_mfma_f32_16x16x32_bf16 v[68:71], v[168:171], v[218:221], 0
	v_mfma_f32_16x16x32_bf16 v[116:119], v[172:175], v[192:195], v[116:119]
	v_mfma_f32_16x16x32_bf16 v[112:115], v[184:187], v[192:195], v[112:115]
	v_mfma_f32_16x16x32_bf16 v[96:99], v[184:187], v[206:209], v[96:99]
	v_mfma_f32_16x16x32_bf16 v[100:103], v[172:175], v[206:209], v[100:103]
	v_mfma_f32_16x16x32_bf16 v[84:87], v[172:175], v[214:217], v[84:87]
	v_mfma_f32_16x16x32_bf16 v[80:83], v[184:187], v[214:217], v[80:83]
	v_mfma_f32_16x16x32_bf16 v[64:67], v[184:187], v[222:225], v[64:67]
	v_mfma_f32_16x16x32_bf16 v[68:71], v[172:175], v[222:225], v[68:71]
	s_setprio 0
	s_barrier
	s_add_i32 s82, s65, s34
	v_lshl_add_u64 v[200:201], s[54:55], 0, v[132:133]
	s_mov_b32 m0, s82
	ds_read_b128 v[188:191], v154 offset:16384
	ds_read_b128 v[192:195], v154 offset:17408
	ds_read_b128 v[196:199], v154 offset:18432
	ds_read_b128 v[206:209], v154 offset:19456
	ds_read_b128 v[210:213], v154 offset:20480
	ds_read_b128 v[214:217], v154 offset:21504
	ds_read_b128 v[218:221], v154 offset:22528
	ds_read_b128 v[222:225], v154 offset:23552
	global_load_lds_dwordx4 v[200:201], off
	s_add_i32 m0, s82, 0x2000
	s_add_u32 s82, s54, 0x40000
	v_lshl_add_u64 v[226:227], s[54:55], 0, v[128:129]
	s_addc_u32 s83, s55, 0
	s_add_i32 s84, s66, s34
	global_load_lds_dwordx4 v[226:227], off
	v_lshl_add_u64 v[228:229], s[82:83], 0, v[132:133]
	s_mov_b32 m0, s84
	global_load_lds_dwordx4 v[228:229], off
	v_lshl_add_u64 v[228:229], s[82:83], 0, v[128:129]
	s_add_i32 m0, s84, 0x2000
	s_nop 0
	global_load_lds_dwordx4 v[228:229], off
	s_waitcnt vmcnt(6)
	s_waitcnt lgkmcnt(0)
	s_barrier
; #define PG8_STAGE(bufoff, gbase, voff) do { _Pragma("unroll") for (int _i = 0; _i < 2; ++_i) \
;         __builtin_amdgcn_global_load_lds((const unsigned*)((const char*)(gbase) + (voff)[_i]), (PG8_LAS unsigned*)(lds + (bufoff) + ldsw + _i * 8192), 16, 0, 0); } while (0)
; #define PG8_LDA(dst, b, h) do { _Pragma("unroll") for (int m = 0; m < 4; ++m) _Pragma("unroll") for (int k = 0; k < 2; ++k) dst[m][k] = *(const PG8_LAS bf16x8*)(lds + PG8_SA(b, h) + aoff + m * 2048 + k * 1024); } while (0)
; #define PG8_LDB(dst, b, h) do { _Pragma("unroll") for (int n = 0; n < 2; ++n) _Pragma("unroll") for (int k = 0; k < 2; ++k) dst[n][k] = *(const PG8_LAS bf16x8*)(lds + PG8_SB(b, h) + boff + n * 2048 + k * 1024); } while (0)
; #define PG8_MMA(ai, bj, At, Bt) do { __builtin_amdgcn_s_setprio(1); _Pragma("unroll") for (int m = 0; m < 4; ++m) _Pragma("unroll") for (int n = 0; n < 2; ++n) _Pragma("unroll") for (int k = 0; k < 2; ++k) \
;         acc[ai][bj][m][n] = __builtin_amdgcn_mfma_f32_16x16x32_bf16(Bt[n][k], At[m][k], acc[ai][bj][m][n], 0, 0, 0); __builtin_amdgcn_s_setprio(0); } while (0)
; #define PG8_WAIT_V(n) asm volatile("s_waitcnt vmcnt(" #n ")" ::: "memory")
; #define PG8_WAIT_L(n) asm volatile("s_waitcnt lgkmcnt(" #n ")" ::: "memory")
; #define PG8_BAR __builtin_amdgcn_s_barrier()
; #define PG8_SCHED __builtin_amdgcn_sched_barrier(0)
; template <class Epi, class Sched, bool ALIGN_EPI = false, bool SP2 = false>
; __device__ __forceinline__ void gemm_phase(PG8_LAS unsigned char* lds, const Gemm g, const Sched& S, const Epi& E) {
;     ...
;             PG8_LDA(At, 0, 1); PG8_STAGE(PG8_SB(0, 0), b2, voffB); PG8_STAGE(PG8_SB(0, 1), b2 + hstep, voffB); PG8_STAGE(PG8_SA(0, 0), a2, voffA);
;             PG8_WAIT_V(8); PG8_WAIT_L(0); PG8_BAR; PG8_MMA(1, 0, At, B0); PG8_MMA(1, 1, At, B1); PG8_BAR; PG8_SCHED;
;             PG8_LDB(B0, 1, 0); PG8_LDB(B1, 1, 1); PG8_SCHED; PG8_LDA(At, 1, 0); PG8_STAGE(PG8_SA(0, 1), a2 + hstep, voffA);
;             PG8_WAIT_V(8); PG8_WAIT_L(0); PG8_BAR; PG8_MMA(0, 0, At, B0); PG8_MMA(0, 1, At, B1); PG8_BAR; PG8_SCHED;
	s_setprio 1
	s_waitcnt lgkmcnt(0)
	v_mfma_f32_16x16x32_bf16 v[60:63], v[146:149], v[188:191], 0
	v_mfma_f32_16x16x32_bf16 v[56:59], v[160:163], v[188:191], 0
	v_mfma_f32_16x16x32_bf16 v[40:43], v[160:163], v[196:199], 0
	v_mfma_f32_16x16x32_bf16 v[44:47], v[146:149], v[196:199], 0
	v_mfma_f32_16x16x32_bf16 v[28:31], v[146:149], v[210:213], 0
	v_mfma_f32_16x16x32_bf16 v[24:27], v[160:163], v[210:213], 0
	v_mfma_f32_16x16x32_bf16 v[8:11], v[160:163], v[218:221], 0
	v_mfma_f32_16x16x32_bf16 v[12:15], v[146:149], v[218:221], 0
	v_mfma_f32_16x16x32_bf16 v[60:63], v[156:159], v[192:195], v[60:63]
	v_mfma_f32_16x16x32_bf16 v[56:59], v[164:167], v[192:195], v[56:59]
	v_mfma_f32_16x16x32_bf16 v[40:43], v[164:167], v[206:209], v[40:43]
	v_mfma_f32_16x16x32_bf16 v[44:47], v[156:159], v[206:209], v[44:47]
	v_mfma_f32_16x16x32_bf16 v[28:31], v[156:159], v[214:217], v[28:31]
	v_mfma_f32_16x16x32_bf16 v[24:27], v[164:167], v[214:217], v[24:27]
	v_lshl_add_u64 v[228:229], s[56:57], 0, v[134:135]
	s_mov_b32 m0, s58
	s_nop 0
	global_load_lds_dwordx4 v[228:229], off
	v_mfma_f32_16x16x32_bf16 v[8:11], v[164:167], v[222:225], v[8:11]
	v_mfma_f32_16x16x32_bf16 v[12:15], v[156:159], v[222:225], v[12:15]
	s_setprio 0
	s_setprio 1
	v_mfma_f32_16x16x32_bf16 v[52:55], v[168:171], v[188:191], 0
	v_mfma_f32_16x16x32_bf16 v[48:51], v[180:183], v[188:191], 0
	v_mfma_f32_16x16x32_bf16 v[32:35], v[180:183], v[196:199], 0
	v_mfma_f32_16x16x32_bf16 v[36:39], v[168:171], v[196:199], 0
	v_mfma_f32_16x16x32_bf16 v[20:23], v[168:171], v[210:213], 0
	v_mfma_f32_16x16x32_bf16 v[16:19], v[180:183], v[210:213], 0
	v_mfma_f32_16x16x32_bf16 v[0:3], v[180:183], v[218:221], 0
	v_mfma_f32_16x16x32_bf16 v[4:7], v[168:171], v[218:221], 0
	v_mfma_f32_16x16x32_bf16 v[52:55], v[172:175], v[192:195], v[52:55]
	v_mfma_f32_16x16x32_bf16 v[48:51], v[184:187], v[192:195], v[48:51]
	v_mfma_f32_16x16x32_bf16 v[32:35], v[184:187], v[206:209], v[32:35]
	v_mfma_f32_16x16x32_bf16 v[36:39], v[172:175], v[206:209], v[36:39]
	v_mfma_f32_16x16x32_bf16 v[20:23], v[172:175], v[214:217], v[20:23]
	v_mfma_f32_16x16x32_bf16 v[16:19], v[184:187], v[214:217], v[16:19]
	v_lshl_add_u64 v[230:231], s[56:57], 0, v[130:131]
	s_mov_b32 m0, s59
	s_nop 0
	global_load_lds_dwordx4 v[230:231], off
	v_mfma_f32_16x16x32_bf16 v[0:3], v[184:187], v[222:225], v[0:3]
	v_mfma_f32_16x16x32_bf16 v[4:7], v[172:175], v[222:225], v[4:7]
	s_setprio 0
	s_barrier
	s_add_i32 s82, 0, 0x18000
	s_add_i32 s83, 0, 0x1c000
	v_add_u32_e32 v164, s82, v150
	v_add_u32_e32 v179, s83, v150
	ds_read_b128 v[146:149], v164
	ds_read_b128 v[156:159], v164 offset:1024
	ds_read_b128 v[160:163], v164 offset:2048
	ds_read_b128 v[164:167], v164 offset:3072
	ds_read_b128 v[168:171], v179
	ds_read_b128 v[172:175], v179 offset:1024
	ds_read_b128 v[180:183], v179 offset:2048
	ds_read_b128 v[184:187], v179 offset:3072
	s_add_u32 s56, s56, 0x40000
	s_addc_u32 s57, s57, 0
	s_mov_b32 m0, s60
	v_lshl_add_u64 v[232:233], s[56:57], 0, v[134:135]
	ds_read_b128 v[188:191], v154 offset:32768
	ds_read_b128 v[192:195], v154 offset:33792
	ds_read_b128 v[196:199], v154 offset:34816
	ds_read_b128 v[206:209], v154 offset:35840
	ds_read_b128 v[210:213], v154 offset:36864
	ds_read_b128 v[214:217], v154 offset:37888
	ds_read_b128 v[218:221], v154 offset:38912
	ds_read_b128 v[222:225], v154 offset:39936
	global_load_lds_dwordx4 v[232:233], off
	v_lshl_add_u64 v[232:233], s[56:57], 0, v[130:131]
	s_mov_b32 m0, s61
	s_nop 0
	global_load_lds_dwordx4 v[232:233], off
	s_waitcnt vmcnt(8)
	s_waitcnt lgkmcnt(0)
	s_barrier
	s_setprio 1
	s_waitcnt lgkmcnt(0)
	v_mfma_f32_16x16x32_bf16 v[124:127], v[146:149], v[188:191], v[124:127]
	v_mfma_f32_16x16x32_bf16 v[120:123], v[160:163], v[188:191], v[120:123]
	v_mfma_f32_16x16x32_bf16 v[104:107], v[160:163], v[196:199], v[104:107]
	v_mfma_f32_16x16x32_bf16 v[108:111], v[146:149], v[196:199], v[108:111]
	v_mfma_f32_16x16x32_bf16 v[92:95], v[146:149], v[210:213], v[92:95]
	v_mfma_f32_16x16x32_bf16 v[88:91], v[160:163], v[210:213], v[88:91]
	v_mfma_f32_16x16x32_bf16 v[72:75], v[160:163], v[218:221], v[72:75]
	v_mfma_f32_16x16x32_bf16 v[76:79], v[146:149], v[218:221], v[76:79]
	v_mfma_f32_16x16x32_bf16 v[124:127], v[156:159], v[192:195], v[124:127]
	v_mfma_f32_16x16x32_bf16 v[120:123], v[164:167], v[192:195], v[120:123]
	v_mfma_f32_16x16x32_bf16 v[104:107], v[164:167], v[206:209], v[104:107]
	v_mfma_f32_16x16x32_bf16 v[108:111], v[156:159], v[206:209], v[108:111]
	v_mfma_f32_16x16x32_bf16 v[92:95], v[156:159], v[214:217], v[92:95]
	v_mfma_f32_16x16x32_bf16 v[88:91], v[164:167], v[214:217], v[88:91]
	v_mfma_f32_16x16x32_bf16 v[72:75], v[164:167], v[222:225], v[72:75]
	v_mfma_f32_16x16x32_bf16 v[76:79], v[156:159], v[222:225], v[76:79]
	s_setprio 0
	s_setprio 1
	v_mfma_f32_16x16x32_bf16 v[116:119], v[168:171], v[188:191], v[116:119]
	v_mfma_f32_16x16x32_bf16 v[112:115], v[180:183], v[188:191], v[112:115]
	v_mfma_f32_16x16x32_bf16 v[96:99], v[180:183], v[196:199], v[96:99]
	v_mfma_f32_16x16x32_bf16 v[100:103], v[168:171], v[196:199], v[100:103]
	v_mfma_f32_16x16x32_bf16 v[84:87], v[168:171], v[210:213], v[84:87]
	v_mfma_f32_16x16x32_bf16 v[80:83], v[180:183], v[210:213], v[80:83]
	v_mfma_f32_16x16x32_bf16 v[64:67], v[180:183], v[218:221], v[64:67]
	v_mfma_f32_16x16x32_bf16 v[68:71], v[168:171], v[218:221], v[68:71]
	v_mfma_f32_16x16x32_bf16 v[116:119], v[172:175], v[192:195], v[116:119]
	v_mfma_f32_16x16x32_bf16 v[112:115], v[184:187], v[192:195], v[112:115]
	v_mfma_f32_16x16x32_bf16 v[96:99], v[184:187], v[206:209], v[96:99]
	v_mfma_f32_16x16x32_bf16 v[100:103], v[172:175], v[206:209], v[100:103]
	v_mfma_f32_16x16x32_bf16 v[84:87], v[172:175], v[214:217], v[84:87]
	v_mfma_f32_16x16x32_bf16 v[80:83], v[184:187], v[214:217], v[80:83]
	v_mfma_f32_16x16x32_bf16 v[64:67], v[184:187], v[222:225], v[64:67]
	v_mfma_f32_16x16x32_bf16 v[68:71], v[172:175], v[222:225], v[68:71]
	s_setprio 0
	s_barrier
; #define PG8_STAGE(bufoff, gbase, voff) do { _Pragma("unroll") for (int _i = 0; _i < 2; ++_i) \
;         __builtin_amdgcn_global_load_lds((const unsigned*)((const char*)(gbase) + (voff)[_i]), (PG8_LAS unsigned*)(lds + (bufoff) + ldsw + _i * 8192), 16, 0, 0); } while (0)
; #define PG8_LDA(dst, b, h) do { _Pragma("unroll") for (int m = 0; m < 4; ++m) _Pragma("unroll") for (int k = 0; k < 2; ++k) dst[m][k] = *(const PG8_LAS bf16x8*)(lds + PG8_SA(b, h) + aoff + m * 2048 + k * 1024); } while (0)
; #define PG8_LDB(dst, b, h) do { _Pragma("unroll") for (int n = 0; n < 2; ++n) _Pragma("unroll") for (int k = 0; k < 2; ++k) dst[n][k] = *(const PG8_LAS bf16x8*)(lds + PG8_SB(b, h) + boff + n * 2048 + k * 1024); } while (0)
; #define PG8_WAIT_V(n) asm volatile("s_waitcnt vmcnt(" #n ")" ::: "memory")
; #define PG8_WAIT_L(n) asm volatile("s_waitcnt lgkmcnt(" #n ")" ::: "memory")
; #define PG8_BAR __builtin_amdgcn_s_barrier()
; #define PG8_SCHED __builtin_amdgcn_sched_barrier(0)
; template <class Epi, class Sched, bool ALIGN_EPI = false, bool SP2 = false>
; __device__ __forceinline__ void gemm_phase(PG8_LAS unsigned char* lds, const Gemm g, const Sched& S, const Epi& E) {
;     ...
;             PG8_LDB(B0, 0, 0); PG8_LDB(B1, 0, 1); PG8_SCHED; PG8_LDA(At, 0, 0); PG8_STAGE(PG8_SA(1, 1), a1 + hstep, voffA);
;             PG8_WAIT_V(8); PG8_WAIT_L(0); PG8_BAR; PG8_MMA(0, 0, At, B0); PG8_MMA(0, 1, At, B1); PG8_BAR; PG8_SCHED;
;             PG8_LDA(At, 0, 1); PG8_STAGE(PG8_SB(0, 0), b2, voffB); PG8_STAGE(PG8_SB(0, 1), b2 + hstep, voffB); PG8_STAGE(PG8_SA(0, 0), a2, voffA);
;             PG8_WAIT_V(8); PG8_WAIT_L(0); PG8_BAR; PG8_MMA(1, 0, At, B0); PG8_MMA(1, 1, At, B1); PG8_BAR; PG8_SCHED;
;             PG8_LDB(B0, 1, 0); PG8_LDB(B1, 1, 1); PG8_SCHED; PG8_LDA(At, 1, 0); PG8_STAGE(PG8_SA(0, 1), a2 + hstep, voffA);
;             PG8_WAIT_V(8); PG8_WAIT_L(0); PG8_BAR; PG8_MMA(0, 0, At, B0); PG8_MMA(0, 1, At, B1); PG8_BAR; PG8_SCHED;
;             PG8_LDA(At, 1, 1); PG8_STAGE(PG8_SB(1, 0), b3, voffB); PG8_STAGE(PG8_SB(1, 1), b3 + hstep, voffB); PG8_STAGE(PG8_SA(1, 0), a3, voffA);
;             PG8_WAIT_V(8); PG8_WAIT_L(0); PG8_BAR; PG8_MMA(1, 0, At, B0); PG8_MMA(1, 1, At, B1); PG8_BAR; PG8_SCHED;
;             } else {
;             PG8_LDB(B0, 0, 0); PG8_SCHED; PG8_LDA(At, 0, 0); PG8_STAGE(PG8_SA(1, 1), a1 + hstep, voffA);
	s_add_i32 s56, s82, s34
	v_lshl_add_u64 v[200:201], v[200:201], 0, s[26:27]
	s_mov_b32 m0, s56
	ds_read_b128 v[188:191], v154 offset:49152
	ds_read_b128 v[192:195], v154 offset:50176
	ds_read_b128 v[196:199], v154 offset:51200
	ds_read_b128 v[206:209], v154 offset:52224
	ds_read_b128 v[210:213], v154 offset:53248
	ds_read_b128 v[214:217], v154 offset:54272
	ds_read_b128 v[218:221], v154 offset:55296
	ds_read_b128 v[222:225], v154 offset:56320
	global_load_lds_dwordx4 v[200:201], off
	s_add_i32 m0, s56, 0x2000
	s_add_u32 s54, s54, 0x40080
	v_lshl_add_u64 v[200:201], v[226:227], 0, s[26:27]
	s_addc_u32 s55, s55, 0
	s_add_i32 s56, s83, s34
	global_load_lds_dwordx4 v[200:201], off
	v_lshl_add_u64 v[200:201], s[54:55], 0, v[132:133]
	s_mov_b32 m0, s56
	s_nop 0
	global_load_lds_dwordx4 v[200:201], off
	v_lshl_add_u64 v[200:201], s[54:55], 0, v[128:129]
	s_add_i32 m0, s56, 0x2000
	s_nop 0
	global_load_lds_dwordx4 v[200:201], off
	s_waitcnt vmcnt(6)
	s_waitcnt lgkmcnt(0)
	s_barrier
	s_setprio 1
	s_waitcnt lgkmcnt(0)
	v_mfma_f32_16x16x32_bf16 v[60:63], v[146:149], v[188:191], v[60:63]
	v_mfma_f32_16x16x32_bf16 v[56:59], v[160:163], v[188:191], v[56:59]
	v_mfma_f32_16x16x32_bf16 v[40:43], v[160:163], v[196:199], v[40:43]
	v_mfma_f32_16x16x32_bf16 v[44:47], v[146:149], v[196:199], v[44:47]
	v_mfma_f32_16x16x32_bf16 v[28:31], v[146:149], v[210:213], v[28:31]
	v_mfma_f32_16x16x32_bf16 v[24:27], v[160:163], v[210:213], v[24:27]
	v_mfma_f32_16x16x32_bf16 v[8:11], v[160:163], v[218:221], v[8:11]
	v_mfma_f32_16x16x32_bf16 v[12:15], v[146:149], v[218:221], v[12:15]
	v_mfma_f32_16x16x32_bf16 v[60:63], v[156:159], v[192:195], v[60:63]
	v_mfma_f32_16x16x32_bf16 v[56:59], v[164:167], v[192:195], v[56:59]
	v_mfma_f32_16x16x32_bf16 v[40:43], v[164:167], v[206:209], v[40:43]
	v_mfma_f32_16x16x32_bf16 v[44:47], v[156:159], v[206:209], v[44:47]
	v_mfma_f32_16x16x32_bf16 v[28:31], v[156:159], v[214:217], v[28:31]
	v_mfma_f32_16x16x32_bf16 v[24:27], v[164:167], v[214:217], v[24:27]
	v_lshl_add_u64 v[200:201], v[228:229], 0, s[26:27]
	s_mov_b32 m0, s63
	s_nop 0
	global_load_lds_dwordx4 v[200:201], off
	v_mfma_f32_16x16x32_bf16 v[8:11], v[164:167], v[222:225], v[8:11]
	v_mfma_f32_16x16x32_bf16 v[12:15], v[156:159], v[222:225], v[12:15]
	s_setprio 0
	s_setprio 1
	v_mfma_f32_16x16x32_bf16 v[52:55], v[168:171], v[188:191], v[52:55]
	v_mfma_f32_16x16x32_bf16 v[48:51], v[180:183], v[188:191], v[48:51]
	v_mfma_f32_16x16x32_bf16 v[32:35], v[180:183], v[196:199], v[32:35]
	v_mfma_f32_16x16x32_bf16 v[36:39], v[168:171], v[196:199], v[36:39]
	v_mfma_f32_16x16x32_bf16 v[20:23], v[168:171], v[210:213], v[20:23]
	v_mfma_f32_16x16x32_bf16 v[16:19], v[180:183], v[210:213], v[16:19]
	v_mfma_f32_16x16x32_bf16 v[0:3], v[180:183], v[218:221], v[0:3]
	v_mfma_f32_16x16x32_bf16 v[4:7], v[168:171], v[218:221], v[4:7]
	v_mfma_f32_16x16x32_bf16 v[52:55], v[172:175], v[192:195], v[52:55]
	v_mfma_f32_16x16x32_bf16 v[48:51], v[184:187], v[192:195], v[48:51]
	v_mfma_f32_16x16x32_bf16 v[32:35], v[184:187], v[206:209], v[32:35]
	v_mfma_f32_16x16x32_bf16 v[36:39], v[172:175], v[206:209], v[36:39]
	v_mfma_f32_16x16x32_bf16 v[20:23], v[172:175], v[214:217], v[20:23]
	v_mfma_f32_16x16x32_bf16 v[16:19], v[184:187], v[214:217], v[16:19]
	v_lshl_add_u64 v[200:201], v[230:231], 0, s[26:27]
	s_mov_b32 m0, s64
	s_nop 0
	global_load_lds_dwordx4 v[200:201], off
	v_mfma_f32_16x16x32_bf16 v[0:3], v[184:187], v[222:225], v[0:3]
	v_mfma_f32_16x16x32_bf16 v[4:7], v[172:175], v[222:225], v[4:7]
	s_setprio 0
	s_barrier
	s_add_i32 s81, s81, 2
	s_add_u32 s52, s52, 0x100
	s_addc_u32 s53, s53, 0
	s_add_u32 s79, s79, 0x100
	s_addc_u32 s80, s80, 0
.LBB0_1681:
	ds_read_b128 v[146:149], v152
	ds_read_b128 v[156:159], v152 offset:1024
	ds_read_b128 v[160:163], v152 offset:2048
	ds_read_b128 v[164:167], v152 offset:3072
	ds_read_b128 v[168:171], v153
	ds_read_b128 v[172:175], v153 offset:1024
	ds_read_b128 v[180:183], v153 offset:2048
	ds_read_b128 v[184:187], v153 offset:3072
	s_add_u32 s54, s52, 0xfffc0080
	s_addc_u32 s55, s53, -1
	s_cmp_eq_u32 s81, 12
	s_cselect_b32 s57, s47, s55
	s_cselect_b32 s56, s77, s54
	s_cselect_b32 s55, s45, s80
	s_cselect_b32 s54, s78, s79
	v_lshl_add_u64 v[200:201], s[52:53], 0, v[136:137]
	s_add_i32 m0, s58, 0xc000
	ds_read_b128 v[188:191], v154
	ds_read_b128 v[192:195], v154 offset:1024
	ds_read_b128 v[196:199], v154 offset:2048
	ds_read_b128 v[206:209], v154 offset:3072
	ds_read_b128 v[210:213], v154 offset:4096
	ds_read_b128 v[214:217], v154 offset:5120
	ds_read_b128 v[218:221], v154 offset:6144
	ds_read_b128 v[222:225], v154 offset:7168
	global_load_lds_dwordx4 v[200:201], off
	v_lshl_add_u64 v[200:201], s[52:53], 0, v[138:139]
	s_add_i32 m0, s58, 0xe000
	s_nop 0
	global_load_lds_dwordx4 v[200:201], off
	s_waitcnt vmcnt(8)
	s_waitcnt lgkmcnt(0)
	s_barrier
; #define PG8_STAGE(bufoff, gbase, voff) do { _Pragma("unroll") for (int _i = 0; _i < 2; ++_i) \
;         __builtin_amdgcn_global_load_lds((const unsigned*)((const char*)(gbase) + (voff)[_i]), (PG8_LAS unsigned*)(lds + (bufoff) + ldsw + _i * 8192), 16, 0, 0); } while (0)
; #define PG8_LDA(dst, b, h) do { _Pragma("unroll") for (int m = 0; m < 4; ++m) _Pragma("unroll") for (int k = 0; k < 2; ++k) dst[m][k] = *(const PG8_LAS bf16x8*)(lds + PG8_SA(b, h) + aoff + m * 2048 + k * 1024); } while (0)
; #define PG8_LDB(dst, b, h) do { _Pragma("unroll") for (int n = 0; n < 2; ++n) _Pragma("unroll") for (int k = 0; k < 2; ++k) dst[n][k] = *(const PG8_LAS bf16x8*)(lds + PG8_SB(b, h) + boff + n * 2048 + k * 1024); } while (0)
; #define PG8_MMA(ai, bj, At, Bt) do { __builtin_amdgcn_s_setprio(1); _Pragma("unroll") for (int m = 0; m < 4; ++m) _Pragma("unroll") for (int n = 0; n < 2; ++n) _Pragma("unroll") for (int k = 0; k < 2; ++k) \
;         acc[ai][bj][m][n] = __builtin_amdgcn_mfma_f32_16x16x32_bf16(Bt[n][k], At[m][k], acc[ai][bj][m][n], 0, 0, 0); __builtin_amdgcn_s_setprio(0); } while (0)
; #define PG8_WAIT_V(n) asm volatile("s_waitcnt vmcnt(" #n ")" ::: "memory")
; #define PG8_WAIT_L(n) asm volatile("s_waitcnt lgkmcnt(" #n ")" ::: "memory")
; #define PG8_BAR __builtin_amdgcn_s_barrier()
; #define PG8_SCHED __builtin_amdgcn_sched_barrier(0)
; template <class Epi, class Sched, bool ALIGN_EPI = false, bool SP2 = false>
; __device__ __forceinline__ void gemm_phase(PG8_LAS unsigned char* lds, const Gemm g, const Sched& S, const Epi& E) {
;     ...
;             PG8_LDB(B0, 0, 0); PG8_LDB(B1, 0, 1); PG8_SCHED; PG8_LDA(At, 0, 0); PG8_STAGE(PG8_SA(1, 1), a1 + hstep, voffA);
;             PG8_WAIT_V(8); PG8_WAIT_L(0); PG8_BAR; PG8_MMA(0, 0, At, B0); PG8_MMA(0, 1, At, B1); PG8_BAR; PG8_SCHED;
;             PG8_LDA(At, 0, 1); PG8_STAGE(PG8_SB(0, 0), b2, voffB); PG8_STAGE(PG8_SB(0, 1), b2 + hstep, voffB); PG8_STAGE(PG8_SA(0, 0), a2, voffA);
;             PG8_WAIT_V(8); PG8_WAIT_L(0); PG8_BAR; PG8_MMA(1, 0, At, B0); PG8_MMA(1, 1, At, B1); PG8_BAR; PG8_SCHED;
	s_setprio 1
	s_waitcnt lgkmcnt(0)
	v_mfma_f32_16x16x32_bf16 v[124:127], v[146:149], v[188:191], v[124:127]
	v_mfma_f32_16x16x32_bf16 v[120:123], v[160:163], v[188:191], v[120:123]
	v_mfma_f32_16x16x32_bf16 v[104:107], v[160:163], v[196:199], v[104:107]
	v_mfma_f32_16x16x32_bf16 v[108:111], v[146:149], v[196:199], v[108:111]
	v_mfma_f32_16x16x32_bf16 v[92:95], v[146:149], v[210:213], v[92:95]
	v_mfma_f32_16x16x32_bf16 v[88:91], v[160:163], v[210:213], v[88:91]
	v_mfma_f32_16x16x32_bf16 v[72:75], v[160:163], v[218:221], v[72:75]
	v_mfma_f32_16x16x32_bf16 v[76:79], v[146:149], v[218:221], v[76:79]
	v_mfma_f32_16x16x32_bf16 v[124:127], v[156:159], v[192:195], v[124:127]
	v_mfma_f32_16x16x32_bf16 v[120:123], v[164:167], v[192:195], v[120:123]
	v_mfma_f32_16x16x32_bf16 v[104:107], v[164:167], v[206:209], v[104:107]
	v_mfma_f32_16x16x32_bf16 v[108:111], v[156:159], v[206:209], v[108:111]
	v_mfma_f32_16x16x32_bf16 v[92:95], v[156:159], v[214:217], v[92:95]
	v_mfma_f32_16x16x32_bf16 v[88:91], v[164:167], v[214:217], v[88:91]
	v_mfma_f32_16x16x32_bf16 v[72:75], v[164:167], v[222:225], v[72:75]
	v_mfma_f32_16x16x32_bf16 v[76:79], v[156:159], v[222:225], v[76:79]
	s_setprio 0
	s_setprio 1
	v_mfma_f32_16x16x32_bf16 v[116:119], v[168:171], v[188:191], v[116:119]
	v_mfma_f32_16x16x32_bf16 v[112:115], v[180:183], v[188:191], v[112:115]
	v_mfma_f32_16x16x32_bf16 v[96:99], v[180:183], v[196:199], v[96:99]
	v_mfma_f32_16x16x32_bf16 v[100:103], v[168:171], v[196:199], v[100:103]
	v_mfma_f32_16x16x32_bf16 v[84:87], v[168:171], v[210:213], v[84:87]
	v_mfma_f32_16x16x32_bf16 v[80:83], v[180:183], v[210:213], v[80:83]
	v_mfma_f32_16x16x32_bf16 v[64:67], v[180:183], v[218:221], v[64:67]
	v_mfma_f32_16x16x32_bf16 v[68:71], v[168:171], v[218:221], v[68:71]
	v_mfma_f32_16x16x32_bf16 v[116:119], v[172:175], v[192:195], v[116:119]
	v_mfma_f32_16x16x32_bf16 v[112:115], v[184:187], v[192:195], v[112:115]
	v_mfma_f32_16x16x32_bf16 v[96:99], v[184:187], v[206:209], v[96:99]
	v_mfma_f32_16x16x32_bf16 v[100:103], v[172:175], v[206:209], v[100:103]
	v_mfma_f32_16x16x32_bf16 v[84:87], v[172:175], v[214:217], v[84:87]
	v_mfma_f32_16x16x32_bf16 v[80:83], v[184:187], v[214:217], v[80:83]
	v_mfma_f32_16x16x32_bf16 v[64:67], v[184:187], v[222:225], v[64:67]
	v_mfma_f32_16x16x32_bf16 v[68:71], v[172:175], v[222:225], v[68:71]
	s_setprio 0
	s_barrier
	s_add_i32 s82, s65, s34
	v_lshl_add_u64 v[200:201], s[54:55], 0, v[132:133]
	s_mov_b32 m0, s82
	ds_read_b128 v[188:191], v154 offset:16384
	ds_read_b128 v[192:195], v154 offset:17408
	ds_read_b128 v[196:199], v154 offset:18432
	ds_read_b128 v[206:209], v154 offset:19456
	ds_read_b128 v[210:213], v154 offset:20480
	ds_read_b128 v[214:217], v154 offset:21504
	ds_read_b128 v[218:221], v154 offset:22528
	ds_read_b128 v[222:225], v154 offset:23552
	global_load_lds_dwordx4 v[200:201], off
	s_add_i32 m0, s82, 0x2000
	s_add_u32 s82, s54, 0x40000
	v_lshl_add_u64 v[226:227], s[54:55], 0, v[128:129]
	s_addc_u32 s83, s55, 0
	s_add_i32 s84, s66, s34
	global_load_lds_dwordx4 v[226:227], off
	v_lshl_add_u64 v[228:229], s[82:83], 0, v[132:133]
	s_mov_b32 m0, s84
	global_load_lds_dwordx4 v[228:229], off
	v_lshl_add_u64 v[228:229], s[82:83], 0, v[128:129]
	s_add_i32 m0, s84, 0x2000
	s_nop 0
	global_load_lds_dwordx4 v[228:229], off
	s_waitcnt vmcnt(6)
	s_waitcnt lgkmcnt(0)
	s_barrier
	s_setprio 1
	s_waitcnt lgkmcnt(0)
	v_mfma_f32_16x16x32_bf16 v[60:63], v[146:149], v[188:191], v[60:63]
	v_mfma_f32_16x16x32_bf16 v[56:59], v[160:163], v[188:191], v[56:59]
	v_mfma_f32_16x16x32_bf16 v[40:43], v[160:163], v[196:199], v[40:43]
	v_mfma_f32_16x16x32_bf16 v[44:47], v[146:149], v[196:199], v[44:47]
	v_mfma_f32_16x16x32_bf16 v[28:31], v[146:149], v[210:213], v[28:31]
	v_mfma_f32_16x16x32_bf16 v[24:27], v[160:163], v[210:213], v[24:27]
	v_mfma_f32_16x16x32_bf16 v[8:11], v[160:163], v[218:221], v[8:11]
	v_mfma_f32_16x16x32_bf16 v[12:15], v[146:149], v[218:221], v[12:15]
	v_mfma_f32_16x16x32_bf16 v[60:63], v[156:159], v[192:195], v[60:63]
	v_mfma_f32_16x16x32_bf16 v[56:59], v[164:167], v[192:195], v[56:59]
	v_mfma_f32_16x16x32_bf16 v[40:43], v[164:167], v[206:209], v[40:43]
	v_mfma_f32_16x16x32_bf16 v[44:47], v[156:159], v[206:209], v[44:47]
	v_mfma_f32_16x16x32_bf16 v[28:31], v[156:159], v[214:217], v[28:31]
	v_mfma_f32_16x16x32_bf16 v[24:27], v[164:167], v[214:217], v[24:27]
	v_lshl_add_u64 v[228:229], s[56:57], 0, v[134:135]
	s_mov_b32 m0, s58
	s_nop 0
	global_load_lds_dwordx4 v[228:229], off
	v_mfma_f32_16x16x32_bf16 v[8:11], v[164:167], v[222:225], v[8:11]
	v_mfma_f32_16x16x32_bf16 v[12:15], v[156:159], v[222:225], v[12:15]
	s_setprio 0
	s_setprio 1
	v_mfma_f32_16x16x32_bf16 v[52:55], v[168:171], v[188:191], v[52:55]
	v_mfma_f32_16x16x32_bf16 v[48:51], v[180:183], v[188:191], v[48:51]
	v_mfma_f32_16x16x32_bf16 v[32:35], v[180:183], v[196:199], v[32:35]
	v_mfma_f32_16x16x32_bf16 v[36:39], v[168:171], v[196:199], v[36:39]
	v_mfma_f32_16x16x32_bf16 v[20:23], v[168:171], v[210:213], v[20:23]
	v_mfma_f32_16x16x32_bf16 v[16:19], v[180:183], v[210:213], v[16:19]
	v_mfma_f32_16x16x32_bf16 v[0:3], v[180:183], v[218:221], v[0:3]
	v_mfma_f32_16x16x32_bf16 v[4:7], v[168:171], v[218:221], v[4:7]
	v_mfma_f32_16x16x32_bf16 v[52:55], v[172:175], v[192:195], v[52:55]
	v_mfma_f32_16x16x32_bf16 v[48:51], v[184:187], v[192:195], v[48:51]
	v_mfma_f32_16x16x32_bf16 v[32:35], v[184:187], v[206:209], v[32:35]
	v_mfma_f32_16x16x32_bf16 v[36:39], v[172:175], v[206:209], v[36:39]
	v_mfma_f32_16x16x32_bf16 v[20:23], v[172:175], v[214:217], v[20:23]
	v_mfma_f32_16x16x32_bf16 v[16:19], v[184:187], v[214:217], v[16:19]
	v_lshl_add_u64 v[230:231], s[56:57], 0, v[130:131]
	s_mov_b32 m0, s59
	s_nop 0
	global_load_lds_dwordx4 v[230:231], off
	v_mfma_f32_16x16x32_bf16 v[0:3], v[184:187], v[222:225], v[0:3]
	v_mfma_f32_16x16x32_bf16 v[4:7], v[172:175], v[222:225], v[4:7]
	s_setprio 0
	s_barrier
; #define PG8_STAGE(bufoff, gbase, voff) do { _Pragma("unroll") for (int _i = 0; _i < 2; ++_i) \
;         __builtin_amdgcn_global_load_lds((const unsigned*)((const char*)(gbase) + (voff)[_i]), (PG8_LAS unsigned*)(lds + (bufoff) + ldsw + _i * 8192), 16, 0, 0); } while (0)
; #define PG8_LDA(dst, b, h) do { _Pragma("unroll") for (int m = 0; m < 4; ++m) _Pragma("unroll") for (int k = 0; k < 2; ++k) dst[m][k] = *(const PG8_LAS bf16x8*)(lds + PG8_SA(b, h) + aoff + m * 2048 + k * 1024); } while (0)
; #define PG8_LDB(dst, b, h) do { _Pragma("unroll") for (int n = 0; n < 2; ++n) _Pragma("unroll") for (int k = 0; k < 2; ++k) dst[n][k] = *(const PG8_LAS bf16x8*)(lds + PG8_SB(b, h) + boff + n * 2048 + k * 1024); } while (0)
; #define PG8_MMA(ai, bj, At, Bt) do { __builtin_amdgcn_s_setprio(1); _Pragma("unroll") for (int m = 0; m < 4; ++m) _Pragma("unroll") for (int n = 0; n < 2; ++n) _Pragma("unroll") for (int k = 0; k < 2; ++k) \
;         acc[ai][bj][m][n] = __builtin_amdgcn_mfma_f32_16x16x32_bf16(Bt[n][k], At[m][k], acc[ai][bj][m][n], 0, 0, 0); __builtin_amdgcn_s_setprio(0); } while (0)
; #define PG8_WAIT_V(n) asm volatile("s_waitcnt vmcnt(" #n ")" ::: "memory")
; #define PG8_WAIT_L(n) asm volatile("s_waitcnt lgkmcnt(" #n ")" ::: "memory")
; #define PG8_BAR __builtin_amdgcn_s_barrier()
; #define PG8_SCHED __builtin_amdgcn_sched_barrier(0)
; template <class Epi, class Sched, bool ALIGN_EPI = false, bool SP2 = false>
; __device__ __forceinline__ void gemm_phase(PG8_LAS unsigned char* lds, const Gemm g, const Sched& S, const Epi& E) {
;     ...
;             PG8_LDB(B0, 1, 0); PG8_LDB(B1, 1, 1); PG8_SCHED; PG8_LDA(At, 1, 0); PG8_STAGE(PG8_SA(0, 1), a2 + hstep, voffA);
;             PG8_WAIT_V(8); PG8_WAIT_L(0); PG8_BAR; PG8_MMA(0, 0, At, B0); PG8_MMA(0, 1, At, B1); PG8_BAR; PG8_SCHED;
	s_add_i32 s82, 0, 0x18000
	s_add_i32 s83, 0, 0x1c000
	v_add_u32_e32 v164, s82, v150
	v_add_u32_e32 v179, s83, v150
	ds_read_b128 v[146:149], v164
	ds_read_b128 v[156:159], v164 offset:1024
	ds_read_b128 v[160:163], v164 offset:2048
	ds_read_b128 v[164:167], v164 offset:3072
	ds_read_b128 v[168:171], v179
	ds_read_b128 v[172:175], v179 offset:1024
	ds_read_b128 v[180:183], v179 offset:2048
	ds_read_b128 v[184:187], v179 offset:3072
	s_add_u32 s56, s56, 0x40000
	s_addc_u32 s57, s57, 0
	s_mov_b32 m0, s60
	v_lshl_add_u64 v[232:233], s[56:57], 0, v[134:135]
	ds_read_b128 v[188:191], v154 offset:32768
	ds_read_b128 v[192:195], v154 offset:33792
	ds_read_b128 v[196:199], v154 offset:34816
	ds_read_b128 v[206:209], v154 offset:35840
	ds_read_b128 v[210:213], v154 offset:36864
	ds_read_b128 v[214:217], v154 offset:37888
	ds_read_b128 v[218:221], v154 offset:38912
	ds_read_b128 v[222:225], v154 offset:39936
	global_load_lds_dwordx4 v[232:233], off
	v_lshl_add_u64 v[232:233], s[56:57], 0, v[130:131]
	s_mov_b32 m0, s61
	s_nop 0
	global_load_lds_dwordx4 v[232:233], off
	s_waitcnt vmcnt(8)
	s_waitcnt lgkmcnt(0)
	s_barrier
	s_setprio 1
	s_waitcnt lgkmcnt(0)
	v_mfma_f32_16x16x32_bf16 v[124:127], v[146:149], v[188:191], v[124:127]
	v_mfma_f32_16x16x32_bf16 v[120:123], v[160:163], v[188:191], v[120:123]
	v_mfma_f32_16x16x32_bf16 v[104:107], v[160:163], v[196:199], v[104:107]
	v_mfma_f32_16x16x32_bf16 v[108:111], v[146:149], v[196:199], v[108:111]
	v_mfma_f32_16x16x32_bf16 v[92:95], v[146:149], v[210:213], v[92:95]
	v_mfma_f32_16x16x32_bf16 v[88:91], v[160:163], v[210:213], v[88:91]
	v_mfma_f32_16x16x32_bf16 v[72:75], v[160:163], v[218:221], v[72:75]
	v_mfma_f32_16x16x32_bf16 v[76:79], v[146:149], v[218:221], v[76:79]
	v_mfma_f32_16x16x32_bf16 v[124:127], v[156:159], v[192:195], v[124:127]
	v_mfma_f32_16x16x32_bf16 v[120:123], v[164:167], v[192:195], v[120:123]
	v_mfma_f32_16x16x32_bf16 v[104:107], v[164:167], v[206:209], v[104:107]
	v_mfma_f32_16x16x32_bf16 v[108:111], v[156:159], v[206:209], v[108:111]
	v_mfma_f32_16x16x32_bf16 v[92:95], v[156:159], v[214:217], v[92:95]
	v_mfma_f32_16x16x32_bf16 v[88:91], v[164:167], v[214:217], v[88:91]
	v_mfma_f32_16x16x32_bf16 v[72:75], v[164:167], v[222:225], v[72:75]
	v_mfma_f32_16x16x32_bf16 v[76:79], v[156:159], v[222:225], v[76:79]
	s_setprio 0
	s_setprio 1
	v_mfma_f32_16x16x32_bf16 v[116:119], v[168:171], v[188:191], v[116:119]
	v_mfma_f32_16x16x32_bf16 v[112:115], v[180:183], v[188:191], v[112:115]
	v_mfma_f32_16x16x32_bf16 v[96:99], v[180:183], v[196:199], v[96:99]
	v_mfma_f32_16x16x32_bf16 v[100:103], v[168:171], v[196:199], v[100:103]
	v_mfma_f32_16x16x32_bf16 v[84:87], v[168:171], v[210:213], v[84:87]
	v_mfma_f32_16x16x32_bf16 v[80:83], v[180:183], v[210:213], v[80:83]
	v_mfma_f32_16x16x32_bf16 v[64:67], v[180:183], v[218:221], v[64:67]
	v_mfma_f32_16x16x32_bf16 v[68:71], v[168:171], v[218:221], v[68:71]
	v_mfma_f32_16x16x32_bf16 v[116:119], v[172:175], v[192:195], v[116:119]
	v_mfma_f32_16x16x32_bf16 v[112:115], v[184:187], v[192:195], v[112:115]
	v_mfma_f32_16x16x32_bf16 v[96:99], v[184:187], v[206:209], v[96:99]
	v_mfma_f32_16x16x32_bf16 v[100:103], v[172:175], v[206:209], v[100:103]
	v_mfma_f32_16x16x32_bf16 v[84:87], v[172:175], v[214:217], v[84:87]
	v_mfma_f32_16x16x32_bf16 v[80:83], v[184:187], v[214:217], v[80:83]
	v_mfma_f32_16x16x32_bf16 v[64:67], v[184:187], v[222:225], v[64:67]
	v_mfma_f32_16x16x32_bf16 v[68:71], v[172:175], v[222:225], v[68:71]
	s_setprio 0
	s_barrier
; #define PG8_STAGE(bufoff, gbase, voff) do { _Pragma("unroll") for (int _i = 0; _i < 2; ++_i) \
;         __builtin_amdgcn_global_load_lds((const unsigned*)((const char*)(gbase) + (voff)[_i]), (PG8_LAS unsigned*)(lds + (bufoff) + ldsw + _i * 8192), 16, 0, 0); } while (0)
; #define PG8_LDA(dst, b, h) do { _Pragma("unroll") for (int m = 0; m < 4; ++m) _Pragma("unroll") for (int k = 0; k < 2; ++k) dst[m][k] = *(const PG8_LAS bf16x8*)(lds + PG8_SA(b, h) + aoff + m * 2048 + k * 1024); } while (0)
; #define PG8_MMA(ai, bj, At, Bt) do { __builtin_amdgcn_s_setprio(1); _Pragma("unroll") for (int m = 0; m < 4; ++m) _Pragma("unroll") for (int n = 0; n < 2; ++n) _Pragma("unroll") for (int k = 0; k < 2; ++k) \
;         acc[ai][bj][m][n] = __builtin_amdgcn_mfma_f32_16x16x32_bf16(Bt[n][k], At[m][k], acc[ai][bj][m][n], 0, 0, 0); __builtin_amdgcn_s_setprio(0); } while (0)
; #define PG8_WAIT_V(n) asm volatile("s_waitcnt vmcnt(" #n ")" ::: "memory")
; #define PG8_WAIT_L(n) asm volatile("s_waitcnt lgkmcnt(" #n ")" ::: "memory")
; #define PG8_BAR __builtin_amdgcn_s_barrier()
; #define PG8_SCHED __builtin_amdgcn_sched_barrier(0)
; template <class Epi, class Sched, bool ALIGN_EPI = false, bool SP2 = false>
; __device__ __forceinline__ void gemm_phase(PG8_LAS unsigned char* lds, const Gemm g, const Sched& S, const Epi& E) {
;     ...
;             PG8_LDA(At, 1, 1); PG8_STAGE(PG8_SB(1, 0), b3, voffB); PG8_STAGE(PG8_SB(1, 1), b3 + hstep, voffB); PG8_STAGE(PG8_SA(1, 0), a3, voffA);
;             PG8_WAIT_V(8); PG8_WAIT_L(0); PG8_BAR; PG8_MMA(1, 0, At, B0); PG8_MMA(1, 1, At, B1); PG8_BAR; PG8_SCHED;
;     ...
;         if constexpr (ALIGN_EPI) { if (wr == 0) PG8_BAR; }
	s_add_i32 s56, s82, s34
	v_lshl_add_u64 v[200:201], v[200:201], 0, s[26:27]
	s_mov_b32 m0, s56
	ds_read_b128 v[188:191], v154 offset:49152
	ds_read_b128 v[192:195], v154 offset:50176
	ds_read_b128 v[196:199], v154 offset:51200
	ds_read_b128 v[206:209], v154 offset:52224
	ds_read_b128 v[210:213], v154 offset:53248
	ds_read_b128 v[214:217], v154 offset:54272
	ds_read_b128 v[218:221], v154 offset:55296
	ds_read_b128 v[222:225], v154 offset:56320
	global_load_lds_dwordx4 v[200:201], off
	s_add_i32 m0, s56, 0x2000
	s_add_u32 s54, s54, 0x40080
	v_lshl_add_u64 v[200:201], v[226:227], 0, s[26:27]
	s_addc_u32 s55, s55, 0
	s_add_i32 s56, s83, s34
	global_load_lds_dwordx4 v[200:201], off
	v_lshl_add_u64 v[200:201], s[54:55], 0, v[132:133]
	s_mov_b32 m0, s56
	s_nop 0
	global_load_lds_dwordx4 v[200:201], off
	v_lshl_add_u64 v[200:201], s[54:55], 0, v[128:129]
	s_add_i32 m0, s56, 0x2000
	s_nop 0
	global_load_lds_dwordx4 v[200:201], off
	s_waitcnt vmcnt(6)
	s_waitcnt lgkmcnt(0)
	s_barrier
	s_setprio 1
	s_waitcnt lgkmcnt(0)
	v_mfma_f32_16x16x32_bf16 v[60:63], v[146:149], v[188:191], v[60:63]
	v_mfma_f32_16x16x32_bf16 v[56:59], v[160:163], v[188:191], v[56:59]
	v_mfma_f32_16x16x32_bf16 v[40:43], v[160:163], v[196:199], v[40:43]
	v_mfma_f32_16x16x32_bf16 v[44:47], v[146:149], v[196:199], v[44:47]
	v_mfma_f32_16x16x32_bf16 v[28:31], v[146:149], v[210:213], v[28:31]
	v_mfma_f32_16x16x32_bf16 v[24:27], v[160:163], v[210:213], v[24:27]
	v_mfma_f32_16x16x32_bf16 v[8:11], v[160:163], v[218:221], v[8:11]
	v_mfma_f32_16x16x32_bf16 v[12:15], v[146:149], v[218:221], v[12:15]
	v_mfma_f32_16x16x32_bf16 v[60:63], v[156:159], v[192:195], v[60:63]
	v_mfma_f32_16x16x32_bf16 v[56:59], v[164:167], v[192:195], v[56:59]
	v_mfma_f32_16x16x32_bf16 v[40:43], v[164:167], v[206:209], v[40:43]
	v_mfma_f32_16x16x32_bf16 v[44:47], v[156:159], v[206:209], v[44:47]
	v_mfma_f32_16x16x32_bf16 v[28:31], v[156:159], v[214:217], v[28:31]
	v_mfma_f32_16x16x32_bf16 v[24:27], v[164:167], v[214:217], v[24:27]
	v_lshl_add_u64 v[200:201], v[228:229], 0, s[26:27]
	s_mov_b32 m0, s63
	s_nop 0
	global_load_lds_dwordx4 v[200:201], off
	v_mfma_f32_16x16x32_bf16 v[8:11], v[164:167], v[222:225], v[8:11]
	v_mfma_f32_16x16x32_bf16 v[12:15], v[156:159], v[222:225], v[12:15]
	s_setprio 0
	s_setprio 1
	v_mfma_f32_16x16x32_bf16 v[52:55], v[168:171], v[188:191], v[52:55]
	v_mfma_f32_16x16x32_bf16 v[48:51], v[180:183], v[188:191], v[48:51]
	v_mfma_f32_16x16x32_bf16 v[32:35], v[180:183], v[196:199], v[32:35]
	v_mfma_f32_16x16x32_bf16 v[36:39], v[168:171], v[196:199], v[36:39]
	v_mfma_f32_16x16x32_bf16 v[20:23], v[168:171], v[210:213], v[20:23]
	v_mfma_f32_16x16x32_bf16 v[16:19], v[180:183], v[210:213], v[16:19]
	v_mfma_f32_16x16x32_bf16 v[0:3], v[180:183], v[218:221], v[0:3]
	v_mfma_f32_16x16x32_bf16 v[4:7], v[168:171], v[218:221], v[4:7]
	v_mfma_f32_16x16x32_bf16 v[52:55], v[172:175], v[192:195], v[52:55]
	v_mfma_f32_16x16x32_bf16 v[48:51], v[184:187], v[192:195], v[48:51]
	v_mfma_f32_16x16x32_bf16 v[32:35], v[184:187], v[206:209], v[32:35]
	v_mfma_f32_16x16x32_bf16 v[36:39], v[172:175], v[206:209], v[36:39]
	v_mfma_f32_16x16x32_bf16 v[20:23], v[172:175], v[214:217], v[20:23]
	v_mfma_f32_16x16x32_bf16 v[16:19], v[184:187], v[214:217], v[16:19]
	v_lshl_add_u64 v[200:201], v[230:231], 0, s[26:27]
	s_mov_b32 m0, s64
	s_nop 0
	global_load_lds_dwordx4 v[200:201], off
	v_mfma_f32_16x16x32_bf16 v[0:3], v[184:187], v[222:225], v[0:3]
	v_mfma_f32_16x16x32_bf16 v[4:7], v[172:175], v[222:225], v[4:7]
	s_setprio 0
	s_barrier
	s_add_i32 s81, s81, 2
	s_add_u32 s52, s52, 0x100
	s_addc_u32 s53, s53, 0
	s_add_u32 s79, s79, 0x100
	s_addc_u32 s80, s80, 0
	s_cmp_gt_u32 s81, 13
	s_cbranch_scc0 .LBB0_1681
	s_and_b64 vcc, exec, s[28:29]
	s_cbranch_vccz .LBB0_1684
	s_barrier

; #define PG8_STAGE(bufoff, gbase, voff) do { _Pragma("unroll") for (int _i = 0; _i < 2; ++_i) \
;         __builtin_amdgcn_global_load_lds((const unsigned*)((const char*)(gbase) + (voff)[_i]), (PG8_LAS unsigned*)(lds + (bufoff) + ldsw + _i * 8192), 16, 0, 0); } while (0)
; #define PG8_LDA(dst, b, h) do { _Pragma("unroll") for (int m = 0; m < 4; ++m) _Pragma("unroll") for (int k = 0; k < 2; ++k) dst[m][k] = *(const PG8_LAS bf16x8*)(lds + PG8_SA(b, h) + aoff + m * 2048 + k * 1024); } while (0)
; #define PG8_LDB(dst, b, h) do { _Pragma("unroll") for (int n = 0; n < 2; ++n) _Pragma("unroll") for (int k = 0; k < 2; ++k) dst[n][k] = *(const PG8_LAS bf16x8*)(lds + PG8_SB(b, h) + boff + n * 2048 + k * 1024); } while (0)
; #define PG8_WAIT_V(n) asm volatile("s_waitcnt vmcnt(" #n ")" ::: "memory")
; #define PG8_WAIT_L(n) asm volatile("s_waitcnt lgkmcnt(" #n ")" ::: "memory")
; #define PG8_BAR __builtin_amdgcn_s_barrier()
; #define PG8_SCHED __builtin_amdgcn_sched_barrier(0)
; template <class Epi, class Sched, bool ALIGN_EPI = false, bool SP2 = false>
; __device__ __forceinline__ void gemm_phase(PG8_LAS unsigned char* lds, const Gemm g, const Sched& S, const Epi& E) {
;     ...
;         const bool has_next = S.next(ui + 1, nxt);
;         const char* nA = has_next ? (const char*)g.A + (size_t)nxt.pm * tstep : cA; const char* nB = has_next ? (const char*)g.Bt + (size_t)nxt.pn * tstep : cB;
;         for (int t = 0; t < nt; t += 2) {
;             const bool last = (t == nt - 2);
;             const char* a1 = cA + (size_t)(t + 1) * kstep;
;             const char* a2 = last ? nA : cA + (size_t)(t + 2) * kstep; const char* b2 = last ? nB : cB + (size_t)(t + 2) * kstep;
;             const char* a3 = a2 + kstep; const char* b3 = b2 + kstep;
;             if (last && has_next) S.a_ready(nxt);
;             if constexpr (SP2) {
;             PG8_LDB(B0, 0, 0); PG8_LDB(B1, 0, 1); PG8_SCHED; PG8_LDA(At, 0, 0); PG8_STAGE(PG8_SA(1, 1), a1 + hstep, voffA);
;             PG8_WAIT_V(8); PG8_WAIT_L(0); PG8_BAR; PG8_MMA(0, 0, At, B0); PG8_MMA(0, 1, At, B1); PG8_BAR; PG8_SCHED;
;             PG8_LDA(At, 0, 1); PG8_STAGE(PG8_SB(0, 0), b2, voffB); PG8_STAGE(PG8_SB(0, 1), b2 + hstep, voffB); PG8_STAGE(PG8_SA(0, 0), a2, voffA);
;             PG8_WAIT_V(8); PG8_WAIT_L(0); PG8_BAR; PG8_MMA(1, 0, At, B0); PG8_MMA(1, 1, At, B1); PG8_BAR; PG8_SCHED;
.LBB0_1815:
	s_ashr_i32 s29, s28, 31
	s_lshl_b64 s[36:37], s[28:29], 18
	s_add_u32 s36, s92, s36
	s_addc_u32 s37, s93, s37
	s_and_b64 s[38:39], s[6:7], exec
	s_cselect_b32 s29, s37, s45
	s_cselect_b32 s41, s36, s44
	s_ashr_i32 s27, s26, 31
	s_lshl_b64 s[38:39], s[26:27], 18
	s_add_u32 s38, s3, s38
	s_addc_u32 s39, s14, s39
	s_and_b64 s[48:49], s[6:7], exec
	s_cselect_b32 s27, s39, s47
	s_cselect_b32 s58, s38, s46
	s_add_u32 s44, s44, 0x20080
	s_addc_u32 s45, s45, 0
	s_add_u32 s59, s46, 0x100
	s_addc_u32 s60, s47, 0
	s_mov_b32 s61, -2
	s_waitcnt lgkmcnt(0)
	ds_read_b128 v[144:147], v151
	ds_read_b128 v[156:159], v151 offset:1024
	ds_read_b128 v[160:163], v151 offset:2048
	ds_read_b128 v[164:167], v151 offset:3072
	ds_read_b128 v[168:171], v152
	ds_read_b128 v[172:175], v152 offset:1024
	ds_read_b128 v[176:179], v152 offset:2048
	ds_read_b128 v[180:183], v152 offset:3072
	s_add_u32 s46, s44, 0xfffe0080
	s_addc_u32 s47, s45, -1
	s_cmp_eq_u32 s61, 4
	s_cselect_b32 s49, s29, s47
	s_cselect_b32 s48, s41, s46
	s_cselect_b32 s47, s27, s60
	s_cselect_b32 s46, s58, s59
	v_lshl_add_u64 v[218:219], s[44:45], 0, v[136:137]
	s_add_i32 m0, s33, 0xc000
	ds_read_b128 v[184:187], v153
	ds_read_b128 v[188:191], v153 offset:1024
	ds_read_b128 v[192:195], v153 offset:2048
	ds_read_b128 v[196:199], v153 offset:3072
	ds_read_b128 v[200:203], v153 offset:4096
	ds_read_b128 v[206:209], v153 offset:5120
	ds_read_b128 v[210:213], v153 offset:6144
	ds_read_b128 v[214:217], v153 offset:7168
	global_load_lds_dwordx4 v[218:219], off
	v_lshl_add_u64 v[218:219], s[44:45], 0, v[138:139]
	s_add_i32 m0, s33, 0xe000
	s_nop 0
	global_load_lds_dwordx4 v[218:219], off
	s_waitcnt vmcnt(8)
	s_waitcnt lgkmcnt(0)
	s_barrier
	s_setprio 1
	s_waitcnt lgkmcnt(0)
	v_mfma_f32_16x16x32_bf16 v[124:127], v[144:147], v[184:187], 0
	v_mfma_f32_16x16x32_bf16 v[120:123], v[160:163], v[184:187], 0
	v_mfma_f32_16x16x32_bf16 v[104:107], v[160:163], v[192:195], 0
	v_mfma_f32_16x16x32_bf16 v[108:111], v[144:147], v[192:195], 0
	v_mfma_f32_16x16x32_bf16 v[92:95], v[144:147], v[200:203], 0
	v_mfma_f32_16x16x32_bf16 v[88:91], v[160:163], v[200:203], 0
	v_mfma_f32_16x16x32_bf16 v[72:75], v[160:163], v[210:213], 0
	v_mfma_f32_16x16x32_bf16 v[76:79], v[144:147], v[210:213], 0
	v_mfma_f32_16x16x32_bf16 v[124:127], v[156:159], v[188:191], v[124:127]
	v_mfma_f32_16x16x32_bf16 v[120:123], v[164:167], v[188:191], v[120:123]
	v_mfma_f32_16x16x32_bf16 v[104:107], v[164:167], v[196:199], v[104:107]
	v_mfma_f32_16x16x32_bf16 v[108:111], v[156:159], v[196:199], v[108:111]
	v_mfma_f32_16x16x32_bf16 v[92:95], v[156:159], v[206:209], v[92:95]
	v_mfma_f32_16x16x32_bf16 v[88:91], v[164:167], v[206:209], v[88:91]
	v_mfma_f32_16x16x32_bf16 v[72:75], v[164:167], v[214:217], v[72:75]
	v_mfma_f32_16x16x32_bf16 v[76:79], v[156:159], v[214:217], v[76:79]
	s_setprio 0
	s_setprio 1
	v_mfma_f32_16x16x32_bf16 v[116:119], v[168:171], v[184:187], 0
	v_mfma_f32_16x16x32_bf16 v[112:115], v[176:179], v[184:187], 0
	v_mfma_f32_16x16x32_bf16 v[96:99], v[176:179], v[192:195], 0
	v_mfma_f32_16x16x32_bf16 v[100:103], v[168:171], v[192:195], 0
	v_mfma_f32_16x16x32_bf16 v[84:87], v[168:171], v[200:203], 0
	v_mfma_f32_16x16x32_bf16 v[80:83], v[176:179], v[200:203], 0
	v_mfma_f32_16x16x32_bf16 v[64:67], v[176:179], v[210:213], 0
	v_mfma_f32_16x16x32_bf16 v[68:71], v[168:171], v[210:213], 0
	v_mfma_f32_16x16x32_bf16 v[116:119], v[172:175], v[188:191], v[116:119]
	v_mfma_f32_16x16x32_bf16 v[112:115], v[180:183], v[188:191], v[112:115]
	v_mfma_f32_16x16x32_bf16 v[96:99], v[180:183], v[196:199], v[96:99]
	v_mfma_f32_16x16x32_bf16 v[100:103], v[172:175], v[196:199], v[100:103]
	v_mfma_f32_16x16x32_bf16 v[84:87], v[172:175], v[206:209], v[84:87]
	v_mfma_f32_16x16x32_bf16 v[80:83], v[180:183], v[206:209], v[80:83]
	v_mfma_f32_16x16x32_bf16 v[64:67], v[180:183], v[214:217], v[64:67]
	v_mfma_f32_16x16x32_bf16 v[68:71], v[172:175], v[214:217], v[68:71]
	s_setprio 0
	s_barrier
	s_add_i32 s62, s54, s15
	v_lshl_add_u64 v[218:219], s[46:47], 0, v[130:131]
	s_mov_b32 m0, s62
	ds_read_b128 v[184:187], v153 offset:16384
	ds_read_b128 v[188:191], v153 offset:17408
	ds_read_b128 v[192:195], v153 offset:18432
	ds_read_b128 v[196:199], v153 offset:19456
	ds_read_b128 v[200:203], v153 offset:20480
	ds_read_b128 v[206:209], v153 offset:21504
	ds_read_b128 v[210:213], v153 offset:22528
	ds_read_b128 v[214:217], v153 offset:23552
	global_load_lds_dwordx4 v[218:219], off
	s_add_i32 m0, s62, 0x2000
	s_add_u32 s62, s46, 0x20000
	v_lshl_add_u64 v[220:221], s[46:47], 0, v[134:135]
	s_addc_u32 s63, s47, 0
	s_add_i32 s64, s55, s15
	global_load_lds_dwordx4 v[220:221], off
	v_lshl_add_u64 v[222:223], s[62:63], 0, v[130:131]
	s_mov_b32 m0, s64
	global_load_lds_dwordx4 v[222:223], off
	v_lshl_add_u64 v[222:223], s[62:63], 0, v[134:135]
	s_add_i32 m0, s64, 0x2000
	s_nop 0
	global_load_lds_dwordx4 v[222:223], off
	s_waitcnt vmcnt(6)
	s_waitcnt lgkmcnt(0)
	s_barrier
; #define PG8_STAGE(bufoff, gbase, voff) do { _Pragma("unroll") for (int _i = 0; _i < 2; ++_i) \
;         __builtin_amdgcn_global_load_lds((const unsigned*)((const char*)(gbase) + (voff)[_i]), (PG8_LAS unsigned*)(lds + (bufoff) + ldsw + _i * 8192), 16, 0, 0); } while (0)
; #define PG8_LDA(dst, b, h) do { _Pragma("unroll") for (int m = 0; m < 4; ++m) _Pragma("unroll") for (int k = 0; k < 2; ++k) dst[m][k] = *(const PG8_LAS bf16x8*)(lds + PG8_SA(b, h) + aoff + m * 2048 + k * 1024); } while (0)
; #define PG8_LDB(dst, b, h) do { _Pragma("unroll") for (int n = 0; n < 2; ++n) _Pragma("unroll") for (int k = 0; k < 2; ++k) dst[n][k] = *(const PG8_LAS bf16x8*)(lds + PG8_SB(b, h) + boff + n * 2048 + k * 1024); } while (0)
; #define PG8_MMA(ai, bj, At, Bt) do { __builtin_amdgcn_s_setprio(1); _Pragma("unroll") for (int m = 0; m < 4; ++m) _Pragma("unroll") for (int n = 0; n < 2; ++n) _Pragma("unroll") for (int k = 0; k < 2; ++k) \
;         acc[ai][bj][m][n] = __builtin_amdgcn_mfma_f32_16x16x32_bf16(Bt[n][k], At[m][k], acc[ai][bj][m][n], 0, 0, 0); __builtin_amdgcn_s_setprio(0); } while (0)
; #define PG8_WAIT_V(n) asm volatile("s_waitcnt vmcnt(" #n ")" ::: "memory")
; #define PG8_WAIT_L(n) asm volatile("s_waitcnt lgkmcnt(" #n ")" ::: "memory")
; #define PG8_BAR __builtin_amdgcn_s_barrier()
; #define PG8_SCHED __builtin_amdgcn_sched_barrier(0)
; template <class Epi, class Sched, bool ALIGN_EPI = false, bool SP2 = false>
; __device__ __forceinline__ void gemm_phase(PG8_LAS unsigned char* lds, const Gemm g, const Sched& S, const Epi& E) {
;     ...
;             PG8_LDA(At, 0, 1); PG8_STAGE(PG8_SB(0, 0), b2, voffB); PG8_STAGE(PG8_SB(0, 1), b2 + hstep, voffB); PG8_STAGE(PG8_SA(0, 0), a2, voffA);
;             PG8_WAIT_V(8); PG8_WAIT_L(0); PG8_BAR; PG8_MMA(1, 0, At, B0); PG8_MMA(1, 1, At, B1); PG8_BAR; PG8_SCHED;
;             PG8_LDB(B0, 1, 0); PG8_LDB(B1, 1, 1); PG8_SCHED; PG8_LDA(At, 1, 0); PG8_STAGE(PG8_SA(0, 1), a2 + hstep, voffA);
;             PG8_WAIT_V(8); PG8_WAIT_L(0); PG8_BAR; PG8_MMA(0, 0, At, B0); PG8_MMA(0, 1, At, B1); PG8_BAR; PG8_SCHED;
	s_setprio 1
	s_waitcnt lgkmcnt(0)
	v_mfma_f32_16x16x32_bf16 v[60:63], v[144:147], v[184:187], 0
	v_mfma_f32_16x16x32_bf16 v[56:59], v[160:163], v[184:187], 0
	v_mfma_f32_16x16x32_bf16 v[40:43], v[160:163], v[192:195], 0
	v_mfma_f32_16x16x32_bf16 v[44:47], v[144:147], v[192:195], 0
	v_mfma_f32_16x16x32_bf16 v[28:31], v[144:147], v[200:203], 0
	v_mfma_f32_16x16x32_bf16 v[24:27], v[160:163], v[200:203], 0
	v_mfma_f32_16x16x32_bf16 v[8:11], v[160:163], v[210:213], 0
	v_mfma_f32_16x16x32_bf16 v[12:15], v[144:147], v[210:213], 0
	v_mfma_f32_16x16x32_bf16 v[60:63], v[156:159], v[188:191], v[60:63]
	v_mfma_f32_16x16x32_bf16 v[56:59], v[164:167], v[188:191], v[56:59]
	v_mfma_f32_16x16x32_bf16 v[40:43], v[164:167], v[196:199], v[40:43]
	v_mfma_f32_16x16x32_bf16 v[44:47], v[156:159], v[196:199], v[44:47]
	v_mfma_f32_16x16x32_bf16 v[28:31], v[156:159], v[206:209], v[28:31]
	v_mfma_f32_16x16x32_bf16 v[24:27], v[164:167], v[206:209], v[24:27]
	v_lshl_add_u64 v[222:223], s[48:49], 0, v[128:129]
	s_mov_b32 m0, s33
	s_nop 0
	global_load_lds_dwordx4 v[222:223], off
	v_mfma_f32_16x16x32_bf16 v[8:11], v[164:167], v[214:217], v[8:11]
	v_mfma_f32_16x16x32_bf16 v[12:15], v[156:159], v[214:217], v[12:15]
	s_setprio 0
	s_setprio 1
	v_mfma_f32_16x16x32_bf16 v[52:55], v[168:171], v[184:187], 0
	v_mfma_f32_16x16x32_bf16 v[48:51], v[176:179], v[184:187], 0
	v_mfma_f32_16x16x32_bf16 v[32:35], v[176:179], v[192:195], 0
	v_mfma_f32_16x16x32_bf16 v[36:39], v[168:171], v[192:195], 0
	v_mfma_f32_16x16x32_bf16 v[20:23], v[168:171], v[200:203], 0
	v_mfma_f32_16x16x32_bf16 v[16:19], v[176:179], v[200:203], 0
	v_mfma_f32_16x16x32_bf16 v[0:3], v[176:179], v[210:213], 0
	v_mfma_f32_16x16x32_bf16 v[4:7], v[168:171], v[210:213], 0
	v_mfma_f32_16x16x32_bf16 v[52:55], v[172:175], v[188:191], v[52:55]
	v_mfma_f32_16x16x32_bf16 v[48:51], v[180:183], v[188:191], v[48:51]
	v_mfma_f32_16x16x32_bf16 v[32:35], v[180:183], v[196:199], v[32:35]
	v_mfma_f32_16x16x32_bf16 v[36:39], v[172:175], v[196:199], v[36:39]
	v_mfma_f32_16x16x32_bf16 v[20:23], v[172:175], v[206:209], v[20:23]
	v_mfma_f32_16x16x32_bf16 v[16:19], v[180:183], v[206:209], v[16:19]
	v_lshl_add_u64 v[224:225], s[48:49], 0, v[132:133]
	s_mov_b32 m0, s34
	s_nop 0
	global_load_lds_dwordx4 v[224:225], off
	v_mfma_f32_16x16x32_bf16 v[0:3], v[180:183], v[214:217], v[0:3]
	v_mfma_f32_16x16x32_bf16 v[4:7], v[172:175], v[214:217], v[4:7]
	s_setprio 0
	s_barrier
	s_add_i32 s62, 0, 0x18000
	v_add_u32_e32 v155, s62, v149
	s_add_i32 s63, 0, 0x1c000
	ds_read_b128 v[144:147], v155
	ds_read_b128 v[156:159], v155 offset:1024
	ds_read_b128 v[160:163], v155 offset:2048
	ds_read_b128 v[164:167], v155 offset:3072
	v_add_u32_e32 v155, s63, v149
	ds_read_b128 v[168:171], v155
	ds_read_b128 v[172:175], v155 offset:1024
	ds_read_b128 v[176:179], v155 offset:2048
	ds_read_b128 v[180:183], v155 offset:3072
	s_add_u32 s48, s48, 0x20000
	s_addc_u32 s49, s49, 0
	s_mov_b32 m0, s43
	v_lshl_add_u64 v[226:227], s[48:49], 0, v[128:129]
	ds_read_b128 v[184:187], v153 offset:32768
	ds_read_b128 v[188:191], v153 offset:33792
	ds_read_b128 v[192:195], v153 offset:34816
	ds_read_b128 v[196:199], v153 offset:35840
	ds_read_b128 v[200:203], v153 offset:36864
	ds_read_b128 v[206:209], v153 offset:37888
	ds_read_b128 v[210:213], v153 offset:38912
	ds_read_b128 v[214:217], v153 offset:39936
	global_load_lds_dwordx4 v[226:227], off
	v_lshl_add_u64 v[226:227], s[48:49], 0, v[132:133]
	s_mov_b32 m0, s50
	s_nop 0
	global_load_lds_dwordx4 v[226:227], off
	s_waitcnt vmcnt(8)
	s_waitcnt lgkmcnt(0)
	s_barrier
	s_setprio 1
	s_waitcnt lgkmcnt(0)
	v_mfma_f32_16x16x32_bf16 v[124:127], v[144:147], v[184:187], v[124:127]
	v_mfma_f32_16x16x32_bf16 v[120:123], v[160:163], v[184:187], v[120:123]
	v_mfma_f32_16x16x32_bf16 v[104:107], v[160:163], v[192:195], v[104:107]
	v_mfma_f32_16x16x32_bf16 v[108:111], v[144:147], v[192:195], v[108:111]
	v_mfma_f32_16x16x32_bf16 v[92:95], v[144:147], v[200:203], v[92:95]
	v_mfma_f32_16x16x32_bf16 v[88:91], v[160:163], v[200:203], v[88:91]
	v_mfma_f32_16x16x32_bf16 v[72:75], v[160:163], v[210:213], v[72:75]
	v_mfma_f32_16x16x32_bf16 v[76:79], v[144:147], v[210:213], v[76:79]
	v_mfma_f32_16x16x32_bf16 v[124:127], v[156:159], v[188:191], v[124:127]
	v_mfma_f32_16x16x32_bf16 v[120:123], v[164:167], v[188:191], v[120:123]
	v_mfma_f32_16x16x32_bf16 v[104:107], v[164:167], v[196:199], v[104:107]
	v_mfma_f32_16x16x32_bf16 v[108:111], v[156:159], v[196:199], v[108:111]
	v_mfma_f32_16x16x32_bf16 v[92:95], v[156:159], v[206:209], v[92:95]
	v_mfma_f32_16x16x32_bf16 v[88:91], v[164:167], v[206:209], v[88:91]
	v_mfma_f32_16x16x32_bf16 v[72:75], v[164:167], v[214:217], v[72:75]
	v_mfma_f32_16x16x32_bf16 v[76:79], v[156:159], v[214:217], v[76:79]
	s_setprio 0
	s_setprio 1
	v_mfma_f32_16x16x32_bf16 v[116:119], v[168:171], v[184:187], v[116:119]
	v_mfma_f32_16x16x32_bf16 v[112:115], v[176:179], v[184:187], v[112:115]
	v_mfma_f32_16x16x32_bf16 v[96:99], v[176:179], v[192:195], v[96:99]
	v_mfma_f32_16x16x32_bf16 v[100:103], v[168:171], v[192:195], v[100:103]
	v_mfma_f32_16x16x32_bf16 v[84:87], v[168:171], v[200:203], v[84:87]
	v_mfma_f32_16x16x32_bf16 v[80:83], v[176:179], v[200:203], v[80:83]
	v_mfma_f32_16x16x32_bf16 v[64:67], v[176:179], v[210:213], v[64:67]
	v_mfma_f32_16x16x32_bf16 v[68:71], v[168:171], v[210:213], v[68:71]
	v_mfma_f32_16x16x32_bf16 v[116:119], v[172:175], v[188:191], v[116:119]
	v_mfma_f32_16x16x32_bf16 v[112:115], v[180:183], v[188:191], v[112:115]
	v_mfma_f32_16x16x32_bf16 v[96:99], v[180:183], v[196:199], v[96:99]
	v_mfma_f32_16x16x32_bf16 v[100:103], v[172:175], v[196:199], v[100:103]
	v_mfma_f32_16x16x32_bf16 v[84:87], v[172:175], v[206:209], v[84:87]
	v_mfma_f32_16x16x32_bf16 v[80:83], v[180:183], v[206:209], v[80:83]
	v_mfma_f32_16x16x32_bf16 v[64:67], v[180:183], v[214:217], v[64:67]
	v_mfma_f32_16x16x32_bf16 v[68:71], v[172:175], v[214:217], v[68:71]
	s_setprio 0
	s_barrier
; #define PG8_STAGE(bufoff, gbase, voff) do { _Pragma("unroll") for (int _i = 0; _i < 2; ++_i) \
;         __builtin_amdgcn_global_load_lds((const unsigned*)((const char*)(gbase) + (voff)[_i]), (PG8_LAS unsigned*)(lds + (bufoff) + ldsw + _i * 8192), 16, 0, 0); } while (0)
; #define PG8_LDA(dst, b, h) do { _Pragma("unroll") for (int m = 0; m < 4; ++m) _Pragma("unroll") for (int k = 0; k < 2; ++k) dst[m][k] = *(const PG8_LAS bf16x8*)(lds + PG8_SA(b, h) + aoff + m * 2048 + k * 1024); } while (0)
; #define PG8_LDB(dst, b, h) do { _Pragma("unroll") for (int n = 0; n < 2; ++n) _Pragma("unroll") for (int k = 0; k < 2; ++k) dst[n][k] = *(const PG8_LAS bf16x8*)(lds + PG8_SB(b, h) + boff + n * 2048 + k * 1024); } while (0)
; #define PG8_WAIT_V(n) asm volatile("s_waitcnt vmcnt(" #n ")" ::: "memory")
; #define PG8_WAIT_L(n) asm volatile("s_waitcnt lgkmcnt(" #n ")" ::: "memory")
; #define PG8_BAR __builtin_amdgcn_s_barrier()
; #define PG8_SCHED __builtin_amdgcn_sched_barrier(0)
; template <class Epi, class Sched, bool ALIGN_EPI = false, bool SP2 = false>
; __device__ __forceinline__ void gemm_phase(PG8_LAS unsigned char* lds, const Gemm g, const Sched& S, const Epi& E) {
;     ...
;             PG8_LDB(B0, 0, 0); PG8_LDB(B1, 0, 1); PG8_SCHED; PG8_LDA(At, 0, 0); PG8_STAGE(PG8_SA(1, 1), a1 + hstep, voffA);
;             PG8_WAIT_V(8); PG8_WAIT_L(0); PG8_BAR; PG8_MMA(0, 0, At, B0); PG8_MMA(0, 1, At, B1); PG8_BAR; PG8_SCHED;
;             PG8_LDA(At, 0, 1); PG8_STAGE(PG8_SB(0, 0), b2, voffB); PG8_STAGE(PG8_SB(0, 1), b2 + hstep, voffB); PG8_STAGE(PG8_SA(0, 0), a2, voffA);
;             PG8_WAIT_V(8); PG8_WAIT_L(0); PG8_BAR; PG8_MMA(1, 0, At, B0); PG8_MMA(1, 1, At, B1); PG8_BAR; PG8_SCHED;
;             PG8_LDB(B0, 1, 0); PG8_LDB(B1, 1, 1); PG8_SCHED; PG8_LDA(At, 1, 0); PG8_STAGE(PG8_SA(0, 1), a2 + hstep, voffA);
;             PG8_WAIT_V(8); PG8_WAIT_L(0); PG8_BAR; PG8_MMA(0, 0, At, B0); PG8_MMA(0, 1, At, B1); PG8_BAR; PG8_SCHED;
;             PG8_LDA(At, 1, 1); PG8_STAGE(PG8_SB(1, 0), b3, voffB); PG8_STAGE(PG8_SB(1, 1), b3 + hstep, voffB); PG8_STAGE(PG8_SA(1, 0), a3, voffA);
;             PG8_WAIT_V(8); PG8_WAIT_L(0); PG8_BAR; PG8_MMA(1, 0, At, B0); PG8_MMA(1, 1, At, B1); PG8_BAR; PG8_SCHED;
;             } else {
;             PG8_LDB(B0, 0, 0); PG8_SCHED; PG8_LDA(At, 0, 0); PG8_STAGE(PG8_SA(1, 1), a1 + hstep, voffA);
	s_add_i32 s48, s62, s15
	v_lshl_add_u64 v[218:219], v[218:219], 0, s[12:13]
	s_mov_b32 m0, s48
	ds_read_b128 v[184:187], v153 offset:49152
	ds_read_b128 v[188:191], v153 offset:50176
	ds_read_b128 v[192:195], v153 offset:51200
	ds_read_b128 v[196:199], v153 offset:52224
	ds_read_b128 v[200:203], v153 offset:53248
	ds_read_b128 v[206:209], v153 offset:54272
	ds_read_b128 v[210:213], v153 offset:55296
	ds_read_b128 v[214:217], v153 offset:56320
	global_load_lds_dwordx4 v[218:219], off
	s_add_i32 m0, s48, 0x2000
	s_add_u32 s46, s46, 0x20080
	v_lshl_add_u64 v[218:219], v[220:221], 0, s[12:13]
	s_addc_u32 s47, s47, 0
	s_add_i32 s48, s63, s15
	global_load_lds_dwordx4 v[218:219], off
	v_lshl_add_u64 v[218:219], s[46:47], 0, v[130:131]
	s_mov_b32 m0, s48
	s_nop 0
	global_load_lds_dwordx4 v[218:219], off
	v_lshl_add_u64 v[218:219], s[46:47], 0, v[134:135]
	s_add_i32 m0, s48, 0x2000
	s_nop 0
	global_load_lds_dwordx4 v[218:219], off
	s_waitcnt vmcnt(6)
	s_waitcnt lgkmcnt(0)
	s_barrier
	s_setprio 1
	s_waitcnt lgkmcnt(0)
	v_mfma_f32_16x16x32_bf16 v[60:63], v[144:147], v[184:187], v[60:63]
	v_mfma_f32_16x16x32_bf16 v[56:59], v[160:163], v[184:187], v[56:59]
	v_mfma_f32_16x16x32_bf16 v[40:43], v[160:163], v[192:195], v[40:43]
	v_mfma_f32_16x16x32_bf16 v[44:47], v[144:147], v[192:195], v[44:47]
	v_mfma_f32_16x16x32_bf16 v[28:31], v[144:147], v[200:203], v[28:31]
	v_mfma_f32_16x16x32_bf16 v[24:27], v[160:163], v[200:203], v[24:27]
	v_mfma_f32_16x16x32_bf16 v[8:11], v[160:163], v[210:213], v[8:11]
	v_mfma_f32_16x16x32_bf16 v[12:15], v[144:147], v[210:213], v[12:15]
	v_mfma_f32_16x16x32_bf16 v[60:63], v[156:159], v[188:191], v[60:63]
	v_mfma_f32_16x16x32_bf16 v[56:59], v[164:167], v[188:191], v[56:59]
	v_mfma_f32_16x16x32_bf16 v[40:43], v[164:167], v[196:199], v[40:43]
	v_mfma_f32_16x16x32_bf16 v[44:47], v[156:159], v[196:199], v[44:47]
	v_mfma_f32_16x16x32_bf16 v[28:31], v[156:159], v[206:209], v[28:31]
	v_mfma_f32_16x16x32_bf16 v[24:27], v[164:167], v[206:209], v[24:27]
	v_lshl_add_u64 v[218:219], v[222:223], 0, s[12:13]
	s_mov_b32 m0, s52
	s_nop 0
	global_load_lds_dwordx4 v[218:219], off
	v_mfma_f32_16x16x32_bf16 v[8:11], v[164:167], v[214:217], v[8:11]
	v_mfma_f32_16x16x32_bf16 v[12:15], v[156:159], v[214:217], v[12:15]
	s_setprio 0
	s_setprio 1
	v_mfma_f32_16x16x32_bf16 v[52:55], v[168:171], v[184:187], v[52:55]
	v_mfma_f32_16x16x32_bf16 v[48:51], v[176:179], v[184:187], v[48:51]
	v_mfma_f32_16x16x32_bf16 v[32:35], v[176:179], v[192:195], v[32:35]
	v_mfma_f32_16x16x32_bf16 v[36:39], v[168:171], v[192:195], v[36:39]
	v_mfma_f32_16x16x32_bf16 v[20:23], v[168:171], v[200:203], v[20:23]
	v_mfma_f32_16x16x32_bf16 v[16:19], v[176:179], v[200:203], v[16:19]
	v_mfma_f32_16x16x32_bf16 v[0:3], v[176:179], v[210:213], v[0:3]
	v_mfma_f32_16x16x32_bf16 v[4:7], v[168:171], v[210:213], v[4:7]
	v_mfma_f32_16x16x32_bf16 v[52:55], v[172:175], v[188:191], v[52:55]
	v_mfma_f32_16x16x32_bf16 v[48:51], v[180:183], v[188:191], v[48:51]
	v_mfma_f32_16x16x32_bf16 v[32:35], v[180:183], v[196:199], v[32:35]
	v_mfma_f32_16x16x32_bf16 v[36:39], v[172:175], v[196:199], v[36:39]
	v_mfma_f32_16x16x32_bf16 v[20:23], v[172:175], v[206:209], v[20:23]
	v_mfma_f32_16x16x32_bf16 v[16:19], v[180:183], v[206:209], v[16:19]
	v_lshl_add_u64 v[218:219], v[224:225], 0, s[12:13]
	s_mov_b32 m0, s53
	s_nop 0
	global_load_lds_dwordx4 v[218:219], off
	v_mfma_f32_16x16x32_bf16 v[0:3], v[180:183], v[214:217], v[0:3]
	v_mfma_f32_16x16x32_bf16 v[4:7], v[172:175], v[214:217], v[4:7]
	s_setprio 0
	s_barrier
	s_add_i32 s61, s61, 2
	s_add_u32 s44, s44, 0x100
	s_addc_u32 s45, s45, 0
	s_add_u32 s59, s59, 0x100
	s_addc_u32 s60, s60, 0
.LBB0_1816:
	ds_read_b128 v[144:147], v151
	ds_read_b128 v[156:159], v151 offset:1024
	ds_read_b128 v[160:163], v151 offset:2048
	ds_read_b128 v[164:167], v151 offset:3072
	ds_read_b128 v[168:171], v152
	ds_read_b128 v[172:175], v152 offset:1024
	ds_read_b128 v[176:179], v152 offset:2048
	ds_read_b128 v[180:183], v152 offset:3072
	s_add_u32 s46, s44, 0xfffe0080
	s_addc_u32 s47, s45, -1
	s_cmp_eq_u32 s61, 4
	s_cselect_b32 s49, s29, s47
	s_cselect_b32 s48, s41, s46
	s_cselect_b32 s47, s27, s60
	s_cselect_b32 s46, s58, s59
	v_lshl_add_u64 v[218:219], s[44:45], 0, v[136:137]
	s_add_i32 m0, s33, 0xc000
	ds_read_b128 v[184:187], v153
	ds_read_b128 v[188:191], v153 offset:1024
	ds_read_b128 v[192:195], v153 offset:2048
	ds_read_b128 v[196:199], v153 offset:3072
	ds_read_b128 v[200:203], v153 offset:4096
	ds_read_b128 v[206:209], v153 offset:5120
	ds_read_b128 v[210:213], v153 offset:6144
	ds_read_b128 v[214:217], v153 offset:7168
	global_load_lds_dwordx4 v[218:219], off
	v_lshl_add_u64 v[218:219], s[44:45], 0, v[138:139]
	s_add_i32 m0, s33, 0xe000
	s_nop 0
	global_load_lds_dwordx4 v[218:219], off
	s_waitcnt vmcnt(8)
	s_waitcnt lgkmcnt(0)
	s_barrier
; #define PG8_STAGE(bufoff, gbase, voff) do { _Pragma("unroll") for (int _i = 0; _i < 2; ++_i) \
;         __builtin_amdgcn_global_load_lds((const unsigned*)((const char*)(gbase) + (voff)[_i]), (PG8_LAS unsigned*)(lds + (bufoff) + ldsw + _i * 8192), 16, 0, 0); } while (0)
; #define PG8_LDA(dst, b, h) do { _Pragma("unroll") for (int m = 0; m < 4; ++m) _Pragma("unroll") for (int k = 0; k < 2; ++k) dst[m][k] = *(const PG8_LAS bf16x8*)(lds + PG8_SA(b, h) + aoff + m * 2048 + k * 1024); } while (0)
; #define PG8_LDB(dst, b, h) do { _Pragma("unroll") for (int n = 0; n < 2; ++n) _Pragma("unroll") for (int k = 0; k < 2; ++k) dst[n][k] = *(const PG8_LAS bf16x8*)(lds + PG8_SB(b, h) + boff + n * 2048 + k * 1024); } while (0)
; #define PG8_MMA(ai, bj, At, Bt) do { __builtin_amdgcn_s_setprio(1); _Pragma("unroll") for (int m = 0; m < 4; ++m) _Pragma("unroll") for (int n = 0; n < 2; ++n) _Pragma("unroll") for (int k = 0; k < 2; ++k) \
;         acc[ai][bj][m][n] = __builtin_amdgcn_mfma_f32_16x16x32_bf16(Bt[n][k], At[m][k], acc[ai][bj][m][n], 0, 0, 0); __builtin_amdgcn_s_setprio(0); } while (0)
; #define PG8_WAIT_V(n) asm volatile("s_waitcnt vmcnt(" #n ")" ::: "memory")
; #define PG8_WAIT_L(n) asm volatile("s_waitcnt lgkmcnt(" #n ")" ::: "memory")
; #define PG8_BAR __builtin_amdgcn_s_barrier()
; #define PG8_SCHED __builtin_amdgcn_sched_barrier(0)
; template <class Epi, class Sched, bool ALIGN_EPI = false, bool SP2 = false>
; __device__ __forceinline__ void gemm_phase(PG8_LAS unsigned char* lds, const Gemm g, const Sched& S, const Epi& E) {
;     ...
;             PG8_LDB(B0, 0, 0); PG8_LDB(B1, 0, 1); PG8_SCHED; PG8_LDA(At, 0, 0); PG8_STAGE(PG8_SA(1, 1), a1 + hstep, voffA);
;             PG8_WAIT_V(8); PG8_WAIT_L(0); PG8_BAR; PG8_MMA(0, 0, At, B0); PG8_MMA(0, 1, At, B1); PG8_BAR; PG8_SCHED;
;             PG8_LDA(At, 0, 1); PG8_STAGE(PG8_SB(0, 0), b2, voffB); PG8_STAGE(PG8_SB(0, 1), b2 + hstep, voffB); PG8_STAGE(PG8_SA(0, 0), a2, voffA);
;             PG8_WAIT_V(8); PG8_WAIT_L(0); PG8_BAR; PG8_MMA(1, 0, At, B0); PG8_MMA(1, 1, At, B1); PG8_BAR; PG8_SCHED;
	s_setprio 1
	s_waitcnt lgkmcnt(0)
	v_mfma_f32_16x16x32_bf16 v[124:127], v[144:147], v[184:187], v[124:127]
	v_mfma_f32_16x16x32_bf16 v[120:123], v[160:163], v[184:187], v[120:123]
	v_mfma_f32_16x16x32_bf16 v[104:107], v[160:163], v[192:195], v[104:107]
	v_mfma_f32_16x16x32_bf16 v[108:111], v[144:147], v[192:195], v[108:111]
	v_mfma_f32_16x16x32_bf16 v[92:95], v[144:147], v[200:203], v[92:95]
	v_mfma_f32_16x16x32_bf16 v[88:91], v[160:163], v[200:203], v[88:91]
	v_mfma_f32_16x16x32_bf16 v[72:75], v[160:163], v[210:213], v[72:75]
	v_mfma_f32_16x16x32_bf16 v[76:79], v[144:147], v[210:213], v[76:79]
	v_mfma_f32_16x16x32_bf16 v[124:127], v[156:159], v[188:191], v[124:127]
	v_mfma_f32_16x16x32_bf16 v[120:123], v[164:167], v[188:191], v[120:123]
	v_mfma_f32_16x16x32_bf16 v[104:107], v[164:167], v[196:199], v[104:107]
	v_mfma_f32_16x16x32_bf16 v[108:111], v[156:159], v[196:199], v[108:111]
	v_mfma_f32_16x16x32_bf16 v[92:95], v[156:159], v[206:209], v[92:95]
	v_mfma_f32_16x16x32_bf16 v[88:91], v[164:167], v[206:209], v[88:91]
	v_mfma_f32_16x16x32_bf16 v[72:75], v[164:167], v[214:217], v[72:75]
	v_mfma_f32_16x16x32_bf16 v[76:79], v[156:159], v[214:217], v[76:79]
	s_setprio 0
	s_setprio 1
	v_mfma_f32_16x16x32_bf16 v[116:119], v[168:171], v[184:187], v[116:119]
	v_mfma_f32_16x16x32_bf16 v[112:115], v[176:179], v[184:187], v[112:115]
	v_mfma_f32_16x16x32_bf16 v[96:99], v[176:179], v[192:195], v[96:99]
	v_mfma_f32_16x16x32_bf16 v[100:103], v[168:171], v[192:195], v[100:103]
	v_mfma_f32_16x16x32_bf16 v[84:87], v[168:171], v[200:203], v[84:87]
	v_mfma_f32_16x16x32_bf16 v[80:83], v[176:179], v[200:203], v[80:83]
	v_mfma_f32_16x16x32_bf16 v[64:67], v[176:179], v[210:213], v[64:67]
	v_mfma_f32_16x16x32_bf16 v[68:71], v[168:171], v[210:213], v[68:71]
	v_mfma_f32_16x16x32_bf16 v[116:119], v[172:175], v[188:191], v[116:119]
	v_mfma_f32_16x16x32_bf16 v[112:115], v[180:183], v[188:191], v[112:115]
	v_mfma_f32_16x16x32_bf16 v[96:99], v[180:183], v[196:199], v[96:99]
	v_mfma_f32_16x16x32_bf16 v[100:103], v[172:175], v[196:199], v[100:103]
	v_mfma_f32_16x16x32_bf16 v[84:87], v[172:175], v[206:209], v[84:87]
	v_mfma_f32_16x16x32_bf16 v[80:83], v[180:183], v[206:209], v[80:83]
	v_mfma_f32_16x16x32_bf16 v[64:67], v[180:183], v[214:217], v[64:67]
	v_mfma_f32_16x16x32_bf16 v[68:71], v[172:175], v[214:217], v[68:71]
	s_setprio 0
	s_barrier
	s_add_i32 s62, s54, s15
	v_lshl_add_u64 v[218:219], s[46:47], 0, v[130:131]
	s_mov_b32 m0, s62
	ds_read_b128 v[184:187], v153 offset:16384
	ds_read_b128 v[188:191], v153 offset:17408
	ds_read_b128 v[192:195], v153 offset:18432
	ds_read_b128 v[196:199], v153 offset:19456
	ds_read_b128 v[200:203], v153 offset:20480
	ds_read_b128 v[206:209], v153 offset:21504
	ds_read_b128 v[210:213], v153 offset:22528
	ds_read_b128 v[214:217], v153 offset:23552
	global_load_lds_dwordx4 v[218:219], off
	s_add_i32 m0, s62, 0x2000
	s_add_u32 s62, s46, 0x20000
	v_lshl_add_u64 v[220:221], s[46:47], 0, v[134:135]
	s_addc_u32 s63, s47, 0
	s_add_i32 s64, s55, s15
	global_load_lds_dwordx4 v[220:221], off
	v_lshl_add_u64 v[222:223], s[62:63], 0, v[130:131]
	s_mov_b32 m0, s64
	global_load_lds_dwordx4 v[222:223], off
	v_lshl_add_u64 v[222:223], s[62:63], 0, v[134:135]
	s_add_i32 m0, s64, 0x2000
	s_nop 0
	global_load_lds_dwordx4 v[222:223], off
	s_waitcnt vmcnt(6)
	s_waitcnt lgkmcnt(0)
	s_barrier
	s_setprio 1
	s_waitcnt lgkmcnt(0)
	v_mfma_f32_16x16x32_bf16 v[60:63], v[144:147], v[184:187], v[60:63]
	v_mfma_f32_16x16x32_bf16 v[56:59], v[160:163], v[184:187], v[56:59]
	v_mfma_f32_16x16x32_bf16 v[40:43], v[160:163], v[192:195], v[40:43]
	v_mfma_f32_16x16x32_bf16 v[44:47], v[144:147], v[192:195], v[44:47]
	v_mfma_f32_16x16x32_bf16 v[28:31], v[144:147], v[200:203], v[28:31]
	v_mfma_f32_16x16x32_bf16 v[24:27], v[160:163], v[200:203], v[24:27]
	v_mfma_f32_16x16x32_bf16 v[8:11], v[160:163], v[210:213], v[8:11]
	v_mfma_f32_16x16x32_bf16 v[12:15], v[144:147], v[210:213], v[12:15]
	v_mfma_f32_16x16x32_bf16 v[60:63], v[156:159], v[188:191], v[60:63]
	v_mfma_f32_16x16x32_bf16 v[56:59], v[164:167], v[188:191], v[56:59]
	v_mfma_f32_16x16x32_bf16 v[40:43], v[164:167], v[196:199], v[40:43]
	v_mfma_f32_16x16x32_bf16 v[44:47], v[156:159], v[196:199], v[44:47]
	v_mfma_f32_16x16x32_bf16 v[28:31], v[156:159], v[206:209], v[28:31]
	v_mfma_f32_16x16x32_bf16 v[24:27], v[164:167], v[206:209], v[24:27]
	v_lshl_add_u64 v[222:223], s[48:49], 0, v[128:129]
	s_mov_b32 m0, s33
	s_nop 0
	global_load_lds_dwordx4 v[222:223], off
	v_mfma_f32_16x16x32_bf16 v[8:11], v[164:167], v[214:217], v[8:11]
	v_mfma_f32_16x16x32_bf16 v[12:15], v[156:159], v[214:217], v[12:15]
	s_setprio 0
	s_setprio 1
	v_mfma_f32_16x16x32_bf16 v[52:55], v[168:171], v[184:187], v[52:55]
	v_mfma_f32_16x16x32_bf16 v[48:51], v[176:179], v[184:187], v[48:51]
	v_mfma_f32_16x16x32_bf16 v[32:35], v[176:179], v[192:195], v[32:35]
	v_mfma_f32_16x16x32_bf16 v[36:39], v[168:171], v[192:195], v[36:39]
	v_mfma_f32_16x16x32_bf16 v[20:23], v[168:171], v[200:203], v[20:23]
	v_mfma_f32_16x16x32_bf16 v[16:19], v[176:179], v[200:203], v[16:19]
	v_mfma_f32_16x16x32_bf16 v[0:3], v[176:179], v[210:213], v[0:3]
	v_mfma_f32_16x16x32_bf16 v[4:7], v[168:171], v[210:213], v[4:7]
	v_mfma_f32_16x16x32_bf16 v[52:55], v[172:175], v[188:191], v[52:55]
	v_mfma_f32_16x16x32_bf16 v[48:51], v[180:183], v[188:191], v[48:51]
	v_mfma_f32_16x16x32_bf16 v[32:35], v[180:183], v[196:199], v[32:35]
	v_mfma_f32_16x16x32_bf16 v[36:39], v[172:175], v[196:199], v[36:39]
	v_mfma_f32_16x16x32_bf16 v[20:23], v[172:175], v[206:209], v[20:23]
	v_mfma_f32_16x16x32_bf16 v[16:19], v[180:183], v[206:209], v[16:19]
	v_lshl_add_u64 v[224:225], s[48:49], 0, v[132:133]
	s_mov_b32 m0, s34
	s_nop 0
	global_load_lds_dwordx4 v[224:225], off
	v_mfma_f32_16x16x32_bf16 v[0:3], v[180:183], v[214:217], v[0:3]
	v_mfma_f32_16x16x32_bf16 v[4:7], v[172:175], v[214:217], v[4:7]
	s_setprio 0
	s_barrier
; #define PG8_STAGE(bufoff, gbase, voff) do { _Pragma("unroll") for (int _i = 0; _i < 2; ++_i) \
;         __builtin_amdgcn_global_load_lds((const unsigned*)((const char*)(gbase) + (voff)[_i]), (PG8_LAS unsigned*)(lds + (bufoff) + ldsw + _i * 8192), 16, 0, 0); } while (0)
; #define PG8_LDA(dst, b, h) do { _Pragma("unroll") for (int m = 0; m < 4; ++m) _Pragma("unroll") for (int k = 0; k < 2; ++k) dst[m][k] = *(const PG8_LAS bf16x8*)(lds + PG8_SA(b, h) + aoff + m * 2048 + k * 1024); } while (0)
; #define PG8_LDB(dst, b, h) do { _Pragma("unroll") for (int n = 0; n < 2; ++n) _Pragma("unroll") for (int k = 0; k < 2; ++k) dst[n][k] = *(const PG8_LAS bf16x8*)(lds + PG8_SB(b, h) + boff + n * 2048 + k * 1024); } while (0)
; #define PG8_MMA(ai, bj, At, Bt) do { __builtin_amdgcn_s_setprio(1); _Pragma("unroll") for (int m = 0; m < 4; ++m) _Pragma("unroll") for (int n = 0; n < 2; ++n) _Pragma("unroll") for (int k = 0; k < 2; ++k) \
;         acc[ai][bj][m][n] = __builtin_amdgcn_mfma_f32_16x16x32_bf16(Bt[n][k], At[m][k], acc[ai][bj][m][n], 0, 0, 0); __builtin_amdgcn_s_setprio(0); } while (0)
; #define PG8_WAIT_V(n) asm volatile("s_waitcnt vmcnt(" #n ")" ::: "memory")
; #define PG8_WAIT_L(n) asm volatile("s_waitcnt lgkmcnt(" #n ")" ::: "memory")
; #define PG8_BAR __builtin_amdgcn_s_barrier()
; #define PG8_SCHED __builtin_amdgcn_sched_barrier(0)
; template <class Epi, class Sched, bool ALIGN_EPI = false, bool SP2 = false>
; __device__ __forceinline__ void gemm_phase(PG8_LAS unsigned char* lds, const Gemm g, const Sched& S, const Epi& E) {
;     ...
;             PG8_LDB(B0, 1, 0); PG8_LDB(B1, 1, 1); PG8_SCHED; PG8_LDA(At, 1, 0); PG8_STAGE(PG8_SA(0, 1), a2 + hstep, voffA);
;             PG8_WAIT_V(8); PG8_WAIT_L(0); PG8_BAR; PG8_MMA(0, 0, At, B0); PG8_MMA(0, 1, At, B1); PG8_BAR; PG8_SCHED;
	s_add_i32 s62, 0, 0x18000
	v_add_u32_e32 v155, s62, v149
	s_add_i32 s63, 0, 0x1c000
	ds_read_b128 v[144:147], v155
	ds_read_b128 v[156:159], v155 offset:1024
	ds_read_b128 v[160:163], v155 offset:2048
	ds_read_b128 v[164:167], v155 offset:3072
	v_add_u32_e32 v155, s63, v149
	ds_read_b128 v[168:171], v155
	ds_read_b128 v[172:175], v155 offset:1024
	ds_read_b128 v[176:179], v155 offset:2048
	ds_read_b128 v[180:183], v155 offset:3072
	s_add_u32 s48, s48, 0x20000
	s_addc_u32 s49, s49, 0
	s_mov_b32 m0, s43
	v_lshl_add_u64 v[226:227], s[48:49], 0, v[128:129]
	ds_read_b128 v[184:187], v153 offset:32768
	ds_read_b128 v[188:191], v153 offset:33792
	ds_read_b128 v[192:195], v153 offset:34816
	ds_read_b128 v[196:199], v153 offset:35840
	ds_read_b128 v[200:203], v153 offset:36864
	ds_read_b128 v[206:209], v153 offset:37888
	ds_read_b128 v[210:213], v153 offset:38912
	ds_read_b128 v[214:217], v153 offset:39936
	global_load_lds_dwordx4 v[226:227], off
	v_lshl_add_u64 v[226:227], s[48:49], 0, v[132:133]
	s_mov_b32 m0, s50
	s_nop 0
	global_load_lds_dwordx4 v[226:227], off
	s_waitcnt vmcnt(8)
	s_waitcnt lgkmcnt(0)
	s_barrier
	s_setprio 1
	s_waitcnt lgkmcnt(0)
	v_mfma_f32_16x16x32_bf16 v[124:127], v[144:147], v[184:187], v[124:127]
	v_mfma_f32_16x16x32_bf16 v[120:123], v[160:163], v[184:187], v[120:123]
	v_mfma_f32_16x16x32_bf16 v[104:107], v[160:163], v[192:195], v[104:107]
	v_mfma_f32_16x16x32_bf16 v[108:111], v[144:147], v[192:195], v[108:111]
	v_mfma_f32_16x16x32_bf16 v[92:95], v[144:147], v[200:203], v[92:95]
	v_mfma_f32_16x16x32_bf16 v[88:91], v[160:163], v[200:203], v[88:91]
	v_mfma_f32_16x16x32_bf16 v[72:75], v[160:163], v[210:213], v[72:75]
	v_mfma_f32_16x16x32_bf16 v[76:79], v[144:147], v[210:213], v[76:79]
	v_mfma_f32_16x16x32_bf16 v[124:127], v[156:159], v[188:191], v[124:127]
	v_mfma_f32_16x16x32_bf16 v[120:123], v[164:167], v[188:191], v[120:123]
	v_mfma_f32_16x16x32_bf16 v[104:107], v[164:167], v[196:199], v[104:107]
	v_mfma_f32_16x16x32_bf16 v[108:111], v[156:159], v[196:199], v[108:111]
	v_mfma_f32_16x16x32_bf16 v[92:95], v[156:159], v[206:209], v[92:95]
	v_mfma_f32_16x16x32_bf16 v[88:91], v[164:167], v[206:209], v[88:91]
	v_mfma_f32_16x16x32_bf16 v[72:75], v[164:167], v[214:217], v[72:75]
	v_mfma_f32_16x16x32_bf16 v[76:79], v[156:159], v[214:217], v[76:79]
	s_setprio 0
	s_setprio 1
	v_mfma_f32_16x16x32_bf16 v[116:119], v[168:171], v[184:187], v[116:119]
	v_mfma_f32_16x16x32_bf16 v[112:115], v[176:179], v[184:187], v[112:115]
	v_mfma_f32_16x16x32_bf16 v[96:99], v[176:179], v[192:195], v[96:99]
	v_mfma_f32_16x16x32_bf16 v[100:103], v[168:171], v[192:195], v[100:103]
	v_mfma_f32_16x16x32_bf16 v[84:87], v[168:171], v[200:203], v[84:87]
	v_mfma_f32_16x16x32_bf16 v[80:83], v[176:179], v[200:203], v[80:83]
	v_mfma_f32_16x16x32_bf16 v[64:67], v[176:179], v[210:213], v[64:67]
	v_mfma_f32_16x16x32_bf16 v[68:71], v[168:171], v[210:213], v[68:71]
	v_mfma_f32_16x16x32_bf16 v[116:119], v[172:175], v[188:191], v[116:119]
	v_mfma_f32_16x16x32_bf16 v[112:115], v[180:183], v[188:191], v[112:115]
	v_mfma_f32_16x16x32_bf16 v[96:99], v[180:183], v[196:199], v[96:99]
	v_mfma_f32_16x16x32_bf16 v[100:103], v[172:175], v[196:199], v[100:103]
	v_mfma_f32_16x16x32_bf16 v[84:87], v[172:175], v[206:209], v[84:87]
	v_mfma_f32_16x16x32_bf16 v[80:83], v[180:183], v[206:209], v[80:83]
	v_mfma_f32_16x16x32_bf16 v[64:67], v[180:183], v[214:217], v[64:67]
	v_mfma_f32_16x16x32_bf16 v[68:71], v[172:175], v[214:217], v[68:71]
	s_setprio 0
	s_barrier
; #define PG8_STAGE(bufoff, gbase, voff) do { _Pragma("unroll") for (int _i = 0; _i < 2; ++_i) \
;         __builtin_amdgcn_global_load_lds((const unsigned*)((const char*)(gbase) + (voff)[_i]), (PG8_LAS unsigned*)(lds + (bufoff) + ldsw + _i * 8192), 16, 0, 0); } while (0)
; #define PG8_LDA(dst, b, h) do { _Pragma("unroll") for (int m = 0; m < 4; ++m) _Pragma("unroll") for (int k = 0; k < 2; ++k) dst[m][k] = *(const PG8_LAS bf16x8*)(lds + PG8_SA(b, h) + aoff + m * 2048 + k * 1024); } while (0)
; #define PG8_MMA(ai, bj, At, Bt) do { __builtin_amdgcn_s_setprio(1); _Pragma("unroll") for (int m = 0; m < 4; ++m) _Pragma("unroll") for (int n = 0; n < 2; ++n) _Pragma("unroll") for (int k = 0; k < 2; ++k) \
;         acc[ai][bj][m][n] = __builtin_amdgcn_mfma_f32_16x16x32_bf16(Bt[n][k], At[m][k], acc[ai][bj][m][n], 0, 0, 0); __builtin_amdgcn_s_setprio(0); } while (0)
; #define PG8_WAIT_V(n) asm volatile("s_waitcnt vmcnt(" #n ")" ::: "memory")
; #define PG8_WAIT_L(n) asm volatile("s_waitcnt lgkmcnt(" #n ")" ::: "memory")
; #define PG8_BAR __builtin_amdgcn_s_barrier()
; #define PG8_SCHED __builtin_amdgcn_sched_barrier(0)
; template <class Epi, class Sched, bool ALIGN_EPI = false, bool SP2 = false>
; __device__ __forceinline__ void gemm_phase(PG8_LAS unsigned char* lds, const Gemm g, const Sched& S, const Epi& E) {
;     ...
;             PG8_LDA(At, 1, 1); PG8_STAGE(PG8_SB(1, 0), b3, voffB); PG8_STAGE(PG8_SB(1, 1), b3 + hstep, voffB); PG8_STAGE(PG8_SA(1, 0), a3, voffA);
;             PG8_WAIT_V(8); PG8_WAIT_L(0); PG8_BAR; PG8_MMA(1, 0, At, B0); PG8_MMA(1, 1, At, B1); PG8_BAR; PG8_SCHED;
;     ...
;         if constexpr (ALIGN_EPI) { if (wr == 0) PG8_BAR; }
	s_add_i32 s48, s62, s15
	v_lshl_add_u64 v[218:219], v[218:219], 0, s[12:13]
	s_mov_b32 m0, s48
	ds_read_b128 v[184:187], v153 offset:49152
	ds_read_b128 v[188:191], v153 offset:50176
	ds_read_b128 v[192:195], v153 offset:51200
	ds_read_b128 v[196:199], v153 offset:52224
	ds_read_b128 v[200:203], v153 offset:53248
	ds_read_b128 v[206:209], v153 offset:54272
	ds_read_b128 v[210:213], v153 offset:55296
	ds_read_b128 v[214:217], v153 offset:56320
	global_load_lds_dwordx4 v[218:219], off
	s_add_i32 m0, s48, 0x2000
	s_add_u32 s46, s46, 0x20080
	v_lshl_add_u64 v[218:219], v[220:221], 0, s[12:13]
	s_addc_u32 s47, s47, 0
	s_add_i32 s48, s63, s15
	global_load_lds_dwordx4 v[218:219], off
	v_lshl_add_u64 v[218:219], s[46:47], 0, v[130:131]
	s_mov_b32 m0, s48
	s_nop 0
	global_load_lds_dwordx4 v[218:219], off
	v_lshl_add_u64 v[218:219], s[46:47], 0, v[134:135]
	s_add_i32 m0, s48, 0x2000
	s_nop 0
	global_load_lds_dwordx4 v[218:219], off
	s_waitcnt vmcnt(6)
	s_waitcnt lgkmcnt(0)
	s_barrier
	s_setprio 1
	s_waitcnt lgkmcnt(0)
	v_mfma_f32_16x16x32_bf16 v[60:63], v[144:147], v[184:187], v[60:63]
	v_mfma_f32_16x16x32_bf16 v[56:59], v[160:163], v[184:187], v[56:59]
	v_mfma_f32_16x16x32_bf16 v[40:43], v[160:163], v[192:195], v[40:43]
	v_mfma_f32_16x16x32_bf16 v[44:47], v[144:147], v[192:195], v[44:47]
	v_mfma_f32_16x16x32_bf16 v[28:31], v[144:147], v[200:203], v[28:31]
	v_mfma_f32_16x16x32_bf16 v[24:27], v[160:163], v[200:203], v[24:27]
	v_mfma_f32_16x16x32_bf16 v[8:11], v[160:163], v[210:213], v[8:11]
	v_mfma_f32_16x16x32_bf16 v[12:15], v[144:147], v[210:213], v[12:15]
	v_mfma_f32_16x16x32_bf16 v[60:63], v[156:159], v[188:191], v[60:63]
	v_mfma_f32_16x16x32_bf16 v[56:59], v[164:167], v[188:191], v[56:59]
	v_mfma_f32_16x16x32_bf16 v[40:43], v[164:167], v[196:199], v[40:43]
	v_mfma_f32_16x16x32_bf16 v[44:47], v[156:159], v[196:199], v[44:47]
	v_mfma_f32_16x16x32_bf16 v[28:31], v[156:159], v[206:209], v[28:31]
	v_mfma_f32_16x16x32_bf16 v[24:27], v[164:167], v[206:209], v[24:27]
	v_lshl_add_u64 v[218:219], v[222:223], 0, s[12:13]
	s_mov_b32 m0, s52
	s_nop 0
	global_load_lds_dwordx4 v[218:219], off
	v_mfma_f32_16x16x32_bf16 v[8:11], v[164:167], v[214:217], v[8:11]
	v_mfma_f32_16x16x32_bf16 v[12:15], v[156:159], v[214:217], v[12:15]
	s_setprio 0
	s_setprio 1
	v_mfma_f32_16x16x32_bf16 v[52:55], v[168:171], v[184:187], v[52:55]
	v_mfma_f32_16x16x32_bf16 v[48:51], v[176:179], v[184:187], v[48:51]
	v_mfma_f32_16x16x32_bf16 v[32:35], v[176:179], v[192:195], v[32:35]
	v_mfma_f32_16x16x32_bf16 v[36:39], v[168:171], v[192:195], v[36:39]
	v_mfma_f32_16x16x32_bf16 v[20:23], v[168:171], v[200:203], v[20:23]
	v_mfma_f32_16x16x32_bf16 v[16:19], v[176:179], v[200:203], v[16:19]
	v_mfma_f32_16x16x32_bf16 v[0:3], v[176:179], v[210:213], v[0:3]
	v_mfma_f32_16x16x32_bf16 v[4:7], v[168:171], v[210:213], v[4:7]
	v_mfma_f32_16x16x32_bf16 v[52:55], v[172:175], v[188:191], v[52:55]
	v_mfma_f32_16x16x32_bf16 v[48:51], v[180:183], v[188:191], v[48:51]
	v_mfma_f32_16x16x32_bf16 v[32:35], v[180:183], v[196:199], v[32:35]
	v_mfma_f32_16x16x32_bf16 v[36:39], v[172:175], v[196:199], v[36:39]
	v_mfma_f32_16x16x32_bf16 v[20:23], v[172:175], v[206:209], v[20:23]
	v_mfma_f32_16x16x32_bf16 v[16:19], v[180:183], v[206:209], v[16:19]
	v_lshl_add_u64 v[218:219], v[224:225], 0, s[12:13]
	s_mov_b32 m0, s53
	s_nop 0
	global_load_lds_dwordx4 v[218:219], off
	v_mfma_f32_16x16x32_bf16 v[0:3], v[180:183], v[214:217], v[0:3]
	v_mfma_f32_16x16x32_bf16 v[4:7], v[172:175], v[214:217], v[4:7]
	s_setprio 0
	s_barrier
	s_add_i32 s61, s61, 2
	s_add_u32 s44, s44, 0x100
	s_addc_u32 s45, s45, 0
	s_add_u32 s59, s59, 0x100
	s_addc_u32 s60, s60, 0
	s_cmp_gt_u32 s61, 5
	s_cbranch_scc0 .LBB0_1816
	s_and_b64 vcc, exec, s[24:25]
	s_cbranch_vccz .LBB0_1819
	s_barrier

; #define PG8_STAGE(bufoff, gbase, voff) do { _Pragma("unroll") for (int _i = 0; _i < 2; ++_i) \
;         __builtin_amdgcn_global_load_lds((const unsigned*)((const char*)(gbase) + (voff)[_i]), (PG8_LAS unsigned*)(lds + (bufoff) + ldsw + _i * 8192), 16, 0, 0); } while (0)
; #define PG8_LDA(dst, b, h) do { _Pragma("unroll") for (int m = 0; m < 4; ++m) _Pragma("unroll") for (int k = 0; k < 2; ++k) dst[m][k] = *(const PG8_LAS bf16x8*)(lds + PG8_SA(b, h) + aoff + m * 2048 + k * 1024); } while (0)
; #define PG8_LDB(dst, b, h) do { _Pragma("unroll") for (int n = 0; n < 2; ++n) _Pragma("unroll") for (int k = 0; k < 2; ++k) dst[n][k] = *(const PG8_LAS bf16x8*)(lds + PG8_SB(b, h) + boff + n * 2048 + k * 1024); } while (0)
; #define PG8_WAIT_V(n) asm volatile("s_waitcnt vmcnt(" #n ")" ::: "memory")
; #define PG8_WAIT_L(n) asm volatile("s_waitcnt lgkmcnt(" #n ")" ::: "memory")
; #define PG8_BAR __builtin_amdgcn_s_barrier()
; #define PG8_SCHED __builtin_amdgcn_sched_barrier(0)
; template <class Epi, class Sched, bool ALIGN_EPI = false, bool SP2 = false>
; __device__ __forceinline__ void gemm_phase(PG8_LAS unsigned char* lds, const Gemm g, const Sched& S, const Epi& E) {
;     ...
;         const bool has_next = S.next(ui + 1, nxt);
;         const char* nA = has_next ? (const char*)g.A + (size_t)nxt.pm * tstep : cA; const char* nB = has_next ? (const char*)g.Bt + (size_t)nxt.pn * tstep : cB;
;         for (int t = 0; t < nt; t += 2) {
;             const bool last = (t == nt - 2);
;             const char* a1 = cA + (size_t)(t + 1) * kstep;
;             const char* a2 = last ? nA : cA + (size_t)(t + 2) * kstep; const char* b2 = last ? nB : cB + (size_t)(t + 2) * kstep;
;             const char* a3 = a2 + kstep; const char* b3 = b2 + kstep;
;             if (last && has_next) S.a_ready(nxt);
;             if constexpr (SP2) {
;             PG8_LDB(B0, 0, 0); PG8_LDB(B1, 0, 1); PG8_SCHED; PG8_LDA(At, 0, 0); PG8_STAGE(PG8_SA(1, 1), a1 + hstep, voffA);
;             PG8_WAIT_V(8); PG8_WAIT_L(0); PG8_BAR; PG8_MMA(0, 0, At, B0); PG8_MMA(0, 1, At, B1); PG8_BAR; PG8_SCHED;
;             PG8_LDA(At, 0, 1); PG8_STAGE(PG8_SB(0, 0), b2, voffB); PG8_STAGE(PG8_SB(0, 1), b2 + hstep, voffB); PG8_STAGE(PG8_SA(0, 0), a2, voffA);
;             PG8_WAIT_V(8); PG8_WAIT_L(0); PG8_BAR; PG8_MMA(1, 0, At, B0); PG8_MMA(1, 1, At, B1); PG8_BAR; PG8_SCHED;
.LBB0_1899:
	s_ashr_i32 s25, s24, 31
	s_lshl_b64 s[26:27], s[24:25], 19
	s_add_u32 s26, s22, s26
	s_addc_u32 s27, s23, s27
	s_and_b64 s[28:29], s[4:5], exec
	s_cselect_b32 s25, s27, s39
	s_cselect_b32 s53, s26, s38
	s_ashr_i32 s13, s12, 31
	s_lshl_b64 s[28:29], s[12:13], 19
	s_add_u32 s28, s3, s28
	s_addc_u32 s29, s14, s29
	s_and_b64 s[42:43], s[4:5], exec
	s_cselect_b32 s13, s29, s41
	s_cselect_b32 s54, s28, s40
	s_add_u32 s38, s38, 0x40080
	s_addc_u32 s39, s39, 0
	s_add_u32 s55, s40, 0x100
	s_addc_u32 s56, s41, 0
	s_mov_b32 s57, -2
	ds_read_b128 v[144:147], v155
	ds_read_b128 v[148:151], v155 offset:1024
	ds_read_b128 v[160:163], v155 offset:2048
	ds_read_b128 v[164:167], v155 offset:3072
	ds_read_b128 v[168:171], v156
	ds_read_b128 v[172:175], v156 offset:1024
	ds_read_b128 v[176:179], v156 offset:2048
	ds_read_b128 v[180:183], v156 offset:3072
	s_add_u32 s40, s38, 0xfffc0080
	s_addc_u32 s41, s39, -1
	s_cmp_eq_u32 s57, 12
	s_cselect_b32 s43, s25, s41
	s_cselect_b32 s42, s53, s40
	s_cselect_b32 s41, s13, s56
	s_cselect_b32 s40, s54, s55
	v_lshl_add_u64 v[218:219], s[38:39], 0, v[136:137]
	s_add_i32 m0, s34, 0xc000
	ds_read_b128 v[184:187], v157
	ds_read_b128 v[188:191], v157 offset:1024
	ds_read_b128 v[192:195], v157 offset:2048
	ds_read_b128 v[196:199], v157 offset:3072
	ds_read_b128 v[200:203], v157 offset:4096
	ds_read_b128 v[206:209], v157 offset:5120
	ds_read_b128 v[210:213], v157 offset:6144
	ds_read_b128 v[214:217], v157 offset:7168
	global_load_lds_dwordx4 v[218:219], off
	v_lshl_add_u64 v[218:219], s[38:39], 0, v[138:139]
	s_add_i32 m0, s34, 0xe000
	s_nop 0
	global_load_lds_dwordx4 v[218:219], off
	s_waitcnt vmcnt(8)
	s_waitcnt lgkmcnt(0)
	s_barrier
	s_setprio 1
	s_waitcnt lgkmcnt(0)
	v_mfma_f32_16x16x32_bf16 v[124:127], v[144:147], v[184:187], 0
	v_mfma_f32_16x16x32_bf16 v[120:123], v[160:163], v[184:187], 0
	v_mfma_f32_16x16x32_bf16 v[104:107], v[160:163], v[192:195], 0
	v_mfma_f32_16x16x32_bf16 v[108:111], v[144:147], v[192:195], 0
	v_mfma_f32_16x16x32_bf16 v[92:95], v[144:147], v[200:203], 0
	v_mfma_f32_16x16x32_bf16 v[88:91], v[160:163], v[200:203], 0
	v_mfma_f32_16x16x32_bf16 v[72:75], v[160:163], v[210:213], 0
	v_mfma_f32_16x16x32_bf16 v[76:79], v[144:147], v[210:213], 0
	v_mfma_f32_16x16x32_bf16 v[124:127], v[148:151], v[188:191], v[124:127]
	v_mfma_f32_16x16x32_bf16 v[120:123], v[164:167], v[188:191], v[120:123]
	v_mfma_f32_16x16x32_bf16 v[104:107], v[164:167], v[196:199], v[104:107]
	v_mfma_f32_16x16x32_bf16 v[108:111], v[148:151], v[196:199], v[108:111]
	v_mfma_f32_16x16x32_bf16 v[92:95], v[148:151], v[206:209], v[92:95]
	v_mfma_f32_16x16x32_bf16 v[88:91], v[164:167], v[206:209], v[88:91]
	v_mfma_f32_16x16x32_bf16 v[72:75], v[164:167], v[214:217], v[72:75]
	v_mfma_f32_16x16x32_bf16 v[76:79], v[148:151], v[214:217], v[76:79]
	s_setprio 0
	s_setprio 1
	v_mfma_f32_16x16x32_bf16 v[116:119], v[168:171], v[184:187], 0
	v_mfma_f32_16x16x32_bf16 v[112:115], v[176:179], v[184:187], 0
	v_mfma_f32_16x16x32_bf16 v[96:99], v[176:179], v[192:195], 0
	v_mfma_f32_16x16x32_bf16 v[100:103], v[168:171], v[192:195], 0
	v_mfma_f32_16x16x32_bf16 v[84:87], v[168:171], v[200:203], 0
	v_mfma_f32_16x16x32_bf16 v[80:83], v[176:179], v[200:203], 0
	v_mfma_f32_16x16x32_bf16 v[64:67], v[176:179], v[210:213], 0
	v_mfma_f32_16x16x32_bf16 v[68:71], v[168:171], v[210:213], 0
	v_mfma_f32_16x16x32_bf16 v[116:119], v[172:175], v[188:191], v[116:119]
	v_mfma_f32_16x16x32_bf16 v[112:115], v[180:183], v[188:191], v[112:115]
	v_mfma_f32_16x16x32_bf16 v[96:99], v[180:183], v[196:199], v[96:99]
	v_mfma_f32_16x16x32_bf16 v[100:103], v[172:175], v[196:199], v[100:103]
	v_mfma_f32_16x16x32_bf16 v[84:87], v[172:175], v[206:209], v[84:87]
	v_mfma_f32_16x16x32_bf16 v[80:83], v[180:183], v[206:209], v[80:83]
	v_mfma_f32_16x16x32_bf16 v[64:67], v[180:183], v[214:217], v[64:67]
	v_mfma_f32_16x16x32_bf16 v[68:71], v[172:175], v[214:217], v[68:71]
	s_setprio 0
	s_barrier
	s_add_i32 s58, s49, s15
	v_lshl_add_u64 v[218:219], s[40:41], 0, v[132:133]
	s_mov_b32 m0, s58
	ds_read_b128 v[184:187], v157 offset:16384
	ds_read_b128 v[188:191], v157 offset:17408
	ds_read_b128 v[192:195], v157 offset:18432
	ds_read_b128 v[196:199], v157 offset:19456
	ds_read_b128 v[200:203], v157 offset:20480
	ds_read_b128 v[206:209], v157 offset:21504
	ds_read_b128 v[210:213], v157 offset:22528
	ds_read_b128 v[214:217], v157 offset:23552
	global_load_lds_dwordx4 v[218:219], off
	s_add_i32 m0, s58, 0x2000
	s_add_u32 s58, s40, 0x40000
	v_lshl_add_u64 v[220:221], s[40:41], 0, v[128:129]
	s_addc_u32 s59, s41, 0
	s_add_i32 s60, s50, s15
	global_load_lds_dwordx4 v[220:221], off
	v_lshl_add_u64 v[222:223], s[58:59], 0, v[132:133]
	s_mov_b32 m0, s60
	global_load_lds_dwordx4 v[222:223], off
	v_lshl_add_u64 v[222:223], s[58:59], 0, v[128:129]
	s_add_i32 m0, s60, 0x2000
	s_nop 0
	global_load_lds_dwordx4 v[222:223], off
	s_waitcnt vmcnt(6)
	s_waitcnt lgkmcnt(0)
	s_barrier
; #define PG8_STAGE(bufoff, gbase, voff) do { _Pragma("unroll") for (int _i = 0; _i < 2; ++_i) \
;         __builtin_amdgcn_global_load_lds((const unsigned*)((const char*)(gbase) + (voff)[_i]), (PG8_LAS unsigned*)(lds + (bufoff) + ldsw + _i * 8192), 16, 0, 0); } while (0)
; #define PG8_LDA(dst, b, h) do { _Pragma("unroll") for (int m = 0; m < 4; ++m) _Pragma("unroll") for (int k = 0; k < 2; ++k) dst[m][k] = *(const PG8_LAS bf16x8*)(lds + PG8_SA(b, h) + aoff + m * 2048 + k * 1024); } while (0)
; #define PG8_LDB(dst, b, h) do { _Pragma("unroll") for (int n = 0; n < 2; ++n) _Pragma("unroll") for (int k = 0; k < 2; ++k) dst[n][k] = *(const PG8_LAS bf16x8*)(lds + PG8_SB(b, h) + boff + n * 2048 + k * 1024); } while (0)
; #define PG8_MMA(ai, bj, At, Bt) do { __builtin_amdgcn_s_setprio(1); _Pragma("unroll") for (int m = 0; m < 4; ++m) _Pragma("unroll") for (int n = 0; n < 2; ++n) _Pragma("unroll") for (int k = 0; k < 2; ++k) \
;         acc[ai][bj][m][n] = __builtin_amdgcn_mfma_f32_16x16x32_bf16(Bt[n][k], At[m][k], acc[ai][bj][m][n], 0, 0, 0); __builtin_amdgcn_s_setprio(0); } while (0)
; #define PG8_WAIT_V(n) asm volatile("s_waitcnt vmcnt(" #n ")" ::: "memory")
; #define PG8_WAIT_L(n) asm volatile("s_waitcnt lgkmcnt(" #n ")" ::: "memory")
; #define PG8_BAR __builtin_amdgcn_s_barrier()
; #define PG8_SCHED __builtin_amdgcn_sched_barrier(0)
; template <class Epi, class Sched, bool ALIGN_EPI = false, bool SP2 = false>
; __device__ __forceinline__ void gemm_phase(PG8_LAS unsigned char* lds, const Gemm g, const Sched& S, const Epi& E) {
;     ...
;             PG8_LDA(At, 0, 1); PG8_STAGE(PG8_SB(0, 0), b2, voffB); PG8_STAGE(PG8_SB(0, 1), b2 + hstep, voffB); PG8_STAGE(PG8_SA(0, 0), a2, voffA);
;             PG8_WAIT_V(8); PG8_WAIT_L(0); PG8_BAR; PG8_MMA(1, 0, At, B0); PG8_MMA(1, 1, At, B1); PG8_BAR; PG8_SCHED;
;             PG8_LDB(B0, 1, 0); PG8_LDB(B1, 1, 1); PG8_SCHED; PG8_LDA(At, 1, 0); PG8_STAGE(PG8_SA(0, 1), a2 + hstep, voffA);
;             PG8_WAIT_V(8); PG8_WAIT_L(0); PG8_BAR; PG8_MMA(0, 0, At, B0); PG8_MMA(0, 1, At, B1); PG8_BAR; PG8_SCHED;
	s_setprio 1
	s_waitcnt lgkmcnt(0)
	v_mfma_f32_16x16x32_bf16 v[60:63], v[144:147], v[184:187], 0
	v_mfma_f32_16x16x32_bf16 v[56:59], v[160:163], v[184:187], 0
	v_mfma_f32_16x16x32_bf16 v[40:43], v[160:163], v[192:195], 0
	v_mfma_f32_16x16x32_bf16 v[44:47], v[144:147], v[192:195], 0
	v_mfma_f32_16x16x32_bf16 v[28:31], v[144:147], v[200:203], 0
	v_mfma_f32_16x16x32_bf16 v[24:27], v[160:163], v[200:203], 0
	v_mfma_f32_16x16x32_bf16 v[8:11], v[160:163], v[210:213], 0
	v_mfma_f32_16x16x32_bf16 v[12:15], v[144:147], v[210:213], 0
	v_mfma_f32_16x16x32_bf16 v[60:63], v[148:151], v[188:191], v[60:63]
	v_mfma_f32_16x16x32_bf16 v[56:59], v[164:167], v[188:191], v[56:59]
	v_mfma_f32_16x16x32_bf16 v[40:43], v[164:167], v[196:199], v[40:43]
	v_mfma_f32_16x16x32_bf16 v[44:47], v[148:151], v[196:199], v[44:47]
	v_mfma_f32_16x16x32_bf16 v[28:31], v[148:151], v[206:209], v[28:31]
	v_mfma_f32_16x16x32_bf16 v[24:27], v[164:167], v[206:209], v[24:27]
	v_lshl_add_u64 v[222:223], s[42:43], 0, v[134:135]
	s_mov_b32 m0, s34
	s_nop 0
	global_load_lds_dwordx4 v[222:223], off
	v_mfma_f32_16x16x32_bf16 v[8:11], v[164:167], v[214:217], v[8:11]
	v_mfma_f32_16x16x32_bf16 v[12:15], v[148:151], v[214:217], v[12:15]
	s_setprio 0
	s_setprio 1
	v_mfma_f32_16x16x32_bf16 v[52:55], v[168:171], v[184:187], 0
	v_mfma_f32_16x16x32_bf16 v[48:51], v[176:179], v[184:187], 0
	v_mfma_f32_16x16x32_bf16 v[32:35], v[176:179], v[192:195], 0
	v_mfma_f32_16x16x32_bf16 v[36:39], v[168:171], v[192:195], 0
	v_mfma_f32_16x16x32_bf16 v[20:23], v[168:171], v[200:203], 0
	v_mfma_f32_16x16x32_bf16 v[16:19], v[176:179], v[200:203], 0
	v_mfma_f32_16x16x32_bf16 v[0:3], v[176:179], v[210:213], 0
	v_mfma_f32_16x16x32_bf16 v[4:7], v[168:171], v[210:213], 0
	v_mfma_f32_16x16x32_bf16 v[52:55], v[172:175], v[188:191], v[52:55]
	v_mfma_f32_16x16x32_bf16 v[48:51], v[180:183], v[188:191], v[48:51]
	v_mfma_f32_16x16x32_bf16 v[32:35], v[180:183], v[196:199], v[32:35]
	v_mfma_f32_16x16x32_bf16 v[36:39], v[172:175], v[196:199], v[36:39]
	v_mfma_f32_16x16x32_bf16 v[20:23], v[172:175], v[206:209], v[20:23]
	v_mfma_f32_16x16x32_bf16 v[16:19], v[180:183], v[206:209], v[16:19]
	v_lshl_add_u64 v[224:225], s[42:43], 0, v[130:131]
	s_mov_b32 m0, s37
	s_nop 0
	global_load_lds_dwordx4 v[224:225], off
	v_mfma_f32_16x16x32_bf16 v[0:3], v[180:183], v[214:217], v[0:3]
	v_mfma_f32_16x16x32_bf16 v[4:7], v[172:175], v[214:217], v[4:7]
	s_setprio 0
	s_barrier
	s_add_i32 s58, 0, 0x18000
	v_add_u32_e32 v159, s58, v153
	s_add_i32 s59, 0, 0x1c000
	ds_read_b128 v[144:147], v159
	ds_read_b128 v[148:151], v159 offset:1024
	ds_read_b128 v[160:163], v159 offset:2048
	ds_read_b128 v[164:167], v159 offset:3072
	v_add_u32_e32 v159, s59, v153
	ds_read_b128 v[168:171], v159
	ds_read_b128 v[172:175], v159 offset:1024
	ds_read_b128 v[176:179], v159 offset:2048
	ds_read_b128 v[180:183], v159 offset:3072
	s_add_u32 s42, s42, 0x40000
	s_addc_u32 s43, s43, 0
	s_mov_b32 m0, s44
	v_lshl_add_u64 v[226:227], s[42:43], 0, v[134:135]
	ds_read_b128 v[184:187], v157 offset:32768
	ds_read_b128 v[188:191], v157 offset:33792
	ds_read_b128 v[192:195], v157 offset:34816
	ds_read_b128 v[196:199], v157 offset:35840
	ds_read_b128 v[200:203], v157 offset:36864
	ds_read_b128 v[206:209], v157 offset:37888
	ds_read_b128 v[210:213], v157 offset:38912
	ds_read_b128 v[214:217], v157 offset:39936
	global_load_lds_dwordx4 v[226:227], off
	v_lshl_add_u64 v[226:227], s[42:43], 0, v[130:131]
	s_mov_b32 m0, s45
	s_nop 0
	global_load_lds_dwordx4 v[226:227], off
	s_waitcnt vmcnt(8)
	s_waitcnt lgkmcnt(0)
	s_barrier
	s_setprio 1
	s_waitcnt lgkmcnt(0)
	v_mfma_f32_16x16x32_bf16 v[124:127], v[144:147], v[184:187], v[124:127]
	v_mfma_f32_16x16x32_bf16 v[120:123], v[160:163], v[184:187], v[120:123]
	v_mfma_f32_16x16x32_bf16 v[104:107], v[160:163], v[192:195], v[104:107]
	v_mfma_f32_16x16x32_bf16 v[108:111], v[144:147], v[192:195], v[108:111]
	v_mfma_f32_16x16x32_bf16 v[92:95], v[144:147], v[200:203], v[92:95]
	v_mfma_f32_16x16x32_bf16 v[88:91], v[160:163], v[200:203], v[88:91]
	v_mfma_f32_16x16x32_bf16 v[72:75], v[160:163], v[210:213], v[72:75]
	v_mfma_f32_16x16x32_bf16 v[76:79], v[144:147], v[210:213], v[76:79]
	v_mfma_f32_16x16x32_bf16 v[124:127], v[148:151], v[188:191], v[124:127]
	v_mfma_f32_16x16x32_bf16 v[120:123], v[164:167], v[188:191], v[120:123]
	v_mfma_f32_16x16x32_bf16 v[104:107], v[164:167], v[196:199], v[104:107]
	v_mfma_f32_16x16x32_bf16 v[108:111], v[148:151], v[196:199], v[108:111]
	v_mfma_f32_16x16x32_bf16 v[92:95], v[148:151], v[206:209], v[92:95]
	v_mfma_f32_16x16x32_bf16 v[88:91], v[164:167], v[206:209], v[88:91]
	v_mfma_f32_16x16x32_bf16 v[72:75], v[164:167], v[214:217], v[72:75]
	v_mfma_f32_16x16x32_bf16 v[76:79], v[148:151], v[214:217], v[76:79]
	s_setprio 0
	s_setprio 1
	v_mfma_f32_16x16x32_bf16 v[116:119], v[168:171], v[184:187], v[116:119]
	v_mfma_f32_16x16x32_bf16 v[112:115], v[176:179], v[184:187], v[112:115]
	v_mfma_f32_16x16x32_bf16 v[96:99], v[176:179], v[192:195], v[96:99]
	v_mfma_f32_16x16x32_bf16 v[100:103], v[168:171], v[192:195], v[100:103]
	v_mfma_f32_16x16x32_bf16 v[84:87], v[168:171], v[200:203], v[84:87]
	v_mfma_f32_16x16x32_bf16 v[80:83], v[176:179], v[200:203], v[80:83]
	v_mfma_f32_16x16x32_bf16 v[64:67], v[176:179], v[210:213], v[64:67]
	v_mfma_f32_16x16x32_bf16 v[68:71], v[168:171], v[210:213], v[68:71]
	v_mfma_f32_16x16x32_bf16 v[116:119], v[172:175], v[188:191], v[116:119]
	v_mfma_f32_16x16x32_bf16 v[112:115], v[180:183], v[188:191], v[112:115]
	v_mfma_f32_16x16x32_bf16 v[96:99], v[180:183], v[196:199], v[96:99]
	v_mfma_f32_16x16x32_bf16 v[100:103], v[172:175], v[196:199], v[100:103]
	v_mfma_f32_16x16x32_bf16 v[84:87], v[172:175], v[206:209], v[84:87]
	v_mfma_f32_16x16x32_bf16 v[80:83], v[180:183], v[206:209], v[80:83]
	v_mfma_f32_16x16x32_bf16 v[64:67], v[180:183], v[214:217], v[64:67]
	v_mfma_f32_16x16x32_bf16 v[68:71], v[172:175], v[214:217], v[68:71]
	s_setprio 0
	s_barrier
; #define PG8_STAGE(bufoff, gbase, voff) do { _Pragma("unroll") for (int _i = 0; _i < 2; ++_i) \
;         __builtin_amdgcn_global_load_lds((const unsigned*)((const char*)(gbase) + (voff)[_i]), (PG8_LAS unsigned*)(lds + (bufoff) + ldsw + _i * 8192), 16, 0, 0); } while (0)
; #define PG8_LDA(dst, b, h) do { _Pragma("unroll") for (int m = 0; m < 4; ++m) _Pragma("unroll") for (int k = 0; k < 2; ++k) dst[m][k] = *(const PG8_LAS bf16x8*)(lds + PG8_SA(b, h) + aoff + m * 2048 + k * 1024); } while (0)
; #define PG8_LDB(dst, b, h) do { _Pragma("unroll") for (int n = 0; n < 2; ++n) _Pragma("unroll") for (int k = 0; k < 2; ++k) dst[n][k] = *(const PG8_LAS bf16x8*)(lds + PG8_SB(b, h) + boff + n * 2048 + k * 1024); } while (0)
; #define PG8_WAIT_V(n) asm volatile("s_waitcnt vmcnt(" #n ")" ::: "memory")
; #define PG8_WAIT_L(n) asm volatile("s_waitcnt lgkmcnt(" #n ")" ::: "memory")
; #define PG8_BAR __builtin_amdgcn_s_barrier()
; #define PG8_SCHED __builtin_amdgcn_sched_barrier(0)
; template <class Epi, class Sched, bool ALIGN_EPI = false, bool SP2 = false>
; __device__ __forceinline__ void gemm_phase(PG8_LAS unsigned char* lds, const Gemm g, const Sched& S, const Epi& E) {
;     ...
;             PG8_LDB(B0, 0, 0); PG8_LDB(B1, 0, 1); PG8_SCHED; PG8_LDA(At, 0, 0); PG8_STAGE(PG8_SA(1, 1), a1 + hstep, voffA);
;             PG8_WAIT_V(8); PG8_WAIT_L(0); PG8_BAR; PG8_MMA(0, 0, At, B0); PG8_MMA(0, 1, At, B1); PG8_BAR; PG8_SCHED;
;             PG8_LDA(At, 0, 1); PG8_STAGE(PG8_SB(0, 0), b2, voffB); PG8_STAGE(PG8_SB(0, 1), b2 + hstep, voffB); PG8_STAGE(PG8_SA(0, 0), a2, voffA);
;             PG8_WAIT_V(8); PG8_WAIT_L(0); PG8_BAR; PG8_MMA(1, 0, At, B0); PG8_MMA(1, 1, At, B1); PG8_BAR; PG8_SCHED;
;             PG8_LDB(B0, 1, 0); PG8_LDB(B1, 1, 1); PG8_SCHED; PG8_LDA(At, 1, 0); PG8_STAGE(PG8_SA(0, 1), a2 + hstep, voffA);
;             PG8_WAIT_V(8); PG8_WAIT_L(0); PG8_BAR; PG8_MMA(0, 0, At, B0); PG8_MMA(0, 1, At, B1); PG8_BAR; PG8_SCHED;
;             PG8_LDA(At, 1, 1); PG8_STAGE(PG8_SB(1, 0), b3, voffB); PG8_STAGE(PG8_SB(1, 1), b3 + hstep, voffB); PG8_STAGE(PG8_SA(1, 0), a3, voffA);
;             PG8_WAIT_V(8); PG8_WAIT_L(0); PG8_BAR; PG8_MMA(1, 0, At, B0); PG8_MMA(1, 1, At, B1); PG8_BAR; PG8_SCHED;
;             } else {
;             PG8_LDB(B0, 0, 0); PG8_SCHED; PG8_LDA(At, 0, 0); PG8_STAGE(PG8_SA(1, 1), a1 + hstep, voffA);
	s_add_i32 s42, s58, s15
	v_lshl_add_u64 v[218:219], v[218:219], 0, s[8:9]
	s_mov_b32 m0, s42
	ds_read_b128 v[184:187], v157 offset:49152
	ds_read_b128 v[188:191], v157 offset:50176
	ds_read_b128 v[192:195], v157 offset:51200
	ds_read_b128 v[196:199], v157 offset:52224
	ds_read_b128 v[200:203], v157 offset:53248
	ds_read_b128 v[206:209], v157 offset:54272
	ds_read_b128 v[210:213], v157 offset:55296
	ds_read_b128 v[214:217], v157 offset:56320
	global_load_lds_dwordx4 v[218:219], off
	s_add_i32 m0, s42, 0x2000
	s_add_u32 s40, s40, 0x40080
	v_lshl_add_u64 v[218:219], v[220:221], 0, s[8:9]
	s_addc_u32 s41, s41, 0
	s_add_i32 s42, s59, s15
	global_load_lds_dwordx4 v[218:219], off
	v_lshl_add_u64 v[218:219], s[40:41], 0, v[132:133]
	s_mov_b32 m0, s42
	s_nop 0
	global_load_lds_dwordx4 v[218:219], off
	v_lshl_add_u64 v[218:219], s[40:41], 0, v[128:129]
	s_add_i32 m0, s42, 0x2000
	s_nop 0
	global_load_lds_dwordx4 v[218:219], off
	s_waitcnt vmcnt(6)
	s_waitcnt lgkmcnt(0)
	s_barrier
	s_setprio 1
	s_waitcnt lgkmcnt(0)
	v_mfma_f32_16x16x32_bf16 v[60:63], v[144:147], v[184:187], v[60:63]
	v_mfma_f32_16x16x32_bf16 v[56:59], v[160:163], v[184:187], v[56:59]
	v_mfma_f32_16x16x32_bf16 v[40:43], v[160:163], v[192:195], v[40:43]
	v_mfma_f32_16x16x32_bf16 v[44:47], v[144:147], v[192:195], v[44:47]
	v_mfma_f32_16x16x32_bf16 v[28:31], v[144:147], v[200:203], v[28:31]
	v_mfma_f32_16x16x32_bf16 v[24:27], v[160:163], v[200:203], v[24:27]
	v_mfma_f32_16x16x32_bf16 v[8:11], v[160:163], v[210:213], v[8:11]
	v_mfma_f32_16x16x32_bf16 v[12:15], v[144:147], v[210:213], v[12:15]
	v_mfma_f32_16x16x32_bf16 v[60:63], v[148:151], v[188:191], v[60:63]
	v_mfma_f32_16x16x32_bf16 v[56:59], v[164:167], v[188:191], v[56:59]
	v_mfma_f32_16x16x32_bf16 v[40:43], v[164:167], v[196:199], v[40:43]
	v_mfma_f32_16x16x32_bf16 v[44:47], v[148:151], v[196:199], v[44:47]
	v_mfma_f32_16x16x32_bf16 v[28:31], v[148:151], v[206:209], v[28:31]
	v_mfma_f32_16x16x32_bf16 v[24:27], v[164:167], v[206:209], v[24:27]
	v_lshl_add_u64 v[218:219], v[222:223], 0, s[8:9]
	s_mov_b32 m0, s47
	s_nop 0
	global_load_lds_dwordx4 v[218:219], off
	v_mfma_f32_16x16x32_bf16 v[8:11], v[164:167], v[214:217], v[8:11]
	v_mfma_f32_16x16x32_bf16 v[12:15], v[148:151], v[214:217], v[12:15]
	s_setprio 0
	s_setprio 1
	v_mfma_f32_16x16x32_bf16 v[52:55], v[168:171], v[184:187], v[52:55]
	v_mfma_f32_16x16x32_bf16 v[48:51], v[176:179], v[184:187], v[48:51]
	v_mfma_f32_16x16x32_bf16 v[32:35], v[176:179], v[192:195], v[32:35]
	v_mfma_f32_16x16x32_bf16 v[36:39], v[168:171], v[192:195], v[36:39]
	v_mfma_f32_16x16x32_bf16 v[20:23], v[168:171], v[200:203], v[20:23]
	v_mfma_f32_16x16x32_bf16 v[16:19], v[176:179], v[200:203], v[16:19]
	v_mfma_f32_16x16x32_bf16 v[0:3], v[176:179], v[210:213], v[0:3]
	v_mfma_f32_16x16x32_bf16 v[4:7], v[168:171], v[210:213], v[4:7]
	v_mfma_f32_16x16x32_bf16 v[52:55], v[172:175], v[188:191], v[52:55]
	v_mfma_f32_16x16x32_bf16 v[48:51], v[180:183], v[188:191], v[48:51]
	v_mfma_f32_16x16x32_bf16 v[32:35], v[180:183], v[196:199], v[32:35]
	v_mfma_f32_16x16x32_bf16 v[36:39], v[172:175], v[196:199], v[36:39]
	v_mfma_f32_16x16x32_bf16 v[20:23], v[172:175], v[206:209], v[20:23]
	v_mfma_f32_16x16x32_bf16 v[16:19], v[180:183], v[206:209], v[16:19]
	v_lshl_add_u64 v[218:219], v[224:225], 0, s[8:9]
	s_mov_b32 m0, s48
	s_nop 0
	global_load_lds_dwordx4 v[218:219], off
	v_mfma_f32_16x16x32_bf16 v[0:3], v[180:183], v[214:217], v[0:3]
	v_mfma_f32_16x16x32_bf16 v[4:7], v[172:175], v[214:217], v[4:7]
	s_setprio 0
	s_barrier
	s_add_i32 s57, s57, 2
	s_add_u32 s38, s38, 0x100
	s_addc_u32 s39, s39, 0
	s_add_u32 s55, s55, 0x100
	s_addc_u32 s56, s56, 0
.LBB0_1900:
	ds_read_b128 v[144:147], v155
	ds_read_b128 v[148:151], v155 offset:1024
	ds_read_b128 v[160:163], v155 offset:2048
	ds_read_b128 v[164:167], v155 offset:3072
	ds_read_b128 v[168:171], v156
	ds_read_b128 v[172:175], v156 offset:1024
	ds_read_b128 v[176:179], v156 offset:2048
	ds_read_b128 v[180:183], v156 offset:3072
	s_add_u32 s40, s38, 0xfffc0080
	s_addc_u32 s41, s39, -1
	s_cmp_eq_u32 s57, 12
	s_cselect_b32 s43, s25, s41
	s_cselect_b32 s42, s53, s40
	s_cselect_b32 s41, s13, s56
	s_cselect_b32 s40, s54, s55
	v_lshl_add_u64 v[218:219], s[38:39], 0, v[136:137]
	s_add_i32 m0, s34, 0xc000
	ds_read_b128 v[184:187], v157
	ds_read_b128 v[188:191], v157 offset:1024
	ds_read_b128 v[192:195], v157 offset:2048
	ds_read_b128 v[196:199], v157 offset:3072
	ds_read_b128 v[200:203], v157 offset:4096
	ds_read_b128 v[206:209], v157 offset:5120
	ds_read_b128 v[210:213], v157 offset:6144
	ds_read_b128 v[214:217], v157 offset:7168
	global_load_lds_dwordx4 v[218:219], off
	v_lshl_add_u64 v[218:219], s[38:39], 0, v[138:139]
	s_add_i32 m0, s34, 0xe000
	s_nop 0
	global_load_lds_dwordx4 v[218:219], off
	s_waitcnt vmcnt(8)
	s_waitcnt lgkmcnt(0)
	s_barrier
; #define PG8_STAGE(bufoff, gbase, voff) do { _Pragma("unroll") for (int _i = 0; _i < 2; ++_i) \
;         __builtin_amdgcn_global_load_lds((const unsigned*)((const char*)(gbase) + (voff)[_i]), (PG8_LAS unsigned*)(lds + (bufoff) + ldsw + _i * 8192), 16, 0, 0); } while (0)
; #define PG8_LDA(dst, b, h) do { _Pragma("unroll") for (int m = 0; m < 4; ++m) _Pragma("unroll") for (int k = 0; k < 2; ++k) dst[m][k] = *(const PG8_LAS bf16x8*)(lds + PG8_SA(b, h) + aoff + m * 2048 + k * 1024); } while (0)
; #define PG8_LDB(dst, b, h) do { _Pragma("unroll") for (int n = 0; n < 2; ++n) _Pragma("unroll") for (int k = 0; k < 2; ++k) dst[n][k] = *(const PG8_LAS bf16x8*)(lds + PG8_SB(b, h) + boff + n * 2048 + k * 1024); } while (0)
; #define PG8_MMA(ai, bj, At, Bt) do { __builtin_amdgcn_s_setprio(1); _Pragma("unroll") for (int m = 0; m < 4; ++m) _Pragma("unroll") for (int n = 0; n < 2; ++n) _Pragma("unroll") for (int k = 0; k < 2; ++k) \
;         acc[ai][bj][m][n] = __builtin_amdgcn_mfma_f32_16x16x32_bf16(Bt[n][k], At[m][k], acc[ai][bj][m][n], 0, 0, 0); __builtin_amdgcn_s_setprio(0); } while (0)
; #define PG8_WAIT_V(n) asm volatile("s_waitcnt vmcnt(" #n ")" ::: "memory")
; #define PG8_WAIT_L(n) asm volatile("s_waitcnt lgkmcnt(" #n ")" ::: "memory")
; #define PG8_BAR __builtin_amdgcn_s_barrier()
; #define PG8_SCHED __builtin_amdgcn_sched_barrier(0)
; template <class Epi, class Sched, bool ALIGN_EPI = false, bool SP2 = false>
; __device__ __forceinline__ void gemm_phase(PG8_LAS unsigned char* lds, const Gemm g, const Sched& S, const Epi& E) {
;     ...
;             PG8_LDB(B0, 0, 0); PG8_LDB(B1, 0, 1); PG8_SCHED; PG8_LDA(At, 0, 0); PG8_STAGE(PG8_SA(1, 1), a1 + hstep, voffA);
;             PG8_WAIT_V(8); PG8_WAIT_L(0); PG8_BAR; PG8_MMA(0, 0, At, B0); PG8_MMA(0, 1, At, B1); PG8_BAR; PG8_SCHED;
;             PG8_LDA(At, 0, 1); PG8_STAGE(PG8_SB(0, 0), b2, voffB); PG8_STAGE(PG8_SB(0, 1), b2 + hstep, voffB); PG8_STAGE(PG8_SA(0, 0), a2, voffA);
;             PG8_WAIT_V(8); PG8_WAIT_L(0); PG8_BAR; PG8_MMA(1, 0, At, B0); PG8_MMA(1, 1, At, B1); PG8_BAR; PG8_SCHED;
	s_setprio 1
	s_waitcnt lgkmcnt(0)
	v_mfma_f32_16x16x32_bf16 v[124:127], v[144:147], v[184:187], v[124:127]
	v_mfma_f32_16x16x32_bf16 v[120:123], v[160:163], v[184:187], v[120:123]
	v_mfma_f32_16x16x32_bf16 v[104:107], v[160:163], v[192:195], v[104:107]
	v_mfma_f32_16x16x32_bf16 v[108:111], v[144:147], v[192:195], v[108:111]
	v_mfma_f32_16x16x32_bf16 v[92:95], v[144:147], v[200:203], v[92:95]
	v_mfma_f32_16x16x32_bf16 v[88:91], v[160:163], v[200:203], v[88:91]
	v_mfma_f32_16x16x32_bf16 v[72:75], v[160:163], v[210:213], v[72:75]
	v_mfma_f32_16x16x32_bf16 v[76:79], v[144:147], v[210:213], v[76:79]
	v_mfma_f32_16x16x32_bf16 v[124:127], v[148:151], v[188:191], v[124:127]
	v_mfma_f32_16x16x32_bf16 v[120:123], v[164:167], v[188:191], v[120:123]
	v_mfma_f32_16x16x32_bf16 v[104:107], v[164:167], v[196:199], v[104:107]
	v_mfma_f32_16x16x32_bf16 v[108:111], v[148:151], v[196:199], v[108:111]
	v_mfma_f32_16x16x32_bf16 v[92:95], v[148:151], v[206:209], v[92:95]
	v_mfma_f32_16x16x32_bf16 v[88:91], v[164:167], v[206:209], v[88:91]
	v_mfma_f32_16x16x32_bf16 v[72:75], v[164:167], v[214:217], v[72:75]
	v_mfma_f32_16x16x32_bf16 v[76:79], v[148:151], v[214:217], v[76:79]
	s_setprio 0
	s_setprio 1
	v_mfma_f32_16x16x32_bf16 v[116:119], v[168:171], v[184:187], v[116:119]
	v_mfma_f32_16x16x32_bf16 v[112:115], v[176:179], v[184:187], v[112:115]
	v_mfma_f32_16x16x32_bf16 v[96:99], v[176:179], v[192:195], v[96:99]
	v_mfma_f32_16x16x32_bf16 v[100:103], v[168:171], v[192:195], v[100:103]
	v_mfma_f32_16x16x32_bf16 v[84:87], v[168:171], v[200:203], v[84:87]
	v_mfma_f32_16x16x32_bf16 v[80:83], v[176:179], v[200:203], v[80:83]
	v_mfma_f32_16x16x32_bf16 v[64:67], v[176:179], v[210:213], v[64:67]
	v_mfma_f32_16x16x32_bf16 v[68:71], v[168:171], v[210:213], v[68:71]
	v_mfma_f32_16x16x32_bf16 v[116:119], v[172:175], v[188:191], v[116:119]
	v_mfma_f32_16x16x32_bf16 v[112:115], v[180:183], v[188:191], v[112:115]
	v_mfma_f32_16x16x32_bf16 v[96:99], v[180:183], v[196:199], v[96:99]
	v_mfma_f32_16x16x32_bf16 v[100:103], v[172:175], v[196:199], v[100:103]
	v_mfma_f32_16x16x32_bf16 v[84:87], v[172:175], v[206:209], v[84:87]
	v_mfma_f32_16x16x32_bf16 v[80:83], v[180:183], v[206:209], v[80:83]
	v_mfma_f32_16x16x32_bf16 v[64:67], v[180:183], v[214:217], v[64:67]
	v_mfma_f32_16x16x32_bf16 v[68:71], v[172:175], v[214:217], v[68:71]
	s_setprio 0
	s_barrier
	s_add_i32 s58, s49, s15
	v_lshl_add_u64 v[218:219], s[40:41], 0, v[132:133]
	s_mov_b32 m0, s58
	ds_read_b128 v[184:187], v157 offset:16384
	ds_read_b128 v[188:191], v157 offset:17408
	ds_read_b128 v[192:195], v157 offset:18432
	ds_read_b128 v[196:199], v157 offset:19456
	ds_read_b128 v[200:203], v157 offset:20480
	ds_read_b128 v[206:209], v157 offset:21504
	ds_read_b128 v[210:213], v157 offset:22528
	ds_read_b128 v[214:217], v157 offset:23552
	global_load_lds_dwordx4 v[218:219], off
	s_add_i32 m0, s58, 0x2000
	s_add_u32 s58, s40, 0x40000
	v_lshl_add_u64 v[220:221], s[40:41], 0, v[128:129]
	s_addc_u32 s59, s41, 0
	s_add_i32 s60, s50, s15
	global_load_lds_dwordx4 v[220:221], off
	v_lshl_add_u64 v[222:223], s[58:59], 0, v[132:133]
	s_mov_b32 m0, s60
	global_load_lds_dwordx4 v[222:223], off
	v_lshl_add_u64 v[222:223], s[58:59], 0, v[128:129]
	s_add_i32 m0, s60, 0x2000
	s_nop 0
	global_load_lds_dwordx4 v[222:223], off
	s_waitcnt vmcnt(6)
	s_waitcnt lgkmcnt(0)
	s_barrier
	s_setprio 1
	s_waitcnt lgkmcnt(0)
	v_mfma_f32_16x16x32_bf16 v[60:63], v[144:147], v[184:187], v[60:63]
	v_mfma_f32_16x16x32_bf16 v[56:59], v[160:163], v[184:187], v[56:59]
	v_mfma_f32_16x16x32_bf16 v[40:43], v[160:163], v[192:195], v[40:43]
	v_mfma_f32_16x16x32_bf16 v[44:47], v[144:147], v[192:195], v[44:47]
	v_mfma_f32_16x16x32_bf16 v[28:31], v[144:147], v[200:203], v[28:31]
	v_mfma_f32_16x16x32_bf16 v[24:27], v[160:163], v[200:203], v[24:27]
	v_mfma_f32_16x16x32_bf16 v[8:11], v[160:163], v[210:213], v[8:11]
	v_mfma_f32_16x16x32_bf16 v[12:15], v[144:147], v[210:213], v[12:15]
	v_mfma_f32_16x16x32_bf16 v[60:63], v[148:151], v[188:191], v[60:63]
	v_mfma_f32_16x16x32_bf16 v[56:59], v[164:167], v[188:191], v[56:59]
	v_mfma_f32_16x16x32_bf16 v[40:43], v[164:167], v[196:199], v[40:43]
	v_mfma_f32_16x16x32_bf16 v[44:47], v[148:151], v[196:199], v[44:47]
	v_mfma_f32_16x16x32_bf16 v[28:31], v[148:151], v[206:209], v[28:31]
	v_mfma_f32_16x16x32_bf16 v[24:27], v[164:167], v[206:209], v[24:27]
	v_lshl_add_u64 v[222:223], s[42:43], 0, v[134:135]
	s_mov_b32 m0, s34
	s_nop 0
	global_load_lds_dwordx4 v[222:223], off
	v_mfma_f32_16x16x32_bf16 v[8:11], v[164:167], v[214:217], v[8:11]
	v_mfma_f32_16x16x32_bf16 v[12:15], v[148:151], v[214:217], v[12:15]
	s_setprio 0
	s_setprio 1
	v_mfma_f32_16x16x32_bf16 v[52:55], v[168:171], v[184:187], v[52:55]
	v_mfma_f32_16x16x32_bf16 v[48:51], v[176:179], v[184:187], v[48:51]
	v_mfma_f32_16x16x32_bf16 v[32:35], v[176:179], v[192:195], v[32:35]
	v_mfma_f32_16x16x32_bf16 v[36:39], v[168:171], v[192:195], v[36:39]
	v_mfma_f32_16x16x32_bf16 v[20:23], v[168:171], v[200:203], v[20:23]
	v_mfma_f32_16x16x32_bf16 v[16:19], v[176:179], v[200:203], v[16:19]
	v_mfma_f32_16x16x32_bf16 v[0:3], v[176:179], v[210:213], v[0:3]
	v_mfma_f32_16x16x32_bf16 v[4:7], v[168:171], v[210:213], v[4:7]
	v_mfma_f32_16x16x32_bf16 v[52:55], v[172:175], v[188:191], v[52:55]
	v_mfma_f32_16x16x32_bf16 v[48:51], v[180:183], v[188:191], v[48:51]
	v_mfma_f32_16x16x32_bf16 v[32:35], v[180:183], v[196:199], v[32:35]
	v_mfma_f32_16x16x32_bf16 v[36:39], v[172:175], v[196:199], v[36:39]
	v_mfma_f32_16x16x32_bf16 v[20:23], v[172:175], v[206:209], v[20:23]
	v_mfma_f32_16x16x32_bf16 v[16:19], v[180:183], v[206:209], v[16:19]
	v_lshl_add_u64 v[224:225], s[42:43], 0, v[130:131]
	s_mov_b32 m0, s37
	s_nop 0
	global_load_lds_dwordx4 v[224:225], off
	v_mfma_f32_16x16x32_bf16 v[0:3], v[180:183], v[214:217], v[0:3]
	v_mfma_f32_16x16x32_bf16 v[4:7], v[172:175], v[214:217], v[4:7]
	s_setprio 0
	s_barrier
; #define PG8_STAGE(bufoff, gbase, voff) do { _Pragma("unroll") for (int _i = 0; _i < 2; ++_i) \
;         __builtin_amdgcn_global_load_lds((const unsigned*)((const char*)(gbase) + (voff)[_i]), (PG8_LAS unsigned*)(lds + (bufoff) + ldsw + _i * 8192), 16, 0, 0); } while (0)
; #define PG8_LDA(dst, b, h) do { _Pragma("unroll") for (int m = 0; m < 4; ++m) _Pragma("unroll") for (int k = 0; k < 2; ++k) dst[m][k] = *(const PG8_LAS bf16x8*)(lds + PG8_SA(b, h) + aoff + m * 2048 + k * 1024); } while (0)
; #define PG8_LDB(dst, b, h) do { _Pragma("unroll") for (int n = 0; n < 2; ++n) _Pragma("unroll") for (int k = 0; k < 2; ++k) dst[n][k] = *(const PG8_LAS bf16x8*)(lds + PG8_SB(b, h) + boff + n * 2048 + k * 1024); } while (0)
; #define PG8_MMA(ai, bj, At, Bt) do { __builtin_amdgcn_s_setprio(1); _Pragma("unroll") for (int m = 0; m < 4; ++m) _Pragma("unroll") for (int n = 0; n < 2; ++n) _Pragma("unroll") for (int k = 0; k < 2; ++k) \
;         acc[ai][bj][m][n] = __builtin_amdgcn_mfma_f32_16x16x32_bf16(Bt[n][k], At[m][k], acc[ai][bj][m][n], 0, 0, 0); __builtin_amdgcn_s_setprio(0); } while (0)
; #define PG8_WAIT_V(n) asm volatile("s_waitcnt vmcnt(" #n ")" ::: "memory")
; #define PG8_WAIT_L(n) asm volatile("s_waitcnt lgkmcnt(" #n ")" ::: "memory")
; #define PG8_BAR __builtin_amdgcn_s_barrier()
; #define PG8_SCHED __builtin_amdgcn_sched_barrier(0)
; template <class Epi, class Sched, bool ALIGN_EPI = false, bool SP2 = false>
; __device__ __forceinline__ void gemm_phase(PG8_LAS unsigned char* lds, const Gemm g, const Sched& S, const Epi& E) {
;     ...
;             PG8_LDB(B0, 1, 0); PG8_LDB(B1, 1, 1); PG8_SCHED; PG8_LDA(At, 1, 0); PG8_STAGE(PG8_SA(0, 1), a2 + hstep, voffA);
;             PG8_WAIT_V(8); PG8_WAIT_L(0); PG8_BAR; PG8_MMA(0, 0, At, B0); PG8_MMA(0, 1, At, B1); PG8_BAR; PG8_SCHED;
	s_add_i32 s58, 0, 0x18000
	v_add_u32_e32 v159, s58, v153
	s_add_i32 s59, 0, 0x1c000
	ds_read_b128 v[144:147], v159
	ds_read_b128 v[148:151], v159 offset:1024
	ds_read_b128 v[160:163], v159 offset:2048
	ds_read_b128 v[164:167], v159 offset:3072
	v_add_u32_e32 v159, s59, v153
	ds_read_b128 v[168:171], v159
	ds_read_b128 v[172:175], v159 offset:1024
	ds_read_b128 v[176:179], v159 offset:2048
	ds_read_b128 v[180:183], v159 offset:3072
	s_add_u32 s42, s42, 0x40000
	s_addc_u32 s43, s43, 0
	s_mov_b32 m0, s44
	v_lshl_add_u64 v[226:227], s[42:43], 0, v[134:135]
	ds_read_b128 v[184:187], v157 offset:32768
	ds_read_b128 v[188:191], v157 offset:33792
	ds_read_b128 v[192:195], v157 offset:34816
	ds_read_b128 v[196:199], v157 offset:35840
	ds_read_b128 v[200:203], v157 offset:36864
	ds_read_b128 v[206:209], v157 offset:37888
	ds_read_b128 v[210:213], v157 offset:38912
	ds_read_b128 v[214:217], v157 offset:39936
	global_load_lds_dwordx4 v[226:227], off
	v_lshl_add_u64 v[226:227], s[42:43], 0, v[130:131]
	s_mov_b32 m0, s45
	s_nop 0
	global_load_lds_dwordx4 v[226:227], off
	s_waitcnt vmcnt(8)
	s_waitcnt lgkmcnt(0)
	s_barrier
	s_setprio 1
	s_waitcnt lgkmcnt(0)
	v_mfma_f32_16x16x32_bf16 v[124:127], v[144:147], v[184:187], v[124:127]
	v_mfma_f32_16x16x32_bf16 v[120:123], v[160:163], v[184:187], v[120:123]
	v_mfma_f32_16x16x32_bf16 v[104:107], v[160:163], v[192:195], v[104:107]
	v_mfma_f32_16x16x32_bf16 v[108:111], v[144:147], v[192:195], v[108:111]
	v_mfma_f32_16x16x32_bf16 v[92:95], v[144:147], v[200:203], v[92:95]
	v_mfma_f32_16x16x32_bf16 v[88:91], v[160:163], v[200:203], v[88:91]
	v_mfma_f32_16x16x32_bf16 v[72:75], v[160:163], v[210:213], v[72:75]
	v_mfma_f32_16x16x32_bf16 v[76:79], v[144:147], v[210:213], v[76:79]
	v_mfma_f32_16x16x32_bf16 v[124:127], v[148:151], v[188:191], v[124:127]
	v_mfma_f32_16x16x32_bf16 v[120:123], v[164:167], v[188:191], v[120:123]
	v_mfma_f32_16x16x32_bf16 v[104:107], v[164:167], v[196:199], v[104:107]
	v_mfma_f32_16x16x32_bf16 v[108:111], v[148:151], v[196:199], v[108:111]
	v_mfma_f32_16x16x32_bf16 v[92:95], v[148:151], v[206:209], v[92:95]
	v_mfma_f32_16x16x32_bf16 v[88:91], v[164:167], v[206:209], v[88:91]
	v_mfma_f32_16x16x32_bf16 v[72:75], v[164:167], v[214:217], v[72:75]
	v_mfma_f32_16x16x32_bf16 v[76:79], v[148:151], v[214:217], v[76:79]
	s_setprio 0
	s_setprio 1
	v_mfma_f32_16x16x32_bf16 v[116:119], v[168:171], v[184:187], v[116:119]
	v_mfma_f32_16x16x32_bf16 v[112:115], v[176:179], v[184:187], v[112:115]
	v_mfma_f32_16x16x32_bf16 v[96:99], v[176:179], v[192:195], v[96:99]
	v_mfma_f32_16x16x32_bf16 v[100:103], v[168:171], v[192:195], v[100:103]
	v_mfma_f32_16x16x32_bf16 v[84:87], v[168:171], v[200:203], v[84:87]
	v_mfma_f32_16x16x32_bf16 v[80:83], v[176:179], v[200:203], v[80:83]
	v_mfma_f32_16x16x32_bf16 v[64:67], v[176:179], v[210:213], v[64:67]
	v_mfma_f32_16x16x32_bf16 v[68:71], v[168:171], v[210:213], v[68:71]
	v_mfma_f32_16x16x32_bf16 v[116:119], v[172:175], v[188:191], v[116:119]
	v_mfma_f32_16x16x32_bf16 v[112:115], v[180:183], v[188:191], v[112:115]
	v_mfma_f32_16x16x32_bf16 v[96:99], v[180:183], v[196:199], v[96:99]
	v_mfma_f32_16x16x32_bf16 v[100:103], v[172:175], v[196:199], v[100:103]
	v_mfma_f32_16x16x32_bf16 v[84:87], v[172:175], v[206:209], v[84:87]
	v_mfma_f32_16x16x32_bf16 v[80:83], v[180:183], v[206:209], v[80:83]
	v_mfma_f32_16x16x32_bf16 v[64:67], v[180:183], v[214:217], v[64:67]
	v_mfma_f32_16x16x32_bf16 v[68:71], v[172:175], v[214:217], v[68:71]
	s_setprio 0
	s_barrier
; #define PG8_STAGE(bufoff, gbase, voff) do { _Pragma("unroll") for (int _i = 0; _i < 2; ++_i) \
;         __builtin_amdgcn_global_load_lds((const unsigned*)((const char*)(gbase) + (voff)[_i]), (PG8_LAS unsigned*)(lds + (bufoff) + ldsw + _i * 8192), 16, 0, 0); } while (0)
; #define PG8_LDA(dst, b, h) do { _Pragma("unroll") for (int m = 0; m < 4; ++m) _Pragma("unroll") for (int k = 0; k < 2; ++k) dst[m][k] = *(const PG8_LAS bf16x8*)(lds + PG8_SA(b, h) + aoff + m * 2048 + k * 1024); } while (0)
; #define PG8_MMA(ai, bj, At, Bt) do { __builtin_amdgcn_s_setprio(1); _Pragma("unroll") for (int m = 0; m < 4; ++m) _Pragma("unroll") for (int n = 0; n < 2; ++n) _Pragma("unroll") for (int k = 0; k < 2; ++k) \
;         acc[ai][bj][m][n] = __builtin_amdgcn_mfma_f32_16x16x32_bf16(Bt[n][k], At[m][k], acc[ai][bj][m][n], 0, 0, 0); __builtin_amdgcn_s_setprio(0); } while (0)
; #define PG8_WAIT_V(n) asm volatile("s_waitcnt vmcnt(" #n ")" ::: "memory")
; #define PG8_WAIT_L(n) asm volatile("s_waitcnt lgkmcnt(" #n ")" ::: "memory")
; #define PG8_BAR __builtin_amdgcn_s_barrier()
; #define PG8_SCHED __builtin_amdgcn_sched_barrier(0)
; __device__ __forceinline__ float row_rs(const float* ssp, int row) { const unsigned long long v = ((const unsigned long long*)ssp)[row];
;     return __builtin_amdgcn_rsqf((float)v * (1.0f / 4294967296.0f) * (1.0f / 1024.0f) + RMS_EPS); }
; template <class Epi, class Sched, bool ALIGN_EPI = false, bool SP2 = false>
; __device__ __forceinline__ void gemm_phase(PG8_LAS unsigned char* lds, const Gemm g, const Sched& S, const Epi& E) {
;     ...
;             PG8_LDA(At, 1, 1); PG8_STAGE(PG8_SB(1, 0), b3, voffB); PG8_STAGE(PG8_SB(1, 1), b3 + hstep, voffB); PG8_STAGE(PG8_SA(1, 0), a3, voffA);
;             PG8_WAIT_V(8); PG8_WAIT_L(0); PG8_BAR; PG8_MMA(1, 0, At, B0); PG8_MMA(1, 1, At, B1); PG8_BAR; PG8_SCHED;
	s_add_i32 s42, s58, s15
	v_lshl_add_u64 v[218:219], v[218:219], 0, s[8:9]
	s_mov_b32 m0, s42
	ds_read_b128 v[184:187], v157 offset:49152
	ds_read_b128 v[188:191], v157 offset:50176
	ds_read_b128 v[192:195], v157 offset:51200
	ds_read_b128 v[196:199], v157 offset:52224
	ds_read_b128 v[200:203], v157 offset:53248
	ds_read_b128 v[206:209], v157 offset:54272
	ds_read_b128 v[210:213], v157 offset:55296
	ds_read_b128 v[214:217], v157 offset:56320
	global_load_lds_dwordx4 v[218:219], off
	s_add_i32 m0, s42, 0x2000
	s_add_u32 s40, s40, 0x40080
	v_lshl_add_u64 v[218:219], v[220:221], 0, s[8:9]
	s_addc_u32 s41, s41, 0
	s_add_i32 s42, s59, s15
	global_load_lds_dwordx4 v[218:219], off
	v_lshl_add_u64 v[218:219], s[40:41], 0, v[132:133]
	s_mov_b32 m0, s42
	s_nop 0
	global_load_lds_dwordx4 v[218:219], off
	v_lshl_add_u64 v[218:219], s[40:41], 0, v[128:129]
	s_add_i32 m0, s42, 0x2000
	s_nop 0
	global_load_lds_dwordx4 v[218:219], off
	s_waitcnt vmcnt(6)
	s_waitcnt lgkmcnt(0)
	s_barrier
	s_setprio 1
	s_waitcnt lgkmcnt(0)
	v_mfma_f32_16x16x32_bf16 v[60:63], v[144:147], v[184:187], v[60:63]
	v_mfma_f32_16x16x32_bf16 v[56:59], v[160:163], v[184:187], v[56:59]
	v_mfma_f32_16x16x32_bf16 v[40:43], v[160:163], v[192:195], v[40:43]
	v_mfma_f32_16x16x32_bf16 v[44:47], v[144:147], v[192:195], v[44:47]
	v_mfma_f32_16x16x32_bf16 v[28:31], v[144:147], v[200:203], v[28:31]
	v_mfma_f32_16x16x32_bf16 v[24:27], v[160:163], v[200:203], v[24:27]
	v_mfma_f32_16x16x32_bf16 v[8:11], v[160:163], v[210:213], v[8:11]
	v_mfma_f32_16x16x32_bf16 v[12:15], v[144:147], v[210:213], v[12:15]
	v_mfma_f32_16x16x32_bf16 v[60:63], v[148:151], v[188:191], v[60:63]
	v_mfma_f32_16x16x32_bf16 v[56:59], v[164:167], v[188:191], v[56:59]
	v_mfma_f32_16x16x32_bf16 v[40:43], v[164:167], v[196:199], v[40:43]
	v_mfma_f32_16x16x32_bf16 v[44:47], v[148:151], v[196:199], v[44:47]
	v_mfma_f32_16x16x32_bf16 v[28:31], v[148:151], v[206:209], v[28:31]
	v_mfma_f32_16x16x32_bf16 v[24:27], v[164:167], v[206:209], v[24:27]
	v_lshl_add_u64 v[218:219], v[222:223], 0, s[8:9]
	s_mov_b32 m0, s47
	s_nop 0
	global_load_lds_dwordx4 v[218:219], off
	v_mfma_f32_16x16x32_bf16 v[8:11], v[164:167], v[214:217], v[8:11]
	v_mfma_f32_16x16x32_bf16 v[12:15], v[148:151], v[214:217], v[12:15]
	s_setprio 0
	s_setprio 1
	v_mfma_f32_16x16x32_bf16 v[52:55], v[168:171], v[184:187], v[52:55]
	v_mfma_f32_16x16x32_bf16 v[48:51], v[176:179], v[184:187], v[48:51]
	v_mfma_f32_16x16x32_bf16 v[32:35], v[176:179], v[192:195], v[32:35]
	v_mfma_f32_16x16x32_bf16 v[36:39], v[168:171], v[192:195], v[36:39]
	v_mfma_f32_16x16x32_bf16 v[20:23], v[168:171], v[200:203], v[20:23]
	v_mfma_f32_16x16x32_bf16 v[16:19], v[176:179], v[200:203], v[16:19]
	v_mfma_f32_16x16x32_bf16 v[0:3], v[176:179], v[210:213], v[0:3]
	v_mfma_f32_16x16x32_bf16 v[4:7], v[168:171], v[210:213], v[4:7]
	v_mfma_f32_16x16x32_bf16 v[52:55], v[172:175], v[188:191], v[52:55]
	v_mfma_f32_16x16x32_bf16 v[48:51], v[180:183], v[188:191], v[48:51]
	v_mfma_f32_16x16x32_bf16 v[32:35], v[180:183], v[196:199], v[32:35]
	v_mfma_f32_16x16x32_bf16 v[36:39], v[172:175], v[196:199], v[36:39]
	v_mfma_f32_16x16x32_bf16 v[20:23], v[172:175], v[206:209], v[20:23]
	v_mfma_f32_16x16x32_bf16 v[16:19], v[180:183], v[206:209], v[16:19]
	v_lshl_add_u64 v[218:219], v[224:225], 0, s[8:9]
	s_mov_b32 m0, s48
	s_nop 0
	global_load_lds_dwordx4 v[218:219], off
	v_mfma_f32_16x16x32_bf16 v[0:3], v[180:183], v[214:217], v[0:3]
	v_mfma_f32_16x16x32_bf16 v[4:7], v[172:175], v[214:217], v[4:7]
	s_setprio 0
	s_barrier
	s_add_i32 s57, s57, 2
	s_add_u32 s38, s38, 0x100
	s_addc_u32 s39, s39, 0
	s_add_u32 s55, s55, 0x100
	s_addc_u32 s56, s56, 0
	s_cmp_gt_u32 s57, 13
	s_cbranch_scc0 .LBB0_1900
	v_lshl_add_u32 v144, s36, 8, v152
	v_ashrrev_i32_e32 v145, 31, v144
	v_lshl_add_u64 v[150:151], v[144:145], 3, s[0:1]
	global_load_dwordx2 v[182:183], v[150:151], off
	global_load_dwordx2 v[184:185], v[150:151], off offset:128
	global_load_dwordx2 v[186:187], v[150:151], off offset:256
	global_load_dwordx2 v[188:189], v[150:151], off offset:384
	global_load_dwordx2 v[190:191], v[150:151], off offset:1024
	global_load_dwordx2 v[192:193], v[150:151], off offset:1152
	global_load_dwordx2 v[194:195], v[150:151], off offset:1280
	global_load_dwordx2 v[196:197], v[150:151], off offset:1408
	s_and_b64 vcc, exec, s[10:11]
	s_cbranch_vccz .LBB0_1903
	s_barrier

; #define PG8_STAGE(bufoff, gbase, voff) do { _Pragma("unroll") for (int _i = 0; _i < 2; ++_i) \
;         __builtin_amdgcn_global_load_lds((const unsigned*)((const char*)(gbase) + (voff)[_i]), (PG8_LAS unsigned*)(lds + (bufoff) + ldsw + _i * 8192), 16, 0, 0); } while (0)
; #define PG8_LDA(dst, b, h) do { _Pragma("unroll") for (int m = 0; m < 4; ++m) _Pragma("unroll") for (int k = 0; k < 2; ++k) dst[m][k] = *(const PG8_LAS bf16x8*)(lds + PG8_SA(b, h) + aoff + m * 2048 + k * 1024); } while (0)
; #define PG8_LDB(dst, b, h) do { _Pragma("unroll") for (int n = 0; n < 2; ++n) _Pragma("unroll") for (int k = 0; k < 2; ++k) dst[n][k] = *(const PG8_LAS bf16x8*)(lds + PG8_SB(b, h) + boff + n * 2048 + k * 1024); } while (0)
; #define PG8_WAIT_V(n) asm volatile("s_waitcnt vmcnt(" #n ")" ::: "memory")
; #define PG8_WAIT_L(n) asm volatile("s_waitcnt lgkmcnt(" #n ")" ::: "memory")
; #define PG8_BAR __builtin_amdgcn_s_barrier()
; #define PG8_SCHED __builtin_amdgcn_sched_barrier(0)
; template <class Epi, class Sched, bool ALIGN_EPI = false, bool SP2 = false>
; __device__ __forceinline__ void gemm_phase(PG8_LAS unsigned char* lds, const Gemm g, const Sched& S, const Epi& E) {
;     ...
;         const bool has_next = S.next(ui + 1, nxt);
;         const char* nA = has_next ? (const char*)g.A + (size_t)nxt.pm * tstep : cA; const char* nB = has_next ? (const char*)g.Bt + (size_t)nxt.pn * tstep : cB;
;         for (int t = 0; t < nt; t += 2) {
;             const bool last = (t == nt - 2);
;             const char* a1 = cA + (size_t)(t + 1) * kstep;
;             const char* a2 = last ? nA : cA + (size_t)(t + 2) * kstep; const char* b2 = last ? nB : cB + (size_t)(t + 2) * kstep;
;             const char* a3 = a2 + kstep; const char* b3 = b2 + kstep;
;             if (last && has_next) S.a_ready(nxt);
;             if constexpr (SP2) {
;             PG8_LDB(B0, 0, 0); PG8_LDB(B1, 0, 1); PG8_SCHED; PG8_LDA(At, 0, 0); PG8_STAGE(PG8_SA(1, 1), a1 + hstep, voffA);
;             PG8_WAIT_V(8); PG8_WAIT_L(0); PG8_BAR; PG8_MMA(0, 0, At, B0); PG8_MMA(0, 1, At, B1); PG8_BAR; PG8_SCHED;
;             PG8_LDA(At, 0, 1); PG8_STAGE(PG8_SB(0, 0), b2, voffB); PG8_STAGE(PG8_SB(0, 1), b2 + hstep, voffB); PG8_STAGE(PG8_SA(0, 0), a2, voffA);
;             PG8_WAIT_V(8); PG8_WAIT_L(0); PG8_BAR; PG8_MMA(1, 0, At, B0); PG8_MMA(1, 1, At, B1); PG8_BAR; PG8_SCHED;
.LBB0_1977:
	s_add_u32 s53, s28, 0x100
	s_addc_u32 s54, s29, 0
	s_mov_b32 s55, -2
	s_waitcnt lgkmcnt(0)
	ds_read_b128 v[144:147], v151
	ds_read_b128 v[156:159], v151 offset:1024
	ds_read_b128 v[160:163], v151 offset:2048
	ds_read_b128 v[164:167], v151 offset:3072
	ds_read_b128 v[168:171], v152
	ds_read_b128 v[172:175], v152 offset:1024
	ds_read_b128 v[176:179], v152 offset:2048
	ds_read_b128 v[180:183], v152 offset:3072
	s_add_u32 s28, s26, 0x100
	s_addc_u32 s29, s27, 0
	s_cmp_eq_u32 s55, 40
	s_cselect_b32 s39, s1, s29
	s_cselect_b32 s38, s0, s28
	s_cselect_b32 s37, s25, s54
	s_cselect_b32 s36, s24, s53
	v_lshl_add_u64 v[218:219], s[26:27], 0, v[136:137]
	s_add_i32 m0, s33, 0xc000
	ds_read_b128 v[184:187], v153
	ds_read_b128 v[188:191], v153 offset:1024
	ds_read_b128 v[192:195], v153 offset:2048
	ds_read_b128 v[196:199], v153 offset:3072
	ds_read_b128 v[200:203], v153 offset:4096
	ds_read_b128 v[206:209], v153 offset:5120
	ds_read_b128 v[210:213], v153 offset:6144
	ds_read_b128 v[214:217], v153 offset:7168
	global_load_lds_dwordx4 v[218:219], off
	v_lshl_add_u64 v[218:219], s[26:27], 0, v[138:139]
	s_add_i32 m0, s33, 0xe000
	s_nop 0
	global_load_lds_dwordx4 v[218:219], off
	s_waitcnt vmcnt(8)
	s_waitcnt lgkmcnt(0)
	s_barrier
	s_setprio 1
	s_waitcnt lgkmcnt(0)
	v_mfma_f32_16x16x32_bf16 v[124:127], v[144:147], v[184:187], 0
	v_mfma_f32_16x16x32_bf16 v[120:123], v[160:163], v[184:187], 0
	v_mfma_f32_16x16x32_bf16 v[104:107], v[160:163], v[192:195], 0
	v_mfma_f32_16x16x32_bf16 v[108:111], v[144:147], v[192:195], 0
	v_mfma_f32_16x16x32_bf16 v[92:95], v[144:147], v[200:203], 0
	v_mfma_f32_16x16x32_bf16 v[88:91], v[160:163], v[200:203], 0
	v_mfma_f32_16x16x32_bf16 v[72:75], v[160:163], v[210:213], 0
	v_mfma_f32_16x16x32_bf16 v[76:79], v[144:147], v[210:213], 0
	v_mfma_f32_16x16x32_bf16 v[124:127], v[156:159], v[188:191], v[124:127]
	v_mfma_f32_16x16x32_bf16 v[120:123], v[164:167], v[188:191], v[120:123]
	v_mfma_f32_16x16x32_bf16 v[104:107], v[164:167], v[196:199], v[104:107]
	v_mfma_f32_16x16x32_bf16 v[108:111], v[156:159], v[196:199], v[108:111]
	v_mfma_f32_16x16x32_bf16 v[92:95], v[156:159], v[206:209], v[92:95]
	v_mfma_f32_16x16x32_bf16 v[88:91], v[164:167], v[206:209], v[88:91]
	v_mfma_f32_16x16x32_bf16 v[72:75], v[164:167], v[214:217], v[72:75]
	v_mfma_f32_16x16x32_bf16 v[76:79], v[156:159], v[214:217], v[76:79]
	s_setprio 0
	s_setprio 1
	v_mfma_f32_16x16x32_bf16 v[116:119], v[168:171], v[184:187], 0
	v_mfma_f32_16x16x32_bf16 v[112:115], v[176:179], v[184:187], 0
	v_mfma_f32_16x16x32_bf16 v[96:99], v[176:179], v[192:195], 0
	v_mfma_f32_16x16x32_bf16 v[100:103], v[168:171], v[192:195], 0
	v_mfma_f32_16x16x32_bf16 v[84:87], v[168:171], v[200:203], 0
	v_mfma_f32_16x16x32_bf16 v[80:83], v[176:179], v[200:203], 0
	v_mfma_f32_16x16x32_bf16 v[64:67], v[176:179], v[210:213], 0
	v_mfma_f32_16x16x32_bf16 v[68:71], v[168:171], v[210:213], 0
	v_mfma_f32_16x16x32_bf16 v[116:119], v[172:175], v[188:191], v[116:119]
	v_mfma_f32_16x16x32_bf16 v[112:115], v[180:183], v[188:191], v[112:115]
	v_mfma_f32_16x16x32_bf16 v[96:99], v[180:183], v[196:199], v[96:99]
	v_mfma_f32_16x16x32_bf16 v[100:103], v[172:175], v[196:199], v[100:103]
	v_mfma_f32_16x16x32_bf16 v[84:87], v[172:175], v[206:209], v[84:87]
	v_mfma_f32_16x16x32_bf16 v[80:83], v[180:183], v[206:209], v[80:83]
	v_mfma_f32_16x16x32_bf16 v[64:67], v[180:183], v[214:217], v[64:67]
	v_mfma_f32_16x16x32_bf16 v[68:71], v[172:175], v[214:217], v[68:71]
	s_setprio 0
	s_barrier
	s_add_i32 s26, s45, s15
	v_lshl_add_u64 v[218:219], s[36:37], 0, v[130:131]
	s_mov_b32 m0, s26
	ds_read_b128 v[184:187], v153 offset:16384
	ds_read_b128 v[188:191], v153 offset:17408
	ds_read_b128 v[192:195], v153 offset:18432
	ds_read_b128 v[196:199], v153 offset:19456
	ds_read_b128 v[200:203], v153 offset:20480
	ds_read_b128 v[206:209], v153 offset:21504
	ds_read_b128 v[210:213], v153 offset:22528
	ds_read_b128 v[214:217], v153 offset:23552
	global_load_lds_dwordx4 v[218:219], off
	s_add_i32 m0, s26, 0x2000
	s_add_u32 s26, s36, 0xb0000
	v_lshl_add_u64 v[220:221], s[36:37], 0, v[134:135]
	s_addc_u32 s27, s37, 0
	s_add_i32 s56, s46, s15
	global_load_lds_dwordx4 v[220:221], off
	v_lshl_add_u64 v[222:223], s[26:27], 0, v[130:131]
	s_mov_b32 m0, s56
	global_load_lds_dwordx4 v[222:223], off
	v_lshl_add_u64 v[222:223], s[26:27], 0, v[134:135]
	s_add_i32 m0, s56, 0x2000
	s_nop 0
	global_load_lds_dwordx4 v[222:223], off
	s_waitcnt vmcnt(6)
	s_waitcnt lgkmcnt(0)
	s_barrier
; #define PG8_STAGE(bufoff, gbase, voff) do { _Pragma("unroll") for (int _i = 0; _i < 2; ++_i) \
;         __builtin_amdgcn_global_load_lds((const unsigned*)((const char*)(gbase) + (voff)[_i]), (PG8_LAS unsigned*)(lds + (bufoff) + ldsw + _i * 8192), 16, 0, 0); } while (0)
; #define PG8_LDA(dst, b, h) do { _Pragma("unroll") for (int m = 0; m < 4; ++m) _Pragma("unroll") for (int k = 0; k < 2; ++k) dst[m][k] = *(const PG8_LAS bf16x8*)(lds + PG8_SA(b, h) + aoff + m * 2048 + k * 1024); } while (0)
; #define PG8_LDB(dst, b, h) do { _Pragma("unroll") for (int n = 0; n < 2; ++n) _Pragma("unroll") for (int k = 0; k < 2; ++k) dst[n][k] = *(const PG8_LAS bf16x8*)(lds + PG8_SB(b, h) + boff + n * 2048 + k * 1024); } while (0)
; #define PG8_MMA(ai, bj, At, Bt) do { __builtin_amdgcn_s_setprio(1); _Pragma("unroll") for (int m = 0; m < 4; ++m) _Pragma("unroll") for (int n = 0; n < 2; ++n) _Pragma("unroll") for (int k = 0; k < 2; ++k) \
;         acc[ai][bj][m][n] = __builtin_amdgcn_mfma_f32_16x16x32_bf16(Bt[n][k], At[m][k], acc[ai][bj][m][n], 0, 0, 0); __builtin_amdgcn_s_setprio(0); } while (0)
; #define PG8_WAIT_V(n) asm volatile("s_waitcnt vmcnt(" #n ")" ::: "memory")
; #define PG8_WAIT_L(n) asm volatile("s_waitcnt lgkmcnt(" #n ")" ::: "memory")
; #define PG8_BAR __builtin_amdgcn_s_barrier()
; #define PG8_SCHED __builtin_amdgcn_sched_barrier(0)
; template <class Epi, class Sched, bool ALIGN_EPI = false, bool SP2 = false>
; __device__ __forceinline__ void gemm_phase(PG8_LAS unsigned char* lds, const Gemm g, const Sched& S, const Epi& E) {
;     ...
;             PG8_LDA(At, 0, 1); PG8_STAGE(PG8_SB(0, 0), b2, voffB); PG8_STAGE(PG8_SB(0, 1), b2 + hstep, voffB); PG8_STAGE(PG8_SA(0, 0), a2, voffA);
;             PG8_WAIT_V(8); PG8_WAIT_L(0); PG8_BAR; PG8_MMA(1, 0, At, B0); PG8_MMA(1, 1, At, B1); PG8_BAR; PG8_SCHED;
;             PG8_LDB(B0, 1, 0); PG8_LDB(B1, 1, 1); PG8_SCHED; PG8_LDA(At, 1, 0); PG8_STAGE(PG8_SA(0, 1), a2 + hstep, voffA);
;             PG8_WAIT_V(8); PG8_WAIT_L(0); PG8_BAR; PG8_MMA(0, 0, At, B0); PG8_MMA(0, 1, At, B1); PG8_BAR; PG8_SCHED;
	s_setprio 1
	s_waitcnt lgkmcnt(0)
	v_mfma_f32_16x16x32_bf16 v[60:63], v[144:147], v[184:187], 0
	v_mfma_f32_16x16x32_bf16 v[56:59], v[160:163], v[184:187], 0
	v_mfma_f32_16x16x32_bf16 v[40:43], v[160:163], v[192:195], 0
	v_mfma_f32_16x16x32_bf16 v[44:47], v[144:147], v[192:195], 0
	v_mfma_f32_16x16x32_bf16 v[28:31], v[144:147], v[200:203], 0
	v_mfma_f32_16x16x32_bf16 v[24:27], v[160:163], v[200:203], 0
	v_mfma_f32_16x16x32_bf16 v[8:11], v[160:163], v[210:213], 0
	v_mfma_f32_16x16x32_bf16 v[12:15], v[144:147], v[210:213], 0
	v_mfma_f32_16x16x32_bf16 v[60:63], v[156:159], v[188:191], v[60:63]
	v_mfma_f32_16x16x32_bf16 v[56:59], v[164:167], v[188:191], v[56:59]
	v_mfma_f32_16x16x32_bf16 v[40:43], v[164:167], v[196:199], v[40:43]
	v_mfma_f32_16x16x32_bf16 v[44:47], v[156:159], v[196:199], v[44:47]
	v_mfma_f32_16x16x32_bf16 v[28:31], v[156:159], v[206:209], v[28:31]
	v_mfma_f32_16x16x32_bf16 v[24:27], v[164:167], v[206:209], v[24:27]
	v_lshl_add_u64 v[222:223], s[38:39], 0, v[128:129]
	s_mov_b32 m0, s33
	s_nop 0
	global_load_lds_dwordx4 v[222:223], off
	v_mfma_f32_16x16x32_bf16 v[8:11], v[164:167], v[214:217], v[8:11]
	v_mfma_f32_16x16x32_bf16 v[12:15], v[156:159], v[214:217], v[12:15]
	s_setprio 0
	s_setprio 1
	v_mfma_f32_16x16x32_bf16 v[52:55], v[168:171], v[184:187], 0
	v_mfma_f32_16x16x32_bf16 v[48:51], v[176:179], v[184:187], 0
	v_mfma_f32_16x16x32_bf16 v[32:35], v[176:179], v[192:195], 0
	v_mfma_f32_16x16x32_bf16 v[36:39], v[168:171], v[192:195], 0
	v_mfma_f32_16x16x32_bf16 v[20:23], v[168:171], v[200:203], 0
	v_mfma_f32_16x16x32_bf16 v[16:19], v[176:179], v[200:203], 0
	v_mfma_f32_16x16x32_bf16 v[0:3], v[176:179], v[210:213], 0
	v_mfma_f32_16x16x32_bf16 v[4:7], v[168:171], v[210:213], 0
	v_mfma_f32_16x16x32_bf16 v[52:55], v[172:175], v[188:191], v[52:55]
	v_mfma_f32_16x16x32_bf16 v[48:51], v[180:183], v[188:191], v[48:51]
	v_mfma_f32_16x16x32_bf16 v[32:35], v[180:183], v[196:199], v[32:35]
	v_mfma_f32_16x16x32_bf16 v[36:39], v[172:175], v[196:199], v[36:39]
	v_mfma_f32_16x16x32_bf16 v[20:23], v[172:175], v[206:209], v[20:23]
	v_mfma_f32_16x16x32_bf16 v[16:19], v[180:183], v[206:209], v[16:19]
	v_lshl_add_u64 v[224:225], s[38:39], 0, v[132:133]
	s_mov_b32 m0, s34
	s_nop 0
	global_load_lds_dwordx4 v[224:225], off
	v_mfma_f32_16x16x32_bf16 v[0:3], v[180:183], v[214:217], v[0:3]
	v_mfma_f32_16x16x32_bf16 v[4:7], v[172:175], v[214:217], v[4:7]
	s_setprio 0
	s_barrier
	s_add_i32 s56, 0, 0x18000
	v_add_u32_e32 v155, s56, v149
	s_add_i32 s57, 0, 0x1c000
	ds_read_b128 v[144:147], v155
	ds_read_b128 v[156:159], v155 offset:1024
	ds_read_b128 v[160:163], v155 offset:2048
	ds_read_b128 v[164:167], v155 offset:3072
	v_add_u32_e32 v155, s57, v149
	ds_read_b128 v[168:171], v155
	ds_read_b128 v[172:175], v155 offset:1024
	ds_read_b128 v[176:179], v155 offset:2048
	ds_read_b128 v[180:183], v155 offset:3072
	s_add_u32 s26, s38, 0xb0000
	s_addc_u32 s27, s39, 0
	s_mov_b32 m0, s40
	v_lshl_add_u64 v[226:227], s[26:27], 0, v[128:129]
	ds_read_b128 v[184:187], v153 offset:32768
	ds_read_b128 v[188:191], v153 offset:33792
	ds_read_b128 v[192:195], v153 offset:34816
	ds_read_b128 v[196:199], v153 offset:35840
	ds_read_b128 v[200:203], v153 offset:36864
	ds_read_b128 v[206:209], v153 offset:37888
	ds_read_b128 v[210:213], v153 offset:38912
	ds_read_b128 v[214:217], v153 offset:39936
	global_load_lds_dwordx4 v[226:227], off
	v_lshl_add_u64 v[226:227], s[26:27], 0, v[132:133]
	s_mov_b32 m0, s41
	s_nop 0
	global_load_lds_dwordx4 v[226:227], off
	s_waitcnt vmcnt(8)
	s_waitcnt lgkmcnt(0)
	s_barrier
	s_setprio 1
	s_waitcnt lgkmcnt(0)
	v_mfma_f32_16x16x32_bf16 v[124:127], v[144:147], v[184:187], v[124:127]
	v_mfma_f32_16x16x32_bf16 v[120:123], v[160:163], v[184:187], v[120:123]
	v_mfma_f32_16x16x32_bf16 v[104:107], v[160:163], v[192:195], v[104:107]
	v_mfma_f32_16x16x32_bf16 v[108:111], v[144:147], v[192:195], v[108:111]
	v_mfma_f32_16x16x32_bf16 v[92:95], v[144:147], v[200:203], v[92:95]
	v_mfma_f32_16x16x32_bf16 v[88:91], v[160:163], v[200:203], v[88:91]
	v_mfma_f32_16x16x32_bf16 v[72:75], v[160:163], v[210:213], v[72:75]
	v_mfma_f32_16x16x32_bf16 v[76:79], v[144:147], v[210:213], v[76:79]
	v_mfma_f32_16x16x32_bf16 v[124:127], v[156:159], v[188:191], v[124:127]
	v_mfma_f32_16x16x32_bf16 v[120:123], v[164:167], v[188:191], v[120:123]
	v_mfma_f32_16x16x32_bf16 v[104:107], v[164:167], v[196:199], v[104:107]
	v_mfma_f32_16x16x32_bf16 v[108:111], v[156:159], v[196:199], v[108:111]
	v_mfma_f32_16x16x32_bf16 v[92:95], v[156:159], v[206:209], v[92:95]
	v_mfma_f32_16x16x32_bf16 v[88:91], v[164:167], v[206:209], v[88:91]
	v_mfma_f32_16x16x32_bf16 v[72:75], v[164:167], v[214:217], v[72:75]
	v_mfma_f32_16x16x32_bf16 v[76:79], v[156:159], v[214:217], v[76:79]
	s_setprio 0
	s_setprio 1
	v_mfma_f32_16x16x32_bf16 v[116:119], v[168:171], v[184:187], v[116:119]
	v_mfma_f32_16x16x32_bf16 v[112:115], v[176:179], v[184:187], v[112:115]
	v_mfma_f32_16x16x32_bf16 v[96:99], v[176:179], v[192:195], v[96:99]
	v_mfma_f32_16x16x32_bf16 v[100:103], v[168:171], v[192:195], v[100:103]
	v_mfma_f32_16x16x32_bf16 v[84:87], v[168:171], v[200:203], v[84:87]
	v_mfma_f32_16x16x32_bf16 v[80:83], v[176:179], v[200:203], v[80:83]
	v_mfma_f32_16x16x32_bf16 v[64:67], v[176:179], v[210:213], v[64:67]
	v_mfma_f32_16x16x32_bf16 v[68:71], v[168:171], v[210:213], v[68:71]
	v_mfma_f32_16x16x32_bf16 v[116:119], v[172:175], v[188:191], v[116:119]
	v_mfma_f32_16x16x32_bf16 v[112:115], v[180:183], v[188:191], v[112:115]
	v_mfma_f32_16x16x32_bf16 v[96:99], v[180:183], v[196:199], v[96:99]
	v_mfma_f32_16x16x32_bf16 v[100:103], v[172:175], v[196:199], v[100:103]
	v_mfma_f32_16x16x32_bf16 v[84:87], v[172:175], v[206:209], v[84:87]
	v_mfma_f32_16x16x32_bf16 v[80:83], v[180:183], v[206:209], v[80:83]
	v_mfma_f32_16x16x32_bf16 v[64:67], v[180:183], v[214:217], v[64:67]
	v_mfma_f32_16x16x32_bf16 v[68:71], v[172:175], v[214:217], v[68:71]
	s_setprio 0
	s_barrier
; #define PG8_STAGE(bufoff, gbase, voff) do { _Pragma("unroll") for (int _i = 0; _i < 2; ++_i) \
;         __builtin_amdgcn_global_load_lds((const unsigned*)((const char*)(gbase) + (voff)[_i]), (PG8_LAS unsigned*)(lds + (bufoff) + ldsw + _i * 8192), 16, 0, 0); } while (0)
; #define PG8_LDA(dst, b, h) do { _Pragma("unroll") for (int m = 0; m < 4; ++m) _Pragma("unroll") for (int k = 0; k < 2; ++k) dst[m][k] = *(const PG8_LAS bf16x8*)(lds + PG8_SA(b, h) + aoff + m * 2048 + k * 1024); } while (0)
; #define PG8_LDB(dst, b, h) do { _Pragma("unroll") for (int n = 0; n < 2; ++n) _Pragma("unroll") for (int k = 0; k < 2; ++k) dst[n][k] = *(const PG8_LAS bf16x8*)(lds + PG8_SB(b, h) + boff + n * 2048 + k * 1024); } while (0)
; #define PG8_MMA(ai, bj, At, Bt) do { __builtin_amdgcn_s_setprio(1); _Pragma("unroll") for (int m = 0; m < 4; ++m) _Pragma("unroll") for (int n = 0; n < 2; ++n) _Pragma("unroll") for (int k = 0; k < 2; ++k) \
;         acc[ai][bj][m][n] = __builtin_amdgcn_mfma_f32_16x16x32_bf16(Bt[n][k], At[m][k], acc[ai][bj][m][n], 0, 0, 0); __builtin_amdgcn_s_setprio(0); } while (0)
; #define PG8_WAIT_V(n) asm volatile("s_waitcnt vmcnt(" #n ")" ::: "memory")
; template <class Epi, class Sched, bool ALIGN_EPI = false, bool SP2 = false>
; __device__ __forceinline__ void gemm_phase(PG8_LAS unsigned char* lds, const Gemm g, const Sched& S, const Epi& E) {
;     ...
;             PG8_LDB(B0, 0, 0); PG8_LDB(B1, 0, 1); PG8_SCHED; PG8_LDA(At, 0, 0); PG8_STAGE(PG8_SA(1, 1), a1 + hstep, voffA);
;             PG8_WAIT_V(8); PG8_WAIT_L(0); PG8_BAR; PG8_MMA(0, 0, At, B0); PG8_MMA(0, 1, At, B1); PG8_BAR; PG8_SCHED;
;             PG8_LDA(At, 0, 1); PG8_STAGE(PG8_SB(0, 0), b2, voffB); PG8_STAGE(PG8_SB(0, 1), b2 + hstep, voffB); PG8_STAGE(PG8_SA(0, 0), a2, voffA);
;             PG8_WAIT_V(8); PG8_WAIT_L(0); PG8_BAR; PG8_MMA(1, 0, At, B0); PG8_MMA(1, 1, At, B1); PG8_BAR; PG8_SCHED;
;             PG8_LDB(B0, 1, 0); PG8_LDB(B1, 1, 1); PG8_SCHED; PG8_LDA(At, 1, 0); PG8_STAGE(PG8_SA(0, 1), a2 + hstep, voffA);
;             PG8_WAIT_V(8); PG8_WAIT_L(0); PG8_BAR; PG8_MMA(0, 0, At, B0); PG8_MMA(0, 1, At, B1); PG8_BAR; PG8_SCHED;
;             PG8_LDA(At, 1, 1); PG8_STAGE(PG8_SB(1, 0), b3, voffB); PG8_STAGE(PG8_SB(1, 1), b3 + hstep, voffB); PG8_STAGE(PG8_SA(1, 0), a3, voffA);
;             PG8_WAIT_V(8); PG8_WAIT_L(0); PG8_BAR; PG8_MMA(1, 0, At, B0); PG8_MMA(1, 1, At, B1); PG8_BAR; PG8_SCHED;
	s_add_i32 s26, s56, s15
	v_lshl_add_u64 v[218:219], v[218:219], 0, s[12:13]
	s_mov_b32 m0, s26
	ds_read_b128 v[184:187], v153 offset:49152
	ds_read_b128 v[188:191], v153 offset:50176
	ds_read_b128 v[192:195], v153 offset:51200
	ds_read_b128 v[196:199], v153 offset:52224
	ds_read_b128 v[200:203], v153 offset:53248
	ds_read_b128 v[206:209], v153 offset:54272
	ds_read_b128 v[210:213], v153 offset:55296
	ds_read_b128 v[214:217], v153 offset:56320
	global_load_lds_dwordx4 v[218:219], off
	s_add_i32 m0, s26, 0x2000
	s_add_u32 s26, s36, 0xb0080
	v_lshl_add_u64 v[218:219], v[220:221], 0, s[12:13]
	s_addc_u32 s27, s37, 0
	s_add_i32 s36, s57, s15
	global_load_lds_dwordx4 v[218:219], off
	v_lshl_add_u64 v[218:219], s[26:27], 0, v[130:131]
	s_mov_b32 m0, s36
	s_nop 0
	global_load_lds_dwordx4 v[218:219], off
	v_lshl_add_u64 v[218:219], s[26:27], 0, v[134:135]
	s_add_i32 m0, s36, 0x2000
	s_nop 0
	global_load_lds_dwordx4 v[218:219], off
	s_waitcnt vmcnt(6)
	s_waitcnt lgkmcnt(0)
	s_barrier
	s_setprio 1
	s_waitcnt lgkmcnt(0)
	v_mfma_f32_16x16x32_bf16 v[60:63], v[144:147], v[184:187], v[60:63]
	v_mfma_f32_16x16x32_bf16 v[56:59], v[160:163], v[184:187], v[56:59]
	v_mfma_f32_16x16x32_bf16 v[40:43], v[160:163], v[192:195], v[40:43]
	v_mfma_f32_16x16x32_bf16 v[44:47], v[144:147], v[192:195], v[44:47]
	v_mfma_f32_16x16x32_bf16 v[28:31], v[144:147], v[200:203], v[28:31]
	v_mfma_f32_16x16x32_bf16 v[24:27], v[160:163], v[200:203], v[24:27]
	v_mfma_f32_16x16x32_bf16 v[8:11], v[160:163], v[210:213], v[8:11]
	v_mfma_f32_16x16x32_bf16 v[12:15], v[144:147], v[210:213], v[12:15]
	v_mfma_f32_16x16x32_bf16 v[60:63], v[156:159], v[188:191], v[60:63]
	v_mfma_f32_16x16x32_bf16 v[56:59], v[164:167], v[188:191], v[56:59]
	v_mfma_f32_16x16x32_bf16 v[40:43], v[164:167], v[196:199], v[40:43]
	v_mfma_f32_16x16x32_bf16 v[44:47], v[156:159], v[196:199], v[44:47]
	v_mfma_f32_16x16x32_bf16 v[28:31], v[156:159], v[206:209], v[28:31]
	v_mfma_f32_16x16x32_bf16 v[24:27], v[164:167], v[206:209], v[24:27]
	v_lshl_add_u64 v[218:219], v[222:223], 0, s[12:13]
	s_mov_b32 m0, s43
	s_nop 0
	global_load_lds_dwordx4 v[218:219], off
	v_mfma_f32_16x16x32_bf16 v[8:11], v[164:167], v[214:217], v[8:11]
	v_mfma_f32_16x16x32_bf16 v[12:15], v[156:159], v[214:217], v[12:15]
	s_setprio 0
	s_setprio 1
	v_mfma_f32_16x16x32_bf16 v[52:55], v[168:171], v[184:187], v[52:55]
	v_mfma_f32_16x16x32_bf16 v[48:51], v[176:179], v[184:187], v[48:51]
	v_mfma_f32_16x16x32_bf16 v[32:35], v[176:179], v[192:195], v[32:35]
	v_mfma_f32_16x16x32_bf16 v[36:39], v[168:171], v[192:195], v[36:39]
	v_mfma_f32_16x16x32_bf16 v[20:23], v[168:171], v[200:203], v[20:23]
	v_mfma_f32_16x16x32_bf16 v[16:19], v[176:179], v[200:203], v[16:19]
	v_mfma_f32_16x16x32_bf16 v[0:3], v[176:179], v[210:213], v[0:3]
	v_mfma_f32_16x16x32_bf16 v[4:7], v[168:171], v[210:213], v[4:7]
	v_mfma_f32_16x16x32_bf16 v[52:55], v[172:175], v[188:191], v[52:55]
	v_mfma_f32_16x16x32_bf16 v[48:51], v[180:183], v[188:191], v[48:51]
	v_mfma_f32_16x16x32_bf16 v[32:35], v[180:183], v[196:199], v[32:35]
	v_mfma_f32_16x16x32_bf16 v[36:39], v[172:175], v[196:199], v[36:39]
	v_mfma_f32_16x16x32_bf16 v[20:23], v[172:175], v[206:209], v[20:23]
	v_mfma_f32_16x16x32_bf16 v[16:19], v[180:183], v[206:209], v[16:19]
	v_lshl_add_u64 v[218:219], v[224:225], 0, s[12:13]
	s_mov_b32 m0, s44
	s_nop 0
	global_load_lds_dwordx4 v[218:219], off
	v_mfma_f32_16x16x32_bf16 v[0:3], v[180:183], v[214:217], v[0:3]
	v_mfma_f32_16x16x32_bf16 v[4:7], v[172:175], v[214:217], v[4:7]
	s_setprio 0
	s_barrier
	s_add_i32 s55, s55, 2
	s_add_u32 s53, s53, 0x100
	s_addc_u32 s54, s54, 0
	s_mov_b64 s[26:27], s[28:29]
.LBB0_1978:
	ds_read_b128 v[144:147], v151
	ds_read_b128 v[156:159], v151 offset:1024
	ds_read_b128 v[160:163], v151 offset:2048
	ds_read_b128 v[164:167], v151 offset:3072
	ds_read_b128 v[168:171], v152
	ds_read_b128 v[172:175], v152 offset:1024
	ds_read_b128 v[176:179], v152 offset:2048
	ds_read_b128 v[180:183], v152 offset:3072
	s_add_u32 s28, s26, 0x100
	s_addc_u32 s29, s27, 0
	s_cmp_eq_u32 s55, 40
	s_cselect_b32 s39, s1, s29
	s_cselect_b32 s38, s0, s28
	s_cselect_b32 s37, s25, s54
	s_cselect_b32 s36, s24, s53
	v_lshl_add_u64 v[218:219], s[26:27], 0, v[136:137]
	s_add_i32 m0, s33, 0xc000
	ds_read_b128 v[184:187], v153
	ds_read_b128 v[188:191], v153 offset:1024
	ds_read_b128 v[192:195], v153 offset:2048
	ds_read_b128 v[196:199], v153 offset:3072
	ds_read_b128 v[200:203], v153 offset:4096
	ds_read_b128 v[206:209], v153 offset:5120
	ds_read_b128 v[210:213], v153 offset:6144
	ds_read_b128 v[214:217], v153 offset:7168
	global_load_lds_dwordx4 v[218:219], off
	v_lshl_add_u64 v[218:219], s[26:27], 0, v[138:139]
	s_add_i32 m0, s33, 0xe000
	s_nop 0
	global_load_lds_dwordx4 v[218:219], off
	s_waitcnt vmcnt(8)
	s_waitcnt lgkmcnt(0)
	s_barrier
; #define PG8_STAGE(bufoff, gbase, voff) do { _Pragma("unroll") for (int _i = 0; _i < 2; ++_i) \
;         __builtin_amdgcn_global_load_lds((const unsigned*)((const char*)(gbase) + (voff)[_i]), (PG8_LAS unsigned*)(lds + (bufoff) + ldsw + _i * 8192), 16, 0, 0); } while (0)
; #define PG8_LDA(dst, b, h) do { _Pragma("unroll") for (int m = 0; m < 4; ++m) _Pragma("unroll") for (int k = 0; k < 2; ++k) dst[m][k] = *(const PG8_LAS bf16x8*)(lds + PG8_SA(b, h) + aoff + m * 2048 + k * 1024); } while (0)
; #define PG8_LDB(dst, b, h) do { _Pragma("unroll") for (int n = 0; n < 2; ++n) _Pragma("unroll") for (int k = 0; k < 2; ++k) dst[n][k] = *(const PG8_LAS bf16x8*)(lds + PG8_SB(b, h) + boff + n * 2048 + k * 1024); } while (0)
; #define PG8_MMA(ai, bj, At, Bt) do { __builtin_amdgcn_s_setprio(1); _Pragma("unroll") for (int m = 0; m < 4; ++m) _Pragma("unroll") for (int n = 0; n < 2; ++n) _Pragma("unroll") for (int k = 0; k < 2; ++k) \
;         acc[ai][bj][m][n] = __builtin_amdgcn_mfma_f32_16x16x32_bf16(Bt[n][k], At[m][k], acc[ai][bj][m][n], 0, 0, 0); __builtin_amdgcn_s_setprio(0); } while (0)
; #define PG8_WAIT_V(n) asm volatile("s_waitcnt vmcnt(" #n ")" ::: "memory")
; #define PG8_WAIT_L(n) asm volatile("s_waitcnt lgkmcnt(" #n ")" ::: "memory")
; #define PG8_BAR __builtin_amdgcn_s_barrier()
; #define PG8_SCHED __builtin_amdgcn_sched_barrier(0)
; template <class Epi, class Sched, bool ALIGN_EPI = false, bool SP2 = false>
; __device__ __forceinline__ void gemm_phase(PG8_LAS unsigned char* lds, const Gemm g, const Sched& S, const Epi& E) {
;     ...
;             PG8_LDB(B0, 0, 0); PG8_LDB(B1, 0, 1); PG8_SCHED; PG8_LDA(At, 0, 0); PG8_STAGE(PG8_SA(1, 1), a1 + hstep, voffA);
;             PG8_WAIT_V(8); PG8_WAIT_L(0); PG8_BAR; PG8_MMA(0, 0, At, B0); PG8_MMA(0, 1, At, B1); PG8_BAR; PG8_SCHED;
;             PG8_LDA(At, 0, 1); PG8_STAGE(PG8_SB(0, 0), b2, voffB); PG8_STAGE(PG8_SB(0, 1), b2 + hstep, voffB); PG8_STAGE(PG8_SA(0, 0), a2, voffA);
;             PG8_WAIT_V(8); PG8_WAIT_L(0); PG8_BAR; PG8_MMA(1, 0, At, B0); PG8_MMA(1, 1, At, B1); PG8_BAR; PG8_SCHED;
;             PG8_LDB(B0, 1, 0); PG8_LDB(B1, 1, 1); PG8_SCHED; PG8_LDA(At, 1, 0); PG8_STAGE(PG8_SA(0, 1), a2 + hstep, voffA);
;             PG8_WAIT_V(8); PG8_WAIT_L(0); PG8_BAR; PG8_MMA(0, 0, At, B0); PG8_MMA(0, 1, At, B1); PG8_BAR; PG8_SCHED;
	s_setprio 1
	s_waitcnt lgkmcnt(0)
	v_mfma_f32_16x16x32_bf16 v[124:127], v[144:147], v[184:187], v[124:127]
	v_mfma_f32_16x16x32_bf16 v[120:123], v[160:163], v[184:187], v[120:123]
	v_mfma_f32_16x16x32_bf16 v[104:107], v[160:163], v[192:195], v[104:107]
	v_mfma_f32_16x16x32_bf16 v[108:111], v[144:147], v[192:195], v[108:111]
	v_mfma_f32_16x16x32_bf16 v[92:95], v[144:147], v[200:203], v[92:95]
	v_mfma_f32_16x16x32_bf16 v[88:91], v[160:163], v[200:203], v[88:91]
	v_mfma_f32_16x16x32_bf16 v[72:75], v[160:163], v[210:213], v[72:75]
	v_mfma_f32_16x16x32_bf16 v[76:79], v[144:147], v[210:213], v[76:79]
	v_mfma_f32_16x16x32_bf16 v[124:127], v[156:159], v[188:191], v[124:127]
	v_mfma_f32_16x16x32_bf16 v[120:123], v[164:167], v[188:191], v[120:123]
	v_mfma_f32_16x16x32_bf16 v[104:107], v[164:167], v[196:199], v[104:107]
	v_mfma_f32_16x16x32_bf16 v[108:111], v[156:159], v[196:199], v[108:111]
	v_mfma_f32_16x16x32_bf16 v[92:95], v[156:159], v[206:209], v[92:95]
	v_mfma_f32_16x16x32_bf16 v[88:91], v[164:167], v[206:209], v[88:91]
	v_mfma_f32_16x16x32_bf16 v[72:75], v[164:167], v[214:217], v[72:75]
	v_mfma_f32_16x16x32_bf16 v[76:79], v[156:159], v[214:217], v[76:79]
	s_setprio 0
	s_setprio 1
	v_mfma_f32_16x16x32_bf16 v[116:119], v[168:171], v[184:187], v[116:119]
	v_mfma_f32_16x16x32_bf16 v[112:115], v[176:179], v[184:187], v[112:115]
	v_mfma_f32_16x16x32_bf16 v[96:99], v[176:179], v[192:195], v[96:99]
	v_mfma_f32_16x16x32_bf16 v[100:103], v[168:171], v[192:195], v[100:103]
	v_mfma_f32_16x16x32_bf16 v[84:87], v[168:171], v[200:203], v[84:87]
	v_mfma_f32_16x16x32_bf16 v[80:83], v[176:179], v[200:203], v[80:83]
	v_mfma_f32_16x16x32_bf16 v[64:67], v[176:179], v[210:213], v[64:67]
	v_mfma_f32_16x16x32_bf16 v[68:71], v[168:171], v[210:213], v[68:71]
	v_mfma_f32_16x16x32_bf16 v[116:119], v[172:175], v[188:191], v[116:119]
	v_mfma_f32_16x16x32_bf16 v[112:115], v[180:183], v[188:191], v[112:115]
	v_mfma_f32_16x16x32_bf16 v[96:99], v[180:183], v[196:199], v[96:99]
	v_mfma_f32_16x16x32_bf16 v[100:103], v[172:175], v[196:199], v[100:103]
	v_mfma_f32_16x16x32_bf16 v[84:87], v[172:175], v[206:209], v[84:87]
	v_mfma_f32_16x16x32_bf16 v[80:83], v[180:183], v[206:209], v[80:83]
	v_mfma_f32_16x16x32_bf16 v[64:67], v[180:183], v[214:217], v[64:67]
	v_mfma_f32_16x16x32_bf16 v[68:71], v[172:175], v[214:217], v[68:71]
	s_setprio 0
	s_barrier
	s_add_i32 s26, s45, s15
	v_lshl_add_u64 v[218:219], s[36:37], 0, v[130:131]
	s_mov_b32 m0, s26
	ds_read_b128 v[184:187], v153 offset:16384
	ds_read_b128 v[188:191], v153 offset:17408
	ds_read_b128 v[192:195], v153 offset:18432
	ds_read_b128 v[196:199], v153 offset:19456
	ds_read_b128 v[200:203], v153 offset:20480
	ds_read_b128 v[206:209], v153 offset:21504
	ds_read_b128 v[210:213], v153 offset:22528
	ds_read_b128 v[214:217], v153 offset:23552
	global_load_lds_dwordx4 v[218:219], off
	s_add_i32 m0, s26, 0x2000
	s_add_u32 s26, s36, 0xb0000
	v_lshl_add_u64 v[220:221], s[36:37], 0, v[134:135]
	s_addc_u32 s27, s37, 0
	s_add_i32 s56, s46, s15
	global_load_lds_dwordx4 v[220:221], off
	v_lshl_add_u64 v[222:223], s[26:27], 0, v[130:131]
	s_mov_b32 m0, s56
	global_load_lds_dwordx4 v[222:223], off
	v_lshl_add_u64 v[222:223], s[26:27], 0, v[134:135]
	s_add_i32 m0, s56, 0x2000
	s_nop 0
	global_load_lds_dwordx4 v[222:223], off
	s_waitcnt vmcnt(6)
	s_waitcnt lgkmcnt(0)
	s_barrier
	s_setprio 1
	s_waitcnt lgkmcnt(0)
	v_mfma_f32_16x16x32_bf16 v[60:63], v[144:147], v[184:187], v[60:63]
	v_mfma_f32_16x16x32_bf16 v[56:59], v[160:163], v[184:187], v[56:59]
	v_mfma_f32_16x16x32_bf16 v[40:43], v[160:163], v[192:195], v[40:43]
	v_mfma_f32_16x16x32_bf16 v[44:47], v[144:147], v[192:195], v[44:47]
	v_mfma_f32_16x16x32_bf16 v[28:31], v[144:147], v[200:203], v[28:31]
	v_mfma_f32_16x16x32_bf16 v[24:27], v[160:163], v[200:203], v[24:27]
	v_mfma_f32_16x16x32_bf16 v[8:11], v[160:163], v[210:213], v[8:11]
	v_mfma_f32_16x16x32_bf16 v[12:15], v[144:147], v[210:213], v[12:15]
	v_mfma_f32_16x16x32_bf16 v[60:63], v[156:159], v[188:191], v[60:63]
	v_mfma_f32_16x16x32_bf16 v[56:59], v[164:167], v[188:191], v[56:59]
	v_mfma_f32_16x16x32_bf16 v[40:43], v[164:167], v[196:199], v[40:43]
	v_mfma_f32_16x16x32_bf16 v[44:47], v[156:159], v[196:199], v[44:47]
	v_mfma_f32_16x16x32_bf16 v[28:31], v[156:159], v[206:209], v[28:31]
	v_mfma_f32_16x16x32_bf16 v[24:27], v[164:167], v[206:209], v[24:27]
	v_lshl_add_u64 v[222:223], s[38:39], 0, v[128:129]
	s_mov_b32 m0, s33
	s_nop 0
	global_load_lds_dwordx4 v[222:223], off
	v_mfma_f32_16x16x32_bf16 v[8:11], v[164:167], v[214:217], v[8:11]
	v_mfma_f32_16x16x32_bf16 v[12:15], v[156:159], v[214:217], v[12:15]
	s_setprio 0
	s_setprio 1
	v_mfma_f32_16x16x32_bf16 v[52:55], v[168:171], v[184:187], v[52:55]
	v_mfma_f32_16x16x32_bf16 v[48:51], v[176:179], v[184:187], v[48:51]
	v_mfma_f32_16x16x32_bf16 v[32:35], v[176:179], v[192:195], v[32:35]
	v_mfma_f32_16x16x32_bf16 v[36:39], v[168:171], v[192:195], v[36:39]
	v_mfma_f32_16x16x32_bf16 v[20:23], v[168:171], v[200:203], v[20:23]
	v_mfma_f32_16x16x32_bf16 v[16:19], v[176:179], v[200:203], v[16:19]
	v_mfma_f32_16x16x32_bf16 v[0:3], v[176:179], v[210:213], v[0:3]
	v_mfma_f32_16x16x32_bf16 v[4:7], v[168:171], v[210:213], v[4:7]
	v_mfma_f32_16x16x32_bf16 v[52:55], v[172:175], v[188:191], v[52:55]
	v_mfma_f32_16x16x32_bf16 v[48:51], v[180:183], v[188:191], v[48:51]
	v_mfma_f32_16x16x32_bf16 v[32:35], v[180:183], v[196:199], v[32:35]
	v_mfma_f32_16x16x32_bf16 v[36:39], v[172:175], v[196:199], v[36:39]
	v_mfma_f32_16x16x32_bf16 v[20:23], v[172:175], v[206:209], v[20:23]
	v_mfma_f32_16x16x32_bf16 v[16:19], v[180:183], v[206:209], v[16:19]
	v_lshl_add_u64 v[224:225], s[38:39], 0, v[132:133]
	s_mov_b32 m0, s34
	s_nop 0
	global_load_lds_dwordx4 v[224:225], off
	v_mfma_f32_16x16x32_bf16 v[0:3], v[180:183], v[214:217], v[0:3]
	v_mfma_f32_16x16x32_bf16 v[4:7], v[172:175], v[214:217], v[4:7]
	s_setprio 0
	s_barrier
; #define PG8_STAGE(bufoff, gbase, voff) do { _Pragma("unroll") for (int _i = 0; _i < 2; ++_i) \
;         __builtin_amdgcn_global_load_lds((const unsigned*)((const char*)(gbase) + (voff)[_i]), (PG8_LAS unsigned*)(lds + (bufoff) + ldsw + _i * 8192), 16, 0, 0); } while (0)
; #define PG8_LDA(dst, b, h) do { _Pragma("unroll") for (int m = 0; m < 4; ++m) _Pragma("unroll") for (int k = 0; k < 2; ++k) dst[m][k] = *(const PG8_LAS bf16x8*)(lds + PG8_SA(b, h) + aoff + m * 2048 + k * 1024); } while (0)
; #define PG8_LDB(dst, b, h) do { _Pragma("unroll") for (int n = 0; n < 2; ++n) _Pragma("unroll") for (int k = 0; k < 2; ++k) dst[n][k] = *(const PG8_LAS bf16x8*)(lds + PG8_SB(b, h) + boff + n * 2048 + k * 1024); } while (0)
; #define PG8_MMA(ai, bj, At, Bt) do { __builtin_amdgcn_s_setprio(1); _Pragma("unroll") for (int m = 0; m < 4; ++m) _Pragma("unroll") for (int n = 0; n < 2; ++n) _Pragma("unroll") for (int k = 0; k < 2; ++k) \
;         acc[ai][bj][m][n] = __builtin_amdgcn_mfma_f32_16x16x32_bf16(Bt[n][k], At[m][k], acc[ai][bj][m][n], 0, 0, 0); __builtin_amdgcn_s_setprio(0); } while (0)
; #define PG8_WAIT_V(n) asm volatile("s_waitcnt vmcnt(" #n ")" ::: "memory")
; #define PG8_WAIT_L(n) asm volatile("s_waitcnt lgkmcnt(" #n ")" ::: "memory")
; #define PG8_BAR __builtin_amdgcn_s_barrier()
; #define PG8_SCHED __builtin_amdgcn_sched_barrier(0)
; template <class Epi, class Sched, bool ALIGN_EPI = false, bool SP2 = false>
; __device__ __forceinline__ void gemm_phase(PG8_LAS unsigned char* lds, const Gemm g, const Sched& S, const Epi& E) {
;     ...
;             PG8_LDB(B0, 1, 0); PG8_LDB(B1, 1, 1); PG8_SCHED; PG8_LDA(At, 1, 0); PG8_STAGE(PG8_SA(0, 1), a2 + hstep, voffA);
;             PG8_WAIT_V(8); PG8_WAIT_L(0); PG8_BAR; PG8_MMA(0, 0, At, B0); PG8_MMA(0, 1, At, B1); PG8_BAR; PG8_SCHED;
	s_add_i32 s56, 0, 0x18000
	v_add_u32_e32 v155, s56, v149
	s_add_i32 s57, 0, 0x1c000
	ds_read_b128 v[144:147], v155
	ds_read_b128 v[156:159], v155 offset:1024
	ds_read_b128 v[160:163], v155 offset:2048
	ds_read_b128 v[164:167], v155 offset:3072
	v_add_u32_e32 v155, s57, v149
	ds_read_b128 v[168:171], v155
	ds_read_b128 v[172:175], v155 offset:1024
	ds_read_b128 v[176:179], v155 offset:2048
	ds_read_b128 v[180:183], v155 offset:3072
	s_add_u32 s26, s38, 0xb0000
	s_addc_u32 s27, s39, 0
	s_mov_b32 m0, s40
	v_lshl_add_u64 v[226:227], s[26:27], 0, v[128:129]
	ds_read_b128 v[184:187], v153 offset:32768
	ds_read_b128 v[188:191], v153 offset:33792
	ds_read_b128 v[192:195], v153 offset:34816
	ds_read_b128 v[196:199], v153 offset:35840
	ds_read_b128 v[200:203], v153 offset:36864
	ds_read_b128 v[206:209], v153 offset:37888
	ds_read_b128 v[210:213], v153 offset:38912
	ds_read_b128 v[214:217], v153 offset:39936
	global_load_lds_dwordx4 v[226:227], off
	v_lshl_add_u64 v[226:227], s[26:27], 0, v[132:133]
	s_mov_b32 m0, s41
	s_nop 0
	global_load_lds_dwordx4 v[226:227], off
	s_waitcnt vmcnt(8)
	s_waitcnt lgkmcnt(0)
	s_barrier
	s_setprio 1
	s_waitcnt lgkmcnt(0)
	v_mfma_f32_16x16x32_bf16 v[124:127], v[144:147], v[184:187], v[124:127]
	v_mfma_f32_16x16x32_bf16 v[120:123], v[160:163], v[184:187], v[120:123]
	v_mfma_f32_16x16x32_bf16 v[104:107], v[160:163], v[192:195], v[104:107]
	v_mfma_f32_16x16x32_bf16 v[108:111], v[144:147], v[192:195], v[108:111]
	v_mfma_f32_16x16x32_bf16 v[92:95], v[144:147], v[200:203], v[92:95]
	v_mfma_f32_16x16x32_bf16 v[88:91], v[160:163], v[200:203], v[88:91]
	v_mfma_f32_16x16x32_bf16 v[72:75], v[160:163], v[210:213], v[72:75]
	v_mfma_f32_16x16x32_bf16 v[76:79], v[144:147], v[210:213], v[76:79]
	v_mfma_f32_16x16x32_bf16 v[124:127], v[156:159], v[188:191], v[124:127]
	v_mfma_f32_16x16x32_bf16 v[120:123], v[164:167], v[188:191], v[120:123]
	v_mfma_f32_16x16x32_bf16 v[104:107], v[164:167], v[196:199], v[104:107]
	v_mfma_f32_16x16x32_bf16 v[108:111], v[156:159], v[196:199], v[108:111]
	v_mfma_f32_16x16x32_bf16 v[92:95], v[156:159], v[206:209], v[92:95]
	v_mfma_f32_16x16x32_bf16 v[88:91], v[164:167], v[206:209], v[88:91]
	v_mfma_f32_16x16x32_bf16 v[72:75], v[164:167], v[214:217], v[72:75]
	v_mfma_f32_16x16x32_bf16 v[76:79], v[156:159], v[214:217], v[76:79]
	s_setprio 0
	s_setprio 1
	v_mfma_f32_16x16x32_bf16 v[116:119], v[168:171], v[184:187], v[116:119]
	v_mfma_f32_16x16x32_bf16 v[112:115], v[176:179], v[184:187], v[112:115]
	v_mfma_f32_16x16x32_bf16 v[96:99], v[176:179], v[192:195], v[96:99]
	v_mfma_f32_16x16x32_bf16 v[100:103], v[168:171], v[192:195], v[100:103]
	v_mfma_f32_16x16x32_bf16 v[84:87], v[168:171], v[200:203], v[84:87]
	v_mfma_f32_16x16x32_bf16 v[80:83], v[176:179], v[200:203], v[80:83]
	v_mfma_f32_16x16x32_bf16 v[64:67], v[176:179], v[210:213], v[64:67]
	v_mfma_f32_16x16x32_bf16 v[68:71], v[168:171], v[210:213], v[68:71]
	v_mfma_f32_16x16x32_bf16 v[116:119], v[172:175], v[188:191], v[116:119]
	v_mfma_f32_16x16x32_bf16 v[112:115], v[180:183], v[188:191], v[112:115]
	v_mfma_f32_16x16x32_bf16 v[96:99], v[180:183], v[196:199], v[96:99]
	v_mfma_f32_16x16x32_bf16 v[100:103], v[172:175], v[196:199], v[100:103]
	v_mfma_f32_16x16x32_bf16 v[84:87], v[172:175], v[206:209], v[84:87]
	v_mfma_f32_16x16x32_bf16 v[80:83], v[180:183], v[206:209], v[80:83]
	v_mfma_f32_16x16x32_bf16 v[64:67], v[180:183], v[214:217], v[64:67]
	v_mfma_f32_16x16x32_bf16 v[68:71], v[172:175], v[214:217], v[68:71]
	s_setprio 0
	s_barrier
; #define PG8_STAGE(bufoff, gbase, voff) do { _Pragma("unroll") for (int _i = 0; _i < 2; ++_i) \
;         __builtin_amdgcn_global_load_lds((const unsigned*)((const char*)(gbase) + (voff)[_i]), (PG8_LAS unsigned*)(lds + (bufoff) + ldsw + _i * 8192), 16, 0, 0); } while (0)
; #define PG8_LDA(dst, b, h) do { _Pragma("unroll") for (int m = 0; m < 4; ++m) _Pragma("unroll") for (int k = 0; k < 2; ++k) dst[m][k] = *(const PG8_LAS bf16x8*)(lds + PG8_SA(b, h) + aoff + m * 2048 + k * 1024); } while (0)
; #define PG8_MMA(ai, bj, At, Bt) do { __builtin_amdgcn_s_setprio(1); _Pragma("unroll") for (int m = 0; m < 4; ++m) _Pragma("unroll") for (int n = 0; n < 2; ++n) _Pragma("unroll") for (int k = 0; k < 2; ++k) \
;         acc[ai][bj][m][n] = __builtin_amdgcn_mfma_f32_16x16x32_bf16(Bt[n][k], At[m][k], acc[ai][bj][m][n], 0, 0, 0); __builtin_amdgcn_s_setprio(0); } while (0)
; #define PG8_WAIT_V(n) asm volatile("s_waitcnt vmcnt(" #n ")" ::: "memory")
; #define PG8_WAIT_L(n) asm volatile("s_waitcnt lgkmcnt(" #n ")" ::: "memory")
; #define PG8_BAR __builtin_amdgcn_s_barrier()
; #define PG8_SCHED __builtin_amdgcn_sched_barrier(0)
; template <class Epi, class Sched, bool ALIGN_EPI = false, bool SP2 = false>
; __device__ __forceinline__ void gemm_phase(PG8_LAS unsigned char* lds, const Gemm g, const Sched& S, const Epi& E) {
;     ...
;             PG8_LDA(At, 1, 1); PG8_STAGE(PG8_SB(1, 0), b3, voffB); PG8_STAGE(PG8_SB(1, 1), b3 + hstep, voffB); PG8_STAGE(PG8_SA(1, 0), a3, voffA);
;             PG8_WAIT_V(8); PG8_WAIT_L(0); PG8_BAR; PG8_MMA(1, 0, At, B0); PG8_MMA(1, 1, At, B1); PG8_BAR; PG8_SCHED;
;     ...
;         if constexpr (ALIGN_EPI) { if (wr == 0) PG8_BAR; }
	s_add_i32 s26, s56, s15
	v_lshl_add_u64 v[218:219], v[218:219], 0, s[12:13]
	s_mov_b32 m0, s26
	ds_read_b128 v[184:187], v153 offset:49152
	ds_read_b128 v[188:191], v153 offset:50176
	ds_read_b128 v[192:195], v153 offset:51200
	ds_read_b128 v[196:199], v153 offset:52224
	ds_read_b128 v[200:203], v153 offset:53248
	ds_read_b128 v[206:209], v153 offset:54272
	ds_read_b128 v[210:213], v153 offset:55296
	ds_read_b128 v[214:217], v153 offset:56320
	global_load_lds_dwordx4 v[218:219], off
	s_add_i32 m0, s26, 0x2000
	s_add_u32 s26, s36, 0xb0080
	v_lshl_add_u64 v[218:219], v[220:221], 0, s[12:13]
	s_addc_u32 s27, s37, 0
	s_add_i32 s36, s57, s15
	global_load_lds_dwordx4 v[218:219], off
	v_lshl_add_u64 v[218:219], s[26:27], 0, v[130:131]
	s_mov_b32 m0, s36
	s_nop 0
	global_load_lds_dwordx4 v[218:219], off
	v_lshl_add_u64 v[218:219], s[26:27], 0, v[134:135]
	s_add_i32 m0, s36, 0x2000
	s_nop 0
	global_load_lds_dwordx4 v[218:219], off
	s_waitcnt vmcnt(6)
	s_waitcnt lgkmcnt(0)
	s_barrier
	s_setprio 1
	s_waitcnt lgkmcnt(0)
	v_mfma_f32_16x16x32_bf16 v[60:63], v[144:147], v[184:187], v[60:63]
	v_mfma_f32_16x16x32_bf16 v[56:59], v[160:163], v[184:187], v[56:59]
	v_mfma_f32_16x16x32_bf16 v[40:43], v[160:163], v[192:195], v[40:43]
	v_mfma_f32_16x16x32_bf16 v[44:47], v[144:147], v[192:195], v[44:47]
	v_mfma_f32_16x16x32_bf16 v[28:31], v[144:147], v[200:203], v[28:31]
	v_mfma_f32_16x16x32_bf16 v[24:27], v[160:163], v[200:203], v[24:27]
	v_mfma_f32_16x16x32_bf16 v[8:11], v[160:163], v[210:213], v[8:11]
	v_mfma_f32_16x16x32_bf16 v[12:15], v[144:147], v[210:213], v[12:15]
	v_mfma_f32_16x16x32_bf16 v[60:63], v[156:159], v[188:191], v[60:63]
	v_mfma_f32_16x16x32_bf16 v[56:59], v[164:167], v[188:191], v[56:59]
	v_mfma_f32_16x16x32_bf16 v[40:43], v[164:167], v[196:199], v[40:43]
	v_mfma_f32_16x16x32_bf16 v[44:47], v[156:159], v[196:199], v[44:47]
	v_mfma_f32_16x16x32_bf16 v[28:31], v[156:159], v[206:209], v[28:31]
	v_mfma_f32_16x16x32_bf16 v[24:27], v[164:167], v[206:209], v[24:27]
	v_lshl_add_u64 v[218:219], v[222:223], 0, s[12:13]
	s_mov_b32 m0, s43
	s_nop 0
	global_load_lds_dwordx4 v[218:219], off
	v_mfma_f32_16x16x32_bf16 v[8:11], v[164:167], v[214:217], v[8:11]
	v_mfma_f32_16x16x32_bf16 v[12:15], v[156:159], v[214:217], v[12:15]
	s_setprio 0
	s_setprio 1
	v_mfma_f32_16x16x32_bf16 v[52:55], v[168:171], v[184:187], v[52:55]
	v_mfma_f32_16x16x32_bf16 v[48:51], v[176:179], v[184:187], v[48:51]
	v_mfma_f32_16x16x32_bf16 v[32:35], v[176:179], v[192:195], v[32:35]
	v_mfma_f32_16x16x32_bf16 v[36:39], v[168:171], v[192:195], v[36:39]
	v_mfma_f32_16x16x32_bf16 v[20:23], v[168:171], v[200:203], v[20:23]
	v_mfma_f32_16x16x32_bf16 v[16:19], v[176:179], v[200:203], v[16:19]
	v_mfma_f32_16x16x32_bf16 v[0:3], v[176:179], v[210:213], v[0:3]
	v_mfma_f32_16x16x32_bf16 v[4:7], v[168:171], v[210:213], v[4:7]
	v_mfma_f32_16x16x32_bf16 v[52:55], v[172:175], v[188:191], v[52:55]
	v_mfma_f32_16x16x32_bf16 v[48:51], v[180:183], v[188:191], v[48:51]
	v_mfma_f32_16x16x32_bf16 v[32:35], v[180:183], v[196:199], v[32:35]
	v_mfma_f32_16x16x32_bf16 v[36:39], v[172:175], v[196:199], v[36:39]
	v_mfma_f32_16x16x32_bf16 v[20:23], v[172:175], v[206:209], v[20:23]
	v_mfma_f32_16x16x32_bf16 v[16:19], v[180:183], v[206:209], v[16:19]
	v_lshl_add_u64 v[218:219], v[224:225], 0, s[12:13]
	s_mov_b32 m0, s44
	s_nop 0
	global_load_lds_dwordx4 v[218:219], off
	v_mfma_f32_16x16x32_bf16 v[0:3], v[180:183], v[214:217], v[0:3]
	v_mfma_f32_16x16x32_bf16 v[4:7], v[172:175], v[214:217], v[4:7]
	s_setprio 0
	s_barrier
	s_add_i32 s55, s55, 2
	s_add_u32 s53, s53, 0x100
	s_addc_u32 s54, s54, 0
	s_cmp_gt_u32 s55, 41
	s_mov_b64 s[26:27], s[28:29]
	s_cbranch_scc0 .LBB0_1978
	s_and_b64 vcc, exec, s[16:17]
	s_cbranch_vccz .LBB0_1981
	s_barrier
